# v-phase tail: h rows of the last two tokens requested one step early, no dead prefetch after the last step
# speedup vs baseline: 1.0151x; 1.0044x over previous
; __device__ __forceinline__ void peer_v_tokens(int j, const LAS unsigned short* EL, const LAS unsigned char* AL  , const LAS float* ASC  , const LAS int* SAL  , ...
;     asm volatile("" : "+v"(lane));
;     const int BUF[3] = {vslot(3 * wave), vslot(3 * wave + 1), vslot(3 * wave + 2)};
;     const int g = lane >> 3, j8 = lane & 7, s16 = lane & 15, grp = lane >> 4;
;     *(LAS unsigned long long*)(ldsb + BUF[0] + 8 * s16) = 0xFEDCBA9876543210ull;
;     CFENCE();
;     const v2i cal = TR4(ldsb + BUF[0] + 8 * s16);
;     const int pc = cal.x & 15;
;     asm volatile("s_waitcnt lgkmcnt(0)" ::: "memory");
;     const unsigned cx0 = 16u * (unsigned)(j8 ^ (g >> 1)), cx1 = 16u * (unsigned)(j8 ^ (4 + (g >> 1)));
;     const int fr = (4 * (s16 >> 3) + ((s16 & 7) >> 1)) & 7;
;     int roff[4];
; #pragma unroll
;     for (int r = 0; r < 4; ++r) roff[r] = 128 * s16 + 16 * ((((grp >> 1) + 2 * r)) ^ fr) + 8 * (grp & 1);
;     ...
; #pragma unroll 1
;     for (int it = 0; it < 8; ++it) {
;         const int tl = it * 8 + wave, t = j * 64 + tl;
;         unsigned E[8];
;         { const LAS v4u* ep = (const LAS v4u*)(EL + tl * 128 + 16 * g); const v4u e0 = ep[0], e1 = ep[1];
;           E[0] = e0.x; E[1] = e0.y; E[2] = e0.z; E[3] = e0.w; E[4] = e1.x; E[5] = e1.y; E[6] = e1.z; E[7] = e1.w; }
;         uint2 hv[4]; float4 gv[4];
;         { unsigned ho = (unsigned)t * (D / 4) + (unsigned)lane; asm volatile("" : "+v"(ho)); const uint2* hp = (const uint2*)HB + ho; const float4* gp = (const float4*)fng + lane;
; #pragma unroll
;           for (int jq = 0; jq < 4; ++jq) { hv[jq] = hp[64 * jq]; gv[jq] = gp[64 * jq]; } }
;         VDMA(0, 0); VDMA(1, 1);
; #pragma unroll
;         for (int m = 0; m < 2; ++m) {
;             const int idx = lane + 64 * m, tau = idx >> 4, sr = idx & 15, k = 16 * (sr & 7) + 2 * tau + (sr >> 3);
;             const int aq = (int)*(const LAS signed char*)(AL + tl * 128 + k); const int tq = aq + 8;
;             const unsigned lo = (((unsigned)tq & 15u) ^ 8u) * 0x11111111u, hi = ((unsigned)(tq >> 4) & 15u) * 0x11111111u;
;             typedef unsigned u2v __attribute__((ext_vector_type(2)));
;             u2v l2; l2.x = lo; l2.y = lo; u2v h2; h2.x = hi; h2.y = hi;
;             *(LAS u2v*)(ATL + 8 * idx) = l2; *(LAS u2v*)(ATL + 1024 + 8 * idx) = h2;
;         }
;         const float asc = ASC[tl]; const int sa = SAL[tl];
;         CFENCE();
.LBB0_691:
	s_or_b64 exec, exec, s[10:11]
	v_mov_b32_e32 v18, v1
	s_waitcnt lgkmcnt(0)
	s_barrier
	v_readlane_b32 s70, v235, 50
	v_and_b32_e32 v19, 15, v18
	v_lshlrev_b32_e32 v58, 3, v19
	v_add_u32_e32 v20, s60, v58
	ds_write_b64 v20, v[84:85]
	v_lshrrev_b32_e32 v23, 1, v18
	v_ashrrev_i32_e32 v24, 5, v18
	v_and_b32_e32 v25, 8, v23
	ds_read_b64_tr_b4 v[20:21], v20
	v_lshl_or_b32 v19, v19, 7, v25
	v_bitop3_b32 v25, v23, v24, 7 bitop3:0x6c
	v_lshl_add_u32 v59, v25, 4, v19
	v_add_u32_e32 v25, 2, v24
	v_bitop3_b32 v25, v25, v23, 7 bitop3:0x78
	v_lshl_add_u32 v60, v25, 4, v19
	v_add_u32_e32 v25, 4, v24
	v_add_u32_e32 v24, 6, v24
	s_waitcnt lgkmcnt(0)
	v_ashrrev_i32_e32 v21, 4, v18
	v_bitop3_b32 v25, v25, v23, 7 bitop3:0x78
	v_bitop3_b32 v23, v24, v23, 7 bitop3:0x78
	v_bitop3_b32 v22, v18, v21, 7 bitop3:0x6c
	v_add_u32_e32 v21, 4, v21
	v_lshl_add_u32 v61, v25, 4, v19
	v_lshl_add_u32 v62, v23, 4, v19
	v_and_b32_e32 v19, 15, v20
	v_bitop3_b32 v21, v21, v18, 7 bitop3:0x78
	v_lshlrev_b32_e32 v63, 4, v22
	v_lshlrev_b32_e32 v22, 1, v19
	v_ashrrev_i32_e32 v19, 31, v18
	v_lshlrev_b32_e32 v64, 4, v21
	v_lshlrev_b64 v[20:21], 4, v[18:19]
	v_and_b32_e32 v25, 0x7ffffff0, v18
	v_lshl_add_u64 v[34:35], s[86:87], 0, v[20:21]
	v_lshlrev_b32_e32 v19, 4, v18
	v_lshlrev_b32_e32 v25, 1, v25
	v_lshl_add_u64 v[36:37], s[88:89], 0, v[20:21]
	v_add_u32_e32 v21, 64, v18
	s_waitcnt lgkmcnt(0)
	v_and_b32_e32 v19, 0x70, v19
	v_add3_u32 v65, s58, v22, v25
	v_ashrrev_i32_e32 v20, 3, v18
	v_ashrrev_i32_e32 v22, 3, v21
	v_lshrrev_b32_e32 v23, 3, v18
	v_bfe_u32 v24, v18, 3, 1
	v_and_b32_e32 v20, -2, v20
	v_and_b32_e32 v22, -2, v22
	v_lshlrev_b32_e32 v21, 3, v21
	v_add_u32_e32 v19, s72, v19
	v_lshlrev_b32_e32 v66, 3, v18
	v_add_u32_e32 v67, 0x200000, v63
	v_add_u32_e32 v68, 0x200000, v64
	v_add_u32_e32 v69, 0x400000, v63
	v_add_u32_e32 v70, 0x400000, v64
	v_add_u32_e32 v71, 0x600000, v63
	v_add_u32_e32 v72, 0x600000, v64
	v_add3_u32 v73, v19, v22, v24
	v_add3_u32 v74, v19, v20, v24
	v_lshl_add_u32 v75, v23, 5, s65
	v_add_u32_e32 v76, s73, v18
	s_mov_b32 s12, 0
	v_add_u32_e32 v77, s59, v21
	s_mov_b32 s13, s67
	v_readlane_b32 s71, v235, 51
	s_mov_b32 s76, s60
	s_add_i32 s77, s60, 0x800
	s_mov_b32 s78, s61
	s_add_i32 s79, s61, 0x800
	s_mov_b32 s98, s62
	s_add_i32 s99, s62, 0x800
	v_add_u32_e32 v159, s59, v66
	v_add_u32_e32 v160, s59, v58
	v_add_u32_e32 v154, s58, v66
	v_add_u32_e32 v227, 0x12000, v75
	v_lshlrev_b32_e32 v138, 1, v66
	v_add_u32_e32 v155, 0x11200, v138
	v_add_u32_e32 v156, 0x27400, v138
	global_load_dwordx4 v[210:213], v[34:35], off
	global_load_dwordx4 v[214:217], v[34:35], off offset:1024
	global_load_dwordx4 v[218:221], v[34:35], off offset:2048
	global_load_dwordx4 v[222:225], v[34:35], off offset:3072
	ds_read_b128 v[18:21], v227
	ds_read_b128 v[22:25], v227 offset:16
	v_mov_b32_e32 v138, v74
	ds_read_u8 v139, v138
	v_mov_b32_e32 v141, v73
	ds_read_u8 v140, v141
	v_mov_b32_e32 v150, v63
	v_mov_b32_e32 v151, v64
	s_waitcnt lgkmcnt(0)
	v_and_b32_e32 v78, 0xffff, v18
	v_lshrrev_b32_e32 v79, 16, v18
	v_lshl_add_u32 v78, v78, 7, v150
	v_lshl_add_u32 v79, v79, 7, v151
	s_mov_b32 m0, s76
	s_add_i32 s43, s76, 0x400
	global_load_lds_dwordx4 v78, s[50:51]
	s_mov_b32 m0, s43
	s_nop 0
	global_load_lds_dwordx4 v79, s[50:51]
	v_and_b32_e32 v78, 0xffff, v19
	v_lshrrev_b32_e32 v79, 16, v19
	v_lshl_add_u32 v78, v78, 7, v150
	v_lshl_add_u32 v79, v79, 7, v151
	s_mov_b32 m0, s77
	s_add_i32 s43, s77, 0x400
	global_load_lds_dwordx4 v78, s[50:51]
	s_mov_b32 m0, s43
	s_nop 0
	global_load_lds_dwordx4 v79, s[50:51]
	v_and_b32_e32 v78, 0xffff, v20
	v_lshrrev_b32_e32 v79, 16, v20
	v_lshl_add_u32 v78, v78, 7, v150
	v_lshl_add_u32 v79, v79, 7, v151
	s_mov_b32 m0, s78
	s_add_i32 s43, s78, 0x400
	global_load_lds_dwordx4 v78, s[50:51]
	s_mov_b32 m0, s43
	s_nop 0
	global_load_lds_dwordx4 v79, s[50:51]
	v_and_b32_e32 v78, 0xffff, v21
	v_lshrrev_b32_e32 v79, 16, v21
	v_lshl_add_u32 v78, v78, 7, v150
	v_lshl_add_u32 v79, v79, 7, v151
	s_mov_b32 m0, s79
	s_add_i32 s43, s79, 0x400
	global_load_lds_dwordx4 v78, s[50:51]
	s_mov_b32 m0, s43
	s_nop 0
	global_load_lds_dwordx4 v79, s[50:51]
	v_and_b32_e32 v78, 0xffff, v22
	v_lshrrev_b32_e32 v79, 16, v22
	v_lshl_add_u32 v78, v78, 7, v150
	v_lshl_add_u32 v79, v79, 7, v151
	s_mov_b32 m0, s98
	s_add_i32 s43, s98, 0x400
	global_load_lds_dwordx4 v78, s[50:51]
	s_mov_b32 m0, s43
	s_nop 0
	global_load_lds_dwordx4 v79, s[50:51]
	v_add_u32_e32 v143, 8, v139
	v_and_b32_e32 v142, 15, v143
	v_xor_b32_e32 v142, 8, v142
	v_bfe_u32 v144, v143, 4, 4
	v_mul_lo_u32 v142, v142, s92
	v_mul_lo_u32 v144, v144, s92
	v_mov_b32_e32 v143, v142
	v_mov_b32_e32 v145, v144
	ds_write2st64_b64 v159, v[142:143], v[144:145] offset1:2
	s_waitcnt vmcnt(10)
	ds_write_b128 v155, v[210:213]
	ds_write_b128 v155, v[214:217] offset:1024
	ds_write_b128 v156, v[218:221]
	ds_write_b128 v156, v[222:225] offset:1024
	s_waitcnt vmcnt(8)
	v_add_u32_e32 v54, s76, v59
	v_add_u32_e32 v55, s76, v60
	v_add_u32_e32 v56, s76, v61
	v_add_u32_e32 v57, s76, v62
	ds_read_b64_tr_b4 v[46:47], v160
	ds_read_b64_tr_b4 v[48:49], v160 offset:1024
	ds_read_b64_tr_b4 v[122:123], v54
	ds_read_b64_tr_b4 v[124:125], v55
	ds_read_b64_tr_b4 v[126:127], v56
	ds_read_b64_tr_b4 v[128:129], v57
	v_add_u32_e32 v147, 8, v140
	v_and_b32_e32 v146, 15, v147
	v_xor_b32_e32 v146, 8, v146
	v_bfe_u32 v148, v147, 4, 4
	v_mul_lo_u32 v146, v146, s92
	v_mul_lo_u32 v148, v148, s92
	v_mov_b32_e32 v147, v146
	v_mov_b32_e32 v149, v148
	ds_write2st64_b64 v77, v[146:147], v[148:149] offset1:2
	v_add_u32_e32 v138, 0x400, v74
	ds_read_u8 v139, v138
	v_add_u32_e32 v141, 0x400, v73
	ds_read_u8 v140, v141
	s_mov_b32 s43, s67
	v_mov_b32_e32 v138, s43
	ds_read2st64_b32 v[228:229], v138 offset1:1
	ds_read_b128 v[26:29], v227 offset:2048
	ds_read_b128 v[30:33], v227 offset:2064
	v_mov_b32_e32 v38, 0
	v_mov_b32_e32 v39, 0
	v_mov_b32_e32 v40, 0
	v_mov_b32_e32 v41, 0
	v_mov_b32_e32 v42, 0
	v_mov_b32_e32 v43, 0
	v_mov_b32_e32 v44, 0
	v_mov_b32_e32 v45, 0
	v_and_b32_e32 v78, 0xffff, v23
	v_lshrrev_b32_e32 v79, 16, v23
	v_lshl_add_u32 v78, v78, 7, v150
	v_lshl_add_u32 v79, v79, 7, v151
	s_mov_b32 m0, s99
	s_add_i32 s43, s99, 0x400
	global_load_lds_dwordx4 v78, s[50:51]
	s_mov_b32 m0, s43
	s_nop 0
	global_load_lds_dwordx4 v79, s[50:51]
	s_waitcnt vmcnt(8)
; #define TR4(p_) __builtin_amdgcn_ds_read_tr4_b64_v2i32((LAS v2i*)(p_))
; #define VDMA(st_, k_) do { _Pragma("unroll") for (int i_ = 0; i_ < 4; ++i_) { \
;         const unsigned off_ = (unsigned)((st_) >> 2) * (16384u * 128u) + (PE_ID(E, 4 * ((st_) & 3) + i_) << 7) + ((i_ & 1) ? cx1 : cx0); \
;         __builtin_amdgcn_global_load_lds((const unsigned*)(V4 + off_), (LAS unsigned*)(ldsb + BUF[k_] + 1024 * i_), 16, 0, 0); } } while (0)
; __device__ __forceinline__ void peer_v_tokens(int j, const LAS unsigned short* EL, const LAS unsigned char* AL  , const LAS float* ASC  , const LAS int* SAL  , ...
;     ...
;         for (int st = 0; st < 16; ++st) {
;             const int p = st >> 2, q = st & 3;
;             if (st < 14) VDMA(st + 2, (st + 2) % 3);
;             if (st < 14) asm volatile("s_waitcnt vmcnt(8)" ::: "memory");
;             else if (st == 14) asm volatile("s_waitcnt vmcnt(4)" ::: "memory");
;             else asm volatile("s_waitcnt vmcnt(0)" ::: "memory");
;             if (q == 0) {
; #pragma unroll
;                 for (int r = 0; r < 4; ++r) { accH[r] = 0; accL[r] = 0; } }
; #pragma unroll
;             for (int tp = 0; tp < 2; ++tp) {
;                 const v2i ao = TR4(ATL + (2 * q + tp) * 128 + 8 * s16), ah = TR4(ATL + 1024 + (2 * q + tp) * 128 + 8 * s16);
; #pragma unroll
;                 for (int r = 0; r < 4; ++r) {
;                     const v2i d = TR4(ldsb + BUF[st % 3] + 2048 * tp + roff[r]);
;                     accH[r] = __builtin_amdgcn_sdot8(d.x, ah.x, accH[r], false); accH[r] = __builtin_amdgcn_sdot8(d.y, ah.y, accH[r], false);
;                     accL[r] = __builtin_amdgcn_sdot8(d.x, ao.x, accL[r], false); accL[r] = __builtin_amdgcn_sdot8(d.y, ao.y, accL[r], false);
;                 }
;             }
	v_add_u32_e32 v54, s77, v59
	v_add_u32_e32 v55, s77, v60
	v_add_u32_e32 v56, s77, v61
	v_add_u32_e32 v57, s77, v62
	ds_read_b64_tr_b4 v[50:51], v160 offset:128
	ds_read_b64_tr_b4 v[52:53], v160 offset:1152
	ds_read_b64_tr_b4 v[130:131], v54
	ds_read_b64_tr_b4 v[132:133], v55
	ds_read_b64_tr_b4 v[134:135], v56
	ds_read_b64_tr_b4 v[136:137], v57
	s_waitcnt lgkmcnt(12)
	v_dot8c_i32_i4_e32 v38, v122, v48
	v_dot8c_i32_i4_e32 v39, v122, v46
	v_dot8c_i32_i4_e32 v40, v124, v48
	v_dot8c_i32_i4_e32 v41, v124, v46
	v_dot8c_i32_i4_e32 v42, v126, v48
	v_dot8c_i32_i4_e32 v43, v126, v46
	v_dot8c_i32_i4_e32 v44, v128, v48
	v_dot8c_i32_i4_e32 v45, v128, v46
	v_dot8c_i32_i4_e32 v38, v123, v49
	v_dot8c_i32_i4_e32 v39, v123, v47
	v_dot8c_i32_i4_e32 v40, v125, v49
	v_dot8c_i32_i4_e32 v41, v125, v47
	v_dot8c_i32_i4_e32 v42, v127, v49
	v_dot8c_i32_i4_e32 v43, v127, v47
	v_dot8c_i32_i4_e32 v44, v129, v49
	v_dot8c_i32_i4_e32 v45, v129, v47
	v_and_b32_e32 v78, 0xffff, v24
	v_lshrrev_b32_e32 v79, 16, v24
	v_lshl_add_u32 v78, v78, 7, v150
	v_lshl_add_u32 v79, v79, 7, v151
	s_mov_b32 m0, s76
	s_add_i32 s43, s76, 0x400
	global_load_lds_dwordx4 v78, s[50:51]
	s_mov_b32 m0, s43
	s_nop 0
	global_load_lds_dwordx4 v79, s[50:51]
	s_waitcnt vmcnt(8)
	v_add_u32_e32 v54, s78, v59
	v_add_u32_e32 v55, s78, v60
	v_add_u32_e32 v56, s78, v61
	v_add_u32_e32 v57, s78, v62
	ds_read_b64_tr_b4 v[46:47], v160 offset:256
	ds_read_b64_tr_b4 v[48:49], v160 offset:1280
	ds_read_b64_tr_b4 v[122:123], v54
	ds_read_b64_tr_b4 v[124:125], v55
	ds_read_b64_tr_b4 v[126:127], v56
	ds_read_b64_tr_b4 v[128:129], v57
	s_waitcnt lgkmcnt(6)
	v_dot8c_i32_i4_e32 v38, v130, v52
	v_dot8c_i32_i4_e32 v39, v130, v50
	v_dot8c_i32_i4_e32 v40, v132, v52
	v_dot8c_i32_i4_e32 v41, v132, v50
	v_dot8c_i32_i4_e32 v42, v134, v52
	v_dot8c_i32_i4_e32 v43, v134, v50
	v_dot8c_i32_i4_e32 v44, v136, v52
	v_dot8c_i32_i4_e32 v45, v136, v50
	v_dot8c_i32_i4_e32 v38, v131, v53
	v_dot8c_i32_i4_e32 v39, v131, v51
	v_dot8c_i32_i4_e32 v40, v133, v53
	v_dot8c_i32_i4_e32 v41, v133, v51
	v_dot8c_i32_i4_e32 v42, v135, v53
	v_dot8c_i32_i4_e32 v43, v135, v51
	v_dot8c_i32_i4_e32 v44, v137, v53
	v_dot8c_i32_i4_e32 v45, v137, v51
	v_and_b32_e32 v78, 0xffff, v25
	v_lshrrev_b32_e32 v79, 16, v25
	v_lshl_add_u32 v78, v78, 7, v150
	v_lshl_add_u32 v79, v79, 7, v151
	s_mov_b32 m0, s77
	s_add_i32 s43, s77, 0x400
	global_load_lds_dwordx4 v78, s[50:51]
	s_mov_b32 m0, s43
	s_nop 0
	global_load_lds_dwordx4 v79, s[50:51]
	s_waitcnt vmcnt(8)
	v_add_u32_e32 v54, s79, v59
	v_add_u32_e32 v55, s79, v60
	v_add_u32_e32 v56, s79, v61
	v_add_u32_e32 v57, s79, v62
	ds_read_b64_tr_b4 v[50:51], v160 offset:384
	ds_read_b64_tr_b4 v[52:53], v160 offset:1408
	ds_read_b64_tr_b4 v[130:131], v54
	ds_read_b64_tr_b4 v[132:133], v55
	ds_read_b64_tr_b4 v[134:135], v56
	ds_read_b64_tr_b4 v[136:137], v57
	s_waitcnt lgkmcnt(6)
	v_dot8c_i32_i4_e32 v38, v122, v48
	v_dot8c_i32_i4_e32 v39, v122, v46
	v_dot8c_i32_i4_e32 v40, v124, v48
	v_dot8c_i32_i4_e32 v41, v124, v46
	v_dot8c_i32_i4_e32 v42, v126, v48
	v_dot8c_i32_i4_e32 v43, v126, v46
	v_dot8c_i32_i4_e32 v44, v128, v48
	v_dot8c_i32_i4_e32 v45, v128, v46
	v_dot8c_i32_i4_e32 v38, v123, v49
	v_dot8c_i32_i4_e32 v39, v123, v47
	v_dot8c_i32_i4_e32 v40, v125, v49
	v_dot8c_i32_i4_e32 v41, v125, v47
	v_dot8c_i32_i4_e32 v42, v127, v49
	v_dot8c_i32_i4_e32 v43, v127, v47
	v_dot8c_i32_i4_e32 v44, v129, v49
	v_dot8c_i32_i4_e32 v45, v129, v47
	s_waitcnt lgkmcnt(15)
	v_and_b32_e32 v78, 0xffff, v26
	v_lshrrev_b32_e32 v79, 16, v26
	v_lshl_add_u32 v78, v78, 7, v150
	v_lshl_add_u32 v79, v79, 7, v151
	s_mov_b32 m0, s78
	s_add_i32 s43, s78, 0x400
	global_load_lds_dwordx4 v78, s[50:51]
	s_mov_b32 m0, s43
	s_nop 0
	global_load_lds_dwordx4 v79, s[50:51]
	s_waitcnt vmcnt(8)
	v_add_u32_e32 v54, s98, v59
	v_add_u32_e32 v55, s98, v60
	v_add_u32_e32 v56, s98, v61
	v_add_u32_e32 v57, s98, v62
	ds_read_b64_tr_b4 v[46:47], v160 offset:512
	ds_read_b64_tr_b4 v[48:49], v160 offset:1536
	ds_read_b64_tr_b4 v[122:123], v54
	ds_read_b64_tr_b4 v[124:125], v55
	ds_read_b64_tr_b4 v[126:127], v56
	ds_read_b64_tr_b4 v[128:129], v57
	s_waitcnt lgkmcnt(6)
	v_dot8c_i32_i4_e32 v38, v130, v52
	v_dot8c_i32_i4_e32 v39, v130, v50
	v_dot8c_i32_i4_e32 v40, v132, v52
	v_dot8c_i32_i4_e32 v41, v132, v50
	v_dot8c_i32_i4_e32 v42, v134, v52
	v_dot8c_i32_i4_e32 v43, v134, v50
	v_dot8c_i32_i4_e32 v44, v136, v52
	v_dot8c_i32_i4_e32 v45, v136, v50
	v_dot8c_i32_i4_e32 v38, v131, v53
	v_dot8c_i32_i4_e32 v39, v131, v51
	v_dot8c_i32_i4_e32 v40, v133, v53
	v_dot8c_i32_i4_e32 v41, v133, v51
	v_dot8c_i32_i4_e32 v42, v135, v53
	v_dot8c_i32_i4_e32 v43, v135, v51
	v_dot8c_i32_i4_e32 v44, v137, v53
	v_dot8c_i32_i4_e32 v45, v137, v51
	v_and_b32_e32 v78, 0xffff, v27
	v_lshrrev_b32_e32 v79, 16, v27
	v_lshl_add_u32 v78, v78, 7, v150
	v_lshl_add_u32 v79, v79, 7, v151
	s_mov_b32 m0, s79
	s_add_i32 s43, s79, 0x400
	global_load_lds_dwordx4 v78, s[50:51]
	s_mov_b32 m0, s43
	s_nop 0
	global_load_lds_dwordx4 v79, s[50:51]
	s_waitcnt vmcnt(8)
	v_add_u32_e32 v54, s99, v59
	v_add_u32_e32 v55, s99, v60
	v_add_u32_e32 v56, s99, v61
	v_add_u32_e32 v57, s99, v62
	ds_read_b64_tr_b4 v[50:51], v160 offset:640
	ds_read_b64_tr_b4 v[52:53], v160 offset:1664
	ds_read_b64_tr_b4 v[130:131], v54
	ds_read_b64_tr_b4 v[132:133], v55
	ds_read_b64_tr_b4 v[134:135], v56
	ds_read_b64_tr_b4 v[136:137], v57
	s_waitcnt lgkmcnt(6)
	v_dot8c_i32_i4_e32 v38, v122, v48
	v_dot8c_i32_i4_e32 v39, v122, v46
	v_dot8c_i32_i4_e32 v40, v124, v48
	v_dot8c_i32_i4_e32 v41, v124, v46
	v_dot8c_i32_i4_e32 v42, v126, v48
	v_dot8c_i32_i4_e32 v43, v126, v46
	v_dot8c_i32_i4_e32 v44, v128, v48
	v_dot8c_i32_i4_e32 v45, v128, v46
	v_dot8c_i32_i4_e32 v38, v123, v49
	v_dot8c_i32_i4_e32 v39, v123, v47
	v_dot8c_i32_i4_e32 v40, v125, v49
	v_dot8c_i32_i4_e32 v41, v125, v47
	v_dot8c_i32_i4_e32 v42, v127, v49
	v_dot8c_i32_i4_e32 v43, v127, v47
	v_dot8c_i32_i4_e32 v44, v129, v49
	v_dot8c_i32_i4_e32 v45, v129, v47
	s_waitcnt lgkmcnt(15)
; __device__ __forceinline__ void peer_v_tokens(int j, const LAS unsigned short* EL, const LAS unsigned char* AL  , const LAS float* ASC  , const LAS int* SAL  , ...
;     ...
;         const int tl = it * 8 + wave, t = j * 64 + tl;
;         unsigned E[8];
;         { const LAS v4u* ep = (const LAS v4u*)(EL + tl * 128 + 16 * g); const v4u e0 = ep[0], e1 = ep[1];
;           E[0] = e0.x; E[1] = e0.y; E[2] = e0.z; E[3] = e0.w; E[4] = e1.x; E[5] = e1.y; E[6] = e1.z; E[7] = e1.w; }
;         uint2 hv[4]; float4 gv[4];
;         { unsigned ho = (unsigned)t * (D / 4) + (unsigned)lane; asm volatile("" : "+v"(ho)); const uint2* hp = (const uint2*)HB + ho; const float4* gp = (const float4*)fng + lane;
; #pragma unroll
;           for (int jq = 0; jq < 4; ++jq) { hv[jq] = hp[64 * jq]; gv[jq] = gp[64 * jq]; } }
;         VDMA(0, 0); VDMA(1, 1);
; #pragma unroll
;         for (int m = 0; m < 2; ++m) {
;             const int idx = lane + 64 * m, tau = idx >> 4, sr = idx & 15, k = 16 * (sr & 7) + 2 * tau + (sr >> 3);
;             const int aq = (int)*(const LAS signed char*)(AL + tl * 128 + k); const int tq = aq + 8;
;             const unsigned lo = (((unsigned)tq & 15u) ^ 8u) * 0x11111111u, hi = ((unsigned)(tq >> 4) & 15u) * 0x11111111u;
;             typedef unsigned u2v __attribute__((ext_vector_type(2)));
;             u2v l2; l2.x = lo; l2.y = lo; u2v h2; h2.x = hi; h2.y = hi;
;             *(LAS u2v*)(ATL + 8 * idx) = l2; *(LAS u2v*)(ATL + 1024 + 8 * idx) = h2;
;         }
;         const float asc = ASC[tl]; const int sa = SAL[tl];
;         CFENCE();
;         int accH[4], accL[4];
; #pragma unroll
;         for (int st = 0; st < 16; ++st) {
;             const int p = st >> 2, q = st & 3;
;             if (st < 14) VDMA(st + 2, (st + 2) % 3);
;             if (st < 14) asm volatile("s_waitcnt vmcnt(8)" ::: "memory");
;             else if (st == 14) asm volatile("s_waitcnt vmcnt(4)" ::: "memory");
;             else asm volatile("s_waitcnt vmcnt(0)" ::: "memory");
;             if (q == 0) {
; #pragma unroll
;                 for (int r = 0; r < 4; ++r) { accH[r] = 0; accL[r] = 0; } }
; #pragma unroll
;             for (int tp = 0; tp < 2; ++tp) {
;                 const v2i ao = TR4(ATL + (2 * q + tp) * 128 + 8 * s16), ah = TR4(ATL + 1024 + (2 * q + tp) * 128 + 8 * s16);
; #pragma unroll
;                 for (int r = 0; r < 4; ++r) {
	v_add_u32_e32 v143, 8, v139
	v_and_b32_e32 v142, 15, v143
	v_xor_b32_e32 v142, 8, v142
	v_bfe_u32 v144, v143, 4, 4
	v_mul_lo_u32 v142, v142, s92
	v_mul_lo_u32 v144, v144, s92
	v_mov_b32_e32 v143, v142
	v_mov_b32_e32 v145, v144
	ds_write2st64_b64 v159, v[142:143], v[144:145] offset1:2
	v_and_b32_e32 v78, 0xffff, v28
	v_lshrrev_b32_e32 v79, 16, v28
	v_lshl_add_u32 v78, v78, 7, v150
	v_lshl_add_u32 v79, v79, 7, v151
	s_mov_b32 m0, s98
	s_add_i32 s43, s98, 0x400
	global_load_lds_dwordx4 v78, s[50:51]
	s_mov_b32 m0, s43
	s_nop 0
	global_load_lds_dwordx4 v79, s[50:51]
	s_waitcnt vmcnt(8)
	v_add_u32_e32 v54, s76, v59
	v_add_u32_e32 v55, s76, v60
	v_add_u32_e32 v56, s76, v61
	v_add_u32_e32 v57, s76, v62
	ds_read_b64_tr_b4 v[46:47], v160 offset:768
	ds_read_b64_tr_b4 v[48:49], v160 offset:1792
	ds_read_b64_tr_b4 v[122:123], v54
	ds_read_b64_tr_b4 v[124:125], v55
	ds_read_b64_tr_b4 v[126:127], v56
	ds_read_b64_tr_b4 v[128:129], v57
	s_waitcnt lgkmcnt(7)
	v_dot8c_i32_i4_e32 v38, v130, v52
	v_dot8c_i32_i4_e32 v39, v130, v50
	v_dot8c_i32_i4_e32 v40, v132, v52
	v_dot8c_i32_i4_e32 v41, v132, v50
	v_dot8c_i32_i4_e32 v42, v134, v52
	v_dot8c_i32_i4_e32 v43, v134, v50
	v_dot8c_i32_i4_e32 v44, v136, v52
	v_dot8c_i32_i4_e32 v45, v136, v50
	v_dot8c_i32_i4_e32 v38, v131, v53
	v_dot8c_i32_i4_e32 v39, v131, v51
	v_dot8c_i32_i4_e32 v40, v133, v53
	v_dot8c_i32_i4_e32 v41, v133, v51
	v_dot8c_i32_i4_e32 v42, v135, v53
	v_dot8c_i32_i4_e32 v43, v135, v51
	v_dot8c_i32_i4_e32 v44, v137, v53
	v_dot8c_i32_i4_e32 v45, v137, v51
	v_and_b32_e32 v78, 0xffff, v29
	v_lshrrev_b32_e32 v79, 16, v29
	v_lshl_add_u32 v78, v78, 7, v150
	v_lshl_add_u32 v79, v79, 7, v151
	s_mov_b32 m0, s99
	s_add_i32 s43, s99, 0x400
	global_load_lds_dwordx4 v78, s[50:51]
	s_mov_b32 m0, s43
	s_nop 0
	global_load_lds_dwordx4 v79, s[50:51]
	s_waitcnt vmcnt(8)
	v_add_u32_e32 v54, s77, v59
	v_add_u32_e32 v55, s77, v60
	v_add_u32_e32 v56, s77, v61
	v_add_u32_e32 v57, s77, v62
	ds_read_b64_tr_b4 v[50:51], v160 offset:896
	ds_read_b64_tr_b4 v[52:53], v160 offset:1920
	ds_read_b64_tr_b4 v[130:131], v54
	ds_read_b64_tr_b4 v[132:133], v55
	ds_read_b64_tr_b4 v[134:135], v56
	ds_read_b64_tr_b4 v[136:137], v57
	s_waitcnt lgkmcnt(6)
	v_dot8c_i32_i4_e32 v38, v122, v48
	v_dot8c_i32_i4_e32 v39, v122, v46
	v_dot8c_i32_i4_e32 v40, v124, v48
	v_dot8c_i32_i4_e32 v41, v124, v46
	v_dot8c_i32_i4_e32 v42, v126, v48
	v_dot8c_i32_i4_e32 v43, v126, v46
	v_dot8c_i32_i4_e32 v44, v128, v48
	v_dot8c_i32_i4_e32 v45, v128, v46
	v_dot8c_i32_i4_e32 v38, v123, v49
	v_dot8c_i32_i4_e32 v39, v123, v47
	v_dot8c_i32_i4_e32 v40, v125, v49
	v_dot8c_i32_i4_e32 v41, v125, v47
	v_dot8c_i32_i4_e32 v42, v127, v49
	v_dot8c_i32_i4_e32 v43, v127, v47
	v_dot8c_i32_i4_e32 v44, v129, v49
	v_dot8c_i32_i4_e32 v45, v129, v47
	v_and_b32_e32 v78, 0xffff, v30
	v_lshrrev_b32_e32 v79, 16, v30
	v_lshl_add_u32 v78, v78, 7, v150
	v_lshl_add_u32 v79, v79, 7, v151
	s_mov_b32 m0, s76
	s_add_i32 s43, s76, 0x400
	global_load_lds_dwordx4 v78, s[50:51]
	s_mov_b32 m0, s43
	s_nop 0
	global_load_lds_dwordx4 v79, s[50:51]
	s_waitcnt vmcnt(8)
	v_add_u32_e32 v54, s78, v59
	v_add_u32_e32 v55, s78, v60
	v_add_u32_e32 v56, s78, v61
	v_add_u32_e32 v57, s78, v62
	ds_read_b64_tr_b4 v[46:47], v160
	ds_read_b64_tr_b4 v[48:49], v160 offset:1024
	ds_read_b64_tr_b4 v[122:123], v54
	ds_read_b64_tr_b4 v[124:125], v55
	ds_read_b64_tr_b4 v[126:127], v56
	ds_read_b64_tr_b4 v[128:129], v57
	s_waitcnt lgkmcnt(6)
	v_dot8c_i32_i4_e32 v38, v130, v52
	v_dot8c_i32_i4_e32 v39, v130, v50
	v_dot8c_i32_i4_e32 v40, v132, v52
	v_dot8c_i32_i4_e32 v41, v132, v50
	v_dot8c_i32_i4_e32 v42, v134, v52
	v_dot8c_i32_i4_e32 v43, v134, v50
	v_dot8c_i32_i4_e32 v44, v136, v52
	v_dot8c_i32_i4_e32 v45, v136, v50
	v_dot8c_i32_i4_e32 v38, v131, v53
	v_dot8c_i32_i4_e32 v39, v131, v51
	v_dot8c_i32_i4_e32 v40, v133, v53
	v_dot8c_i32_i4_e32 v41, v133, v51
	v_dot8c_i32_i4_e32 v42, v135, v53
	v_dot8c_i32_i4_e32 v43, v135, v51
	v_dot8c_i32_i4_e32 v44, v137, v53
	v_dot8c_i32_i4_e32 v45, v137, v51
	s_nop 3
	s_waitcnt lgkmcnt(15)
	v_lshlrev_b32_e32 v38, 5, v38
	v_lshlrev_b32_e32 v39, 1, v39
	v_add3_u32 v38, v39, v229, v38
	v_cvt_f32_i32_e32 v38, v38
	v_mul_f32_e32 v38, v228, v38
	v_lshlrev_b32_e32 v40, 5, v40
	v_lshlrev_b32_e32 v41, 1, v41
	v_add3_u32 v40, v41, v229, v40
	v_cvt_f32_i32_e32 v40, v40
	v_mul_f32_e32 v40, v228, v40
	v_lshlrev_b32_e32 v42, 5, v42
	v_lshlrev_b32_e32 v43, 1, v43
	v_add3_u32 v42, v43, v229, v42
	v_cvt_f32_i32_e32 v42, v42
	v_mul_f32_e32 v42, v228, v42
	v_lshlrev_b32_e32 v44, 5, v44
	v_lshlrev_b32_e32 v45, 1, v45
	v_add3_u32 v44, v45, v229, v44
	v_cvt_f32_i32_e32 v44, v44
	v_mul_f32_e32 v44, v228, v44
	v_cvt_pk_bf16_f32 v162, v38, v40
	v_cvt_pk_bf16_f32 v163, v42, v44
	v_add_u32_e32 v147, 8, v140
	v_and_b32_e32 v146, 15, v147
	v_xor_b32_e32 v146, 8, v146
	v_bfe_u32 v148, v147, 4, 4
	v_mul_lo_u32 v146, v146, s92
	v_mul_lo_u32 v148, v148, s92
	v_mov_b32_e32 v147, v146
	v_mov_b32_e32 v149, v148
	ds_write2st64_b64 v77, v[146:147], v[148:149] offset1:2
	v_mov_b32_e32 v138, v74
	ds_read_u8 v139, v138
	v_mov_b32_e32 v141, v73
	ds_read_u8 v140, v141
	s_add_i32 s43, s67, 32
	v_mov_b32_e32 v138, s43
	ds_read2st64_b32 v[228:229], v138 offset1:1
	ds_read_b128 v[18:21], v227
	ds_read_b128 v[22:25], v227 offset:16
	v_add_u32_e32 v152, 0x200000, v63
	v_add_u32_e32 v153, 0x200000, v64
	v_mov_b32_e32 v38, 0
	v_mov_b32_e32 v39, 0
	v_mov_b32_e32 v40, 0
	v_mov_b32_e32 v41, 0
	v_mov_b32_e32 v42, 0
	v_mov_b32_e32 v43, 0
	v_mov_b32_e32 v44, 0
	v_mov_b32_e32 v45, 0
	v_and_b32_e32 v78, 0xffff, v31
	v_lshrrev_b32_e32 v79, 16, v31
	v_lshl_add_u32 v78, v78, 7, v150
	v_lshl_add_u32 v79, v79, 7, v151
	s_mov_b32 m0, s77
	s_add_i32 s43, s77, 0x400
	global_load_lds_dwordx4 v78, s[50:51]
	s_mov_b32 m0, s43
	s_nop 0
	global_load_lds_dwordx4 v79, s[50:51]
	s_waitcnt vmcnt(8)
; __device__ __forceinline__ bf16 f2bf(float f) { return (bf16)f2bfu(f); }
; #define TR4(p_) __builtin_amdgcn_ds_read_tr4_b64_v2i32((LAS v2i*)(p_))
; #define VDMA(st_, k_) do { _Pragma("unroll") for (int i_ = 0; i_ < 4; ++i_) { \
;         const unsigned off_ = (unsigned)((st_) >> 2) * (16384u * 128u) + (PE_ID(E, 4 * ((st_) & 3) + i_) << 7) + ((i_ & 1) ? cx1 : cx0); \
;         __builtin_amdgcn_global_load_lds((const unsigned*)(V4 + off_), (LAS unsigned*)(ldsb + BUF[k_] + 1024 * i_), 16, 0, 0); } } while (0)
; __device__ __forceinline__ void peer_v_tokens(int j, const LAS unsigned short* EL, const LAS unsigned char* AL  , const LAS float* ASC  , const LAS int* SAL  , ...
;     ...
;         for (int st = 0; st < 16; ++st) {
;             const int p = st >> 2, q = st & 3;
;             if (st < 14) VDMA(st + 2, (st + 2) % 3);
;             if (st < 14) asm volatile("s_waitcnt vmcnt(8)" ::: "memory");
;             else if (st == 14) asm volatile("s_waitcnt vmcnt(4)" ::: "memory");
;             else asm volatile("s_waitcnt vmcnt(0)" ::: "memory");
;             if (q == 0) {
; #pragma unroll
;                 for (int r = 0; r < 4; ++r) { accH[r] = 0; accL[r] = 0; } }
; #pragma unroll
;             for (int tp = 0; tp < 2; ++tp) {
;                 const v2i ao = TR4(ATL + (2 * q + tp) * 128 + 8 * s16), ah = TR4(ATL + 1024 + (2 * q + tp) * 128 + 8 * s16);
; #pragma unroll
;                 for (int r = 0; r < 4; ++r) {
;                     const v2i d = TR4(ldsb + BUF[st % 3] + 2048 * tp + roff[r]);
;                     accH[r] = __builtin_amdgcn_sdot8(d.x, ah.x, accH[r], false); accH[r] = __builtin_amdgcn_sdot8(d.y, ah.y, accH[r], false);
;                     accL[r] = __builtin_amdgcn_sdot8(d.x, ao.x, accL[r], false); accL[r] = __builtin_amdgcn_sdot8(d.y, ao.y, accL[r], false);
;                 }
;             }
;             asm volatile("s_waitcnt lgkmcnt(0)" ::: "memory");
;             if (q == 3) {
; #pragma unroll
;                 for (int r = 0; r < 4; ++r) STASH[256 * p + 16 * (grp + 4 * r) + pc] = f2bf(asc * (float)(2 * ((accH[r] << 4) + accL[r]) + sa));
;             }
;         }
	v_add_u32_e32 v54, s79, v59
	v_add_u32_e32 v55, s79, v60
	v_add_u32_e32 v56, s79, v61
	v_add_u32_e32 v57, s79, v62
	ds_read_b64_tr_b4 v[50:51], v160 offset:128
	ds_read_b64_tr_b4 v[52:53], v160 offset:1152
	ds_read_b64_tr_b4 v[130:131], v54
	ds_read_b64_tr_b4 v[132:133], v55
	ds_read_b64_tr_b4 v[134:135], v56
	ds_read_b64_tr_b4 v[136:137], v57
	s_waitcnt lgkmcnt(12)
	v_dot8c_i32_i4_e32 v38, v122, v48
	v_dot8c_i32_i4_e32 v39, v122, v46
	v_dot8c_i32_i4_e32 v40, v124, v48
	v_dot8c_i32_i4_e32 v41, v124, v46
	v_dot8c_i32_i4_e32 v42, v126, v48
	v_dot8c_i32_i4_e32 v43, v126, v46
	v_dot8c_i32_i4_e32 v44, v128, v48
	v_dot8c_i32_i4_e32 v45, v128, v46
	v_dot8c_i32_i4_e32 v38, v123, v49
	v_dot8c_i32_i4_e32 v39, v123, v47
	v_dot8c_i32_i4_e32 v40, v125, v49
	v_dot8c_i32_i4_e32 v41, v125, v47
	v_dot8c_i32_i4_e32 v42, v127, v49
	v_dot8c_i32_i4_e32 v43, v127, v47
	v_dot8c_i32_i4_e32 v44, v129, v49
	v_dot8c_i32_i4_e32 v45, v129, v47
	v_and_b32_e32 v78, 0xffff, v32
	v_lshrrev_b32_e32 v79, 16, v32
	v_lshl_add_u32 v78, v78, 7, v150
	v_lshl_add_u32 v79, v79, 7, v151
	s_mov_b32 m0, s78
	s_add_i32 s43, s78, 0x400
	global_load_lds_dwordx4 v78, s[50:51]
	s_mov_b32 m0, s43
	s_nop 0
	global_load_lds_dwordx4 v79, s[50:51]
	s_waitcnt vmcnt(8)
	v_add_u32_e32 v54, s98, v59
	v_add_u32_e32 v55, s98, v60
	v_add_u32_e32 v56, s98, v61
	v_add_u32_e32 v57, s98, v62
	ds_read_b64_tr_b4 v[46:47], v160 offset:256
	ds_read_b64_tr_b4 v[48:49], v160 offset:1280
	ds_read_b64_tr_b4 v[122:123], v54
	ds_read_b64_tr_b4 v[124:125], v55
	ds_read_b64_tr_b4 v[126:127], v56
	ds_read_b64_tr_b4 v[128:129], v57
	s_waitcnt lgkmcnt(6)
	v_dot8c_i32_i4_e32 v38, v130, v52
	v_dot8c_i32_i4_e32 v39, v130, v50
	v_dot8c_i32_i4_e32 v40, v132, v52
	v_dot8c_i32_i4_e32 v41, v132, v50
	v_dot8c_i32_i4_e32 v42, v134, v52
	v_dot8c_i32_i4_e32 v43, v134, v50
	v_dot8c_i32_i4_e32 v44, v136, v52
	v_dot8c_i32_i4_e32 v45, v136, v50
	v_dot8c_i32_i4_e32 v38, v131, v53
	v_dot8c_i32_i4_e32 v39, v131, v51
	v_dot8c_i32_i4_e32 v40, v133, v53
	v_dot8c_i32_i4_e32 v41, v133, v51
	v_dot8c_i32_i4_e32 v42, v135, v53
	v_dot8c_i32_i4_e32 v43, v135, v51
	v_dot8c_i32_i4_e32 v44, v137, v53
	v_dot8c_i32_i4_e32 v45, v137, v51
	v_and_b32_e32 v78, 0xffff, v33
	v_lshrrev_b32_e32 v79, 16, v33
	v_lshl_add_u32 v78, v78, 7, v150
	v_lshl_add_u32 v79, v79, 7, v151
	s_mov_b32 m0, s79
	s_add_i32 s43, s79, 0x400
	global_load_lds_dwordx4 v78, s[50:51]
	s_mov_b32 m0, s43
	s_nop 0
	global_load_lds_dwordx4 v79, s[50:51]
	s_waitcnt vmcnt(8)
	v_add_u32_e32 v54, s99, v59
	v_add_u32_e32 v55, s99, v60
	v_add_u32_e32 v56, s99, v61
	v_add_u32_e32 v57, s99, v62
	ds_read_b64_tr_b4 v[50:51], v160 offset:384
	ds_read_b64_tr_b4 v[52:53], v160 offset:1408
	ds_read_b64_tr_b4 v[130:131], v54
	ds_read_b64_tr_b4 v[132:133], v55
	ds_read_b64_tr_b4 v[134:135], v56
	ds_read_b64_tr_b4 v[136:137], v57
	s_waitcnt lgkmcnt(6)
	v_dot8c_i32_i4_e32 v38, v122, v48
	v_dot8c_i32_i4_e32 v39, v122, v46
	v_dot8c_i32_i4_e32 v40, v124, v48
	v_dot8c_i32_i4_e32 v41, v124, v46
	v_dot8c_i32_i4_e32 v42, v126, v48
	v_dot8c_i32_i4_e32 v43, v126, v46
	v_dot8c_i32_i4_e32 v44, v128, v48
	v_dot8c_i32_i4_e32 v45, v128, v46
	v_dot8c_i32_i4_e32 v38, v123, v49
	v_dot8c_i32_i4_e32 v39, v123, v47
	v_dot8c_i32_i4_e32 v40, v125, v49
	v_dot8c_i32_i4_e32 v41, v125, v47
	v_dot8c_i32_i4_e32 v42, v127, v49
	v_dot8c_i32_i4_e32 v43, v127, v47
	v_dot8c_i32_i4_e32 v44, v129, v49
	v_dot8c_i32_i4_e32 v45, v129, v47
	s_waitcnt lgkmcnt(15)
	v_and_b32_e32 v78, 0xffff, v18
	v_lshrrev_b32_e32 v79, 16, v18
	v_lshl_add_u32 v78, v78, 7, v152
	v_lshl_add_u32 v79, v79, 7, v153
	s_mov_b32 m0, s98
	s_add_i32 s43, s98, 0x400
	global_load_lds_dwordx4 v78, s[50:51]
	s_mov_b32 m0, s43
	s_nop 0
	global_load_lds_dwordx4 v79, s[50:51]
	s_waitcnt vmcnt(8)
	v_add_u32_e32 v54, s76, v59
	v_add_u32_e32 v55, s76, v60
	v_add_u32_e32 v56, s76, v61
	v_add_u32_e32 v57, s76, v62
	ds_read_b64_tr_b4 v[46:47], v160 offset:512
	ds_read_b64_tr_b4 v[48:49], v160 offset:1536
	ds_read_b64_tr_b4 v[122:123], v54
	ds_read_b64_tr_b4 v[124:125], v55
	ds_read_b64_tr_b4 v[126:127], v56
	ds_read_b64_tr_b4 v[128:129], v57
	s_waitcnt lgkmcnt(6)
	v_dot8c_i32_i4_e32 v38, v130, v52
	v_dot8c_i32_i4_e32 v39, v130, v50
	v_dot8c_i32_i4_e32 v40, v132, v52
	v_dot8c_i32_i4_e32 v41, v132, v50
	v_dot8c_i32_i4_e32 v42, v134, v52
	v_dot8c_i32_i4_e32 v43, v134, v50
	v_dot8c_i32_i4_e32 v44, v136, v52
	v_dot8c_i32_i4_e32 v45, v136, v50
	v_dot8c_i32_i4_e32 v38, v131, v53
	v_dot8c_i32_i4_e32 v39, v131, v51
	v_dot8c_i32_i4_e32 v40, v133, v53
	v_dot8c_i32_i4_e32 v41, v133, v51
	v_dot8c_i32_i4_e32 v42, v135, v53
	v_dot8c_i32_i4_e32 v43, v135, v51
	v_dot8c_i32_i4_e32 v44, v137, v53
	v_dot8c_i32_i4_e32 v45, v137, v51
	v_and_b32_e32 v78, 0xffff, v19
	v_lshrrev_b32_e32 v79, 16, v19
	v_lshl_add_u32 v78, v78, 7, v152
	v_lshl_add_u32 v79, v79, 7, v153
	s_mov_b32 m0, s99
	s_add_i32 s43, s99, 0x400
	global_load_lds_dwordx4 v78, s[50:51]
	s_mov_b32 m0, s43
	s_nop 0
	global_load_lds_dwordx4 v79, s[50:51]
	s_waitcnt vmcnt(8)
	v_add_u32_e32 v54, s77, v59
	v_add_u32_e32 v55, s77, v60
	v_add_u32_e32 v56, s77, v61
	v_add_u32_e32 v57, s77, v62
	ds_read_b64_tr_b4 v[50:51], v160 offset:640
	ds_read_b64_tr_b4 v[52:53], v160 offset:1664
	ds_read_b64_tr_b4 v[130:131], v54
	ds_read_b64_tr_b4 v[132:133], v55
	ds_read_b64_tr_b4 v[134:135], v56
	ds_read_b64_tr_b4 v[136:137], v57
	s_waitcnt lgkmcnt(6)
	v_dot8c_i32_i4_e32 v38, v122, v48
	v_dot8c_i32_i4_e32 v39, v122, v46
	v_dot8c_i32_i4_e32 v40, v124, v48
	v_dot8c_i32_i4_e32 v41, v124, v46
	v_dot8c_i32_i4_e32 v42, v126, v48
	v_dot8c_i32_i4_e32 v43, v126, v46
	v_dot8c_i32_i4_e32 v44, v128, v48
	v_dot8c_i32_i4_e32 v45, v128, v46
	v_dot8c_i32_i4_e32 v38, v123, v49
	v_dot8c_i32_i4_e32 v39, v123, v47
	v_dot8c_i32_i4_e32 v40, v125, v49
	v_dot8c_i32_i4_e32 v41, v125, v47
	v_dot8c_i32_i4_e32 v42, v127, v49
	v_dot8c_i32_i4_e32 v43, v127, v47
	v_dot8c_i32_i4_e32 v44, v129, v49
	v_dot8c_i32_i4_e32 v45, v129, v47
	s_waitcnt lgkmcnt(15)
; #define LAS __attribute__((address_space(3)))
; __device__ __forceinline__ bf16 f2bf(float f) { return (bf16)f2bfu(f); }
; __device__ __forceinline__ void peer_v_tokens(int j, const LAS unsigned short* EL, const LAS unsigned char* AL  , const LAS float* ASC  , const LAS int* SAL  , ...
;     ...
;         for (int m = 0; m < 2; ++m) {
;             const int idx = lane + 64 * m, tau = idx >> 4, sr = idx & 15, k = 16 * (sr & 7) + 2 * tau + (sr >> 3);
;             const int aq = (int)*(const LAS signed char*)(AL + tl * 128 + k); const int tq = aq + 8;
;             const unsigned lo = (((unsigned)tq & 15u) ^ 8u) * 0x11111111u, hi = ((unsigned)(tq >> 4) & 15u) * 0x11111111u;
;             typedef unsigned u2v __attribute__((ext_vector_type(2)));
;             u2v l2; l2.x = lo; l2.y = lo; u2v h2; h2.x = hi; h2.y = hi;
;             *(LAS u2v*)(ATL + 8 * idx) = l2; *(LAS u2v*)(ATL + 1024 + 8 * idx) = h2;
;         }
;     ...
;         for (int st = 0; st < 16; ++st) {
;             const int p = st >> 2, q = st & 3;
;             if (st < 14) VDMA(st + 2, (st + 2) % 3);
;             if (st < 14) asm volatile("s_waitcnt vmcnt(8)" ::: "memory");
;             else if (st == 14) asm volatile("s_waitcnt vmcnt(4)" ::: "memory");
;             else asm volatile("s_waitcnt vmcnt(0)" ::: "memory");
;             if (q == 0) {
; #pragma unroll
;                 for (int r = 0; r < 4; ++r) { accH[r] = 0; accL[r] = 0; } }
; #pragma unroll
;             for (int tp = 0; tp < 2; ++tp) {
;                 const v2i ao = TR4(ATL + (2 * q + tp) * 128 + 8 * s16), ah = TR4(ATL + 1024 + (2 * q + tp) * 128 + 8 * s16);
; #pragma unroll
;                 for (int r = 0; r < 4; ++r) {
;                     const v2i d = TR4(ldsb + BUF[st % 3] + 2048 * tp + roff[r]);
;                     accH[r] = __builtin_amdgcn_sdot8(d.x, ah.x, accH[r], false); accH[r] = __builtin_amdgcn_sdot8(d.y, ah.y, accH[r], false);
;                     accL[r] = __builtin_amdgcn_sdot8(d.x, ao.x, accL[r], false); accL[r] = __builtin_amdgcn_sdot8(d.y, ao.y, accL[r], false);
;                 }
;             }
;             asm volatile("s_waitcnt lgkmcnt(0)" ::: "memory");
;             if (q == 3) {
; #pragma unroll
;                 for (int r = 0; r < 4; ++r) STASH[256 * p + 16 * (grp + 4 * r) + pc] = f2bf(asc * (float)(2 * ((accH[r] << 4) + accL[r]) + sa));
;             }
;         }
	v_add_u32_e32 v143, 8, v139
	v_and_b32_e32 v142, 15, v143
	v_xor_b32_e32 v142, 8, v142
	v_bfe_u32 v144, v143, 4, 4
	v_mul_lo_u32 v142, v142, s92
	v_mul_lo_u32 v144, v144, s92
	v_mov_b32_e32 v143, v142
	v_mov_b32_e32 v145, v144
	ds_write2st64_b64 v159, v[142:143], v[144:145] offset1:2
	v_and_b32_e32 v78, 0xffff, v20
	v_lshrrev_b32_e32 v79, 16, v20
	v_lshl_add_u32 v78, v78, 7, v152
	v_lshl_add_u32 v79, v79, 7, v153
	s_mov_b32 m0, s76
	s_add_i32 s43, s76, 0x400
	global_load_lds_dwordx4 v78, s[50:51]
	s_mov_b32 m0, s43
	s_nop 0
	global_load_lds_dwordx4 v79, s[50:51]
	s_waitcnt vmcnt(8)
	v_add_u32_e32 v54, s78, v59
	v_add_u32_e32 v55, s78, v60
	v_add_u32_e32 v56, s78, v61
	v_add_u32_e32 v57, s78, v62
	ds_read_b64_tr_b4 v[46:47], v160 offset:768
	ds_read_b64_tr_b4 v[48:49], v160 offset:1792
	ds_read_b64_tr_b4 v[122:123], v54
	ds_read_b64_tr_b4 v[124:125], v55
	ds_read_b64_tr_b4 v[126:127], v56
	ds_read_b64_tr_b4 v[128:129], v57
	s_waitcnt lgkmcnt(7)
	v_dot8c_i32_i4_e32 v38, v130, v52
	v_dot8c_i32_i4_e32 v39, v130, v50
	v_dot8c_i32_i4_e32 v40, v132, v52
	v_dot8c_i32_i4_e32 v41, v132, v50
	v_dot8c_i32_i4_e32 v42, v134, v52
	v_dot8c_i32_i4_e32 v43, v134, v50
	v_dot8c_i32_i4_e32 v44, v136, v52
	v_dot8c_i32_i4_e32 v45, v136, v50
	v_dot8c_i32_i4_e32 v38, v131, v53
	v_dot8c_i32_i4_e32 v39, v131, v51
	v_dot8c_i32_i4_e32 v40, v133, v53
	v_dot8c_i32_i4_e32 v41, v133, v51
	v_dot8c_i32_i4_e32 v42, v135, v53
	v_dot8c_i32_i4_e32 v43, v135, v51
	v_dot8c_i32_i4_e32 v44, v137, v53
	v_dot8c_i32_i4_e32 v45, v137, v51
	v_and_b32_e32 v78, 0xffff, v21
	v_lshrrev_b32_e32 v79, 16, v21
	v_lshl_add_u32 v78, v78, 7, v152
	v_lshl_add_u32 v79, v79, 7, v153
	s_mov_b32 m0, s77
	s_add_i32 s43, s77, 0x400
	global_load_lds_dwordx4 v78, s[50:51]
	s_mov_b32 m0, s43
	s_nop 0
	global_load_lds_dwordx4 v79, s[50:51]
	s_waitcnt vmcnt(8)
	v_add_u32_e32 v54, s79, v59
	v_add_u32_e32 v55, s79, v60
	v_add_u32_e32 v56, s79, v61
	v_add_u32_e32 v57, s79, v62
	ds_read_b64_tr_b4 v[50:51], v160 offset:896
	ds_read_b64_tr_b4 v[52:53], v160 offset:1920
	ds_read_b64_tr_b4 v[130:131], v54
	ds_read_b64_tr_b4 v[132:133], v55
	ds_read_b64_tr_b4 v[134:135], v56
	ds_read_b64_tr_b4 v[136:137], v57
	s_waitcnt lgkmcnt(6)
	v_dot8c_i32_i4_e32 v38, v122, v48
	v_dot8c_i32_i4_e32 v39, v122, v46
	v_dot8c_i32_i4_e32 v40, v124, v48
	v_dot8c_i32_i4_e32 v41, v124, v46
	v_dot8c_i32_i4_e32 v42, v126, v48
	v_dot8c_i32_i4_e32 v43, v126, v46
	v_dot8c_i32_i4_e32 v44, v128, v48
	v_dot8c_i32_i4_e32 v45, v128, v46
	v_dot8c_i32_i4_e32 v38, v123, v49
	v_dot8c_i32_i4_e32 v39, v123, v47
	v_dot8c_i32_i4_e32 v40, v125, v49
	v_dot8c_i32_i4_e32 v41, v125, v47
	v_dot8c_i32_i4_e32 v42, v127, v49
	v_dot8c_i32_i4_e32 v43, v127, v47
	v_dot8c_i32_i4_e32 v44, v129, v49
	v_dot8c_i32_i4_e32 v45, v129, v47
	v_and_b32_e32 v78, 0xffff, v22
	v_lshrrev_b32_e32 v79, 16, v22
	v_lshl_add_u32 v78, v78, 7, v152
	v_lshl_add_u32 v79, v79, 7, v153
	s_mov_b32 m0, s78
	s_add_i32 s43, s78, 0x400
	global_load_lds_dwordx4 v78, s[50:51]
	s_mov_b32 m0, s43
	s_nop 0
	global_load_lds_dwordx4 v79, s[50:51]
	s_waitcnt vmcnt(8)
	v_add_u32_e32 v54, s98, v59
	v_add_u32_e32 v55, s98, v60
	v_add_u32_e32 v56, s98, v61
	v_add_u32_e32 v57, s98, v62
	ds_read_b64_tr_b4 v[46:47], v160
	ds_read_b64_tr_b4 v[48:49], v160 offset:1024
	ds_read_b64_tr_b4 v[122:123], v54
	ds_read_b64_tr_b4 v[124:125], v55
	ds_read_b64_tr_b4 v[126:127], v56
	ds_read_b64_tr_b4 v[128:129], v57
	s_waitcnt lgkmcnt(6)
	v_dot8c_i32_i4_e32 v38, v130, v52
	v_dot8c_i32_i4_e32 v39, v130, v50
	v_dot8c_i32_i4_e32 v40, v132, v52
	v_dot8c_i32_i4_e32 v41, v132, v50
	v_dot8c_i32_i4_e32 v42, v134, v52
	v_dot8c_i32_i4_e32 v43, v134, v50
	v_dot8c_i32_i4_e32 v44, v136, v52
	v_dot8c_i32_i4_e32 v45, v136, v50
	v_dot8c_i32_i4_e32 v38, v131, v53
	v_dot8c_i32_i4_e32 v39, v131, v51
	v_dot8c_i32_i4_e32 v40, v133, v53
	v_dot8c_i32_i4_e32 v41, v133, v51
	v_dot8c_i32_i4_e32 v42, v135, v53
	v_dot8c_i32_i4_e32 v43, v135, v51
	v_dot8c_i32_i4_e32 v44, v137, v53
	v_dot8c_i32_i4_e32 v45, v137, v51
	s_nop 3
	s_waitcnt lgkmcnt(15)
	v_lshlrev_b32_e32 v38, 5, v38
	v_lshlrev_b32_e32 v39, 1, v39
	v_add3_u32 v38, v39, v229, v38
	v_cvt_f32_i32_e32 v38, v38
	v_mul_f32_e32 v38, v228, v38
	v_lshlrev_b32_e32 v40, 5, v40
	v_lshlrev_b32_e32 v41, 1, v41
	v_add3_u32 v40, v41, v229, v40
	v_cvt_f32_i32_e32 v40, v40
	v_mul_f32_e32 v40, v228, v40
	v_lshlrev_b32_e32 v42, 5, v42
	v_lshlrev_b32_e32 v43, 1, v43
	v_add3_u32 v42, v43, v229, v42
	v_cvt_f32_i32_e32 v42, v42
	v_mul_f32_e32 v42, v228, v42
	v_lshlrev_b32_e32 v44, 5, v44
	v_lshlrev_b32_e32 v45, 1, v45
	v_add3_u32 v44, v45, v229, v44
	v_cvt_f32_i32_e32 v44, v44
	v_mul_f32_e32 v44, v228, v44
	v_cvt_pk_bf16_f32 v170, v38, v40
	v_cvt_pk_bf16_f32 v171, v42, v44
	v_add_u32_e32 v147, 8, v140
	v_and_b32_e32 v146, 15, v147
	v_xor_b32_e32 v146, 8, v146
	v_bfe_u32 v148, v147, 4, 4
	v_mul_lo_u32 v146, v146, s92
	v_mul_lo_u32 v148, v148, s92
	v_mov_b32_e32 v147, v146
	v_mov_b32_e32 v149, v148
	ds_write2st64_b64 v77, v[146:147], v[148:149] offset1:2
	v_add_u32_e32 v138, 0x400, v74
	ds_read_u8 v139, v138
	v_add_u32_e32 v141, 0x400, v73
	ds_read_u8 v140, v141
	s_mov_b32 s43, s67
	v_mov_b32_e32 v138, s43
	ds_read2st64_b32 v[228:229], v138 offset1:1
	ds_read_b128 v[26:29], v227 offset:2048
	ds_read_b128 v[30:33], v227 offset:2064
	v_mov_b32_e32 v38, 0
	v_mov_b32_e32 v39, 0
	v_mov_b32_e32 v40, 0
	v_mov_b32_e32 v41, 0
	v_mov_b32_e32 v42, 0
	v_mov_b32_e32 v43, 0
	v_mov_b32_e32 v44, 0
	v_mov_b32_e32 v45, 0
	v_and_b32_e32 v78, 0xffff, v23
	v_lshrrev_b32_e32 v79, 16, v23
	v_lshl_add_u32 v78, v78, 7, v152
	v_lshl_add_u32 v79, v79, 7, v153
	s_mov_b32 m0, s79
	s_add_i32 s43, s79, 0x400
	global_load_lds_dwordx4 v78, s[50:51]
	s_mov_b32 m0, s43
	s_nop 0
	global_load_lds_dwordx4 v79, s[50:51]
	s_waitcnt vmcnt(8)
; __device__ __forceinline__ bf16 f2bf(float f) { return (bf16)f2bfu(f); }
; #define TR4(p_) __builtin_amdgcn_ds_read_tr4_b64_v2i32((LAS v2i*)(p_))
; #define VDMA(st_, k_) do { _Pragma("unroll") for (int i_ = 0; i_ < 4; ++i_) { \
;         const unsigned off_ = (unsigned)((st_) >> 2) * (16384u * 128u) + (PE_ID(E, 4 * ((st_) & 3) + i_) << 7) + ((i_ & 1) ? cx1 : cx0); \
;         __builtin_amdgcn_global_load_lds((const unsigned*)(V4 + off_), (LAS unsigned*)(ldsb + BUF[k_] + 1024 * i_), 16, 0, 0); } } while (0)
; __device__ __forceinline__ void peer_v_tokens(int j, const LAS unsigned short* EL, const LAS unsigned char* AL  , const LAS float* ASC  , const LAS int* SAL  , ...
;     ...
;         for (int st = 0; st < 16; ++st) {
;             const int p = st >> 2, q = st & 3;
;             if (st < 14) VDMA(st + 2, (st + 2) % 3);
;             if (st < 14) asm volatile("s_waitcnt vmcnt(8)" ::: "memory");
;             else if (st == 14) asm volatile("s_waitcnt vmcnt(4)" ::: "memory");
;             else asm volatile("s_waitcnt vmcnt(0)" ::: "memory");
;             if (q == 0) {
; #pragma unroll
;                 for (int r = 0; r < 4; ++r) { accH[r] = 0; accL[r] = 0; } }
; #pragma unroll
;             for (int tp = 0; tp < 2; ++tp) {
;                 const v2i ao = TR4(ATL + (2 * q + tp) * 128 + 8 * s16), ah = TR4(ATL + 1024 + (2 * q + tp) * 128 + 8 * s16);
; #pragma unroll
;                 for (int r = 0; r < 4; ++r) {
;                     const v2i d = TR4(ldsb + BUF[st % 3] + 2048 * tp + roff[r]);
;                     accH[r] = __builtin_amdgcn_sdot8(d.x, ah.x, accH[r], false); accH[r] = __builtin_amdgcn_sdot8(d.y, ah.y, accH[r], false);
;                     accL[r] = __builtin_amdgcn_sdot8(d.x, ao.x, accL[r], false); accL[r] = __builtin_amdgcn_sdot8(d.y, ao.y, accL[r], false);
;                 }
;             }
;             asm volatile("s_waitcnt lgkmcnt(0)" ::: "memory");
;             if (q == 3) {
; #pragma unroll
;                 for (int r = 0; r < 4; ++r) STASH[256 * p + 16 * (grp + 4 * r) + pc] = f2bf(asc * (float)(2 * ((accH[r] << 4) + accL[r]) + sa));
;             }
;         }
	v_add_u32_e32 v54, s99, v59
	v_add_u32_e32 v55, s99, v60
	v_add_u32_e32 v56, s99, v61
	v_add_u32_e32 v57, s99, v62
	ds_read_b64_tr_b4 v[50:51], v160 offset:128
	ds_read_b64_tr_b4 v[52:53], v160 offset:1152
	ds_read_b64_tr_b4 v[130:131], v54
	ds_read_b64_tr_b4 v[132:133], v55
	ds_read_b64_tr_b4 v[134:135], v56
	ds_read_b64_tr_b4 v[136:137], v57
	s_waitcnt lgkmcnt(12)
	v_dot8c_i32_i4_e32 v38, v122, v48
	v_dot8c_i32_i4_e32 v39, v122, v46
	v_dot8c_i32_i4_e32 v40, v124, v48
	v_dot8c_i32_i4_e32 v41, v124, v46
	v_dot8c_i32_i4_e32 v42, v126, v48
	v_dot8c_i32_i4_e32 v43, v126, v46
	v_dot8c_i32_i4_e32 v44, v128, v48
	v_dot8c_i32_i4_e32 v45, v128, v46
	v_dot8c_i32_i4_e32 v38, v123, v49
	v_dot8c_i32_i4_e32 v39, v123, v47
	v_dot8c_i32_i4_e32 v40, v125, v49
	v_dot8c_i32_i4_e32 v41, v125, v47
	v_dot8c_i32_i4_e32 v42, v127, v49
	v_dot8c_i32_i4_e32 v43, v127, v47
	v_dot8c_i32_i4_e32 v44, v129, v49
	v_dot8c_i32_i4_e32 v45, v129, v47
	v_and_b32_e32 v78, 0xffff, v24
	v_lshrrev_b32_e32 v79, 16, v24
	v_lshl_add_u32 v78, v78, 7, v152
	v_lshl_add_u32 v79, v79, 7, v153
	s_mov_b32 m0, s98
	s_add_i32 s43, s98, 0x400
	global_load_lds_dwordx4 v78, s[50:51]
	s_mov_b32 m0, s43
	s_nop 0
	global_load_lds_dwordx4 v79, s[50:51]
	s_waitcnt vmcnt(8)
	v_add_u32_e32 v54, s76, v59
	v_add_u32_e32 v55, s76, v60
	v_add_u32_e32 v56, s76, v61
	v_add_u32_e32 v57, s76, v62
	ds_read_b64_tr_b4 v[46:47], v160 offset:256
	ds_read_b64_tr_b4 v[48:49], v160 offset:1280
	ds_read_b64_tr_b4 v[122:123], v54
	ds_read_b64_tr_b4 v[124:125], v55
	ds_read_b64_tr_b4 v[126:127], v56
	ds_read_b64_tr_b4 v[128:129], v57
	s_waitcnt lgkmcnt(6)
	v_dot8c_i32_i4_e32 v38, v130, v52
	v_dot8c_i32_i4_e32 v39, v130, v50
	v_dot8c_i32_i4_e32 v40, v132, v52
	v_dot8c_i32_i4_e32 v41, v132, v50
	v_dot8c_i32_i4_e32 v42, v134, v52
	v_dot8c_i32_i4_e32 v43, v134, v50
	v_dot8c_i32_i4_e32 v44, v136, v52
	v_dot8c_i32_i4_e32 v45, v136, v50
	v_dot8c_i32_i4_e32 v38, v131, v53
	v_dot8c_i32_i4_e32 v39, v131, v51
	v_dot8c_i32_i4_e32 v40, v133, v53
	v_dot8c_i32_i4_e32 v41, v133, v51
	v_dot8c_i32_i4_e32 v42, v135, v53
	v_dot8c_i32_i4_e32 v43, v135, v51
	v_dot8c_i32_i4_e32 v44, v137, v53
	v_dot8c_i32_i4_e32 v45, v137, v51
	v_and_b32_e32 v78, 0xffff, v25
	v_lshrrev_b32_e32 v79, 16, v25
	v_lshl_add_u32 v78, v78, 7, v152
	v_lshl_add_u32 v79, v79, 7, v153
	s_mov_b32 m0, s99
	s_add_i32 s43, s99, 0x400
	global_load_lds_dwordx4 v78, s[50:51]
	s_mov_b32 m0, s43
	s_nop 0
	global_load_lds_dwordx4 v79, s[50:51]
	s_waitcnt vmcnt(8)
	v_add_u32_e32 v54, s77, v59
	v_add_u32_e32 v55, s77, v60
	v_add_u32_e32 v56, s77, v61
	v_add_u32_e32 v57, s77, v62
	ds_read_b64_tr_b4 v[50:51], v160 offset:384
	ds_read_b64_tr_b4 v[52:53], v160 offset:1408
	ds_read_b64_tr_b4 v[130:131], v54
	ds_read_b64_tr_b4 v[132:133], v55
	ds_read_b64_tr_b4 v[134:135], v56
	ds_read_b64_tr_b4 v[136:137], v57
	s_waitcnt lgkmcnt(6)
	v_dot8c_i32_i4_e32 v38, v122, v48
	v_dot8c_i32_i4_e32 v39, v122, v46
	v_dot8c_i32_i4_e32 v40, v124, v48
	v_dot8c_i32_i4_e32 v41, v124, v46
	v_dot8c_i32_i4_e32 v42, v126, v48
	v_dot8c_i32_i4_e32 v43, v126, v46
	v_dot8c_i32_i4_e32 v44, v128, v48
	v_dot8c_i32_i4_e32 v45, v128, v46
	v_dot8c_i32_i4_e32 v38, v123, v49
	v_dot8c_i32_i4_e32 v39, v123, v47
	v_dot8c_i32_i4_e32 v40, v125, v49
	v_dot8c_i32_i4_e32 v41, v125, v47
	v_dot8c_i32_i4_e32 v42, v127, v49
	v_dot8c_i32_i4_e32 v43, v127, v47
	v_dot8c_i32_i4_e32 v44, v129, v49
	v_dot8c_i32_i4_e32 v45, v129, v47
	s_waitcnt lgkmcnt(15)
	v_and_b32_e32 v78, 0xffff, v26
	v_lshrrev_b32_e32 v79, 16, v26
	v_lshl_add_u32 v78, v78, 7, v152
	v_lshl_add_u32 v79, v79, 7, v153
	s_mov_b32 m0, s76
	s_add_i32 s43, s76, 0x400
	global_load_lds_dwordx4 v78, s[50:51]
	s_mov_b32 m0, s43
	s_nop 0
	global_load_lds_dwordx4 v79, s[50:51]
	s_waitcnt vmcnt(8)
	v_add_u32_e32 v54, s78, v59
	v_add_u32_e32 v55, s78, v60
	v_add_u32_e32 v56, s78, v61
	v_add_u32_e32 v57, s78, v62
	ds_read_b64_tr_b4 v[46:47], v160 offset:512
	ds_read_b64_tr_b4 v[48:49], v160 offset:1536
	ds_read_b64_tr_b4 v[122:123], v54
	ds_read_b64_tr_b4 v[124:125], v55
	ds_read_b64_tr_b4 v[126:127], v56
	ds_read_b64_tr_b4 v[128:129], v57
	s_waitcnt lgkmcnt(6)
	v_dot8c_i32_i4_e32 v38, v130, v52
	v_dot8c_i32_i4_e32 v39, v130, v50
	v_dot8c_i32_i4_e32 v40, v132, v52
	v_dot8c_i32_i4_e32 v41, v132, v50
	v_dot8c_i32_i4_e32 v42, v134, v52
	v_dot8c_i32_i4_e32 v43, v134, v50
	v_dot8c_i32_i4_e32 v44, v136, v52
	v_dot8c_i32_i4_e32 v45, v136, v50
	v_dot8c_i32_i4_e32 v38, v131, v53
	v_dot8c_i32_i4_e32 v39, v131, v51
	v_dot8c_i32_i4_e32 v40, v133, v53
	v_dot8c_i32_i4_e32 v41, v133, v51
	v_dot8c_i32_i4_e32 v42, v135, v53
	v_dot8c_i32_i4_e32 v43, v135, v51
	v_dot8c_i32_i4_e32 v44, v137, v53
	v_dot8c_i32_i4_e32 v45, v137, v51
	v_and_b32_e32 v78, 0xffff, v27
	v_lshrrev_b32_e32 v79, 16, v27
	v_lshl_add_u32 v78, v78, 7, v152
	v_lshl_add_u32 v79, v79, 7, v153
	s_mov_b32 m0, s77
	s_add_i32 s43, s77, 0x400
	global_load_lds_dwordx4 v78, s[50:51]
	s_mov_b32 m0, s43
	s_nop 0
	global_load_lds_dwordx4 v79, s[50:51]
	s_waitcnt vmcnt(8)
	v_add_u32_e32 v54, s79, v59
	v_add_u32_e32 v55, s79, v60
	v_add_u32_e32 v56, s79, v61
	v_add_u32_e32 v57, s79, v62
	ds_read_b64_tr_b4 v[50:51], v160 offset:640
	ds_read_b64_tr_b4 v[52:53], v160 offset:1664
	ds_read_b64_tr_b4 v[130:131], v54
	ds_read_b64_tr_b4 v[132:133], v55
	ds_read_b64_tr_b4 v[134:135], v56
	ds_read_b64_tr_b4 v[136:137], v57
	s_waitcnt lgkmcnt(6)
	v_dot8c_i32_i4_e32 v38, v122, v48
	v_dot8c_i32_i4_e32 v39, v122, v46
	v_dot8c_i32_i4_e32 v40, v124, v48
	v_dot8c_i32_i4_e32 v41, v124, v46
	v_dot8c_i32_i4_e32 v42, v126, v48
	v_dot8c_i32_i4_e32 v43, v126, v46
	v_dot8c_i32_i4_e32 v44, v128, v48
	v_dot8c_i32_i4_e32 v45, v128, v46
	v_dot8c_i32_i4_e32 v38, v123, v49
	v_dot8c_i32_i4_e32 v39, v123, v47
	v_dot8c_i32_i4_e32 v40, v125, v49
	v_dot8c_i32_i4_e32 v41, v125, v47
	v_dot8c_i32_i4_e32 v42, v127, v49
	v_dot8c_i32_i4_e32 v43, v127, v47
	v_dot8c_i32_i4_e32 v44, v129, v49
	v_dot8c_i32_i4_e32 v45, v129, v47
	s_waitcnt lgkmcnt(15)
; #define LAS __attribute__((address_space(3)))
; __device__ __forceinline__ bf16 f2bf(float f) { return (bf16)f2bfu(f); }
; __device__ __forceinline__ void peer_v_tokens(int j, const LAS unsigned short* EL, const LAS unsigned char* AL  , const LAS float* ASC  , const LAS int* SAL  , ...
;     ...
;         for (int m = 0; m < 2; ++m) {
;             const int idx = lane + 64 * m, tau = idx >> 4, sr = idx & 15, k = 16 * (sr & 7) + 2 * tau + (sr >> 3);
;             const int aq = (int)*(const LAS signed char*)(AL + tl * 128 + k); const int tq = aq + 8;
;             const unsigned lo = (((unsigned)tq & 15u) ^ 8u) * 0x11111111u, hi = ((unsigned)(tq >> 4) & 15u) * 0x11111111u;
;             typedef unsigned u2v __attribute__((ext_vector_type(2)));
;             u2v l2; l2.x = lo; l2.y = lo; u2v h2; h2.x = hi; h2.y = hi;
;             *(LAS u2v*)(ATL + 8 * idx) = l2; *(LAS u2v*)(ATL + 1024 + 8 * idx) = h2;
;         }
;     ...
;         for (int st = 0; st < 16; ++st) {
;             const int p = st >> 2, q = st & 3;
;             if (st < 14) VDMA(st + 2, (st + 2) % 3);
;             if (st < 14) asm volatile("s_waitcnt vmcnt(8)" ::: "memory");
;             else if (st == 14) asm volatile("s_waitcnt vmcnt(4)" ::: "memory");
;             else asm volatile("s_waitcnt vmcnt(0)" ::: "memory");
;             if (q == 0) {
; #pragma unroll
;                 for (int r = 0; r < 4; ++r) { accH[r] = 0; accL[r] = 0; } }
; #pragma unroll
;             for (int tp = 0; tp < 2; ++tp) {
;                 const v2i ao = TR4(ATL + (2 * q + tp) * 128 + 8 * s16), ah = TR4(ATL + 1024 + (2 * q + tp) * 128 + 8 * s16);
; #pragma unroll
;                 for (int r = 0; r < 4; ++r) {
;                     const v2i d = TR4(ldsb + BUF[st % 3] + 2048 * tp + roff[r]);
;                     accH[r] = __builtin_amdgcn_sdot8(d.x, ah.x, accH[r], false); accH[r] = __builtin_amdgcn_sdot8(d.y, ah.y, accH[r], false);
;                     accL[r] = __builtin_amdgcn_sdot8(d.x, ao.x, accL[r], false); accL[r] = __builtin_amdgcn_sdot8(d.y, ao.y, accL[r], false);
;                 }
;             }
;             asm volatile("s_waitcnt lgkmcnt(0)" ::: "memory");
;             if (q == 3) {
; #pragma unroll
;                 for (int r = 0; r < 4; ++r) STASH[256 * p + 16 * (grp + 4 * r) + pc] = f2bf(asc * (float)(2 * ((accH[r] << 4) + accL[r]) + sa));
;             }
;         }
	v_add_u32_e32 v143, 8, v139
	v_and_b32_e32 v142, 15, v143
	v_xor_b32_e32 v142, 8, v142
	v_bfe_u32 v144, v143, 4, 4
	v_mul_lo_u32 v142, v142, s92
	v_mul_lo_u32 v144, v144, s92
	v_mov_b32_e32 v143, v142
	v_mov_b32_e32 v145, v144
	ds_write2st64_b64 v159, v[142:143], v[144:145] offset1:2
	v_and_b32_e32 v78, 0xffff, v28
	v_lshrrev_b32_e32 v79, 16, v28
	v_lshl_add_u32 v78, v78, 7, v152
	v_lshl_add_u32 v79, v79, 7, v153
	s_mov_b32 m0, s78
	s_add_i32 s43, s78, 0x400
	global_load_lds_dwordx4 v78, s[50:51]
	s_mov_b32 m0, s43
	s_nop 0
	global_load_lds_dwordx4 v79, s[50:51]
	s_waitcnt vmcnt(8)
	v_add_u32_e32 v54, s98, v59
	v_add_u32_e32 v55, s98, v60
	v_add_u32_e32 v56, s98, v61
	v_add_u32_e32 v57, s98, v62
	ds_read_b64_tr_b4 v[46:47], v160 offset:768
	ds_read_b64_tr_b4 v[48:49], v160 offset:1792
	ds_read_b64_tr_b4 v[122:123], v54
	ds_read_b64_tr_b4 v[124:125], v55
	ds_read_b64_tr_b4 v[126:127], v56
	ds_read_b64_tr_b4 v[128:129], v57
	s_waitcnt lgkmcnt(7)
	v_dot8c_i32_i4_e32 v38, v130, v52
	v_dot8c_i32_i4_e32 v39, v130, v50
	v_dot8c_i32_i4_e32 v40, v132, v52
	v_dot8c_i32_i4_e32 v41, v132, v50
	v_dot8c_i32_i4_e32 v42, v134, v52
	v_dot8c_i32_i4_e32 v43, v134, v50
	v_dot8c_i32_i4_e32 v44, v136, v52
	v_dot8c_i32_i4_e32 v45, v136, v50
	v_dot8c_i32_i4_e32 v38, v131, v53
	v_dot8c_i32_i4_e32 v39, v131, v51
	v_dot8c_i32_i4_e32 v40, v133, v53
	v_dot8c_i32_i4_e32 v41, v133, v51
	v_dot8c_i32_i4_e32 v42, v135, v53
	v_dot8c_i32_i4_e32 v43, v135, v51
	v_dot8c_i32_i4_e32 v44, v137, v53
	v_dot8c_i32_i4_e32 v45, v137, v51
	v_and_b32_e32 v78, 0xffff, v29
	v_lshrrev_b32_e32 v79, 16, v29
	v_lshl_add_u32 v78, v78, 7, v152
	v_lshl_add_u32 v79, v79, 7, v153
	s_mov_b32 m0, s79
	s_add_i32 s43, s79, 0x400
	global_load_lds_dwordx4 v78, s[50:51]
	s_mov_b32 m0, s43
	s_nop 0
	global_load_lds_dwordx4 v79, s[50:51]
	s_waitcnt vmcnt(8)
	v_add_u32_e32 v54, s99, v59
	v_add_u32_e32 v55, s99, v60
	v_add_u32_e32 v56, s99, v61
	v_add_u32_e32 v57, s99, v62
	ds_read_b64_tr_b4 v[50:51], v160 offset:896
	ds_read_b64_tr_b4 v[52:53], v160 offset:1920
	ds_read_b64_tr_b4 v[130:131], v54
	ds_read_b64_tr_b4 v[132:133], v55
	ds_read_b64_tr_b4 v[134:135], v56
	ds_read_b64_tr_b4 v[136:137], v57
	s_waitcnt lgkmcnt(6)
	v_dot8c_i32_i4_e32 v38, v122, v48
	v_dot8c_i32_i4_e32 v39, v122, v46
	v_dot8c_i32_i4_e32 v40, v124, v48
	v_dot8c_i32_i4_e32 v41, v124, v46
	v_dot8c_i32_i4_e32 v42, v126, v48
	v_dot8c_i32_i4_e32 v43, v126, v46
	v_dot8c_i32_i4_e32 v44, v128, v48
	v_dot8c_i32_i4_e32 v45, v128, v46
	v_dot8c_i32_i4_e32 v38, v123, v49
	v_dot8c_i32_i4_e32 v39, v123, v47
	v_dot8c_i32_i4_e32 v40, v125, v49
	v_dot8c_i32_i4_e32 v41, v125, v47
	v_dot8c_i32_i4_e32 v42, v127, v49
	v_dot8c_i32_i4_e32 v43, v127, v47
	v_dot8c_i32_i4_e32 v44, v129, v49
	v_dot8c_i32_i4_e32 v45, v129, v47
	v_and_b32_e32 v78, 0xffff, v30
	v_lshrrev_b32_e32 v79, 16, v30
	v_lshl_add_u32 v78, v78, 7, v152
	v_lshl_add_u32 v79, v79, 7, v153
	s_mov_b32 m0, s98
	s_add_i32 s43, s98, 0x400
	global_load_lds_dwordx4 v78, s[50:51]
	s_mov_b32 m0, s43
	s_nop 0
	global_load_lds_dwordx4 v79, s[50:51]
	s_waitcnt vmcnt(8)
	v_add_u32_e32 v54, s76, v59
	v_add_u32_e32 v55, s76, v60
	v_add_u32_e32 v56, s76, v61
	v_add_u32_e32 v57, s76, v62
	ds_read_b64_tr_b4 v[46:47], v160
	ds_read_b64_tr_b4 v[48:49], v160 offset:1024
	ds_read_b64_tr_b4 v[122:123], v54
	ds_read_b64_tr_b4 v[124:125], v55
	ds_read_b64_tr_b4 v[126:127], v56
	ds_read_b64_tr_b4 v[128:129], v57
	s_waitcnt lgkmcnt(6)
	v_dot8c_i32_i4_e32 v38, v130, v52
	v_dot8c_i32_i4_e32 v39, v130, v50
	v_dot8c_i32_i4_e32 v40, v132, v52
	v_dot8c_i32_i4_e32 v41, v132, v50
	v_dot8c_i32_i4_e32 v42, v134, v52
	v_dot8c_i32_i4_e32 v43, v134, v50
	v_dot8c_i32_i4_e32 v44, v136, v52
	v_dot8c_i32_i4_e32 v45, v136, v50
	v_dot8c_i32_i4_e32 v38, v131, v53
	v_dot8c_i32_i4_e32 v39, v131, v51
	v_dot8c_i32_i4_e32 v40, v133, v53
	v_dot8c_i32_i4_e32 v41, v133, v51
	v_dot8c_i32_i4_e32 v42, v135, v53
	v_dot8c_i32_i4_e32 v43, v135, v51
	v_dot8c_i32_i4_e32 v44, v137, v53
	v_dot8c_i32_i4_e32 v45, v137, v51
	s_nop 3
	s_waitcnt lgkmcnt(15)
	v_lshlrev_b32_e32 v38, 5, v38
	v_lshlrev_b32_e32 v39, 1, v39
	v_add3_u32 v38, v39, v229, v38
	v_cvt_f32_i32_e32 v38, v38
	v_mul_f32_e32 v38, v228, v38
	v_lshlrev_b32_e32 v40, 5, v40
	v_lshlrev_b32_e32 v41, 1, v41
	v_add3_u32 v40, v41, v229, v40
	v_cvt_f32_i32_e32 v40, v40
	v_mul_f32_e32 v40, v228, v40
	v_lshlrev_b32_e32 v42, 5, v42
	v_lshlrev_b32_e32 v43, 1, v43
	v_add3_u32 v42, v43, v229, v42
	v_cvt_f32_i32_e32 v42, v42
	v_mul_f32_e32 v42, v228, v42
	v_lshlrev_b32_e32 v44, 5, v44
	v_lshlrev_b32_e32 v45, 1, v45
	v_add3_u32 v44, v45, v229, v44
	v_cvt_f32_i32_e32 v44, v44
	v_mul_f32_e32 v44, v228, v44
	v_cvt_pk_bf16_f32 v164, v38, v40
	v_cvt_pk_bf16_f32 v165, v42, v44
	v_add_u32_e32 v147, 8, v140
	v_and_b32_e32 v146, 15, v147
	v_xor_b32_e32 v146, 8, v146
	v_bfe_u32 v148, v147, 4, 4
	v_mul_lo_u32 v146, v146, s92
	v_mul_lo_u32 v148, v148, s92
	v_mov_b32_e32 v147, v146
	v_mov_b32_e32 v149, v148
	ds_write2st64_b64 v77, v[146:147], v[148:149] offset1:2
	v_mov_b32_e32 v138, v74
	ds_read_u8 v139, v138
	v_mov_b32_e32 v141, v73
	ds_read_u8 v140, v141
	s_add_i32 s43, s67, 32
	v_mov_b32_e32 v138, s43
	ds_read2st64_b32 v[228:229], v138 offset1:1
	ds_read_b128 v[18:21], v227
	ds_read_b128 v[22:25], v227 offset:16
	v_add_u32_e32 v150, 0x400000, v63
	v_add_u32_e32 v151, 0x400000, v64
	v_mov_b32_e32 v38, 0
	v_mov_b32_e32 v39, 0
	v_mov_b32_e32 v40, 0
	v_mov_b32_e32 v41, 0
	v_mov_b32_e32 v42, 0
	v_mov_b32_e32 v43, 0
	v_mov_b32_e32 v44, 0
	v_mov_b32_e32 v45, 0
	v_and_b32_e32 v78, 0xffff, v31
	v_lshrrev_b32_e32 v79, 16, v31
	v_lshl_add_u32 v78, v78, 7, v152
	v_lshl_add_u32 v79, v79, 7, v153
	s_mov_b32 m0, s99
	s_add_i32 s43, s99, 0x400
	global_load_lds_dwordx4 v78, s[50:51]
	s_mov_b32 m0, s43
	s_nop 0
	global_load_lds_dwordx4 v79, s[50:51]
	s_waitcnt vmcnt(8)
; __device__ __forceinline__ bf16 f2bf(float f) { return (bf16)f2bfu(f); }
; #define TR4(p_) __builtin_amdgcn_ds_read_tr4_b64_v2i32((LAS v2i*)(p_))
; #define VDMA(st_, k_) do { _Pragma("unroll") for (int i_ = 0; i_ < 4; ++i_) { \
;         const unsigned off_ = (unsigned)((st_) >> 2) * (16384u * 128u) + (PE_ID(E, 4 * ((st_) & 3) + i_) << 7) + ((i_ & 1) ? cx1 : cx0); \
;         __builtin_amdgcn_global_load_lds((const unsigned*)(V4 + off_), (LAS unsigned*)(ldsb + BUF[k_] + 1024 * i_), 16, 0, 0); } } while (0)
; __device__ __forceinline__ void peer_v_tokens(int j, const LAS unsigned short* EL, const LAS unsigned char* AL  , const LAS float* ASC  , const LAS int* SAL  , ...
;     ...
;         for (int st = 0; st < 16; ++st) {
;             const int p = st >> 2, q = st & 3;
;             if (st < 14) VDMA(st + 2, (st + 2) % 3);
;             if (st < 14) asm volatile("s_waitcnt vmcnt(8)" ::: "memory");
;             else if (st == 14) asm volatile("s_waitcnt vmcnt(4)" ::: "memory");
;             else asm volatile("s_waitcnt vmcnt(0)" ::: "memory");
;             if (q == 0) {
; #pragma unroll
;                 for (int r = 0; r < 4; ++r) { accH[r] = 0; accL[r] = 0; } }
; #pragma unroll
;             for (int tp = 0; tp < 2; ++tp) {
;                 const v2i ao = TR4(ATL + (2 * q + tp) * 128 + 8 * s16), ah = TR4(ATL + 1024 + (2 * q + tp) * 128 + 8 * s16);
; #pragma unroll
;                 for (int r = 0; r < 4; ++r) {
;                     const v2i d = TR4(ldsb + BUF[st % 3] + 2048 * tp + roff[r]);
;                     accH[r] = __builtin_amdgcn_sdot8(d.x, ah.x, accH[r], false); accH[r] = __builtin_amdgcn_sdot8(d.y, ah.y, accH[r], false);
;                     accL[r] = __builtin_amdgcn_sdot8(d.x, ao.x, accL[r], false); accL[r] = __builtin_amdgcn_sdot8(d.y, ao.y, accL[r], false);
;                 }
;             }
;             asm volatile("s_waitcnt lgkmcnt(0)" ::: "memory");
;             if (q == 3) {
; #pragma unroll
;                 for (int r = 0; r < 4; ++r) STASH[256 * p + 16 * (grp + 4 * r) + pc] = f2bf(asc * (float)(2 * ((accH[r] << 4) + accL[r]) + sa));
;             }
;         }
	v_add_u32_e32 v54, s77, v59
	v_add_u32_e32 v55, s77, v60
	v_add_u32_e32 v56, s77, v61
	v_add_u32_e32 v57, s77, v62
	ds_read_b64_tr_b4 v[50:51], v160 offset:128
	ds_read_b64_tr_b4 v[52:53], v160 offset:1152
	ds_read_b64_tr_b4 v[130:131], v54
	ds_read_b64_tr_b4 v[132:133], v55
	ds_read_b64_tr_b4 v[134:135], v56
	ds_read_b64_tr_b4 v[136:137], v57
	s_waitcnt lgkmcnt(12)
	v_dot8c_i32_i4_e32 v38, v122, v48
	v_dot8c_i32_i4_e32 v39, v122, v46
	v_dot8c_i32_i4_e32 v40, v124, v48
	v_dot8c_i32_i4_e32 v41, v124, v46
	v_dot8c_i32_i4_e32 v42, v126, v48
	v_dot8c_i32_i4_e32 v43, v126, v46
	v_dot8c_i32_i4_e32 v44, v128, v48
	v_dot8c_i32_i4_e32 v45, v128, v46
	v_dot8c_i32_i4_e32 v38, v123, v49
	v_dot8c_i32_i4_e32 v39, v123, v47
	v_dot8c_i32_i4_e32 v40, v125, v49
	v_dot8c_i32_i4_e32 v41, v125, v47
	v_dot8c_i32_i4_e32 v42, v127, v49
	v_dot8c_i32_i4_e32 v43, v127, v47
	v_dot8c_i32_i4_e32 v44, v129, v49
	v_dot8c_i32_i4_e32 v45, v129, v47
	v_and_b32_e32 v78, 0xffff, v32
	v_lshrrev_b32_e32 v79, 16, v32
	v_lshl_add_u32 v78, v78, 7, v152
	v_lshl_add_u32 v79, v79, 7, v153
	s_mov_b32 m0, s76
	s_add_i32 s43, s76, 0x400
	global_load_lds_dwordx4 v78, s[50:51]
	s_mov_b32 m0, s43
	s_nop 0
	global_load_lds_dwordx4 v79, s[50:51]
	s_waitcnt vmcnt(8)
	v_add_u32_e32 v54, s78, v59
	v_add_u32_e32 v55, s78, v60
	v_add_u32_e32 v56, s78, v61
	v_add_u32_e32 v57, s78, v62
	ds_read_b64_tr_b4 v[46:47], v160 offset:256
	ds_read_b64_tr_b4 v[48:49], v160 offset:1280
	ds_read_b64_tr_b4 v[122:123], v54
	ds_read_b64_tr_b4 v[124:125], v55
	ds_read_b64_tr_b4 v[126:127], v56
	ds_read_b64_tr_b4 v[128:129], v57
	s_waitcnt lgkmcnt(6)
	v_dot8c_i32_i4_e32 v38, v130, v52
	v_dot8c_i32_i4_e32 v39, v130, v50
	v_dot8c_i32_i4_e32 v40, v132, v52
	v_dot8c_i32_i4_e32 v41, v132, v50
	v_dot8c_i32_i4_e32 v42, v134, v52
	v_dot8c_i32_i4_e32 v43, v134, v50
	v_dot8c_i32_i4_e32 v44, v136, v52
	v_dot8c_i32_i4_e32 v45, v136, v50
	v_dot8c_i32_i4_e32 v38, v131, v53
	v_dot8c_i32_i4_e32 v39, v131, v51
	v_dot8c_i32_i4_e32 v40, v133, v53
	v_dot8c_i32_i4_e32 v41, v133, v51
	v_dot8c_i32_i4_e32 v42, v135, v53
	v_dot8c_i32_i4_e32 v43, v135, v51
	v_dot8c_i32_i4_e32 v44, v137, v53
	v_dot8c_i32_i4_e32 v45, v137, v51
	v_and_b32_e32 v78, 0xffff, v33
	v_lshrrev_b32_e32 v79, 16, v33
	v_lshl_add_u32 v78, v78, 7, v152
	v_lshl_add_u32 v79, v79, 7, v153
	s_mov_b32 m0, s77
	s_add_i32 s43, s77, 0x400
	global_load_lds_dwordx4 v78, s[50:51]
	s_mov_b32 m0, s43
	s_nop 0
	global_load_lds_dwordx4 v79, s[50:51]
	s_waitcnt vmcnt(8)
	v_add_u32_e32 v54, s79, v59
	v_add_u32_e32 v55, s79, v60
	v_add_u32_e32 v56, s79, v61
	v_add_u32_e32 v57, s79, v62
	ds_read_b64_tr_b4 v[50:51], v160 offset:384
	ds_read_b64_tr_b4 v[52:53], v160 offset:1408
	ds_read_b64_tr_b4 v[130:131], v54
	ds_read_b64_tr_b4 v[132:133], v55
	ds_read_b64_tr_b4 v[134:135], v56
	ds_read_b64_tr_b4 v[136:137], v57
	s_waitcnt lgkmcnt(6)
	v_dot8c_i32_i4_e32 v38, v122, v48
	v_dot8c_i32_i4_e32 v39, v122, v46
	v_dot8c_i32_i4_e32 v40, v124, v48
	v_dot8c_i32_i4_e32 v41, v124, v46
	v_dot8c_i32_i4_e32 v42, v126, v48
	v_dot8c_i32_i4_e32 v43, v126, v46
	v_dot8c_i32_i4_e32 v44, v128, v48
	v_dot8c_i32_i4_e32 v45, v128, v46
	v_dot8c_i32_i4_e32 v38, v123, v49
	v_dot8c_i32_i4_e32 v39, v123, v47
	v_dot8c_i32_i4_e32 v40, v125, v49
	v_dot8c_i32_i4_e32 v41, v125, v47
	v_dot8c_i32_i4_e32 v42, v127, v49
	v_dot8c_i32_i4_e32 v43, v127, v47
	v_dot8c_i32_i4_e32 v44, v129, v49
	v_dot8c_i32_i4_e32 v45, v129, v47
	s_waitcnt lgkmcnt(15)
	v_and_b32_e32 v78, 0xffff, v18
	v_lshrrev_b32_e32 v79, 16, v18
	v_lshl_add_u32 v78, v78, 7, v150
	v_lshl_add_u32 v79, v79, 7, v151
	s_mov_b32 m0, s78
	s_add_i32 s43, s78, 0x400
	global_load_lds_dwordx4 v78, s[50:51]
	s_mov_b32 m0, s43
	s_nop 0
	global_load_lds_dwordx4 v79, s[50:51]
	s_waitcnt vmcnt(8)
	v_add_u32_e32 v54, s98, v59
	v_add_u32_e32 v55, s98, v60
	v_add_u32_e32 v56, s98, v61
	v_add_u32_e32 v57, s98, v62
	ds_read_b64_tr_b4 v[46:47], v160 offset:512
	ds_read_b64_tr_b4 v[48:49], v160 offset:1536
	ds_read_b64_tr_b4 v[122:123], v54
	ds_read_b64_tr_b4 v[124:125], v55
	ds_read_b64_tr_b4 v[126:127], v56
	ds_read_b64_tr_b4 v[128:129], v57
	s_waitcnt lgkmcnt(6)
	v_dot8c_i32_i4_e32 v38, v130, v52
	v_dot8c_i32_i4_e32 v39, v130, v50
	v_dot8c_i32_i4_e32 v40, v132, v52
	v_dot8c_i32_i4_e32 v41, v132, v50
	v_dot8c_i32_i4_e32 v42, v134, v52
	v_dot8c_i32_i4_e32 v43, v134, v50
	v_dot8c_i32_i4_e32 v44, v136, v52
	v_dot8c_i32_i4_e32 v45, v136, v50
	v_dot8c_i32_i4_e32 v38, v131, v53
	v_dot8c_i32_i4_e32 v39, v131, v51
	v_dot8c_i32_i4_e32 v40, v133, v53
	v_dot8c_i32_i4_e32 v41, v133, v51
	v_dot8c_i32_i4_e32 v42, v135, v53
	v_dot8c_i32_i4_e32 v43, v135, v51
	v_dot8c_i32_i4_e32 v44, v137, v53
	v_dot8c_i32_i4_e32 v45, v137, v51
	v_and_b32_e32 v78, 0xffff, v19
	v_lshrrev_b32_e32 v79, 16, v19
	v_lshl_add_u32 v78, v78, 7, v150
	v_lshl_add_u32 v79, v79, 7, v151
	s_mov_b32 m0, s79
	s_add_i32 s43, s79, 0x400
	global_load_lds_dwordx4 v78, s[50:51]
	s_mov_b32 m0, s43
	s_nop 0
	global_load_lds_dwordx4 v79, s[50:51]
	s_waitcnt vmcnt(8)
	v_add_u32_e32 v54, s99, v59
	v_add_u32_e32 v55, s99, v60
	v_add_u32_e32 v56, s99, v61
	v_add_u32_e32 v57, s99, v62
	ds_read_b64_tr_b4 v[50:51], v160 offset:640
	ds_read_b64_tr_b4 v[52:53], v160 offset:1664
	ds_read_b64_tr_b4 v[130:131], v54
	ds_read_b64_tr_b4 v[132:133], v55
	ds_read_b64_tr_b4 v[134:135], v56
	ds_read_b64_tr_b4 v[136:137], v57
	s_waitcnt lgkmcnt(6)
	v_dot8c_i32_i4_e32 v38, v122, v48
	v_dot8c_i32_i4_e32 v39, v122, v46
	v_dot8c_i32_i4_e32 v40, v124, v48
	v_dot8c_i32_i4_e32 v41, v124, v46
	v_dot8c_i32_i4_e32 v42, v126, v48
	v_dot8c_i32_i4_e32 v43, v126, v46
	v_dot8c_i32_i4_e32 v44, v128, v48
	v_dot8c_i32_i4_e32 v45, v128, v46
	v_dot8c_i32_i4_e32 v38, v123, v49
	v_dot8c_i32_i4_e32 v39, v123, v47
	v_dot8c_i32_i4_e32 v40, v125, v49
	v_dot8c_i32_i4_e32 v41, v125, v47
	v_dot8c_i32_i4_e32 v42, v127, v49
	v_dot8c_i32_i4_e32 v43, v127, v47
	v_dot8c_i32_i4_e32 v44, v129, v49
	v_dot8c_i32_i4_e32 v45, v129, v47
	s_waitcnt lgkmcnt(15)
; #define LAS __attribute__((address_space(3)))
; __device__ __forceinline__ bf16 f2bf(float f) { return (bf16)f2bfu(f); }
; __device__ __forceinline__ void peer_v_tokens(int j, const LAS unsigned short* EL, const LAS unsigned char* AL  , const LAS float* ASC  , const LAS int* SAL  , ...
;     ...
;         for (int m = 0; m < 2; ++m) {
;             const int idx = lane + 64 * m, tau = idx >> 4, sr = idx & 15, k = 16 * (sr & 7) + 2 * tau + (sr >> 3);
;             const int aq = (int)*(const LAS signed char*)(AL + tl * 128 + k); const int tq = aq + 8;
;             const unsigned lo = (((unsigned)tq & 15u) ^ 8u) * 0x11111111u, hi = ((unsigned)(tq >> 4) & 15u) * 0x11111111u;
;             typedef unsigned u2v __attribute__((ext_vector_type(2)));
;             u2v l2; l2.x = lo; l2.y = lo; u2v h2; h2.x = hi; h2.y = hi;
;             *(LAS u2v*)(ATL + 8 * idx) = l2; *(LAS u2v*)(ATL + 1024 + 8 * idx) = h2;
;         }
;     ...
;         for (int st = 0; st < 16; ++st) {
;             const int p = st >> 2, q = st & 3;
;             if (st < 14) VDMA(st + 2, (st + 2) % 3);
;             if (st < 14) asm volatile("s_waitcnt vmcnt(8)" ::: "memory");
;             else if (st == 14) asm volatile("s_waitcnt vmcnt(4)" ::: "memory");
;             else asm volatile("s_waitcnt vmcnt(0)" ::: "memory");
;             if (q == 0) {
; #pragma unroll
;                 for (int r = 0; r < 4; ++r) { accH[r] = 0; accL[r] = 0; } }
; #pragma unroll
;             for (int tp = 0; tp < 2; ++tp) {
;                 const v2i ao = TR4(ATL + (2 * q + tp) * 128 + 8 * s16), ah = TR4(ATL + 1024 + (2 * q + tp) * 128 + 8 * s16);
; #pragma unroll
;                 for (int r = 0; r < 4; ++r) {
;                     const v2i d = TR4(ldsb + BUF[st % 3] + 2048 * tp + roff[r]);
;                     accH[r] = __builtin_amdgcn_sdot8(d.x, ah.x, accH[r], false); accH[r] = __builtin_amdgcn_sdot8(d.y, ah.y, accH[r], false);
;                     accL[r] = __builtin_amdgcn_sdot8(d.x, ao.x, accL[r], false); accL[r] = __builtin_amdgcn_sdot8(d.y, ao.y, accL[r], false);
;                 }
;             }
;             asm volatile("s_waitcnt lgkmcnt(0)" ::: "memory");
;             if (q == 3) {
; #pragma unroll
;                 for (int r = 0; r < 4; ++r) STASH[256 * p + 16 * (grp + 4 * r) + pc] = f2bf(asc * (float)(2 * ((accH[r] << 4) + accL[r]) + sa));
;             }
;         }
	v_add_u32_e32 v143, 8, v139
	v_and_b32_e32 v142, 15, v143
	v_xor_b32_e32 v142, 8, v142
	v_bfe_u32 v144, v143, 4, 4
	v_mul_lo_u32 v142, v142, s92
	v_mul_lo_u32 v144, v144, s92
	v_mov_b32_e32 v143, v142
	v_mov_b32_e32 v145, v144
	ds_write2st64_b64 v159, v[142:143], v[144:145] offset1:2
	v_and_b32_e32 v78, 0xffff, v20
	v_lshrrev_b32_e32 v79, 16, v20
	v_lshl_add_u32 v78, v78, 7, v150
	v_lshl_add_u32 v79, v79, 7, v151
	s_mov_b32 m0, s98
	s_add_i32 s43, s98, 0x400
	global_load_lds_dwordx4 v78, s[50:51]
	s_mov_b32 m0, s43
	s_nop 0
	global_load_lds_dwordx4 v79, s[50:51]
	s_waitcnt vmcnt(8)
	v_add_u32_e32 v54, s76, v59
	v_add_u32_e32 v55, s76, v60
	v_add_u32_e32 v56, s76, v61
	v_add_u32_e32 v57, s76, v62
	ds_read_b64_tr_b4 v[46:47], v160 offset:768
	ds_read_b64_tr_b4 v[48:49], v160 offset:1792
	ds_read_b64_tr_b4 v[122:123], v54
	ds_read_b64_tr_b4 v[124:125], v55
	ds_read_b64_tr_b4 v[126:127], v56
	ds_read_b64_tr_b4 v[128:129], v57
	s_waitcnt lgkmcnt(7)
	v_dot8c_i32_i4_e32 v38, v130, v52
	v_dot8c_i32_i4_e32 v39, v130, v50
	v_dot8c_i32_i4_e32 v40, v132, v52
	v_dot8c_i32_i4_e32 v41, v132, v50
	v_dot8c_i32_i4_e32 v42, v134, v52
	v_dot8c_i32_i4_e32 v43, v134, v50
	v_dot8c_i32_i4_e32 v44, v136, v52
	v_dot8c_i32_i4_e32 v45, v136, v50
	v_dot8c_i32_i4_e32 v38, v131, v53
	v_dot8c_i32_i4_e32 v39, v131, v51
	v_dot8c_i32_i4_e32 v40, v133, v53
	v_dot8c_i32_i4_e32 v41, v133, v51
	v_dot8c_i32_i4_e32 v42, v135, v53
	v_dot8c_i32_i4_e32 v43, v135, v51
	v_dot8c_i32_i4_e32 v44, v137, v53
	v_dot8c_i32_i4_e32 v45, v137, v51
	v_and_b32_e32 v78, 0xffff, v21
	v_lshrrev_b32_e32 v79, 16, v21
	v_lshl_add_u32 v78, v78, 7, v150
	v_lshl_add_u32 v79, v79, 7, v151
	s_mov_b32 m0, s99
	s_add_i32 s43, s99, 0x400
	global_load_lds_dwordx4 v78, s[50:51]
	s_mov_b32 m0, s43
	s_nop 0
	global_load_lds_dwordx4 v79, s[50:51]
	s_waitcnt vmcnt(8)
	v_add_u32_e32 v54, s77, v59
	v_add_u32_e32 v55, s77, v60
	v_add_u32_e32 v56, s77, v61
	v_add_u32_e32 v57, s77, v62
	ds_read_b64_tr_b4 v[50:51], v160 offset:896
	ds_read_b64_tr_b4 v[52:53], v160 offset:1920
	ds_read_b64_tr_b4 v[130:131], v54
	ds_read_b64_tr_b4 v[132:133], v55
	ds_read_b64_tr_b4 v[134:135], v56
	ds_read_b64_tr_b4 v[136:137], v57
	s_waitcnt lgkmcnt(6)
	v_dot8c_i32_i4_e32 v38, v122, v48
	v_dot8c_i32_i4_e32 v39, v122, v46
	v_dot8c_i32_i4_e32 v40, v124, v48
	v_dot8c_i32_i4_e32 v41, v124, v46
	v_dot8c_i32_i4_e32 v42, v126, v48
	v_dot8c_i32_i4_e32 v43, v126, v46
	v_dot8c_i32_i4_e32 v44, v128, v48
	v_dot8c_i32_i4_e32 v45, v128, v46
	v_dot8c_i32_i4_e32 v38, v123, v49
	v_dot8c_i32_i4_e32 v39, v123, v47
	v_dot8c_i32_i4_e32 v40, v125, v49
	v_dot8c_i32_i4_e32 v41, v125, v47
	v_dot8c_i32_i4_e32 v42, v127, v49
	v_dot8c_i32_i4_e32 v43, v127, v47
	v_dot8c_i32_i4_e32 v44, v129, v49
	v_dot8c_i32_i4_e32 v45, v129, v47
	v_and_b32_e32 v78, 0xffff, v22
	v_lshrrev_b32_e32 v79, 16, v22
	v_lshl_add_u32 v78, v78, 7, v150
	v_lshl_add_u32 v79, v79, 7, v151
	s_mov_b32 m0, s76
	s_add_i32 s43, s76, 0x400
	global_load_lds_dwordx4 v78, s[50:51]
	s_mov_b32 m0, s43
	s_nop 0
	global_load_lds_dwordx4 v79, s[50:51]
	s_waitcnt vmcnt(8)
	v_add_u32_e32 v54, s78, v59
	v_add_u32_e32 v55, s78, v60
	v_add_u32_e32 v56, s78, v61
	v_add_u32_e32 v57, s78, v62
	ds_read_b64_tr_b4 v[46:47], v160
	ds_read_b64_tr_b4 v[48:49], v160 offset:1024
	ds_read_b64_tr_b4 v[122:123], v54
	ds_read_b64_tr_b4 v[124:125], v55
	ds_read_b64_tr_b4 v[126:127], v56
	ds_read_b64_tr_b4 v[128:129], v57
	s_waitcnt lgkmcnt(6)
	v_dot8c_i32_i4_e32 v38, v130, v52
	v_dot8c_i32_i4_e32 v39, v130, v50
	v_dot8c_i32_i4_e32 v40, v132, v52
	v_dot8c_i32_i4_e32 v41, v132, v50
	v_dot8c_i32_i4_e32 v42, v134, v52
	v_dot8c_i32_i4_e32 v43, v134, v50
	v_dot8c_i32_i4_e32 v44, v136, v52
	v_dot8c_i32_i4_e32 v45, v136, v50
	v_dot8c_i32_i4_e32 v38, v131, v53
	v_dot8c_i32_i4_e32 v39, v131, v51
	v_dot8c_i32_i4_e32 v40, v133, v53
	v_dot8c_i32_i4_e32 v41, v133, v51
	v_dot8c_i32_i4_e32 v42, v135, v53
	v_dot8c_i32_i4_e32 v43, v135, v51
	v_dot8c_i32_i4_e32 v44, v137, v53
	v_dot8c_i32_i4_e32 v45, v137, v51
	s_nop 3
	s_waitcnt lgkmcnt(15)
	v_lshlrev_b32_e32 v38, 5, v38
	v_lshlrev_b32_e32 v39, 1, v39
	v_add3_u32 v38, v39, v229, v38
	v_cvt_f32_i32_e32 v38, v38
	v_mul_f32_e32 v38, v228, v38
	v_lshlrev_b32_e32 v40, 5, v40
	v_lshlrev_b32_e32 v41, 1, v41
	v_add3_u32 v40, v41, v229, v40
	v_cvt_f32_i32_e32 v40, v40
	v_mul_f32_e32 v40, v228, v40
	v_lshlrev_b32_e32 v42, 5, v42
	v_lshlrev_b32_e32 v43, 1, v43
	v_add3_u32 v42, v43, v229, v42
	v_cvt_f32_i32_e32 v42, v42
	v_mul_f32_e32 v42, v228, v42
	v_lshlrev_b32_e32 v44, 5, v44
	v_lshlrev_b32_e32 v45, 1, v45
	v_add3_u32 v44, v45, v229, v44
	v_cvt_f32_i32_e32 v44, v44
	v_mul_f32_e32 v44, v228, v44
	v_cvt_pk_bf16_f32 v172, v38, v40
	v_cvt_pk_bf16_f32 v173, v42, v44
	v_add_u32_e32 v147, 8, v140
	v_and_b32_e32 v146, 15, v147
	v_xor_b32_e32 v146, 8, v146
	v_bfe_u32 v148, v147, 4, 4
	v_mul_lo_u32 v146, v146, s92
	v_mul_lo_u32 v148, v148, s92
	v_mov_b32_e32 v147, v146
	v_mov_b32_e32 v149, v148
	ds_write2st64_b64 v77, v[146:147], v[148:149] offset1:2
	v_add_u32_e32 v138, 0x400, v74
	ds_read_u8 v139, v138
	v_add_u32_e32 v141, 0x400, v73
	ds_read_u8 v140, v141
	s_mov_b32 s43, s67
	v_mov_b32_e32 v138, s43
	ds_read2st64_b32 v[228:229], v138 offset1:1
	ds_read_b128 v[26:29], v227 offset:2048
	ds_read_b128 v[30:33], v227 offset:2064
	v_mov_b32_e32 v38, 0
	v_mov_b32_e32 v39, 0
	v_mov_b32_e32 v40, 0
	v_mov_b32_e32 v41, 0
	v_mov_b32_e32 v42, 0
	v_mov_b32_e32 v43, 0
	v_mov_b32_e32 v44, 0
	v_mov_b32_e32 v45, 0
	v_and_b32_e32 v78, 0xffff, v23
	v_lshrrev_b32_e32 v79, 16, v23
	v_lshl_add_u32 v78, v78, 7, v150
	v_lshl_add_u32 v79, v79, 7, v151
	s_mov_b32 m0, s77
	s_add_i32 s43, s77, 0x400
	global_load_lds_dwordx4 v78, s[50:51]
	s_mov_b32 m0, s43
	s_nop 0
	global_load_lds_dwordx4 v79, s[50:51]
	s_waitcnt vmcnt(8)
; __device__ __forceinline__ bf16 f2bf(float f) { return (bf16)f2bfu(f); }
; #define TR4(p_) __builtin_amdgcn_ds_read_tr4_b64_v2i32((LAS v2i*)(p_))
; #define VDMA(st_, k_) do { _Pragma("unroll") for (int i_ = 0; i_ < 4; ++i_) { \
;         const unsigned off_ = (unsigned)((st_) >> 2) * (16384u * 128u) + (PE_ID(E, 4 * ((st_) & 3) + i_) << 7) + ((i_ & 1) ? cx1 : cx0); \
;         __builtin_amdgcn_global_load_lds((const unsigned*)(V4 + off_), (LAS unsigned*)(ldsb + BUF[k_] + 1024 * i_), 16, 0, 0); } } while (0)
; __device__ __forceinline__ void peer_v_tokens(int j, const LAS unsigned short* EL, const LAS unsigned char* AL  , const LAS float* ASC  , const LAS int* SAL  , ...
;     ...
;         for (int st = 0; st < 16; ++st) {
;             const int p = st >> 2, q = st & 3;
;             if (st < 14) VDMA(st + 2, (st + 2) % 3);
;             if (st < 14) asm volatile("s_waitcnt vmcnt(8)" ::: "memory");
;             else if (st == 14) asm volatile("s_waitcnt vmcnt(4)" ::: "memory");
;             else asm volatile("s_waitcnt vmcnt(0)" ::: "memory");
;             if (q == 0) {
; #pragma unroll
;                 for (int r = 0; r < 4; ++r) { accH[r] = 0; accL[r] = 0; } }
; #pragma unroll
;             for (int tp = 0; tp < 2; ++tp) {
;                 const v2i ao = TR4(ATL + (2 * q + tp) * 128 + 8 * s16), ah = TR4(ATL + 1024 + (2 * q + tp) * 128 + 8 * s16);
; #pragma unroll
;                 for (int r = 0; r < 4; ++r) {
;                     const v2i d = TR4(ldsb + BUF[st % 3] + 2048 * tp + roff[r]);
;                     accH[r] = __builtin_amdgcn_sdot8(d.x, ah.x, accH[r], false); accH[r] = __builtin_amdgcn_sdot8(d.y, ah.y, accH[r], false);
;                     accL[r] = __builtin_amdgcn_sdot8(d.x, ao.x, accL[r], false); accL[r] = __builtin_amdgcn_sdot8(d.y, ao.y, accL[r], false);
;                 }
;             }
;             asm volatile("s_waitcnt lgkmcnt(0)" ::: "memory");
;             if (q == 3) {
; #pragma unroll
;                 for (int r = 0; r < 4; ++r) STASH[256 * p + 16 * (grp + 4 * r) + pc] = f2bf(asc * (float)(2 * ((accH[r] << 4) + accL[r]) + sa));
;             }
;         }
	v_add_u32_e32 v54, s79, v59
	v_add_u32_e32 v55, s79, v60
	v_add_u32_e32 v56, s79, v61
	v_add_u32_e32 v57, s79, v62
	ds_read_b64_tr_b4 v[50:51], v160 offset:128
	ds_read_b64_tr_b4 v[52:53], v160 offset:1152
	ds_read_b64_tr_b4 v[130:131], v54
	ds_read_b64_tr_b4 v[132:133], v55
	ds_read_b64_tr_b4 v[134:135], v56
	ds_read_b64_tr_b4 v[136:137], v57
	s_waitcnt lgkmcnt(12)
	v_dot8c_i32_i4_e32 v38, v122, v48
	v_dot8c_i32_i4_e32 v39, v122, v46
	v_dot8c_i32_i4_e32 v40, v124, v48
	v_dot8c_i32_i4_e32 v41, v124, v46
	v_dot8c_i32_i4_e32 v42, v126, v48
	v_dot8c_i32_i4_e32 v43, v126, v46
	v_dot8c_i32_i4_e32 v44, v128, v48
	v_dot8c_i32_i4_e32 v45, v128, v46
	v_dot8c_i32_i4_e32 v38, v123, v49
	v_dot8c_i32_i4_e32 v39, v123, v47
	v_dot8c_i32_i4_e32 v40, v125, v49
	v_dot8c_i32_i4_e32 v41, v125, v47
	v_dot8c_i32_i4_e32 v42, v127, v49
	v_dot8c_i32_i4_e32 v43, v127, v47
	v_dot8c_i32_i4_e32 v44, v129, v49
	v_dot8c_i32_i4_e32 v45, v129, v47
	v_and_b32_e32 v78, 0xffff, v24
	v_lshrrev_b32_e32 v79, 16, v24
	v_lshl_add_u32 v78, v78, 7, v150
	v_lshl_add_u32 v79, v79, 7, v151
	s_mov_b32 m0, s78
	s_add_i32 s43, s78, 0x400
	global_load_lds_dwordx4 v78, s[50:51]
	s_mov_b32 m0, s43
	s_nop 0
	global_load_lds_dwordx4 v79, s[50:51]
	s_waitcnt vmcnt(8)
	v_add_u32_e32 v54, s98, v59
	v_add_u32_e32 v55, s98, v60
	v_add_u32_e32 v56, s98, v61
	v_add_u32_e32 v57, s98, v62
	ds_read_b64_tr_b4 v[46:47], v160 offset:256
	ds_read_b64_tr_b4 v[48:49], v160 offset:1280
	ds_read_b64_tr_b4 v[122:123], v54
	ds_read_b64_tr_b4 v[124:125], v55
	ds_read_b64_tr_b4 v[126:127], v56
	ds_read_b64_tr_b4 v[128:129], v57
	s_waitcnt lgkmcnt(6)
	v_dot8c_i32_i4_e32 v38, v130, v52
	v_dot8c_i32_i4_e32 v39, v130, v50
	v_dot8c_i32_i4_e32 v40, v132, v52
	v_dot8c_i32_i4_e32 v41, v132, v50
	v_dot8c_i32_i4_e32 v42, v134, v52
	v_dot8c_i32_i4_e32 v43, v134, v50
	v_dot8c_i32_i4_e32 v44, v136, v52
	v_dot8c_i32_i4_e32 v45, v136, v50
	v_dot8c_i32_i4_e32 v38, v131, v53
	v_dot8c_i32_i4_e32 v39, v131, v51
	v_dot8c_i32_i4_e32 v40, v133, v53
	v_dot8c_i32_i4_e32 v41, v133, v51
	v_dot8c_i32_i4_e32 v42, v135, v53
	v_dot8c_i32_i4_e32 v43, v135, v51
	v_dot8c_i32_i4_e32 v44, v137, v53
	v_dot8c_i32_i4_e32 v45, v137, v51
	v_and_b32_e32 v78, 0xffff, v25
	v_lshrrev_b32_e32 v79, 16, v25
	v_lshl_add_u32 v78, v78, 7, v150
	v_lshl_add_u32 v79, v79, 7, v151
	s_mov_b32 m0, s79
	s_add_i32 s43, s79, 0x400
	global_load_lds_dwordx4 v78, s[50:51]
	s_mov_b32 m0, s43
	s_nop 0
	global_load_lds_dwordx4 v79, s[50:51]
	s_waitcnt vmcnt(8)
	v_add_u32_e32 v54, s99, v59
	v_add_u32_e32 v55, s99, v60
	v_add_u32_e32 v56, s99, v61
	v_add_u32_e32 v57, s99, v62
	ds_read_b64_tr_b4 v[50:51], v160 offset:384
	ds_read_b64_tr_b4 v[52:53], v160 offset:1408
	ds_read_b64_tr_b4 v[130:131], v54
	ds_read_b64_tr_b4 v[132:133], v55
	ds_read_b64_tr_b4 v[134:135], v56
	ds_read_b64_tr_b4 v[136:137], v57
	s_waitcnt lgkmcnt(6)
	v_dot8c_i32_i4_e32 v38, v122, v48
	v_dot8c_i32_i4_e32 v39, v122, v46
	v_dot8c_i32_i4_e32 v40, v124, v48
	v_dot8c_i32_i4_e32 v41, v124, v46
	v_dot8c_i32_i4_e32 v42, v126, v48
	v_dot8c_i32_i4_e32 v43, v126, v46
	v_dot8c_i32_i4_e32 v44, v128, v48
	v_dot8c_i32_i4_e32 v45, v128, v46
	v_dot8c_i32_i4_e32 v38, v123, v49
	v_dot8c_i32_i4_e32 v39, v123, v47
	v_dot8c_i32_i4_e32 v40, v125, v49
	v_dot8c_i32_i4_e32 v41, v125, v47
	v_dot8c_i32_i4_e32 v42, v127, v49
	v_dot8c_i32_i4_e32 v43, v127, v47
	v_dot8c_i32_i4_e32 v44, v129, v49
	v_dot8c_i32_i4_e32 v45, v129, v47
	s_waitcnt lgkmcnt(15)
	v_and_b32_e32 v78, 0xffff, v26
	v_lshrrev_b32_e32 v79, 16, v26
	v_lshl_add_u32 v78, v78, 7, v150
	v_lshl_add_u32 v79, v79, 7, v151
	s_mov_b32 m0, s98
	s_add_i32 s43, s98, 0x400
	global_load_lds_dwordx4 v78, s[50:51]
	s_mov_b32 m0, s43
	s_nop 0
	global_load_lds_dwordx4 v79, s[50:51]
	s_waitcnt vmcnt(8)
	v_add_u32_e32 v54, s76, v59
	v_add_u32_e32 v55, s76, v60
	v_add_u32_e32 v56, s76, v61
	v_add_u32_e32 v57, s76, v62
	ds_read_b64_tr_b4 v[46:47], v160 offset:512
	ds_read_b64_tr_b4 v[48:49], v160 offset:1536
	ds_read_b64_tr_b4 v[122:123], v54
	ds_read_b64_tr_b4 v[124:125], v55
	ds_read_b64_tr_b4 v[126:127], v56
	ds_read_b64_tr_b4 v[128:129], v57
	s_waitcnt lgkmcnt(6)
	v_dot8c_i32_i4_e32 v38, v130, v52
	v_dot8c_i32_i4_e32 v39, v130, v50
	v_dot8c_i32_i4_e32 v40, v132, v52
	v_dot8c_i32_i4_e32 v41, v132, v50
	v_dot8c_i32_i4_e32 v42, v134, v52
	v_dot8c_i32_i4_e32 v43, v134, v50
	v_dot8c_i32_i4_e32 v44, v136, v52
	v_dot8c_i32_i4_e32 v45, v136, v50
	v_dot8c_i32_i4_e32 v38, v131, v53
	v_dot8c_i32_i4_e32 v39, v131, v51
	v_dot8c_i32_i4_e32 v40, v133, v53
	v_dot8c_i32_i4_e32 v41, v133, v51
	v_dot8c_i32_i4_e32 v42, v135, v53
	v_dot8c_i32_i4_e32 v43, v135, v51
	v_dot8c_i32_i4_e32 v44, v137, v53
	v_dot8c_i32_i4_e32 v45, v137, v51
	v_and_b32_e32 v78, 0xffff, v27
	v_lshrrev_b32_e32 v79, 16, v27
	v_lshl_add_u32 v78, v78, 7, v150
	v_lshl_add_u32 v79, v79, 7, v151
	s_mov_b32 m0, s99
	s_add_i32 s43, s99, 0x400
	global_load_lds_dwordx4 v78, s[50:51]
	s_mov_b32 m0, s43
	s_nop 0
	global_load_lds_dwordx4 v79, s[50:51]
	s_waitcnt vmcnt(8)
	v_add_u32_e32 v54, s77, v59
	v_add_u32_e32 v55, s77, v60
	v_add_u32_e32 v56, s77, v61
	v_add_u32_e32 v57, s77, v62
	ds_read_b64_tr_b4 v[50:51], v160 offset:640
	ds_read_b64_tr_b4 v[52:53], v160 offset:1664
	ds_read_b64_tr_b4 v[130:131], v54
	ds_read_b64_tr_b4 v[132:133], v55
	ds_read_b64_tr_b4 v[134:135], v56
	ds_read_b64_tr_b4 v[136:137], v57
	s_waitcnt lgkmcnt(6)
	v_dot8c_i32_i4_e32 v38, v122, v48
	v_dot8c_i32_i4_e32 v39, v122, v46
	v_dot8c_i32_i4_e32 v40, v124, v48
	v_dot8c_i32_i4_e32 v41, v124, v46
	v_dot8c_i32_i4_e32 v42, v126, v48
	v_dot8c_i32_i4_e32 v43, v126, v46
	v_dot8c_i32_i4_e32 v44, v128, v48
	v_dot8c_i32_i4_e32 v45, v128, v46
	v_dot8c_i32_i4_e32 v38, v123, v49
	v_dot8c_i32_i4_e32 v39, v123, v47
	v_dot8c_i32_i4_e32 v40, v125, v49
	v_dot8c_i32_i4_e32 v41, v125, v47
	v_dot8c_i32_i4_e32 v42, v127, v49
	v_dot8c_i32_i4_e32 v43, v127, v47
	v_dot8c_i32_i4_e32 v44, v129, v49
	v_dot8c_i32_i4_e32 v45, v129, v47
	s_waitcnt lgkmcnt(15)
; #define LAS __attribute__((address_space(3)))
; __device__ __forceinline__ bf16 f2bf(float f) { return (bf16)f2bfu(f); }
; __device__ __forceinline__ void peer_v_tokens(int j, const LAS unsigned short* EL, const LAS unsigned char* AL  , const LAS float* ASC  , const LAS int* SAL  , ...
;     ...
;         for (int m = 0; m < 2; ++m) {
;             const int idx = lane + 64 * m, tau = idx >> 4, sr = idx & 15, k = 16 * (sr & 7) + 2 * tau + (sr >> 3);
;             const int aq = (int)*(const LAS signed char*)(AL + tl * 128 + k); const int tq = aq + 8;
;             const unsigned lo = (((unsigned)tq & 15u) ^ 8u) * 0x11111111u, hi = ((unsigned)(tq >> 4) & 15u) * 0x11111111u;
;             typedef unsigned u2v __attribute__((ext_vector_type(2)));
;             u2v l2; l2.x = lo; l2.y = lo; u2v h2; h2.x = hi; h2.y = hi;
;             *(LAS u2v*)(ATL + 8 * idx) = l2; *(LAS u2v*)(ATL + 1024 + 8 * idx) = h2;
;         }
;     ...
;         for (int st = 0; st < 16; ++st) {
;             const int p = st >> 2, q = st & 3;
;             if (st < 14) VDMA(st + 2, (st + 2) % 3);
;             if (st < 14) asm volatile("s_waitcnt vmcnt(8)" ::: "memory");
;             else if (st == 14) asm volatile("s_waitcnt vmcnt(4)" ::: "memory");
;             else asm volatile("s_waitcnt vmcnt(0)" ::: "memory");
;             if (q == 0) {
; #pragma unroll
;                 for (int r = 0; r < 4; ++r) { accH[r] = 0; accL[r] = 0; } }
; #pragma unroll
;             for (int tp = 0; tp < 2; ++tp) {
;                 const v2i ao = TR4(ATL + (2 * q + tp) * 128 + 8 * s16), ah = TR4(ATL + 1024 + (2 * q + tp) * 128 + 8 * s16);
; #pragma unroll
;                 for (int r = 0; r < 4; ++r) {
;                     const v2i d = TR4(ldsb + BUF[st % 3] + 2048 * tp + roff[r]);
;                     accH[r] = __builtin_amdgcn_sdot8(d.x, ah.x, accH[r], false); accH[r] = __builtin_amdgcn_sdot8(d.y, ah.y, accH[r], false);
;                     accL[r] = __builtin_amdgcn_sdot8(d.x, ao.x, accL[r], false); accL[r] = __builtin_amdgcn_sdot8(d.y, ao.y, accL[r], false);
;                 }
;             }
;             asm volatile("s_waitcnt lgkmcnt(0)" ::: "memory");
;             if (q == 3) {
; #pragma unroll
;                 for (int r = 0; r < 4; ++r) STASH[256 * p + 16 * (grp + 4 * r) + pc] = f2bf(asc * (float)(2 * ((accH[r] << 4) + accL[r]) + sa));
;             }
;         }
	v_add_u32_e32 v143, 8, v139
	v_and_b32_e32 v142, 15, v143
	v_xor_b32_e32 v142, 8, v142
	v_bfe_u32 v144, v143, 4, 4
	v_mul_lo_u32 v142, v142, s92
	v_mul_lo_u32 v144, v144, s92
	v_mov_b32_e32 v143, v142
	v_mov_b32_e32 v145, v144
	ds_write2st64_b64 v159, v[142:143], v[144:145] offset1:2
	v_and_b32_e32 v78, 0xffff, v28
	v_lshrrev_b32_e32 v79, 16, v28
	v_lshl_add_u32 v78, v78, 7, v150
	v_lshl_add_u32 v79, v79, 7, v151
	s_mov_b32 m0, s76
	s_add_i32 s43, s76, 0x400
	global_load_lds_dwordx4 v78, s[50:51]
	s_mov_b32 m0, s43
	s_nop 0
	global_load_lds_dwordx4 v79, s[50:51]
	s_waitcnt vmcnt(8)
	v_add_u32_e32 v54, s78, v59
	v_add_u32_e32 v55, s78, v60
	v_add_u32_e32 v56, s78, v61
	v_add_u32_e32 v57, s78, v62
	ds_read_b64_tr_b4 v[46:47], v160 offset:768
	ds_read_b64_tr_b4 v[48:49], v160 offset:1792
	ds_read_b64_tr_b4 v[122:123], v54
	ds_read_b64_tr_b4 v[124:125], v55
	ds_read_b64_tr_b4 v[126:127], v56
	ds_read_b64_tr_b4 v[128:129], v57
	s_waitcnt lgkmcnt(7)
	v_dot8c_i32_i4_e32 v38, v130, v52
	v_dot8c_i32_i4_e32 v39, v130, v50
	v_dot8c_i32_i4_e32 v40, v132, v52
	v_dot8c_i32_i4_e32 v41, v132, v50
	v_dot8c_i32_i4_e32 v42, v134, v52
	v_dot8c_i32_i4_e32 v43, v134, v50
	v_dot8c_i32_i4_e32 v44, v136, v52
	v_dot8c_i32_i4_e32 v45, v136, v50
	v_dot8c_i32_i4_e32 v38, v131, v53
	v_dot8c_i32_i4_e32 v39, v131, v51
	v_dot8c_i32_i4_e32 v40, v133, v53
	v_dot8c_i32_i4_e32 v41, v133, v51
	v_dot8c_i32_i4_e32 v42, v135, v53
	v_dot8c_i32_i4_e32 v43, v135, v51
	v_dot8c_i32_i4_e32 v44, v137, v53
	v_dot8c_i32_i4_e32 v45, v137, v51
	v_and_b32_e32 v78, 0xffff, v29
	v_lshrrev_b32_e32 v79, 16, v29
	v_lshl_add_u32 v78, v78, 7, v150
	v_lshl_add_u32 v79, v79, 7, v151
	s_mov_b32 m0, s77
	s_add_i32 s43, s77, 0x400
	global_load_lds_dwordx4 v78, s[50:51]
	s_mov_b32 m0, s43
	s_nop 0
	global_load_lds_dwordx4 v79, s[50:51]
	s_waitcnt vmcnt(8)
	v_add_u32_e32 v54, s79, v59
	v_add_u32_e32 v55, s79, v60
	v_add_u32_e32 v56, s79, v61
	v_add_u32_e32 v57, s79, v62
	ds_read_b64_tr_b4 v[50:51], v160 offset:896
	ds_read_b64_tr_b4 v[52:53], v160 offset:1920
	ds_read_b64_tr_b4 v[130:131], v54
	ds_read_b64_tr_b4 v[132:133], v55
	ds_read_b64_tr_b4 v[134:135], v56
	ds_read_b64_tr_b4 v[136:137], v57
	s_waitcnt lgkmcnt(6)
	v_dot8c_i32_i4_e32 v38, v122, v48
	v_dot8c_i32_i4_e32 v39, v122, v46
	v_dot8c_i32_i4_e32 v40, v124, v48
	v_dot8c_i32_i4_e32 v41, v124, v46
	v_dot8c_i32_i4_e32 v42, v126, v48
	v_dot8c_i32_i4_e32 v43, v126, v46
	v_dot8c_i32_i4_e32 v44, v128, v48
	v_dot8c_i32_i4_e32 v45, v128, v46
	v_dot8c_i32_i4_e32 v38, v123, v49
	v_dot8c_i32_i4_e32 v39, v123, v47
	v_dot8c_i32_i4_e32 v40, v125, v49
	v_dot8c_i32_i4_e32 v41, v125, v47
	v_dot8c_i32_i4_e32 v42, v127, v49
	v_dot8c_i32_i4_e32 v43, v127, v47
	v_dot8c_i32_i4_e32 v44, v129, v49
	v_dot8c_i32_i4_e32 v45, v129, v47
	v_and_b32_e32 v78, 0xffff, v30
	v_lshrrev_b32_e32 v79, 16, v30
	v_lshl_add_u32 v78, v78, 7, v150
	v_lshl_add_u32 v79, v79, 7, v151
	s_mov_b32 m0, s78
	s_add_i32 s43, s78, 0x400
	global_load_lds_dwordx4 v78, s[50:51]
	s_mov_b32 m0, s43
	s_nop 0
	global_load_lds_dwordx4 v79, s[50:51]
	s_waitcnt vmcnt(8)
	v_add_u32_e32 v54, s98, v59
	v_add_u32_e32 v55, s98, v60
	v_add_u32_e32 v56, s98, v61
	v_add_u32_e32 v57, s98, v62
	ds_read_b64_tr_b4 v[46:47], v160
	ds_read_b64_tr_b4 v[48:49], v160 offset:1024
	ds_read_b64_tr_b4 v[122:123], v54
	ds_read_b64_tr_b4 v[124:125], v55
	ds_read_b64_tr_b4 v[126:127], v56
	ds_read_b64_tr_b4 v[128:129], v57
	s_waitcnt lgkmcnt(6)
	v_dot8c_i32_i4_e32 v38, v130, v52
	v_dot8c_i32_i4_e32 v39, v130, v50
	v_dot8c_i32_i4_e32 v40, v132, v52
	v_dot8c_i32_i4_e32 v41, v132, v50
	v_dot8c_i32_i4_e32 v42, v134, v52
	v_dot8c_i32_i4_e32 v43, v134, v50
	v_dot8c_i32_i4_e32 v44, v136, v52
	v_dot8c_i32_i4_e32 v45, v136, v50
	v_dot8c_i32_i4_e32 v38, v131, v53
	v_dot8c_i32_i4_e32 v39, v131, v51
	v_dot8c_i32_i4_e32 v40, v133, v53
	v_dot8c_i32_i4_e32 v41, v133, v51
	v_dot8c_i32_i4_e32 v42, v135, v53
	v_dot8c_i32_i4_e32 v43, v135, v51
	v_dot8c_i32_i4_e32 v44, v137, v53
	v_dot8c_i32_i4_e32 v45, v137, v51
	s_nop 3
	s_waitcnt lgkmcnt(15)
	v_lshlrev_b32_e32 v38, 5, v38
	v_lshlrev_b32_e32 v39, 1, v39
	v_add3_u32 v38, v39, v229, v38
	v_cvt_f32_i32_e32 v38, v38
	v_mul_f32_e32 v38, v228, v38
	v_lshlrev_b32_e32 v40, 5, v40
	v_lshlrev_b32_e32 v41, 1, v41
	v_add3_u32 v40, v41, v229, v40
	v_cvt_f32_i32_e32 v40, v40
	v_mul_f32_e32 v40, v228, v40
	v_lshlrev_b32_e32 v42, 5, v42
	v_lshlrev_b32_e32 v43, 1, v43
	v_add3_u32 v42, v43, v229, v42
	v_cvt_f32_i32_e32 v42, v42
	v_mul_f32_e32 v42, v228, v42
	v_lshlrev_b32_e32 v44, 5, v44
	v_lshlrev_b32_e32 v45, 1, v45
	v_add3_u32 v44, v45, v229, v44
	v_cvt_f32_i32_e32 v44, v44
	v_mul_f32_e32 v44, v228, v44
	v_cvt_pk_bf16_f32 v166, v38, v40
	v_cvt_pk_bf16_f32 v167, v42, v44
	v_add_u32_e32 v147, 8, v140
	v_and_b32_e32 v146, 15, v147
	v_xor_b32_e32 v146, 8, v146
	v_bfe_u32 v148, v147, 4, 4
	v_mul_lo_u32 v146, v146, s92
	v_mul_lo_u32 v148, v148, s92
	v_mov_b32_e32 v147, v146
	v_mov_b32_e32 v149, v148
	ds_write2st64_b64 v77, v[146:147], v[148:149] offset1:2
	v_mov_b32_e32 v138, v74
	ds_read_u8 v139, v138
	v_mov_b32_e32 v141, v73
	ds_read_u8 v140, v141
	s_add_i32 s43, s67, 32
	v_mov_b32_e32 v138, s43
	ds_read2st64_b32 v[228:229], v138 offset1:1
	ds_read_b128 v[18:21], v227
	ds_read_b128 v[22:25], v227 offset:16
	v_add_u32_e32 v152, 0x600000, v63
	v_add_u32_e32 v153, 0x600000, v64
	v_mov_b32_e32 v38, 0
	v_mov_b32_e32 v39, 0
	v_mov_b32_e32 v40, 0
	v_mov_b32_e32 v41, 0
	v_mov_b32_e32 v42, 0
	v_mov_b32_e32 v43, 0
	v_mov_b32_e32 v44, 0
	v_mov_b32_e32 v45, 0
	v_and_b32_e32 v78, 0xffff, v31
	v_lshrrev_b32_e32 v79, 16, v31
	v_lshl_add_u32 v78, v78, 7, v150
	v_lshl_add_u32 v79, v79, 7, v151
	s_mov_b32 m0, s79
	s_add_i32 s43, s79, 0x400
	global_load_lds_dwordx4 v78, s[50:51]
	s_mov_b32 m0, s43
	s_nop 0
	global_load_lds_dwordx4 v79, s[50:51]
	s_waitcnt vmcnt(8)
; __device__ __forceinline__ bf16 f2bf(float f) { return (bf16)f2bfu(f); }
; #define TR4(p_) __builtin_amdgcn_ds_read_tr4_b64_v2i32((LAS v2i*)(p_))
; #define VDMA(st_, k_) do { _Pragma("unroll") for (int i_ = 0; i_ < 4; ++i_) { \
;         const unsigned off_ = (unsigned)((st_) >> 2) * (16384u * 128u) + (PE_ID(E, 4 * ((st_) & 3) + i_) << 7) + ((i_ & 1) ? cx1 : cx0); \
;         __builtin_amdgcn_global_load_lds((const unsigned*)(V4 + off_), (LAS unsigned*)(ldsb + BUF[k_] + 1024 * i_), 16, 0, 0); } } while (0)
; __device__ __forceinline__ void peer_v_tokens(int j, const LAS unsigned short* EL, const LAS unsigned char* AL  , const LAS float* ASC  , const LAS int* SAL  , ...
;     ...
;         for (int st = 0; st < 16; ++st) {
;             const int p = st >> 2, q = st & 3;
;             if (st < 14) VDMA(st + 2, (st + 2) % 3);
;             if (st < 14) asm volatile("s_waitcnt vmcnt(8)" ::: "memory");
;             else if (st == 14) asm volatile("s_waitcnt vmcnt(4)" ::: "memory");
;             else asm volatile("s_waitcnt vmcnt(0)" ::: "memory");
;             if (q == 0) {
; #pragma unroll
;                 for (int r = 0; r < 4; ++r) { accH[r] = 0; accL[r] = 0; } }
; #pragma unroll
;             for (int tp = 0; tp < 2; ++tp) {
;                 const v2i ao = TR4(ATL + (2 * q + tp) * 128 + 8 * s16), ah = TR4(ATL + 1024 + (2 * q + tp) * 128 + 8 * s16);
; #pragma unroll
;                 for (int r = 0; r < 4; ++r) {
;                     const v2i d = TR4(ldsb + BUF[st % 3] + 2048 * tp + roff[r]);
;                     accH[r] = __builtin_amdgcn_sdot8(d.x, ah.x, accH[r], false); accH[r] = __builtin_amdgcn_sdot8(d.y, ah.y, accH[r], false);
;                     accL[r] = __builtin_amdgcn_sdot8(d.x, ao.x, accL[r], false); accL[r] = __builtin_amdgcn_sdot8(d.y, ao.y, accL[r], false);
;                 }
;             }
;             asm volatile("s_waitcnt lgkmcnt(0)" ::: "memory");
;             if (q == 3) {
; #pragma unroll
;                 for (int r = 0; r < 4; ++r) STASH[256 * p + 16 * (grp + 4 * r) + pc] = f2bf(asc * (float)(2 * ((accH[r] << 4) + accL[r]) + sa));
;             }
;         }
	v_add_u32_e32 v54, s99, v59
	v_add_u32_e32 v55, s99, v60
	v_add_u32_e32 v56, s99, v61
	v_add_u32_e32 v57, s99, v62
	ds_read_b64_tr_b4 v[50:51], v160 offset:128
	ds_read_b64_tr_b4 v[52:53], v160 offset:1152
	ds_read_b64_tr_b4 v[130:131], v54
	ds_read_b64_tr_b4 v[132:133], v55
	ds_read_b64_tr_b4 v[134:135], v56
	ds_read_b64_tr_b4 v[136:137], v57
	s_waitcnt lgkmcnt(12)
	v_dot8c_i32_i4_e32 v38, v122, v48
	v_dot8c_i32_i4_e32 v39, v122, v46
	v_dot8c_i32_i4_e32 v40, v124, v48
	v_dot8c_i32_i4_e32 v41, v124, v46
	v_dot8c_i32_i4_e32 v42, v126, v48
	v_dot8c_i32_i4_e32 v43, v126, v46
	v_dot8c_i32_i4_e32 v44, v128, v48
	v_dot8c_i32_i4_e32 v45, v128, v46
	v_dot8c_i32_i4_e32 v38, v123, v49
	v_dot8c_i32_i4_e32 v39, v123, v47
	v_dot8c_i32_i4_e32 v40, v125, v49
	v_dot8c_i32_i4_e32 v41, v125, v47
	v_dot8c_i32_i4_e32 v42, v127, v49
	v_dot8c_i32_i4_e32 v43, v127, v47
	v_dot8c_i32_i4_e32 v44, v129, v49
	v_dot8c_i32_i4_e32 v45, v129, v47
	v_and_b32_e32 v78, 0xffff, v32
	v_lshrrev_b32_e32 v79, 16, v32
	v_lshl_add_u32 v78, v78, 7, v150
	v_lshl_add_u32 v79, v79, 7, v151
	s_mov_b32 m0, s98
	s_add_i32 s43, s98, 0x400
	global_load_lds_dwordx4 v78, s[50:51]
	s_mov_b32 m0, s43
	s_nop 0
	global_load_lds_dwordx4 v79, s[50:51]
	s_waitcnt vmcnt(8)
	v_add_u32_e32 v54, s76, v59
	v_add_u32_e32 v55, s76, v60
	v_add_u32_e32 v56, s76, v61
	v_add_u32_e32 v57, s76, v62
	ds_read_b64_tr_b4 v[46:47], v160 offset:256
	ds_read_b64_tr_b4 v[48:49], v160 offset:1280
	ds_read_b64_tr_b4 v[122:123], v54
	ds_read_b64_tr_b4 v[124:125], v55
	ds_read_b64_tr_b4 v[126:127], v56
	ds_read_b64_tr_b4 v[128:129], v57
	s_waitcnt lgkmcnt(6)
	v_dot8c_i32_i4_e32 v38, v130, v52
	v_dot8c_i32_i4_e32 v39, v130, v50
	v_dot8c_i32_i4_e32 v40, v132, v52
	v_dot8c_i32_i4_e32 v41, v132, v50
	v_dot8c_i32_i4_e32 v42, v134, v52
	v_dot8c_i32_i4_e32 v43, v134, v50
	v_dot8c_i32_i4_e32 v44, v136, v52
	v_dot8c_i32_i4_e32 v45, v136, v50
	v_dot8c_i32_i4_e32 v38, v131, v53
	v_dot8c_i32_i4_e32 v39, v131, v51
	v_dot8c_i32_i4_e32 v40, v133, v53
	v_dot8c_i32_i4_e32 v41, v133, v51
	v_dot8c_i32_i4_e32 v42, v135, v53
	v_dot8c_i32_i4_e32 v43, v135, v51
	v_dot8c_i32_i4_e32 v44, v137, v53
	v_dot8c_i32_i4_e32 v45, v137, v51
	v_and_b32_e32 v78, 0xffff, v33
	v_lshrrev_b32_e32 v79, 16, v33
	v_lshl_add_u32 v78, v78, 7, v150
	v_lshl_add_u32 v79, v79, 7, v151
	s_mov_b32 m0, s99
	s_add_i32 s43, s99, 0x400
	global_load_lds_dwordx4 v78, s[50:51]
	s_mov_b32 m0, s43
	s_nop 0
	global_load_lds_dwordx4 v79, s[50:51]
	s_waitcnt vmcnt(8)
	v_add_u32_e32 v54, s77, v59
	v_add_u32_e32 v55, s77, v60
	v_add_u32_e32 v56, s77, v61
	v_add_u32_e32 v57, s77, v62
	ds_read_b64_tr_b4 v[50:51], v160 offset:384
	ds_read_b64_tr_b4 v[52:53], v160 offset:1408
	ds_read_b64_tr_b4 v[130:131], v54
	ds_read_b64_tr_b4 v[132:133], v55
	ds_read_b64_tr_b4 v[134:135], v56
	ds_read_b64_tr_b4 v[136:137], v57
	s_waitcnt lgkmcnt(6)
	v_dot8c_i32_i4_e32 v38, v122, v48
	v_dot8c_i32_i4_e32 v39, v122, v46
	v_dot8c_i32_i4_e32 v40, v124, v48
	v_dot8c_i32_i4_e32 v41, v124, v46
	v_dot8c_i32_i4_e32 v42, v126, v48
	v_dot8c_i32_i4_e32 v43, v126, v46
	v_dot8c_i32_i4_e32 v44, v128, v48
	v_dot8c_i32_i4_e32 v45, v128, v46
	v_dot8c_i32_i4_e32 v38, v123, v49
	v_dot8c_i32_i4_e32 v39, v123, v47
	v_dot8c_i32_i4_e32 v40, v125, v49
	v_dot8c_i32_i4_e32 v41, v125, v47
	v_dot8c_i32_i4_e32 v42, v127, v49
	v_dot8c_i32_i4_e32 v43, v127, v47
	v_dot8c_i32_i4_e32 v44, v129, v49
	v_dot8c_i32_i4_e32 v45, v129, v47
	s_waitcnt lgkmcnt(15)
	v_and_b32_e32 v78, 0xffff, v18
	v_lshrrev_b32_e32 v79, 16, v18
	v_lshl_add_u32 v78, v78, 7, v152
	v_lshl_add_u32 v79, v79, 7, v153
	s_mov_b32 m0, s76
	s_add_i32 s43, s76, 0x400
	global_load_lds_dwordx4 v78, s[50:51]
	s_mov_b32 m0, s43
	s_nop 0
	global_load_lds_dwordx4 v79, s[50:51]
	s_waitcnt vmcnt(8)
	v_add_u32_e32 v54, s78, v59
	v_add_u32_e32 v55, s78, v60
	v_add_u32_e32 v56, s78, v61
	v_add_u32_e32 v57, s78, v62
	ds_read_b64_tr_b4 v[46:47], v160 offset:512
	ds_read_b64_tr_b4 v[48:49], v160 offset:1536
	ds_read_b64_tr_b4 v[122:123], v54
	ds_read_b64_tr_b4 v[124:125], v55
	ds_read_b64_tr_b4 v[126:127], v56
	ds_read_b64_tr_b4 v[128:129], v57
	s_waitcnt lgkmcnt(6)
	v_dot8c_i32_i4_e32 v38, v130, v52
	v_dot8c_i32_i4_e32 v39, v130, v50
	v_dot8c_i32_i4_e32 v40, v132, v52
	v_dot8c_i32_i4_e32 v41, v132, v50
	v_dot8c_i32_i4_e32 v42, v134, v52
	v_dot8c_i32_i4_e32 v43, v134, v50
	v_dot8c_i32_i4_e32 v44, v136, v52
	v_dot8c_i32_i4_e32 v45, v136, v50
	v_dot8c_i32_i4_e32 v38, v131, v53
	v_dot8c_i32_i4_e32 v39, v131, v51
	v_dot8c_i32_i4_e32 v40, v133, v53
	v_dot8c_i32_i4_e32 v41, v133, v51
	v_dot8c_i32_i4_e32 v42, v135, v53
	v_dot8c_i32_i4_e32 v43, v135, v51
	v_dot8c_i32_i4_e32 v44, v137, v53
	v_dot8c_i32_i4_e32 v45, v137, v51
	v_and_b32_e32 v78, 0xffff, v19
	v_lshrrev_b32_e32 v79, 16, v19
	v_lshl_add_u32 v78, v78, 7, v152
	v_lshl_add_u32 v79, v79, 7, v153
	s_mov_b32 m0, s77
	s_add_i32 s43, s77, 0x400
	global_load_lds_dwordx4 v78, s[50:51]
	s_mov_b32 m0, s43
	s_nop 0
	global_load_lds_dwordx4 v79, s[50:51]
	s_waitcnt vmcnt(8)
	v_add_u32_e32 v54, s79, v59
	v_add_u32_e32 v55, s79, v60
	v_add_u32_e32 v56, s79, v61
	v_add_u32_e32 v57, s79, v62
	ds_read_b64_tr_b4 v[50:51], v160 offset:640
	ds_read_b64_tr_b4 v[52:53], v160 offset:1664
	ds_read_b64_tr_b4 v[130:131], v54
	ds_read_b64_tr_b4 v[132:133], v55
	ds_read_b64_tr_b4 v[134:135], v56
	ds_read_b64_tr_b4 v[136:137], v57
	s_waitcnt lgkmcnt(6)
	v_dot8c_i32_i4_e32 v38, v122, v48
	v_dot8c_i32_i4_e32 v39, v122, v46
	v_dot8c_i32_i4_e32 v40, v124, v48
	v_dot8c_i32_i4_e32 v41, v124, v46
	v_dot8c_i32_i4_e32 v42, v126, v48
	v_dot8c_i32_i4_e32 v43, v126, v46
	v_dot8c_i32_i4_e32 v44, v128, v48
	v_dot8c_i32_i4_e32 v45, v128, v46
	v_dot8c_i32_i4_e32 v38, v123, v49
	v_dot8c_i32_i4_e32 v39, v123, v47
	v_dot8c_i32_i4_e32 v40, v125, v49
	v_dot8c_i32_i4_e32 v41, v125, v47
	v_dot8c_i32_i4_e32 v42, v127, v49
	v_dot8c_i32_i4_e32 v43, v127, v47
	v_dot8c_i32_i4_e32 v44, v129, v49
	v_dot8c_i32_i4_e32 v45, v129, v47
	s_waitcnt lgkmcnt(15)
; #define LAS __attribute__((address_space(3)))
; __device__ __forceinline__ bf16 f2bf(float f) { return (bf16)f2bfu(f); }
; __device__ __forceinline__ void peer_v_tokens(int j, const LAS unsigned short* EL, const LAS unsigned char* AL  , const LAS float* ASC  , const LAS int* SAL  , ...
;     ...
;         for (int m = 0; m < 2; ++m) {
;             const int idx = lane + 64 * m, tau = idx >> 4, sr = idx & 15, k = 16 * (sr & 7) + 2 * tau + (sr >> 3);
;             const int aq = (int)*(const LAS signed char*)(AL + tl * 128 + k); const int tq = aq + 8;
;             const unsigned lo = (((unsigned)tq & 15u) ^ 8u) * 0x11111111u, hi = ((unsigned)(tq >> 4) & 15u) * 0x11111111u;
;             typedef unsigned u2v __attribute__((ext_vector_type(2)));
;             u2v l2; l2.x = lo; l2.y = lo; u2v h2; h2.x = hi; h2.y = hi;
;             *(LAS u2v*)(ATL + 8 * idx) = l2; *(LAS u2v*)(ATL + 1024 + 8 * idx) = h2;
;         }
;     ...
;         for (int st = 0; st < 16; ++st) {
;             const int p = st >> 2, q = st & 3;
;             if (st < 14) VDMA(st + 2, (st + 2) % 3);
;             if (st < 14) asm volatile("s_waitcnt vmcnt(8)" ::: "memory");
;             else if (st == 14) asm volatile("s_waitcnt vmcnt(4)" ::: "memory");
;             else asm volatile("s_waitcnt vmcnt(0)" ::: "memory");
;             if (q == 0) {
; #pragma unroll
;                 for (int r = 0; r < 4; ++r) { accH[r] = 0; accL[r] = 0; } }
; #pragma unroll
;             for (int tp = 0; tp < 2; ++tp) {
;                 const v2i ao = TR4(ATL + (2 * q + tp) * 128 + 8 * s16), ah = TR4(ATL + 1024 + (2 * q + tp) * 128 + 8 * s16);
; #pragma unroll
;                 for (int r = 0; r < 4; ++r) {
;                     const v2i d = TR4(ldsb + BUF[st % 3] + 2048 * tp + roff[r]);
;                     accH[r] = __builtin_amdgcn_sdot8(d.x, ah.x, accH[r], false); accH[r] = __builtin_amdgcn_sdot8(d.y, ah.y, accH[r], false);
;                     accL[r] = __builtin_amdgcn_sdot8(d.x, ao.x, accL[r], false); accL[r] = __builtin_amdgcn_sdot8(d.y, ao.y, accL[r], false);
;                 }
;             }
;             asm volatile("s_waitcnt lgkmcnt(0)" ::: "memory");
;             if (q == 3) {
; #pragma unroll
;                 for (int r = 0; r < 4; ++r) STASH[256 * p + 16 * (grp + 4 * r) + pc] = f2bf(asc * (float)(2 * ((accH[r] << 4) + accL[r]) + sa));
;             }
;         }
	v_add_u32_e32 v143, 8, v139
	v_and_b32_e32 v142, 15, v143
	v_xor_b32_e32 v142, 8, v142
	v_bfe_u32 v144, v143, 4, 4
	v_mul_lo_u32 v142, v142, s92
	v_mul_lo_u32 v144, v144, s92
	v_mov_b32_e32 v143, v142
	v_mov_b32_e32 v145, v144
	ds_write2st64_b64 v159, v[142:143], v[144:145] offset1:2
	v_and_b32_e32 v78, 0xffff, v20
	v_lshrrev_b32_e32 v79, 16, v20
	v_lshl_add_u32 v78, v78, 7, v152
	v_lshl_add_u32 v79, v79, 7, v153
	s_mov_b32 m0, s78
	s_add_i32 s43, s78, 0x400
	global_load_lds_dwordx4 v78, s[50:51]
	s_mov_b32 m0, s43
	s_nop 0
	global_load_lds_dwordx4 v79, s[50:51]
	s_waitcnt vmcnt(8)
	v_add_u32_e32 v54, s98, v59
	v_add_u32_e32 v55, s98, v60
	v_add_u32_e32 v56, s98, v61
	v_add_u32_e32 v57, s98, v62
	ds_read_b64_tr_b4 v[46:47], v160 offset:768
	ds_read_b64_tr_b4 v[48:49], v160 offset:1792
	ds_read_b64_tr_b4 v[122:123], v54
	ds_read_b64_tr_b4 v[124:125], v55
	ds_read_b64_tr_b4 v[126:127], v56
	ds_read_b64_tr_b4 v[128:129], v57
	s_waitcnt lgkmcnt(7)
	v_dot8c_i32_i4_e32 v38, v130, v52
	v_dot8c_i32_i4_e32 v39, v130, v50
	v_dot8c_i32_i4_e32 v40, v132, v52
	v_dot8c_i32_i4_e32 v41, v132, v50
	v_dot8c_i32_i4_e32 v42, v134, v52
	v_dot8c_i32_i4_e32 v43, v134, v50
	v_dot8c_i32_i4_e32 v44, v136, v52
	v_dot8c_i32_i4_e32 v45, v136, v50
	v_dot8c_i32_i4_e32 v38, v131, v53
	v_dot8c_i32_i4_e32 v39, v131, v51
	v_dot8c_i32_i4_e32 v40, v133, v53
	v_dot8c_i32_i4_e32 v41, v133, v51
	v_dot8c_i32_i4_e32 v42, v135, v53
	v_dot8c_i32_i4_e32 v43, v135, v51
	v_dot8c_i32_i4_e32 v44, v137, v53
	v_dot8c_i32_i4_e32 v45, v137, v51
	v_and_b32_e32 v78, 0xffff, v21
	v_lshrrev_b32_e32 v79, 16, v21
	v_lshl_add_u32 v78, v78, 7, v152
	v_lshl_add_u32 v79, v79, 7, v153
	s_mov_b32 m0, s79
	s_add_i32 s43, s79, 0x400
	global_load_lds_dwordx4 v78, s[50:51]
	s_mov_b32 m0, s43
	s_nop 0
	global_load_lds_dwordx4 v79, s[50:51]
	s_waitcnt vmcnt(8)
	v_add_u32_e32 v54, s99, v59
	v_add_u32_e32 v55, s99, v60
	v_add_u32_e32 v56, s99, v61
	v_add_u32_e32 v57, s99, v62
	ds_read_b64_tr_b4 v[50:51], v160 offset:896
	ds_read_b64_tr_b4 v[52:53], v160 offset:1920
	ds_read_b64_tr_b4 v[130:131], v54
	ds_read_b64_tr_b4 v[132:133], v55
	ds_read_b64_tr_b4 v[134:135], v56
	ds_read_b64_tr_b4 v[136:137], v57
	s_waitcnt lgkmcnt(6)
	v_dot8c_i32_i4_e32 v38, v122, v48
	v_dot8c_i32_i4_e32 v39, v122, v46
	v_dot8c_i32_i4_e32 v40, v124, v48
	v_dot8c_i32_i4_e32 v41, v124, v46
	v_dot8c_i32_i4_e32 v42, v126, v48
	v_dot8c_i32_i4_e32 v43, v126, v46
	v_dot8c_i32_i4_e32 v44, v128, v48
	v_dot8c_i32_i4_e32 v45, v128, v46
	v_dot8c_i32_i4_e32 v38, v123, v49
	v_dot8c_i32_i4_e32 v39, v123, v47
	v_dot8c_i32_i4_e32 v40, v125, v49
	v_dot8c_i32_i4_e32 v41, v125, v47
	v_dot8c_i32_i4_e32 v42, v127, v49
	v_dot8c_i32_i4_e32 v43, v127, v47
	v_dot8c_i32_i4_e32 v44, v129, v49
	v_dot8c_i32_i4_e32 v45, v129, v47
	v_and_b32_e32 v78, 0xffff, v22
	v_lshrrev_b32_e32 v79, 16, v22
	v_lshl_add_u32 v78, v78, 7, v152
	v_lshl_add_u32 v79, v79, 7, v153
	s_mov_b32 m0, s98
	s_add_i32 s43, s98, 0x400
	global_load_lds_dwordx4 v78, s[50:51]
	s_mov_b32 m0, s43
	s_nop 0
	global_load_lds_dwordx4 v79, s[50:51]
	s_waitcnt vmcnt(8)
	v_add_u32_e32 v54, s76, v59
	v_add_u32_e32 v55, s76, v60
	v_add_u32_e32 v56, s76, v61
	v_add_u32_e32 v57, s76, v62
	ds_read_b64_tr_b4 v[46:47], v160
	ds_read_b64_tr_b4 v[48:49], v160 offset:1024
	ds_read_b64_tr_b4 v[122:123], v54
	ds_read_b64_tr_b4 v[124:125], v55
	ds_read_b64_tr_b4 v[126:127], v56
	ds_read_b64_tr_b4 v[128:129], v57
	s_waitcnt lgkmcnt(6)
	v_dot8c_i32_i4_e32 v38, v130, v52
	v_dot8c_i32_i4_e32 v39, v130, v50
	v_dot8c_i32_i4_e32 v40, v132, v52
	v_dot8c_i32_i4_e32 v41, v132, v50
	v_dot8c_i32_i4_e32 v42, v134, v52
	v_dot8c_i32_i4_e32 v43, v134, v50
	v_dot8c_i32_i4_e32 v44, v136, v52
	v_dot8c_i32_i4_e32 v45, v136, v50
	v_dot8c_i32_i4_e32 v38, v131, v53
	v_dot8c_i32_i4_e32 v39, v131, v51
	v_dot8c_i32_i4_e32 v40, v133, v53
	v_dot8c_i32_i4_e32 v41, v133, v51
	v_dot8c_i32_i4_e32 v42, v135, v53
	v_dot8c_i32_i4_e32 v43, v135, v51
	v_dot8c_i32_i4_e32 v44, v137, v53
	v_dot8c_i32_i4_e32 v45, v137, v51
	s_nop 3
	s_waitcnt lgkmcnt(15)
	v_lshlrev_b32_e32 v38, 5, v38
	v_lshlrev_b32_e32 v39, 1, v39
	v_add3_u32 v38, v39, v229, v38
	v_cvt_f32_i32_e32 v38, v38
	v_mul_f32_e32 v38, v228, v38
	v_lshlrev_b32_e32 v40, 5, v40
	v_lshlrev_b32_e32 v41, 1, v41
	v_add3_u32 v40, v41, v229, v40
	v_cvt_f32_i32_e32 v40, v40
	v_mul_f32_e32 v40, v228, v40
	v_lshlrev_b32_e32 v42, 5, v42
	v_lshlrev_b32_e32 v43, 1, v43
	v_add3_u32 v42, v43, v229, v42
	v_cvt_f32_i32_e32 v42, v42
	v_mul_f32_e32 v42, v228, v42
	v_lshlrev_b32_e32 v44, 5, v44
	v_lshlrev_b32_e32 v45, 1, v45
	v_add3_u32 v44, v45, v229, v44
	v_cvt_f32_i32_e32 v44, v44
	v_mul_f32_e32 v44, v228, v44
	v_cvt_pk_bf16_f32 v174, v38, v40
	v_cvt_pk_bf16_f32 v175, v42, v44
	v_add_u32_e32 v147, 8, v140
	v_and_b32_e32 v146, 15, v147
	v_xor_b32_e32 v146, 8, v146
	v_bfe_u32 v148, v147, 4, 4
	v_mul_lo_u32 v146, v146, s92
	v_mul_lo_u32 v148, v148, s92
	v_mov_b32_e32 v147, v146
	v_mov_b32_e32 v149, v148
	ds_write2st64_b64 v77, v[146:147], v[148:149] offset1:2
	v_add_u32_e32 v138, 0x400, v74
	ds_read_u8 v139, v138
	v_add_u32_e32 v141, 0x400, v73
	ds_read_u8 v140, v141
	s_mov_b32 s43, s67
	v_mov_b32_e32 v138, s43
	ds_read2st64_b32 v[228:229], v138 offset1:1
	ds_read_b128 v[26:29], v227 offset:2048
	ds_read_b128 v[30:33], v227 offset:2064
	v_mov_b32_e32 v38, 0
	v_mov_b32_e32 v39, 0
	v_mov_b32_e32 v40, 0
	v_mov_b32_e32 v41, 0
	v_mov_b32_e32 v42, 0
	v_mov_b32_e32 v43, 0
	v_mov_b32_e32 v44, 0
	v_mov_b32_e32 v45, 0
	v_and_b32_e32 v78, 0xffff, v23
	v_lshrrev_b32_e32 v79, 16, v23
	v_lshl_add_u32 v78, v78, 7, v152
	v_lshl_add_u32 v79, v79, 7, v153
	s_mov_b32 m0, s99
	s_add_i32 s43, s99, 0x400
	global_load_lds_dwordx4 v78, s[50:51]
	s_mov_b32 m0, s43
	s_nop 0
	global_load_lds_dwordx4 v79, s[50:51]
	s_waitcnt vmcnt(8)
; __device__ __forceinline__ bf16 f2bf(float f) { return (bf16)f2bfu(f); }
; #define TR4(p_) __builtin_amdgcn_ds_read_tr4_b64_v2i32((LAS v2i*)(p_))
; #define VDMA(st_, k_) do { _Pragma("unroll") for (int i_ = 0; i_ < 4; ++i_) { \
;         const unsigned off_ = (unsigned)((st_) >> 2) * (16384u * 128u) + (PE_ID(E, 4 * ((st_) & 3) + i_) << 7) + ((i_ & 1) ? cx1 : cx0); \
;         __builtin_amdgcn_global_load_lds((const unsigned*)(V4 + off_), (LAS unsigned*)(ldsb + BUF[k_] + 1024 * i_), 16, 0, 0); } } while (0)
; __device__ __forceinline__ void peer_v_tokens(int j, const LAS unsigned short* EL, const LAS unsigned char* AL  , const LAS float* ASC  , const LAS int* SAL  , ...
;     ...
;         for (int st = 0; st < 16; ++st) {
;             const int p = st >> 2, q = st & 3;
;             if (st < 14) VDMA(st + 2, (st + 2) % 3);
;             if (st < 14) asm volatile("s_waitcnt vmcnt(8)" ::: "memory");
;             else if (st == 14) asm volatile("s_waitcnt vmcnt(4)" ::: "memory");
;             else asm volatile("s_waitcnt vmcnt(0)" ::: "memory");
;             if (q == 0) {
; #pragma unroll
;                 for (int r = 0; r < 4; ++r) { accH[r] = 0; accL[r] = 0; } }
; #pragma unroll
;             for (int tp = 0; tp < 2; ++tp) {
;                 const v2i ao = TR4(ATL + (2 * q + tp) * 128 + 8 * s16), ah = TR4(ATL + 1024 + (2 * q + tp) * 128 + 8 * s16);
; #pragma unroll
;                 for (int r = 0; r < 4; ++r) {
;                     const v2i d = TR4(ldsb + BUF[st % 3] + 2048 * tp + roff[r]);
;                     accH[r] = __builtin_amdgcn_sdot8(d.x, ah.x, accH[r], false); accH[r] = __builtin_amdgcn_sdot8(d.y, ah.y, accH[r], false);
;                     accL[r] = __builtin_amdgcn_sdot8(d.x, ao.x, accL[r], false); accL[r] = __builtin_amdgcn_sdot8(d.y, ao.y, accL[r], false);
;                 }
;             }
;             asm volatile("s_waitcnt lgkmcnt(0)" ::: "memory");
;             if (q == 3) {
; #pragma unroll
;                 for (int r = 0; r < 4; ++r) STASH[256 * p + 16 * (grp + 4 * r) + pc] = f2bf(asc * (float)(2 * ((accH[r] << 4) + accL[r]) + sa));
;             }
;         }
	v_add_u32_e32 v54, s77, v59
	v_add_u32_e32 v55, s77, v60
	v_add_u32_e32 v56, s77, v61
	v_add_u32_e32 v57, s77, v62
	ds_read_b64_tr_b4 v[50:51], v160 offset:128
	ds_read_b64_tr_b4 v[52:53], v160 offset:1152
	ds_read_b64_tr_b4 v[130:131], v54
	ds_read_b64_tr_b4 v[132:133], v55
	ds_read_b64_tr_b4 v[134:135], v56
	ds_read_b64_tr_b4 v[136:137], v57
	s_waitcnt lgkmcnt(12)
	v_dot8c_i32_i4_e32 v38, v122, v48
	v_dot8c_i32_i4_e32 v39, v122, v46
	v_dot8c_i32_i4_e32 v40, v124, v48
	v_dot8c_i32_i4_e32 v41, v124, v46
	v_dot8c_i32_i4_e32 v42, v126, v48
	v_dot8c_i32_i4_e32 v43, v126, v46
	v_dot8c_i32_i4_e32 v44, v128, v48
	v_dot8c_i32_i4_e32 v45, v128, v46
	v_dot8c_i32_i4_e32 v38, v123, v49
	v_dot8c_i32_i4_e32 v39, v123, v47
	v_dot8c_i32_i4_e32 v40, v125, v49
	v_dot8c_i32_i4_e32 v41, v125, v47
	v_dot8c_i32_i4_e32 v42, v127, v49
	v_dot8c_i32_i4_e32 v43, v127, v47
	v_dot8c_i32_i4_e32 v44, v129, v49
	v_dot8c_i32_i4_e32 v45, v129, v47
	v_and_b32_e32 v78, 0xffff, v24
	v_lshrrev_b32_e32 v79, 16, v24
	v_lshl_add_u32 v78, v78, 7, v152
	v_lshl_add_u32 v79, v79, 7, v153
	s_mov_b32 m0, s76
	s_add_i32 s43, s76, 0x400
	global_load_lds_dwordx4 v78, s[50:51]
	s_mov_b32 m0, s43
	s_nop 0
	global_load_lds_dwordx4 v79, s[50:51]
	s_waitcnt vmcnt(8)
	v_add_u32_e32 v54, s78, v59
	v_add_u32_e32 v55, s78, v60
	v_add_u32_e32 v56, s78, v61
	v_add_u32_e32 v57, s78, v62
	ds_read_b64_tr_b4 v[46:47], v160 offset:256
	ds_read_b64_tr_b4 v[48:49], v160 offset:1280
	ds_read_b64_tr_b4 v[122:123], v54
	ds_read_b64_tr_b4 v[124:125], v55
	ds_read_b64_tr_b4 v[126:127], v56
	ds_read_b64_tr_b4 v[128:129], v57
	s_waitcnt lgkmcnt(6)
	v_dot8c_i32_i4_e32 v38, v130, v52
	v_dot8c_i32_i4_e32 v39, v130, v50
	v_dot8c_i32_i4_e32 v40, v132, v52
	v_dot8c_i32_i4_e32 v41, v132, v50
	v_dot8c_i32_i4_e32 v42, v134, v52
	v_dot8c_i32_i4_e32 v43, v134, v50
	v_dot8c_i32_i4_e32 v44, v136, v52
	v_dot8c_i32_i4_e32 v45, v136, v50
	v_dot8c_i32_i4_e32 v38, v131, v53
	v_dot8c_i32_i4_e32 v39, v131, v51
	v_dot8c_i32_i4_e32 v40, v133, v53
	v_dot8c_i32_i4_e32 v41, v133, v51
	v_dot8c_i32_i4_e32 v42, v135, v53
	v_dot8c_i32_i4_e32 v43, v135, v51
	v_dot8c_i32_i4_e32 v44, v137, v53
	v_dot8c_i32_i4_e32 v45, v137, v51
	v_and_b32_e32 v78, 0xffff, v25
	v_lshrrev_b32_e32 v79, 16, v25
	v_lshl_add_u32 v78, v78, 7, v152
	v_lshl_add_u32 v79, v79, 7, v153
	s_mov_b32 m0, s77
	s_add_i32 s43, s77, 0x400
	global_load_lds_dwordx4 v78, s[50:51]
	s_mov_b32 m0, s43
	s_nop 0
	global_load_lds_dwordx4 v79, s[50:51]
	s_waitcnt vmcnt(8)
	v_add_u32_e32 v54, s79, v59
	v_add_u32_e32 v55, s79, v60
	v_add_u32_e32 v56, s79, v61
	v_add_u32_e32 v57, s79, v62
	ds_read_b64_tr_b4 v[50:51], v160 offset:384
	ds_read_b64_tr_b4 v[52:53], v160 offset:1408
	ds_read_b64_tr_b4 v[130:131], v54
	ds_read_b64_tr_b4 v[132:133], v55
	ds_read_b64_tr_b4 v[134:135], v56
	ds_read_b64_tr_b4 v[136:137], v57
	s_waitcnt lgkmcnt(6)
	v_dot8c_i32_i4_e32 v38, v122, v48
	v_dot8c_i32_i4_e32 v39, v122, v46
	v_dot8c_i32_i4_e32 v40, v124, v48
	v_dot8c_i32_i4_e32 v41, v124, v46
	v_dot8c_i32_i4_e32 v42, v126, v48
	v_dot8c_i32_i4_e32 v43, v126, v46
	v_dot8c_i32_i4_e32 v44, v128, v48
	v_dot8c_i32_i4_e32 v45, v128, v46
	v_dot8c_i32_i4_e32 v38, v123, v49
	v_dot8c_i32_i4_e32 v39, v123, v47
	v_dot8c_i32_i4_e32 v40, v125, v49
	v_dot8c_i32_i4_e32 v41, v125, v47
	v_dot8c_i32_i4_e32 v42, v127, v49
	v_dot8c_i32_i4_e32 v43, v127, v47
	v_dot8c_i32_i4_e32 v44, v129, v49
	v_dot8c_i32_i4_e32 v45, v129, v47
	s_waitcnt lgkmcnt(15)
	v_and_b32_e32 v78, 0xffff, v26
	v_lshrrev_b32_e32 v79, 16, v26
	v_lshl_add_u32 v78, v78, 7, v152
	v_lshl_add_u32 v79, v79, 7, v153
	s_mov_b32 m0, s78
	s_add_i32 s43, s78, 0x400
	global_load_lds_dwordx4 v78, s[50:51]
	s_mov_b32 m0, s43
	s_nop 0
	global_load_lds_dwordx4 v79, s[50:51]
	s_waitcnt vmcnt(8)
	v_add_u32_e32 v54, s98, v59
	v_add_u32_e32 v55, s98, v60
	v_add_u32_e32 v56, s98, v61
	v_add_u32_e32 v57, s98, v62
	ds_read_b64_tr_b4 v[46:47], v160 offset:512
	ds_read_b64_tr_b4 v[48:49], v160 offset:1536
	ds_read_b64_tr_b4 v[122:123], v54
	ds_read_b64_tr_b4 v[124:125], v55
	ds_read_b64_tr_b4 v[126:127], v56
	ds_read_b64_tr_b4 v[128:129], v57
	s_waitcnt lgkmcnt(6)
	v_dot8c_i32_i4_e32 v38, v130, v52
	v_dot8c_i32_i4_e32 v39, v130, v50
	v_dot8c_i32_i4_e32 v40, v132, v52
	v_dot8c_i32_i4_e32 v41, v132, v50
	v_dot8c_i32_i4_e32 v42, v134, v52
	v_dot8c_i32_i4_e32 v43, v134, v50
	v_dot8c_i32_i4_e32 v44, v136, v52
	v_dot8c_i32_i4_e32 v45, v136, v50
	v_dot8c_i32_i4_e32 v38, v131, v53
	v_dot8c_i32_i4_e32 v39, v131, v51
	v_dot8c_i32_i4_e32 v40, v133, v53
	v_dot8c_i32_i4_e32 v41, v133, v51
	v_dot8c_i32_i4_e32 v42, v135, v53
	v_dot8c_i32_i4_e32 v43, v135, v51
	v_dot8c_i32_i4_e32 v44, v137, v53
	v_dot8c_i32_i4_e32 v45, v137, v51
	v_and_b32_e32 v78, 0xffff, v27
	v_lshrrev_b32_e32 v79, 16, v27
	v_lshl_add_u32 v78, v78, 7, v152
	v_lshl_add_u32 v79, v79, 7, v153
	s_mov_b32 m0, s79
	s_add_i32 s43, s79, 0x400
	global_load_lds_dwordx4 v78, s[50:51]
	s_mov_b32 m0, s43
	s_nop 0
	global_load_lds_dwordx4 v79, s[50:51]
	s_waitcnt vmcnt(8)
	v_add_u32_e32 v54, s99, v59
	v_add_u32_e32 v55, s99, v60
	v_add_u32_e32 v56, s99, v61
	v_add_u32_e32 v57, s99, v62
	ds_read_b64_tr_b4 v[50:51], v160 offset:640
	ds_read_b64_tr_b4 v[52:53], v160 offset:1664
	ds_read_b64_tr_b4 v[130:131], v54
	ds_read_b64_tr_b4 v[132:133], v55
	ds_read_b64_tr_b4 v[134:135], v56
	ds_read_b64_tr_b4 v[136:137], v57
	s_waitcnt lgkmcnt(6)
	v_dot8c_i32_i4_e32 v38, v122, v48
	v_dot8c_i32_i4_e32 v39, v122, v46
	v_dot8c_i32_i4_e32 v40, v124, v48
	v_dot8c_i32_i4_e32 v41, v124, v46
	v_dot8c_i32_i4_e32 v42, v126, v48
	v_dot8c_i32_i4_e32 v43, v126, v46
	v_dot8c_i32_i4_e32 v44, v128, v48
	v_dot8c_i32_i4_e32 v45, v128, v46
	v_dot8c_i32_i4_e32 v38, v123, v49
	v_dot8c_i32_i4_e32 v39, v123, v47
	v_dot8c_i32_i4_e32 v40, v125, v49
	v_dot8c_i32_i4_e32 v41, v125, v47
	v_dot8c_i32_i4_e32 v42, v127, v49
	v_dot8c_i32_i4_e32 v43, v127, v47
	v_dot8c_i32_i4_e32 v44, v129, v49
	v_dot8c_i32_i4_e32 v45, v129, v47
	s_waitcnt lgkmcnt(15)
; __device__ __forceinline__ bf16 f2bf(float f) { return (bf16)f2bfu(f); }
; #define TR4(p_) __builtin_amdgcn_ds_read_tr4_b64_v2i32((LAS v2i*)(p_))
; __device__ __forceinline__ void peer_v_tokens(int j, const LAS unsigned short* EL, const LAS unsigned char* AL  , const LAS float* ASC  , const LAS int* SAL  , ...
;     ...
;         uint2 hv[4]; float4 gv[4];
;         { unsigned ho = (unsigned)t * (D / 4) + (unsigned)lane; asm volatile("" : "+v"(ho)); const uint2* hp = (const uint2*)HB + ho; const float4* gp = (const float4*)fng + lane;
; #pragma unroll
;           for (int jq = 0; jq < 4; ++jq) { hv[jq] = hp[64 * jq]; gv[jq] = gp[64 * jq]; } }
;     ...
;         for (int st = 0; st < 16; ++st) {
;             const int p = st >> 2, q = st & 3;
;             if (st < 14) VDMA(st + 2, (st + 2) % 3);
;             if (st < 14) asm volatile("s_waitcnt vmcnt(8)" ::: "memory");
;             else if (st == 14) asm volatile("s_waitcnt vmcnt(4)" ::: "memory");
;             else asm volatile("s_waitcnt vmcnt(0)" ::: "memory");
;             if (q == 0) {
; #pragma unroll
;                 for (int r = 0; r < 4; ++r) { accH[r] = 0; accL[r] = 0; } }
; #pragma unroll
;             for (int tp = 0; tp < 2; ++tp) {
;                 const v2i ao = TR4(ATL + (2 * q + tp) * 128 + 8 * s16), ah = TR4(ATL + 1024 + (2 * q + tp) * 128 + 8 * s16);
; #pragma unroll
;                 for (int r = 0; r < 4; ++r) {
;                     const v2i d = TR4(ldsb + BUF[st % 3] + 2048 * tp + roff[r]);
;                     accH[r] = __builtin_amdgcn_sdot8(d.x, ah.x, accH[r], false); accH[r] = __builtin_amdgcn_sdot8(d.y, ah.y, accH[r], false);
;                     accL[r] = __builtin_amdgcn_sdot8(d.x, ao.x, accL[r], false); accL[r] = __builtin_amdgcn_sdot8(d.y, ao.y, accL[r], false);
;                 }
;             }
;             asm volatile("s_waitcnt lgkmcnt(0)" ::: "memory");
;             if (q == 3) {
; #pragma unroll
;                 for (int r = 0; r < 4; ++r) STASH[256 * p + 16 * (grp + 4 * r) + pc] = f2bf(asc * (float)(2 * ((accH[r] << 4) + accL[r]) + sa));
;             }
;         }
	v_add_u32_e32 v143, 8, v139
	v_and_b32_e32 v142, 15, v143
	v_xor_b32_e32 v142, 8, v142
	v_bfe_u32 v144, v143, 4, 4
	v_mul_lo_u32 v142, v142, s92
	v_mul_lo_u32 v144, v144, s92
	v_mov_b32_e32 v143, v142
	v_mov_b32_e32 v145, v144
	ds_write2st64_b64 v159, v[142:143], v[144:145] offset1:2
	v_and_b32_e32 v78, 0xffff, v28
	v_lshrrev_b32_e32 v79, 16, v28
	v_lshl_add_u32 v78, v78, 7, v152
	v_lshl_add_u32 v79, v79, 7, v153
	s_mov_b32 m0, s98
	s_add_i32 s43, s98, 0x400
	global_load_lds_dwordx4 v78, s[50:51]
	s_mov_b32 m0, s43
	s_nop 0
	global_load_lds_dwordx4 v79, s[50:51]
	s_waitcnt vmcnt(8)
	v_add_u32_e32 v54, s76, v59
	v_add_u32_e32 v55, s76, v60
	v_add_u32_e32 v56, s76, v61
	v_add_u32_e32 v57, s76, v62
	ds_read_b64_tr_b4 v[46:47], v160 offset:768
	ds_read_b64_tr_b4 v[48:49], v160 offset:1792
	ds_read_b64_tr_b4 v[122:123], v54
	ds_read_b64_tr_b4 v[124:125], v55
	ds_read_b64_tr_b4 v[126:127], v56
	ds_read_b64_tr_b4 v[128:129], v57
	s_waitcnt lgkmcnt(7)
	v_dot8c_i32_i4_e32 v38, v130, v52
	v_dot8c_i32_i4_e32 v39, v130, v50
	v_dot8c_i32_i4_e32 v40, v132, v52
	v_dot8c_i32_i4_e32 v41, v132, v50
	v_dot8c_i32_i4_e32 v42, v134, v52
	v_dot8c_i32_i4_e32 v43, v134, v50
	v_dot8c_i32_i4_e32 v44, v136, v52
	v_dot8c_i32_i4_e32 v45, v136, v50
	v_dot8c_i32_i4_e32 v38, v131, v53
	v_dot8c_i32_i4_e32 v39, v131, v51
	v_dot8c_i32_i4_e32 v40, v133, v53
	v_dot8c_i32_i4_e32 v41, v133, v51
	v_dot8c_i32_i4_e32 v42, v135, v53
	v_dot8c_i32_i4_e32 v43, v135, v51
	v_dot8c_i32_i4_e32 v44, v137, v53
	v_dot8c_i32_i4_e32 v45, v137, v51
	v_and_b32_e32 v78, 0xffff, v29
	v_lshrrev_b32_e32 v79, 16, v29
	v_lshl_add_u32 v78, v78, 7, v152
	v_lshl_add_u32 v79, v79, 7, v153
	s_mov_b32 m0, s99
	s_add_i32 s43, s99, 0x400
	global_load_lds_dwordx4 v78, s[50:51]
	s_mov_b32 m0, s43
	s_nop 0
	global_load_lds_dwordx4 v79, s[50:51]
	s_waitcnt vmcnt(8)
	v_add_u32_e32 v54, s77, v59
	v_add_u32_e32 v55, s77, v60
	v_add_u32_e32 v56, s77, v61
	v_add_u32_e32 v57, s77, v62
	ds_read_b64_tr_b4 v[50:51], v160 offset:896
	ds_read_b64_tr_b4 v[52:53], v160 offset:1920
	ds_read_b64_tr_b4 v[130:131], v54
	ds_read_b64_tr_b4 v[132:133], v55
	ds_read_b64_tr_b4 v[134:135], v56
	ds_read_b64_tr_b4 v[136:137], v57
	s_waitcnt lgkmcnt(6)
	v_dot8c_i32_i4_e32 v38, v122, v48
	v_dot8c_i32_i4_e32 v39, v122, v46
	v_dot8c_i32_i4_e32 v40, v124, v48
	v_dot8c_i32_i4_e32 v41, v124, v46
	v_dot8c_i32_i4_e32 v42, v126, v48
	v_dot8c_i32_i4_e32 v43, v126, v46
	v_dot8c_i32_i4_e32 v44, v128, v48
	v_dot8c_i32_i4_e32 v45, v128, v46
	v_dot8c_i32_i4_e32 v38, v123, v49
	v_dot8c_i32_i4_e32 v39, v123, v47
	v_dot8c_i32_i4_e32 v40, v125, v49
	v_dot8c_i32_i4_e32 v41, v125, v47
	v_dot8c_i32_i4_e32 v42, v127, v49
	v_dot8c_i32_i4_e32 v43, v127, v47
	v_dot8c_i32_i4_e32 v44, v129, v49
	v_dot8c_i32_i4_e32 v45, v129, v47
	v_and_b32_e32 v78, 0xffff, v30
	v_lshrrev_b32_e32 v79, 16, v30
	v_lshl_add_u32 v78, v78, 7, v152
	v_lshl_add_u32 v79, v79, 7, v153
	s_mov_b32 m0, s76
	s_add_i32 s43, s76, 0x400
	global_load_lds_dwordx4 v78, s[50:51]
	s_mov_b32 m0, s43
	s_nop 0
	global_load_lds_dwordx4 v79, s[50:51]
	s_waitcnt vmcnt(8)
	v_add_u32_e32 v54, s78, v59
	v_add_u32_e32 v55, s78, v60
	v_add_u32_e32 v56, s78, v61
	v_add_u32_e32 v57, s78, v62
	ds_read_b64_tr_b4 v[46:47], v160
	ds_read_b64_tr_b4 v[48:49], v160 offset:1024
	ds_read_b64_tr_b4 v[122:123], v54
	ds_read_b64_tr_b4 v[124:125], v55
	ds_read_b64_tr_b4 v[126:127], v56
	ds_read_b64_tr_b4 v[128:129], v57
	s_waitcnt lgkmcnt(6)
	v_dot8c_i32_i4_e32 v38, v130, v52
	v_dot8c_i32_i4_e32 v39, v130, v50
	v_dot8c_i32_i4_e32 v40, v132, v52
	v_dot8c_i32_i4_e32 v41, v132, v50
	v_dot8c_i32_i4_e32 v42, v134, v52
	v_dot8c_i32_i4_e32 v43, v134, v50
	v_dot8c_i32_i4_e32 v44, v136, v52
	v_dot8c_i32_i4_e32 v45, v136, v50
	v_dot8c_i32_i4_e32 v38, v131, v53
	v_dot8c_i32_i4_e32 v39, v131, v51
	v_dot8c_i32_i4_e32 v40, v133, v53
	v_dot8c_i32_i4_e32 v41, v133, v51
	v_dot8c_i32_i4_e32 v42, v135, v53
	v_dot8c_i32_i4_e32 v43, v135, v51
	v_dot8c_i32_i4_e32 v44, v137, v53
	v_dot8c_i32_i4_e32 v45, v137, v51
	s_nop 3
	s_waitcnt lgkmcnt(15)
	v_lshlrev_b32_e32 v38, 5, v38
	v_lshlrev_b32_e32 v39, 1, v39
	v_add3_u32 v38, v39, v229, v38
	v_cvt_f32_i32_e32 v38, v38
	v_mul_f32_e32 v38, v228, v38
	v_lshlrev_b32_e32 v40, 5, v40
	v_lshlrev_b32_e32 v41, 1, v41
	v_add3_u32 v40, v41, v229, v40
	v_cvt_f32_i32_e32 v40, v40
	v_mul_f32_e32 v40, v228, v40
	v_lshlrev_b32_e32 v42, 5, v42
	v_lshlrev_b32_e32 v43, 1, v43
	v_add3_u32 v42, v43, v229, v42
	v_cvt_f32_i32_e32 v42, v42
	v_mul_f32_e32 v42, v228, v42
	v_lshlrev_b32_e32 v44, 5, v44
	v_lshlrev_b32_e32 v45, 1, v45
	v_add3_u32 v44, v45, v229, v44
	v_cvt_f32_i32_e32 v44, v44
	v_mul_f32_e32 v44, v228, v44
	v_cvt_pk_bf16_f32 v168, v38, v40
	v_cvt_pk_bf16_f32 v169, v42, v44
	s_add_i32 s43, s40, 0
	s_lshl_b32 s43, s43, 11
	v_add_u32_e32 v138, s43, v66
	global_load_dwordx2 v[194:195], v138, s[70:71]
	global_load_dwordx2 v[196:197], v138, s[70:71] offset:512
	global_load_dwordx2 v[198:199], v138, s[70:71] offset:1024
	global_load_dwordx2 v[200:201], v138, s[70:71] offset:1536
	v_add_u32_e32 v147, 8, v140
	v_and_b32_e32 v146, 15, v147
	v_xor_b32_e32 v146, 8, v146
	v_bfe_u32 v148, v147, 4, 4
	v_mul_lo_u32 v146, v146, s92
	v_mul_lo_u32 v148, v148, s92
	v_mov_b32_e32 v147, v146
	v_mov_b32_e32 v149, v148
	ds_write2st64_b64 v77, v[146:147], v[148:149] offset1:2
	v_add_u32_e32 v138, 0x800, v74
	ds_read_u8 v139, v138
	v_add_u32_e32 v141, 0x800, v73
	ds_read_u8 v140, v141
	s_add_i32 s43, s67, 32
	v_mov_b32_e32 v138, s43
	ds_read2st64_b32 v[228:229], v138 offset1:1
	ds_read_b128 v[18:21], v227 offset:4096
	ds_read_b128 v[22:25], v227 offset:4112
	v_mov_b32_e32 v150, v63
	v_mov_b32_e32 v151, v64
	v_mov_b32_e32 v38, 0
	v_mov_b32_e32 v39, 0
	v_mov_b32_e32 v40, 0
	v_mov_b32_e32 v41, 0
	v_mov_b32_e32 v42, 0
	v_mov_b32_e32 v43, 0
	v_mov_b32_e32 v44, 0
	v_mov_b32_e32 v45, 0
	v_and_b32_e32 v78, 0xffff, v31
	v_lshrrev_b32_e32 v79, 16, v31
	v_lshl_add_u32 v78, v78, 7, v152
	v_lshl_add_u32 v79, v79, 7, v153
	s_mov_b32 m0, s77
	s_add_i32 s43, s77, 0x400
	global_load_lds_dwordx4 v78, s[50:51]
	s_mov_b32 m0, s43
	s_nop 0
	global_load_lds_dwordx4 v79, s[50:51]
	s_waitcnt vmcnt(12)
; __device__ __forceinline__ bf16 f2bf(float f) { return (bf16)f2bfu(f); }
; #define TR4(p_) __builtin_amdgcn_ds_read_tr4_b64_v2i32((LAS v2i*)(p_))
; #define VDMA(st_, k_) do { _Pragma("unroll") for (int i_ = 0; i_ < 4; ++i_) { \
;         const unsigned off_ = (unsigned)((st_) >> 2) * (16384u * 128u) + (PE_ID(E, 4 * ((st_) & 3) + i_) << 7) + ((i_ & 1) ? cx1 : cx0); \
;         __builtin_amdgcn_global_load_lds((const unsigned*)(V4 + off_), (LAS unsigned*)(ldsb + BUF[k_] + 1024 * i_), 16, 0, 0); } } while (0)
; __device__ __forceinline__ void peer_v_tokens(int j, const LAS unsigned short* EL, const LAS unsigned char* AL  , const LAS float* ASC  , const LAS int* SAL  , ...
;     ...
;         for (int st = 0; st < 16; ++st) {
;             const int p = st >> 2, q = st & 3;
;             if (st < 14) VDMA(st + 2, (st + 2) % 3);
;             if (st < 14) asm volatile("s_waitcnt vmcnt(8)" ::: "memory");
;             else if (st == 14) asm volatile("s_waitcnt vmcnt(4)" ::: "memory");
;             else asm volatile("s_waitcnt vmcnt(0)" ::: "memory");
;             if (q == 0) {
; #pragma unroll
;                 for (int r = 0; r < 4; ++r) { accH[r] = 0; accL[r] = 0; } }
; #pragma unroll
;             for (int tp = 0; tp < 2; ++tp) {
;                 const v2i ao = TR4(ATL + (2 * q + tp) * 128 + 8 * s16), ah = TR4(ATL + 1024 + (2 * q + tp) * 128 + 8 * s16);
; #pragma unroll
;                 for (int r = 0; r < 4; ++r) {
;                     const v2i d = TR4(ldsb + BUF[st % 3] + 2048 * tp + roff[r]);
;                     accH[r] = __builtin_amdgcn_sdot8(d.x, ah.x, accH[r], false); accH[r] = __builtin_amdgcn_sdot8(d.y, ah.y, accH[r], false);
;                     accL[r] = __builtin_amdgcn_sdot8(d.x, ao.x, accL[r], false); accL[r] = __builtin_amdgcn_sdot8(d.y, ao.y, accL[r], false);
;                 }
;             }
;             asm volatile("s_waitcnt lgkmcnt(0)" ::: "memory");
;             if (q == 3) {
; #pragma unroll
;                 for (int r = 0; r < 4; ++r) STASH[256 * p + 16 * (grp + 4 * r) + pc] = f2bf(asc * (float)(2 * ((accH[r] << 4) + accL[r]) + sa));
;             }
;         }
	v_add_u32_e32 v54, s79, v59
	v_add_u32_e32 v55, s79, v60
	v_add_u32_e32 v56, s79, v61
	v_add_u32_e32 v57, s79, v62
	ds_read_b64_tr_b4 v[50:51], v160 offset:128
	ds_read_b64_tr_b4 v[52:53], v160 offset:1152
	ds_read_b64_tr_b4 v[130:131], v54
	ds_read_b64_tr_b4 v[132:133], v55
	ds_read_b64_tr_b4 v[134:135], v56
	ds_read_b64_tr_b4 v[136:137], v57
	s_waitcnt lgkmcnt(12)
	v_dot8c_i32_i4_e32 v38, v122, v48
	v_dot8c_i32_i4_e32 v39, v122, v46
	v_dot8c_i32_i4_e32 v40, v124, v48
	v_dot8c_i32_i4_e32 v41, v124, v46
	v_dot8c_i32_i4_e32 v42, v126, v48
	v_dot8c_i32_i4_e32 v43, v126, v46
	v_dot8c_i32_i4_e32 v44, v128, v48
	v_dot8c_i32_i4_e32 v45, v128, v46
	v_dot8c_i32_i4_e32 v38, v123, v49
	v_dot8c_i32_i4_e32 v39, v123, v47
	v_dot8c_i32_i4_e32 v40, v125, v49
	v_dot8c_i32_i4_e32 v41, v125, v47
	v_dot8c_i32_i4_e32 v42, v127, v49
	v_dot8c_i32_i4_e32 v43, v127, v47
	v_dot8c_i32_i4_e32 v44, v129, v49
	v_dot8c_i32_i4_e32 v45, v129, v47
	v_and_b32_e32 v78, 0xffff, v32
	v_lshrrev_b32_e32 v79, 16, v32
	v_lshl_add_u32 v78, v78, 7, v152
	v_lshl_add_u32 v79, v79, 7, v153
	s_mov_b32 m0, s78
	s_add_i32 s43, s78, 0x400
	global_load_lds_dwordx4 v78, s[50:51]
	s_mov_b32 m0, s43
	s_nop 0
	global_load_lds_dwordx4 v79, s[50:51]
	s_waitcnt vmcnt(12)
	v_add_u32_e32 v54, s98, v59
	v_add_u32_e32 v55, s98, v60
	v_add_u32_e32 v56, s98, v61
	v_add_u32_e32 v57, s98, v62
	ds_read_b64_tr_b4 v[46:47], v160 offset:256
	ds_read_b64_tr_b4 v[48:49], v160 offset:1280
	ds_read_b64_tr_b4 v[122:123], v54
	ds_read_b64_tr_b4 v[124:125], v55
	ds_read_b64_tr_b4 v[126:127], v56
	ds_read_b64_tr_b4 v[128:129], v57
	s_waitcnt lgkmcnt(6)
	v_dot8c_i32_i4_e32 v38, v130, v52
	v_dot8c_i32_i4_e32 v39, v130, v50
	v_dot8c_i32_i4_e32 v40, v132, v52
	v_dot8c_i32_i4_e32 v41, v132, v50
	v_dot8c_i32_i4_e32 v42, v134, v52
	v_dot8c_i32_i4_e32 v43, v134, v50
	v_dot8c_i32_i4_e32 v44, v136, v52
	v_dot8c_i32_i4_e32 v45, v136, v50
	v_dot8c_i32_i4_e32 v38, v131, v53
	v_dot8c_i32_i4_e32 v39, v131, v51
	v_dot8c_i32_i4_e32 v40, v133, v53
	v_dot8c_i32_i4_e32 v41, v133, v51
	v_dot8c_i32_i4_e32 v42, v135, v53
	v_dot8c_i32_i4_e32 v43, v135, v51
	v_dot8c_i32_i4_e32 v44, v137, v53
	v_dot8c_i32_i4_e32 v45, v137, v51
	v_and_b32_e32 v78, 0xffff, v33
	v_lshrrev_b32_e32 v79, 16, v33
	v_lshl_add_u32 v78, v78, 7, v152
	v_lshl_add_u32 v79, v79, 7, v153
	s_mov_b32 m0, s79
	s_add_i32 s43, s79, 0x400
	global_load_lds_dwordx4 v78, s[50:51]
	s_mov_b32 m0, s43
	s_nop 0
	global_load_lds_dwordx4 v79, s[50:51]
	s_waitcnt vmcnt(12)
	v_add_u32_e32 v54, s99, v59
	v_add_u32_e32 v55, s99, v60
	v_add_u32_e32 v56, s99, v61
	v_add_u32_e32 v57, s99, v62
	ds_read_b64_tr_b4 v[50:51], v160 offset:384
	ds_read_b64_tr_b4 v[52:53], v160 offset:1408
	ds_read_b64_tr_b4 v[130:131], v54
	ds_read_b64_tr_b4 v[132:133], v55
	ds_read_b64_tr_b4 v[134:135], v56
	ds_read_b64_tr_b4 v[136:137], v57
	s_waitcnt lgkmcnt(6)
	v_dot8c_i32_i4_e32 v38, v122, v48
	v_dot8c_i32_i4_e32 v39, v122, v46
	v_dot8c_i32_i4_e32 v40, v124, v48
	v_dot8c_i32_i4_e32 v41, v124, v46
	v_dot8c_i32_i4_e32 v42, v126, v48
	v_dot8c_i32_i4_e32 v43, v126, v46
	v_dot8c_i32_i4_e32 v44, v128, v48
	v_dot8c_i32_i4_e32 v45, v128, v46
	v_dot8c_i32_i4_e32 v38, v123, v49
	v_dot8c_i32_i4_e32 v39, v123, v47
	v_dot8c_i32_i4_e32 v40, v125, v49
	v_dot8c_i32_i4_e32 v41, v125, v47
	v_dot8c_i32_i4_e32 v42, v127, v49
	v_dot8c_i32_i4_e32 v43, v127, v47
	v_dot8c_i32_i4_e32 v44, v129, v49
	v_dot8c_i32_i4_e32 v45, v129, v47
	s_waitcnt lgkmcnt(15)
	v_and_b32_e32 v78, 0xffff, v18
	v_lshrrev_b32_e32 v79, 16, v18
	v_lshl_add_u32 v78, v78, 7, v150
	v_lshl_add_u32 v79, v79, 7, v151
	s_mov_b32 m0, s98
	s_add_i32 s43, s98, 0x400
	global_load_lds_dwordx4 v78, s[50:51]
	s_mov_b32 m0, s43
	s_nop 0
	global_load_lds_dwordx4 v79, s[50:51]
	s_waitcnt vmcnt(12)
	v_add_u32_e32 v54, s76, v59
	v_add_u32_e32 v55, s76, v60
	v_add_u32_e32 v56, s76, v61
	v_add_u32_e32 v57, s76, v62
	ds_read_b64_tr_b4 v[46:47], v160 offset:512
	ds_read_b64_tr_b4 v[48:49], v160 offset:1536
	ds_read_b64_tr_b4 v[122:123], v54
	ds_read_b64_tr_b4 v[124:125], v55
	ds_read_b64_tr_b4 v[126:127], v56
	ds_read_b64_tr_b4 v[128:129], v57
	s_waitcnt lgkmcnt(6)
	v_dot8c_i32_i4_e32 v38, v130, v52
	v_dot8c_i32_i4_e32 v39, v130, v50
	v_dot8c_i32_i4_e32 v40, v132, v52
	v_dot8c_i32_i4_e32 v41, v132, v50
	v_dot8c_i32_i4_e32 v42, v134, v52
	v_dot8c_i32_i4_e32 v43, v134, v50
	v_dot8c_i32_i4_e32 v44, v136, v52
	v_dot8c_i32_i4_e32 v45, v136, v50
	v_dot8c_i32_i4_e32 v38, v131, v53
	v_dot8c_i32_i4_e32 v39, v131, v51
	v_dot8c_i32_i4_e32 v40, v133, v53
	v_dot8c_i32_i4_e32 v41, v133, v51
	v_dot8c_i32_i4_e32 v42, v135, v53
	v_dot8c_i32_i4_e32 v43, v135, v51
	v_dot8c_i32_i4_e32 v44, v137, v53
	v_dot8c_i32_i4_e32 v45, v137, v51
	v_and_b32_e32 v78, 0xffff, v19
	v_lshrrev_b32_e32 v79, 16, v19
	v_lshl_add_u32 v78, v78, 7, v150
	v_lshl_add_u32 v79, v79, 7, v151
	s_mov_b32 m0, s99
	s_add_i32 s43, s99, 0x400
	global_load_lds_dwordx4 v78, s[50:51]
	s_mov_b32 m0, s43
	s_nop 0
	global_load_lds_dwordx4 v79, s[50:51]
	s_waitcnt vmcnt(8)
	v_add_u32_e32 v54, s77, v59
	v_add_u32_e32 v55, s77, v60
	v_add_u32_e32 v56, s77, v61
	v_add_u32_e32 v57, s77, v62
	ds_read_b64_tr_b4 v[50:51], v160 offset:640
	ds_read_b64_tr_b4 v[52:53], v160 offset:1664
	ds_read_b64_tr_b4 v[130:131], v54
	ds_read_b64_tr_b4 v[132:133], v55
	ds_read_b64_tr_b4 v[134:135], v56
	ds_read_b64_tr_b4 v[136:137], v57
	s_waitcnt lgkmcnt(6)
	v_dot8c_i32_i4_e32 v38, v122, v48
	v_dot8c_i32_i4_e32 v39, v122, v46
	v_dot8c_i32_i4_e32 v40, v124, v48
	v_dot8c_i32_i4_e32 v41, v124, v46
	v_dot8c_i32_i4_e32 v42, v126, v48
	v_dot8c_i32_i4_e32 v43, v126, v46
	v_dot8c_i32_i4_e32 v44, v128, v48
	v_dot8c_i32_i4_e32 v45, v128, v46
	v_dot8c_i32_i4_e32 v38, v123, v49
	v_dot8c_i32_i4_e32 v39, v123, v47
	v_dot8c_i32_i4_e32 v40, v125, v49
	v_dot8c_i32_i4_e32 v41, v125, v47
	v_dot8c_i32_i4_e32 v42, v127, v49
	v_dot8c_i32_i4_e32 v43, v127, v47
	v_dot8c_i32_i4_e32 v44, v129, v49
	v_dot8c_i32_i4_e32 v45, v129, v47
	s_waitcnt lgkmcnt(15)
; #define LAS __attribute__((address_space(3)))
; __device__ __forceinline__ bf16 f2bf(float f) { return (bf16)f2bfu(f); }
; __device__ __forceinline__ void peer_v_tokens(int j, const LAS unsigned short* EL, const LAS unsigned char* AL  , const LAS float* ASC  , const LAS int* SAL  , ...
;     ...
;         for (int m = 0; m < 2; ++m) {
;             const int idx = lane + 64 * m, tau = idx >> 4, sr = idx & 15, k = 16 * (sr & 7) + 2 * tau + (sr >> 3);
;             const int aq = (int)*(const LAS signed char*)(AL + tl * 128 + k); const int tq = aq + 8;
;             const unsigned lo = (((unsigned)tq & 15u) ^ 8u) * 0x11111111u, hi = ((unsigned)(tq >> 4) & 15u) * 0x11111111u;
;             typedef unsigned u2v __attribute__((ext_vector_type(2)));
;             u2v l2; l2.x = lo; l2.y = lo; u2v h2; h2.x = hi; h2.y = hi;
;             *(LAS u2v*)(ATL + 8 * idx) = l2; *(LAS u2v*)(ATL + 1024 + 8 * idx) = h2;
;         }
;     ...
;         for (int st = 0; st < 16; ++st) {
;             const int p = st >> 2, q = st & 3;
;             if (st < 14) VDMA(st + 2, (st + 2) % 3);
;             if (st < 14) asm volatile("s_waitcnt vmcnt(8)" ::: "memory");
;             else if (st == 14) asm volatile("s_waitcnt vmcnt(4)" ::: "memory");
;             else asm volatile("s_waitcnt vmcnt(0)" ::: "memory");
;             if (q == 0) {
; #pragma unroll
;                 for (int r = 0; r < 4; ++r) { accH[r] = 0; accL[r] = 0; } }
; #pragma unroll
;             for (int tp = 0; tp < 2; ++tp) {
;                 const v2i ao = TR4(ATL + (2 * q + tp) * 128 + 8 * s16), ah = TR4(ATL + 1024 + (2 * q + tp) * 128 + 8 * s16);
; #pragma unroll
;                 for (int r = 0; r < 4; ++r) {
;                     const v2i d = TR4(ldsb + BUF[st % 3] + 2048 * tp + roff[r]);
;                     accH[r] = __builtin_amdgcn_sdot8(d.x, ah.x, accH[r], false); accH[r] = __builtin_amdgcn_sdot8(d.y, ah.y, accH[r], false);
;                     accL[r] = __builtin_amdgcn_sdot8(d.x, ao.x, accL[r], false); accL[r] = __builtin_amdgcn_sdot8(d.y, ao.y, accL[r], false);
;                 }
;             }
;             asm volatile("s_waitcnt lgkmcnt(0)" ::: "memory");
;             if (q == 3) {
; #pragma unroll
;                 for (int r = 0; r < 4; ++r) STASH[256 * p + 16 * (grp + 4 * r) + pc] = f2bf(asc * (float)(2 * ((accH[r] << 4) + accL[r]) + sa));
;             }
;         }
	v_add_u32_e32 v143, 8, v139
	v_and_b32_e32 v142, 15, v143
	v_xor_b32_e32 v142, 8, v142
	v_bfe_u32 v144, v143, 4, 4
	v_mul_lo_u32 v142, v142, s92
	v_mul_lo_u32 v144, v144, s92
	v_mov_b32_e32 v143, v142
	v_mov_b32_e32 v145, v144
	ds_write2st64_b64 v159, v[142:143], v[144:145] offset1:2
	v_and_b32_e32 v78, 0xffff, v20
	v_lshrrev_b32_e32 v79, 16, v20
	v_lshl_add_u32 v78, v78, 7, v150
	v_lshl_add_u32 v79, v79, 7, v151
	s_mov_b32 m0, s76
	s_add_i32 s43, s76, 0x400
	global_load_lds_dwordx4 v78, s[50:51]
	s_mov_b32 m0, s43
	s_nop 0
	global_load_lds_dwordx4 v79, s[50:51]
	s_waitcnt vmcnt(8)
	v_add_u32_e32 v54, s78, v59
	v_add_u32_e32 v55, s78, v60
	v_add_u32_e32 v56, s78, v61
	v_add_u32_e32 v57, s78, v62
	ds_read_b64_tr_b4 v[46:47], v160 offset:768
	ds_read_b64_tr_b4 v[48:49], v160 offset:1792
	ds_read_b64_tr_b4 v[122:123], v54
	ds_read_b64_tr_b4 v[124:125], v55
	ds_read_b64_tr_b4 v[126:127], v56
	ds_read_b64_tr_b4 v[128:129], v57
	s_waitcnt lgkmcnt(7)
	v_dot8c_i32_i4_e32 v38, v130, v52
	v_dot8c_i32_i4_e32 v39, v130, v50
	v_dot8c_i32_i4_e32 v40, v132, v52
	v_dot8c_i32_i4_e32 v41, v132, v50
	v_dot8c_i32_i4_e32 v42, v134, v52
	v_dot8c_i32_i4_e32 v43, v134, v50
	v_dot8c_i32_i4_e32 v44, v136, v52
	v_dot8c_i32_i4_e32 v45, v136, v50
	v_dot8c_i32_i4_e32 v38, v131, v53
	v_dot8c_i32_i4_e32 v39, v131, v51
	v_dot8c_i32_i4_e32 v40, v133, v53
	v_dot8c_i32_i4_e32 v41, v133, v51
	v_dot8c_i32_i4_e32 v42, v135, v53
	v_dot8c_i32_i4_e32 v43, v135, v51
	v_dot8c_i32_i4_e32 v44, v137, v53
	v_dot8c_i32_i4_e32 v45, v137, v51
	v_and_b32_e32 v78, 0xffff, v21
	v_lshrrev_b32_e32 v79, 16, v21
	v_lshl_add_u32 v78, v78, 7, v150
	v_lshl_add_u32 v79, v79, 7, v151
	s_mov_b32 m0, s77
	s_add_i32 s43, s77, 0x400
	global_load_lds_dwordx4 v78, s[50:51]
	s_mov_b32 m0, s43
	s_nop 0
	global_load_lds_dwordx4 v79, s[50:51]
	s_waitcnt vmcnt(8)
	v_add_u32_e32 v54, s79, v59
	v_add_u32_e32 v55, s79, v60
	v_add_u32_e32 v56, s79, v61
	v_add_u32_e32 v57, s79, v62
	ds_read_b64_tr_b4 v[50:51], v160 offset:896
	ds_read_b64_tr_b4 v[52:53], v160 offset:1920
	ds_read_b64_tr_b4 v[130:131], v54
	ds_read_b64_tr_b4 v[132:133], v55
	ds_read_b64_tr_b4 v[134:135], v56
	ds_read_b64_tr_b4 v[136:137], v57
	s_waitcnt lgkmcnt(6)
	v_dot8c_i32_i4_e32 v38, v122, v48
	v_dot8c_i32_i4_e32 v39, v122, v46
	v_dot8c_i32_i4_e32 v40, v124, v48
	v_dot8c_i32_i4_e32 v41, v124, v46
	v_dot8c_i32_i4_e32 v42, v126, v48
	v_dot8c_i32_i4_e32 v43, v126, v46
	v_dot8c_i32_i4_e32 v44, v128, v48
	v_dot8c_i32_i4_e32 v45, v128, v46
	v_dot8c_i32_i4_e32 v38, v123, v49
	v_dot8c_i32_i4_e32 v39, v123, v47
	v_dot8c_i32_i4_e32 v40, v125, v49
	v_dot8c_i32_i4_e32 v41, v125, v47
	v_dot8c_i32_i4_e32 v42, v127, v49
	v_dot8c_i32_i4_e32 v43, v127, v47
	v_dot8c_i32_i4_e32 v44, v129, v49
	v_dot8c_i32_i4_e32 v45, v129, v47
	v_and_b32_e32 v78, 0xffff, v22
	v_lshrrev_b32_e32 v79, 16, v22
	v_lshl_add_u32 v78, v78, 7, v150
	v_lshl_add_u32 v79, v79, 7, v151
	s_mov_b32 m0, s78
	s_add_i32 s43, s78, 0x400
	global_load_lds_dwordx4 v78, s[50:51]
	s_mov_b32 m0, s43
	s_nop 0
	global_load_lds_dwordx4 v79, s[50:51]
	s_waitcnt vmcnt(8)
	v_add_u32_e32 v54, s98, v59
	v_add_u32_e32 v55, s98, v60
	v_add_u32_e32 v56, s98, v61
	v_add_u32_e32 v57, s98, v62
	ds_read_b64_tr_b4 v[46:47], v160
	ds_read_b64_tr_b4 v[48:49], v160 offset:1024
	ds_read_b64_tr_b4 v[122:123], v54
	ds_read_b64_tr_b4 v[124:125], v55
	ds_read_b64_tr_b4 v[126:127], v56
	ds_read_b64_tr_b4 v[128:129], v57
	s_waitcnt lgkmcnt(6)
	v_dot8c_i32_i4_e32 v38, v130, v52
	v_dot8c_i32_i4_e32 v39, v130, v50
	v_dot8c_i32_i4_e32 v40, v132, v52
	v_dot8c_i32_i4_e32 v41, v132, v50
	v_dot8c_i32_i4_e32 v42, v134, v52
	v_dot8c_i32_i4_e32 v43, v134, v50
	v_dot8c_i32_i4_e32 v44, v136, v52
	v_dot8c_i32_i4_e32 v45, v136, v50
	v_dot8c_i32_i4_e32 v38, v131, v53
	v_dot8c_i32_i4_e32 v39, v131, v51
	v_dot8c_i32_i4_e32 v40, v133, v53
	v_dot8c_i32_i4_e32 v41, v133, v51
	v_dot8c_i32_i4_e32 v42, v135, v53
	v_dot8c_i32_i4_e32 v43, v135, v51
	v_dot8c_i32_i4_e32 v44, v137, v53
	v_dot8c_i32_i4_e32 v45, v137, v51
	s_nop 3
	s_waitcnt lgkmcnt(15)
	v_lshlrev_b32_e32 v38, 5, v38
	v_lshlrev_b32_e32 v39, 1, v39
	v_add3_u32 v38, v39, v229, v38
	v_cvt_f32_i32_e32 v38, v38
	v_mul_f32_e32 v38, v228, v38
	v_lshlrev_b32_e32 v40, 5, v40
	v_lshlrev_b32_e32 v41, 1, v41
	v_add3_u32 v40, v41, v229, v40
	v_cvt_f32_i32_e32 v40, v40
	v_mul_f32_e32 v40, v228, v40
	v_lshlrev_b32_e32 v42, 5, v42
	v_lshlrev_b32_e32 v43, 1, v43
	v_add3_u32 v42, v43, v229, v42
	v_cvt_f32_i32_e32 v42, v42
	v_mul_f32_e32 v42, v228, v42
	v_lshlrev_b32_e32 v44, 5, v44
	v_lshlrev_b32_e32 v45, 1, v45
	v_add3_u32 v44, v45, v229, v44
	v_cvt_f32_i32_e32 v44, v44
	v_mul_f32_e32 v44, v228, v44
	v_cvt_pk_bf16_f32 v176, v38, v40
	v_cvt_pk_bf16_f32 v177, v42, v44
	v_add_u32_e32 v147, 8, v140
	v_and_b32_e32 v146, 15, v147
	v_xor_b32_e32 v146, 8, v146
	v_bfe_u32 v148, v147, 4, 4
	v_mul_lo_u32 v146, v146, s92
	v_mul_lo_u32 v148, v148, s92
	v_mov_b32_e32 v147, v146
	v_mov_b32_e32 v149, v148
	ds_write2st64_b64 v77, v[146:147], v[148:149] offset1:2
	v_add_u32_e32 v138, 0xc00, v74
	ds_read_u8 v139, v138
	v_add_u32_e32 v141, 0xc00, v73
	ds_read_u8 v140, v141
	s_add_i32 s43, s67, 64
	v_mov_b32_e32 v138, s43
	ds_read2st64_b32 v[228:229], v138 offset1:1
	ds_read_b128 v[26:29], v227 offset:6144
	ds_read_b128 v[30:33], v227 offset:6160
	v_mov_b32_e32 v38, 0
	v_mov_b32_e32 v39, 0
	v_mov_b32_e32 v40, 0
	v_mov_b32_e32 v41, 0
	v_mov_b32_e32 v42, 0
	v_mov_b32_e32 v43, 0
	v_mov_b32_e32 v44, 0
	v_mov_b32_e32 v45, 0
	v_and_b32_e32 v78, 0xffff, v23
	v_lshrrev_b32_e32 v79, 16, v23
	v_lshl_add_u32 v78, v78, 7, v150
	v_lshl_add_u32 v79, v79, 7, v151
	s_mov_b32 m0, s79
	s_add_i32 s43, s79, 0x400
	global_load_lds_dwordx4 v78, s[50:51]
	s_mov_b32 m0, s43
	s_nop 0
	global_load_lds_dwordx4 v79, s[50:51]
	s_waitcnt vmcnt(8)
; #define LAS __attribute__((address_space(3)))
; __device__ __forceinline__ bf16 f2bf(float f) { return (bf16)f2bfu(f); }
; #define TR4(p_) __builtin_amdgcn_ds_read_tr4_b64_v2i32((LAS v2i*)(p_))
; #define CFENCE() asm volatile("" ::: "memory")
; __device__ __forceinline__ void peer_v_tokens(int j, const LAS unsigned short* EL, const LAS unsigned char* AL  , const LAS float* ASC  , const LAS int* SAL  , ...
;     ...
;         for (int st = 0; st < 16; ++st) {
;             const int p = st >> 2, q = st & 3;
;             if (st < 14) VDMA(st + 2, (st + 2) % 3);
;             if (st < 14) asm volatile("s_waitcnt vmcnt(8)" ::: "memory");
;             else if (st == 14) asm volatile("s_waitcnt vmcnt(4)" ::: "memory");
;             else asm volatile("s_waitcnt vmcnt(0)" ::: "memory");
;             if (q == 0) {
; #pragma unroll
;                 for (int r = 0; r < 4; ++r) { accH[r] = 0; accL[r] = 0; } }
; #pragma unroll
;             for (int tp = 0; tp < 2; ++tp) {
;                 const v2i ao = TR4(ATL + (2 * q + tp) * 128 + 8 * s16), ah = TR4(ATL + 1024 + (2 * q + tp) * 128 + 8 * s16);
; #pragma unroll
;                 for (int r = 0; r < 4; ++r) {
;                     const v2i d = TR4(ldsb + BUF[st % 3] + 2048 * tp + roff[r]);
;                     accH[r] = __builtin_amdgcn_sdot8(d.x, ah.x, accH[r], false); accH[r] = __builtin_amdgcn_sdot8(d.y, ah.y, accH[r], false);
;                     accL[r] = __builtin_amdgcn_sdot8(d.x, ao.x, accL[r], false); accL[r] = __builtin_amdgcn_sdot8(d.y, ao.y, accL[r], false);
;                 }
;             }
;             asm volatile("s_waitcnt lgkmcnt(0)" ::: "memory");
;             if (q == 3) {
; #pragma unroll
;                 for (int r = 0; r < 4; ++r) STASH[256 * p + 16 * (grp + 4 * r) + pc] = f2bf(asc * (float)(2 * ((accH[r] << 4) + accL[r]) + sa));
;             }
;         }
;         CFENCE();
;         {
;             float4 v[4]; float ss = 0.f;
; #pragma unroll
;             for (int jq = 0; jq < 4; ++jq) { typedef unsigned u2v __attribute__((ext_vector_type(2))); const u2v pw = *(const LAS u2v*)(STASH + 4 * lane + 256 * jq); const uint2 hw = hv[jq];
	v_add_u32_e32 v54, s99, v59
	v_add_u32_e32 v55, s99, v60
	v_add_u32_e32 v56, s99, v61
	v_add_u32_e32 v57, s99, v62
	ds_read_b64_tr_b4 v[50:51], v160 offset:128
	ds_read_b64_tr_b4 v[52:53], v160 offset:1152
	ds_read_b64_tr_b4 v[130:131], v54
	ds_read_b64_tr_b4 v[132:133], v55
	ds_read_b64_tr_b4 v[134:135], v56
	ds_read_b64_tr_b4 v[136:137], v57
	s_waitcnt lgkmcnt(12)
	v_dot8c_i32_i4_e32 v38, v122, v48
	v_dot8c_i32_i4_e32 v39, v122, v46
	v_dot8c_i32_i4_e32 v40, v124, v48
	v_dot8c_i32_i4_e32 v41, v124, v46
	v_dot8c_i32_i4_e32 v42, v126, v48
	v_dot8c_i32_i4_e32 v43, v126, v46
	v_dot8c_i32_i4_e32 v44, v128, v48
	v_dot8c_i32_i4_e32 v45, v128, v46
	v_dot8c_i32_i4_e32 v38, v123, v49
	v_dot8c_i32_i4_e32 v39, v123, v47
	v_dot8c_i32_i4_e32 v40, v125, v49
	v_dot8c_i32_i4_e32 v41, v125, v47
	v_dot8c_i32_i4_e32 v42, v127, v49
	v_dot8c_i32_i4_e32 v43, v127, v47
	v_dot8c_i32_i4_e32 v44, v129, v49
	v_dot8c_i32_i4_e32 v45, v129, v47
	v_and_b32_e32 v78, 0xffff, v24
	v_lshrrev_b32_e32 v79, 16, v24
	v_lshl_add_u32 v78, v78, 7, v150
	v_lshl_add_u32 v79, v79, 7, v151
	s_mov_b32 m0, s98
	s_add_i32 s43, s98, 0x400
	global_load_lds_dwordx4 v78, s[50:51]
	s_mov_b32 m0, s43
	s_nop 0
	global_load_lds_dwordx4 v79, s[50:51]
	s_waitcnt vmcnt(8)
	v_add_u32_e32 v54, s76, v59
	v_add_u32_e32 v55, s76, v60
	v_add_u32_e32 v56, s76, v61
	v_add_u32_e32 v57, s76, v62
	ds_read_b64_tr_b4 v[46:47], v160 offset:256
	ds_read_b64_tr_b4 v[48:49], v160 offset:1280
	ds_read_b64_tr_b4 v[122:123], v54
	ds_read_b64_tr_b4 v[124:125], v55
	ds_read_b64_tr_b4 v[126:127], v56
	ds_read_b64_tr_b4 v[128:129], v57
	s_waitcnt lgkmcnt(6)
	v_dot8c_i32_i4_e32 v38, v130, v52
	v_dot8c_i32_i4_e32 v39, v130, v50
	v_dot8c_i32_i4_e32 v40, v132, v52
	v_dot8c_i32_i4_e32 v41, v132, v50
	v_dot8c_i32_i4_e32 v42, v134, v52
	v_dot8c_i32_i4_e32 v43, v134, v50
	v_dot8c_i32_i4_e32 v44, v136, v52
	v_dot8c_i32_i4_e32 v45, v136, v50
	v_dot8c_i32_i4_e32 v38, v131, v53
	v_dot8c_i32_i4_e32 v39, v131, v51
	v_dot8c_i32_i4_e32 v40, v133, v53
	v_dot8c_i32_i4_e32 v41, v133, v51
	v_dot8c_i32_i4_e32 v42, v135, v53
	v_dot8c_i32_i4_e32 v43, v135, v51
	v_dot8c_i32_i4_e32 v44, v137, v53
	v_dot8c_i32_i4_e32 v45, v137, v51
	ds_write_b16 v65, v162
	ds_write_b16_d16_hi v65, v162 offset:128
	ds_write_b16 v65, v163 offset:256
	ds_write_b16_d16_hi v65, v163 offset:384
	ds_write_b16 v65, v164 offset:512
	ds_write_b16_d16_hi v65, v164 offset:640
	ds_write_b16 v65, v165 offset:768
	ds_write_b16_d16_hi v65, v165 offset:896
	ds_write_b16 v65, v166 offset:1024
	ds_write_b16_d16_hi v65, v166 offset:1152
	ds_write_b16 v65, v167 offset:1280
	ds_write_b16_d16_hi v65, v167 offset:1408
	ds_write_b16 v65, v168 offset:1536
	ds_write_b16_d16_hi v65, v168 offset:1664
	ds_write_b16 v65, v169 offset:1792
	ds_write_b16_d16_hi v65, v169 offset:1920
	ds_read_b64 v[202:203], v154
	ds_read_b64 v[204:205], v154 offset:512
	ds_read_b64 v[206:207], v154 offset:1024
	ds_read_b64 v[208:209], v154 offset:1536
	v_and_b32_e32 v78, 0xffff, v25
	v_lshrrev_b32_e32 v79, 16, v25
	v_lshl_add_u32 v78, v78, 7, v150
	v_lshl_add_u32 v79, v79, 7, v151
	s_mov_b32 m0, s99
	s_add_i32 s43, s99, 0x400
	global_load_lds_dwordx4 v78, s[50:51]
	s_mov_b32 m0, s43
	s_nop 0
	global_load_lds_dwordx4 v79, s[50:51]
	s_waitcnt vmcnt(8)
	v_add_u32_e32 v54, s77, v59
	v_add_u32_e32 v55, s77, v60
	v_add_u32_e32 v56, s77, v61
	v_add_u32_e32 v57, s77, v62
	ds_read_b64_tr_b4 v[50:51], v160 offset:384
	ds_read_b64_tr_b4 v[52:53], v160 offset:1408
	ds_read_b64_tr_b4 v[130:131], v54
	ds_read_b64_tr_b4 v[132:133], v55
	ds_read_b64_tr_b4 v[134:135], v56
	ds_read_b64_tr_b4 v[136:137], v57
	s_waitcnt lgkmcnt(15)
	v_dot8c_i32_i4_e32 v38, v122, v48
	v_dot8c_i32_i4_e32 v39, v122, v46
	v_dot8c_i32_i4_e32 v40, v124, v48
	v_dot8c_i32_i4_e32 v41, v124, v46
	v_dot8c_i32_i4_e32 v42, v126, v48
	v_dot8c_i32_i4_e32 v43, v126, v46
	v_dot8c_i32_i4_e32 v44, v128, v48
	v_dot8c_i32_i4_e32 v45, v128, v46
	v_dot8c_i32_i4_e32 v38, v123, v49
	v_dot8c_i32_i4_e32 v39, v123, v47
	v_dot8c_i32_i4_e32 v40, v125, v49
	v_dot8c_i32_i4_e32 v41, v125, v47
	v_dot8c_i32_i4_e32 v42, v127, v49
	v_dot8c_i32_i4_e32 v43, v127, v47
	v_dot8c_i32_i4_e32 v44, v129, v49
	v_dot8c_i32_i4_e32 v45, v129, v47
	s_waitcnt lgkmcnt(15)
	v_and_b32_e32 v78, 0xffff, v26
	v_lshrrev_b32_e32 v79, 16, v26
	v_lshl_add_u32 v78, v78, 7, v150
	v_lshl_add_u32 v79, v79, 7, v151
	s_mov_b32 m0, s76
	s_add_i32 s43, s76, 0x400
	global_load_lds_dwordx4 v78, s[50:51]
	s_mov_b32 m0, s43
	s_nop 0
	global_load_lds_dwordx4 v79, s[50:51]
	s_waitcnt vmcnt(8)
	v_add_u32_e32 v54, s78, v59
	v_add_u32_e32 v55, s78, v60
	v_add_u32_e32 v56, s78, v61
	v_add_u32_e32 v57, s78, v62
	ds_read_b64_tr_b4 v[46:47], v160 offset:512
	ds_read_b64_tr_b4 v[48:49], v160 offset:1536
	ds_read_b64_tr_b4 v[122:123], v54
	ds_read_b64_tr_b4 v[124:125], v55
	ds_read_b64_tr_b4 v[126:127], v56
	ds_read_b64_tr_b4 v[128:129], v57
	s_waitcnt lgkmcnt(6)
	v_dot8c_i32_i4_e32 v38, v130, v52
	v_dot8c_i32_i4_e32 v39, v130, v50
	v_dot8c_i32_i4_e32 v40, v132, v52
	v_dot8c_i32_i4_e32 v41, v132, v50
	v_dot8c_i32_i4_e32 v42, v134, v52
	v_dot8c_i32_i4_e32 v43, v134, v50
	v_dot8c_i32_i4_e32 v44, v136, v52
	v_dot8c_i32_i4_e32 v45, v136, v50
	v_dot8c_i32_i4_e32 v38, v131, v53
	v_dot8c_i32_i4_e32 v39, v131, v51
	v_dot8c_i32_i4_e32 v40, v133, v53
	v_dot8c_i32_i4_e32 v41, v133, v51
	v_dot8c_i32_i4_e32 v42, v135, v53
	v_dot8c_i32_i4_e32 v43, v135, v51
	v_dot8c_i32_i4_e32 v44, v137, v53
	v_dot8c_i32_i4_e32 v45, v137, v51
	v_and_b32_e32 v78, 0xffff, v27
	v_lshrrev_b32_e32 v79, 16, v27
	v_lshl_add_u32 v78, v78, 7, v150
	v_lshl_add_u32 v79, v79, 7, v151
	s_mov_b32 m0, s77
	s_add_i32 s43, s77, 0x400
	global_load_lds_dwordx4 v78, s[50:51]
	s_mov_b32 m0, s43
	s_nop 0
	global_load_lds_dwordx4 v79, s[50:51]
	s_waitcnt vmcnt(8)
; #define LAS __attribute__((address_space(3)))
; __device__ __forceinline__ bf16 f2bf(float f) { return (bf16)f2bfu(f); }
; __device__ __forceinline__ void peer_v_tokens(int j, const LAS unsigned short* EL, const LAS unsigned char* AL  , const LAS float* ASC  , const LAS int* SAL  , ...
;     ...
;         for (int m = 0; m < 2; ++m) {
;             const int idx = lane + 64 * m, tau = idx >> 4, sr = idx & 15, k = 16 * (sr & 7) + 2 * tau + (sr >> 3);
;             const int aq = (int)*(const LAS signed char*)(AL + tl * 128 + k); const int tq = aq + 8;
;             const unsigned lo = (((unsigned)tq & 15u) ^ 8u) * 0x11111111u, hi = ((unsigned)(tq >> 4) & 15u) * 0x11111111u;
;             typedef unsigned u2v __attribute__((ext_vector_type(2)));
;             u2v l2; l2.x = lo; l2.y = lo; u2v h2; h2.x = hi; h2.y = hi;
;             *(LAS u2v*)(ATL + 8 * idx) = l2; *(LAS u2v*)(ATL + 1024 + 8 * idx) = h2;
;         }
;     ...
;         for (int st = 0; st < 16; ++st) {
;             const int p = st >> 2, q = st & 3;
;             if (st < 14) VDMA(st + 2, (st + 2) % 3);
;             if (st < 14) asm volatile("s_waitcnt vmcnt(8)" ::: "memory");
;             else if (st == 14) asm volatile("s_waitcnt vmcnt(4)" ::: "memory");
;             else asm volatile("s_waitcnt vmcnt(0)" ::: "memory");
;             if (q == 0) {
; #pragma unroll
;                 for (int r = 0; r < 4; ++r) { accH[r] = 0; accL[r] = 0; } }
; #pragma unroll
;             for (int tp = 0; tp < 2; ++tp) {
;                 const v2i ao = TR4(ATL + (2 * q + tp) * 128 + 8 * s16), ah = TR4(ATL + 1024 + (2 * q + tp) * 128 + 8 * s16);
; #pragma unroll
;                 for (int r = 0; r < 4; ++r) {
;                     const v2i d = TR4(ldsb + BUF[st % 3] + 2048 * tp + roff[r]);
;                     accH[r] = __builtin_amdgcn_sdot8(d.x, ah.x, accH[r], false); accH[r] = __builtin_amdgcn_sdot8(d.y, ah.y, accH[r], false);
;                     accL[r] = __builtin_amdgcn_sdot8(d.x, ao.x, accL[r], false); accL[r] = __builtin_amdgcn_sdot8(d.y, ao.y, accL[r], false);
;                 }
;             }
;             asm volatile("s_waitcnt lgkmcnt(0)" ::: "memory");
;             if (q == 3) {
; #pragma unroll
;                 for (int r = 0; r < 4; ++r) STASH[256 * p + 16 * (grp + 4 * r) + pc] = f2bf(asc * (float)(2 * ((accH[r] << 4) + accL[r]) + sa));
;             }
;         }
	v_add_u32_e32 v54, s79, v59
	v_add_u32_e32 v55, s79, v60
	v_add_u32_e32 v56, s79, v61
	v_add_u32_e32 v57, s79, v62
	ds_read_b64_tr_b4 v[50:51], v160 offset:640
	ds_read_b64_tr_b4 v[52:53], v160 offset:1664
	ds_read_b64_tr_b4 v[130:131], v54
	ds_read_b64_tr_b4 v[132:133], v55
	ds_read_b64_tr_b4 v[134:135], v56
	ds_read_b64_tr_b4 v[136:137], v57
	s_waitcnt lgkmcnt(6)
	v_dot8c_i32_i4_e32 v38, v122, v48
	v_dot8c_i32_i4_e32 v39, v122, v46
	v_dot8c_i32_i4_e32 v40, v124, v48
	v_dot8c_i32_i4_e32 v41, v124, v46
	v_dot8c_i32_i4_e32 v42, v126, v48
	v_dot8c_i32_i4_e32 v43, v126, v46
	v_dot8c_i32_i4_e32 v44, v128, v48
	v_dot8c_i32_i4_e32 v45, v128, v46
	v_dot8c_i32_i4_e32 v38, v123, v49
	v_dot8c_i32_i4_e32 v39, v123, v47
	v_dot8c_i32_i4_e32 v40, v125, v49
	v_dot8c_i32_i4_e32 v41, v125, v47
	v_dot8c_i32_i4_e32 v42, v127, v49
	v_dot8c_i32_i4_e32 v43, v127, v47
	v_dot8c_i32_i4_e32 v44, v129, v49
	v_dot8c_i32_i4_e32 v45, v129, v47
	s_waitcnt lgkmcnt(15)
	v_add_u32_e32 v143, 8, v139
	v_and_b32_e32 v142, 15, v143
	v_xor_b32_e32 v142, 8, v142
	v_bfe_u32 v144, v143, 4, 4
	v_mul_lo_u32 v142, v142, s92
	v_mul_lo_u32 v144, v144, s92
	v_mov_b32_e32 v143, v142
	v_mov_b32_e32 v145, v144
	ds_write2st64_b64 v159, v[142:143], v[144:145] offset1:2
	v_and_b32_e32 v78, 0xffff, v28
	v_lshrrev_b32_e32 v79, 16, v28
	v_lshl_add_u32 v78, v78, 7, v150
	v_lshl_add_u32 v79, v79, 7, v151
	s_mov_b32 m0, s78
	s_add_i32 s43, s78, 0x400
	global_load_lds_dwordx4 v78, s[50:51]
	s_mov_b32 m0, s43
	s_nop 0
	global_load_lds_dwordx4 v79, s[50:51]
	s_waitcnt vmcnt(8)
	v_add_u32_e32 v54, s98, v59
	v_add_u32_e32 v55, s98, v60
	v_add_u32_e32 v56, s98, v61
	v_add_u32_e32 v57, s98, v62
	ds_read_b64_tr_b4 v[46:47], v160 offset:768
	ds_read_b64_tr_b4 v[48:49], v160 offset:1792
	ds_read_b64_tr_b4 v[122:123], v54
	ds_read_b64_tr_b4 v[124:125], v55
	ds_read_b64_tr_b4 v[126:127], v56
	ds_read_b64_tr_b4 v[128:129], v57
	s_waitcnt lgkmcnt(7)
	v_dot8c_i32_i4_e32 v38, v130, v52
	v_dot8c_i32_i4_e32 v39, v130, v50
	v_dot8c_i32_i4_e32 v40, v132, v52
	v_dot8c_i32_i4_e32 v41, v132, v50
	v_dot8c_i32_i4_e32 v42, v134, v52
	v_dot8c_i32_i4_e32 v43, v134, v50
	v_dot8c_i32_i4_e32 v44, v136, v52
	v_dot8c_i32_i4_e32 v45, v136, v50
	v_dot8c_i32_i4_e32 v38, v131, v53
	v_dot8c_i32_i4_e32 v39, v131, v51
	v_dot8c_i32_i4_e32 v40, v133, v53
	v_dot8c_i32_i4_e32 v41, v133, v51
	v_dot8c_i32_i4_e32 v42, v135, v53
	v_dot8c_i32_i4_e32 v43, v135, v51
	v_dot8c_i32_i4_e32 v44, v137, v53
	v_dot8c_i32_i4_e32 v45, v137, v51
	v_and_b32_e32 v78, 0xffff, v29
	v_lshrrev_b32_e32 v79, 16, v29
	v_lshl_add_u32 v78, v78, 7, v150
	v_lshl_add_u32 v79, v79, 7, v151
	s_mov_b32 m0, s79
	s_add_i32 s43, s79, 0x400
	global_load_lds_dwordx4 v78, s[50:51]
	s_mov_b32 m0, s43
	s_nop 0
	global_load_lds_dwordx4 v79, s[50:51]
	s_waitcnt vmcnt(8)
	v_add_u32_e32 v54, s99, v59
	v_add_u32_e32 v55, s99, v60
	v_add_u32_e32 v56, s99, v61
	v_add_u32_e32 v57, s99, v62
	ds_read_b64_tr_b4 v[50:51], v160 offset:896
	ds_read_b64_tr_b4 v[52:53], v160 offset:1920
	ds_read_b64_tr_b4 v[130:131], v54
	ds_read_b64_tr_b4 v[132:133], v55
	ds_read_b64_tr_b4 v[134:135], v56
	ds_read_b64_tr_b4 v[136:137], v57
	s_waitcnt lgkmcnt(6)
	v_dot8c_i32_i4_e32 v38, v122, v48
	v_dot8c_i32_i4_e32 v39, v122, v46
	v_dot8c_i32_i4_e32 v40, v124, v48
	v_dot8c_i32_i4_e32 v41, v124, v46
	v_dot8c_i32_i4_e32 v42, v126, v48
	v_dot8c_i32_i4_e32 v43, v126, v46
	v_dot8c_i32_i4_e32 v44, v128, v48
	v_dot8c_i32_i4_e32 v45, v128, v46
	v_dot8c_i32_i4_e32 v38, v123, v49
	v_dot8c_i32_i4_e32 v39, v123, v47
	v_dot8c_i32_i4_e32 v40, v125, v49
	v_dot8c_i32_i4_e32 v41, v125, v47
	v_dot8c_i32_i4_e32 v42, v127, v49
	v_dot8c_i32_i4_e32 v43, v127, v47
	v_dot8c_i32_i4_e32 v44, v129, v49
	v_dot8c_i32_i4_e32 v45, v129, v47
	v_and_b32_e32 v78, 0xffff, v30
	v_lshrrev_b32_e32 v79, 16, v30
	v_lshl_add_u32 v78, v78, 7, v150
	v_lshl_add_u32 v79, v79, 7, v151
	s_mov_b32 m0, s98
	s_add_i32 s43, s98, 0x400
	global_load_lds_dwordx4 v78, s[50:51]
	s_mov_b32 m0, s43
	s_nop 0
	global_load_lds_dwordx4 v79, s[50:51]
	s_waitcnt vmcnt(8)
	v_add_u32_e32 v54, s76, v59
	v_add_u32_e32 v55, s76, v60
	v_add_u32_e32 v56, s76, v61
	v_add_u32_e32 v57, s76, v62
	ds_read_b64_tr_b4 v[46:47], v160
	ds_read_b64_tr_b4 v[48:49], v160 offset:1024
	ds_read_b64_tr_b4 v[122:123], v54
	ds_read_b64_tr_b4 v[124:125], v55
	ds_read_b64_tr_b4 v[126:127], v56
	ds_read_b64_tr_b4 v[128:129], v57
	s_waitcnt lgkmcnt(6)
	v_dot8c_i32_i4_e32 v38, v130, v52
	v_dot8c_i32_i4_e32 v39, v130, v50
	v_dot8c_i32_i4_e32 v40, v132, v52
	v_dot8c_i32_i4_e32 v41, v132, v50
	v_dot8c_i32_i4_e32 v42, v134, v52
	v_dot8c_i32_i4_e32 v43, v134, v50
	v_dot8c_i32_i4_e32 v44, v136, v52
	v_dot8c_i32_i4_e32 v45, v136, v50
	v_dot8c_i32_i4_e32 v38, v131, v53
	v_dot8c_i32_i4_e32 v39, v131, v51
	v_dot8c_i32_i4_e32 v40, v133, v53
	v_dot8c_i32_i4_e32 v41, v133, v51
	v_dot8c_i32_i4_e32 v42, v135, v53
	v_dot8c_i32_i4_e32 v43, v135, v51
	v_dot8c_i32_i4_e32 v44, v137, v53
	v_dot8c_i32_i4_e32 v45, v137, v51
	s_nop 3
	s_waitcnt lgkmcnt(15)
; __device__ __forceinline__ void peer_v_tokens(int j, const LAS unsigned short* EL, const LAS unsigned char* AL  , const LAS float* ASC  , const LAS int* SAL  , ...
;     ...
;         for (int st = 0; st < 16; ++st) {
;             const int p = st >> 2, q = st & 3;
;             if (st < 14) VDMA(st + 2, (st + 2) % 3);
;             if (st < 14) asm volatile("s_waitcnt vmcnt(8)" ::: "memory");
;             else if (st == 14) asm volatile("s_waitcnt vmcnt(4)" ::: "memory");
;             else asm volatile("s_waitcnt vmcnt(0)" ::: "memory");
;             if (q == 0) {
; #pragma unroll
;                 for (int r = 0; r < 4; ++r) { accH[r] = 0; accL[r] = 0; } }
; #pragma unroll
;             for (int tp = 0; tp < 2; ++tp) {
;                 const v2i ao = TR4(ATL + (2 * q + tp) * 128 + 8 * s16), ah = TR4(ATL + 1024 + (2 * q + tp) * 128 + 8 * s16);
; #pragma unroll
;                 for (int r = 0; r < 4; ++r) {
;                     const v2i d = TR4(ldsb + BUF[st % 3] + 2048 * tp + roff[r]);
;                     accH[r] = __builtin_amdgcn_sdot8(d.x, ah.x, accH[r], false); accH[r] = __builtin_amdgcn_sdot8(d.y, ah.y, accH[r], false);
;                     accL[r] = __builtin_amdgcn_sdot8(d.x, ao.x, accL[r], false); accL[r] = __builtin_amdgcn_sdot8(d.y, ao.y, accL[r], false);
;                 }
;             }
;             asm volatile("s_waitcnt lgkmcnt(0)" ::: "memory");
;             if (q == 3) {
; #pragma unroll
;                 for (int r = 0; r < 4; ++r) STASH[256 * p + 16 * (grp + 4 * r) + pc] = f2bf(asc * (float)(2 * ((accH[r] << 4) + accL[r]) + sa));
;     ...
;         {
;             float4 v[4]; float ss = 0.f;
; #pragma unroll
;             for (int jq = 0; jq < 4; ++jq) { typedef unsigned u2v __attribute__((ext_vector_type(2))); const u2v pw = *(const LAS u2v*)(STASH + 4 * lane + 256 * jq); const uint2 hw = hv[jq];
;                 v[jq] = make_float4(__uint_as_float(hw.x << 16) + __uint_as_float(pw.x << 16), __uint_as_float(hw.x & 0xffff0000u) + __uint_as_float(pw.x & 0xffff0000u),
;                                     __uint_as_float(hw.y << 16) + __uint_as_float(pw.y << 16), __uint_as_float(hw.y & 0xffff0000u) + __uint_as_float(pw.y & 0xffff0000u));
;                 ss += v[jq].x * v[jq].x + v[jq].y * v[jq].y + v[jq].z * v[jq].z + v[jq].w * v[jq].w; }
;             ss = wave_sum(ss);
;             const float r3 = rsqrtf(ss * (1.f / D) + EPS);
	v_lshlrev_b32_e32 v38, 5, v38
	v_lshlrev_b32_e32 v39, 1, v39
	v_add3_u32 v38, v39, v229, v38
	v_cvt_f32_i32_e32 v38, v38
	v_mul_f32_e32 v38, v228, v38
	v_lshlrev_b32_e32 v40, 5, v40
	v_lshlrev_b32_e32 v41, 1, v41
	v_add3_u32 v40, v41, v229, v40
	v_cvt_f32_i32_e32 v40, v40
	v_mul_f32_e32 v40, v228, v40
	v_lshlrev_b32_e32 v42, 5, v42
	v_lshlrev_b32_e32 v43, 1, v43
	v_add3_u32 v42, v43, v229, v42
	v_cvt_f32_i32_e32 v42, v42
	v_mul_f32_e32 v42, v228, v42
	v_lshlrev_b32_e32 v44, 5, v44
	v_lshlrev_b32_e32 v45, 1, v45
	v_add3_u32 v44, v45, v229, v44
	v_cvt_f32_i32_e32 v44, v44
	v_mul_f32_e32 v44, v228, v44
	v_cvt_pk_bf16_f32 v178, v38, v40
	v_cvt_pk_bf16_f32 v179, v42, v44
	v_add_u32_e32 v147, 8, v140
	v_and_b32_e32 v146, 15, v147
	v_xor_b32_e32 v146, 8, v146
	v_bfe_u32 v148, v147, 4, 4
	v_mul_lo_u32 v146, v146, s92
	v_mul_lo_u32 v148, v148, s92
	v_mov_b32_e32 v147, v146
	v_mov_b32_e32 v149, v148
	ds_write2st64_b64 v77, v[146:147], v[148:149] offset1:2
	v_add_u32_e32 v138, 0x800, v74
	ds_read_u8 v139, v138
	v_add_u32_e32 v141, 0x800, v73
	ds_read_u8 v140, v141
	s_add_i32 s43, s67, 96
	v_mov_b32_e32 v138, s43
	ds_read2st64_b32 v[228:229], v138 offset1:1
	ds_read_b128 v[18:21], v227 offset:4096
	ds_read_b128 v[22:25], v227 offset:4112
	v_add_u32_e32 v152, 0x200000, v63
	v_add_u32_e32 v153, 0x200000, v64
	v_mov_b32_e32 v38, 0
	v_mov_b32_e32 v39, 0
	v_mov_b32_e32 v40, 0
	v_mov_b32_e32 v41, 0
	v_mov_b32_e32 v42, 0
	v_mov_b32_e32 v43, 0
	v_mov_b32_e32 v44, 0
	v_mov_b32_e32 v45, 0
	v_and_b32_e32 v78, 0xffff, v31
	v_lshrrev_b32_e32 v79, 16, v31
	v_lshl_add_u32 v78, v78, 7, v150
	v_lshl_add_u32 v79, v79, 7, v151
	s_mov_b32 m0, s99
	s_add_i32 s43, s99, 0x400
	global_load_lds_dwordx4 v78, s[50:51]
	s_mov_b32 m0, s43
	s_nop 0
	global_load_lds_dwordx4 v79, s[50:51]
	s_waitcnt vmcnt(8)
	v_add_u32_e32 v54, s77, v59
	v_add_u32_e32 v55, s77, v60
	v_add_u32_e32 v56, s77, v61
	v_add_u32_e32 v57, s77, v62
	ds_read_b64_tr_b4 v[50:51], v160 offset:128
	ds_read_b64_tr_b4 v[52:53], v160 offset:1152
	ds_read_b64_tr_b4 v[130:131], v54
	ds_read_b64_tr_b4 v[132:133], v55
	ds_read_b64_tr_b4 v[134:135], v56
	ds_read_b64_tr_b4 v[136:137], v57
	s_waitcnt lgkmcnt(12)
	s_waitcnt vmcnt(34) lgkmcnt(15)
	v_lshlrev_b32_e32 v210, 16, v194
	v_and_b32_e32 v211, 0xffff0000, v194
	v_lshlrev_b32_e32 v142, 16, v202
	v_and_b32_e32 v143, 0xffff0000, v202
	v_add_f32_e32 v210, v210, v142
	v_add_f32_e32 v211, v211, v143
	v_lshlrev_b32_e32 v212, 16, v195
	v_and_b32_e32 v213, 0xffff0000, v195
	v_lshlrev_b32_e32 v142, 16, v203
	v_and_b32_e32 v143, 0xffff0000, v203
	v_add_f32_e32 v212, v212, v142
	v_add_f32_e32 v213, v213, v143
	v_lshlrev_b32_e32 v214, 16, v196
	v_and_b32_e32 v215, 0xffff0000, v196
	v_lshlrev_b32_e32 v142, 16, v204
	v_and_b32_e32 v143, 0xffff0000, v204
	v_add_f32_e32 v214, v214, v142
	v_add_f32_e32 v215, v215, v143
	v_lshlrev_b32_e32 v216, 16, v197
	v_and_b32_e32 v217, 0xffff0000, v197
	v_lshlrev_b32_e32 v142, 16, v205
	v_and_b32_e32 v143, 0xffff0000, v205
	v_add_f32_e32 v216, v216, v142
	v_add_f32_e32 v217, v217, v143
	v_lshlrev_b32_e32 v218, 16, v198
	v_and_b32_e32 v219, 0xffff0000, v198
	v_lshlrev_b32_e32 v142, 16, v206
	v_and_b32_e32 v143, 0xffff0000, v206
	v_add_f32_e32 v218, v218, v142
	v_add_f32_e32 v219, v219, v143
	v_lshlrev_b32_e32 v220, 16, v199
	v_and_b32_e32 v221, 0xffff0000, v199
	v_lshlrev_b32_e32 v142, 16, v207
	v_and_b32_e32 v143, 0xffff0000, v207
	v_add_f32_e32 v220, v220, v142
	v_add_f32_e32 v221, v221, v143
	v_lshlrev_b32_e32 v222, 16, v200
	v_and_b32_e32 v223, 0xffff0000, v200
	v_lshlrev_b32_e32 v142, 16, v208
	v_and_b32_e32 v143, 0xffff0000, v208
	v_add_f32_e32 v222, v222, v142
	v_add_f32_e32 v223, v223, v143
	v_lshlrev_b32_e32 v224, 16, v201
	v_and_b32_e32 v225, 0xffff0000, v201
	v_lshlrev_b32_e32 v142, 16, v209
	v_and_b32_e32 v143, 0xffff0000, v209
	v_add_f32_e32 v224, v224, v142
	v_add_f32_e32 v225, v225, v143
	v_mov_b32_e32 v144, 0
	v_mul_f32_e32 v145, v210, v210
	v_fmac_f32_e32 v145, v211, v211
	v_fmac_f32_e32 v145, v212, v212
	v_fmac_f32_e32 v145, v213, v213
	v_add_f32_e32 v144, v144, v145
	v_mul_f32_e32 v145, v214, v214
	v_fmac_f32_e32 v145, v215, v215
	v_fmac_f32_e32 v145, v216, v216
	v_fmac_f32_e32 v145, v217, v217
	v_add_f32_e32 v144, v144, v145
	v_mul_f32_e32 v145, v218, v218
	v_fmac_f32_e32 v145, v219, v219
	v_fmac_f32_e32 v145, v220, v220
	v_fmac_f32_e32 v145, v221, v221
	v_add_f32_e32 v144, v144, v145
	v_mul_f32_e32 v145, v222, v222
	v_fmac_f32_e32 v145, v223, v223
	v_fmac_f32_e32 v145, v224, v224
	v_fmac_f32_e32 v145, v225, v225
	v_add_f32_e32 v144, v144, v145
	s_nop 1
	v_add_f32_dpp v144, v144, v144 quad_perm:[1,0,3,2] row_mask:0xf bank_mask:0xf bound_ctrl:1
	s_nop 1
	v_add_f32_dpp v144, v144, v144 quad_perm:[2,3,0,1] row_mask:0xf bank_mask:0xf bound_ctrl:1
	s_nop 1
	v_add_f32_dpp v144, v144, v144 row_half_mirror row_mask:0xf bank_mask:0xf bound_ctrl:1
	s_nop 1
	v_add_f32_dpp v144, v144, v144 row_mirror row_mask:0xf bank_mask:0xf bound_ctrl:1
	s_nop 1
	v_readlane_b32 s10, v144, 0
	v_readlane_b32 s11, v144, 16
	v_readlane_b32 s14, v144, 32
	v_readlane_b32 s15, v144, 48
	s_nop 3
	v_mov_b32_e32 v144, s11
	v_mov_b32_e32 v145, s15
	v_add_f32_e32 v144, s10, v144
	v_add_f32_e32 v145, s14, v145
	v_add_f32_e32 v144, v144, v145
	v_fmamk_f32 v144, v144, 0x3a800000, v111
	v_rsq_f32_e32 v144, v144
	s_nop 0
	v_mul_f32_e32 v210, v210, v144
	v_mul_f32_e32 v211, v211, v144
	v_mul_f32_e32 v212, v212, v144
	v_mul_f32_e32 v213, v213, v144
	v_mul_f32_e32 v214, v214, v144
	v_mul_f32_e32 v215, v215, v144
	v_mul_f32_e32 v216, v216, v144
	v_mul_f32_e32 v217, v217, v144
	v_mul_f32_e32 v218, v218, v144
	v_mul_f32_e32 v219, v219, v144
	v_mul_f32_e32 v220, v220, v144
	v_mul_f32_e32 v221, v221, v144
	v_mul_f32_e32 v222, v222, v144
	v_mul_f32_e32 v223, v223, v144
	v_mul_f32_e32 v224, v224, v144
	v_mul_f32_e32 v225, v225, v144
	v_dot8c_i32_i4_e32 v38, v122, v48
	v_dot8c_i32_i4_e32 v39, v122, v46
	v_dot8c_i32_i4_e32 v40, v124, v48
	v_dot8c_i32_i4_e32 v41, v124, v46
	v_dot8c_i32_i4_e32 v42, v126, v48
	v_dot8c_i32_i4_e32 v43, v126, v46
	v_dot8c_i32_i4_e32 v44, v128, v48
	v_dot8c_i32_i4_e32 v45, v128, v46
	v_dot8c_i32_i4_e32 v38, v123, v49
	v_dot8c_i32_i4_e32 v39, v123, v47
	v_dot8c_i32_i4_e32 v40, v125, v49
	v_dot8c_i32_i4_e32 v41, v125, v47
	v_dot8c_i32_i4_e32 v42, v127, v49
	v_dot8c_i32_i4_e32 v43, v127, v47
	v_dot8c_i32_i4_e32 v44, v129, v49
	v_dot8c_i32_i4_e32 v45, v129, v47
	v_and_b32_e32 v78, 0xffff, v32
	v_lshrrev_b32_e32 v79, 16, v32
	v_lshl_add_u32 v78, v78, 7, v150
	v_lshl_add_u32 v79, v79, 7, v151
	s_mov_b32 m0, s76
	s_add_i32 s43, s76, 0x400
	global_load_lds_dwordx4 v78, s[50:51]
	s_mov_b32 m0, s43
	s_nop 0
	global_load_lds_dwordx4 v79, s[50:51]
	s_waitcnt vmcnt(8)
; __device__ __forceinline__ bf16 f2bf(float f) { return (bf16)f2bfu(f); }
; #define TR4(p_) __builtin_amdgcn_ds_read_tr4_b64_v2i32((LAS v2i*)(p_))
; #define VDMA(st_, k_) do { _Pragma("unroll") for (int i_ = 0; i_ < 4; ++i_) { \
;         const unsigned off_ = (unsigned)((st_) >> 2) * (16384u * 128u) + (PE_ID(E, 4 * ((st_) & 3) + i_) << 7) + ((i_ & 1) ? cx1 : cx0); \
;         __builtin_amdgcn_global_load_lds((const unsigned*)(V4 + off_), (LAS unsigned*)(ldsb + BUF[k_] + 1024 * i_), 16, 0, 0); } } while (0)
; __device__ __forceinline__ void peer_v_tokens(int j, const LAS unsigned short* EL, const LAS unsigned char* AL  , const LAS float* ASC  , const LAS int* SAL  , ...
;     ...
;         for (int st = 0; st < 16; ++st) {
;             const int p = st >> 2, q = st & 3;
;             if (st < 14) VDMA(st + 2, (st + 2) % 3);
;             if (st < 14) asm volatile("s_waitcnt vmcnt(8)" ::: "memory");
;             else if (st == 14) asm volatile("s_waitcnt vmcnt(4)" ::: "memory");
;             else asm volatile("s_waitcnt vmcnt(0)" ::: "memory");
;             if (q == 0) {
; #pragma unroll
;                 for (int r = 0; r < 4; ++r) { accH[r] = 0; accL[r] = 0; } }
; #pragma unroll
;             for (int tp = 0; tp < 2; ++tp) {
;                 const v2i ao = TR4(ATL + (2 * q + tp) * 128 + 8 * s16), ah = TR4(ATL + 1024 + (2 * q + tp) * 128 + 8 * s16);
; #pragma unroll
;                 for (int r = 0; r < 4; ++r) {
;                     const v2i d = TR4(ldsb + BUF[st % 3] + 2048 * tp + roff[r]);
;                     accH[r] = __builtin_amdgcn_sdot8(d.x, ah.x, accH[r], false); accH[r] = __builtin_amdgcn_sdot8(d.y, ah.y, accH[r], false);
;                     accL[r] = __builtin_amdgcn_sdot8(d.x, ao.x, accL[r], false); accL[r] = __builtin_amdgcn_sdot8(d.y, ao.y, accL[r], false);
;                 }
;             }
;             asm volatile("s_waitcnt lgkmcnt(0)" ::: "memory");
;             if (q == 3) {
; #pragma unroll
;                 for (int r = 0; r < 4; ++r) STASH[256 * p + 16 * (grp + 4 * r) + pc] = f2bf(asc * (float)(2 * ((accH[r] << 4) + accL[r]) + sa));
;             }
;         }
	v_add_u32_e32 v54, s78, v59
	v_add_u32_e32 v55, s78, v60
	v_add_u32_e32 v56, s78, v61
	v_add_u32_e32 v57, s78, v62
	ds_read_b64_tr_b4 v[46:47], v160 offset:256
	ds_read_b64_tr_b4 v[48:49], v160 offset:1280
	ds_read_b64_tr_b4 v[122:123], v54
	ds_read_b64_tr_b4 v[124:125], v55
	ds_read_b64_tr_b4 v[126:127], v56
	ds_read_b64_tr_b4 v[128:129], v57
	s_waitcnt lgkmcnt(6)
	v_dot8c_i32_i4_e32 v38, v130, v52
	v_dot8c_i32_i4_e32 v39, v130, v50
	v_dot8c_i32_i4_e32 v40, v132, v52
	v_dot8c_i32_i4_e32 v41, v132, v50
	v_dot8c_i32_i4_e32 v42, v134, v52
	v_dot8c_i32_i4_e32 v43, v134, v50
	v_dot8c_i32_i4_e32 v44, v136, v52
	v_dot8c_i32_i4_e32 v45, v136, v50
	v_dot8c_i32_i4_e32 v38, v131, v53
	v_dot8c_i32_i4_e32 v39, v131, v51
	v_dot8c_i32_i4_e32 v40, v133, v53
	v_dot8c_i32_i4_e32 v41, v133, v51
	v_dot8c_i32_i4_e32 v42, v135, v53
	v_dot8c_i32_i4_e32 v43, v135, v51
	v_dot8c_i32_i4_e32 v44, v137, v53
	v_dot8c_i32_i4_e32 v45, v137, v51
	v_and_b32_e32 v78, 0xffff, v33
	v_lshrrev_b32_e32 v79, 16, v33
	v_lshl_add_u32 v78, v78, 7, v150
	v_lshl_add_u32 v79, v79, 7, v151
	s_mov_b32 m0, s77
	s_add_i32 s43, s77, 0x400
	global_load_lds_dwordx4 v78, s[50:51]
	s_mov_b32 m0, s43
	s_nop 0
	global_load_lds_dwordx4 v79, s[50:51]
	s_waitcnt vmcnt(8)
	v_add_u32_e32 v54, s79, v59
	v_add_u32_e32 v55, s79, v60
	v_add_u32_e32 v56, s79, v61
	v_add_u32_e32 v57, s79, v62
	ds_read_b64_tr_b4 v[50:51], v160 offset:384
	ds_read_b64_tr_b4 v[52:53], v160 offset:1408
	ds_read_b64_tr_b4 v[130:131], v54
	ds_read_b64_tr_b4 v[132:133], v55
	ds_read_b64_tr_b4 v[134:135], v56
	ds_read_b64_tr_b4 v[136:137], v57
	s_waitcnt lgkmcnt(6)
	v_dot8c_i32_i4_e32 v38, v122, v48
	v_dot8c_i32_i4_e32 v39, v122, v46
	v_dot8c_i32_i4_e32 v40, v124, v48
	v_dot8c_i32_i4_e32 v41, v124, v46
	v_dot8c_i32_i4_e32 v42, v126, v48
	v_dot8c_i32_i4_e32 v43, v126, v46
	v_dot8c_i32_i4_e32 v44, v128, v48
	v_dot8c_i32_i4_e32 v45, v128, v46
	v_dot8c_i32_i4_e32 v38, v123, v49
	v_dot8c_i32_i4_e32 v39, v123, v47
	v_dot8c_i32_i4_e32 v40, v125, v49
	v_dot8c_i32_i4_e32 v41, v125, v47
	v_dot8c_i32_i4_e32 v42, v127, v49
	v_dot8c_i32_i4_e32 v43, v127, v47
	v_dot8c_i32_i4_e32 v44, v129, v49
	v_dot8c_i32_i4_e32 v45, v129, v47
	s_waitcnt lgkmcnt(15)
	v_and_b32_e32 v78, 0xffff, v18
	v_lshrrev_b32_e32 v79, 16, v18
	v_lshl_add_u32 v78, v78, 7, v152
	v_lshl_add_u32 v79, v79, 7, v153
	s_mov_b32 m0, s78
	s_add_i32 s43, s78, 0x400
	global_load_lds_dwordx4 v78, s[50:51]
	s_mov_b32 m0, s43
	s_nop 0
	global_load_lds_dwordx4 v79, s[50:51]
	s_waitcnt vmcnt(8)
	v_add_u32_e32 v54, s98, v59
	v_add_u32_e32 v55, s98, v60
	v_add_u32_e32 v56, s98, v61
	v_add_u32_e32 v57, s98, v62
	ds_read_b64_tr_b4 v[46:47], v160 offset:512
	ds_read_b64_tr_b4 v[48:49], v160 offset:1536
	ds_read_b64_tr_b4 v[122:123], v54
	ds_read_b64_tr_b4 v[124:125], v55
	ds_read_b64_tr_b4 v[126:127], v56
	ds_read_b64_tr_b4 v[128:129], v57
	s_waitcnt lgkmcnt(6)
	v_dot8c_i32_i4_e32 v38, v130, v52
	v_dot8c_i32_i4_e32 v39, v130, v50
	v_dot8c_i32_i4_e32 v40, v132, v52
	v_dot8c_i32_i4_e32 v41, v132, v50
	v_dot8c_i32_i4_e32 v42, v134, v52
	v_dot8c_i32_i4_e32 v43, v134, v50
	v_dot8c_i32_i4_e32 v44, v136, v52
	v_dot8c_i32_i4_e32 v45, v136, v50
	v_dot8c_i32_i4_e32 v38, v131, v53
	v_dot8c_i32_i4_e32 v39, v131, v51
	v_dot8c_i32_i4_e32 v40, v133, v53
	v_dot8c_i32_i4_e32 v41, v133, v51
	v_dot8c_i32_i4_e32 v42, v135, v53
	v_dot8c_i32_i4_e32 v43, v135, v51
	v_dot8c_i32_i4_e32 v44, v137, v53
	v_dot8c_i32_i4_e32 v45, v137, v51
	v_and_b32_e32 v78, 0xffff, v19
	v_lshrrev_b32_e32 v79, 16, v19
	v_lshl_add_u32 v78, v78, 7, v152
	v_lshl_add_u32 v79, v79, 7, v153
	s_mov_b32 m0, s79
	s_add_i32 s43, s79, 0x400
	global_load_lds_dwordx4 v78, s[50:51]
	s_mov_b32 m0, s43
	s_nop 0
	global_load_lds_dwordx4 v79, s[50:51]
	s_waitcnt vmcnt(8)
	v_add_u32_e32 v54, s99, v59
	v_add_u32_e32 v55, s99, v60
	v_add_u32_e32 v56, s99, v61
	v_add_u32_e32 v57, s99, v62
	ds_read_b64_tr_b4 v[50:51], v160 offset:640
	ds_read_b64_tr_b4 v[52:53], v160 offset:1664
	ds_read_b64_tr_b4 v[130:131], v54
	ds_read_b64_tr_b4 v[132:133], v55
	ds_read_b64_tr_b4 v[134:135], v56
	ds_read_b64_tr_b4 v[136:137], v57
	s_waitcnt lgkmcnt(6)
	v_dot8c_i32_i4_e32 v38, v122, v48
	v_dot8c_i32_i4_e32 v39, v122, v46
	v_dot8c_i32_i4_e32 v40, v124, v48
	v_dot8c_i32_i4_e32 v41, v124, v46
	v_dot8c_i32_i4_e32 v42, v126, v48
	v_dot8c_i32_i4_e32 v43, v126, v46
	v_dot8c_i32_i4_e32 v44, v128, v48
	v_dot8c_i32_i4_e32 v45, v128, v46
	v_dot8c_i32_i4_e32 v38, v123, v49
	v_dot8c_i32_i4_e32 v39, v123, v47
	v_dot8c_i32_i4_e32 v40, v125, v49
	v_dot8c_i32_i4_e32 v41, v125, v47
	v_dot8c_i32_i4_e32 v42, v127, v49
	v_dot8c_i32_i4_e32 v43, v127, v47
	v_dot8c_i32_i4_e32 v44, v129, v49
	v_dot8c_i32_i4_e32 v45, v129, v47
	s_waitcnt lgkmcnt(15)
	v_add_u32_e32 v143, 8, v139
	v_and_b32_e32 v142, 15, v143
	v_xor_b32_e32 v142, 8, v142
	v_bfe_u32 v144, v143, 4, 4
	v_mul_lo_u32 v142, v142, s92
	v_mul_lo_u32 v144, v144, s92
	v_mov_b32_e32 v143, v142
	v_mov_b32_e32 v145, v144
	ds_write2st64_b64 v159, v[142:143], v[144:145] offset1:2
	v_and_b32_e32 v78, 0xffff, v20
	v_lshrrev_b32_e32 v79, 16, v20
	v_lshl_add_u32 v78, v78, 7, v152
	v_lshl_add_u32 v79, v79, 7, v153
	s_mov_b32 m0, s98
	s_add_i32 s43, s98, 0x400
	global_load_lds_dwordx4 v78, s[50:51]
	s_mov_b32 m0, s43
	s_nop 0
	global_load_lds_dwordx4 v79, s[50:51]
	s_waitcnt vmcnt(8)
	v_add_u32_e32 v54, s76, v59
	v_add_u32_e32 v55, s76, v60
	v_add_u32_e32 v56, s76, v61
	v_add_u32_e32 v57, s76, v62
	ds_read_b64_tr_b4 v[46:47], v160 offset:768
	ds_read_b64_tr_b4 v[48:49], v160 offset:1792
	ds_read_b64_tr_b4 v[122:123], v54
	ds_read_b64_tr_b4 v[124:125], v55
	ds_read_b64_tr_b4 v[126:127], v56
	ds_read_b64_tr_b4 v[128:129], v57
	s_waitcnt lgkmcnt(7)
; __device__ __forceinline__ void peer_v_tokens(int j, const LAS unsigned short* EL, const LAS unsigned char* AL  , const LAS float* ASC  , const LAS int* SAL  , ...
;     ...
;         uint2 hv[4]; float4 gv[4];
;         { unsigned ho = (unsigned)t * (D / 4) + (unsigned)lane; asm volatile("" : "+v"(ho)); const uint2* hp = (const uint2*)HB + ho; const float4* gp = (const float4*)fng + lane;
; #pragma unroll
;           for (int jq = 0; jq < 4; ++jq) { hv[jq] = hp[64 * jq]; gv[jq] = gp[64 * jq]; } }
;     ...
;         for (int st = 0; st < 16; ++st) {
;             const int p = st >> 2, q = st & 3;
;             if (st < 14) VDMA(st + 2, (st + 2) % 3);
;             if (st < 14) asm volatile("s_waitcnt vmcnt(8)" ::: "memory");
;             else if (st == 14) asm volatile("s_waitcnt vmcnt(4)" ::: "memory");
;             else asm volatile("s_waitcnt vmcnt(0)" ::: "memory");
;             if (q == 0) {
; #pragma unroll
;                 for (int r = 0; r < 4; ++r) { accH[r] = 0; accL[r] = 0; } }
; #pragma unroll
;             for (int tp = 0; tp < 2; ++tp) {
;                 const v2i ao = TR4(ATL + (2 * q + tp) * 128 + 8 * s16), ah = TR4(ATL + 1024 + (2 * q + tp) * 128 + 8 * s16);
; #pragma unroll
;                 for (int r = 0; r < 4; ++r) {
;                     const v2i d = TR4(ldsb + BUF[st % 3] + 2048 * tp + roff[r]);
;                     accH[r] = __builtin_amdgcn_sdot8(d.x, ah.x, accH[r], false); accH[r] = __builtin_amdgcn_sdot8(d.y, ah.y, accH[r], false);
;                     accL[r] = __builtin_amdgcn_sdot8(d.x, ao.x, accL[r], false); accL[r] = __builtin_amdgcn_sdot8(d.y, ao.y, accL[r], false);
;                 }
;             }
;             asm volatile("s_waitcnt lgkmcnt(0)" ::: "memory");
;             if (q == 3) {
; #pragma unroll
;                 for (int r = 0; r < 4; ++r) STASH[256 * p + 16 * (grp + 4 * r) + pc] = f2bf(asc * (float)(2 * ((accH[r] << 4) + accL[r]) + sa));
;             }
;         }
;     ...
;             float4* op = (float4*)(outp + (size_t)t * D) + lane;
; #pragma unroll
;             for (int jq = 0; jq < 4; ++jq) { typedef float f4v __attribute__((ext_vector_type(4))); f4v o4; o4.x = v[jq].x * r3 * gv[jq].x; o4.y = v[jq].y * r3 * gv[jq].y; o4.z = v[jq].z * r3 * gv[jq].z; o4.w = v[jq].w * r3 * gv[jq].w;
;                 __builtin_nontemporal_store(o4, (f4v*)op + 64 * jq); }
	v_dot8c_i32_i4_e32 v38, v130, v52
	v_dot8c_i32_i4_e32 v39, v130, v50
	v_dot8c_i32_i4_e32 v40, v132, v52
	v_dot8c_i32_i4_e32 v41, v132, v50
	v_dot8c_i32_i4_e32 v42, v134, v52
	v_dot8c_i32_i4_e32 v43, v134, v50
	v_dot8c_i32_i4_e32 v44, v136, v52
	v_dot8c_i32_i4_e32 v45, v136, v50
	v_dot8c_i32_i4_e32 v38, v131, v53
	v_dot8c_i32_i4_e32 v39, v131, v51
	v_dot8c_i32_i4_e32 v40, v133, v53
	v_dot8c_i32_i4_e32 v41, v133, v51
	v_dot8c_i32_i4_e32 v42, v135, v53
	v_dot8c_i32_i4_e32 v43, v135, v51
	v_dot8c_i32_i4_e32 v44, v137, v53
	v_dot8c_i32_i4_e32 v45, v137, v51
	v_and_b32_e32 v78, 0xffff, v21
	v_lshrrev_b32_e32 v79, 16, v21
	v_lshl_add_u32 v78, v78, 7, v152
	v_lshl_add_u32 v79, v79, 7, v153
	s_mov_b32 m0, s99
	s_add_i32 s43, s99, 0x400
	global_load_lds_dwordx4 v78, s[50:51]
	s_mov_b32 m0, s43
	s_nop 0
	global_load_lds_dwordx4 v79, s[50:51]
	s_waitcnt vmcnt(8)
	v_add_u32_e32 v54, s77, v59
	v_add_u32_e32 v55, s77, v60
	v_add_u32_e32 v56, s77, v61
	v_add_u32_e32 v57, s77, v62
	ds_read_b64_tr_b4 v[50:51], v160 offset:896
	ds_read_b64_tr_b4 v[52:53], v160 offset:1920
	ds_read_b64_tr_b4 v[130:131], v54
	ds_read_b64_tr_b4 v[132:133], v55
	ds_read_b64_tr_b4 v[134:135], v56
	ds_read_b64_tr_b4 v[136:137], v57
	s_waitcnt lgkmcnt(6)
	v_dot8c_i32_i4_e32 v38, v122, v48
	v_dot8c_i32_i4_e32 v39, v122, v46
	v_dot8c_i32_i4_e32 v40, v124, v48
	v_dot8c_i32_i4_e32 v41, v124, v46
	v_dot8c_i32_i4_e32 v42, v126, v48
	v_dot8c_i32_i4_e32 v43, v126, v46
	v_dot8c_i32_i4_e32 v44, v128, v48
	v_dot8c_i32_i4_e32 v45, v128, v46
	v_dot8c_i32_i4_e32 v38, v123, v49
	v_dot8c_i32_i4_e32 v39, v123, v47
	v_dot8c_i32_i4_e32 v40, v125, v49
	v_dot8c_i32_i4_e32 v41, v125, v47
	v_dot8c_i32_i4_e32 v42, v127, v49
	v_dot8c_i32_i4_e32 v43, v127, v47
	v_dot8c_i32_i4_e32 v44, v129, v49
	v_dot8c_i32_i4_e32 v45, v129, v47
	v_and_b32_e32 v78, 0xffff, v22
	v_lshrrev_b32_e32 v79, 16, v22
	v_lshl_add_u32 v78, v78, 7, v152
	v_lshl_add_u32 v79, v79, 7, v153
	s_mov_b32 m0, s76
	s_add_i32 s43, s76, 0x400
	global_load_lds_dwordx4 v78, s[50:51]
	s_mov_b32 m0, s43
	s_nop 0
	global_load_lds_dwordx4 v79, s[50:51]
	s_waitcnt vmcnt(8)
	v_add_u32_e32 v54, s78, v59
	v_add_u32_e32 v55, s78, v60
	v_add_u32_e32 v56, s78, v61
	v_add_u32_e32 v57, s78, v62
	ds_read_b64_tr_b4 v[46:47], v160
	ds_read_b64_tr_b4 v[48:49], v160 offset:1024
	ds_read_b64_tr_b4 v[122:123], v54
	ds_read_b64_tr_b4 v[124:125], v55
	ds_read_b64_tr_b4 v[126:127], v56
	ds_read_b64_tr_b4 v[128:129], v57
	s_waitcnt lgkmcnt(6)
	v_dot8c_i32_i4_e32 v38, v130, v52
	v_dot8c_i32_i4_e32 v39, v130, v50
	v_dot8c_i32_i4_e32 v40, v132, v52
	v_dot8c_i32_i4_e32 v41, v132, v50
	v_dot8c_i32_i4_e32 v42, v134, v52
	v_dot8c_i32_i4_e32 v43, v134, v50
	v_dot8c_i32_i4_e32 v44, v136, v52
	v_dot8c_i32_i4_e32 v45, v136, v50
	v_dot8c_i32_i4_e32 v38, v131, v53
	v_dot8c_i32_i4_e32 v39, v131, v51
	v_dot8c_i32_i4_e32 v40, v133, v53
	v_dot8c_i32_i4_e32 v41, v133, v51
	v_dot8c_i32_i4_e32 v42, v135, v53
	v_dot8c_i32_i4_e32 v43, v135, v51
	v_dot8c_i32_i4_e32 v44, v137, v53
	v_dot8c_i32_i4_e32 v45, v137, v51
	s_nop 3
	s_waitcnt lgkmcnt(15)
	v_lshlrev_b32_e32 v38, 5, v38
	v_lshlrev_b32_e32 v39, 1, v39
	v_add3_u32 v38, v39, v229, v38
	v_cvt_f32_i32_e32 v38, v38
	v_mul_f32_e32 v38, v228, v38
	v_lshlrev_b32_e32 v40, 5, v40
	v_lshlrev_b32_e32 v41, 1, v41
	v_add3_u32 v40, v41, v229, v40
	v_cvt_f32_i32_e32 v40, v40
	v_mul_f32_e32 v40, v228, v40
	v_lshlrev_b32_e32 v42, 5, v42
	v_lshlrev_b32_e32 v43, 1, v43
	v_add3_u32 v42, v43, v229, v42
	v_cvt_f32_i32_e32 v42, v42
	v_mul_f32_e32 v42, v228, v42
	v_lshlrev_b32_e32 v44, 5, v44
	v_lshlrev_b32_e32 v45, 1, v45
	v_add3_u32 v44, v45, v229, v44
	v_cvt_f32_i32_e32 v44, v44
	v_mul_f32_e32 v44, v228, v44
	v_cvt_pk_bf16_f32 v186, v38, v40
	v_cvt_pk_bf16_f32 v187, v42, v44
	ds_read_b128 v[252:255], v155
	s_add_i32 s44, s40, 0
	s_ashr_i32 s45, s44, 31
	s_lshl_b64 s[44:45], s[44:45], 12
	v_lshl_add_u64 v[80:81], v[36:37], 0, s[44:45]
	s_waitcnt lgkmcnt(0)
	v_mul_f32_e32 v210, v210, v252
	v_mul_f32_e32 v211, v211, v253
	v_mul_f32_e32 v212, v212, v254
	v_mul_f32_e32 v213, v213, v255
	global_store_dwordx4 v[80:81], v[210:213], off nt
	s_add_i32 s43, s40, 8
	s_lshl_b32 s43, s43, 11
	v_add_u32_e32 v138, s43, v66
	global_load_dwordx2 v[194:195], v138, s[70:71]
	global_load_dwordx2 v[196:197], v138, s[70:71] offset:512
	global_load_dwordx2 v[198:199], v138, s[70:71] offset:1024
	global_load_dwordx2 v[200:201], v138, s[70:71] offset:1536
	v_add_u32_e32 v147, 8, v140
	v_and_b32_e32 v146, 15, v147
	v_xor_b32_e32 v146, 8, v146
	v_bfe_u32 v148, v147, 4, 4
	v_mul_lo_u32 v146, v146, s92
	v_mul_lo_u32 v148, v148, s92
	v_mov_b32_e32 v147, v146
	v_mov_b32_e32 v149, v148
	ds_write2st64_b64 v77, v[146:147], v[148:149] offset1:2
	v_add_u32_e32 v138, 0xc00, v74
	ds_read_u8 v139, v138
	v_add_u32_e32 v141, 0xc00, v73
	ds_read_u8 v140, v141
	s_add_i32 s43, s67, 64
	v_mov_b32_e32 v138, s43
	ds_read2st64_b32 v[228:229], v138 offset1:1
	ds_read_b128 v[26:29], v227 offset:6144
	ds_read_b128 v[30:33], v227 offset:6160
	v_mov_b32_e32 v38, 0
	v_mov_b32_e32 v39, 0
	v_mov_b32_e32 v40, 0
	v_mov_b32_e32 v41, 0
	v_mov_b32_e32 v42, 0
	v_mov_b32_e32 v43, 0
	v_mov_b32_e32 v44, 0
	v_mov_b32_e32 v45, 0
	v_and_b32_e32 v78, 0xffff, v23
	v_lshrrev_b32_e32 v79, 16, v23
	v_lshl_add_u32 v78, v78, 7, v152
	v_lshl_add_u32 v79, v79, 7, v153
	s_mov_b32 m0, s77
	s_add_i32 s43, s77, 0x400
	global_load_lds_dwordx4 v78, s[50:51]
	s_mov_b32 m0, s43
	s_nop 0
	global_load_lds_dwordx4 v79, s[50:51]
	s_waitcnt vmcnt(13)
	v_add_u32_e32 v54, s79, v59
	v_add_u32_e32 v55, s79, v60
	v_add_u32_e32 v56, s79, v61
	v_add_u32_e32 v57, s79, v62
	ds_read_b64_tr_b4 v[50:51], v160 offset:128
	ds_read_b64_tr_b4 v[52:53], v160 offset:1152
	ds_read_b64_tr_b4 v[130:131], v54
	ds_read_b64_tr_b4 v[132:133], v55
	ds_read_b64_tr_b4 v[134:135], v56
	ds_read_b64_tr_b4 v[136:137], v57
	s_waitcnt lgkmcnt(13)
; __device__ __forceinline__ bf16 f2bf(float f) { return (bf16)f2bfu(f); }
; #define TR4(p_) __builtin_amdgcn_ds_read_tr4_b64_v2i32((LAS v2i*)(p_))
; #define VDMA(st_, k_) do { _Pragma("unroll") for (int i_ = 0; i_ < 4; ++i_) { \
;         const unsigned off_ = (unsigned)((st_) >> 2) * (16384u * 128u) + (PE_ID(E, 4 * ((st_) & 3) + i_) << 7) + ((i_ & 1) ? cx1 : cx0); \
;         __builtin_amdgcn_global_load_lds((const unsigned*)(V4 + off_), (LAS unsigned*)(ldsb + BUF[k_] + 1024 * i_), 16, 0, 0); } } while (0)
; __device__ __forceinline__ void peer_v_tokens(int j, const LAS unsigned short* EL, const LAS unsigned char* AL  , const LAS float* ASC  , const LAS int* SAL  , ...
;     ...
;         for (int st = 0; st < 16; ++st) {
;             const int p = st >> 2, q = st & 3;
;             if (st < 14) VDMA(st + 2, (st + 2) % 3);
;             if (st < 14) asm volatile("s_waitcnt vmcnt(8)" ::: "memory");
;             else if (st == 14) asm volatile("s_waitcnt vmcnt(4)" ::: "memory");
;             else asm volatile("s_waitcnt vmcnt(0)" ::: "memory");
;             if (q == 0) {
; #pragma unroll
;                 for (int r = 0; r < 4; ++r) { accH[r] = 0; accL[r] = 0; } }
; #pragma unroll
;             for (int tp = 0; tp < 2; ++tp) {
;                 const v2i ao = TR4(ATL + (2 * q + tp) * 128 + 8 * s16), ah = TR4(ATL + 1024 + (2 * q + tp) * 128 + 8 * s16);
; #pragma unroll
;                 for (int r = 0; r < 4; ++r) {
;                     const v2i d = TR4(ldsb + BUF[st % 3] + 2048 * tp + roff[r]);
;                     accH[r] = __builtin_amdgcn_sdot8(d.x, ah.x, accH[r], false); accH[r] = __builtin_amdgcn_sdot8(d.y, ah.y, accH[r], false);
;                     accL[r] = __builtin_amdgcn_sdot8(d.x, ao.x, accL[r], false); accL[r] = __builtin_amdgcn_sdot8(d.y, ao.y, accL[r], false);
;                 }
;             }
;             asm volatile("s_waitcnt lgkmcnt(0)" ::: "memory");
;             if (q == 3) {
; #pragma unroll
;                 for (int r = 0; r < 4; ++r) STASH[256 * p + 16 * (grp + 4 * r) + pc] = f2bf(asc * (float)(2 * ((accH[r] << 4) + accL[r]) + sa));
;             }
;         }
	v_dot8c_i32_i4_e32 v38, v122, v48
	v_dot8c_i32_i4_e32 v39, v122, v46
	v_dot8c_i32_i4_e32 v40, v124, v48
	v_dot8c_i32_i4_e32 v41, v124, v46
	v_dot8c_i32_i4_e32 v42, v126, v48
	v_dot8c_i32_i4_e32 v43, v126, v46
	v_dot8c_i32_i4_e32 v44, v128, v48
	v_dot8c_i32_i4_e32 v45, v128, v46
	v_dot8c_i32_i4_e32 v38, v123, v49
	v_dot8c_i32_i4_e32 v39, v123, v47
	v_dot8c_i32_i4_e32 v40, v125, v49
	v_dot8c_i32_i4_e32 v41, v125, v47
	v_dot8c_i32_i4_e32 v42, v127, v49
	v_dot8c_i32_i4_e32 v43, v127, v47
	v_dot8c_i32_i4_e32 v44, v129, v49
	v_dot8c_i32_i4_e32 v45, v129, v47
	v_and_b32_e32 v78, 0xffff, v24
	v_lshrrev_b32_e32 v79, 16, v24
	v_lshl_add_u32 v78, v78, 7, v152
	v_lshl_add_u32 v79, v79, 7, v153
	s_mov_b32 m0, s78
	s_add_i32 s43, s78, 0x400
	global_load_lds_dwordx4 v78, s[50:51]
	s_mov_b32 m0, s43
	s_nop 0
	global_load_lds_dwordx4 v79, s[50:51]
	s_waitcnt vmcnt(13)
	v_add_u32_e32 v54, s98, v59
	v_add_u32_e32 v55, s98, v60
	v_add_u32_e32 v56, s98, v61
	v_add_u32_e32 v57, s98, v62
	ds_read_b64_tr_b4 v[46:47], v160 offset:256
	ds_read_b64_tr_b4 v[48:49], v160 offset:1280
	ds_read_b64_tr_b4 v[122:123], v54
	ds_read_b64_tr_b4 v[124:125], v55
	ds_read_b64_tr_b4 v[126:127], v56
	ds_read_b64_tr_b4 v[128:129], v57
	s_waitcnt lgkmcnt(6)
	v_dot8c_i32_i4_e32 v38, v130, v52
	v_dot8c_i32_i4_e32 v39, v130, v50
	v_dot8c_i32_i4_e32 v40, v132, v52
	v_dot8c_i32_i4_e32 v41, v132, v50
	v_dot8c_i32_i4_e32 v42, v134, v52
	v_dot8c_i32_i4_e32 v43, v134, v50
	v_dot8c_i32_i4_e32 v44, v136, v52
	v_dot8c_i32_i4_e32 v45, v136, v50
	v_dot8c_i32_i4_e32 v38, v131, v53
	v_dot8c_i32_i4_e32 v39, v131, v51
	v_dot8c_i32_i4_e32 v40, v133, v53
	v_dot8c_i32_i4_e32 v41, v133, v51
	v_dot8c_i32_i4_e32 v42, v135, v53
	v_dot8c_i32_i4_e32 v43, v135, v51
	v_dot8c_i32_i4_e32 v44, v137, v53
	v_dot8c_i32_i4_e32 v45, v137, v51
	v_and_b32_e32 v78, 0xffff, v25
	v_lshrrev_b32_e32 v79, 16, v25
	v_lshl_add_u32 v78, v78, 7, v152
	v_lshl_add_u32 v79, v79, 7, v153
	s_mov_b32 m0, s79
	s_add_i32 s43, s79, 0x400
	global_load_lds_dwordx4 v78, s[50:51]
	s_mov_b32 m0, s43
	s_nop 0
	global_load_lds_dwordx4 v79, s[50:51]
	s_waitcnt vmcnt(13)
	v_add_u32_e32 v54, s99, v59
	v_add_u32_e32 v55, s99, v60
	v_add_u32_e32 v56, s99, v61
	v_add_u32_e32 v57, s99, v62
	ds_read_b64_tr_b4 v[50:51], v160 offset:384
	ds_read_b64_tr_b4 v[52:53], v160 offset:1408
	ds_read_b64_tr_b4 v[130:131], v54
	ds_read_b64_tr_b4 v[132:133], v55
	ds_read_b64_tr_b4 v[134:135], v56
	ds_read_b64_tr_b4 v[136:137], v57
	s_waitcnt lgkmcnt(6)
	v_dot8c_i32_i4_e32 v38, v122, v48
	v_dot8c_i32_i4_e32 v39, v122, v46
	v_dot8c_i32_i4_e32 v40, v124, v48
	v_dot8c_i32_i4_e32 v41, v124, v46
	v_dot8c_i32_i4_e32 v42, v126, v48
	v_dot8c_i32_i4_e32 v43, v126, v46
	v_dot8c_i32_i4_e32 v44, v128, v48
	v_dot8c_i32_i4_e32 v45, v128, v46
	v_dot8c_i32_i4_e32 v38, v123, v49
	v_dot8c_i32_i4_e32 v39, v123, v47
	v_dot8c_i32_i4_e32 v40, v125, v49
	v_dot8c_i32_i4_e32 v41, v125, v47
	v_dot8c_i32_i4_e32 v42, v127, v49
	v_dot8c_i32_i4_e32 v43, v127, v47
	v_dot8c_i32_i4_e32 v44, v129, v49
	v_dot8c_i32_i4_e32 v45, v129, v47
	s_waitcnt lgkmcnt(15)
	v_and_b32_e32 v78, 0xffff, v26
	v_lshrrev_b32_e32 v79, 16, v26
	v_lshl_add_u32 v78, v78, 7, v152
	v_lshl_add_u32 v79, v79, 7, v153
	s_mov_b32 m0, s98
	s_add_i32 s43, s98, 0x400
	global_load_lds_dwordx4 v78, s[50:51]
	s_mov_b32 m0, s43
	s_nop 0
	global_load_lds_dwordx4 v79, s[50:51]
	s_waitcnt vmcnt(13)
	v_add_u32_e32 v54, s76, v59
	v_add_u32_e32 v55, s76, v60
	v_add_u32_e32 v56, s76, v61
	v_add_u32_e32 v57, s76, v62
	ds_read_b64_tr_b4 v[46:47], v160 offset:512
	ds_read_b64_tr_b4 v[48:49], v160 offset:1536
	ds_read_b64_tr_b4 v[122:123], v54
	ds_read_b64_tr_b4 v[124:125], v55
	ds_read_b64_tr_b4 v[126:127], v56
	ds_read_b64_tr_b4 v[128:129], v57
	s_waitcnt lgkmcnt(6)
	v_dot8c_i32_i4_e32 v38, v130, v52
	v_dot8c_i32_i4_e32 v39, v130, v50
	v_dot8c_i32_i4_e32 v40, v132, v52
	v_dot8c_i32_i4_e32 v41, v132, v50
	v_dot8c_i32_i4_e32 v42, v134, v52
	v_dot8c_i32_i4_e32 v43, v134, v50
	v_dot8c_i32_i4_e32 v44, v136, v52
	v_dot8c_i32_i4_e32 v45, v136, v50
	v_dot8c_i32_i4_e32 v38, v131, v53
	v_dot8c_i32_i4_e32 v39, v131, v51
	v_dot8c_i32_i4_e32 v40, v133, v53
	v_dot8c_i32_i4_e32 v41, v133, v51
	v_dot8c_i32_i4_e32 v42, v135, v53
	v_dot8c_i32_i4_e32 v43, v135, v51
	v_dot8c_i32_i4_e32 v44, v137, v53
	v_dot8c_i32_i4_e32 v45, v137, v51
	v_and_b32_e32 v78, 0xffff, v27
	v_lshrrev_b32_e32 v79, 16, v27
	v_lshl_add_u32 v78, v78, 7, v152
	v_lshl_add_u32 v79, v79, 7, v153
	s_mov_b32 m0, s99
	s_add_i32 s43, s99, 0x400
	global_load_lds_dwordx4 v78, s[50:51]
	s_mov_b32 m0, s43
	s_nop 0
	global_load_lds_dwordx4 v79, s[50:51]
	s_waitcnt vmcnt(8)
	v_add_u32_e32 v54, s77, v59
	v_add_u32_e32 v55, s77, v60
	v_add_u32_e32 v56, s77, v61
	v_add_u32_e32 v57, s77, v62
	ds_read_b64_tr_b4 v[50:51], v160 offset:640
	ds_read_b64_tr_b4 v[52:53], v160 offset:1664
	ds_read_b64_tr_b4 v[130:131], v54
	ds_read_b64_tr_b4 v[132:133], v55
	ds_read_b64_tr_b4 v[134:135], v56
	ds_read_b64_tr_b4 v[136:137], v57
	s_waitcnt lgkmcnt(6)
	v_dot8c_i32_i4_e32 v38, v122, v48
	v_dot8c_i32_i4_e32 v39, v122, v46
	v_dot8c_i32_i4_e32 v40, v124, v48
	v_dot8c_i32_i4_e32 v41, v124, v46
	v_dot8c_i32_i4_e32 v42, v126, v48
	v_dot8c_i32_i4_e32 v43, v126, v46
	v_dot8c_i32_i4_e32 v44, v128, v48
	v_dot8c_i32_i4_e32 v45, v128, v46
	v_dot8c_i32_i4_e32 v38, v123, v49
	v_dot8c_i32_i4_e32 v39, v123, v47
	v_dot8c_i32_i4_e32 v40, v125, v49
	v_dot8c_i32_i4_e32 v41, v125, v47
	v_dot8c_i32_i4_e32 v42, v127, v49
	v_dot8c_i32_i4_e32 v43, v127, v47
	v_dot8c_i32_i4_e32 v44, v129, v49
	v_dot8c_i32_i4_e32 v45, v129, v47
	s_waitcnt lgkmcnt(15)
; __device__ __forceinline__ void peer_v_tokens(int j, const LAS unsigned short* EL, const LAS unsigned char* AL  , const LAS float* ASC  , const LAS int* SAL  , ...
;     ...
;         for (int m = 0; m < 2; ++m) {
;             const int idx = lane + 64 * m, tau = idx >> 4, sr = idx & 15, k = 16 * (sr & 7) + 2 * tau + (sr >> 3);
;             const int aq = (int)*(const LAS signed char*)(AL + tl * 128 + k); const int tq = aq + 8;
;             const unsigned lo = (((unsigned)tq & 15u) ^ 8u) * 0x11111111u, hi = ((unsigned)(tq >> 4) & 15u) * 0x11111111u;
;     ...
;         for (int st = 0; st < 16; ++st) {
;             const int p = st >> 2, q = st & 3;
;             if (st < 14) VDMA(st + 2, (st + 2) % 3);
;             if (st < 14) asm volatile("s_waitcnt vmcnt(8)" ::: "memory");
;             else if (st == 14) asm volatile("s_waitcnt vmcnt(4)" ::: "memory");
;             else asm volatile("s_waitcnt vmcnt(0)" ::: "memory");
;             if (q == 0) {
; #pragma unroll
;                 for (int r = 0; r < 4; ++r) { accH[r] = 0; accL[r] = 0; } }
; #pragma unroll
;             for (int tp = 0; tp < 2; ++tp) {
;                 const v2i ao = TR4(ATL + (2 * q + tp) * 128 + 8 * s16), ah = TR4(ATL + 1024 + (2 * q + tp) * 128 + 8 * s16);
; #pragma unroll
;                 for (int r = 0; r < 4; ++r) {
;                     const v2i d = TR4(ldsb + BUF[st % 3] + 2048 * tp + roff[r]);
;                     accH[r] = __builtin_amdgcn_sdot8(d.x, ah.x, accH[r], false); accH[r] = __builtin_amdgcn_sdot8(d.y, ah.y, accH[r], false);
;                     accL[r] = __builtin_amdgcn_sdot8(d.x, ao.x, accL[r], false); accL[r] = __builtin_amdgcn_sdot8(d.y, ao.y, accL[r], false);
;                 }
;             }
;             asm volatile("s_waitcnt lgkmcnt(0)" ::: "memory");
;             if (q == 3) {
; #pragma unroll
;                 for (int r = 0; r < 4; ++r) STASH[256 * p + 16 * (grp + 4 * r) + pc] = f2bf(asc * (float)(2 * ((accH[r] << 4) + accL[r]) + sa));
;             }
;         }
;     ...
;             float4* op = (float4*)(outp + (size_t)t * D) + lane;
; #pragma unroll
;             for (int jq = 0; jq < 4; ++jq) { typedef float f4v __attribute__((ext_vector_type(4))); f4v o4; o4.x = v[jq].x * r3 * gv[jq].x; o4.y = v[jq].y * r3 * gv[jq].y; o4.z = v[jq].z * r3 * gv[jq].z; o4.w = v[jq].w * r3 * gv[jq].w;
;                 __builtin_nontemporal_store(o4, (f4v*)op + 64 * jq); }
	v_add_u32_e32 v143, 8, v139
	v_and_b32_e32 v142, 15, v143
	v_xor_b32_e32 v142, 8, v142
	v_bfe_u32 v144, v143, 4, 4
	v_mul_lo_u32 v142, v142, s92
	v_mul_lo_u32 v144, v144, s92
	v_mov_b32_e32 v143, v142
	v_mov_b32_e32 v145, v144
	ds_write2st64_b64 v159, v[142:143], v[144:145] offset1:2
	v_and_b32_e32 v78, 0xffff, v28
	v_lshrrev_b32_e32 v79, 16, v28
	v_lshl_add_u32 v78, v78, 7, v152
	v_lshl_add_u32 v79, v79, 7, v153
	s_mov_b32 m0, s76
	s_add_i32 s43, s76, 0x400
	global_load_lds_dwordx4 v78, s[50:51]
	s_mov_b32 m0, s43
	s_nop 0
	global_load_lds_dwordx4 v79, s[50:51]
	s_waitcnt vmcnt(8)
	v_add_u32_e32 v54, s78, v59
	v_add_u32_e32 v55, s78, v60
	v_add_u32_e32 v56, s78, v61
	v_add_u32_e32 v57, s78, v62
	ds_read_b64_tr_b4 v[46:47], v160 offset:768
	ds_read_b64_tr_b4 v[48:49], v160 offset:1792
	ds_read_b64_tr_b4 v[122:123], v54
	ds_read_b64_tr_b4 v[124:125], v55
	ds_read_b64_tr_b4 v[126:127], v56
	ds_read_b64_tr_b4 v[128:129], v57
	s_waitcnt lgkmcnt(7)
	v_dot8c_i32_i4_e32 v38, v130, v52
	v_dot8c_i32_i4_e32 v39, v130, v50
	v_dot8c_i32_i4_e32 v40, v132, v52
	v_dot8c_i32_i4_e32 v41, v132, v50
	v_dot8c_i32_i4_e32 v42, v134, v52
	v_dot8c_i32_i4_e32 v43, v134, v50
	v_dot8c_i32_i4_e32 v44, v136, v52
	v_dot8c_i32_i4_e32 v45, v136, v50
	v_dot8c_i32_i4_e32 v38, v131, v53
	v_dot8c_i32_i4_e32 v39, v131, v51
	v_dot8c_i32_i4_e32 v40, v133, v53
	v_dot8c_i32_i4_e32 v41, v133, v51
	v_dot8c_i32_i4_e32 v42, v135, v53
	v_dot8c_i32_i4_e32 v43, v135, v51
	v_dot8c_i32_i4_e32 v44, v137, v53
	v_dot8c_i32_i4_e32 v45, v137, v51
	v_and_b32_e32 v78, 0xffff, v29
	v_lshrrev_b32_e32 v79, 16, v29
	v_lshl_add_u32 v78, v78, 7, v152
	v_lshl_add_u32 v79, v79, 7, v153
	s_mov_b32 m0, s77
	s_add_i32 s43, s77, 0x400
	global_load_lds_dwordx4 v78, s[50:51]
	s_mov_b32 m0, s43
	s_nop 0
	global_load_lds_dwordx4 v79, s[50:51]
	s_waitcnt vmcnt(8)
	v_add_u32_e32 v54, s79, v59
	v_add_u32_e32 v55, s79, v60
	v_add_u32_e32 v56, s79, v61
	v_add_u32_e32 v57, s79, v62
	ds_read_b64_tr_b4 v[50:51], v160 offset:896
	ds_read_b64_tr_b4 v[52:53], v160 offset:1920
	ds_read_b64_tr_b4 v[130:131], v54
	ds_read_b64_tr_b4 v[132:133], v55
	ds_read_b64_tr_b4 v[134:135], v56
	ds_read_b64_tr_b4 v[136:137], v57
	s_waitcnt lgkmcnt(6)
	v_dot8c_i32_i4_e32 v38, v122, v48
	v_dot8c_i32_i4_e32 v39, v122, v46
	v_dot8c_i32_i4_e32 v40, v124, v48
	v_dot8c_i32_i4_e32 v41, v124, v46
	v_dot8c_i32_i4_e32 v42, v126, v48
	v_dot8c_i32_i4_e32 v43, v126, v46
	v_dot8c_i32_i4_e32 v44, v128, v48
	v_dot8c_i32_i4_e32 v45, v128, v46
	v_dot8c_i32_i4_e32 v38, v123, v49
	v_dot8c_i32_i4_e32 v39, v123, v47
	v_dot8c_i32_i4_e32 v40, v125, v49
	v_dot8c_i32_i4_e32 v41, v125, v47
	v_dot8c_i32_i4_e32 v42, v127, v49
	v_dot8c_i32_i4_e32 v43, v127, v47
	v_dot8c_i32_i4_e32 v44, v129, v49
	v_dot8c_i32_i4_e32 v45, v129, v47
	v_and_b32_e32 v78, 0xffff, v30
	v_lshrrev_b32_e32 v79, 16, v30
	v_lshl_add_u32 v78, v78, 7, v152
	v_lshl_add_u32 v79, v79, 7, v153
	s_mov_b32 m0, s78
	s_add_i32 s43, s78, 0x400
	global_load_lds_dwordx4 v78, s[50:51]
	s_mov_b32 m0, s43
	s_nop 0
	global_load_lds_dwordx4 v79, s[50:51]
	s_waitcnt vmcnt(8)
	v_add_u32_e32 v54, s98, v59
	v_add_u32_e32 v55, s98, v60
	v_add_u32_e32 v56, s98, v61
	v_add_u32_e32 v57, s98, v62
	ds_read_b64_tr_b4 v[46:47], v160
	ds_read_b64_tr_b4 v[48:49], v160 offset:1024
	ds_read_b64_tr_b4 v[122:123], v54
	ds_read_b64_tr_b4 v[124:125], v55
	ds_read_b64_tr_b4 v[126:127], v56
	ds_read_b64_tr_b4 v[128:129], v57
	s_waitcnt lgkmcnt(6)
	v_dot8c_i32_i4_e32 v38, v130, v52
	v_dot8c_i32_i4_e32 v39, v130, v50
	v_dot8c_i32_i4_e32 v40, v132, v52
	v_dot8c_i32_i4_e32 v41, v132, v50
	v_dot8c_i32_i4_e32 v42, v134, v52
	v_dot8c_i32_i4_e32 v43, v134, v50
	v_dot8c_i32_i4_e32 v44, v136, v52
	v_dot8c_i32_i4_e32 v45, v136, v50
	v_dot8c_i32_i4_e32 v38, v131, v53
	v_dot8c_i32_i4_e32 v39, v131, v51
	v_dot8c_i32_i4_e32 v40, v133, v53
	v_dot8c_i32_i4_e32 v41, v133, v51
	v_dot8c_i32_i4_e32 v42, v135, v53
	v_dot8c_i32_i4_e32 v43, v135, v51
	v_dot8c_i32_i4_e32 v44, v137, v53
	v_dot8c_i32_i4_e32 v45, v137, v51
	s_nop 3
	s_waitcnt lgkmcnt(15)
	v_lshlrev_b32_e32 v38, 5, v38
	v_lshlrev_b32_e32 v39, 1, v39
	v_add3_u32 v38, v39, v229, v38
	v_cvt_f32_i32_e32 v38, v38
	v_mul_f32_e32 v38, v228, v38
	v_lshlrev_b32_e32 v40, 5, v40
	v_lshlrev_b32_e32 v41, 1, v41
	v_add3_u32 v40, v41, v229, v40
	v_cvt_f32_i32_e32 v40, v40
	v_mul_f32_e32 v40, v228, v40
	v_lshlrev_b32_e32 v42, 5, v42
	v_lshlrev_b32_e32 v43, 1, v43
	v_add3_u32 v42, v43, v229, v42
	v_cvt_f32_i32_e32 v42, v42
	v_mul_f32_e32 v42, v228, v42
	v_lshlrev_b32_e32 v44, 5, v44
	v_lshlrev_b32_e32 v45, 1, v45
	v_add3_u32 v44, v45, v229, v44
	v_cvt_f32_i32_e32 v44, v44
	v_mul_f32_e32 v44, v228, v44
	v_cvt_pk_bf16_f32 v180, v38, v40
	v_cvt_pk_bf16_f32 v181, v42, v44
	ds_read_b128 v[252:255], v155 offset:1024
	s_add_i32 s44, s40, 0
	s_ashr_i32 s45, s44, 31
	s_lshl_b64 s[44:45], s[44:45], 12
	v_lshl_add_u64 v[80:81], v[36:37], 0, s[44:45]
	s_waitcnt lgkmcnt(0)
	v_mul_f32_e32 v214, v214, v252
	v_mul_f32_e32 v215, v215, v253
	v_mul_f32_e32 v216, v216, v254
	v_mul_f32_e32 v217, v217, v255
	global_store_dwordx4 v[80:81], v[214:217], off offset:1024 nt
	v_add_u32_e32 v147, 8, v140
	v_and_b32_e32 v146, 15, v147
	v_xor_b32_e32 v146, 8, v146
	v_bfe_u32 v148, v147, 4, 4
	v_mul_lo_u32 v146, v146, s92
	v_mul_lo_u32 v148, v148, s92
	v_mov_b32_e32 v147, v146
	v_mov_b32_e32 v149, v148
	ds_write2st64_b64 v77, v[146:147], v[148:149] offset1:2
	v_add_u32_e32 v138, 0x800, v74
	ds_read_u8 v139, v138
	v_add_u32_e32 v141, 0x800, v73
	ds_read_u8 v140, v141
	s_add_i32 s43, s67, 96
	v_mov_b32_e32 v138, s43
	ds_read2st64_b32 v[228:229], v138 offset1:1
	ds_read_b128 v[18:21], v227 offset:4096
	ds_read_b128 v[22:25], v227 offset:4112
	v_add_u32_e32 v150, 0x400000, v63
	v_add_u32_e32 v151, 0x400000, v64
	v_mov_b32_e32 v38, 0
	v_mov_b32_e32 v39, 0
	v_mov_b32_e32 v40, 0
	v_mov_b32_e32 v41, 0
	v_mov_b32_e32 v42, 0
	v_mov_b32_e32 v43, 0
	v_mov_b32_e32 v44, 0
	v_mov_b32_e32 v45, 0
	v_and_b32_e32 v78, 0xffff, v31
	v_lshrrev_b32_e32 v79, 16, v31
	v_lshl_add_u32 v78, v78, 7, v152
	v_lshl_add_u32 v79, v79, 7, v153
	s_mov_b32 m0, s79
	s_add_i32 s43, s79, 0x400
	global_load_lds_dwordx4 v78, s[50:51]
	s_mov_b32 m0, s43
	s_nop 0
	global_load_lds_dwordx4 v79, s[50:51]
	s_waitcnt vmcnt(9)
; __device__ __forceinline__ bf16 f2bf(float f) { return (bf16)f2bfu(f); }
; #define TR4(p_) __builtin_amdgcn_ds_read_tr4_b64_v2i32((LAS v2i*)(p_))
; #define VDMA(st_, k_) do { _Pragma("unroll") for (int i_ = 0; i_ < 4; ++i_) { \
;         const unsigned off_ = (unsigned)((st_) >> 2) * (16384u * 128u) + (PE_ID(E, 4 * ((st_) & 3) + i_) << 7) + ((i_ & 1) ? cx1 : cx0); \
;         __builtin_amdgcn_global_load_lds((const unsigned*)(V4 + off_), (LAS unsigned*)(ldsb + BUF[k_] + 1024 * i_), 16, 0, 0); } } while (0)
; __device__ __forceinline__ void peer_v_tokens(int j, const LAS unsigned short* EL, const LAS unsigned char* AL  , const LAS float* ASC  , const LAS int* SAL  , ...
;     ...
;         for (int st = 0; st < 16; ++st) {
;             const int p = st >> 2, q = st & 3;
;             if (st < 14) VDMA(st + 2, (st + 2) % 3);
;             if (st < 14) asm volatile("s_waitcnt vmcnt(8)" ::: "memory");
;             else if (st == 14) asm volatile("s_waitcnt vmcnt(4)" ::: "memory");
;             else asm volatile("s_waitcnt vmcnt(0)" ::: "memory");
;             if (q == 0) {
; #pragma unroll
;                 for (int r = 0; r < 4; ++r) { accH[r] = 0; accL[r] = 0; } }
; #pragma unroll
;             for (int tp = 0; tp < 2; ++tp) {
;                 const v2i ao = TR4(ATL + (2 * q + tp) * 128 + 8 * s16), ah = TR4(ATL + 1024 + (2 * q + tp) * 128 + 8 * s16);
; #pragma unroll
;                 for (int r = 0; r < 4; ++r) {
;                     const v2i d = TR4(ldsb + BUF[st % 3] + 2048 * tp + roff[r]);
;                     accH[r] = __builtin_amdgcn_sdot8(d.x, ah.x, accH[r], false); accH[r] = __builtin_amdgcn_sdot8(d.y, ah.y, accH[r], false);
;                     accL[r] = __builtin_amdgcn_sdot8(d.x, ao.x, accL[r], false); accL[r] = __builtin_amdgcn_sdot8(d.y, ao.y, accL[r], false);
;                 }
;             }
;             asm volatile("s_waitcnt lgkmcnt(0)" ::: "memory");
;             if (q == 3) {
; #pragma unroll
;                 for (int r = 0; r < 4; ++r) STASH[256 * p + 16 * (grp + 4 * r) + pc] = f2bf(asc * (float)(2 * ((accH[r] << 4) + accL[r]) + sa));
;             }
	v_add_u32_e32 v54, s99, v59
	v_add_u32_e32 v55, s99, v60
	v_add_u32_e32 v56, s99, v61
	v_add_u32_e32 v57, s99, v62
	ds_read_b64_tr_b4 v[50:51], v160 offset:128
	ds_read_b64_tr_b4 v[52:53], v160 offset:1152
	ds_read_b64_tr_b4 v[130:131], v54
	ds_read_b64_tr_b4 v[132:133], v55
	ds_read_b64_tr_b4 v[134:135], v56
	ds_read_b64_tr_b4 v[136:137], v57
	s_waitcnt lgkmcnt(13)
	v_dot8c_i32_i4_e32 v38, v122, v48
	v_dot8c_i32_i4_e32 v39, v122, v46
	v_dot8c_i32_i4_e32 v40, v124, v48
	v_dot8c_i32_i4_e32 v41, v124, v46
	v_dot8c_i32_i4_e32 v42, v126, v48
	v_dot8c_i32_i4_e32 v43, v126, v46
	v_dot8c_i32_i4_e32 v44, v128, v48
	v_dot8c_i32_i4_e32 v45, v128, v46
	v_dot8c_i32_i4_e32 v38, v123, v49
	v_dot8c_i32_i4_e32 v39, v123, v47
	v_dot8c_i32_i4_e32 v40, v125, v49
	v_dot8c_i32_i4_e32 v41, v125, v47
	v_dot8c_i32_i4_e32 v42, v127, v49
	v_dot8c_i32_i4_e32 v43, v127, v47
	v_dot8c_i32_i4_e32 v44, v129, v49
	v_dot8c_i32_i4_e32 v45, v129, v47
	v_and_b32_e32 v78, 0xffff, v32
	v_lshrrev_b32_e32 v79, 16, v32
	v_lshl_add_u32 v78, v78, 7, v152
	v_lshl_add_u32 v79, v79, 7, v153
	s_mov_b32 m0, s98
	s_add_i32 s43, s98, 0x400
	global_load_lds_dwordx4 v78, s[50:51]
	s_mov_b32 m0, s43
	s_nop 0
	global_load_lds_dwordx4 v79, s[50:51]
	s_waitcnt vmcnt(9)
	v_add_u32_e32 v54, s76, v59
	v_add_u32_e32 v55, s76, v60
	v_add_u32_e32 v56, s76, v61
	v_add_u32_e32 v57, s76, v62
	ds_read_b64_tr_b4 v[46:47], v160 offset:256
	ds_read_b64_tr_b4 v[48:49], v160 offset:1280
	ds_read_b64_tr_b4 v[122:123], v54
	ds_read_b64_tr_b4 v[124:125], v55
	ds_read_b64_tr_b4 v[126:127], v56
	ds_read_b64_tr_b4 v[128:129], v57
	s_waitcnt lgkmcnt(6)
	v_dot8c_i32_i4_e32 v38, v130, v52
	v_dot8c_i32_i4_e32 v39, v130, v50
	v_dot8c_i32_i4_e32 v40, v132, v52
	v_dot8c_i32_i4_e32 v41, v132, v50
	v_dot8c_i32_i4_e32 v42, v134, v52
	v_dot8c_i32_i4_e32 v43, v134, v50
	v_dot8c_i32_i4_e32 v44, v136, v52
	v_dot8c_i32_i4_e32 v45, v136, v50
	v_dot8c_i32_i4_e32 v38, v131, v53
	v_dot8c_i32_i4_e32 v39, v131, v51
	v_dot8c_i32_i4_e32 v40, v133, v53
	v_dot8c_i32_i4_e32 v41, v133, v51
	v_dot8c_i32_i4_e32 v42, v135, v53
	v_dot8c_i32_i4_e32 v43, v135, v51
	v_dot8c_i32_i4_e32 v44, v137, v53
	v_dot8c_i32_i4_e32 v45, v137, v51
	ds_write_b16 v65, v170
	ds_write_b16_d16_hi v65, v170 offset:128
	ds_write_b16 v65, v171 offset:256
	ds_write_b16_d16_hi v65, v171 offset:384
	ds_write_b16 v65, v172 offset:512
	ds_write_b16_d16_hi v65, v172 offset:640
	ds_write_b16 v65, v173 offset:768
	ds_write_b16_d16_hi v65, v173 offset:896
	ds_write_b16 v65, v174 offset:1024
	ds_write_b16_d16_hi v65, v174 offset:1152
	ds_write_b16 v65, v175 offset:1280
	ds_write_b16_d16_hi v65, v175 offset:1408
	ds_write_b16 v65, v176 offset:1536
	ds_write_b16_d16_hi v65, v176 offset:1664
	ds_write_b16 v65, v177 offset:1792
	ds_write_b16_d16_hi v65, v177 offset:1920
	ds_read_b64 v[202:203], v154
	ds_read_b64 v[204:205], v154 offset:512
	ds_read_b64 v[206:207], v154 offset:1024
	ds_read_b64 v[208:209], v154 offset:1536
	v_and_b32_e32 v78, 0xffff, v33
	v_lshrrev_b32_e32 v79, 16, v33
	v_lshl_add_u32 v78, v78, 7, v152
	v_lshl_add_u32 v79, v79, 7, v153
	s_mov_b32 m0, s99
	s_add_i32 s43, s99, 0x400
	global_load_lds_dwordx4 v78, s[50:51]
	s_mov_b32 m0, s43
	s_nop 0
	global_load_lds_dwordx4 v79, s[50:51]
	s_waitcnt vmcnt(9)
	v_add_u32_e32 v54, s77, v59
	v_add_u32_e32 v55, s77, v60
	v_add_u32_e32 v56, s77, v61
	v_add_u32_e32 v57, s77, v62
	ds_read_b64_tr_b4 v[50:51], v160 offset:384
	ds_read_b64_tr_b4 v[52:53], v160 offset:1408
	ds_read_b64_tr_b4 v[130:131], v54
	ds_read_b64_tr_b4 v[132:133], v55
	ds_read_b64_tr_b4 v[134:135], v56
	ds_read_b64_tr_b4 v[136:137], v57
	s_waitcnt lgkmcnt(15)
	v_dot8c_i32_i4_e32 v38, v122, v48
	v_dot8c_i32_i4_e32 v39, v122, v46
	v_dot8c_i32_i4_e32 v40, v124, v48
	v_dot8c_i32_i4_e32 v41, v124, v46
	v_dot8c_i32_i4_e32 v42, v126, v48
	v_dot8c_i32_i4_e32 v43, v126, v46
	v_dot8c_i32_i4_e32 v44, v128, v48
	v_dot8c_i32_i4_e32 v45, v128, v46
	v_dot8c_i32_i4_e32 v38, v123, v49
	v_dot8c_i32_i4_e32 v39, v123, v47
	v_dot8c_i32_i4_e32 v40, v125, v49
	v_dot8c_i32_i4_e32 v41, v125, v47
	v_dot8c_i32_i4_e32 v42, v127, v49
	v_dot8c_i32_i4_e32 v43, v127, v47
	v_dot8c_i32_i4_e32 v44, v129, v49
	v_dot8c_i32_i4_e32 v45, v129, v47
	s_waitcnt lgkmcnt(15)
	v_and_b32_e32 v78, 0xffff, v18
	v_lshrrev_b32_e32 v79, 16, v18
	v_lshl_add_u32 v78, v78, 7, v150
	v_lshl_add_u32 v79, v79, 7, v151
	s_mov_b32 m0, s76
	s_add_i32 s43, s76, 0x400
	global_load_lds_dwordx4 v78, s[50:51]
	s_mov_b32 m0, s43
	s_nop 0
	global_load_lds_dwordx4 v79, s[50:51]
	s_waitcnt vmcnt(9)
	v_add_u32_e32 v54, s78, v59
	v_add_u32_e32 v55, s78, v60
	v_add_u32_e32 v56, s78, v61
	v_add_u32_e32 v57, s78, v62
	ds_read_b64_tr_b4 v[46:47], v160 offset:512
	ds_read_b64_tr_b4 v[48:49], v160 offset:1536
	ds_read_b64_tr_b4 v[122:123], v54
	ds_read_b64_tr_b4 v[124:125], v55
	ds_read_b64_tr_b4 v[126:127], v56
	ds_read_b64_tr_b4 v[128:129], v57
	s_waitcnt lgkmcnt(6)
	v_dot8c_i32_i4_e32 v38, v130, v52
	v_dot8c_i32_i4_e32 v39, v130, v50
	v_dot8c_i32_i4_e32 v40, v132, v52
	v_dot8c_i32_i4_e32 v41, v132, v50
	v_dot8c_i32_i4_e32 v42, v134, v52
	v_dot8c_i32_i4_e32 v43, v134, v50
	v_dot8c_i32_i4_e32 v44, v136, v52
	v_dot8c_i32_i4_e32 v45, v136, v50
	v_dot8c_i32_i4_e32 v38, v131, v53
	v_dot8c_i32_i4_e32 v39, v131, v51
	v_dot8c_i32_i4_e32 v40, v133, v53
	v_dot8c_i32_i4_e32 v41, v133, v51
	v_dot8c_i32_i4_e32 v42, v135, v53
	v_dot8c_i32_i4_e32 v43, v135, v51
	v_dot8c_i32_i4_e32 v44, v137, v53
	v_dot8c_i32_i4_e32 v45, v137, v51
	v_and_b32_e32 v78, 0xffff, v19
	v_lshrrev_b32_e32 v79, 16, v19
	v_lshl_add_u32 v78, v78, 7, v150
	v_lshl_add_u32 v79, v79, 7, v151
	s_mov_b32 m0, s77
	s_add_i32 s43, s77, 0x400
	global_load_lds_dwordx4 v78, s[50:51]
	s_mov_b32 m0, s43
	s_nop 0
	global_load_lds_dwordx4 v79, s[50:51]
	s_waitcnt vmcnt(8)
; __device__ __forceinline__ bf16 f2bf(float f) { return (bf16)f2bfu(f); }
; #define TR4(p_) __builtin_amdgcn_ds_read_tr4_b64_v2i32((LAS v2i*)(p_))
; __device__ __forceinline__ void peer_v_tokens(int j, const LAS unsigned short* EL, const LAS unsigned char* AL  , const LAS float* ASC  , const LAS int* SAL  , ...
;     ...
;         for (int st = 0; st < 16; ++st) {
;             const int p = st >> 2, q = st & 3;
;             if (st < 14) VDMA(st + 2, (st + 2) % 3);
;             if (st < 14) asm volatile("s_waitcnt vmcnt(8)" ::: "memory");
;             else if (st == 14) asm volatile("s_waitcnt vmcnt(4)" ::: "memory");
;             else asm volatile("s_waitcnt vmcnt(0)" ::: "memory");
;             if (q == 0) {
; #pragma unroll
;                 for (int r = 0; r < 4; ++r) { accH[r] = 0; accL[r] = 0; } }
; #pragma unroll
;             for (int tp = 0; tp < 2; ++tp) {
;                 const v2i ao = TR4(ATL + (2 * q + tp) * 128 + 8 * s16), ah = TR4(ATL + 1024 + (2 * q + tp) * 128 + 8 * s16);
; #pragma unroll
;                 for (int r = 0; r < 4; ++r) {
;                     const v2i d = TR4(ldsb + BUF[st % 3] + 2048 * tp + roff[r]);
;                     accH[r] = __builtin_amdgcn_sdot8(d.x, ah.x, accH[r], false); accH[r] = __builtin_amdgcn_sdot8(d.y, ah.y, accH[r], false);
;                     accL[r] = __builtin_amdgcn_sdot8(d.x, ao.x, accL[r], false); accL[r] = __builtin_amdgcn_sdot8(d.y, ao.y, accL[r], false);
;                 }
;             }
;             asm volatile("s_waitcnt lgkmcnt(0)" ::: "memory");
;             if (q == 3) {
; #pragma unroll
;                 for (int r = 0; r < 4; ++r) STASH[256 * p + 16 * (grp + 4 * r) + pc] = f2bf(asc * (float)(2 * ((accH[r] << 4) + accL[r]) + sa));
;             }
;     ...
;             for (int jq = 0; jq < 4; ++jq) { typedef float f4v __attribute__((ext_vector_type(4))); f4v o4; o4.x = v[jq].x * r3 * gv[jq].x; o4.y = v[jq].y * r3 * gv[jq].y; o4.z = v[jq].z * r3 * gv[jq].z; o4.w = v[jq].w * r3 * gv[jq].w;
;                 __builtin_nontemporal_store(o4, (f4v*)op + 64 * jq); }
	v_add_u32_e32 v54, s79, v59
	v_add_u32_e32 v55, s79, v60
	v_add_u32_e32 v56, s79, v61
	v_add_u32_e32 v57, s79, v62
	ds_read_b64_tr_b4 v[50:51], v160 offset:640
	ds_read_b64_tr_b4 v[52:53], v160 offset:1664
	ds_read_b64_tr_b4 v[130:131], v54
	ds_read_b64_tr_b4 v[132:133], v55
	ds_read_b64_tr_b4 v[134:135], v56
	ds_read_b64_tr_b4 v[136:137], v57
	s_waitcnt lgkmcnt(6)
	v_dot8c_i32_i4_e32 v38, v122, v48
	v_dot8c_i32_i4_e32 v39, v122, v46
	v_dot8c_i32_i4_e32 v40, v124, v48
	v_dot8c_i32_i4_e32 v41, v124, v46
	v_dot8c_i32_i4_e32 v42, v126, v48
	v_dot8c_i32_i4_e32 v43, v126, v46
	v_dot8c_i32_i4_e32 v44, v128, v48
	v_dot8c_i32_i4_e32 v45, v128, v46
	v_dot8c_i32_i4_e32 v38, v123, v49
	v_dot8c_i32_i4_e32 v39, v123, v47
	v_dot8c_i32_i4_e32 v40, v125, v49
	v_dot8c_i32_i4_e32 v41, v125, v47
	v_dot8c_i32_i4_e32 v42, v127, v49
	v_dot8c_i32_i4_e32 v43, v127, v47
	v_dot8c_i32_i4_e32 v44, v129, v49
	v_dot8c_i32_i4_e32 v45, v129, v47
	s_waitcnt lgkmcnt(15)
	v_add_u32_e32 v143, 8, v139
	v_and_b32_e32 v142, 15, v143
	v_xor_b32_e32 v142, 8, v142
	v_bfe_u32 v144, v143, 4, 4
	v_mul_lo_u32 v142, v142, s92
	v_mul_lo_u32 v144, v144, s92
	v_mov_b32_e32 v143, v142
	v_mov_b32_e32 v145, v144
	ds_write2st64_b64 v159, v[142:143], v[144:145] offset1:2
	v_and_b32_e32 v78, 0xffff, v20
	v_lshrrev_b32_e32 v79, 16, v20
	v_lshl_add_u32 v78, v78, 7, v150
	v_lshl_add_u32 v79, v79, 7, v151
	s_mov_b32 m0, s78
	s_add_i32 s43, s78, 0x400
	global_load_lds_dwordx4 v78, s[50:51]
	s_mov_b32 m0, s43
	s_nop 0
	global_load_lds_dwordx4 v79, s[50:51]
	s_waitcnt vmcnt(8)
	v_add_u32_e32 v54, s98, v59
	v_add_u32_e32 v55, s98, v60
	v_add_u32_e32 v56, s98, v61
	v_add_u32_e32 v57, s98, v62
	ds_read_b64_tr_b4 v[46:47], v160 offset:768
	ds_read_b64_tr_b4 v[48:49], v160 offset:1792
	ds_read_b64_tr_b4 v[122:123], v54
	ds_read_b64_tr_b4 v[124:125], v55
	ds_read_b64_tr_b4 v[126:127], v56
	ds_read_b64_tr_b4 v[128:129], v57
	s_waitcnt lgkmcnt(7)
	v_dot8c_i32_i4_e32 v38, v130, v52
	v_dot8c_i32_i4_e32 v39, v130, v50
	v_dot8c_i32_i4_e32 v40, v132, v52
	v_dot8c_i32_i4_e32 v41, v132, v50
	v_dot8c_i32_i4_e32 v42, v134, v52
	v_dot8c_i32_i4_e32 v43, v134, v50
	v_dot8c_i32_i4_e32 v44, v136, v52
	v_dot8c_i32_i4_e32 v45, v136, v50
	v_dot8c_i32_i4_e32 v38, v131, v53
	v_dot8c_i32_i4_e32 v39, v131, v51
	v_dot8c_i32_i4_e32 v40, v133, v53
	v_dot8c_i32_i4_e32 v41, v133, v51
	v_dot8c_i32_i4_e32 v42, v135, v53
	v_dot8c_i32_i4_e32 v43, v135, v51
	v_dot8c_i32_i4_e32 v44, v137, v53
	v_dot8c_i32_i4_e32 v45, v137, v51
	v_and_b32_e32 v78, 0xffff, v21
	v_lshrrev_b32_e32 v79, 16, v21
	v_lshl_add_u32 v78, v78, 7, v150
	v_lshl_add_u32 v79, v79, 7, v151
	s_mov_b32 m0, s79
	s_add_i32 s43, s79, 0x400
	global_load_lds_dwordx4 v78, s[50:51]
	s_mov_b32 m0, s43
	s_nop 0
	global_load_lds_dwordx4 v79, s[50:51]
	s_waitcnt vmcnt(8)
	v_add_u32_e32 v54, s99, v59
	v_add_u32_e32 v55, s99, v60
	v_add_u32_e32 v56, s99, v61
	v_add_u32_e32 v57, s99, v62
	ds_read_b64_tr_b4 v[50:51], v160 offset:896
	ds_read_b64_tr_b4 v[52:53], v160 offset:1920
	ds_read_b64_tr_b4 v[130:131], v54
	ds_read_b64_tr_b4 v[132:133], v55
	ds_read_b64_tr_b4 v[134:135], v56
	ds_read_b64_tr_b4 v[136:137], v57
	s_waitcnt lgkmcnt(6)
	v_dot8c_i32_i4_e32 v38, v122, v48
	v_dot8c_i32_i4_e32 v39, v122, v46
	v_dot8c_i32_i4_e32 v40, v124, v48
	v_dot8c_i32_i4_e32 v41, v124, v46
	v_dot8c_i32_i4_e32 v42, v126, v48
	v_dot8c_i32_i4_e32 v43, v126, v46
	v_dot8c_i32_i4_e32 v44, v128, v48
	v_dot8c_i32_i4_e32 v45, v128, v46
	v_dot8c_i32_i4_e32 v38, v123, v49
	v_dot8c_i32_i4_e32 v39, v123, v47
	v_dot8c_i32_i4_e32 v40, v125, v49
	v_dot8c_i32_i4_e32 v41, v125, v47
	v_dot8c_i32_i4_e32 v42, v127, v49
	v_dot8c_i32_i4_e32 v43, v127, v47
	v_dot8c_i32_i4_e32 v44, v129, v49
	v_dot8c_i32_i4_e32 v45, v129, v47
	v_and_b32_e32 v78, 0xffff, v22
	v_lshrrev_b32_e32 v79, 16, v22
	v_lshl_add_u32 v78, v78, 7, v150
	v_lshl_add_u32 v79, v79, 7, v151
	s_mov_b32 m0, s98
	s_add_i32 s43, s98, 0x400
	global_load_lds_dwordx4 v78, s[50:51]
	s_mov_b32 m0, s43
	s_nop 0
	global_load_lds_dwordx4 v79, s[50:51]
	s_waitcnt vmcnt(8)
	v_add_u32_e32 v54, s76, v59
	v_add_u32_e32 v55, s76, v60
	v_add_u32_e32 v56, s76, v61
	v_add_u32_e32 v57, s76, v62
	ds_read_b64_tr_b4 v[46:47], v160
	ds_read_b64_tr_b4 v[48:49], v160 offset:1024
	ds_read_b64_tr_b4 v[122:123], v54
	ds_read_b64_tr_b4 v[124:125], v55
	ds_read_b64_tr_b4 v[126:127], v56
	ds_read_b64_tr_b4 v[128:129], v57
	s_waitcnt lgkmcnt(6)
	v_dot8c_i32_i4_e32 v38, v130, v52
	v_dot8c_i32_i4_e32 v39, v130, v50
	v_dot8c_i32_i4_e32 v40, v132, v52
	v_dot8c_i32_i4_e32 v41, v132, v50
	v_dot8c_i32_i4_e32 v42, v134, v52
	v_dot8c_i32_i4_e32 v43, v134, v50
	v_dot8c_i32_i4_e32 v44, v136, v52
	v_dot8c_i32_i4_e32 v45, v136, v50
	v_dot8c_i32_i4_e32 v38, v131, v53
	v_dot8c_i32_i4_e32 v39, v131, v51
	v_dot8c_i32_i4_e32 v40, v133, v53
	v_dot8c_i32_i4_e32 v41, v133, v51
	v_dot8c_i32_i4_e32 v42, v135, v53
	v_dot8c_i32_i4_e32 v43, v135, v51
	v_dot8c_i32_i4_e32 v44, v137, v53
	v_dot8c_i32_i4_e32 v45, v137, v51
	s_nop 3
	s_waitcnt lgkmcnt(15)
	v_lshlrev_b32_e32 v38, 5, v38
	v_lshlrev_b32_e32 v39, 1, v39
	v_add3_u32 v38, v39, v229, v38
	v_cvt_f32_i32_e32 v38, v38
	v_mul_f32_e32 v38, v228, v38
	v_lshlrev_b32_e32 v40, 5, v40
	v_lshlrev_b32_e32 v41, 1, v41
	v_add3_u32 v40, v41, v229, v40
	v_cvt_f32_i32_e32 v40, v40
	v_mul_f32_e32 v40, v228, v40
	v_lshlrev_b32_e32 v42, 5, v42
	v_lshlrev_b32_e32 v43, 1, v43
	v_add3_u32 v42, v43, v229, v42
	v_cvt_f32_i32_e32 v42, v42
	v_mul_f32_e32 v42, v228, v42
	v_lshlrev_b32_e32 v44, 5, v44
	v_lshlrev_b32_e32 v45, 1, v45
	v_add3_u32 v44, v45, v229, v44
	v_cvt_f32_i32_e32 v44, v44
	v_mul_f32_e32 v44, v228, v44
	v_cvt_pk_bf16_f32 v188, v38, v40
	v_cvt_pk_bf16_f32 v189, v42, v44
	ds_read_b128 v[252:255], v156
	s_add_i32 s44, s40, 0
	s_ashr_i32 s45, s44, 31
	s_lshl_b64 s[44:45], s[44:45], 12
	v_lshl_add_u64 v[80:81], v[36:37], 0, s[44:45]
	s_waitcnt lgkmcnt(0)
; __device__ __forceinline__ void peer_v_tokens(int j, const LAS unsigned short* EL, const LAS unsigned char* AL  , const LAS float* ASC  , const LAS int* SAL  , ...
;     ...
;         { const LAS v4u* ep = (const LAS v4u*)(EL + tl * 128 + 16 * g); const v4u e0 = ep[0], e1 = ep[1];
;           E[0] = e0.x; E[1] = e0.y; E[2] = e0.z; E[3] = e0.w; E[4] = e1.x; E[5] = e1.y; E[6] = e1.z; E[7] = e1.w; }
;         uint2 hv[4]; float4 gv[4];
;         { unsigned ho = (unsigned)t * (D / 4) + (unsigned)lane; asm volatile("" : "+v"(ho)); const uint2* hp = (const uint2*)HB + ho; const float4* gp = (const float4*)fng + lane;
; #pragma unroll
;           for (int jq = 0; jq < 4; ++jq) { hv[jq] = hp[64 * jq]; gv[jq] = gp[64 * jq]; } }
;         VDMA(0, 0); VDMA(1, 1);
; #pragma unroll
;         for (int m = 0; m < 2; ++m) {
;             const int idx = lane + 64 * m, tau = idx >> 4, sr = idx & 15, k = 16 * (sr & 7) + 2 * tau + (sr >> 3);
;             const int aq = (int)*(const LAS signed char*)(AL + tl * 128 + k); const int tq = aq + 8;
;             const unsigned lo = (((unsigned)tq & 15u) ^ 8u) * 0x11111111u, hi = ((unsigned)(tq >> 4) & 15u) * 0x11111111u;
;     ...
;         {
;             float4 v[4]; float ss = 0.f;
; #pragma unroll
;             for (int jq = 0; jq < 4; ++jq) { typedef unsigned u2v __attribute__((ext_vector_type(2))); const u2v pw = *(const LAS u2v*)(STASH + 4 * lane + 256 * jq); const uint2 hw = hv[jq];
;                 v[jq] = make_float4(__uint_as_float(hw.x << 16) + __uint_as_float(pw.x << 16), __uint_as_float(hw.x & 0xffff0000u) + __uint_as_float(pw.x & 0xffff0000u),
;                                     __uint_as_float(hw.y << 16) + __uint_as_float(pw.y << 16), __uint_as_float(hw.y & 0xffff0000u) + __uint_as_float(pw.y & 0xffff0000u));
;                 ss += v[jq].x * v[jq].x + v[jq].y * v[jq].y + v[jq].z * v[jq].z + v[jq].w * v[jq].w; }
;             ss = wave_sum(ss);
;             const float r3 = rsqrtf(ss * (1.f / D) + EPS);
;             float4* op = (float4*)(outp + (size_t)t * D) + lane;
; #pragma unroll
;             for (int jq = 0; jq < 4; ++jq) { typedef float f4v __attribute__((ext_vector_type(4))); f4v o4; o4.x = v[jq].x * r3 * gv[jq].x; o4.y = v[jq].y * r3 * gv[jq].y; o4.z = v[jq].z * r3 * gv[jq].z; o4.w = v[jq].w * r3 * gv[jq].w;
;                 __builtin_nontemporal_store(o4, (f4v*)op + 64 * jq); }
	v_mul_f32_e32 v218, v218, v252
	v_mul_f32_e32 v219, v219, v253
	v_mul_f32_e32 v220, v220, v254
	v_mul_f32_e32 v221, v221, v255
	global_store_dwordx4 v[80:81], v[218:221], off offset:2048 nt
	v_add_u32_e32 v147, 8, v140
	v_and_b32_e32 v146, 15, v147
	v_xor_b32_e32 v146, 8, v146
	v_bfe_u32 v148, v147, 4, 4
	v_mul_lo_u32 v146, v146, s92
	v_mul_lo_u32 v148, v148, s92
	v_mov_b32_e32 v147, v146
	v_mov_b32_e32 v149, v148
	ds_write2st64_b64 v77, v[146:147], v[148:149] offset1:2
	v_add_u32_e32 v138, 0xc00, v74
	ds_read_u8 v139, v138
	v_add_u32_e32 v141, 0xc00, v73
	ds_read_u8 v140, v141
	s_add_i32 s43, s67, 64
	v_mov_b32_e32 v138, s43
	ds_read2st64_b32 v[228:229], v138 offset1:1
	ds_read_b128 v[26:29], v227 offset:6144
	ds_read_b128 v[30:33], v227 offset:6160
	v_mov_b32_e32 v38, 0
	v_mov_b32_e32 v39, 0
	v_mov_b32_e32 v40, 0
	v_mov_b32_e32 v41, 0
	v_mov_b32_e32 v42, 0
	v_mov_b32_e32 v43, 0
	v_mov_b32_e32 v44, 0
	v_mov_b32_e32 v45, 0
	v_and_b32_e32 v78, 0xffff, v23
	v_lshrrev_b32_e32 v79, 16, v23
	v_lshl_add_u32 v78, v78, 7, v150
	v_lshl_add_u32 v79, v79, 7, v151
	s_mov_b32 m0, s99
	s_add_i32 s43, s99, 0x400
	global_load_lds_dwordx4 v78, s[50:51]
	s_mov_b32 m0, s43
	s_nop 0
	global_load_lds_dwordx4 v79, s[50:51]
	s_waitcnt vmcnt(9)
	v_add_u32_e32 v54, s77, v59
	v_add_u32_e32 v55, s77, v60
	v_add_u32_e32 v56, s77, v61
	v_add_u32_e32 v57, s77, v62
	ds_read_b64_tr_b4 v[50:51], v160 offset:128
	ds_read_b64_tr_b4 v[52:53], v160 offset:1152
	ds_read_b64_tr_b4 v[130:131], v54
	ds_read_b64_tr_b4 v[132:133], v55
	ds_read_b64_tr_b4 v[134:135], v56
	ds_read_b64_tr_b4 v[136:137], v57
	s_waitcnt lgkmcnt(13)
	s_waitcnt vmcnt(36) lgkmcnt(15)
	v_lshlrev_b32_e32 v236, 16, v194
	v_and_b32_e32 v237, 0xffff0000, v194
	v_lshlrev_b32_e32 v142, 16, v202
	v_and_b32_e32 v143, 0xffff0000, v202
	v_add_f32_e32 v236, v236, v142
	v_add_f32_e32 v237, v237, v143
	v_lshlrev_b32_e32 v238, 16, v195
	v_and_b32_e32 v239, 0xffff0000, v195
	v_lshlrev_b32_e32 v142, 16, v203
	v_and_b32_e32 v143, 0xffff0000, v203
	v_add_f32_e32 v238, v238, v142
	v_add_f32_e32 v239, v239, v143
	v_lshlrev_b32_e32 v240, 16, v196
	v_and_b32_e32 v241, 0xffff0000, v196
	v_lshlrev_b32_e32 v142, 16, v204
	v_and_b32_e32 v143, 0xffff0000, v204
	v_add_f32_e32 v240, v240, v142
	v_add_f32_e32 v241, v241, v143
	v_lshlrev_b32_e32 v242, 16, v197
	v_and_b32_e32 v243, 0xffff0000, v197
	v_lshlrev_b32_e32 v142, 16, v205
	v_and_b32_e32 v143, 0xffff0000, v205
	v_add_f32_e32 v242, v242, v142
	v_add_f32_e32 v243, v243, v143
	v_lshlrev_b32_e32 v244, 16, v198
	v_and_b32_e32 v245, 0xffff0000, v198
	v_lshlrev_b32_e32 v142, 16, v206
	v_and_b32_e32 v143, 0xffff0000, v206
	v_add_f32_e32 v244, v244, v142
	v_add_f32_e32 v245, v245, v143
	v_lshlrev_b32_e32 v246, 16, v199
	v_and_b32_e32 v247, 0xffff0000, v199
	v_lshlrev_b32_e32 v142, 16, v207
	v_and_b32_e32 v143, 0xffff0000, v207
	v_add_f32_e32 v246, v246, v142
	v_add_f32_e32 v247, v247, v143
	v_lshlrev_b32_e32 v248, 16, v200
	v_and_b32_e32 v249, 0xffff0000, v200
	v_lshlrev_b32_e32 v142, 16, v208
	v_and_b32_e32 v143, 0xffff0000, v208
	v_add_f32_e32 v248, v248, v142
	v_add_f32_e32 v249, v249, v143
	v_lshlrev_b32_e32 v250, 16, v201
	v_and_b32_e32 v251, 0xffff0000, v201
	v_lshlrev_b32_e32 v142, 16, v209
	v_and_b32_e32 v143, 0xffff0000, v209
	v_add_f32_e32 v250, v250, v142
	v_add_f32_e32 v251, v251, v143
	v_mov_b32_e32 v144, 0
	v_mul_f32_e32 v145, v236, v236
	v_fmac_f32_e32 v145, v237, v237
	v_fmac_f32_e32 v145, v238, v238
	v_fmac_f32_e32 v145, v239, v239
	v_add_f32_e32 v144, v144, v145
	v_mul_f32_e32 v145, v240, v240
	v_fmac_f32_e32 v145, v241, v241
	v_fmac_f32_e32 v145, v242, v242
	v_fmac_f32_e32 v145, v243, v243
	v_add_f32_e32 v144, v144, v145
	v_mul_f32_e32 v145, v244, v244
	v_fmac_f32_e32 v145, v245, v245
	v_fmac_f32_e32 v145, v246, v246
	v_fmac_f32_e32 v145, v247, v247
	v_add_f32_e32 v144, v144, v145
	v_mul_f32_e32 v145, v248, v248
	v_fmac_f32_e32 v145, v249, v249
	v_fmac_f32_e32 v145, v250, v250
	v_fmac_f32_e32 v145, v251, v251
	v_add_f32_e32 v144, v144, v145
	s_nop 1
	v_add_f32_dpp v144, v144, v144 quad_perm:[1,0,3,2] row_mask:0xf bank_mask:0xf bound_ctrl:1
	s_nop 1
	v_add_f32_dpp v144, v144, v144 quad_perm:[2,3,0,1] row_mask:0xf bank_mask:0xf bound_ctrl:1
	s_nop 1
	v_add_f32_dpp v144, v144, v144 row_half_mirror row_mask:0xf bank_mask:0xf bound_ctrl:1
	s_nop 1
	v_add_f32_dpp v144, v144, v144 row_mirror row_mask:0xf bank_mask:0xf bound_ctrl:1
	s_nop 1
	v_readlane_b32 s10, v144, 0
	v_readlane_b32 s11, v144, 16
	v_readlane_b32 s14, v144, 32
	v_readlane_b32 s15, v144, 48
	s_nop 3
	v_mov_b32_e32 v144, s11
	v_mov_b32_e32 v145, s15
	v_add_f32_e32 v144, s10, v144
	v_add_f32_e32 v145, s14, v145
	v_add_f32_e32 v144, v144, v145
	v_fmamk_f32 v144, v144, 0x3a800000, v111
	v_rsq_f32_e32 v144, v144
	s_nop 0
	v_mul_f32_e32 v236, v236, v144
	v_mul_f32_e32 v237, v237, v144
	v_mul_f32_e32 v238, v238, v144
	v_mul_f32_e32 v239, v239, v144
	v_mul_f32_e32 v240, v240, v144
	v_mul_f32_e32 v241, v241, v144
	v_mul_f32_e32 v242, v242, v144
	v_mul_f32_e32 v243, v243, v144
	v_mul_f32_e32 v244, v244, v144
	v_mul_f32_e32 v245, v245, v144
	v_mul_f32_e32 v246, v246, v144
	v_mul_f32_e32 v247, v247, v144
	v_mul_f32_e32 v248, v248, v144
	v_mul_f32_e32 v249, v249, v144
	v_mul_f32_e32 v250, v250, v144
	v_mul_f32_e32 v251, v251, v144
	v_dot8c_i32_i4_e32 v38, v122, v48
	v_dot8c_i32_i4_e32 v39, v122, v46
	v_dot8c_i32_i4_e32 v40, v124, v48
	v_dot8c_i32_i4_e32 v41, v124, v46
	v_dot8c_i32_i4_e32 v42, v126, v48
	v_dot8c_i32_i4_e32 v43, v126, v46
	v_dot8c_i32_i4_e32 v44, v128, v48
	v_dot8c_i32_i4_e32 v45, v128, v46
	v_dot8c_i32_i4_e32 v38, v123, v49
	v_dot8c_i32_i4_e32 v39, v123, v47
	v_dot8c_i32_i4_e32 v40, v125, v49
	v_dot8c_i32_i4_e32 v41, v125, v47
	v_dot8c_i32_i4_e32 v42, v127, v49
	v_dot8c_i32_i4_e32 v43, v127, v47
	v_dot8c_i32_i4_e32 v44, v129, v49
	v_dot8c_i32_i4_e32 v45, v129, v47
	v_and_b32_e32 v78, 0xffff, v24
	v_lshrrev_b32_e32 v79, 16, v24
	v_lshl_add_u32 v78, v78, 7, v150
	v_lshl_add_u32 v79, v79, 7, v151
	s_mov_b32 m0, s76
	s_add_i32 s43, s76, 0x400
	global_load_lds_dwordx4 v78, s[50:51]
	s_mov_b32 m0, s43
	s_nop 0
	global_load_lds_dwordx4 v79, s[50:51]
	s_waitcnt vmcnt(9)
; #define LAS __attribute__((address_space(3)))
; #define TR4(p_) __builtin_amdgcn_ds_read_tr4_b64_v2i32((LAS v2i*)(p_))
; #define VDMA(st_, k_) do { _Pragma("unroll") for (int i_ = 0; i_ < 4; ++i_) { \
;         const unsigned off_ = (unsigned)((st_) >> 2) * (16384u * 128u) + (PE_ID(E, 4 * ((st_) & 3) + i_) << 7) + ((i_ & 1) ? cx1 : cx0); \
;         __builtin_amdgcn_global_load_lds((const unsigned*)(V4 + off_), (LAS unsigned*)(ldsb + BUF[k_] + 1024 * i_), 16, 0, 0); } } while (0)
; __device__ __forceinline__ void peer_v_tokens(int j, const LAS unsigned short* EL, const LAS unsigned char* AL  , const LAS float* ASC  , const LAS int* SAL  , ...
;     ...
;             const int aq = (int)*(const LAS signed char*)(AL + tl * 128 + k); const int tq = aq + 8;
;             const unsigned lo = (((unsigned)tq & 15u) ^ 8u) * 0x11111111u, hi = ((unsigned)(tq >> 4) & 15u) * 0x11111111u;
;             typedef unsigned u2v __attribute__((ext_vector_type(2)));
;             u2v l2; l2.x = lo; l2.y = lo; u2v h2; h2.x = hi; h2.y = hi;
;             *(LAS u2v*)(ATL + 8 * idx) = l2; *(LAS u2v*)(ATL + 1024 + 8 * idx) = h2;
;     ...
;         for (int st = 0; st < 16; ++st) {
;             const int p = st >> 2, q = st & 3;
;             if (st < 14) VDMA(st + 2, (st + 2) % 3);
;             if (st < 14) asm volatile("s_waitcnt vmcnt(8)" ::: "memory");
;             else if (st == 14) asm volatile("s_waitcnt vmcnt(4)" ::: "memory");
;             else asm volatile("s_waitcnt vmcnt(0)" ::: "memory");
;             if (q == 0) {
; #pragma unroll
;                 for (int r = 0; r < 4; ++r) { accH[r] = 0; accL[r] = 0; } }
; #pragma unroll
;             for (int tp = 0; tp < 2; ++tp) {
;                 const v2i ao = TR4(ATL + (2 * q + tp) * 128 + 8 * s16), ah = TR4(ATL + 1024 + (2 * q + tp) * 128 + 8 * s16);
; #pragma unroll
;                 for (int r = 0; r < 4; ++r) {
;                     const v2i d = TR4(ldsb + BUF[st % 3] + 2048 * tp + roff[r]);
;                     accH[r] = __builtin_amdgcn_sdot8(d.x, ah.x, accH[r], false); accH[r] = __builtin_amdgcn_sdot8(d.y, ah.y, accH[r], false);
;                     accL[r] = __builtin_amdgcn_sdot8(d.x, ao.x, accL[r], false); accL[r] = __builtin_amdgcn_sdot8(d.y, ao.y, accL[r], false);
;                 }
	v_add_u32_e32 v54, s78, v59
	v_add_u32_e32 v55, s78, v60
	v_add_u32_e32 v56, s78, v61
	v_add_u32_e32 v57, s78, v62
	ds_read_b64_tr_b4 v[46:47], v160 offset:256
	ds_read_b64_tr_b4 v[48:49], v160 offset:1280
	ds_read_b64_tr_b4 v[122:123], v54
	ds_read_b64_tr_b4 v[124:125], v55
	ds_read_b64_tr_b4 v[126:127], v56
	ds_read_b64_tr_b4 v[128:129], v57
	s_waitcnt lgkmcnt(6)
	v_dot8c_i32_i4_e32 v38, v130, v52
	v_dot8c_i32_i4_e32 v39, v130, v50
	v_dot8c_i32_i4_e32 v40, v132, v52
	v_dot8c_i32_i4_e32 v41, v132, v50
	v_dot8c_i32_i4_e32 v42, v134, v52
	v_dot8c_i32_i4_e32 v43, v134, v50
	v_dot8c_i32_i4_e32 v44, v136, v52
	v_dot8c_i32_i4_e32 v45, v136, v50
	v_dot8c_i32_i4_e32 v38, v131, v53
	v_dot8c_i32_i4_e32 v39, v131, v51
	v_dot8c_i32_i4_e32 v40, v133, v53
	v_dot8c_i32_i4_e32 v41, v133, v51
	v_dot8c_i32_i4_e32 v42, v135, v53
	v_dot8c_i32_i4_e32 v43, v135, v51
	v_dot8c_i32_i4_e32 v44, v137, v53
	v_dot8c_i32_i4_e32 v45, v137, v51
	v_and_b32_e32 v78, 0xffff, v25
	v_lshrrev_b32_e32 v79, 16, v25
	v_lshl_add_u32 v78, v78, 7, v150
	v_lshl_add_u32 v79, v79, 7, v151
	s_mov_b32 m0, s77
	s_add_i32 s43, s77, 0x400
	global_load_lds_dwordx4 v78, s[50:51]
	s_mov_b32 m0, s43
	s_nop 0
	global_load_lds_dwordx4 v79, s[50:51]
	s_waitcnt vmcnt(9)
	v_add_u32_e32 v54, s79, v59
	v_add_u32_e32 v55, s79, v60
	v_add_u32_e32 v56, s79, v61
	v_add_u32_e32 v57, s79, v62
	ds_read_b64_tr_b4 v[50:51], v160 offset:384
	ds_read_b64_tr_b4 v[52:53], v160 offset:1408
	ds_read_b64_tr_b4 v[130:131], v54
	ds_read_b64_tr_b4 v[132:133], v55
	ds_read_b64_tr_b4 v[134:135], v56
	ds_read_b64_tr_b4 v[136:137], v57
	s_waitcnt lgkmcnt(6)
	v_dot8c_i32_i4_e32 v38, v122, v48
	v_dot8c_i32_i4_e32 v39, v122, v46
	v_dot8c_i32_i4_e32 v40, v124, v48
	v_dot8c_i32_i4_e32 v41, v124, v46
	v_dot8c_i32_i4_e32 v42, v126, v48
	v_dot8c_i32_i4_e32 v43, v126, v46
	v_dot8c_i32_i4_e32 v44, v128, v48
	v_dot8c_i32_i4_e32 v45, v128, v46
	v_dot8c_i32_i4_e32 v38, v123, v49
	v_dot8c_i32_i4_e32 v39, v123, v47
	v_dot8c_i32_i4_e32 v40, v125, v49
	v_dot8c_i32_i4_e32 v41, v125, v47
	v_dot8c_i32_i4_e32 v42, v127, v49
	v_dot8c_i32_i4_e32 v43, v127, v47
	v_dot8c_i32_i4_e32 v44, v129, v49
	v_dot8c_i32_i4_e32 v45, v129, v47
	s_waitcnt lgkmcnt(15)
	v_and_b32_e32 v78, 0xffff, v26
	v_lshrrev_b32_e32 v79, 16, v26
	v_lshl_add_u32 v78, v78, 7, v150
	v_lshl_add_u32 v79, v79, 7, v151
	s_mov_b32 m0, s78
	s_add_i32 s43, s78, 0x400
	global_load_lds_dwordx4 v78, s[50:51]
	s_mov_b32 m0, s43
	s_nop 0
	global_load_lds_dwordx4 v79, s[50:51]
	s_waitcnt vmcnt(9)
	v_add_u32_e32 v54, s98, v59
	v_add_u32_e32 v55, s98, v60
	v_add_u32_e32 v56, s98, v61
	v_add_u32_e32 v57, s98, v62
	ds_read_b64_tr_b4 v[46:47], v160 offset:512
	ds_read_b64_tr_b4 v[48:49], v160 offset:1536
	ds_read_b64_tr_b4 v[122:123], v54
	ds_read_b64_tr_b4 v[124:125], v55
	ds_read_b64_tr_b4 v[126:127], v56
	ds_read_b64_tr_b4 v[128:129], v57
	s_waitcnt lgkmcnt(6)
	v_dot8c_i32_i4_e32 v38, v130, v52
	v_dot8c_i32_i4_e32 v39, v130, v50
	v_dot8c_i32_i4_e32 v40, v132, v52
	v_dot8c_i32_i4_e32 v41, v132, v50
	v_dot8c_i32_i4_e32 v42, v134, v52
	v_dot8c_i32_i4_e32 v43, v134, v50
	v_dot8c_i32_i4_e32 v44, v136, v52
	v_dot8c_i32_i4_e32 v45, v136, v50
	v_dot8c_i32_i4_e32 v38, v131, v53
	v_dot8c_i32_i4_e32 v39, v131, v51
	v_dot8c_i32_i4_e32 v40, v133, v53
	v_dot8c_i32_i4_e32 v41, v133, v51
	v_dot8c_i32_i4_e32 v42, v135, v53
	v_dot8c_i32_i4_e32 v43, v135, v51
	v_dot8c_i32_i4_e32 v44, v137, v53
	v_dot8c_i32_i4_e32 v45, v137, v51
	v_and_b32_e32 v78, 0xffff, v27
	v_lshrrev_b32_e32 v79, 16, v27
	v_lshl_add_u32 v78, v78, 7, v150
	v_lshl_add_u32 v79, v79, 7, v151
	s_mov_b32 m0, s79
	s_add_i32 s43, s79, 0x400
	global_load_lds_dwordx4 v78, s[50:51]
	s_mov_b32 m0, s43
	s_nop 0
	global_load_lds_dwordx4 v79, s[50:51]
	s_waitcnt vmcnt(8)
	v_add_u32_e32 v54, s99, v59
	v_add_u32_e32 v55, s99, v60
	v_add_u32_e32 v56, s99, v61
	v_add_u32_e32 v57, s99, v62
	ds_read_b64_tr_b4 v[50:51], v160 offset:640
	ds_read_b64_tr_b4 v[52:53], v160 offset:1664
	ds_read_b64_tr_b4 v[130:131], v54
	ds_read_b64_tr_b4 v[132:133], v55
	ds_read_b64_tr_b4 v[134:135], v56
	ds_read_b64_tr_b4 v[136:137], v57
	s_waitcnt lgkmcnt(6)
	v_dot8c_i32_i4_e32 v38, v122, v48
	v_dot8c_i32_i4_e32 v39, v122, v46
	v_dot8c_i32_i4_e32 v40, v124, v48
	v_dot8c_i32_i4_e32 v41, v124, v46
	v_dot8c_i32_i4_e32 v42, v126, v48
	v_dot8c_i32_i4_e32 v43, v126, v46
	v_dot8c_i32_i4_e32 v44, v128, v48
	v_dot8c_i32_i4_e32 v45, v128, v46
	v_dot8c_i32_i4_e32 v38, v123, v49
	v_dot8c_i32_i4_e32 v39, v123, v47
	v_dot8c_i32_i4_e32 v40, v125, v49
	v_dot8c_i32_i4_e32 v41, v125, v47
	v_dot8c_i32_i4_e32 v42, v127, v49
	v_dot8c_i32_i4_e32 v43, v127, v47
	v_dot8c_i32_i4_e32 v44, v129, v49
	v_dot8c_i32_i4_e32 v45, v129, v47
	s_waitcnt lgkmcnt(15)
	v_add_u32_e32 v143, 8, v139
	v_and_b32_e32 v142, 15, v143
	v_xor_b32_e32 v142, 8, v142
	v_bfe_u32 v144, v143, 4, 4
	v_mul_lo_u32 v142, v142, s92
	v_mul_lo_u32 v144, v144, s92
	v_mov_b32_e32 v143, v142
	v_mov_b32_e32 v145, v144
	ds_write2st64_b64 v159, v[142:143], v[144:145] offset1:2
	v_and_b32_e32 v78, 0xffff, v28
	v_lshrrev_b32_e32 v79, 16, v28
	v_lshl_add_u32 v78, v78, 7, v150
	v_lshl_add_u32 v79, v79, 7, v151
	s_mov_b32 m0, s98
	s_add_i32 s43, s98, 0x400
	global_load_lds_dwordx4 v78, s[50:51]
	s_mov_b32 m0, s43
	s_nop 0
	global_load_lds_dwordx4 v79, s[50:51]
	s_waitcnt vmcnt(8)
	v_add_u32_e32 v54, s76, v59
	v_add_u32_e32 v55, s76, v60
	v_add_u32_e32 v56, s76, v61
	v_add_u32_e32 v57, s76, v62
	ds_read_b64_tr_b4 v[46:47], v160 offset:768
	ds_read_b64_tr_b4 v[48:49], v160 offset:1792
	ds_read_b64_tr_b4 v[122:123], v54
	ds_read_b64_tr_b4 v[124:125], v55
	ds_read_b64_tr_b4 v[126:127], v56
	ds_read_b64_tr_b4 v[128:129], v57
	s_waitcnt lgkmcnt(7)
; __device__ __forceinline__ bf16 f2bf(float f) { return (bf16)f2bfu(f); }
; #define TR4(p_) __builtin_amdgcn_ds_read_tr4_b64_v2i32((LAS v2i*)(p_))
; __device__ __forceinline__ void peer_v_tokens(int j, const LAS unsigned short* EL, const LAS unsigned char* AL  , const LAS float* ASC  , const LAS int* SAL  , ...
;     ...
;         for (int st = 0; st < 16; ++st) {
;             const int p = st >> 2, q = st & 3;
;             if (st < 14) VDMA(st + 2, (st + 2) % 3);
;             if (st < 14) asm volatile("s_waitcnt vmcnt(8)" ::: "memory");
;             else if (st == 14) asm volatile("s_waitcnt vmcnt(4)" ::: "memory");
;             else asm volatile("s_waitcnt vmcnt(0)" ::: "memory");
;             if (q == 0) {
; #pragma unroll
;                 for (int r = 0; r < 4; ++r) { accH[r] = 0; accL[r] = 0; } }
; #pragma unroll
;             for (int tp = 0; tp < 2; ++tp) {
;                 const v2i ao = TR4(ATL + (2 * q + tp) * 128 + 8 * s16), ah = TR4(ATL + 1024 + (2 * q + tp) * 128 + 8 * s16);
; #pragma unroll
;                 for (int r = 0; r < 4; ++r) {
;                     const v2i d = TR4(ldsb + BUF[st % 3] + 2048 * tp + roff[r]);
;                     accH[r] = __builtin_amdgcn_sdot8(d.x, ah.x, accH[r], false); accH[r] = __builtin_amdgcn_sdot8(d.y, ah.y, accH[r], false);
;                     accL[r] = __builtin_amdgcn_sdot8(d.x, ao.x, accL[r], false); accL[r] = __builtin_amdgcn_sdot8(d.y, ao.y, accL[r], false);
;                 }
;             }
;             asm volatile("s_waitcnt lgkmcnt(0)" ::: "memory");
;             if (q == 3) {
; #pragma unroll
;                 for (int r = 0; r < 4; ++r) STASH[256 * p + 16 * (grp + 4 * r) + pc] = f2bf(asc * (float)(2 * ((accH[r] << 4) + accL[r]) + sa));
;             }
;     ...
;             float4* op = (float4*)(outp + (size_t)t * D) + lane;
; #pragma unroll
;             for (int jq = 0; jq < 4; ++jq) { typedef float f4v __attribute__((ext_vector_type(4))); f4v o4; o4.x = v[jq].x * r3 * gv[jq].x; o4.y = v[jq].y * r3 * gv[jq].y; o4.z = v[jq].z * r3 * gv[jq].z; o4.w = v[jq].w * r3 * gv[jq].w;
;                 __builtin_nontemporal_store(o4, (f4v*)op + 64 * jq); }
	v_dot8c_i32_i4_e32 v38, v130, v52
	v_dot8c_i32_i4_e32 v39, v130, v50
	v_dot8c_i32_i4_e32 v40, v132, v52
	v_dot8c_i32_i4_e32 v41, v132, v50
	v_dot8c_i32_i4_e32 v42, v134, v52
	v_dot8c_i32_i4_e32 v43, v134, v50
	v_dot8c_i32_i4_e32 v44, v136, v52
	v_dot8c_i32_i4_e32 v45, v136, v50
	v_dot8c_i32_i4_e32 v38, v131, v53
	v_dot8c_i32_i4_e32 v39, v131, v51
	v_dot8c_i32_i4_e32 v40, v133, v53
	v_dot8c_i32_i4_e32 v41, v133, v51
	v_dot8c_i32_i4_e32 v42, v135, v53
	v_dot8c_i32_i4_e32 v43, v135, v51
	v_dot8c_i32_i4_e32 v44, v137, v53
	v_dot8c_i32_i4_e32 v45, v137, v51
	v_and_b32_e32 v78, 0xffff, v29
	v_lshrrev_b32_e32 v79, 16, v29
	v_lshl_add_u32 v78, v78, 7, v150
	v_lshl_add_u32 v79, v79, 7, v151
	s_mov_b32 m0, s99
	s_add_i32 s43, s99, 0x400
	global_load_lds_dwordx4 v78, s[50:51]
	s_mov_b32 m0, s43
	s_nop 0
	global_load_lds_dwordx4 v79, s[50:51]
	s_waitcnt vmcnt(8)
	v_add_u32_e32 v54, s77, v59
	v_add_u32_e32 v55, s77, v60
	v_add_u32_e32 v56, s77, v61
	v_add_u32_e32 v57, s77, v62
	ds_read_b64_tr_b4 v[50:51], v160 offset:896
	ds_read_b64_tr_b4 v[52:53], v160 offset:1920
	ds_read_b64_tr_b4 v[130:131], v54
	ds_read_b64_tr_b4 v[132:133], v55
	ds_read_b64_tr_b4 v[134:135], v56
	ds_read_b64_tr_b4 v[136:137], v57
	s_waitcnt lgkmcnt(6)
	v_dot8c_i32_i4_e32 v38, v122, v48
	v_dot8c_i32_i4_e32 v39, v122, v46
	v_dot8c_i32_i4_e32 v40, v124, v48
	v_dot8c_i32_i4_e32 v41, v124, v46
	v_dot8c_i32_i4_e32 v42, v126, v48
	v_dot8c_i32_i4_e32 v43, v126, v46
	v_dot8c_i32_i4_e32 v44, v128, v48
	v_dot8c_i32_i4_e32 v45, v128, v46
	v_dot8c_i32_i4_e32 v38, v123, v49
	v_dot8c_i32_i4_e32 v39, v123, v47
	v_dot8c_i32_i4_e32 v40, v125, v49
	v_dot8c_i32_i4_e32 v41, v125, v47
	v_dot8c_i32_i4_e32 v42, v127, v49
	v_dot8c_i32_i4_e32 v43, v127, v47
	v_dot8c_i32_i4_e32 v44, v129, v49
	v_dot8c_i32_i4_e32 v45, v129, v47
	v_and_b32_e32 v78, 0xffff, v30
	v_lshrrev_b32_e32 v79, 16, v30
	v_lshl_add_u32 v78, v78, 7, v150
	v_lshl_add_u32 v79, v79, 7, v151
	s_mov_b32 m0, s76
	s_add_i32 s43, s76, 0x400
	global_load_lds_dwordx4 v78, s[50:51]
	s_mov_b32 m0, s43
	s_nop 0
	global_load_lds_dwordx4 v79, s[50:51]
	s_waitcnt vmcnt(8)
	v_add_u32_e32 v54, s78, v59
	v_add_u32_e32 v55, s78, v60
	v_add_u32_e32 v56, s78, v61
	v_add_u32_e32 v57, s78, v62
	ds_read_b64_tr_b4 v[46:47], v160
	ds_read_b64_tr_b4 v[48:49], v160 offset:1024
	ds_read_b64_tr_b4 v[122:123], v54
	ds_read_b64_tr_b4 v[124:125], v55
	ds_read_b64_tr_b4 v[126:127], v56
	ds_read_b64_tr_b4 v[128:129], v57
	s_waitcnt lgkmcnt(6)
	v_dot8c_i32_i4_e32 v38, v130, v52
	v_dot8c_i32_i4_e32 v39, v130, v50
	v_dot8c_i32_i4_e32 v40, v132, v52
	v_dot8c_i32_i4_e32 v41, v132, v50
	v_dot8c_i32_i4_e32 v42, v134, v52
	v_dot8c_i32_i4_e32 v43, v134, v50
	v_dot8c_i32_i4_e32 v44, v136, v52
	v_dot8c_i32_i4_e32 v45, v136, v50
	v_dot8c_i32_i4_e32 v38, v131, v53
	v_dot8c_i32_i4_e32 v39, v131, v51
	v_dot8c_i32_i4_e32 v40, v133, v53
	v_dot8c_i32_i4_e32 v41, v133, v51
	v_dot8c_i32_i4_e32 v42, v135, v53
	v_dot8c_i32_i4_e32 v43, v135, v51
	v_dot8c_i32_i4_e32 v44, v137, v53
	v_dot8c_i32_i4_e32 v45, v137, v51
	s_nop 3
	s_waitcnt lgkmcnt(15)
	v_lshlrev_b32_e32 v38, 5, v38
	v_lshlrev_b32_e32 v39, 1, v39
	v_add3_u32 v38, v39, v229, v38
	v_cvt_f32_i32_e32 v38, v38
	v_mul_f32_e32 v38, v228, v38
	v_lshlrev_b32_e32 v40, 5, v40
	v_lshlrev_b32_e32 v41, 1, v41
	v_add3_u32 v40, v41, v229, v40
	v_cvt_f32_i32_e32 v40, v40
	v_mul_f32_e32 v40, v228, v40
	v_lshlrev_b32_e32 v42, 5, v42
	v_lshlrev_b32_e32 v43, 1, v43
	v_add3_u32 v42, v43, v229, v42
	v_cvt_f32_i32_e32 v42, v42
	v_mul_f32_e32 v42, v228, v42
	v_lshlrev_b32_e32 v44, 5, v44
	v_lshlrev_b32_e32 v45, 1, v45
	v_add3_u32 v44, v45, v229, v44
	v_cvt_f32_i32_e32 v44, v44
	v_mul_f32_e32 v44, v228, v44
	v_cvt_pk_bf16_f32 v182, v38, v40
	v_cvt_pk_bf16_f32 v183, v42, v44
	ds_read_b128 v[252:255], v156 offset:1024
	s_add_i32 s44, s40, 0
	s_ashr_i32 s45, s44, 31
	s_lshl_b64 s[44:45], s[44:45], 12
	v_lshl_add_u64 v[80:81], v[36:37], 0, s[44:45]
	s_waitcnt lgkmcnt(0)
	v_mul_f32_e32 v222, v222, v252
	v_mul_f32_e32 v223, v223, v253
	v_mul_f32_e32 v224, v224, v254
	v_mul_f32_e32 v225, v225, v255
	global_store_dwordx4 v[80:81], v[222:225], off offset:3072 nt
	ds_read_b128 v[252:255], v155
	s_add_i32 s44, s40, 8
	s_ashr_i32 s45, s44, 31
	s_lshl_b64 s[44:45], s[44:45], 12
	v_lshl_add_u64 v[80:81], v[36:37], 0, s[44:45]
	s_waitcnt lgkmcnt(0)
	v_mul_f32_e32 v236, v236, v252
	v_mul_f32_e32 v237, v237, v253
	v_mul_f32_e32 v238, v238, v254
	v_mul_f32_e32 v239, v239, v255
	global_store_dwordx4 v[80:81], v[236:239], off nt
	v_add_u32_e32 v147, 8, v140
	v_and_b32_e32 v146, 15, v147
	v_xor_b32_e32 v146, 8, v146
	v_bfe_u32 v148, v147, 4, 4
	v_mul_lo_u32 v146, v146, s92
	v_mul_lo_u32 v148, v148, s92
	v_mov_b32_e32 v147, v146
	v_mov_b32_e32 v149, v148
	ds_write2st64_b64 v77, v[146:147], v[148:149] offset1:2
	v_add_u32_e32 v138, 0x800, v74
	ds_read_u8 v139, v138
	v_add_u32_e32 v141, 0x800, v73
	ds_read_u8 v140, v141
	s_add_i32 s43, s67, 96
	v_mov_b32_e32 v138, s43
	ds_read2st64_b32 v[228:229], v138 offset1:1
	ds_read_b128 v[18:21], v227 offset:4096
	ds_read_b128 v[22:25], v227 offset:4112
	v_add_u32_e32 v152, 0x600000, v63
	v_add_u32_e32 v153, 0x600000, v64
	v_mov_b32_e32 v38, 0
	v_mov_b32_e32 v39, 0
	v_mov_b32_e32 v40, 0
	v_mov_b32_e32 v41, 0
	v_mov_b32_e32 v42, 0
	v_mov_b32_e32 v43, 0
	v_mov_b32_e32 v44, 0
	v_mov_b32_e32 v45, 0
	v_and_b32_e32 v78, 0xffff, v31
	v_lshrrev_b32_e32 v79, 16, v31
	v_lshl_add_u32 v78, v78, 7, v150
	v_lshl_add_u32 v79, v79, 7, v151
	s_mov_b32 m0, s77
	s_add_i32 s43, s77, 0x400
	global_load_lds_dwordx4 v78, s[50:51]
	s_mov_b32 m0, s43
	s_nop 0
	global_load_lds_dwordx4 v79, s[50:51]
	s_waitcnt vmcnt(10)
; #define TR4(p_) __builtin_amdgcn_ds_read_tr4_b64_v2i32((LAS v2i*)(p_))
; #define VDMA(st_, k_) do { _Pragma("unroll") for (int i_ = 0; i_ < 4; ++i_) { \
;         const unsigned off_ = (unsigned)((st_) >> 2) * (16384u * 128u) + (PE_ID(E, 4 * ((st_) & 3) + i_) << 7) + ((i_ & 1) ? cx1 : cx0); \
;         __builtin_amdgcn_global_load_lds((const unsigned*)(V4 + off_), (LAS unsigned*)(ldsb + BUF[k_] + 1024 * i_), 16, 0, 0); } } while (0)
; __device__ __forceinline__ void peer_v_tokens(int j, const LAS unsigned short* EL, const LAS unsigned char* AL  , const LAS float* ASC  , const LAS int* SAL  , ...
;     ...
;         for (int st = 0; st < 16; ++st) {
;             const int p = st >> 2, q = st & 3;
;             if (st < 14) VDMA(st + 2, (st + 2) % 3);
;             if (st < 14) asm volatile("s_waitcnt vmcnt(8)" ::: "memory");
;             else if (st == 14) asm volatile("s_waitcnt vmcnt(4)" ::: "memory");
;             else asm volatile("s_waitcnt vmcnt(0)" ::: "memory");
;             if (q == 0) {
; #pragma unroll
;                 for (int r = 0; r < 4; ++r) { accH[r] = 0; accL[r] = 0; } }
; #pragma unroll
;             for (int tp = 0; tp < 2; ++tp) {
;                 const v2i ao = TR4(ATL + (2 * q + tp) * 128 + 8 * s16), ah = TR4(ATL + 1024 + (2 * q + tp) * 128 + 8 * s16);
; #pragma unroll
;                 for (int r = 0; r < 4; ++r) {
;                     const v2i d = TR4(ldsb + BUF[st % 3] + 2048 * tp + roff[r]);
;                     accH[r] = __builtin_amdgcn_sdot8(d.x, ah.x, accH[r], false); accH[r] = __builtin_amdgcn_sdot8(d.y, ah.y, accH[r], false);
;                     accL[r] = __builtin_amdgcn_sdot8(d.x, ao.x, accL[r], false); accL[r] = __builtin_amdgcn_sdot8(d.y, ao.y, accL[r], false);
;                 }
	v_add_u32_e32 v54, s79, v59
	v_add_u32_e32 v55, s79, v60
	v_add_u32_e32 v56, s79, v61
	v_add_u32_e32 v57, s79, v62
	ds_read_b64_tr_b4 v[50:51], v160 offset:128
	ds_read_b64_tr_b4 v[52:53], v160 offset:1152
	ds_read_b64_tr_b4 v[130:131], v54
	ds_read_b64_tr_b4 v[132:133], v55
	ds_read_b64_tr_b4 v[134:135], v56
	ds_read_b64_tr_b4 v[136:137], v57
	s_waitcnt lgkmcnt(14)
	v_dot8c_i32_i4_e32 v38, v122, v48
	v_dot8c_i32_i4_e32 v39, v122, v46
	v_dot8c_i32_i4_e32 v40, v124, v48
	v_dot8c_i32_i4_e32 v41, v124, v46
	v_dot8c_i32_i4_e32 v42, v126, v48
	v_dot8c_i32_i4_e32 v43, v126, v46
	v_dot8c_i32_i4_e32 v44, v128, v48
	v_dot8c_i32_i4_e32 v45, v128, v46
	v_dot8c_i32_i4_e32 v38, v123, v49
	v_dot8c_i32_i4_e32 v39, v123, v47
	v_dot8c_i32_i4_e32 v40, v125, v49
	v_dot8c_i32_i4_e32 v41, v125, v47
	v_dot8c_i32_i4_e32 v42, v127, v49
	v_dot8c_i32_i4_e32 v43, v127, v47
	v_dot8c_i32_i4_e32 v44, v129, v49
	v_dot8c_i32_i4_e32 v45, v129, v47
	v_and_b32_e32 v78, 0xffff, v32
	v_lshrrev_b32_e32 v79, 16, v32
	v_lshl_add_u32 v78, v78, 7, v150
	v_lshl_add_u32 v79, v79, 7, v151
	s_mov_b32 m0, s78
	s_add_i32 s43, s78, 0x400
	global_load_lds_dwordx4 v78, s[50:51]
	s_mov_b32 m0, s43
	s_nop 0
	global_load_lds_dwordx4 v79, s[50:51]
	s_waitcnt vmcnt(10)
	v_add_u32_e32 v54, s98, v59
	v_add_u32_e32 v55, s98, v60
	v_add_u32_e32 v56, s98, v61
	v_add_u32_e32 v57, s98, v62
	ds_read_b64_tr_b4 v[46:47], v160 offset:256
	ds_read_b64_tr_b4 v[48:49], v160 offset:1280
	ds_read_b64_tr_b4 v[122:123], v54
	ds_read_b64_tr_b4 v[124:125], v55
	ds_read_b64_tr_b4 v[126:127], v56
	ds_read_b64_tr_b4 v[128:129], v57
	s_waitcnt lgkmcnt(6)
	v_dot8c_i32_i4_e32 v38, v130, v52
	v_dot8c_i32_i4_e32 v39, v130, v50
	v_dot8c_i32_i4_e32 v40, v132, v52
	v_dot8c_i32_i4_e32 v41, v132, v50
	v_dot8c_i32_i4_e32 v42, v134, v52
	v_dot8c_i32_i4_e32 v43, v134, v50
	v_dot8c_i32_i4_e32 v44, v136, v52
	v_dot8c_i32_i4_e32 v45, v136, v50
	v_dot8c_i32_i4_e32 v38, v131, v53
	v_dot8c_i32_i4_e32 v39, v131, v51
	v_dot8c_i32_i4_e32 v40, v133, v53
	v_dot8c_i32_i4_e32 v41, v133, v51
	v_dot8c_i32_i4_e32 v42, v135, v53
	v_dot8c_i32_i4_e32 v43, v135, v51
	v_dot8c_i32_i4_e32 v44, v137, v53
	v_dot8c_i32_i4_e32 v45, v137, v51
	v_and_b32_e32 v78, 0xffff, v33
	v_lshrrev_b32_e32 v79, 16, v33
	v_lshl_add_u32 v78, v78, 7, v150
	v_lshl_add_u32 v79, v79, 7, v151
	s_mov_b32 m0, s79
	s_add_i32 s43, s79, 0x400
	global_load_lds_dwordx4 v78, s[50:51]
	s_mov_b32 m0, s43
	s_nop 0
	global_load_lds_dwordx4 v79, s[50:51]
	s_waitcnt vmcnt(10)
	v_add_u32_e32 v54, s99, v59
	v_add_u32_e32 v55, s99, v60
	v_add_u32_e32 v56, s99, v61
	v_add_u32_e32 v57, s99, v62
	ds_read_b64_tr_b4 v[50:51], v160 offset:384
	ds_read_b64_tr_b4 v[52:53], v160 offset:1408
	ds_read_b64_tr_b4 v[130:131], v54
	ds_read_b64_tr_b4 v[132:133], v55
	ds_read_b64_tr_b4 v[134:135], v56
	ds_read_b64_tr_b4 v[136:137], v57
	s_waitcnt lgkmcnt(6)
	v_dot8c_i32_i4_e32 v38, v122, v48
	v_dot8c_i32_i4_e32 v39, v122, v46
	v_dot8c_i32_i4_e32 v40, v124, v48
	v_dot8c_i32_i4_e32 v41, v124, v46
	v_dot8c_i32_i4_e32 v42, v126, v48
	v_dot8c_i32_i4_e32 v43, v126, v46
	v_dot8c_i32_i4_e32 v44, v128, v48
	v_dot8c_i32_i4_e32 v45, v128, v46
	v_dot8c_i32_i4_e32 v38, v123, v49
	v_dot8c_i32_i4_e32 v39, v123, v47
	v_dot8c_i32_i4_e32 v40, v125, v49
	v_dot8c_i32_i4_e32 v41, v125, v47
	v_dot8c_i32_i4_e32 v42, v127, v49
	v_dot8c_i32_i4_e32 v43, v127, v47
	v_dot8c_i32_i4_e32 v44, v129, v49
	v_dot8c_i32_i4_e32 v45, v129, v47
	s_waitcnt lgkmcnt(15)
	v_and_b32_e32 v78, 0xffff, v18
	v_lshrrev_b32_e32 v79, 16, v18
	v_lshl_add_u32 v78, v78, 7, v152
	v_lshl_add_u32 v79, v79, 7, v153
	s_mov_b32 m0, s98
	s_add_i32 s43, s98, 0x400
	global_load_lds_dwordx4 v78, s[50:51]
	s_mov_b32 m0, s43
	s_nop 0
	global_load_lds_dwordx4 v79, s[50:51]
	s_waitcnt vmcnt(10)
	v_add_u32_e32 v54, s76, v59
	v_add_u32_e32 v55, s76, v60
	v_add_u32_e32 v56, s76, v61
	v_add_u32_e32 v57, s76, v62
	ds_read_b64_tr_b4 v[46:47], v160 offset:512
	ds_read_b64_tr_b4 v[48:49], v160 offset:1536
	ds_read_b64_tr_b4 v[122:123], v54
	ds_read_b64_tr_b4 v[124:125], v55
	ds_read_b64_tr_b4 v[126:127], v56
	ds_read_b64_tr_b4 v[128:129], v57
	s_waitcnt lgkmcnt(6)
	v_dot8c_i32_i4_e32 v38, v130, v52
	v_dot8c_i32_i4_e32 v39, v130, v50
	v_dot8c_i32_i4_e32 v40, v132, v52
	v_dot8c_i32_i4_e32 v41, v132, v50
	v_dot8c_i32_i4_e32 v42, v134, v52
	v_dot8c_i32_i4_e32 v43, v134, v50
	v_dot8c_i32_i4_e32 v44, v136, v52
	v_dot8c_i32_i4_e32 v45, v136, v50
	v_dot8c_i32_i4_e32 v38, v131, v53
	v_dot8c_i32_i4_e32 v39, v131, v51
	v_dot8c_i32_i4_e32 v40, v133, v53
	v_dot8c_i32_i4_e32 v41, v133, v51
	v_dot8c_i32_i4_e32 v42, v135, v53
	v_dot8c_i32_i4_e32 v43, v135, v51
	v_dot8c_i32_i4_e32 v44, v137, v53
	v_dot8c_i32_i4_e32 v45, v137, v51
	v_and_b32_e32 v78, 0xffff, v19
	v_lshrrev_b32_e32 v79, 16, v19
	v_lshl_add_u32 v78, v78, 7, v152
	v_lshl_add_u32 v79, v79, 7, v153
	s_mov_b32 m0, s99
	s_add_i32 s43, s99, 0x400
	global_load_lds_dwordx4 v78, s[50:51]
	s_mov_b32 m0, s43
	s_nop 0
	global_load_lds_dwordx4 v79, s[50:51]
	s_waitcnt vmcnt(8)
	v_add_u32_e32 v54, s77, v59
	v_add_u32_e32 v55, s77, v60
	v_add_u32_e32 v56, s77, v61
	v_add_u32_e32 v57, s77, v62
	ds_read_b64_tr_b4 v[50:51], v160 offset:640
	ds_read_b64_tr_b4 v[52:53], v160 offset:1664
	ds_read_b64_tr_b4 v[130:131], v54
	ds_read_b64_tr_b4 v[132:133], v55
	ds_read_b64_tr_b4 v[134:135], v56
	ds_read_b64_tr_b4 v[136:137], v57
	s_waitcnt lgkmcnt(6)
	v_dot8c_i32_i4_e32 v38, v122, v48
	v_dot8c_i32_i4_e32 v39, v122, v46
	v_dot8c_i32_i4_e32 v40, v124, v48
	v_dot8c_i32_i4_e32 v41, v124, v46
	v_dot8c_i32_i4_e32 v42, v126, v48
	v_dot8c_i32_i4_e32 v43, v126, v46
	v_dot8c_i32_i4_e32 v44, v128, v48
	v_dot8c_i32_i4_e32 v45, v128, v46
	v_dot8c_i32_i4_e32 v38, v123, v49
	v_dot8c_i32_i4_e32 v39, v123, v47
	v_dot8c_i32_i4_e32 v40, v125, v49
	v_dot8c_i32_i4_e32 v41, v125, v47
	v_dot8c_i32_i4_e32 v42, v127, v49
	v_dot8c_i32_i4_e32 v43, v127, v47
	v_dot8c_i32_i4_e32 v44, v129, v49
	v_dot8c_i32_i4_e32 v45, v129, v47
	s_waitcnt lgkmcnt(15)
; __device__ __forceinline__ bf16 f2bf(float f) { return (bf16)f2bfu(f); }
; #define TR4(p_) __builtin_amdgcn_ds_read_tr4_b64_v2i32((LAS v2i*)(p_))
; __device__ __forceinline__ void peer_v_tokens(int j, const LAS unsigned short* EL, const LAS unsigned char* AL  , const LAS float* ASC  , const LAS int* SAL  , ...
;     ...
;         for (int st = 0; st < 16; ++st) {
;             const int p = st >> 2, q = st & 3;
;             if (st < 14) VDMA(st + 2, (st + 2) % 3);
;             if (st < 14) asm volatile("s_waitcnt vmcnt(8)" ::: "memory");
;             else if (st == 14) asm volatile("s_waitcnt vmcnt(4)" ::: "memory");
;             else asm volatile("s_waitcnt vmcnt(0)" ::: "memory");
;             if (q == 0) {
; #pragma unroll
;                 for (int r = 0; r < 4; ++r) { accH[r] = 0; accL[r] = 0; } }
; #pragma unroll
;             for (int tp = 0; tp < 2; ++tp) {
;                 const v2i ao = TR4(ATL + (2 * q + tp) * 128 + 8 * s16), ah = TR4(ATL + 1024 + (2 * q + tp) * 128 + 8 * s16);
; #pragma unroll
;                 for (int r = 0; r < 4; ++r) {
;                     const v2i d = TR4(ldsb + BUF[st % 3] + 2048 * tp + roff[r]);
;                     accH[r] = __builtin_amdgcn_sdot8(d.x, ah.x, accH[r], false); accH[r] = __builtin_amdgcn_sdot8(d.y, ah.y, accH[r], false);
;                     accL[r] = __builtin_amdgcn_sdot8(d.x, ao.x, accL[r], false); accL[r] = __builtin_amdgcn_sdot8(d.y, ao.y, accL[r], false);
;                 }
;             }
;             asm volatile("s_waitcnt lgkmcnt(0)" ::: "memory");
;             if (q == 3) {
; #pragma unroll
;                 for (int r = 0; r < 4; ++r) STASH[256 * p + 16 * (grp + 4 * r) + pc] = f2bf(asc * (float)(2 * ((accH[r] << 4) + accL[r]) + sa));
;             }
;     ...
;             float4* op = (float4*)(outp + (size_t)t * D) + lane;
; #pragma unroll
;             for (int jq = 0; jq < 4; ++jq) { typedef float f4v __attribute__((ext_vector_type(4))); f4v o4; o4.x = v[jq].x * r3 * gv[jq].x; o4.y = v[jq].y * r3 * gv[jq].y; o4.z = v[jq].z * r3 * gv[jq].z; o4.w = v[jq].w * r3 * gv[jq].w;
;                 __builtin_nontemporal_store(o4, (f4v*)op + 64 * jq); }
	v_add_u32_e32 v143, 8, v139
	v_and_b32_e32 v142, 15, v143
	v_xor_b32_e32 v142, 8, v142
	v_bfe_u32 v144, v143, 4, 4
	v_mul_lo_u32 v142, v142, s92
	v_mul_lo_u32 v144, v144, s92
	v_mov_b32_e32 v143, v142
	v_mov_b32_e32 v145, v144
	ds_write2st64_b64 v159, v[142:143], v[144:145] offset1:2
	v_and_b32_e32 v78, 0xffff, v20
	v_lshrrev_b32_e32 v79, 16, v20
	v_lshl_add_u32 v78, v78, 7, v152
	v_lshl_add_u32 v79, v79, 7, v153
	s_mov_b32 m0, s76
	s_add_i32 s43, s76, 0x400
	global_load_lds_dwordx4 v78, s[50:51]
	s_mov_b32 m0, s43
	s_nop 0
	global_load_lds_dwordx4 v79, s[50:51]
	s_waitcnt vmcnt(8)
	v_add_u32_e32 v54, s78, v59
	v_add_u32_e32 v55, s78, v60
	v_add_u32_e32 v56, s78, v61
	v_add_u32_e32 v57, s78, v62
	ds_read_b64_tr_b4 v[46:47], v160 offset:768
	ds_read_b64_tr_b4 v[48:49], v160 offset:1792
	ds_read_b64_tr_b4 v[122:123], v54
	ds_read_b64_tr_b4 v[124:125], v55
	ds_read_b64_tr_b4 v[126:127], v56
	ds_read_b64_tr_b4 v[128:129], v57
	s_waitcnt lgkmcnt(7)
	v_dot8c_i32_i4_e32 v38, v130, v52
	v_dot8c_i32_i4_e32 v39, v130, v50
	v_dot8c_i32_i4_e32 v40, v132, v52
	v_dot8c_i32_i4_e32 v41, v132, v50
	v_dot8c_i32_i4_e32 v42, v134, v52
	v_dot8c_i32_i4_e32 v43, v134, v50
	v_dot8c_i32_i4_e32 v44, v136, v52
	v_dot8c_i32_i4_e32 v45, v136, v50
	v_dot8c_i32_i4_e32 v38, v131, v53
	v_dot8c_i32_i4_e32 v39, v131, v51
	v_dot8c_i32_i4_e32 v40, v133, v53
	v_dot8c_i32_i4_e32 v41, v133, v51
	v_dot8c_i32_i4_e32 v42, v135, v53
	v_dot8c_i32_i4_e32 v43, v135, v51
	v_dot8c_i32_i4_e32 v44, v137, v53
	v_dot8c_i32_i4_e32 v45, v137, v51
	v_and_b32_e32 v78, 0xffff, v21
	v_lshrrev_b32_e32 v79, 16, v21
	v_lshl_add_u32 v78, v78, 7, v152
	v_lshl_add_u32 v79, v79, 7, v153
	s_mov_b32 m0, s77
	s_add_i32 s43, s77, 0x400
	global_load_lds_dwordx4 v78, s[50:51]
	s_mov_b32 m0, s43
	s_nop 0
	global_load_lds_dwordx4 v79, s[50:51]
	s_waitcnt vmcnt(8)
	v_add_u32_e32 v54, s79, v59
	v_add_u32_e32 v55, s79, v60
	v_add_u32_e32 v56, s79, v61
	v_add_u32_e32 v57, s79, v62
	ds_read_b64_tr_b4 v[50:51], v160 offset:896
	ds_read_b64_tr_b4 v[52:53], v160 offset:1920
	ds_read_b64_tr_b4 v[130:131], v54
	ds_read_b64_tr_b4 v[132:133], v55
	ds_read_b64_tr_b4 v[134:135], v56
	ds_read_b64_tr_b4 v[136:137], v57
	s_waitcnt lgkmcnt(6)
	v_dot8c_i32_i4_e32 v38, v122, v48
	v_dot8c_i32_i4_e32 v39, v122, v46
	v_dot8c_i32_i4_e32 v40, v124, v48
	v_dot8c_i32_i4_e32 v41, v124, v46
	v_dot8c_i32_i4_e32 v42, v126, v48
	v_dot8c_i32_i4_e32 v43, v126, v46
	v_dot8c_i32_i4_e32 v44, v128, v48
	v_dot8c_i32_i4_e32 v45, v128, v46
	v_dot8c_i32_i4_e32 v38, v123, v49
	v_dot8c_i32_i4_e32 v39, v123, v47
	v_dot8c_i32_i4_e32 v40, v125, v49
	v_dot8c_i32_i4_e32 v41, v125, v47
	v_dot8c_i32_i4_e32 v42, v127, v49
	v_dot8c_i32_i4_e32 v43, v127, v47
	v_dot8c_i32_i4_e32 v44, v129, v49
	v_dot8c_i32_i4_e32 v45, v129, v47
	v_and_b32_e32 v78, 0xffff, v22
	v_lshrrev_b32_e32 v79, 16, v22
	v_lshl_add_u32 v78, v78, 7, v152
	v_lshl_add_u32 v79, v79, 7, v153
	s_mov_b32 m0, s78
	s_add_i32 s43, s78, 0x400
	global_load_lds_dwordx4 v78, s[50:51]
	s_mov_b32 m0, s43
	s_nop 0
	global_load_lds_dwordx4 v79, s[50:51]
	s_waitcnt vmcnt(8)
	v_add_u32_e32 v54, s98, v59
	v_add_u32_e32 v55, s98, v60
	v_add_u32_e32 v56, s98, v61
	v_add_u32_e32 v57, s98, v62
	ds_read_b64_tr_b4 v[46:47], v160
	ds_read_b64_tr_b4 v[48:49], v160 offset:1024
	ds_read_b64_tr_b4 v[122:123], v54
	ds_read_b64_tr_b4 v[124:125], v55
	ds_read_b64_tr_b4 v[126:127], v56
	ds_read_b64_tr_b4 v[128:129], v57
	s_waitcnt lgkmcnt(6)
	v_dot8c_i32_i4_e32 v38, v130, v52
	v_dot8c_i32_i4_e32 v39, v130, v50
	v_dot8c_i32_i4_e32 v40, v132, v52
	v_dot8c_i32_i4_e32 v41, v132, v50
	v_dot8c_i32_i4_e32 v42, v134, v52
	v_dot8c_i32_i4_e32 v43, v134, v50
	v_dot8c_i32_i4_e32 v44, v136, v52
	v_dot8c_i32_i4_e32 v45, v136, v50
	v_dot8c_i32_i4_e32 v38, v131, v53
	v_dot8c_i32_i4_e32 v39, v131, v51
	v_dot8c_i32_i4_e32 v40, v133, v53
	v_dot8c_i32_i4_e32 v41, v133, v51
	v_dot8c_i32_i4_e32 v42, v135, v53
	v_dot8c_i32_i4_e32 v43, v135, v51
	v_dot8c_i32_i4_e32 v44, v137, v53
	v_dot8c_i32_i4_e32 v45, v137, v51
	s_nop 3
	s_waitcnt lgkmcnt(15)
	v_lshlrev_b32_e32 v38, 5, v38
	v_lshlrev_b32_e32 v39, 1, v39
	v_add3_u32 v38, v39, v229, v38
	v_cvt_f32_i32_e32 v38, v38
	v_mul_f32_e32 v38, v228, v38
	v_lshlrev_b32_e32 v40, 5, v40
	v_lshlrev_b32_e32 v41, 1, v41
	v_add3_u32 v40, v41, v229, v40
	v_cvt_f32_i32_e32 v40, v40
	v_mul_f32_e32 v40, v228, v40
	v_lshlrev_b32_e32 v42, 5, v42
	v_lshlrev_b32_e32 v43, 1, v43
	v_add3_u32 v42, v43, v229, v42
	v_cvt_f32_i32_e32 v42, v42
	v_mul_f32_e32 v42, v228, v42
	v_lshlrev_b32_e32 v44, 5, v44
	v_lshlrev_b32_e32 v45, 1, v45
	v_add3_u32 v44, v45, v229, v44
	v_cvt_f32_i32_e32 v44, v44
	v_mul_f32_e32 v44, v228, v44
	v_cvt_pk_bf16_f32 v190, v38, v40
	v_cvt_pk_bf16_f32 v191, v42, v44
	ds_read_b128 v[252:255], v155 offset:1024
	s_add_i32 s44, s40, 8
	s_ashr_i32 s45, s44, 31
	s_lshl_b64 s[44:45], s[44:45], 12
	v_lshl_add_u64 v[80:81], v[36:37], 0, s[44:45]
	s_waitcnt lgkmcnt(0)
	v_mul_f32_e32 v240, v240, v252
	v_mul_f32_e32 v241, v241, v253
	v_mul_f32_e32 v242, v242, v254
	v_mul_f32_e32 v243, v243, v255
	global_store_dwordx4 v[80:81], v[240:243], off offset:1024 nt
	v_add_u32_e32 v147, 8, v140
	v_and_b32_e32 v146, 15, v147
	v_xor_b32_e32 v146, 8, v146
	v_bfe_u32 v148, v147, 4, 4
	v_mul_lo_u32 v146, v146, s92
	v_mul_lo_u32 v148, v148, s92
	v_mov_b32_e32 v147, v146
	v_mov_b32_e32 v149, v148
	ds_write2st64_b64 v77, v[146:147], v[148:149] offset1:2
	v_add_u32_e32 v138, 0xc00, v74
	ds_read_u8 v139, v138
	v_add_u32_e32 v141, 0xc00, v73
	ds_read_u8 v140, v141
	s_add_i32 s43, s67, 64
	v_mov_b32_e32 v138, s43
	ds_read2st64_b32 v[228:229], v138 offset1:1
	ds_read_b128 v[26:29], v227 offset:6144
	ds_read_b128 v[30:33], v227 offset:6160
	v_mov_b32_e32 v38, 0
	v_mov_b32_e32 v39, 0
	v_mov_b32_e32 v40, 0
	v_mov_b32_e32 v41, 0
	v_mov_b32_e32 v42, 0
	v_mov_b32_e32 v43, 0
	v_mov_b32_e32 v44, 0
	v_mov_b32_e32 v45, 0
	v_and_b32_e32 v78, 0xffff, v23
	v_lshrrev_b32_e32 v79, 16, v23
	v_lshl_add_u32 v78, v78, 7, v152
	v_lshl_add_u32 v79, v79, 7, v153
	s_mov_b32 m0, s79
	s_add_i32 s43, s79, 0x400
	global_load_lds_dwordx4 v78, s[50:51]
	s_mov_b32 m0, s43
	s_nop 0
	global_load_lds_dwordx4 v79, s[50:51]
	s_waitcnt vmcnt(9)
; #define TR4(p_) __builtin_amdgcn_ds_read_tr4_b64_v2i32((LAS v2i*)(p_))
; #define VDMA(st_, k_) do { _Pragma("unroll") for (int i_ = 0; i_ < 4; ++i_) { \
;         const unsigned off_ = (unsigned)((st_) >> 2) * (16384u * 128u) + (PE_ID(E, 4 * ((st_) & 3) + i_) << 7) + ((i_ & 1) ? cx1 : cx0); \
;         __builtin_amdgcn_global_load_lds((const unsigned*)(V4 + off_), (LAS unsigned*)(ldsb + BUF[k_] + 1024 * i_), 16, 0, 0); } } while (0)
; __device__ __forceinline__ void peer_v_tokens(int j, const LAS unsigned short* EL, const LAS unsigned char* AL  , const LAS float* ASC  , const LAS int* SAL  , ...
;     ...
;         for (int st = 0; st < 16; ++st) {
;             const int p = st >> 2, q = st & 3;
;             if (st < 14) VDMA(st + 2, (st + 2) % 3);
;             if (st < 14) asm volatile("s_waitcnt vmcnt(8)" ::: "memory");
;             else if (st == 14) asm volatile("s_waitcnt vmcnt(4)" ::: "memory");
;             else asm volatile("s_waitcnt vmcnt(0)" ::: "memory");
;             if (q == 0) {
; #pragma unroll
;                 for (int r = 0; r < 4; ++r) { accH[r] = 0; accL[r] = 0; } }
; #pragma unroll
;             for (int tp = 0; tp < 2; ++tp) {
;                 const v2i ao = TR4(ATL + (2 * q + tp) * 128 + 8 * s16), ah = TR4(ATL + 1024 + (2 * q + tp) * 128 + 8 * s16);
; #pragma unroll
;                 for (int r = 0; r < 4; ++r) {
;                     const v2i d = TR4(ldsb + BUF[st % 3] + 2048 * tp + roff[r]);
;                     accH[r] = __builtin_amdgcn_sdot8(d.x, ah.x, accH[r], false); accH[r] = __builtin_amdgcn_sdot8(d.y, ah.y, accH[r], false);
;                     accL[r] = __builtin_amdgcn_sdot8(d.x, ao.x, accL[r], false); accL[r] = __builtin_amdgcn_sdot8(d.y, ao.y, accL[r], false);
;                 }
	v_add_u32_e32 v54, s99, v59
	v_add_u32_e32 v55, s99, v60
	v_add_u32_e32 v56, s99, v61
	v_add_u32_e32 v57, s99, v62
	ds_read_b64_tr_b4 v[50:51], v160 offset:128
	ds_read_b64_tr_b4 v[52:53], v160 offset:1152
	ds_read_b64_tr_b4 v[130:131], v54
	ds_read_b64_tr_b4 v[132:133], v55
	ds_read_b64_tr_b4 v[134:135], v56
	ds_read_b64_tr_b4 v[136:137], v57
	s_waitcnt lgkmcnt(13)
	v_dot8c_i32_i4_e32 v38, v122, v48
	v_dot8c_i32_i4_e32 v39, v122, v46
	v_dot8c_i32_i4_e32 v40, v124, v48
	v_dot8c_i32_i4_e32 v41, v124, v46
	v_dot8c_i32_i4_e32 v42, v126, v48
	v_dot8c_i32_i4_e32 v43, v126, v46
	v_dot8c_i32_i4_e32 v44, v128, v48
	v_dot8c_i32_i4_e32 v45, v128, v46
	v_dot8c_i32_i4_e32 v38, v123, v49
	v_dot8c_i32_i4_e32 v39, v123, v47
	v_dot8c_i32_i4_e32 v40, v125, v49
	v_dot8c_i32_i4_e32 v41, v125, v47
	v_dot8c_i32_i4_e32 v42, v127, v49
	v_dot8c_i32_i4_e32 v43, v127, v47
	v_dot8c_i32_i4_e32 v44, v129, v49
	v_dot8c_i32_i4_e32 v45, v129, v47
	v_and_b32_e32 v78, 0xffff, v24
	v_lshrrev_b32_e32 v79, 16, v24
	v_lshl_add_u32 v78, v78, 7, v152
	v_lshl_add_u32 v79, v79, 7, v153
	s_mov_b32 m0, s98
	s_add_i32 s43, s98, 0x400
	global_load_lds_dwordx4 v78, s[50:51]
	s_mov_b32 m0, s43
	s_nop 0
	global_load_lds_dwordx4 v79, s[50:51]
	s_waitcnt vmcnt(9)
	v_add_u32_e32 v54, s76, v59
	v_add_u32_e32 v55, s76, v60
	v_add_u32_e32 v56, s76, v61
	v_add_u32_e32 v57, s76, v62
	ds_read_b64_tr_b4 v[46:47], v160 offset:256
	ds_read_b64_tr_b4 v[48:49], v160 offset:1280
	ds_read_b64_tr_b4 v[122:123], v54
	ds_read_b64_tr_b4 v[124:125], v55
	ds_read_b64_tr_b4 v[126:127], v56
	ds_read_b64_tr_b4 v[128:129], v57
	s_waitcnt lgkmcnt(6)
	v_dot8c_i32_i4_e32 v38, v130, v52
	v_dot8c_i32_i4_e32 v39, v130, v50
	v_dot8c_i32_i4_e32 v40, v132, v52
	v_dot8c_i32_i4_e32 v41, v132, v50
	v_dot8c_i32_i4_e32 v42, v134, v52
	v_dot8c_i32_i4_e32 v43, v134, v50
	v_dot8c_i32_i4_e32 v44, v136, v52
	v_dot8c_i32_i4_e32 v45, v136, v50
	v_dot8c_i32_i4_e32 v38, v131, v53
	v_dot8c_i32_i4_e32 v39, v131, v51
	v_dot8c_i32_i4_e32 v40, v133, v53
	v_dot8c_i32_i4_e32 v41, v133, v51
	v_dot8c_i32_i4_e32 v42, v135, v53
	v_dot8c_i32_i4_e32 v43, v135, v51
	v_dot8c_i32_i4_e32 v44, v137, v53
	v_dot8c_i32_i4_e32 v45, v137, v51
	v_and_b32_e32 v78, 0xffff, v25
	v_lshrrev_b32_e32 v79, 16, v25
	v_lshl_add_u32 v78, v78, 7, v152
	v_lshl_add_u32 v79, v79, 7, v153
	s_mov_b32 m0, s99
	s_add_i32 s43, s99, 0x400
	global_load_lds_dwordx4 v78, s[50:51]
	s_mov_b32 m0, s43
	s_nop 0
	global_load_lds_dwordx4 v79, s[50:51]
	s_waitcnt vmcnt(9)
	v_add_u32_e32 v54, s77, v59
	v_add_u32_e32 v55, s77, v60
	v_add_u32_e32 v56, s77, v61
	v_add_u32_e32 v57, s77, v62
	ds_read_b64_tr_b4 v[50:51], v160 offset:384
	ds_read_b64_tr_b4 v[52:53], v160 offset:1408
	ds_read_b64_tr_b4 v[130:131], v54
	ds_read_b64_tr_b4 v[132:133], v55
	ds_read_b64_tr_b4 v[134:135], v56
	ds_read_b64_tr_b4 v[136:137], v57
	s_waitcnt lgkmcnt(6)
	v_dot8c_i32_i4_e32 v38, v122, v48
	v_dot8c_i32_i4_e32 v39, v122, v46
	v_dot8c_i32_i4_e32 v40, v124, v48
	v_dot8c_i32_i4_e32 v41, v124, v46
	v_dot8c_i32_i4_e32 v42, v126, v48
	v_dot8c_i32_i4_e32 v43, v126, v46
	v_dot8c_i32_i4_e32 v44, v128, v48
	v_dot8c_i32_i4_e32 v45, v128, v46
	v_dot8c_i32_i4_e32 v38, v123, v49
	v_dot8c_i32_i4_e32 v39, v123, v47
	v_dot8c_i32_i4_e32 v40, v125, v49
	v_dot8c_i32_i4_e32 v41, v125, v47
	v_dot8c_i32_i4_e32 v42, v127, v49
	v_dot8c_i32_i4_e32 v43, v127, v47
	v_dot8c_i32_i4_e32 v44, v129, v49
	v_dot8c_i32_i4_e32 v45, v129, v47
	s_waitcnt lgkmcnt(15)
	v_and_b32_e32 v78, 0xffff, v26
	v_lshrrev_b32_e32 v79, 16, v26
	v_lshl_add_u32 v78, v78, 7, v152
	v_lshl_add_u32 v79, v79, 7, v153
	s_mov_b32 m0, s76
	s_add_i32 s43, s76, 0x400
	global_load_lds_dwordx4 v78, s[50:51]
	s_mov_b32 m0, s43
	s_nop 0
	global_load_lds_dwordx4 v79, s[50:51]
	s_waitcnt vmcnt(9)
	v_add_u32_e32 v54, s78, v59
	v_add_u32_e32 v55, s78, v60
	v_add_u32_e32 v56, s78, v61
	v_add_u32_e32 v57, s78, v62
	ds_read_b64_tr_b4 v[46:47], v160 offset:512
	ds_read_b64_tr_b4 v[48:49], v160 offset:1536
	ds_read_b64_tr_b4 v[122:123], v54
	ds_read_b64_tr_b4 v[124:125], v55
	ds_read_b64_tr_b4 v[126:127], v56
	ds_read_b64_tr_b4 v[128:129], v57
	s_waitcnt lgkmcnt(6)
	v_dot8c_i32_i4_e32 v38, v130, v52
	v_dot8c_i32_i4_e32 v39, v130, v50
	v_dot8c_i32_i4_e32 v40, v132, v52
	v_dot8c_i32_i4_e32 v41, v132, v50
	v_dot8c_i32_i4_e32 v42, v134, v52
	v_dot8c_i32_i4_e32 v43, v134, v50
	v_dot8c_i32_i4_e32 v44, v136, v52
	v_dot8c_i32_i4_e32 v45, v136, v50
	v_dot8c_i32_i4_e32 v38, v131, v53
	v_dot8c_i32_i4_e32 v39, v131, v51
	v_dot8c_i32_i4_e32 v40, v133, v53
	v_dot8c_i32_i4_e32 v41, v133, v51
	v_dot8c_i32_i4_e32 v42, v135, v53
	v_dot8c_i32_i4_e32 v43, v135, v51
	v_dot8c_i32_i4_e32 v44, v137, v53
	v_dot8c_i32_i4_e32 v45, v137, v51
	v_and_b32_e32 v78, 0xffff, v27
	v_lshrrev_b32_e32 v79, 16, v27
	v_lshl_add_u32 v78, v78, 7, v152
	v_lshl_add_u32 v79, v79, 7, v153
	s_mov_b32 m0, s77
	s_add_i32 s43, s77, 0x400
	global_load_lds_dwordx4 v78, s[50:51]
	s_mov_b32 m0, s43
	s_nop 0
	global_load_lds_dwordx4 v79, s[50:51]
	s_waitcnt vmcnt(8)
	v_add_u32_e32 v54, s79, v59
	v_add_u32_e32 v55, s79, v60
	v_add_u32_e32 v56, s79, v61
	v_add_u32_e32 v57, s79, v62
	ds_read_b64_tr_b4 v[50:51], v160 offset:640
	ds_read_b64_tr_b4 v[52:53], v160 offset:1664
	ds_read_b64_tr_b4 v[130:131], v54
	ds_read_b64_tr_b4 v[132:133], v55
	ds_read_b64_tr_b4 v[134:135], v56
	ds_read_b64_tr_b4 v[136:137], v57
	s_waitcnt lgkmcnt(6)
	v_dot8c_i32_i4_e32 v38, v122, v48
	v_dot8c_i32_i4_e32 v39, v122, v46
	v_dot8c_i32_i4_e32 v40, v124, v48
	v_dot8c_i32_i4_e32 v41, v124, v46
	v_dot8c_i32_i4_e32 v42, v126, v48
	v_dot8c_i32_i4_e32 v43, v126, v46
	v_dot8c_i32_i4_e32 v44, v128, v48
	v_dot8c_i32_i4_e32 v45, v128, v46
	v_dot8c_i32_i4_e32 v38, v123, v49
	v_dot8c_i32_i4_e32 v39, v123, v47
	v_dot8c_i32_i4_e32 v40, v125, v49
	v_dot8c_i32_i4_e32 v41, v125, v47
	v_dot8c_i32_i4_e32 v42, v127, v49
	v_dot8c_i32_i4_e32 v43, v127, v47
	v_dot8c_i32_i4_e32 v44, v129, v49
	v_dot8c_i32_i4_e32 v45, v129, v47
	s_waitcnt lgkmcnt(15)
; __device__ __forceinline__ bf16 f2bf(float f) { return (bf16)f2bfu(f); }
; #define TR4(p_) __builtin_amdgcn_ds_read_tr4_b64_v2i32((LAS v2i*)(p_))
; #define VDMA(st_, k_) do { _Pragma("unroll") for (int i_ = 0; i_ < 4; ++i_) { \
;         const unsigned off_ = (unsigned)((st_) >> 2) * (16384u * 128u) + (PE_ID(E, 4 * ((st_) & 3) + i_) << 7) + ((i_ & 1) ? cx1 : cx0); \
;         __builtin_amdgcn_global_load_lds((const unsigned*)(V4 + off_), (LAS unsigned*)(ldsb + BUF[k_] + 1024 * i_), 16, 0, 0); } } while (0)
; __device__ __forceinline__ void peer_v_tokens(int j, const LAS unsigned short* EL, const LAS unsigned char* AL  , const LAS float* ASC  , const LAS int* SAL  , ...
;     ...
;         for (int st = 0; st < 16; ++st) {
;             const int p = st >> 2, q = st & 3;
;             if (st < 14) VDMA(st + 2, (st + 2) % 3);
;             if (st < 14) asm volatile("s_waitcnt vmcnt(8)" ::: "memory");
;             else if (st == 14) asm volatile("s_waitcnt vmcnt(4)" ::: "memory");
;             else asm volatile("s_waitcnt vmcnt(0)" ::: "memory");
;             if (q == 0) {
; #pragma unroll
;                 for (int r = 0; r < 4; ++r) { accH[r] = 0; accL[r] = 0; } }
; #pragma unroll
;             for (int tp = 0; tp < 2; ++tp) {
;                 const v2i ao = TR4(ATL + (2 * q + tp) * 128 + 8 * s16), ah = TR4(ATL + 1024 + (2 * q + tp) * 128 + 8 * s16);
; #pragma unroll
;                 for (int r = 0; r < 4; ++r) {
;                     const v2i d = TR4(ldsb + BUF[st % 3] + 2048 * tp + roff[r]);
;                     accH[r] = __builtin_amdgcn_sdot8(d.x, ah.x, accH[r], false); accH[r] = __builtin_amdgcn_sdot8(d.y, ah.y, accH[r], false);
;                     accL[r] = __builtin_amdgcn_sdot8(d.x, ao.x, accL[r], false); accL[r] = __builtin_amdgcn_sdot8(d.y, ao.y, accL[r], false);
;                 }
;             }
;             asm volatile("s_waitcnt lgkmcnt(0)" ::: "memory");
;             if (q == 3) {
; #pragma unroll
;                 for (int r = 0; r < 4; ++r) STASH[256 * p + 16 * (grp + 4 * r) + pc] = f2bf(asc * (float)(2 * ((accH[r] << 4) + accL[r]) + sa));
;             }
	v_add_u32_e32 v143, 8, v139
	v_and_b32_e32 v142, 15, v143
	v_xor_b32_e32 v142, 8, v142
	v_bfe_u32 v144, v143, 4, 4
	v_mul_lo_u32 v142, v142, s92
	v_mul_lo_u32 v144, v144, s92
	v_mov_b32_e32 v143, v142
	v_mov_b32_e32 v145, v144
	ds_write2st64_b64 v159, v[142:143], v[144:145] offset1:2
	v_and_b32_e32 v78, 0xffff, v28
	v_lshrrev_b32_e32 v79, 16, v28
	v_lshl_add_u32 v78, v78, 7, v152
	v_lshl_add_u32 v79, v79, 7, v153
	s_mov_b32 m0, s78
	s_add_i32 s43, s78, 0x400
	global_load_lds_dwordx4 v78, s[50:51]
	s_mov_b32 m0, s43
	s_nop 0
	global_load_lds_dwordx4 v79, s[50:51]
	s_waitcnt vmcnt(8)
	v_add_u32_e32 v54, s98, v59
	v_add_u32_e32 v55, s98, v60
	v_add_u32_e32 v56, s98, v61
	v_add_u32_e32 v57, s98, v62
	ds_read_b64_tr_b4 v[46:47], v160 offset:768
	ds_read_b64_tr_b4 v[48:49], v160 offset:1792
	ds_read_b64_tr_b4 v[122:123], v54
	ds_read_b64_tr_b4 v[124:125], v55
	ds_read_b64_tr_b4 v[126:127], v56
	ds_read_b64_tr_b4 v[128:129], v57
	s_waitcnt lgkmcnt(7)
	v_dot8c_i32_i4_e32 v38, v130, v52
	v_dot8c_i32_i4_e32 v39, v130, v50
	v_dot8c_i32_i4_e32 v40, v132, v52
	v_dot8c_i32_i4_e32 v41, v132, v50
	v_dot8c_i32_i4_e32 v42, v134, v52
	v_dot8c_i32_i4_e32 v43, v134, v50
	v_dot8c_i32_i4_e32 v44, v136, v52
	v_dot8c_i32_i4_e32 v45, v136, v50
	v_dot8c_i32_i4_e32 v38, v131, v53
	v_dot8c_i32_i4_e32 v39, v131, v51
	v_dot8c_i32_i4_e32 v40, v133, v53
	v_dot8c_i32_i4_e32 v41, v133, v51
	v_dot8c_i32_i4_e32 v42, v135, v53
	v_dot8c_i32_i4_e32 v43, v135, v51
	v_dot8c_i32_i4_e32 v44, v137, v53
	v_dot8c_i32_i4_e32 v45, v137, v51
	v_and_b32_e32 v78, 0xffff, v29
	v_lshrrev_b32_e32 v79, 16, v29
	v_lshl_add_u32 v78, v78, 7, v152
	v_lshl_add_u32 v79, v79, 7, v153
	s_mov_b32 m0, s79
	s_add_i32 s43, s79, 0x400
	global_load_lds_dwordx4 v78, s[50:51]
	s_mov_b32 m0, s43
	s_nop 0
	global_load_lds_dwordx4 v79, s[50:51]
	s_waitcnt vmcnt(8)
	v_add_u32_e32 v54, s99, v59
	v_add_u32_e32 v55, s99, v60
	v_add_u32_e32 v56, s99, v61
	v_add_u32_e32 v57, s99, v62
	ds_read_b64_tr_b4 v[50:51], v160 offset:896
	ds_read_b64_tr_b4 v[52:53], v160 offset:1920
	ds_read_b64_tr_b4 v[130:131], v54
	ds_read_b64_tr_b4 v[132:133], v55
	ds_read_b64_tr_b4 v[134:135], v56
	ds_read_b64_tr_b4 v[136:137], v57
	s_waitcnt lgkmcnt(6)
	v_dot8c_i32_i4_e32 v38, v122, v48
	v_dot8c_i32_i4_e32 v39, v122, v46
	v_dot8c_i32_i4_e32 v40, v124, v48
	v_dot8c_i32_i4_e32 v41, v124, v46
	v_dot8c_i32_i4_e32 v42, v126, v48
	v_dot8c_i32_i4_e32 v43, v126, v46
	v_dot8c_i32_i4_e32 v44, v128, v48
	v_dot8c_i32_i4_e32 v45, v128, v46
	v_dot8c_i32_i4_e32 v38, v123, v49
	v_dot8c_i32_i4_e32 v39, v123, v47
	v_dot8c_i32_i4_e32 v40, v125, v49
	v_dot8c_i32_i4_e32 v41, v125, v47
	v_dot8c_i32_i4_e32 v42, v127, v49
	v_dot8c_i32_i4_e32 v43, v127, v47
	v_dot8c_i32_i4_e32 v44, v129, v49
	v_dot8c_i32_i4_e32 v45, v129, v47
	v_and_b32_e32 v78, 0xffff, v30
	v_lshrrev_b32_e32 v79, 16, v30
	v_lshl_add_u32 v78, v78, 7, v152
	v_lshl_add_u32 v79, v79, 7, v153
	s_mov_b32 m0, s98
	s_add_i32 s43, s98, 0x400
	global_load_lds_dwordx4 v78, s[50:51]
	s_mov_b32 m0, s43
	s_nop 0
	global_load_lds_dwordx4 v79, s[50:51]
	s_waitcnt vmcnt(8)
	v_add_u32_e32 v54, s76, v59
	v_add_u32_e32 v55, s76, v60
	v_add_u32_e32 v56, s76, v61
	v_add_u32_e32 v57, s76, v62
	ds_read_b64_tr_b4 v[46:47], v160
	ds_read_b64_tr_b4 v[48:49], v160 offset:1024
	ds_read_b64_tr_b4 v[122:123], v54
	ds_read_b64_tr_b4 v[124:125], v55
	ds_read_b64_tr_b4 v[126:127], v56
	ds_read_b64_tr_b4 v[128:129], v57
	s_waitcnt lgkmcnt(6)
	v_dot8c_i32_i4_e32 v38, v130, v52
	v_dot8c_i32_i4_e32 v39, v130, v50
	v_dot8c_i32_i4_e32 v40, v132, v52
	v_dot8c_i32_i4_e32 v41, v132, v50
	v_dot8c_i32_i4_e32 v42, v134, v52
	v_dot8c_i32_i4_e32 v43, v134, v50
	v_dot8c_i32_i4_e32 v44, v136, v52
	v_dot8c_i32_i4_e32 v45, v136, v50
	v_dot8c_i32_i4_e32 v38, v131, v53
	v_dot8c_i32_i4_e32 v39, v131, v51
	v_dot8c_i32_i4_e32 v40, v133, v53
	v_dot8c_i32_i4_e32 v41, v133, v51
	v_dot8c_i32_i4_e32 v42, v135, v53
	v_dot8c_i32_i4_e32 v43, v135, v51
	v_dot8c_i32_i4_e32 v44, v137, v53
	v_dot8c_i32_i4_e32 v45, v137, v51
	s_nop 3
	s_waitcnt lgkmcnt(15)
	v_lshlrev_b32_e32 v38, 5, v38
	v_lshlrev_b32_e32 v39, 1, v39
	v_add3_u32 v38, v39, v229, v38
	v_cvt_f32_i32_e32 v38, v38
	v_mul_f32_e32 v38, v228, v38
	v_lshlrev_b32_e32 v40, 5, v40
	v_lshlrev_b32_e32 v41, 1, v41
	v_add3_u32 v40, v41, v229, v40
	v_cvt_f32_i32_e32 v40, v40
	v_mul_f32_e32 v40, v228, v40
	v_lshlrev_b32_e32 v42, 5, v42
	v_lshlrev_b32_e32 v43, 1, v43
	v_add3_u32 v42, v43, v229, v42
	v_cvt_f32_i32_e32 v42, v42
	v_mul_f32_e32 v42, v228, v42
	v_lshlrev_b32_e32 v44, 5, v44
	v_lshlrev_b32_e32 v45, 1, v45
	v_add3_u32 v44, v45, v229, v44
	v_cvt_f32_i32_e32 v44, v44
	v_mul_f32_e32 v44, v228, v44
	v_cvt_pk_bf16_f32 v184, v38, v40
	v_cvt_pk_bf16_f32 v185, v42, v44
	ds_read_b128 v[252:255], v156
	s_add_i32 s44, s40, 8
	s_ashr_i32 s45, s44, 31
	s_lshl_b64 s[44:45], s[44:45], 12
	v_lshl_add_u64 v[80:81], v[36:37], 0, s[44:45]
	s_waitcnt lgkmcnt(0)
; #define TR4(p_) __builtin_amdgcn_ds_read_tr4_b64_v2i32((LAS v2i*)(p_))
; #define VDMA(st_, k_) do { _Pragma("unroll") for (int i_ = 0; i_ < 4; ++i_) { \
;         const unsigned off_ = (unsigned)((st_) >> 2) * (16384u * 128u) + (PE_ID(E, 4 * ((st_) & 3) + i_) << 7) + ((i_ & 1) ? cx1 : cx0); \
;         __builtin_amdgcn_global_load_lds((const unsigned*)(V4 + off_), (LAS unsigned*)(ldsb + BUF[k_] + 1024 * i_), 16, 0, 0); } } while (0)
; __device__ __forceinline__ void peer_v_tokens(int j, const LAS unsigned short* EL, const LAS unsigned char* AL  , const LAS float* ASC  , const LAS int* SAL  , ...
;     ...
;         { unsigned ho = (unsigned)t * (D / 4) + (unsigned)lane; asm volatile("" : "+v"(ho)); const uint2* hp = (const uint2*)HB + ho; const float4* gp = (const float4*)fng + lane;
; #pragma unroll
;           for (int jq = 0; jq < 4; ++jq) { hv[jq] = hp[64 * jq]; gv[jq] = gp[64 * jq]; } }
;     ...
;         for (int st = 0; st < 16; ++st) {
;             const int p = st >> 2, q = st & 3;
;             if (st < 14) VDMA(st + 2, (st + 2) % 3);
;             if (st < 14) asm volatile("s_waitcnt vmcnt(8)" ::: "memory");
;             else if (st == 14) asm volatile("s_waitcnt vmcnt(4)" ::: "memory");
;             else asm volatile("s_waitcnt vmcnt(0)" ::: "memory");
;             if (q == 0) {
; #pragma unroll
;                 for (int r = 0; r < 4; ++r) { accH[r] = 0; accL[r] = 0; } }
; #pragma unroll
;             for (int tp = 0; tp < 2; ++tp) {
;                 const v2i ao = TR4(ATL + (2 * q + tp) * 128 + 8 * s16), ah = TR4(ATL + 1024 + (2 * q + tp) * 128 + 8 * s16);
; #pragma unroll
;                 for (int r = 0; r < 4; ++r) {
;                     const v2i d = TR4(ldsb + BUF[st % 3] + 2048 * tp + roff[r]);
;                     accH[r] = __builtin_amdgcn_sdot8(d.x, ah.x, accH[r], false); accH[r] = __builtin_amdgcn_sdot8(d.y, ah.y, accH[r], false);
;                     accL[r] = __builtin_amdgcn_sdot8(d.x, ao.x, accL[r], false); accL[r] = __builtin_amdgcn_sdot8(d.y, ao.y, accL[r], false);
;                 }
	v_mul_f32_e32 v244, v244, v252
	v_mul_f32_e32 v245, v245, v253
	v_mul_f32_e32 v246, v246, v254
	v_mul_f32_e32 v247, v247, v255
	global_store_dwordx4 v[80:81], v[244:247], off offset:2048 nt
	s_add_i32 s43, s40, 16
	s_lshl_b32 s43, s43, 11
	v_add_u32_e32 v138, s43, v66
	global_load_dwordx2 v[194:195], v138, s[70:71]
	global_load_dwordx2 v[196:197], v138, s[70:71] offset:512
	global_load_dwordx2 v[198:199], v138, s[70:71] offset:1024
	global_load_dwordx2 v[200:201], v138, s[70:71] offset:1536
	v_add_u32_e32 v147, 8, v140
	v_and_b32_e32 v146, 15, v147
	v_xor_b32_e32 v146, 8, v146
	v_bfe_u32 v148, v147, 4, 4
	v_mul_lo_u32 v146, v146, s92
	v_mul_lo_u32 v148, v148, s92
	v_mov_b32_e32 v147, v146
	v_mov_b32_e32 v149, v148
	ds_write2st64_b64 v77, v[146:147], v[148:149] offset1:2
	v_add_u32_e32 v138, 0x1000, v74
	ds_read_u8 v139, v138
	v_add_u32_e32 v141, 0x1000, v73
	ds_read_u8 v140, v141
	s_add_i32 s43, s67, 96
	v_mov_b32_e32 v138, s43
	ds_read2st64_b32 v[228:229], v138 offset1:1
	ds_read_b128 v[18:21], v227 offset:8192
	ds_read_b128 v[22:25], v227 offset:8208
	v_mov_b32_e32 v150, v63
	v_mov_b32_e32 v151, v64
	v_mov_b32_e32 v38, 0
	v_mov_b32_e32 v39, 0
	v_mov_b32_e32 v40, 0
	v_mov_b32_e32 v41, 0
	v_mov_b32_e32 v42, 0
	v_mov_b32_e32 v43, 0
	v_mov_b32_e32 v44, 0
	v_mov_b32_e32 v45, 0
	v_and_b32_e32 v78, 0xffff, v31
	v_lshrrev_b32_e32 v79, 16, v31
	v_lshl_add_u32 v78, v78, 7, v152
	v_lshl_add_u32 v79, v79, 7, v153
	s_mov_b32 m0, s99
	s_add_i32 s43, s99, 0x400
	global_load_lds_dwordx4 v78, s[50:51]
	s_mov_b32 m0, s43
	s_nop 0
	global_load_lds_dwordx4 v79, s[50:51]
	s_waitcnt vmcnt(13)
	v_add_u32_e32 v54, s77, v59
	v_add_u32_e32 v55, s77, v60
	v_add_u32_e32 v56, s77, v61
	v_add_u32_e32 v57, s77, v62
	ds_read_b64_tr_b4 v[50:51], v160 offset:128
	ds_read_b64_tr_b4 v[52:53], v160 offset:1152
	ds_read_b64_tr_b4 v[130:131], v54
	ds_read_b64_tr_b4 v[132:133], v55
	ds_read_b64_tr_b4 v[134:135], v56
	ds_read_b64_tr_b4 v[136:137], v57
	s_waitcnt lgkmcnt(13)
	v_dot8c_i32_i4_e32 v38, v122, v48
	v_dot8c_i32_i4_e32 v39, v122, v46
	v_dot8c_i32_i4_e32 v40, v124, v48
	v_dot8c_i32_i4_e32 v41, v124, v46
	v_dot8c_i32_i4_e32 v42, v126, v48
	v_dot8c_i32_i4_e32 v43, v126, v46
	v_dot8c_i32_i4_e32 v44, v128, v48
	v_dot8c_i32_i4_e32 v45, v128, v46
	v_dot8c_i32_i4_e32 v38, v123, v49
	v_dot8c_i32_i4_e32 v39, v123, v47
	v_dot8c_i32_i4_e32 v40, v125, v49
	v_dot8c_i32_i4_e32 v41, v125, v47
	v_dot8c_i32_i4_e32 v42, v127, v49
	v_dot8c_i32_i4_e32 v43, v127, v47
	v_dot8c_i32_i4_e32 v44, v129, v49
	v_dot8c_i32_i4_e32 v45, v129, v47
	v_and_b32_e32 v78, 0xffff, v32
	v_lshrrev_b32_e32 v79, 16, v32
	v_lshl_add_u32 v78, v78, 7, v152
	v_lshl_add_u32 v79, v79, 7, v153
	s_mov_b32 m0, s76
	s_add_i32 s43, s76, 0x400
	global_load_lds_dwordx4 v78, s[50:51]
	s_mov_b32 m0, s43
	s_nop 0
	global_load_lds_dwordx4 v79, s[50:51]
	s_waitcnt vmcnt(13)
	v_add_u32_e32 v54, s78, v59
	v_add_u32_e32 v55, s78, v60
	v_add_u32_e32 v56, s78, v61
	v_add_u32_e32 v57, s78, v62
	ds_read_b64_tr_b4 v[46:47], v160 offset:256
	ds_read_b64_tr_b4 v[48:49], v160 offset:1280
	ds_read_b64_tr_b4 v[122:123], v54
	ds_read_b64_tr_b4 v[124:125], v55
	ds_read_b64_tr_b4 v[126:127], v56
	ds_read_b64_tr_b4 v[128:129], v57
	s_waitcnt lgkmcnt(6)
	v_dot8c_i32_i4_e32 v38, v130, v52
	v_dot8c_i32_i4_e32 v39, v130, v50
	v_dot8c_i32_i4_e32 v40, v132, v52
	v_dot8c_i32_i4_e32 v41, v132, v50
	v_dot8c_i32_i4_e32 v42, v134, v52
	v_dot8c_i32_i4_e32 v43, v134, v50
	v_dot8c_i32_i4_e32 v44, v136, v52
	v_dot8c_i32_i4_e32 v45, v136, v50
	v_dot8c_i32_i4_e32 v38, v131, v53
	v_dot8c_i32_i4_e32 v39, v131, v51
	v_dot8c_i32_i4_e32 v40, v133, v53
	v_dot8c_i32_i4_e32 v41, v133, v51
	v_dot8c_i32_i4_e32 v42, v135, v53
	v_dot8c_i32_i4_e32 v43, v135, v51
	v_dot8c_i32_i4_e32 v44, v137, v53
	v_dot8c_i32_i4_e32 v45, v137, v51
	v_and_b32_e32 v78, 0xffff, v33
	v_lshrrev_b32_e32 v79, 16, v33
	v_lshl_add_u32 v78, v78, 7, v152
	v_lshl_add_u32 v79, v79, 7, v153
	s_mov_b32 m0, s77
	s_add_i32 s43, s77, 0x400
	global_load_lds_dwordx4 v78, s[50:51]
	s_mov_b32 m0, s43
	s_nop 0
	global_load_lds_dwordx4 v79, s[50:51]
	s_waitcnt vmcnt(13)
	v_add_u32_e32 v54, s79, v59
	v_add_u32_e32 v55, s79, v60
	v_add_u32_e32 v56, s79, v61
	v_add_u32_e32 v57, s79, v62
	ds_read_b64_tr_b4 v[50:51], v160 offset:384
	ds_read_b64_tr_b4 v[52:53], v160 offset:1408
	ds_read_b64_tr_b4 v[130:131], v54
	ds_read_b64_tr_b4 v[132:133], v55
	ds_read_b64_tr_b4 v[134:135], v56
	ds_read_b64_tr_b4 v[136:137], v57
	s_waitcnt lgkmcnt(6)
	v_dot8c_i32_i4_e32 v38, v122, v48
	v_dot8c_i32_i4_e32 v39, v122, v46
	v_dot8c_i32_i4_e32 v40, v124, v48
	v_dot8c_i32_i4_e32 v41, v124, v46
	v_dot8c_i32_i4_e32 v42, v126, v48
	v_dot8c_i32_i4_e32 v43, v126, v46
	v_dot8c_i32_i4_e32 v44, v128, v48
	v_dot8c_i32_i4_e32 v45, v128, v46
	v_dot8c_i32_i4_e32 v38, v123, v49
	v_dot8c_i32_i4_e32 v39, v123, v47
	v_dot8c_i32_i4_e32 v40, v125, v49
	v_dot8c_i32_i4_e32 v41, v125, v47
	v_dot8c_i32_i4_e32 v42, v127, v49
	v_dot8c_i32_i4_e32 v43, v127, v47
	v_dot8c_i32_i4_e32 v44, v129, v49
	v_dot8c_i32_i4_e32 v45, v129, v47
	s_waitcnt lgkmcnt(15)
	v_and_b32_e32 v78, 0xffff, v18
	v_lshrrev_b32_e32 v79, 16, v18
	v_lshl_add_u32 v78, v78, 7, v150
	v_lshl_add_u32 v79, v79, 7, v151
	s_mov_b32 m0, s78
	s_add_i32 s43, s78, 0x400
	global_load_lds_dwordx4 v78, s[50:51]
	s_mov_b32 m0, s43
	s_nop 0
	global_load_lds_dwordx4 v79, s[50:51]
	s_waitcnt vmcnt(13)
	v_add_u32_e32 v54, s98, v59
	v_add_u32_e32 v55, s98, v60
	v_add_u32_e32 v56, s98, v61
	v_add_u32_e32 v57, s98, v62
	ds_read_b64_tr_b4 v[46:47], v160 offset:512
	ds_read_b64_tr_b4 v[48:49], v160 offset:1536
	ds_read_b64_tr_b4 v[122:123], v54
	ds_read_b64_tr_b4 v[124:125], v55
	ds_read_b64_tr_b4 v[126:127], v56
	ds_read_b64_tr_b4 v[128:129], v57
	s_waitcnt lgkmcnt(6)
; #define TR4(p_) __builtin_amdgcn_ds_read_tr4_b64_v2i32((LAS v2i*)(p_))
; #define VDMA(st_, k_) do { _Pragma("unroll") for (int i_ = 0; i_ < 4; ++i_) { \
;         const unsigned off_ = (unsigned)((st_) >> 2) * (16384u * 128u) + (PE_ID(E, 4 * ((st_) & 3) + i_) << 7) + ((i_ & 1) ? cx1 : cx0); \
;         __builtin_amdgcn_global_load_lds((const unsigned*)(V4 + off_), (LAS unsigned*)(ldsb + BUF[k_] + 1024 * i_), 16, 0, 0); } } while (0)
; __device__ __forceinline__ void peer_v_tokens(int j, const LAS unsigned short* EL, const LAS unsigned char* AL  , const LAS float* ASC  , const LAS int* SAL  , ...
;     ...
;         for (int st = 0; st < 16; ++st) {
;             const int p = st >> 2, q = st & 3;
;             if (st < 14) VDMA(st + 2, (st + 2) % 3);
;             if (st < 14) asm volatile("s_waitcnt vmcnt(8)" ::: "memory");
;             else if (st == 14) asm volatile("s_waitcnt vmcnt(4)" ::: "memory");
;             else asm volatile("s_waitcnt vmcnt(0)" ::: "memory");
;             if (q == 0) {
; #pragma unroll
;                 for (int r = 0; r < 4; ++r) { accH[r] = 0; accL[r] = 0; } }
; #pragma unroll
;             for (int tp = 0; tp < 2; ++tp) {
;                 const v2i ao = TR4(ATL + (2 * q + tp) * 128 + 8 * s16), ah = TR4(ATL + 1024 + (2 * q + tp) * 128 + 8 * s16);
; #pragma unroll
;                 for (int r = 0; r < 4; ++r) {
;                     const v2i d = TR4(ldsb + BUF[st % 3] + 2048 * tp + roff[r]);
;                     accH[r] = __builtin_amdgcn_sdot8(d.x, ah.x, accH[r], false); accH[r] = __builtin_amdgcn_sdot8(d.y, ah.y, accH[r], false);
;                     accL[r] = __builtin_amdgcn_sdot8(d.x, ao.x, accL[r], false); accL[r] = __builtin_amdgcn_sdot8(d.y, ao.y, accL[r], false);
;                 }
	v_dot8c_i32_i4_e32 v38, v130, v52
	v_dot8c_i32_i4_e32 v39, v130, v50
	v_dot8c_i32_i4_e32 v40, v132, v52
	v_dot8c_i32_i4_e32 v41, v132, v50
	v_dot8c_i32_i4_e32 v42, v134, v52
	v_dot8c_i32_i4_e32 v43, v134, v50
	v_dot8c_i32_i4_e32 v44, v136, v52
	v_dot8c_i32_i4_e32 v45, v136, v50
	v_dot8c_i32_i4_e32 v38, v131, v53
	v_dot8c_i32_i4_e32 v39, v131, v51
	v_dot8c_i32_i4_e32 v40, v133, v53
	v_dot8c_i32_i4_e32 v41, v133, v51
	v_dot8c_i32_i4_e32 v42, v135, v53
	v_dot8c_i32_i4_e32 v43, v135, v51
	v_dot8c_i32_i4_e32 v44, v137, v53
	v_dot8c_i32_i4_e32 v45, v137, v51
	v_and_b32_e32 v78, 0xffff, v19
	v_lshrrev_b32_e32 v79, 16, v19
	v_lshl_add_u32 v78, v78, 7, v150
	v_lshl_add_u32 v79, v79, 7, v151
	s_mov_b32 m0, s79
	s_add_i32 s43, s79, 0x400
	global_load_lds_dwordx4 v78, s[50:51]
	s_mov_b32 m0, s43
	s_nop 0
	global_load_lds_dwordx4 v79, s[50:51]
	s_waitcnt vmcnt(8)
	v_add_u32_e32 v54, s99, v59
	v_add_u32_e32 v55, s99, v60
	v_add_u32_e32 v56, s99, v61
	v_add_u32_e32 v57, s99, v62
	ds_read_b64_tr_b4 v[50:51], v160 offset:640
	ds_read_b64_tr_b4 v[52:53], v160 offset:1664
	ds_read_b64_tr_b4 v[130:131], v54
	ds_read_b64_tr_b4 v[132:133], v55
	ds_read_b64_tr_b4 v[134:135], v56
	ds_read_b64_tr_b4 v[136:137], v57
	s_waitcnt lgkmcnt(6)
	v_dot8c_i32_i4_e32 v38, v122, v48
	v_dot8c_i32_i4_e32 v39, v122, v46
	v_dot8c_i32_i4_e32 v40, v124, v48
	v_dot8c_i32_i4_e32 v41, v124, v46
	v_dot8c_i32_i4_e32 v42, v126, v48
	v_dot8c_i32_i4_e32 v43, v126, v46
	v_dot8c_i32_i4_e32 v44, v128, v48
	v_dot8c_i32_i4_e32 v45, v128, v46
	v_dot8c_i32_i4_e32 v38, v123, v49
	v_dot8c_i32_i4_e32 v39, v123, v47
	v_dot8c_i32_i4_e32 v40, v125, v49
	v_dot8c_i32_i4_e32 v41, v125, v47
	v_dot8c_i32_i4_e32 v42, v127, v49
	v_dot8c_i32_i4_e32 v43, v127, v47
	v_dot8c_i32_i4_e32 v44, v129, v49
	v_dot8c_i32_i4_e32 v45, v129, v47
	s_waitcnt lgkmcnt(15)
	v_add_u32_e32 v143, 8, v139
	v_and_b32_e32 v142, 15, v143
	v_xor_b32_e32 v142, 8, v142
	v_bfe_u32 v144, v143, 4, 4
	v_mul_lo_u32 v142, v142, s92
	v_mul_lo_u32 v144, v144, s92
	v_mov_b32_e32 v143, v142
	v_mov_b32_e32 v145, v144
	ds_write2st64_b64 v159, v[142:143], v[144:145] offset1:2
	v_and_b32_e32 v78, 0xffff, v20
	v_lshrrev_b32_e32 v79, 16, v20
	v_lshl_add_u32 v78, v78, 7, v150
	v_lshl_add_u32 v79, v79, 7, v151
	s_mov_b32 m0, s98
	s_add_i32 s43, s98, 0x400
	global_load_lds_dwordx4 v78, s[50:51]
	s_mov_b32 m0, s43
	s_nop 0
	global_load_lds_dwordx4 v79, s[50:51]
	s_waitcnt vmcnt(8)
	v_add_u32_e32 v54, s76, v59
	v_add_u32_e32 v55, s76, v60
	v_add_u32_e32 v56, s76, v61
	v_add_u32_e32 v57, s76, v62
	ds_read_b64_tr_b4 v[46:47], v160 offset:768
	ds_read_b64_tr_b4 v[48:49], v160 offset:1792
	ds_read_b64_tr_b4 v[122:123], v54
	ds_read_b64_tr_b4 v[124:125], v55
	ds_read_b64_tr_b4 v[126:127], v56
	ds_read_b64_tr_b4 v[128:129], v57
	s_waitcnt lgkmcnt(7)
	v_dot8c_i32_i4_e32 v38, v130, v52
	v_dot8c_i32_i4_e32 v39, v130, v50
	v_dot8c_i32_i4_e32 v40, v132, v52
	v_dot8c_i32_i4_e32 v41, v132, v50
	v_dot8c_i32_i4_e32 v42, v134, v52
	v_dot8c_i32_i4_e32 v43, v134, v50
	v_dot8c_i32_i4_e32 v44, v136, v52
	v_dot8c_i32_i4_e32 v45, v136, v50
	v_dot8c_i32_i4_e32 v38, v131, v53
	v_dot8c_i32_i4_e32 v39, v131, v51
	v_dot8c_i32_i4_e32 v40, v133, v53
	v_dot8c_i32_i4_e32 v41, v133, v51
	v_dot8c_i32_i4_e32 v42, v135, v53
	v_dot8c_i32_i4_e32 v43, v135, v51
	v_dot8c_i32_i4_e32 v44, v137, v53
	v_dot8c_i32_i4_e32 v45, v137, v51
	v_and_b32_e32 v78, 0xffff, v21
	v_lshrrev_b32_e32 v79, 16, v21
	v_lshl_add_u32 v78, v78, 7, v150
	v_lshl_add_u32 v79, v79, 7, v151
	s_mov_b32 m0, s99
	s_add_i32 s43, s99, 0x400
	global_load_lds_dwordx4 v78, s[50:51]
	s_mov_b32 m0, s43
	s_nop 0
	global_load_lds_dwordx4 v79, s[50:51]
	s_waitcnt vmcnt(8)
	v_add_u32_e32 v54, s77, v59
	v_add_u32_e32 v55, s77, v60
	v_add_u32_e32 v56, s77, v61
	v_add_u32_e32 v57, s77, v62
	ds_read_b64_tr_b4 v[50:51], v160 offset:896
	ds_read_b64_tr_b4 v[52:53], v160 offset:1920
	ds_read_b64_tr_b4 v[130:131], v54
	ds_read_b64_tr_b4 v[132:133], v55
	ds_read_b64_tr_b4 v[134:135], v56
	ds_read_b64_tr_b4 v[136:137], v57
	s_waitcnt lgkmcnt(6)
	v_dot8c_i32_i4_e32 v38, v122, v48
	v_dot8c_i32_i4_e32 v39, v122, v46
	v_dot8c_i32_i4_e32 v40, v124, v48
	v_dot8c_i32_i4_e32 v41, v124, v46
	v_dot8c_i32_i4_e32 v42, v126, v48
	v_dot8c_i32_i4_e32 v43, v126, v46
	v_dot8c_i32_i4_e32 v44, v128, v48
	v_dot8c_i32_i4_e32 v45, v128, v46
	v_dot8c_i32_i4_e32 v38, v123, v49
	v_dot8c_i32_i4_e32 v39, v123, v47
	v_dot8c_i32_i4_e32 v40, v125, v49
	v_dot8c_i32_i4_e32 v41, v125, v47
	v_dot8c_i32_i4_e32 v42, v127, v49
	v_dot8c_i32_i4_e32 v43, v127, v47
	v_dot8c_i32_i4_e32 v44, v129, v49
	v_dot8c_i32_i4_e32 v45, v129, v47
	v_and_b32_e32 v78, 0xffff, v22
	v_lshrrev_b32_e32 v79, 16, v22
	v_lshl_add_u32 v78, v78, 7, v150
	v_lshl_add_u32 v79, v79, 7, v151
	s_mov_b32 m0, s76
	s_add_i32 s43, s76, 0x400
	global_load_lds_dwordx4 v78, s[50:51]
	s_mov_b32 m0, s43
	s_nop 0
	global_load_lds_dwordx4 v79, s[50:51]
	s_waitcnt vmcnt(8)
	v_add_u32_e32 v54, s78, v59
	v_add_u32_e32 v55, s78, v60
	v_add_u32_e32 v56, s78, v61
	v_add_u32_e32 v57, s78, v62
	ds_read_b64_tr_b4 v[46:47], v160
	ds_read_b64_tr_b4 v[48:49], v160 offset:1024
	ds_read_b64_tr_b4 v[122:123], v54
	ds_read_b64_tr_b4 v[124:125], v55
	ds_read_b64_tr_b4 v[126:127], v56
	ds_read_b64_tr_b4 v[128:129], v57
	s_waitcnt lgkmcnt(6)
	v_dot8c_i32_i4_e32 v38, v130, v52
	v_dot8c_i32_i4_e32 v39, v130, v50
	v_dot8c_i32_i4_e32 v40, v132, v52
	v_dot8c_i32_i4_e32 v41, v132, v50
	v_dot8c_i32_i4_e32 v42, v134, v52
	v_dot8c_i32_i4_e32 v43, v134, v50
	v_dot8c_i32_i4_e32 v44, v136, v52
	v_dot8c_i32_i4_e32 v45, v136, v50
	v_dot8c_i32_i4_e32 v38, v131, v53
	v_dot8c_i32_i4_e32 v39, v131, v51
	v_dot8c_i32_i4_e32 v40, v133, v53
	v_dot8c_i32_i4_e32 v41, v133, v51
	v_dot8c_i32_i4_e32 v42, v135, v53
	v_dot8c_i32_i4_e32 v43, v135, v51
	v_dot8c_i32_i4_e32 v44, v137, v53
	v_dot8c_i32_i4_e32 v45, v137, v51
	s_nop 3
	s_waitcnt lgkmcnt(15)
; #define LAS __attribute__((address_space(3)))
; __device__ __forceinline__ bf16 f2bf(float f) { return (bf16)f2bfu(f); }
; #define TR4(p_) __builtin_amdgcn_ds_read_tr4_b64_v2i32((LAS v2i*)(p_))
; #define VDMA(st_, k_) do { _Pragma("unroll") for (int i_ = 0; i_ < 4; ++i_) { \
;         const unsigned off_ = (unsigned)((st_) >> 2) * (16384u * 128u) + (PE_ID(E, 4 * ((st_) & 3) + i_) << 7) + ((i_ & 1) ? cx1 : cx0); \
;         __builtin_amdgcn_global_load_lds((const unsigned*)(V4 + off_), (LAS unsigned*)(ldsb + BUF[k_] + 1024 * i_), 16, 0, 0); } } while (0)
; __device__ __forceinline__ void peer_v_tokens(int j, const LAS unsigned short* EL, const LAS unsigned char* AL  , const LAS float* ASC  , const LAS int* SAL  , ...
;     ...
;         for (int st = 0; st < 16; ++st) {
;             const int p = st >> 2, q = st & 3;
;             if (st < 14) VDMA(st + 2, (st + 2) % 3);
;             if (st < 14) asm volatile("s_waitcnt vmcnt(8)" ::: "memory");
;             else if (st == 14) asm volatile("s_waitcnt vmcnt(4)" ::: "memory");
;             else asm volatile("s_waitcnt vmcnt(0)" ::: "memory");
;             if (q == 0) {
; #pragma unroll
;                 for (int r = 0; r < 4; ++r) { accH[r] = 0; accL[r] = 0; } }
; #pragma unroll
;             for (int tp = 0; tp < 2; ++tp) {
;                 const v2i ao = TR4(ATL + (2 * q + tp) * 128 + 8 * s16), ah = TR4(ATL + 1024 + (2 * q + tp) * 128 + 8 * s16);
; #pragma unroll
;                 for (int r = 0; r < 4; ++r) {
;                     const v2i d = TR4(ldsb + BUF[st % 3] + 2048 * tp + roff[r]);
;                     accH[r] = __builtin_amdgcn_sdot8(d.x, ah.x, accH[r], false); accH[r] = __builtin_amdgcn_sdot8(d.y, ah.y, accH[r], false);
;                     accL[r] = __builtin_amdgcn_sdot8(d.x, ao.x, accL[r], false); accL[r] = __builtin_amdgcn_sdot8(d.y, ao.y, accL[r], false);
;                 }
;             }
;             asm volatile("s_waitcnt lgkmcnt(0)" ::: "memory");
;             if (q == 3) {
; #pragma unroll
;                 for (int r = 0; r < 4; ++r) STASH[256 * p + 16 * (grp + 4 * r) + pc] = f2bf(asc * (float)(2 * ((accH[r] << 4) + accL[r]) + sa));
;             }
;     ...
;             for (int jq = 0; jq < 4; ++jq) { typedef unsigned u2v __attribute__((ext_vector_type(2))); const u2v pw = *(const LAS u2v*)(STASH + 4 * lane + 256 * jq); const uint2 hw = hv[jq];
	v_lshlrev_b32_e32 v38, 5, v38
	v_lshlrev_b32_e32 v39, 1, v39
	v_add3_u32 v38, v39, v229, v38
	v_cvt_f32_i32_e32 v38, v38
	v_mul_f32_e32 v38, v228, v38
	v_lshlrev_b32_e32 v40, 5, v40
	v_lshlrev_b32_e32 v41, 1, v41
	v_add3_u32 v40, v41, v229, v40
	v_cvt_f32_i32_e32 v40, v40
	v_mul_f32_e32 v40, v228, v40
	v_lshlrev_b32_e32 v42, 5, v42
	v_lshlrev_b32_e32 v43, 1, v43
	v_add3_u32 v42, v43, v229, v42
	v_cvt_f32_i32_e32 v42, v42
	v_mul_f32_e32 v42, v228, v42
	v_lshlrev_b32_e32 v44, 5, v44
	v_lshlrev_b32_e32 v45, 1, v45
	v_add3_u32 v44, v45, v229, v44
	v_cvt_f32_i32_e32 v44, v44
	v_mul_f32_e32 v44, v228, v44
	v_cvt_pk_bf16_f32 v192, v38, v40
	v_cvt_pk_bf16_f32 v193, v42, v44
	ds_read_b128 v[252:255], v156 offset:1024
	s_add_i32 s44, s40, 8
	s_ashr_i32 s45, s44, 31
	s_lshl_b64 s[44:45], s[44:45], 12
	v_lshl_add_u64 v[80:81], v[36:37], 0, s[44:45]
	s_waitcnt lgkmcnt(0)
	v_mul_f32_e32 v248, v248, v252
	v_mul_f32_e32 v249, v249, v253
	v_mul_f32_e32 v250, v250, v254
	v_mul_f32_e32 v251, v251, v255
	global_store_dwordx4 v[80:81], v[248:251], off offset:3072 nt
	v_add_u32_e32 v147, 8, v140
	v_and_b32_e32 v146, 15, v147
	v_xor_b32_e32 v146, 8, v146
	v_bfe_u32 v148, v147, 4, 4
	v_mul_lo_u32 v146, v146, s92
	v_mul_lo_u32 v148, v148, s92
	v_mov_b32_e32 v147, v146
	v_mov_b32_e32 v149, v148
	ds_write2st64_b64 v77, v[146:147], v[148:149] offset1:2
	v_add_u32_e32 v138, 0x1400, v74
	ds_read_u8 v139, v138
	v_add_u32_e32 v141, 0x1400, v73
	ds_read_u8 v140, v141
	s_add_i32 s43, s67, 128
	v_mov_b32_e32 v138, s43
	ds_read2st64_b32 v[228:229], v138 offset1:1
	ds_read_b128 v[26:29], v227 offset:10240
	ds_read_b128 v[30:33], v227 offset:10256
	v_mov_b32_e32 v38, 0
	v_mov_b32_e32 v39, 0
	v_mov_b32_e32 v40, 0
	v_mov_b32_e32 v41, 0
	v_mov_b32_e32 v42, 0
	v_mov_b32_e32 v43, 0
	v_mov_b32_e32 v44, 0
	v_mov_b32_e32 v45, 0
	v_and_b32_e32 v78, 0xffff, v23
	v_lshrrev_b32_e32 v79, 16, v23
	v_lshl_add_u32 v78, v78, 7, v150
	v_lshl_add_u32 v79, v79, 7, v151
	s_mov_b32 m0, s77
	s_add_i32 s43, s77, 0x400
	global_load_lds_dwordx4 v78, s[50:51]
	s_mov_b32 m0, s43
	s_nop 0
	global_load_lds_dwordx4 v79, s[50:51]
	s_waitcnt vmcnt(9)
	v_add_u32_e32 v54, s79, v59
	v_add_u32_e32 v55, s79, v60
	v_add_u32_e32 v56, s79, v61
	v_add_u32_e32 v57, s79, v62
	ds_read_b64_tr_b4 v[50:51], v160 offset:128
	ds_read_b64_tr_b4 v[52:53], v160 offset:1152
	ds_read_b64_tr_b4 v[130:131], v54
	ds_read_b64_tr_b4 v[132:133], v55
	ds_read_b64_tr_b4 v[134:135], v56
	ds_read_b64_tr_b4 v[136:137], v57
	s_waitcnt lgkmcnt(13)
	v_dot8c_i32_i4_e32 v38, v122, v48
	v_dot8c_i32_i4_e32 v39, v122, v46
	v_dot8c_i32_i4_e32 v40, v124, v48
	v_dot8c_i32_i4_e32 v41, v124, v46
	v_dot8c_i32_i4_e32 v42, v126, v48
	v_dot8c_i32_i4_e32 v43, v126, v46
	v_dot8c_i32_i4_e32 v44, v128, v48
	v_dot8c_i32_i4_e32 v45, v128, v46
	v_dot8c_i32_i4_e32 v38, v123, v49
	v_dot8c_i32_i4_e32 v39, v123, v47
	v_dot8c_i32_i4_e32 v40, v125, v49
	v_dot8c_i32_i4_e32 v41, v125, v47
	v_dot8c_i32_i4_e32 v42, v127, v49
	v_dot8c_i32_i4_e32 v43, v127, v47
	v_dot8c_i32_i4_e32 v44, v129, v49
	v_dot8c_i32_i4_e32 v45, v129, v47
	v_and_b32_e32 v78, 0xffff, v24
	v_lshrrev_b32_e32 v79, 16, v24
	v_lshl_add_u32 v78, v78, 7, v150
	v_lshl_add_u32 v79, v79, 7, v151
	s_mov_b32 m0, s78
	s_add_i32 s43, s78, 0x400
	global_load_lds_dwordx4 v78, s[50:51]
	s_mov_b32 m0, s43
	s_nop 0
	global_load_lds_dwordx4 v79, s[50:51]
	s_waitcnt vmcnt(9)
	v_add_u32_e32 v54, s98, v59
	v_add_u32_e32 v55, s98, v60
	v_add_u32_e32 v56, s98, v61
	v_add_u32_e32 v57, s98, v62
	ds_read_b64_tr_b4 v[46:47], v160 offset:256
	ds_read_b64_tr_b4 v[48:49], v160 offset:1280
	ds_read_b64_tr_b4 v[122:123], v54
	ds_read_b64_tr_b4 v[124:125], v55
	ds_read_b64_tr_b4 v[126:127], v56
	ds_read_b64_tr_b4 v[128:129], v57
	s_waitcnt lgkmcnt(6)
	v_dot8c_i32_i4_e32 v38, v130, v52
	v_dot8c_i32_i4_e32 v39, v130, v50
	v_dot8c_i32_i4_e32 v40, v132, v52
	v_dot8c_i32_i4_e32 v41, v132, v50
	v_dot8c_i32_i4_e32 v42, v134, v52
	v_dot8c_i32_i4_e32 v43, v134, v50
	v_dot8c_i32_i4_e32 v44, v136, v52
	v_dot8c_i32_i4_e32 v45, v136, v50
	v_dot8c_i32_i4_e32 v38, v131, v53
	v_dot8c_i32_i4_e32 v39, v131, v51
	v_dot8c_i32_i4_e32 v40, v133, v53
	v_dot8c_i32_i4_e32 v41, v133, v51
	v_dot8c_i32_i4_e32 v42, v135, v53
	v_dot8c_i32_i4_e32 v43, v135, v51
	v_dot8c_i32_i4_e32 v44, v137, v53
	v_dot8c_i32_i4_e32 v45, v137, v51
	ds_write_b16 v65, v178
	ds_write_b16_d16_hi v65, v178 offset:128
	ds_write_b16 v65, v179 offset:256
	ds_write_b16_d16_hi v65, v179 offset:384
	ds_write_b16 v65, v180 offset:512
	ds_write_b16_d16_hi v65, v180 offset:640
	ds_write_b16 v65, v181 offset:768
	ds_write_b16_d16_hi v65, v181 offset:896
	ds_write_b16 v65, v182 offset:1024
	ds_write_b16_d16_hi v65, v182 offset:1152
	ds_write_b16 v65, v183 offset:1280
	ds_write_b16_d16_hi v65, v183 offset:1408
	ds_write_b16 v65, v184 offset:1536
	ds_write_b16_d16_hi v65, v184 offset:1664
	ds_write_b16 v65, v185 offset:1792
	ds_write_b16_d16_hi v65, v185 offset:1920
	ds_read_b64 v[202:203], v154
	ds_read_b64 v[204:205], v154 offset:512
	ds_read_b64 v[206:207], v154 offset:1024
	ds_read_b64 v[208:209], v154 offset:1536
	v_and_b32_e32 v78, 0xffff, v25
	v_lshrrev_b32_e32 v79, 16, v25
	v_lshl_add_u32 v78, v78, 7, v150
	v_lshl_add_u32 v79, v79, 7, v151
	s_mov_b32 m0, s79
	s_add_i32 s43, s79, 0x400
	global_load_lds_dwordx4 v78, s[50:51]
	s_mov_b32 m0, s43
	s_nop 0
	global_load_lds_dwordx4 v79, s[50:51]
	s_waitcnt vmcnt(9)
	v_add_u32_e32 v54, s99, v59
	v_add_u32_e32 v55, s99, v60
	v_add_u32_e32 v56, s99, v61
	v_add_u32_e32 v57, s99, v62
	ds_read_b64_tr_b4 v[50:51], v160 offset:384
	ds_read_b64_tr_b4 v[52:53], v160 offset:1408
	ds_read_b64_tr_b4 v[130:131], v54
	ds_read_b64_tr_b4 v[132:133], v55
	ds_read_b64_tr_b4 v[134:135], v56
	ds_read_b64_tr_b4 v[136:137], v57
	s_waitcnt lgkmcnt(15)
; #define TR4(p_) __builtin_amdgcn_ds_read_tr4_b64_v2i32((LAS v2i*)(p_))
; #define VDMA(st_, k_) do { _Pragma("unroll") for (int i_ = 0; i_ < 4; ++i_) { \
;         const unsigned off_ = (unsigned)((st_) >> 2) * (16384u * 128u) + (PE_ID(E, 4 * ((st_) & 3) + i_) << 7) + ((i_ & 1) ? cx1 : cx0); \
;         __builtin_amdgcn_global_load_lds((const unsigned*)(V4 + off_), (LAS unsigned*)(ldsb + BUF[k_] + 1024 * i_), 16, 0, 0); } } while (0)
; __device__ __forceinline__ void peer_v_tokens(int j, const LAS unsigned short* EL, const LAS unsigned char* AL  , const LAS float* ASC  , const LAS int* SAL  , ...
;     ...
;         for (int st = 0; st < 16; ++st) {
;             const int p = st >> 2, q = st & 3;
;             if (st < 14) VDMA(st + 2, (st + 2) % 3);
;             if (st < 14) asm volatile("s_waitcnt vmcnt(8)" ::: "memory");
;             else if (st == 14) asm volatile("s_waitcnt vmcnt(4)" ::: "memory");
;             else asm volatile("s_waitcnt vmcnt(0)" ::: "memory");
;             if (q == 0) {
; #pragma unroll
;                 for (int r = 0; r < 4; ++r) { accH[r] = 0; accL[r] = 0; } }
; #pragma unroll
;             for (int tp = 0; tp < 2; ++tp) {
;                 const v2i ao = TR4(ATL + (2 * q + tp) * 128 + 8 * s16), ah = TR4(ATL + 1024 + (2 * q + tp) * 128 + 8 * s16);
; #pragma unroll
;                 for (int r = 0; r < 4; ++r) {
;                     const v2i d = TR4(ldsb + BUF[st % 3] + 2048 * tp + roff[r]);
;                     accH[r] = __builtin_amdgcn_sdot8(d.x, ah.x, accH[r], false); accH[r] = __builtin_amdgcn_sdot8(d.y, ah.y, accH[r], false);
;                     accL[r] = __builtin_amdgcn_sdot8(d.x, ao.x, accL[r], false); accL[r] = __builtin_amdgcn_sdot8(d.y, ao.y, accL[r], false);
;                 }
	v_dot8c_i32_i4_e32 v38, v122, v48
	v_dot8c_i32_i4_e32 v39, v122, v46
	v_dot8c_i32_i4_e32 v40, v124, v48
	v_dot8c_i32_i4_e32 v41, v124, v46
	v_dot8c_i32_i4_e32 v42, v126, v48
	v_dot8c_i32_i4_e32 v43, v126, v46
	v_dot8c_i32_i4_e32 v44, v128, v48
	v_dot8c_i32_i4_e32 v45, v128, v46
	v_dot8c_i32_i4_e32 v38, v123, v49
	v_dot8c_i32_i4_e32 v39, v123, v47
	v_dot8c_i32_i4_e32 v40, v125, v49
	v_dot8c_i32_i4_e32 v41, v125, v47
	v_dot8c_i32_i4_e32 v42, v127, v49
	v_dot8c_i32_i4_e32 v43, v127, v47
	v_dot8c_i32_i4_e32 v44, v129, v49
	v_dot8c_i32_i4_e32 v45, v129, v47
	s_waitcnt lgkmcnt(15)
	v_and_b32_e32 v78, 0xffff, v26
	v_lshrrev_b32_e32 v79, 16, v26
	v_lshl_add_u32 v78, v78, 7, v150
	v_lshl_add_u32 v79, v79, 7, v151
	s_mov_b32 m0, s98
	s_add_i32 s43, s98, 0x400
	global_load_lds_dwordx4 v78, s[50:51]
	s_mov_b32 m0, s43
	s_nop 0
	global_load_lds_dwordx4 v79, s[50:51]
	s_waitcnt vmcnt(9)
	v_add_u32_e32 v54, s76, v59
	v_add_u32_e32 v55, s76, v60
	v_add_u32_e32 v56, s76, v61
	v_add_u32_e32 v57, s76, v62
	ds_read_b64_tr_b4 v[46:47], v160 offset:512
	ds_read_b64_tr_b4 v[48:49], v160 offset:1536
	ds_read_b64_tr_b4 v[122:123], v54
	ds_read_b64_tr_b4 v[124:125], v55
	ds_read_b64_tr_b4 v[126:127], v56
	ds_read_b64_tr_b4 v[128:129], v57
	s_waitcnt lgkmcnt(6)
	v_dot8c_i32_i4_e32 v38, v130, v52
	v_dot8c_i32_i4_e32 v39, v130, v50
	v_dot8c_i32_i4_e32 v40, v132, v52
	v_dot8c_i32_i4_e32 v41, v132, v50
	v_dot8c_i32_i4_e32 v42, v134, v52
	v_dot8c_i32_i4_e32 v43, v134, v50
	v_dot8c_i32_i4_e32 v44, v136, v52
	v_dot8c_i32_i4_e32 v45, v136, v50
	v_dot8c_i32_i4_e32 v38, v131, v53
	v_dot8c_i32_i4_e32 v39, v131, v51
	v_dot8c_i32_i4_e32 v40, v133, v53
	v_dot8c_i32_i4_e32 v41, v133, v51
	v_dot8c_i32_i4_e32 v42, v135, v53
	v_dot8c_i32_i4_e32 v43, v135, v51
	v_dot8c_i32_i4_e32 v44, v137, v53
	v_dot8c_i32_i4_e32 v45, v137, v51
	v_and_b32_e32 v78, 0xffff, v27
	v_lshrrev_b32_e32 v79, 16, v27
	v_lshl_add_u32 v78, v78, 7, v150
	v_lshl_add_u32 v79, v79, 7, v151
	s_mov_b32 m0, s99
	s_add_i32 s43, s99, 0x400
	global_load_lds_dwordx4 v78, s[50:51]
	s_mov_b32 m0, s43
	s_nop 0
	global_load_lds_dwordx4 v79, s[50:51]
	s_waitcnt vmcnt(8)
	v_add_u32_e32 v54, s77, v59
	v_add_u32_e32 v55, s77, v60
	v_add_u32_e32 v56, s77, v61
	v_add_u32_e32 v57, s77, v62
	ds_read_b64_tr_b4 v[50:51], v160 offset:640
	ds_read_b64_tr_b4 v[52:53], v160 offset:1664
	ds_read_b64_tr_b4 v[130:131], v54
	ds_read_b64_tr_b4 v[132:133], v55
	ds_read_b64_tr_b4 v[134:135], v56
	ds_read_b64_tr_b4 v[136:137], v57
	s_waitcnt lgkmcnt(6)
	v_dot8c_i32_i4_e32 v38, v122, v48
	v_dot8c_i32_i4_e32 v39, v122, v46
	v_dot8c_i32_i4_e32 v40, v124, v48
	v_dot8c_i32_i4_e32 v41, v124, v46
	v_dot8c_i32_i4_e32 v42, v126, v48
	v_dot8c_i32_i4_e32 v43, v126, v46
	v_dot8c_i32_i4_e32 v44, v128, v48
	v_dot8c_i32_i4_e32 v45, v128, v46
	v_dot8c_i32_i4_e32 v38, v123, v49
	v_dot8c_i32_i4_e32 v39, v123, v47
	v_dot8c_i32_i4_e32 v40, v125, v49
	v_dot8c_i32_i4_e32 v41, v125, v47
	v_dot8c_i32_i4_e32 v42, v127, v49
	v_dot8c_i32_i4_e32 v43, v127, v47
	v_dot8c_i32_i4_e32 v44, v129, v49
	v_dot8c_i32_i4_e32 v45, v129, v47
	s_waitcnt lgkmcnt(15)
	v_add_u32_e32 v143, 8, v139
	v_and_b32_e32 v142, 15, v143
	v_xor_b32_e32 v142, 8, v142
	v_bfe_u32 v144, v143, 4, 4
	v_mul_lo_u32 v142, v142, s92
	v_mul_lo_u32 v144, v144, s92
	v_mov_b32_e32 v143, v142
	v_mov_b32_e32 v145, v144
	ds_write2st64_b64 v159, v[142:143], v[144:145] offset1:2
	v_and_b32_e32 v78, 0xffff, v28
	v_lshrrev_b32_e32 v79, 16, v28
	v_lshl_add_u32 v78, v78, 7, v150
	v_lshl_add_u32 v79, v79, 7, v151
	s_mov_b32 m0, s76
	s_add_i32 s43, s76, 0x400
	global_load_lds_dwordx4 v78, s[50:51]
	s_mov_b32 m0, s43
	s_nop 0
	global_load_lds_dwordx4 v79, s[50:51]
	s_waitcnt vmcnt(8)
	v_add_u32_e32 v54, s78, v59
	v_add_u32_e32 v55, s78, v60
	v_add_u32_e32 v56, s78, v61
	v_add_u32_e32 v57, s78, v62
	ds_read_b64_tr_b4 v[46:47], v160 offset:768
	ds_read_b64_tr_b4 v[48:49], v160 offset:1792
	ds_read_b64_tr_b4 v[122:123], v54
	ds_read_b64_tr_b4 v[124:125], v55
	ds_read_b64_tr_b4 v[126:127], v56
	ds_read_b64_tr_b4 v[128:129], v57
	s_waitcnt lgkmcnt(7)
	v_dot8c_i32_i4_e32 v38, v130, v52
	v_dot8c_i32_i4_e32 v39, v130, v50
	v_dot8c_i32_i4_e32 v40, v132, v52
	v_dot8c_i32_i4_e32 v41, v132, v50
	v_dot8c_i32_i4_e32 v42, v134, v52
	v_dot8c_i32_i4_e32 v43, v134, v50
	v_dot8c_i32_i4_e32 v44, v136, v52
	v_dot8c_i32_i4_e32 v45, v136, v50
	v_dot8c_i32_i4_e32 v38, v131, v53
	v_dot8c_i32_i4_e32 v39, v131, v51
	v_dot8c_i32_i4_e32 v40, v133, v53
	v_dot8c_i32_i4_e32 v41, v133, v51
	v_dot8c_i32_i4_e32 v42, v135, v53
	v_dot8c_i32_i4_e32 v43, v135, v51
	v_dot8c_i32_i4_e32 v44, v137, v53
	v_dot8c_i32_i4_e32 v45, v137, v51
	v_and_b32_e32 v78, 0xffff, v29
	v_lshrrev_b32_e32 v79, 16, v29
	v_lshl_add_u32 v78, v78, 7, v150
	v_lshl_add_u32 v79, v79, 7, v151
	s_mov_b32 m0, s77
	s_add_i32 s43, s77, 0x400
	global_load_lds_dwordx4 v78, s[50:51]
	s_mov_b32 m0, s43
	s_nop 0
	global_load_lds_dwordx4 v79, s[50:51]
	s_waitcnt vmcnt(8)
	v_add_u32_e32 v54, s79, v59
	v_add_u32_e32 v55, s79, v60
	v_add_u32_e32 v56, s79, v61
	v_add_u32_e32 v57, s79, v62
	ds_read_b64_tr_b4 v[50:51], v160 offset:896
	ds_read_b64_tr_b4 v[52:53], v160 offset:1920
	ds_read_b64_tr_b4 v[130:131], v54
	ds_read_b64_tr_b4 v[132:133], v55
	ds_read_b64_tr_b4 v[134:135], v56
	ds_read_b64_tr_b4 v[136:137], v57
	s_waitcnt lgkmcnt(6)
; #define LAS __attribute__((address_space(3)))
; __device__ __forceinline__ void peer_v_tokens(int j, const LAS unsigned short* EL, const LAS unsigned char* AL  , const LAS float* ASC  , const LAS int* SAL  , ...
;     ...
;         for (int st = 0; st < 16; ++st) {
;             const int p = st >> 2, q = st & 3;
;             if (st < 14) VDMA(st + 2, (st + 2) % 3);
;             if (st < 14) asm volatile("s_waitcnt vmcnt(8)" ::: "memory");
;             else if (st == 14) asm volatile("s_waitcnt vmcnt(4)" ::: "memory");
;             else asm volatile("s_waitcnt vmcnt(0)" ::: "memory");
;             if (q == 0) {
; #pragma unroll
;                 for (int r = 0; r < 4; ++r) { accH[r] = 0; accL[r] = 0; } }
; #pragma unroll
;             for (int tp = 0; tp < 2; ++tp) {
;                 const v2i ao = TR4(ATL + (2 * q + tp) * 128 + 8 * s16), ah = TR4(ATL + 1024 + (2 * q + tp) * 128 + 8 * s16);
; #pragma unroll
;                 for (int r = 0; r < 4; ++r) {
;                     const v2i d = TR4(ldsb + BUF[st % 3] + 2048 * tp + roff[r]);
;                     accH[r] = __builtin_amdgcn_sdot8(d.x, ah.x, accH[r], false); accH[r] = __builtin_amdgcn_sdot8(d.y, ah.y, accH[r], false);
;                     accL[r] = __builtin_amdgcn_sdot8(d.x, ao.x, accL[r], false); accL[r] = __builtin_amdgcn_sdot8(d.y, ao.y, accL[r], false);
;                 }
;             }
;             asm volatile("s_waitcnt lgkmcnt(0)" ::: "memory");
;             if (q == 3) {
; #pragma unroll
;                 for (int r = 0; r < 4; ++r) STASH[256 * p + 16 * (grp + 4 * r) + pc] = f2bf(asc * (float)(2 * ((accH[r] << 4) + accL[r]) + sa));
;             }
;     ...
;         {
;             float4 v[4]; float ss = 0.f;
; #pragma unroll
;             for (int jq = 0; jq < 4; ++jq) { typedef unsigned u2v __attribute__((ext_vector_type(2))); const u2v pw = *(const LAS u2v*)(STASH + 4 * lane + 256 * jq); const uint2 hw = hv[jq];
;                 v[jq] = make_float4(__uint_as_float(hw.x << 16) + __uint_as_float(pw.x << 16), __uint_as_float(hw.x & 0xffff0000u) + __uint_as_float(pw.x & 0xffff0000u),
;                                     __uint_as_float(hw.y << 16) + __uint_as_float(pw.y << 16), __uint_as_float(hw.y & 0xffff0000u) + __uint_as_float(pw.y & 0xffff0000u));
;                 ss += v[jq].x * v[jq].x + v[jq].y * v[jq].y + v[jq].z * v[jq].z + v[jq].w * v[jq].w; }
	v_dot8c_i32_i4_e32 v38, v122, v48
	v_dot8c_i32_i4_e32 v39, v122, v46
	v_dot8c_i32_i4_e32 v40, v124, v48
	v_dot8c_i32_i4_e32 v41, v124, v46
	v_dot8c_i32_i4_e32 v42, v126, v48
	v_dot8c_i32_i4_e32 v43, v126, v46
	v_dot8c_i32_i4_e32 v44, v128, v48
	v_dot8c_i32_i4_e32 v45, v128, v46
	v_dot8c_i32_i4_e32 v38, v123, v49
	v_dot8c_i32_i4_e32 v39, v123, v47
	v_dot8c_i32_i4_e32 v40, v125, v49
	v_dot8c_i32_i4_e32 v41, v125, v47
	v_dot8c_i32_i4_e32 v42, v127, v49
	v_dot8c_i32_i4_e32 v43, v127, v47
	v_dot8c_i32_i4_e32 v44, v129, v49
	v_dot8c_i32_i4_e32 v45, v129, v47
	v_and_b32_e32 v78, 0xffff, v30
	v_lshrrev_b32_e32 v79, 16, v30
	v_lshl_add_u32 v78, v78, 7, v150
	v_lshl_add_u32 v79, v79, 7, v151
	s_mov_b32 m0, s78
	s_add_i32 s43, s78, 0x400
	global_load_lds_dwordx4 v78, s[50:51]
	s_mov_b32 m0, s43
	s_nop 0
	global_load_lds_dwordx4 v79, s[50:51]
	s_waitcnt vmcnt(8)
	v_add_u32_e32 v54, s98, v59
	v_add_u32_e32 v55, s98, v60
	v_add_u32_e32 v56, s98, v61
	v_add_u32_e32 v57, s98, v62
	ds_read_b64_tr_b4 v[46:47], v160
	ds_read_b64_tr_b4 v[48:49], v160 offset:1024
	ds_read_b64_tr_b4 v[122:123], v54
	ds_read_b64_tr_b4 v[124:125], v55
	ds_read_b64_tr_b4 v[126:127], v56
	ds_read_b64_tr_b4 v[128:129], v57
	s_waitcnt lgkmcnt(6)
	v_dot8c_i32_i4_e32 v38, v130, v52
	v_dot8c_i32_i4_e32 v39, v130, v50
	v_dot8c_i32_i4_e32 v40, v132, v52
	v_dot8c_i32_i4_e32 v41, v132, v50
	v_dot8c_i32_i4_e32 v42, v134, v52
	v_dot8c_i32_i4_e32 v43, v134, v50
	v_dot8c_i32_i4_e32 v44, v136, v52
	v_dot8c_i32_i4_e32 v45, v136, v50
	v_dot8c_i32_i4_e32 v38, v131, v53
	v_dot8c_i32_i4_e32 v39, v131, v51
	v_dot8c_i32_i4_e32 v40, v133, v53
	v_dot8c_i32_i4_e32 v41, v133, v51
	v_dot8c_i32_i4_e32 v42, v135, v53
	v_dot8c_i32_i4_e32 v43, v135, v51
	v_dot8c_i32_i4_e32 v44, v137, v53
	v_dot8c_i32_i4_e32 v45, v137, v51
	s_nop 3
	s_waitcnt lgkmcnt(15)
	v_lshlrev_b32_e32 v38, 5, v38
	v_lshlrev_b32_e32 v39, 1, v39
	v_add3_u32 v38, v39, v229, v38
	v_cvt_f32_i32_e32 v38, v38
	v_mul_f32_e32 v38, v228, v38
	v_lshlrev_b32_e32 v40, 5, v40
	v_lshlrev_b32_e32 v41, 1, v41
	v_add3_u32 v40, v41, v229, v40
	v_cvt_f32_i32_e32 v40, v40
	v_mul_f32_e32 v40, v228, v40
	v_lshlrev_b32_e32 v42, 5, v42
	v_lshlrev_b32_e32 v43, 1, v43
	v_add3_u32 v42, v43, v229, v42
	v_cvt_f32_i32_e32 v42, v42
	v_mul_f32_e32 v42, v228, v42
	v_lshlrev_b32_e32 v44, 5, v44
	v_lshlrev_b32_e32 v45, 1, v45
	v_add3_u32 v44, v45, v229, v44
	v_cvt_f32_i32_e32 v44, v44
	v_mul_f32_e32 v44, v228, v44
	v_cvt_pk_bf16_f32 v162, v38, v40
	v_cvt_pk_bf16_f32 v163, v42, v44
	v_add_u32_e32 v147, 8, v140
	v_and_b32_e32 v146, 15, v147
	v_xor_b32_e32 v146, 8, v146
	v_bfe_u32 v148, v147, 4, 4
	v_mul_lo_u32 v146, v146, s92
	v_mul_lo_u32 v148, v148, s92
	v_mov_b32_e32 v147, v146
	v_mov_b32_e32 v149, v148
	ds_write2st64_b64 v77, v[146:147], v[148:149] offset1:2
	v_add_u32_e32 v138, 0x1000, v74
	ds_read_u8 v139, v138
	v_add_u32_e32 v141, 0x1000, v73
	ds_read_u8 v140, v141
	s_add_i32 s43, s67, 160
	v_mov_b32_e32 v138, s43
	ds_read2st64_b32 v[228:229], v138 offset1:1
	ds_read_b128 v[18:21], v227 offset:8192
	ds_read_b128 v[22:25], v227 offset:8208
	v_add_u32_e32 v152, 0x200000, v63
	v_add_u32_e32 v153, 0x200000, v64
	v_mov_b32_e32 v38, 0
	v_mov_b32_e32 v39, 0
	v_mov_b32_e32 v40, 0
	v_mov_b32_e32 v41, 0
	v_mov_b32_e32 v42, 0
	v_mov_b32_e32 v43, 0
	v_mov_b32_e32 v44, 0
	v_mov_b32_e32 v45, 0
	v_and_b32_e32 v78, 0xffff, v31
	v_lshrrev_b32_e32 v79, 16, v31
	v_lshl_add_u32 v78, v78, 7, v150
	v_lshl_add_u32 v79, v79, 7, v151
	s_mov_b32 m0, s79
	s_add_i32 s43, s79, 0x400
	global_load_lds_dwordx4 v78, s[50:51]
	s_mov_b32 m0, s43
	s_nop 0
	global_load_lds_dwordx4 v79, s[50:51]
	s_waitcnt vmcnt(8)
	v_add_u32_e32 v54, s99, v59
	v_add_u32_e32 v55, s99, v60
	v_add_u32_e32 v56, s99, v61
	v_add_u32_e32 v57, s99, v62
	ds_read_b64_tr_b4 v[50:51], v160 offset:128
	ds_read_b64_tr_b4 v[52:53], v160 offset:1152
	ds_read_b64_tr_b4 v[130:131], v54
	ds_read_b64_tr_b4 v[132:133], v55
	ds_read_b64_tr_b4 v[134:135], v56
	ds_read_b64_tr_b4 v[136:137], v57
	s_waitcnt lgkmcnt(12)
	s_waitcnt vmcnt(35) lgkmcnt(15)
	v_lshlrev_b32_e32 v210, 16, v194
	v_and_b32_e32 v211, 0xffff0000, v194
	v_lshlrev_b32_e32 v142, 16, v202
	v_and_b32_e32 v143, 0xffff0000, v202
	v_add_f32_e32 v210, v210, v142
	v_add_f32_e32 v211, v211, v143
	v_lshlrev_b32_e32 v212, 16, v195
	v_and_b32_e32 v213, 0xffff0000, v195
	v_lshlrev_b32_e32 v142, 16, v203
	v_and_b32_e32 v143, 0xffff0000, v203
	v_add_f32_e32 v212, v212, v142
	v_add_f32_e32 v213, v213, v143
	v_lshlrev_b32_e32 v214, 16, v196
	v_and_b32_e32 v215, 0xffff0000, v196
	v_lshlrev_b32_e32 v142, 16, v204
	v_and_b32_e32 v143, 0xffff0000, v204
	v_add_f32_e32 v214, v214, v142
	v_add_f32_e32 v215, v215, v143
	v_lshlrev_b32_e32 v216, 16, v197
	v_and_b32_e32 v217, 0xffff0000, v197
	v_lshlrev_b32_e32 v142, 16, v205
	v_and_b32_e32 v143, 0xffff0000, v205
	v_add_f32_e32 v216, v216, v142
	v_add_f32_e32 v217, v217, v143
	v_lshlrev_b32_e32 v218, 16, v198
	v_and_b32_e32 v219, 0xffff0000, v198
	v_lshlrev_b32_e32 v142, 16, v206
	v_and_b32_e32 v143, 0xffff0000, v206
	v_add_f32_e32 v218, v218, v142
	v_add_f32_e32 v219, v219, v143
	v_lshlrev_b32_e32 v220, 16, v199
	v_and_b32_e32 v221, 0xffff0000, v199
	v_lshlrev_b32_e32 v142, 16, v207
	v_and_b32_e32 v143, 0xffff0000, v207
	v_add_f32_e32 v220, v220, v142
	v_add_f32_e32 v221, v221, v143
	v_lshlrev_b32_e32 v222, 16, v200
	v_and_b32_e32 v223, 0xffff0000, v200
	v_lshlrev_b32_e32 v142, 16, v208
	v_and_b32_e32 v143, 0xffff0000, v208
	v_add_f32_e32 v222, v222, v142
	v_add_f32_e32 v223, v223, v143
	v_lshlrev_b32_e32 v224, 16, v201
	v_and_b32_e32 v225, 0xffff0000, v201
	v_lshlrev_b32_e32 v142, 16, v209
	v_and_b32_e32 v143, 0xffff0000, v209
	v_add_f32_e32 v224, v224, v142
; #define LAS __attribute__((address_space(3)))
; __device__ __forceinline__ void peer_v_tokens(int j, const LAS unsigned short* EL, const LAS unsigned char* AL  , const LAS float* ASC  , const LAS int* SAL  , ...
;     ...
;         {
;             float4 v[4]; float ss = 0.f;
; #pragma unroll
;             for (int jq = 0; jq < 4; ++jq) { typedef unsigned u2v __attribute__((ext_vector_type(2))); const u2v pw = *(const LAS u2v*)(STASH + 4 * lane + 256 * jq); const uint2 hw = hv[jq];
;                 v[jq] = make_float4(__uint_as_float(hw.x << 16) + __uint_as_float(pw.x << 16), __uint_as_float(hw.x & 0xffff0000u) + __uint_as_float(pw.x & 0xffff0000u),
;                                     __uint_as_float(hw.y << 16) + __uint_as_float(pw.y << 16), __uint_as_float(hw.y & 0xffff0000u) + __uint_as_float(pw.y & 0xffff0000u));
;                 ss += v[jq].x * v[jq].x + v[jq].y * v[jq].y + v[jq].z * v[jq].z + v[jq].w * v[jq].w; }
;             ss = wave_sum(ss);
;             const float r3 = rsqrtf(ss * (1.f / D) + EPS);
	v_add_f32_e32 v225, v225, v143
	v_mov_b32_e32 v144, 0
	v_mul_f32_e32 v145, v210, v210
	v_fmac_f32_e32 v145, v211, v211
	v_fmac_f32_e32 v145, v212, v212
	v_fmac_f32_e32 v145, v213, v213
	v_add_f32_e32 v144, v144, v145
	v_mul_f32_e32 v145, v214, v214
	v_fmac_f32_e32 v145, v215, v215
	v_fmac_f32_e32 v145, v216, v216
	v_fmac_f32_e32 v145, v217, v217
	v_add_f32_e32 v144, v144, v145
	v_mul_f32_e32 v145, v218, v218
	v_fmac_f32_e32 v145, v219, v219
	v_fmac_f32_e32 v145, v220, v220
	v_fmac_f32_e32 v145, v221, v221
	v_add_f32_e32 v144, v144, v145
	v_mul_f32_e32 v145, v222, v222
	v_fmac_f32_e32 v145, v223, v223
	v_fmac_f32_e32 v145, v224, v224
	v_fmac_f32_e32 v145, v225, v225
	v_add_f32_e32 v144, v144, v145
	s_nop 1
	v_add_f32_dpp v144, v144, v144 quad_perm:[1,0,3,2] row_mask:0xf bank_mask:0xf bound_ctrl:1
	s_nop 1
	v_add_f32_dpp v144, v144, v144 quad_perm:[2,3,0,1] row_mask:0xf bank_mask:0xf bound_ctrl:1
	s_nop 1
	v_add_f32_dpp v144, v144, v144 row_half_mirror row_mask:0xf bank_mask:0xf bound_ctrl:1
	s_nop 1
	v_add_f32_dpp v144, v144, v144 row_mirror row_mask:0xf bank_mask:0xf bound_ctrl:1
	s_nop 1
	v_readlane_b32 s10, v144, 0
	v_readlane_b32 s11, v144, 16
	v_readlane_b32 s14, v144, 32
	v_readlane_b32 s15, v144, 48
	s_nop 3
	v_mov_b32_e32 v144, s11
	v_mov_b32_e32 v145, s15
	v_add_f32_e32 v144, s10, v144
	v_add_f32_e32 v145, s14, v145
	v_add_f32_e32 v144, v144, v145
	v_fmamk_f32 v144, v144, 0x3a800000, v111
	v_rsq_f32_e32 v144, v144
	s_nop 0
	v_mul_f32_e32 v210, v210, v144
	v_mul_f32_e32 v211, v211, v144
	v_mul_f32_e32 v212, v212, v144
	v_mul_f32_e32 v213, v213, v144
	v_mul_f32_e32 v214, v214, v144
	v_mul_f32_e32 v215, v215, v144
	v_mul_f32_e32 v216, v216, v144
	v_mul_f32_e32 v217, v217, v144
	v_mul_f32_e32 v218, v218, v144
	v_mul_f32_e32 v219, v219, v144
	v_mul_f32_e32 v220, v220, v144
	v_mul_f32_e32 v221, v221, v144
	v_mul_f32_e32 v222, v222, v144
	v_mul_f32_e32 v223, v223, v144
	v_mul_f32_e32 v224, v224, v144
	v_mul_f32_e32 v225, v225, v144
	v_dot8c_i32_i4_e32 v38, v122, v48
	v_dot8c_i32_i4_e32 v39, v122, v46
	v_dot8c_i32_i4_e32 v40, v124, v48
	v_dot8c_i32_i4_e32 v41, v124, v46
	v_dot8c_i32_i4_e32 v42, v126, v48
	v_dot8c_i32_i4_e32 v43, v126, v46
	v_dot8c_i32_i4_e32 v44, v128, v48
	v_dot8c_i32_i4_e32 v45, v128, v46
	v_dot8c_i32_i4_e32 v38, v123, v49
	v_dot8c_i32_i4_e32 v39, v123, v47
	v_dot8c_i32_i4_e32 v40, v125, v49
	v_dot8c_i32_i4_e32 v41, v125, v47
	v_dot8c_i32_i4_e32 v42, v127, v49
	v_dot8c_i32_i4_e32 v43, v127, v47
	v_dot8c_i32_i4_e32 v44, v129, v49
	v_dot8c_i32_i4_e32 v45, v129, v47
	v_and_b32_e32 v78, 0xffff, v32
	v_lshrrev_b32_e32 v79, 16, v32
	v_lshl_add_u32 v78, v78, 7, v150
	v_lshl_add_u32 v79, v79, 7, v151
	s_mov_b32 m0, s98
	s_add_i32 s43, s98, 0x400
	global_load_lds_dwordx4 v78, s[50:51]
	s_mov_b32 m0, s43
	s_nop 0
	global_load_lds_dwordx4 v79, s[50:51]
	s_waitcnt vmcnt(8)
	v_add_u32_e32 v54, s76, v59
	v_add_u32_e32 v55, s76, v60
	v_add_u32_e32 v56, s76, v61
	v_add_u32_e32 v57, s76, v62
	ds_read_b64_tr_b4 v[46:47], v160 offset:256
	ds_read_b64_tr_b4 v[48:49], v160 offset:1280
	ds_read_b64_tr_b4 v[122:123], v54
	ds_read_b64_tr_b4 v[124:125], v55
	ds_read_b64_tr_b4 v[126:127], v56
	ds_read_b64_tr_b4 v[128:129], v57
	s_waitcnt lgkmcnt(6)
	v_dot8c_i32_i4_e32 v38, v130, v52
	v_dot8c_i32_i4_e32 v39, v130, v50
	v_dot8c_i32_i4_e32 v40, v132, v52
	v_dot8c_i32_i4_e32 v41, v132, v50
	v_dot8c_i32_i4_e32 v42, v134, v52
	v_dot8c_i32_i4_e32 v43, v134, v50
	v_dot8c_i32_i4_e32 v44, v136, v52
	v_dot8c_i32_i4_e32 v45, v136, v50
	v_dot8c_i32_i4_e32 v38, v131, v53
	v_dot8c_i32_i4_e32 v39, v131, v51
	v_dot8c_i32_i4_e32 v40, v133, v53
	v_dot8c_i32_i4_e32 v41, v133, v51
	v_dot8c_i32_i4_e32 v42, v135, v53
	v_dot8c_i32_i4_e32 v43, v135, v51
	v_dot8c_i32_i4_e32 v44, v137, v53
	v_dot8c_i32_i4_e32 v45, v137, v51
	v_and_b32_e32 v78, 0xffff, v33
	v_lshrrev_b32_e32 v79, 16, v33
	v_lshl_add_u32 v78, v78, 7, v150
	v_lshl_add_u32 v79, v79, 7, v151
	s_mov_b32 m0, s99
	s_add_i32 s43, s99, 0x400
	global_load_lds_dwordx4 v78, s[50:51]
	s_mov_b32 m0, s43
	s_nop 0
	global_load_lds_dwordx4 v79, s[50:51]
	s_waitcnt vmcnt(8)
	v_add_u32_e32 v54, s77, v59
	v_add_u32_e32 v55, s77, v60
	v_add_u32_e32 v56, s77, v61
	v_add_u32_e32 v57, s77, v62
	ds_read_b64_tr_b4 v[50:51], v160 offset:384
	ds_read_b64_tr_b4 v[52:53], v160 offset:1408
	ds_read_b64_tr_b4 v[130:131], v54
	ds_read_b64_tr_b4 v[132:133], v55
	ds_read_b64_tr_b4 v[134:135], v56
	ds_read_b64_tr_b4 v[136:137], v57
	s_waitcnt lgkmcnt(6)
	v_dot8c_i32_i4_e32 v38, v122, v48
	v_dot8c_i32_i4_e32 v39, v122, v46
	v_dot8c_i32_i4_e32 v40, v124, v48
	v_dot8c_i32_i4_e32 v41, v124, v46
	v_dot8c_i32_i4_e32 v42, v126, v48
	v_dot8c_i32_i4_e32 v43, v126, v46
	v_dot8c_i32_i4_e32 v44, v128, v48
	v_dot8c_i32_i4_e32 v45, v128, v46
	v_dot8c_i32_i4_e32 v38, v123, v49
	v_dot8c_i32_i4_e32 v39, v123, v47
	v_dot8c_i32_i4_e32 v40, v125, v49
	v_dot8c_i32_i4_e32 v41, v125, v47
	v_dot8c_i32_i4_e32 v42, v127, v49
	v_dot8c_i32_i4_e32 v43, v127, v47
	v_dot8c_i32_i4_e32 v44, v129, v49
	v_dot8c_i32_i4_e32 v45, v129, v47
	s_waitcnt lgkmcnt(15)
	v_and_b32_e32 v78, 0xffff, v18
	v_lshrrev_b32_e32 v79, 16, v18
	v_lshl_add_u32 v78, v78, 7, v152
	v_lshl_add_u32 v79, v79, 7, v153
	s_mov_b32 m0, s76
	s_add_i32 s43, s76, 0x400
	global_load_lds_dwordx4 v78, s[50:51]
	s_mov_b32 m0, s43
	s_nop 0
	global_load_lds_dwordx4 v79, s[50:51]
	s_waitcnt vmcnt(8)
	v_add_u32_e32 v54, s78, v59
	v_add_u32_e32 v55, s78, v60
	v_add_u32_e32 v56, s78, v61
	v_add_u32_e32 v57, s78, v62
	ds_read_b64_tr_b4 v[46:47], v160 offset:512
	ds_read_b64_tr_b4 v[48:49], v160 offset:1536
	ds_read_b64_tr_b4 v[122:123], v54
	ds_read_b64_tr_b4 v[124:125], v55
	ds_read_b64_tr_b4 v[126:127], v56
	ds_read_b64_tr_b4 v[128:129], v57
	s_waitcnt lgkmcnt(6)
; #define TR4(p_) __builtin_amdgcn_ds_read_tr4_b64_v2i32((LAS v2i*)(p_))
; #define VDMA(st_, k_) do { _Pragma("unroll") for (int i_ = 0; i_ < 4; ++i_) { \
;         const unsigned off_ = (unsigned)((st_) >> 2) * (16384u * 128u) + (PE_ID(E, 4 * ((st_) & 3) + i_) << 7) + ((i_ & 1) ? cx1 : cx0); \
;         __builtin_amdgcn_global_load_lds((const unsigned*)(V4 + off_), (LAS unsigned*)(ldsb + BUF[k_] + 1024 * i_), 16, 0, 0); } } while (0)
; __device__ __forceinline__ void peer_v_tokens(int j, const LAS unsigned short* EL, const LAS unsigned char* AL  , const LAS float* ASC  , const LAS int* SAL  , ...
;     ...
;         for (int st = 0; st < 16; ++st) {
;             const int p = st >> 2, q = st & 3;
;             if (st < 14) VDMA(st + 2, (st + 2) % 3);
;             if (st < 14) asm volatile("s_waitcnt vmcnt(8)" ::: "memory");
;             else if (st == 14) asm volatile("s_waitcnt vmcnt(4)" ::: "memory");
;             else asm volatile("s_waitcnt vmcnt(0)" ::: "memory");
;             if (q == 0) {
; #pragma unroll
;                 for (int r = 0; r < 4; ++r) { accH[r] = 0; accL[r] = 0; } }
; #pragma unroll
;             for (int tp = 0; tp < 2; ++tp) {
;                 const v2i ao = TR4(ATL + (2 * q + tp) * 128 + 8 * s16), ah = TR4(ATL + 1024 + (2 * q + tp) * 128 + 8 * s16);
; #pragma unroll
;                 for (int r = 0; r < 4; ++r) {
;                     const v2i d = TR4(ldsb + BUF[st % 3] + 2048 * tp + roff[r]);
;                     accH[r] = __builtin_amdgcn_sdot8(d.x, ah.x, accH[r], false); accH[r] = __builtin_amdgcn_sdot8(d.y, ah.y, accH[r], false);
;                     accL[r] = __builtin_amdgcn_sdot8(d.x, ao.x, accL[r], false); accL[r] = __builtin_amdgcn_sdot8(d.y, ao.y, accL[r], false);
;                 }
	v_dot8c_i32_i4_e32 v38, v130, v52
	v_dot8c_i32_i4_e32 v39, v130, v50
	v_dot8c_i32_i4_e32 v40, v132, v52
	v_dot8c_i32_i4_e32 v41, v132, v50
	v_dot8c_i32_i4_e32 v42, v134, v52
	v_dot8c_i32_i4_e32 v43, v134, v50
	v_dot8c_i32_i4_e32 v44, v136, v52
	v_dot8c_i32_i4_e32 v45, v136, v50
	v_dot8c_i32_i4_e32 v38, v131, v53
	v_dot8c_i32_i4_e32 v39, v131, v51
	v_dot8c_i32_i4_e32 v40, v133, v53
	v_dot8c_i32_i4_e32 v41, v133, v51
	v_dot8c_i32_i4_e32 v42, v135, v53
	v_dot8c_i32_i4_e32 v43, v135, v51
	v_dot8c_i32_i4_e32 v44, v137, v53
	v_dot8c_i32_i4_e32 v45, v137, v51
	v_and_b32_e32 v78, 0xffff, v19
	v_lshrrev_b32_e32 v79, 16, v19
	v_lshl_add_u32 v78, v78, 7, v152
	v_lshl_add_u32 v79, v79, 7, v153
	s_mov_b32 m0, s77
	s_add_i32 s43, s77, 0x400
	global_load_lds_dwordx4 v78, s[50:51]
	s_mov_b32 m0, s43
	s_nop 0
	global_load_lds_dwordx4 v79, s[50:51]
	s_waitcnt vmcnt(8)
	v_add_u32_e32 v54, s79, v59
	v_add_u32_e32 v55, s79, v60
	v_add_u32_e32 v56, s79, v61
	v_add_u32_e32 v57, s79, v62
	ds_read_b64_tr_b4 v[50:51], v160 offset:640
	ds_read_b64_tr_b4 v[52:53], v160 offset:1664
	ds_read_b64_tr_b4 v[130:131], v54
	ds_read_b64_tr_b4 v[132:133], v55
	ds_read_b64_tr_b4 v[134:135], v56
	ds_read_b64_tr_b4 v[136:137], v57
	s_waitcnt lgkmcnt(6)
	v_dot8c_i32_i4_e32 v38, v122, v48
	v_dot8c_i32_i4_e32 v39, v122, v46
	v_dot8c_i32_i4_e32 v40, v124, v48
	v_dot8c_i32_i4_e32 v41, v124, v46
	v_dot8c_i32_i4_e32 v42, v126, v48
	v_dot8c_i32_i4_e32 v43, v126, v46
	v_dot8c_i32_i4_e32 v44, v128, v48
	v_dot8c_i32_i4_e32 v45, v128, v46
	v_dot8c_i32_i4_e32 v38, v123, v49
	v_dot8c_i32_i4_e32 v39, v123, v47
	v_dot8c_i32_i4_e32 v40, v125, v49
	v_dot8c_i32_i4_e32 v41, v125, v47
	v_dot8c_i32_i4_e32 v42, v127, v49
	v_dot8c_i32_i4_e32 v43, v127, v47
	v_dot8c_i32_i4_e32 v44, v129, v49
	v_dot8c_i32_i4_e32 v45, v129, v47
	s_waitcnt lgkmcnt(15)
	v_add_u32_e32 v143, 8, v139
	v_and_b32_e32 v142, 15, v143
	v_xor_b32_e32 v142, 8, v142
	v_bfe_u32 v144, v143, 4, 4
	v_mul_lo_u32 v142, v142, s92
	v_mul_lo_u32 v144, v144, s92
	v_mov_b32_e32 v143, v142
	v_mov_b32_e32 v145, v144
	ds_write2st64_b64 v159, v[142:143], v[144:145] offset1:2
	v_and_b32_e32 v78, 0xffff, v20
	v_lshrrev_b32_e32 v79, 16, v20
	v_lshl_add_u32 v78, v78, 7, v152
	v_lshl_add_u32 v79, v79, 7, v153
	s_mov_b32 m0, s78
	s_add_i32 s43, s78, 0x400
	global_load_lds_dwordx4 v78, s[50:51]
	s_mov_b32 m0, s43
	s_nop 0
	global_load_lds_dwordx4 v79, s[50:51]
	s_waitcnt vmcnt(8)
	v_add_u32_e32 v54, s98, v59
	v_add_u32_e32 v55, s98, v60
	v_add_u32_e32 v56, s98, v61
	v_add_u32_e32 v57, s98, v62
	ds_read_b64_tr_b4 v[46:47], v160 offset:768
	ds_read_b64_tr_b4 v[48:49], v160 offset:1792
	ds_read_b64_tr_b4 v[122:123], v54
	ds_read_b64_tr_b4 v[124:125], v55
	ds_read_b64_tr_b4 v[126:127], v56
	ds_read_b64_tr_b4 v[128:129], v57
	s_waitcnt lgkmcnt(7)
	v_dot8c_i32_i4_e32 v38, v130, v52
	v_dot8c_i32_i4_e32 v39, v130, v50
	v_dot8c_i32_i4_e32 v40, v132, v52
	v_dot8c_i32_i4_e32 v41, v132, v50
	v_dot8c_i32_i4_e32 v42, v134, v52
	v_dot8c_i32_i4_e32 v43, v134, v50
	v_dot8c_i32_i4_e32 v44, v136, v52
	v_dot8c_i32_i4_e32 v45, v136, v50
	v_dot8c_i32_i4_e32 v38, v131, v53
	v_dot8c_i32_i4_e32 v39, v131, v51
	v_dot8c_i32_i4_e32 v40, v133, v53
	v_dot8c_i32_i4_e32 v41, v133, v51
	v_dot8c_i32_i4_e32 v42, v135, v53
	v_dot8c_i32_i4_e32 v43, v135, v51
	v_dot8c_i32_i4_e32 v44, v137, v53
	v_dot8c_i32_i4_e32 v45, v137, v51
	v_and_b32_e32 v78, 0xffff, v21
	v_lshrrev_b32_e32 v79, 16, v21
	v_lshl_add_u32 v78, v78, 7, v152
	v_lshl_add_u32 v79, v79, 7, v153
	s_mov_b32 m0, s79
	s_add_i32 s43, s79, 0x400
	global_load_lds_dwordx4 v78, s[50:51]
	s_mov_b32 m0, s43
	s_nop 0
	global_load_lds_dwordx4 v79, s[50:51]
	s_waitcnt vmcnt(8)
	v_add_u32_e32 v54, s99, v59
	v_add_u32_e32 v55, s99, v60
	v_add_u32_e32 v56, s99, v61
	v_add_u32_e32 v57, s99, v62
	ds_read_b64_tr_b4 v[50:51], v160 offset:896
	ds_read_b64_tr_b4 v[52:53], v160 offset:1920
	ds_read_b64_tr_b4 v[130:131], v54
	ds_read_b64_tr_b4 v[132:133], v55
	ds_read_b64_tr_b4 v[134:135], v56
	ds_read_b64_tr_b4 v[136:137], v57
	s_waitcnt lgkmcnt(6)
	v_dot8c_i32_i4_e32 v38, v122, v48
	v_dot8c_i32_i4_e32 v39, v122, v46
	v_dot8c_i32_i4_e32 v40, v124, v48
	v_dot8c_i32_i4_e32 v41, v124, v46
	v_dot8c_i32_i4_e32 v42, v126, v48
	v_dot8c_i32_i4_e32 v43, v126, v46
	v_dot8c_i32_i4_e32 v44, v128, v48
	v_dot8c_i32_i4_e32 v45, v128, v46
	v_dot8c_i32_i4_e32 v38, v123, v49
	v_dot8c_i32_i4_e32 v39, v123, v47
	v_dot8c_i32_i4_e32 v40, v125, v49
	v_dot8c_i32_i4_e32 v41, v125, v47
	v_dot8c_i32_i4_e32 v42, v127, v49
	v_dot8c_i32_i4_e32 v43, v127, v47
	v_dot8c_i32_i4_e32 v44, v129, v49
	v_dot8c_i32_i4_e32 v45, v129, v47
	v_and_b32_e32 v78, 0xffff, v22
	v_lshrrev_b32_e32 v79, 16, v22
	v_lshl_add_u32 v78, v78, 7, v152
	v_lshl_add_u32 v79, v79, 7, v153
	s_mov_b32 m0, s98
	s_add_i32 s43, s98, 0x400
	global_load_lds_dwordx4 v78, s[50:51]
	s_mov_b32 m0, s43
	s_nop 0
	global_load_lds_dwordx4 v79, s[50:51]
	s_waitcnt vmcnt(8)
	v_add_u32_e32 v54, s76, v59
	v_add_u32_e32 v55, s76, v60
	v_add_u32_e32 v56, s76, v61
	v_add_u32_e32 v57, s76, v62
	ds_read_b64_tr_b4 v[46:47], v160
	ds_read_b64_tr_b4 v[48:49], v160 offset:1024
	ds_read_b64_tr_b4 v[122:123], v54
	ds_read_b64_tr_b4 v[124:125], v55
	ds_read_b64_tr_b4 v[126:127], v56
	ds_read_b64_tr_b4 v[128:129], v57
	s_waitcnt lgkmcnt(6)
	v_dot8c_i32_i4_e32 v38, v130, v52
	v_dot8c_i32_i4_e32 v39, v130, v50
	v_dot8c_i32_i4_e32 v40, v132, v52
	v_dot8c_i32_i4_e32 v41, v132, v50
	v_dot8c_i32_i4_e32 v42, v134, v52
	v_dot8c_i32_i4_e32 v43, v134, v50
	v_dot8c_i32_i4_e32 v44, v136, v52
	v_dot8c_i32_i4_e32 v45, v136, v50
	v_dot8c_i32_i4_e32 v38, v131, v53
	v_dot8c_i32_i4_e32 v39, v131, v51
	v_dot8c_i32_i4_e32 v40, v133, v53
	v_dot8c_i32_i4_e32 v41, v133, v51
	v_dot8c_i32_i4_e32 v42, v135, v53
	v_dot8c_i32_i4_e32 v43, v135, v51
	v_dot8c_i32_i4_e32 v44, v137, v53
	v_dot8c_i32_i4_e32 v45, v137, v51
	s_nop 3
	s_waitcnt lgkmcnt(15)
; __device__ __forceinline__ bf16 f2bf(float f) { return (bf16)f2bfu(f); }
; __device__ __forceinline__ void peer_v_tokens(int j, const LAS unsigned short* EL, const LAS unsigned char* AL  , const LAS float* ASC  , const LAS int* SAL  , ...
;     ...
;         { unsigned ho = (unsigned)t * (D / 4) + (unsigned)lane; asm volatile("" : "+v"(ho)); const uint2* hp = (const uint2*)HB + ho; const float4* gp = (const float4*)fng + lane;
; #pragma unroll
;           for (int jq = 0; jq < 4; ++jq) { hv[jq] = hp[64 * jq]; gv[jq] = gp[64 * jq]; } }
;     ...
;         for (int st = 0; st < 16; ++st) {
;             const int p = st >> 2, q = st & 3;
;             if (st < 14) VDMA(st + 2, (st + 2) % 3);
;             if (st < 14) asm volatile("s_waitcnt vmcnt(8)" ::: "memory");
;             else if (st == 14) asm volatile("s_waitcnt vmcnt(4)" ::: "memory");
;             else asm volatile("s_waitcnt vmcnt(0)" ::: "memory");
;             if (q == 0) {
; #pragma unroll
;                 for (int r = 0; r < 4; ++r) { accH[r] = 0; accL[r] = 0; } }
; #pragma unroll
;             for (int tp = 0; tp < 2; ++tp) {
;                 const v2i ao = TR4(ATL + (2 * q + tp) * 128 + 8 * s16), ah = TR4(ATL + 1024 + (2 * q + tp) * 128 + 8 * s16);
; #pragma unroll
;                 for (int r = 0; r < 4; ++r) {
;                     const v2i d = TR4(ldsb + BUF[st % 3] + 2048 * tp + roff[r]);
;                     accH[r] = __builtin_amdgcn_sdot8(d.x, ah.x, accH[r], false); accH[r] = __builtin_amdgcn_sdot8(d.y, ah.y, accH[r], false);
;                     accL[r] = __builtin_amdgcn_sdot8(d.x, ao.x, accL[r], false); accL[r] = __builtin_amdgcn_sdot8(d.y, ao.y, accL[r], false);
;                 }
;             }
;             asm volatile("s_waitcnt lgkmcnt(0)" ::: "memory");
;             if (q == 3) {
; #pragma unroll
;                 for (int r = 0; r < 4; ++r) STASH[256 * p + 16 * (grp + 4 * r) + pc] = f2bf(asc * (float)(2 * ((accH[r] << 4) + accL[r]) + sa));
;             }
;     ...
;             float4* op = (float4*)(outp + (size_t)t * D) + lane;
; #pragma unroll
;             for (int jq = 0; jq < 4; ++jq) { typedef float f4v __attribute__((ext_vector_type(4))); f4v o4; o4.x = v[jq].x * r3 * gv[jq].x; o4.y = v[jq].y * r3 * gv[jq].y; o4.z = v[jq].z * r3 * gv[jq].z; o4.w = v[jq].w * r3 * gv[jq].w;
;                 __builtin_nontemporal_store(o4, (f4v*)op + 64 * jq); }
	v_lshlrev_b32_e32 v38, 5, v38
	v_lshlrev_b32_e32 v39, 1, v39
	v_add3_u32 v38, v39, v229, v38
	v_cvt_f32_i32_e32 v38, v38
	v_mul_f32_e32 v38, v228, v38
	v_lshlrev_b32_e32 v40, 5, v40
	v_lshlrev_b32_e32 v41, 1, v41
	v_add3_u32 v40, v41, v229, v40
	v_cvt_f32_i32_e32 v40, v40
	v_mul_f32_e32 v40, v228, v40
	v_lshlrev_b32_e32 v42, 5, v42
	v_lshlrev_b32_e32 v43, 1, v43
	v_add3_u32 v42, v43, v229, v42
	v_cvt_f32_i32_e32 v42, v42
	v_mul_f32_e32 v42, v228, v42
	v_lshlrev_b32_e32 v44, 5, v44
	v_lshlrev_b32_e32 v45, 1, v45
	v_add3_u32 v44, v45, v229, v44
	v_cvt_f32_i32_e32 v44, v44
	v_mul_f32_e32 v44, v228, v44
	v_cvt_pk_bf16_f32 v170, v38, v40
	v_cvt_pk_bf16_f32 v171, v42, v44
	ds_read_b128 v[252:255], v155
	s_add_i32 s44, s40, 16
	s_ashr_i32 s45, s44, 31
	s_lshl_b64 s[44:45], s[44:45], 12
	v_lshl_add_u64 v[80:81], v[36:37], 0, s[44:45]
	s_waitcnt lgkmcnt(0)
	v_mul_f32_e32 v210, v210, v252
	v_mul_f32_e32 v211, v211, v253
	v_mul_f32_e32 v212, v212, v254
	v_mul_f32_e32 v213, v213, v255
	global_store_dwordx4 v[80:81], v[210:213], off nt
	s_add_i32 s43, s40, 24
	s_lshl_b32 s43, s43, 11
	v_add_u32_e32 v138, s43, v66
	global_load_dwordx2 v[194:195], v138, s[70:71]
	global_load_dwordx2 v[196:197], v138, s[70:71] offset:512
	global_load_dwordx2 v[198:199], v138, s[70:71] offset:1024
	global_load_dwordx2 v[200:201], v138, s[70:71] offset:1536
	v_add_u32_e32 v147, 8, v140
	v_and_b32_e32 v146, 15, v147
	v_xor_b32_e32 v146, 8, v146
	v_bfe_u32 v148, v147, 4, 4
	v_mul_lo_u32 v146, v146, s92
	v_mul_lo_u32 v148, v148, s92
	v_mov_b32_e32 v147, v146
	v_mov_b32_e32 v149, v148
	ds_write2st64_b64 v77, v[146:147], v[148:149] offset1:2
	v_add_u32_e32 v138, 0x1400, v74
	ds_read_u8 v139, v138
	v_add_u32_e32 v141, 0x1400, v73
	ds_read_u8 v140, v141
	s_add_i32 s43, s67, 128
	v_mov_b32_e32 v138, s43
	ds_read2st64_b32 v[228:229], v138 offset1:1
	ds_read_b128 v[26:29], v227 offset:10240
	ds_read_b128 v[30:33], v227 offset:10256
	v_mov_b32_e32 v38, 0
	v_mov_b32_e32 v39, 0
	v_mov_b32_e32 v40, 0
	v_mov_b32_e32 v41, 0
	v_mov_b32_e32 v42, 0
	v_mov_b32_e32 v43, 0
	v_mov_b32_e32 v44, 0
	v_mov_b32_e32 v45, 0
	v_and_b32_e32 v78, 0xffff, v23
	v_lshrrev_b32_e32 v79, 16, v23
	v_lshl_add_u32 v78, v78, 7, v152
	v_lshl_add_u32 v79, v79, 7, v153
	s_mov_b32 m0, s99
	s_add_i32 s43, s99, 0x400
	global_load_lds_dwordx4 v78, s[50:51]
	s_mov_b32 m0, s43
	s_nop 0
	global_load_lds_dwordx4 v79, s[50:51]
	s_waitcnt vmcnt(13)
	v_add_u32_e32 v54, s77, v59
	v_add_u32_e32 v55, s77, v60
	v_add_u32_e32 v56, s77, v61
	v_add_u32_e32 v57, s77, v62
	ds_read_b64_tr_b4 v[50:51], v160 offset:128
	ds_read_b64_tr_b4 v[52:53], v160 offset:1152
	ds_read_b64_tr_b4 v[130:131], v54
	ds_read_b64_tr_b4 v[132:133], v55
	ds_read_b64_tr_b4 v[134:135], v56
	ds_read_b64_tr_b4 v[136:137], v57
	s_waitcnt lgkmcnt(13)
	v_dot8c_i32_i4_e32 v38, v122, v48
	v_dot8c_i32_i4_e32 v39, v122, v46
	v_dot8c_i32_i4_e32 v40, v124, v48
	v_dot8c_i32_i4_e32 v41, v124, v46
	v_dot8c_i32_i4_e32 v42, v126, v48
	v_dot8c_i32_i4_e32 v43, v126, v46
	v_dot8c_i32_i4_e32 v44, v128, v48
	v_dot8c_i32_i4_e32 v45, v128, v46
	v_dot8c_i32_i4_e32 v38, v123, v49
	v_dot8c_i32_i4_e32 v39, v123, v47
	v_dot8c_i32_i4_e32 v40, v125, v49
	v_dot8c_i32_i4_e32 v41, v125, v47
	v_dot8c_i32_i4_e32 v42, v127, v49
	v_dot8c_i32_i4_e32 v43, v127, v47
	v_dot8c_i32_i4_e32 v44, v129, v49
	v_dot8c_i32_i4_e32 v45, v129, v47
	v_and_b32_e32 v78, 0xffff, v24
	v_lshrrev_b32_e32 v79, 16, v24
	v_lshl_add_u32 v78, v78, 7, v152
	v_lshl_add_u32 v79, v79, 7, v153
	s_mov_b32 m0, s76
	s_add_i32 s43, s76, 0x400
	global_load_lds_dwordx4 v78, s[50:51]
	s_mov_b32 m0, s43
	s_nop 0
	global_load_lds_dwordx4 v79, s[50:51]
	s_waitcnt vmcnt(13)
	v_add_u32_e32 v54, s78, v59
	v_add_u32_e32 v55, s78, v60
	v_add_u32_e32 v56, s78, v61
	v_add_u32_e32 v57, s78, v62
	ds_read_b64_tr_b4 v[46:47], v160 offset:256
	ds_read_b64_tr_b4 v[48:49], v160 offset:1280
	ds_read_b64_tr_b4 v[122:123], v54
	ds_read_b64_tr_b4 v[124:125], v55
	ds_read_b64_tr_b4 v[126:127], v56
	ds_read_b64_tr_b4 v[128:129], v57
	s_waitcnt lgkmcnt(6)
	v_dot8c_i32_i4_e32 v38, v130, v52
	v_dot8c_i32_i4_e32 v39, v130, v50
	v_dot8c_i32_i4_e32 v40, v132, v52
	v_dot8c_i32_i4_e32 v41, v132, v50
	v_dot8c_i32_i4_e32 v42, v134, v52
	v_dot8c_i32_i4_e32 v43, v134, v50
	v_dot8c_i32_i4_e32 v44, v136, v52
	v_dot8c_i32_i4_e32 v45, v136, v50
	v_dot8c_i32_i4_e32 v38, v131, v53
	v_dot8c_i32_i4_e32 v39, v131, v51
	v_dot8c_i32_i4_e32 v40, v133, v53
	v_dot8c_i32_i4_e32 v41, v133, v51
	v_dot8c_i32_i4_e32 v42, v135, v53
	v_dot8c_i32_i4_e32 v43, v135, v51
	v_dot8c_i32_i4_e32 v44, v137, v53
	v_dot8c_i32_i4_e32 v45, v137, v51
	v_and_b32_e32 v78, 0xffff, v25
	v_lshrrev_b32_e32 v79, 16, v25
	v_lshl_add_u32 v78, v78, 7, v152
	v_lshl_add_u32 v79, v79, 7, v153
	s_mov_b32 m0, s77
	s_add_i32 s43, s77, 0x400
	global_load_lds_dwordx4 v78, s[50:51]
	s_mov_b32 m0, s43
	s_nop 0
	global_load_lds_dwordx4 v79, s[50:51]
	s_waitcnt vmcnt(13)
	v_add_u32_e32 v54, s79, v59
	v_add_u32_e32 v55, s79, v60
	v_add_u32_e32 v56, s79, v61
	v_add_u32_e32 v57, s79, v62
	ds_read_b64_tr_b4 v[50:51], v160 offset:384
	ds_read_b64_tr_b4 v[52:53], v160 offset:1408
	ds_read_b64_tr_b4 v[130:131], v54
	ds_read_b64_tr_b4 v[132:133], v55
	ds_read_b64_tr_b4 v[134:135], v56
	ds_read_b64_tr_b4 v[136:137], v57
	s_waitcnt lgkmcnt(6)
	v_dot8c_i32_i4_e32 v38, v122, v48
	v_dot8c_i32_i4_e32 v39, v122, v46
	v_dot8c_i32_i4_e32 v40, v124, v48
	v_dot8c_i32_i4_e32 v41, v124, v46
	v_dot8c_i32_i4_e32 v42, v126, v48
	v_dot8c_i32_i4_e32 v43, v126, v46
	v_dot8c_i32_i4_e32 v44, v128, v48
	v_dot8c_i32_i4_e32 v45, v128, v46
	v_dot8c_i32_i4_e32 v38, v123, v49
	v_dot8c_i32_i4_e32 v39, v123, v47
	v_dot8c_i32_i4_e32 v40, v125, v49
	v_dot8c_i32_i4_e32 v41, v125, v47
	v_dot8c_i32_i4_e32 v42, v127, v49
	v_dot8c_i32_i4_e32 v43, v127, v47
	v_dot8c_i32_i4_e32 v44, v129, v49
	v_dot8c_i32_i4_e32 v45, v129, v47
	s_waitcnt lgkmcnt(15)
; #define TR4(p_) __builtin_amdgcn_ds_read_tr4_b64_v2i32((LAS v2i*)(p_))
; #define VDMA(st_, k_) do { _Pragma("unroll") for (int i_ = 0; i_ < 4; ++i_) { \
;         const unsigned off_ = (unsigned)((st_) >> 2) * (16384u * 128u) + (PE_ID(E, 4 * ((st_) & 3) + i_) << 7) + ((i_ & 1) ? cx1 : cx0); \
;         __builtin_amdgcn_global_load_lds((const unsigned*)(V4 + off_), (LAS unsigned*)(ldsb + BUF[k_] + 1024 * i_), 16, 0, 0); } } while (0)
; __device__ __forceinline__ void peer_v_tokens(int j, const LAS unsigned short* EL, const LAS unsigned char* AL  , const LAS float* ASC  , const LAS int* SAL  , ...
;     ...
;         for (int st = 0; st < 16; ++st) {
;             const int p = st >> 2, q = st & 3;
;             if (st < 14) VDMA(st + 2, (st + 2) % 3);
;             if (st < 14) asm volatile("s_waitcnt vmcnt(8)" ::: "memory");
;             else if (st == 14) asm volatile("s_waitcnt vmcnt(4)" ::: "memory");
;             else asm volatile("s_waitcnt vmcnt(0)" ::: "memory");
;             if (q == 0) {
; #pragma unroll
;                 for (int r = 0; r < 4; ++r) { accH[r] = 0; accL[r] = 0; } }
; #pragma unroll
;             for (int tp = 0; tp < 2; ++tp) {
;                 const v2i ao = TR4(ATL + (2 * q + tp) * 128 + 8 * s16), ah = TR4(ATL + 1024 + (2 * q + tp) * 128 + 8 * s16);
; #pragma unroll
;                 for (int r = 0; r < 4; ++r) {
;                     const v2i d = TR4(ldsb + BUF[st % 3] + 2048 * tp + roff[r]);
;                     accH[r] = __builtin_amdgcn_sdot8(d.x, ah.x, accH[r], false); accH[r] = __builtin_amdgcn_sdot8(d.y, ah.y, accH[r], false);
;                     accL[r] = __builtin_amdgcn_sdot8(d.x, ao.x, accL[r], false); accL[r] = __builtin_amdgcn_sdot8(d.y, ao.y, accL[r], false);
;                 }
	v_and_b32_e32 v78, 0xffff, v26
	v_lshrrev_b32_e32 v79, 16, v26
	v_lshl_add_u32 v78, v78, 7, v152
	v_lshl_add_u32 v79, v79, 7, v153
	s_mov_b32 m0, s78
	s_add_i32 s43, s78, 0x400
	global_load_lds_dwordx4 v78, s[50:51]
	s_mov_b32 m0, s43
	s_nop 0
	global_load_lds_dwordx4 v79, s[50:51]
	s_waitcnt vmcnt(13)
	v_add_u32_e32 v54, s98, v59
	v_add_u32_e32 v55, s98, v60
	v_add_u32_e32 v56, s98, v61
	v_add_u32_e32 v57, s98, v62
	ds_read_b64_tr_b4 v[46:47], v160 offset:512
	ds_read_b64_tr_b4 v[48:49], v160 offset:1536
	ds_read_b64_tr_b4 v[122:123], v54
	ds_read_b64_tr_b4 v[124:125], v55
	ds_read_b64_tr_b4 v[126:127], v56
	ds_read_b64_tr_b4 v[128:129], v57
	s_waitcnt lgkmcnt(6)
	v_dot8c_i32_i4_e32 v38, v130, v52
	v_dot8c_i32_i4_e32 v39, v130, v50
	v_dot8c_i32_i4_e32 v40, v132, v52
	v_dot8c_i32_i4_e32 v41, v132, v50
	v_dot8c_i32_i4_e32 v42, v134, v52
	v_dot8c_i32_i4_e32 v43, v134, v50
	v_dot8c_i32_i4_e32 v44, v136, v52
	v_dot8c_i32_i4_e32 v45, v136, v50
	v_dot8c_i32_i4_e32 v38, v131, v53
	v_dot8c_i32_i4_e32 v39, v131, v51
	v_dot8c_i32_i4_e32 v40, v133, v53
	v_dot8c_i32_i4_e32 v41, v133, v51
	v_dot8c_i32_i4_e32 v42, v135, v53
	v_dot8c_i32_i4_e32 v43, v135, v51
	v_dot8c_i32_i4_e32 v44, v137, v53
	v_dot8c_i32_i4_e32 v45, v137, v51
	v_and_b32_e32 v78, 0xffff, v27
	v_lshrrev_b32_e32 v79, 16, v27
	v_lshl_add_u32 v78, v78, 7, v152
	v_lshl_add_u32 v79, v79, 7, v153
	s_mov_b32 m0, s79
	s_add_i32 s43, s79, 0x400
	global_load_lds_dwordx4 v78, s[50:51]
	s_mov_b32 m0, s43
	s_nop 0
	global_load_lds_dwordx4 v79, s[50:51]
	s_waitcnt vmcnt(8)
	v_add_u32_e32 v54, s99, v59
	v_add_u32_e32 v55, s99, v60
	v_add_u32_e32 v56, s99, v61
	v_add_u32_e32 v57, s99, v62
	ds_read_b64_tr_b4 v[50:51], v160 offset:640
	ds_read_b64_tr_b4 v[52:53], v160 offset:1664
	ds_read_b64_tr_b4 v[130:131], v54
	ds_read_b64_tr_b4 v[132:133], v55
	ds_read_b64_tr_b4 v[134:135], v56
	ds_read_b64_tr_b4 v[136:137], v57
	s_waitcnt lgkmcnt(6)
	v_dot8c_i32_i4_e32 v38, v122, v48
	v_dot8c_i32_i4_e32 v39, v122, v46
	v_dot8c_i32_i4_e32 v40, v124, v48
	v_dot8c_i32_i4_e32 v41, v124, v46
	v_dot8c_i32_i4_e32 v42, v126, v48
	v_dot8c_i32_i4_e32 v43, v126, v46
	v_dot8c_i32_i4_e32 v44, v128, v48
	v_dot8c_i32_i4_e32 v45, v128, v46
	v_dot8c_i32_i4_e32 v38, v123, v49
	v_dot8c_i32_i4_e32 v39, v123, v47
	v_dot8c_i32_i4_e32 v40, v125, v49
	v_dot8c_i32_i4_e32 v41, v125, v47
	v_dot8c_i32_i4_e32 v42, v127, v49
	v_dot8c_i32_i4_e32 v43, v127, v47
	v_dot8c_i32_i4_e32 v44, v129, v49
	v_dot8c_i32_i4_e32 v45, v129, v47
	s_waitcnt lgkmcnt(15)
	v_add_u32_e32 v143, 8, v139
	v_and_b32_e32 v142, 15, v143
	v_xor_b32_e32 v142, 8, v142
	v_bfe_u32 v144, v143, 4, 4
	v_mul_lo_u32 v142, v142, s92
	v_mul_lo_u32 v144, v144, s92
	v_mov_b32_e32 v143, v142
	v_mov_b32_e32 v145, v144
	ds_write2st64_b64 v159, v[142:143], v[144:145] offset1:2
	v_and_b32_e32 v78, 0xffff, v28
	v_lshrrev_b32_e32 v79, 16, v28
	v_lshl_add_u32 v78, v78, 7, v152
	v_lshl_add_u32 v79, v79, 7, v153
	s_mov_b32 m0, s98
	s_add_i32 s43, s98, 0x400
	global_load_lds_dwordx4 v78, s[50:51]
	s_mov_b32 m0, s43
	s_nop 0
	global_load_lds_dwordx4 v79, s[50:51]
	s_waitcnt vmcnt(8)
	v_add_u32_e32 v54, s76, v59
	v_add_u32_e32 v55, s76, v60
	v_add_u32_e32 v56, s76, v61
	v_add_u32_e32 v57, s76, v62
	ds_read_b64_tr_b4 v[46:47], v160 offset:768
	ds_read_b64_tr_b4 v[48:49], v160 offset:1792
	ds_read_b64_tr_b4 v[122:123], v54
	ds_read_b64_tr_b4 v[124:125], v55
	ds_read_b64_tr_b4 v[126:127], v56
	ds_read_b64_tr_b4 v[128:129], v57
	s_waitcnt lgkmcnt(7)
	v_dot8c_i32_i4_e32 v38, v130, v52
	v_dot8c_i32_i4_e32 v39, v130, v50
	v_dot8c_i32_i4_e32 v40, v132, v52
	v_dot8c_i32_i4_e32 v41, v132, v50
	v_dot8c_i32_i4_e32 v42, v134, v52
	v_dot8c_i32_i4_e32 v43, v134, v50
	v_dot8c_i32_i4_e32 v44, v136, v52
	v_dot8c_i32_i4_e32 v45, v136, v50
	v_dot8c_i32_i4_e32 v38, v131, v53
	v_dot8c_i32_i4_e32 v39, v131, v51
	v_dot8c_i32_i4_e32 v40, v133, v53
	v_dot8c_i32_i4_e32 v41, v133, v51
	v_dot8c_i32_i4_e32 v42, v135, v53
	v_dot8c_i32_i4_e32 v43, v135, v51
	v_dot8c_i32_i4_e32 v44, v137, v53
	v_dot8c_i32_i4_e32 v45, v137, v51
	v_and_b32_e32 v78, 0xffff, v29
	v_lshrrev_b32_e32 v79, 16, v29
	v_lshl_add_u32 v78, v78, 7, v152
	v_lshl_add_u32 v79, v79, 7, v153
	s_mov_b32 m0, s99
	s_add_i32 s43, s99, 0x400
	global_load_lds_dwordx4 v78, s[50:51]
	s_mov_b32 m0, s43
	s_nop 0
	global_load_lds_dwordx4 v79, s[50:51]
	s_waitcnt vmcnt(8)
	v_add_u32_e32 v54, s77, v59
	v_add_u32_e32 v55, s77, v60
	v_add_u32_e32 v56, s77, v61
	v_add_u32_e32 v57, s77, v62
	ds_read_b64_tr_b4 v[50:51], v160 offset:896
	ds_read_b64_tr_b4 v[52:53], v160 offset:1920
	ds_read_b64_tr_b4 v[130:131], v54
	ds_read_b64_tr_b4 v[132:133], v55
	ds_read_b64_tr_b4 v[134:135], v56
	ds_read_b64_tr_b4 v[136:137], v57
	s_waitcnt lgkmcnt(6)
	v_dot8c_i32_i4_e32 v38, v122, v48
	v_dot8c_i32_i4_e32 v39, v122, v46
	v_dot8c_i32_i4_e32 v40, v124, v48
	v_dot8c_i32_i4_e32 v41, v124, v46
	v_dot8c_i32_i4_e32 v42, v126, v48
	v_dot8c_i32_i4_e32 v43, v126, v46
	v_dot8c_i32_i4_e32 v44, v128, v48
	v_dot8c_i32_i4_e32 v45, v128, v46
	v_dot8c_i32_i4_e32 v38, v123, v49
	v_dot8c_i32_i4_e32 v39, v123, v47
	v_dot8c_i32_i4_e32 v40, v125, v49
	v_dot8c_i32_i4_e32 v41, v125, v47
	v_dot8c_i32_i4_e32 v42, v127, v49
	v_dot8c_i32_i4_e32 v43, v127, v47
	v_dot8c_i32_i4_e32 v44, v129, v49
	v_dot8c_i32_i4_e32 v45, v129, v47
	v_and_b32_e32 v78, 0xffff, v30
	v_lshrrev_b32_e32 v79, 16, v30
	v_lshl_add_u32 v78, v78, 7, v152
	v_lshl_add_u32 v79, v79, 7, v153
	s_mov_b32 m0, s76
	s_add_i32 s43, s76, 0x400
	global_load_lds_dwordx4 v78, s[50:51]
	s_mov_b32 m0, s43
	s_nop 0
	global_load_lds_dwordx4 v79, s[50:51]
	s_waitcnt vmcnt(8)
; #define LAS __attribute__((address_space(3)))
; __device__ __forceinline__ bf16 f2bf(float f) { return (bf16)f2bfu(f); }
; #define TR4(p_) __builtin_amdgcn_ds_read_tr4_b64_v2i32((LAS v2i*)(p_))
; #define VDMA(st_, k_) do { _Pragma("unroll") for (int i_ = 0; i_ < 4; ++i_) { \
;         const unsigned off_ = (unsigned)((st_) >> 2) * (16384u * 128u) + (PE_ID(E, 4 * ((st_) & 3) + i_) << 7) + ((i_ & 1) ? cx1 : cx0); \
;         __builtin_amdgcn_global_load_lds((const unsigned*)(V4 + off_), (LAS unsigned*)(ldsb + BUF[k_] + 1024 * i_), 16, 0, 0); } } while (0)
; __device__ __forceinline__ void peer_v_tokens(int j, const LAS unsigned short* EL, const LAS unsigned char* AL  , const LAS float* ASC  , const LAS int* SAL  , ...
;     ...
;         for (int st = 0; st < 16; ++st) {
;             const int p = st >> 2, q = st & 3;
;             if (st < 14) VDMA(st + 2, (st + 2) % 3);
;             if (st < 14) asm volatile("s_waitcnt vmcnt(8)" ::: "memory");
;             else if (st == 14) asm volatile("s_waitcnt vmcnt(4)" ::: "memory");
;             else asm volatile("s_waitcnt vmcnt(0)" ::: "memory");
;             if (q == 0) {
; #pragma unroll
;                 for (int r = 0; r < 4; ++r) { accH[r] = 0; accL[r] = 0; } }
; #pragma unroll
;             for (int tp = 0; tp < 2; ++tp) {
;                 const v2i ao = TR4(ATL + (2 * q + tp) * 128 + 8 * s16), ah = TR4(ATL + 1024 + (2 * q + tp) * 128 + 8 * s16);
; #pragma unroll
;                 for (int r = 0; r < 4; ++r) {
;                     const v2i d = TR4(ldsb + BUF[st % 3] + 2048 * tp + roff[r]);
;                     accH[r] = __builtin_amdgcn_sdot8(d.x, ah.x, accH[r], false); accH[r] = __builtin_amdgcn_sdot8(d.y, ah.y, accH[r], false);
;                     accL[r] = __builtin_amdgcn_sdot8(d.x, ao.x, accL[r], false); accL[r] = __builtin_amdgcn_sdot8(d.y, ao.y, accL[r], false);
;                 }
;             }
;             asm volatile("s_waitcnt lgkmcnt(0)" ::: "memory");
;             if (q == 3) {
; #pragma unroll
;                 for (int r = 0; r < 4; ++r) STASH[256 * p + 16 * (grp + 4 * r) + pc] = f2bf(asc * (float)(2 * ((accH[r] << 4) + accL[r]) + sa));
;             }
;     ...
;             for (int jq = 0; jq < 4; ++jq) { typedef unsigned u2v __attribute__((ext_vector_type(2))); const u2v pw = *(const LAS u2v*)(STASH + 4 * lane + 256 * jq); const uint2 hw = hv[jq];
	v_add_u32_e32 v54, s78, v59
	v_add_u32_e32 v55, s78, v60
	v_add_u32_e32 v56, s78, v61
	v_add_u32_e32 v57, s78, v62
	ds_read_b64_tr_b4 v[46:47], v160
	ds_read_b64_tr_b4 v[48:49], v160 offset:1024
	ds_read_b64_tr_b4 v[122:123], v54
	ds_read_b64_tr_b4 v[124:125], v55
	ds_read_b64_tr_b4 v[126:127], v56
	ds_read_b64_tr_b4 v[128:129], v57
	s_waitcnt lgkmcnt(6)
	v_dot8c_i32_i4_e32 v38, v130, v52
	v_dot8c_i32_i4_e32 v39, v130, v50
	v_dot8c_i32_i4_e32 v40, v132, v52
	v_dot8c_i32_i4_e32 v41, v132, v50
	v_dot8c_i32_i4_e32 v42, v134, v52
	v_dot8c_i32_i4_e32 v43, v134, v50
	v_dot8c_i32_i4_e32 v44, v136, v52
	v_dot8c_i32_i4_e32 v45, v136, v50
	v_dot8c_i32_i4_e32 v38, v131, v53
	v_dot8c_i32_i4_e32 v39, v131, v51
	v_dot8c_i32_i4_e32 v40, v133, v53
	v_dot8c_i32_i4_e32 v41, v133, v51
	v_dot8c_i32_i4_e32 v42, v135, v53
	v_dot8c_i32_i4_e32 v43, v135, v51
	v_dot8c_i32_i4_e32 v44, v137, v53
	v_dot8c_i32_i4_e32 v45, v137, v51
	s_nop 3
	s_waitcnt lgkmcnt(15)
	v_lshlrev_b32_e32 v38, 5, v38
	v_lshlrev_b32_e32 v39, 1, v39
	v_add3_u32 v38, v39, v229, v38
	v_cvt_f32_i32_e32 v38, v38
	v_mul_f32_e32 v38, v228, v38
	v_lshlrev_b32_e32 v40, 5, v40
	v_lshlrev_b32_e32 v41, 1, v41
	v_add3_u32 v40, v41, v229, v40
	v_cvt_f32_i32_e32 v40, v40
	v_mul_f32_e32 v40, v228, v40
	v_lshlrev_b32_e32 v42, 5, v42
	v_lshlrev_b32_e32 v43, 1, v43
	v_add3_u32 v42, v43, v229, v42
	v_cvt_f32_i32_e32 v42, v42
	v_mul_f32_e32 v42, v228, v42
	v_lshlrev_b32_e32 v44, 5, v44
	v_lshlrev_b32_e32 v45, 1, v45
	v_add3_u32 v44, v45, v229, v44
	v_cvt_f32_i32_e32 v44, v44
	v_mul_f32_e32 v44, v228, v44
	v_cvt_pk_bf16_f32 v164, v38, v40
	v_cvt_pk_bf16_f32 v165, v42, v44
	ds_read_b128 v[252:255], v155 offset:1024
	s_add_i32 s44, s40, 16
	s_ashr_i32 s45, s44, 31
	s_lshl_b64 s[44:45], s[44:45], 12
	v_lshl_add_u64 v[80:81], v[36:37], 0, s[44:45]
	s_waitcnt lgkmcnt(0)
	v_mul_f32_e32 v214, v214, v252
	v_mul_f32_e32 v215, v215, v253
	v_mul_f32_e32 v216, v216, v254
	v_mul_f32_e32 v217, v217, v255
	global_store_dwordx4 v[80:81], v[214:217], off offset:1024 nt
	v_add_u32_e32 v147, 8, v140
	v_and_b32_e32 v146, 15, v147
	v_xor_b32_e32 v146, 8, v146
	v_bfe_u32 v148, v147, 4, 4
	v_mul_lo_u32 v146, v146, s92
	v_mul_lo_u32 v148, v148, s92
	v_mov_b32_e32 v147, v146
	v_mov_b32_e32 v149, v148
	ds_write2st64_b64 v77, v[146:147], v[148:149] offset1:2
	v_add_u32_e32 v138, 0x1000, v74
	ds_read_u8 v139, v138
	v_add_u32_e32 v141, 0x1000, v73
	ds_read_u8 v140, v141
	s_add_i32 s43, s67, 160
	v_mov_b32_e32 v138, s43
	ds_read2st64_b32 v[228:229], v138 offset1:1
	ds_read_b128 v[18:21], v227 offset:8192
	ds_read_b128 v[22:25], v227 offset:8208
	v_add_u32_e32 v150, 0x400000, v63
	v_add_u32_e32 v151, 0x400000, v64
	v_mov_b32_e32 v38, 0
	v_mov_b32_e32 v39, 0
	v_mov_b32_e32 v40, 0
	v_mov_b32_e32 v41, 0
	v_mov_b32_e32 v42, 0
	v_mov_b32_e32 v43, 0
	v_mov_b32_e32 v44, 0
	v_mov_b32_e32 v45, 0
	v_and_b32_e32 v78, 0xffff, v31
	v_lshrrev_b32_e32 v79, 16, v31
	v_lshl_add_u32 v78, v78, 7, v152
	v_lshl_add_u32 v79, v79, 7, v153
	s_mov_b32 m0, s77
	s_add_i32 s43, s77, 0x400
	global_load_lds_dwordx4 v78, s[50:51]
	s_mov_b32 m0, s43
	s_nop 0
	global_load_lds_dwordx4 v79, s[50:51]
	s_waitcnt vmcnt(9)
	v_add_u32_e32 v54, s79, v59
	v_add_u32_e32 v55, s79, v60
	v_add_u32_e32 v56, s79, v61
	v_add_u32_e32 v57, s79, v62
	ds_read_b64_tr_b4 v[50:51], v160 offset:128
	ds_read_b64_tr_b4 v[52:53], v160 offset:1152
	ds_read_b64_tr_b4 v[130:131], v54
	ds_read_b64_tr_b4 v[132:133], v55
	ds_read_b64_tr_b4 v[134:135], v56
	ds_read_b64_tr_b4 v[136:137], v57
	s_waitcnt lgkmcnt(13)
	v_dot8c_i32_i4_e32 v38, v122, v48
	v_dot8c_i32_i4_e32 v39, v122, v46
	v_dot8c_i32_i4_e32 v40, v124, v48
	v_dot8c_i32_i4_e32 v41, v124, v46
	v_dot8c_i32_i4_e32 v42, v126, v48
	v_dot8c_i32_i4_e32 v43, v126, v46
	v_dot8c_i32_i4_e32 v44, v128, v48
	v_dot8c_i32_i4_e32 v45, v128, v46
	v_dot8c_i32_i4_e32 v38, v123, v49
	v_dot8c_i32_i4_e32 v39, v123, v47
	v_dot8c_i32_i4_e32 v40, v125, v49
	v_dot8c_i32_i4_e32 v41, v125, v47
	v_dot8c_i32_i4_e32 v42, v127, v49
	v_dot8c_i32_i4_e32 v43, v127, v47
	v_dot8c_i32_i4_e32 v44, v129, v49
	v_dot8c_i32_i4_e32 v45, v129, v47
	v_and_b32_e32 v78, 0xffff, v32
	v_lshrrev_b32_e32 v79, 16, v32
	v_lshl_add_u32 v78, v78, 7, v152
	v_lshl_add_u32 v79, v79, 7, v153
	s_mov_b32 m0, s78
	s_add_i32 s43, s78, 0x400
	global_load_lds_dwordx4 v78, s[50:51]
	s_mov_b32 m0, s43
	s_nop 0
	global_load_lds_dwordx4 v79, s[50:51]
	s_waitcnt vmcnt(9)
	v_add_u32_e32 v54, s98, v59
	v_add_u32_e32 v55, s98, v60
	v_add_u32_e32 v56, s98, v61
	v_add_u32_e32 v57, s98, v62
	ds_read_b64_tr_b4 v[46:47], v160 offset:256
	ds_read_b64_tr_b4 v[48:49], v160 offset:1280
	ds_read_b64_tr_b4 v[122:123], v54
	ds_read_b64_tr_b4 v[124:125], v55
	ds_read_b64_tr_b4 v[126:127], v56
	ds_read_b64_tr_b4 v[128:129], v57
	s_waitcnt lgkmcnt(6)
	v_dot8c_i32_i4_e32 v38, v130, v52
	v_dot8c_i32_i4_e32 v39, v130, v50
	v_dot8c_i32_i4_e32 v40, v132, v52
	v_dot8c_i32_i4_e32 v41, v132, v50
	v_dot8c_i32_i4_e32 v42, v134, v52
	v_dot8c_i32_i4_e32 v43, v134, v50
	v_dot8c_i32_i4_e32 v44, v136, v52
	v_dot8c_i32_i4_e32 v45, v136, v50
	v_dot8c_i32_i4_e32 v38, v131, v53
	v_dot8c_i32_i4_e32 v39, v131, v51
	v_dot8c_i32_i4_e32 v40, v133, v53
	v_dot8c_i32_i4_e32 v41, v133, v51
	v_dot8c_i32_i4_e32 v42, v135, v53
	v_dot8c_i32_i4_e32 v43, v135, v51
	v_dot8c_i32_i4_e32 v44, v137, v53
	v_dot8c_i32_i4_e32 v45, v137, v51
	ds_write_b16 v65, v186
	ds_write_b16_d16_hi v65, v186 offset:128
	ds_write_b16 v65, v187 offset:256
	ds_write_b16_d16_hi v65, v187 offset:384
	ds_write_b16 v65, v188 offset:512
	ds_write_b16_d16_hi v65, v188 offset:640
	ds_write_b16 v65, v189 offset:768
	ds_write_b16_d16_hi v65, v189 offset:896
	ds_write_b16 v65, v190 offset:1024
	ds_write_b16_d16_hi v65, v190 offset:1152
	ds_write_b16 v65, v191 offset:1280
	ds_write_b16_d16_hi v65, v191 offset:1408
	ds_write_b16 v65, v192 offset:1536
	ds_write_b16_d16_hi v65, v192 offset:1664
	ds_write_b16 v65, v193 offset:1792
	ds_write_b16_d16_hi v65, v193 offset:1920
	ds_read_b64 v[202:203], v154
	ds_read_b64 v[204:205], v154 offset:512
	ds_read_b64 v[206:207], v154 offset:1024
	ds_read_b64 v[208:209], v154 offset:1536
	v_and_b32_e32 v78, 0xffff, v33
	v_lshrrev_b32_e32 v79, 16, v33
	v_lshl_add_u32 v78, v78, 7, v152
	v_lshl_add_u32 v79, v79, 7, v153
	s_mov_b32 m0, s79
	s_add_i32 s43, s79, 0x400
	global_load_lds_dwordx4 v78, s[50:51]
	s_mov_b32 m0, s43
	s_nop 0
	global_load_lds_dwordx4 v79, s[50:51]
	s_waitcnt vmcnt(9)
; #define TR4(p_) __builtin_amdgcn_ds_read_tr4_b64_v2i32((LAS v2i*)(p_))
; #define VDMA(st_, k_) do { _Pragma("unroll") for (int i_ = 0; i_ < 4; ++i_) { \
;         const unsigned off_ = (unsigned)((st_) >> 2) * (16384u * 128u) + (PE_ID(E, 4 * ((st_) & 3) + i_) << 7) + ((i_ & 1) ? cx1 : cx0); \
;         __builtin_amdgcn_global_load_lds((const unsigned*)(V4 + off_), (LAS unsigned*)(ldsb + BUF[k_] + 1024 * i_), 16, 0, 0); } } while (0)
; __device__ __forceinline__ void peer_v_tokens(int j, const LAS unsigned short* EL, const LAS unsigned char* AL  , const LAS float* ASC  , const LAS int* SAL  , ...
;     ...
;         for (int st = 0; st < 16; ++st) {
;             const int p = st >> 2, q = st & 3;
;             if (st < 14) VDMA(st + 2, (st + 2) % 3);
;             if (st < 14) asm volatile("s_waitcnt vmcnt(8)" ::: "memory");
;             else if (st == 14) asm volatile("s_waitcnt vmcnt(4)" ::: "memory");
;             else asm volatile("s_waitcnt vmcnt(0)" ::: "memory");
;             if (q == 0) {
; #pragma unroll
;                 for (int r = 0; r < 4; ++r) { accH[r] = 0; accL[r] = 0; } }
; #pragma unroll
;             for (int tp = 0; tp < 2; ++tp) {
;                 const v2i ao = TR4(ATL + (2 * q + tp) * 128 + 8 * s16), ah = TR4(ATL + 1024 + (2 * q + tp) * 128 + 8 * s16);
; #pragma unroll
;                 for (int r = 0; r < 4; ++r) {
;                     const v2i d = TR4(ldsb + BUF[st % 3] + 2048 * tp + roff[r]);
;                     accH[r] = __builtin_amdgcn_sdot8(d.x, ah.x, accH[r], false); accH[r] = __builtin_amdgcn_sdot8(d.y, ah.y, accH[r], false);
;                     accL[r] = __builtin_amdgcn_sdot8(d.x, ao.x, accL[r], false); accL[r] = __builtin_amdgcn_sdot8(d.y, ao.y, accL[r], false);
;                 }
	v_add_u32_e32 v54, s99, v59
	v_add_u32_e32 v55, s99, v60
	v_add_u32_e32 v56, s99, v61
	v_add_u32_e32 v57, s99, v62
	ds_read_b64_tr_b4 v[50:51], v160 offset:384
	ds_read_b64_tr_b4 v[52:53], v160 offset:1408
	ds_read_b64_tr_b4 v[130:131], v54
	ds_read_b64_tr_b4 v[132:133], v55
	ds_read_b64_tr_b4 v[134:135], v56
	ds_read_b64_tr_b4 v[136:137], v57
	s_waitcnt lgkmcnt(15)
	v_dot8c_i32_i4_e32 v38, v122, v48
	v_dot8c_i32_i4_e32 v39, v122, v46
	v_dot8c_i32_i4_e32 v40, v124, v48
	v_dot8c_i32_i4_e32 v41, v124, v46
	v_dot8c_i32_i4_e32 v42, v126, v48
	v_dot8c_i32_i4_e32 v43, v126, v46
	v_dot8c_i32_i4_e32 v44, v128, v48
	v_dot8c_i32_i4_e32 v45, v128, v46
	v_dot8c_i32_i4_e32 v38, v123, v49
	v_dot8c_i32_i4_e32 v39, v123, v47
	v_dot8c_i32_i4_e32 v40, v125, v49
	v_dot8c_i32_i4_e32 v41, v125, v47
	v_dot8c_i32_i4_e32 v42, v127, v49
	v_dot8c_i32_i4_e32 v43, v127, v47
	v_dot8c_i32_i4_e32 v44, v129, v49
	v_dot8c_i32_i4_e32 v45, v129, v47
	s_waitcnt lgkmcnt(15)
	v_and_b32_e32 v78, 0xffff, v18
	v_lshrrev_b32_e32 v79, 16, v18
	v_lshl_add_u32 v78, v78, 7, v150
	v_lshl_add_u32 v79, v79, 7, v151
	s_mov_b32 m0, s98
	s_add_i32 s43, s98, 0x400
	global_load_lds_dwordx4 v78, s[50:51]
	s_mov_b32 m0, s43
	s_nop 0
	global_load_lds_dwordx4 v79, s[50:51]
	s_waitcnt vmcnt(9)
	v_add_u32_e32 v54, s76, v59
	v_add_u32_e32 v55, s76, v60
	v_add_u32_e32 v56, s76, v61
	v_add_u32_e32 v57, s76, v62
	ds_read_b64_tr_b4 v[46:47], v160 offset:512
	ds_read_b64_tr_b4 v[48:49], v160 offset:1536
	ds_read_b64_tr_b4 v[122:123], v54
	ds_read_b64_tr_b4 v[124:125], v55
	ds_read_b64_tr_b4 v[126:127], v56
	ds_read_b64_tr_b4 v[128:129], v57
	s_waitcnt lgkmcnt(6)
	v_dot8c_i32_i4_e32 v38, v130, v52
	v_dot8c_i32_i4_e32 v39, v130, v50
	v_dot8c_i32_i4_e32 v40, v132, v52
	v_dot8c_i32_i4_e32 v41, v132, v50
	v_dot8c_i32_i4_e32 v42, v134, v52
	v_dot8c_i32_i4_e32 v43, v134, v50
	v_dot8c_i32_i4_e32 v44, v136, v52
	v_dot8c_i32_i4_e32 v45, v136, v50
	v_dot8c_i32_i4_e32 v38, v131, v53
	v_dot8c_i32_i4_e32 v39, v131, v51
	v_dot8c_i32_i4_e32 v40, v133, v53
	v_dot8c_i32_i4_e32 v41, v133, v51
	v_dot8c_i32_i4_e32 v42, v135, v53
	v_dot8c_i32_i4_e32 v43, v135, v51
	v_dot8c_i32_i4_e32 v44, v137, v53
	v_dot8c_i32_i4_e32 v45, v137, v51
	v_and_b32_e32 v78, 0xffff, v19
	v_lshrrev_b32_e32 v79, 16, v19
	v_lshl_add_u32 v78, v78, 7, v150
	v_lshl_add_u32 v79, v79, 7, v151
	s_mov_b32 m0, s99
	s_add_i32 s43, s99, 0x400
	global_load_lds_dwordx4 v78, s[50:51]
	s_mov_b32 m0, s43
	s_nop 0
	global_load_lds_dwordx4 v79, s[50:51]
	s_waitcnt vmcnt(8)
	v_add_u32_e32 v54, s77, v59
	v_add_u32_e32 v55, s77, v60
	v_add_u32_e32 v56, s77, v61
	v_add_u32_e32 v57, s77, v62
	ds_read_b64_tr_b4 v[50:51], v160 offset:640
	ds_read_b64_tr_b4 v[52:53], v160 offset:1664
	ds_read_b64_tr_b4 v[130:131], v54
	ds_read_b64_tr_b4 v[132:133], v55
	ds_read_b64_tr_b4 v[134:135], v56
	ds_read_b64_tr_b4 v[136:137], v57
	s_waitcnt lgkmcnt(6)
	v_dot8c_i32_i4_e32 v38, v122, v48
	v_dot8c_i32_i4_e32 v39, v122, v46
	v_dot8c_i32_i4_e32 v40, v124, v48
	v_dot8c_i32_i4_e32 v41, v124, v46
	v_dot8c_i32_i4_e32 v42, v126, v48
	v_dot8c_i32_i4_e32 v43, v126, v46
	v_dot8c_i32_i4_e32 v44, v128, v48
	v_dot8c_i32_i4_e32 v45, v128, v46
	v_dot8c_i32_i4_e32 v38, v123, v49
	v_dot8c_i32_i4_e32 v39, v123, v47
	v_dot8c_i32_i4_e32 v40, v125, v49
	v_dot8c_i32_i4_e32 v41, v125, v47
	v_dot8c_i32_i4_e32 v42, v127, v49
	v_dot8c_i32_i4_e32 v43, v127, v47
	v_dot8c_i32_i4_e32 v44, v129, v49
	v_dot8c_i32_i4_e32 v45, v129, v47
	s_waitcnt lgkmcnt(15)
	v_add_u32_e32 v143, 8, v139
	v_and_b32_e32 v142, 15, v143
	v_xor_b32_e32 v142, 8, v142
	v_bfe_u32 v144, v143, 4, 4
	v_mul_lo_u32 v142, v142, s92
	v_mul_lo_u32 v144, v144, s92
	v_mov_b32_e32 v143, v142
	v_mov_b32_e32 v145, v144
	ds_write2st64_b64 v159, v[142:143], v[144:145] offset1:2
	v_and_b32_e32 v78, 0xffff, v20
	v_lshrrev_b32_e32 v79, 16, v20
	v_lshl_add_u32 v78, v78, 7, v150
	v_lshl_add_u32 v79, v79, 7, v151
	s_mov_b32 m0, s76
	s_add_i32 s43, s76, 0x400
	global_load_lds_dwordx4 v78, s[50:51]
	s_mov_b32 m0, s43
	s_nop 0
	global_load_lds_dwordx4 v79, s[50:51]
	s_waitcnt vmcnt(8)
	v_add_u32_e32 v54, s78, v59
	v_add_u32_e32 v55, s78, v60
	v_add_u32_e32 v56, s78, v61
	v_add_u32_e32 v57, s78, v62
	ds_read_b64_tr_b4 v[46:47], v160 offset:768
	ds_read_b64_tr_b4 v[48:49], v160 offset:1792
	ds_read_b64_tr_b4 v[122:123], v54
	ds_read_b64_tr_b4 v[124:125], v55
	ds_read_b64_tr_b4 v[126:127], v56
	ds_read_b64_tr_b4 v[128:129], v57
	s_waitcnt lgkmcnt(7)
	v_dot8c_i32_i4_e32 v38, v130, v52
	v_dot8c_i32_i4_e32 v39, v130, v50
	v_dot8c_i32_i4_e32 v40, v132, v52
	v_dot8c_i32_i4_e32 v41, v132, v50
	v_dot8c_i32_i4_e32 v42, v134, v52
	v_dot8c_i32_i4_e32 v43, v134, v50
	v_dot8c_i32_i4_e32 v44, v136, v52
	v_dot8c_i32_i4_e32 v45, v136, v50
	v_dot8c_i32_i4_e32 v38, v131, v53
	v_dot8c_i32_i4_e32 v39, v131, v51
	v_dot8c_i32_i4_e32 v40, v133, v53
	v_dot8c_i32_i4_e32 v41, v133, v51
	v_dot8c_i32_i4_e32 v42, v135, v53
	v_dot8c_i32_i4_e32 v43, v135, v51
	v_dot8c_i32_i4_e32 v44, v137, v53
	v_dot8c_i32_i4_e32 v45, v137, v51
	v_and_b32_e32 v78, 0xffff, v21
	v_lshrrev_b32_e32 v79, 16, v21
	v_lshl_add_u32 v78, v78, 7, v150
	v_lshl_add_u32 v79, v79, 7, v151
	s_mov_b32 m0, s77
	s_add_i32 s43, s77, 0x400
	global_load_lds_dwordx4 v78, s[50:51]
	s_mov_b32 m0, s43
	s_nop 0
	global_load_lds_dwordx4 v79, s[50:51]
	s_waitcnt vmcnt(8)
	v_add_u32_e32 v54, s79, v59
	v_add_u32_e32 v55, s79, v60
	v_add_u32_e32 v56, s79, v61
	v_add_u32_e32 v57, s79, v62
	ds_read_b64_tr_b4 v[50:51], v160 offset:896
	ds_read_b64_tr_b4 v[52:53], v160 offset:1920
	ds_read_b64_tr_b4 v[130:131], v54
	ds_read_b64_tr_b4 v[132:133], v55
	ds_read_b64_tr_b4 v[134:135], v56
	ds_read_b64_tr_b4 v[136:137], v57
	s_waitcnt lgkmcnt(6)
; __device__ __forceinline__ bf16 f2bf(float f) { return (bf16)f2bfu(f); }
; #define TR4(p_) __builtin_amdgcn_ds_read_tr4_b64_v2i32((LAS v2i*)(p_))
; __device__ __forceinline__ void peer_v_tokens(int j, const LAS unsigned short* EL, const LAS unsigned char* AL  , const LAS float* ASC  , const LAS int* SAL  , ...
;     ...
;         for (int st = 0; st < 16; ++st) {
;             const int p = st >> 2, q = st & 3;
;             if (st < 14) VDMA(st + 2, (st + 2) % 3);
;             if (st < 14) asm volatile("s_waitcnt vmcnt(8)" ::: "memory");
;             else if (st == 14) asm volatile("s_waitcnt vmcnt(4)" ::: "memory");
;             else asm volatile("s_waitcnt vmcnt(0)" ::: "memory");
;             if (q == 0) {
; #pragma unroll
;                 for (int r = 0; r < 4; ++r) { accH[r] = 0; accL[r] = 0; } }
; #pragma unroll
;             for (int tp = 0; tp < 2; ++tp) {
;                 const v2i ao = TR4(ATL + (2 * q + tp) * 128 + 8 * s16), ah = TR4(ATL + 1024 + (2 * q + tp) * 128 + 8 * s16);
; #pragma unroll
;                 for (int r = 0; r < 4; ++r) {
;                     const v2i d = TR4(ldsb + BUF[st % 3] + 2048 * tp + roff[r]);
;                     accH[r] = __builtin_amdgcn_sdot8(d.x, ah.x, accH[r], false); accH[r] = __builtin_amdgcn_sdot8(d.y, ah.y, accH[r], false);
;                     accL[r] = __builtin_amdgcn_sdot8(d.x, ao.x, accL[r], false); accL[r] = __builtin_amdgcn_sdot8(d.y, ao.y, accL[r], false);
;                 }
;             }
;             asm volatile("s_waitcnt lgkmcnt(0)" ::: "memory");
;             if (q == 3) {
; #pragma unroll
;                 for (int r = 0; r < 4; ++r) STASH[256 * p + 16 * (grp + 4 * r) + pc] = f2bf(asc * (float)(2 * ((accH[r] << 4) + accL[r]) + sa));
;             }
;     ...
;             float4* op = (float4*)(outp + (size_t)t * D) + lane;
; #pragma unroll
;             for (int jq = 0; jq < 4; ++jq) { typedef float f4v __attribute__((ext_vector_type(4))); f4v o4; o4.x = v[jq].x * r3 * gv[jq].x; o4.y = v[jq].y * r3 * gv[jq].y; o4.z = v[jq].z * r3 * gv[jq].z; o4.w = v[jq].w * r3 * gv[jq].w;
;                 __builtin_nontemporal_store(o4, (f4v*)op + 64 * jq); }
	v_dot8c_i32_i4_e32 v38, v122, v48
	v_dot8c_i32_i4_e32 v39, v122, v46
	v_dot8c_i32_i4_e32 v40, v124, v48
	v_dot8c_i32_i4_e32 v41, v124, v46
	v_dot8c_i32_i4_e32 v42, v126, v48
	v_dot8c_i32_i4_e32 v43, v126, v46
	v_dot8c_i32_i4_e32 v44, v128, v48
	v_dot8c_i32_i4_e32 v45, v128, v46
	v_dot8c_i32_i4_e32 v38, v123, v49
	v_dot8c_i32_i4_e32 v39, v123, v47
	v_dot8c_i32_i4_e32 v40, v125, v49
	v_dot8c_i32_i4_e32 v41, v125, v47
	v_dot8c_i32_i4_e32 v42, v127, v49
	v_dot8c_i32_i4_e32 v43, v127, v47
	v_dot8c_i32_i4_e32 v44, v129, v49
	v_dot8c_i32_i4_e32 v45, v129, v47
	v_and_b32_e32 v78, 0xffff, v22
	v_lshrrev_b32_e32 v79, 16, v22
	v_lshl_add_u32 v78, v78, 7, v150
	v_lshl_add_u32 v79, v79, 7, v151
	s_mov_b32 m0, s78
	s_add_i32 s43, s78, 0x400
	global_load_lds_dwordx4 v78, s[50:51]
	s_mov_b32 m0, s43
	s_nop 0
	global_load_lds_dwordx4 v79, s[50:51]
	s_waitcnt vmcnt(8)
	v_add_u32_e32 v54, s98, v59
	v_add_u32_e32 v55, s98, v60
	v_add_u32_e32 v56, s98, v61
	v_add_u32_e32 v57, s98, v62
	ds_read_b64_tr_b4 v[46:47], v160
	ds_read_b64_tr_b4 v[48:49], v160 offset:1024
	ds_read_b64_tr_b4 v[122:123], v54
	ds_read_b64_tr_b4 v[124:125], v55
	ds_read_b64_tr_b4 v[126:127], v56
	ds_read_b64_tr_b4 v[128:129], v57
	s_waitcnt lgkmcnt(6)
	v_dot8c_i32_i4_e32 v38, v130, v52
	v_dot8c_i32_i4_e32 v39, v130, v50
	v_dot8c_i32_i4_e32 v40, v132, v52
	v_dot8c_i32_i4_e32 v41, v132, v50
	v_dot8c_i32_i4_e32 v42, v134, v52
	v_dot8c_i32_i4_e32 v43, v134, v50
	v_dot8c_i32_i4_e32 v44, v136, v52
	v_dot8c_i32_i4_e32 v45, v136, v50
	v_dot8c_i32_i4_e32 v38, v131, v53
	v_dot8c_i32_i4_e32 v39, v131, v51
	v_dot8c_i32_i4_e32 v40, v133, v53
	v_dot8c_i32_i4_e32 v41, v133, v51
	v_dot8c_i32_i4_e32 v42, v135, v53
	v_dot8c_i32_i4_e32 v43, v135, v51
	v_dot8c_i32_i4_e32 v44, v137, v53
	v_dot8c_i32_i4_e32 v45, v137, v51
	s_nop 3
	s_waitcnt lgkmcnt(15)
	v_lshlrev_b32_e32 v38, 5, v38
	v_lshlrev_b32_e32 v39, 1, v39
	v_add3_u32 v38, v39, v229, v38
	v_cvt_f32_i32_e32 v38, v38
	v_mul_f32_e32 v38, v228, v38
	v_lshlrev_b32_e32 v40, 5, v40
	v_lshlrev_b32_e32 v41, 1, v41
	v_add3_u32 v40, v41, v229, v40
	v_cvt_f32_i32_e32 v40, v40
	v_mul_f32_e32 v40, v228, v40
	v_lshlrev_b32_e32 v42, 5, v42
	v_lshlrev_b32_e32 v43, 1, v43
	v_add3_u32 v42, v43, v229, v42
	v_cvt_f32_i32_e32 v42, v42
	v_mul_f32_e32 v42, v228, v42
	v_lshlrev_b32_e32 v44, 5, v44
	v_lshlrev_b32_e32 v45, 1, v45
	v_add3_u32 v44, v45, v229, v44
	v_cvt_f32_i32_e32 v44, v44
	v_mul_f32_e32 v44, v228, v44
	v_cvt_pk_bf16_f32 v172, v38, v40
	v_cvt_pk_bf16_f32 v173, v42, v44
	ds_read_b128 v[252:255], v156
	s_add_i32 s44, s40, 16
	s_ashr_i32 s45, s44, 31
	s_lshl_b64 s[44:45], s[44:45], 12
	v_lshl_add_u64 v[80:81], v[36:37], 0, s[44:45]
	s_waitcnt lgkmcnt(0)
	v_mul_f32_e32 v218, v218, v252
	v_mul_f32_e32 v219, v219, v253
	v_mul_f32_e32 v220, v220, v254
	v_mul_f32_e32 v221, v221, v255
	global_store_dwordx4 v[80:81], v[218:221], off offset:2048 nt
	v_add_u32_e32 v147, 8, v140
	v_and_b32_e32 v146, 15, v147
	v_xor_b32_e32 v146, 8, v146
	v_bfe_u32 v148, v147, 4, 4
	v_mul_lo_u32 v146, v146, s92
	v_mul_lo_u32 v148, v148, s92
	v_mov_b32_e32 v147, v146
	v_mov_b32_e32 v149, v148
	ds_write2st64_b64 v77, v[146:147], v[148:149] offset1:2
	v_add_u32_e32 v138, 0x1400, v74
	ds_read_u8 v139, v138
	v_add_u32_e32 v141, 0x1400, v73
	ds_read_u8 v140, v141
	s_add_i32 s43, s67, 128
	v_mov_b32_e32 v138, s43
	ds_read2st64_b32 v[228:229], v138 offset1:1
	ds_read_b128 v[26:29], v227 offset:10240
	ds_read_b128 v[30:33], v227 offset:10256
	v_mov_b32_e32 v38, 0
	v_mov_b32_e32 v39, 0
	v_mov_b32_e32 v40, 0
	v_mov_b32_e32 v41, 0
	v_mov_b32_e32 v42, 0
	v_mov_b32_e32 v43, 0
	v_mov_b32_e32 v44, 0
	v_mov_b32_e32 v45, 0
	v_and_b32_e32 v78, 0xffff, v23
	v_lshrrev_b32_e32 v79, 16, v23
	v_lshl_add_u32 v78, v78, 7, v150
	v_lshl_add_u32 v79, v79, 7, v151
	s_mov_b32 m0, s79
	s_add_i32 s43, s79, 0x400
	global_load_lds_dwordx4 v78, s[50:51]
	s_mov_b32 m0, s43
	s_nop 0
	global_load_lds_dwordx4 v79, s[50:51]
	s_waitcnt vmcnt(9)
	v_add_u32_e32 v54, s99, v59
	v_add_u32_e32 v55, s99, v60
	v_add_u32_e32 v56, s99, v61
	v_add_u32_e32 v57, s99, v62
	ds_read_b64_tr_b4 v[50:51], v160 offset:128
	ds_read_b64_tr_b4 v[52:53], v160 offset:1152
	ds_read_b64_tr_b4 v[130:131], v54
	ds_read_b64_tr_b4 v[132:133], v55
	ds_read_b64_tr_b4 v[134:135], v56
	ds_read_b64_tr_b4 v[136:137], v57
	s_waitcnt lgkmcnt(13)
	s_waitcnt vmcnt(36) lgkmcnt(15)
; #define LAS __attribute__((address_space(3)))
; #define TR4(p_) __builtin_amdgcn_ds_read_tr4_b64_v2i32((LAS v2i*)(p_))
; __device__ __forceinline__ void peer_v_tokens(int j, const LAS unsigned short* EL, const LAS unsigned char* AL  , const LAS float* ASC  , const LAS int* SAL  , ...
;     ...
;             for (int tp = 0; tp < 2; ++tp) {
;                 const v2i ao = TR4(ATL + (2 * q + tp) * 128 + 8 * s16), ah = TR4(ATL + 1024 + (2 * q + tp) * 128 + 8 * s16);
; #pragma unroll
;                 for (int r = 0; r < 4; ++r) {
;                     const v2i d = TR4(ldsb + BUF[st % 3] + 2048 * tp + roff[r]);
;                     accH[r] = __builtin_amdgcn_sdot8(d.x, ah.x, accH[r], false); accH[r] = __builtin_amdgcn_sdot8(d.y, ah.y, accH[r], false);
;                     accL[r] = __builtin_amdgcn_sdot8(d.x, ao.x, accL[r], false); accL[r] = __builtin_amdgcn_sdot8(d.y, ao.y, accL[r], false);
;                 }
;             }
;     ...
;         {
;             float4 v[4]; float ss = 0.f;
; #pragma unroll
;             for (int jq = 0; jq < 4; ++jq) { typedef unsigned u2v __attribute__((ext_vector_type(2))); const u2v pw = *(const LAS u2v*)(STASH + 4 * lane + 256 * jq); const uint2 hw = hv[jq];
;                 v[jq] = make_float4(__uint_as_float(hw.x << 16) + __uint_as_float(pw.x << 16), __uint_as_float(hw.x & 0xffff0000u) + __uint_as_float(pw.x & 0xffff0000u),
;                                     __uint_as_float(hw.y << 16) + __uint_as_float(pw.y << 16), __uint_as_float(hw.y & 0xffff0000u) + __uint_as_float(pw.y & 0xffff0000u));
;                 ss += v[jq].x * v[jq].x + v[jq].y * v[jq].y + v[jq].z * v[jq].z + v[jq].w * v[jq].w; }
;             ss = wave_sum(ss);
;             const float r3 = rsqrtf(ss * (1.f / D) + EPS);
	v_lshlrev_b32_e32 v236, 16, v194
	v_and_b32_e32 v237, 0xffff0000, v194
	v_lshlrev_b32_e32 v142, 16, v202
	v_and_b32_e32 v143, 0xffff0000, v202
	v_add_f32_e32 v236, v236, v142
	v_add_f32_e32 v237, v237, v143
	v_lshlrev_b32_e32 v238, 16, v195
	v_and_b32_e32 v239, 0xffff0000, v195
	v_lshlrev_b32_e32 v142, 16, v203
	v_and_b32_e32 v143, 0xffff0000, v203
	v_add_f32_e32 v238, v238, v142
	v_add_f32_e32 v239, v239, v143
	v_lshlrev_b32_e32 v240, 16, v196
	v_and_b32_e32 v241, 0xffff0000, v196
	v_lshlrev_b32_e32 v142, 16, v204
	v_and_b32_e32 v143, 0xffff0000, v204
	v_add_f32_e32 v240, v240, v142
	v_add_f32_e32 v241, v241, v143
	v_lshlrev_b32_e32 v242, 16, v197
	v_and_b32_e32 v243, 0xffff0000, v197
	v_lshlrev_b32_e32 v142, 16, v205
	v_and_b32_e32 v143, 0xffff0000, v205
	v_add_f32_e32 v242, v242, v142
	v_add_f32_e32 v243, v243, v143
	v_lshlrev_b32_e32 v244, 16, v198
	v_and_b32_e32 v245, 0xffff0000, v198
	v_lshlrev_b32_e32 v142, 16, v206
	v_and_b32_e32 v143, 0xffff0000, v206
	v_add_f32_e32 v244, v244, v142
	v_add_f32_e32 v245, v245, v143
	v_lshlrev_b32_e32 v246, 16, v199
	v_and_b32_e32 v247, 0xffff0000, v199
	v_lshlrev_b32_e32 v142, 16, v207
	v_and_b32_e32 v143, 0xffff0000, v207
	v_add_f32_e32 v246, v246, v142
	v_add_f32_e32 v247, v247, v143
	v_lshlrev_b32_e32 v248, 16, v200
	v_and_b32_e32 v249, 0xffff0000, v200
	v_lshlrev_b32_e32 v142, 16, v208
	v_and_b32_e32 v143, 0xffff0000, v208
	v_add_f32_e32 v248, v248, v142
	v_add_f32_e32 v249, v249, v143
	v_lshlrev_b32_e32 v250, 16, v201
	v_and_b32_e32 v251, 0xffff0000, v201
	v_lshlrev_b32_e32 v142, 16, v209
	v_and_b32_e32 v143, 0xffff0000, v209
	v_add_f32_e32 v250, v250, v142
	v_add_f32_e32 v251, v251, v143
	v_mov_b32_e32 v144, 0
	v_mul_f32_e32 v145, v236, v236
	v_fmac_f32_e32 v145, v237, v237
	v_fmac_f32_e32 v145, v238, v238
	v_fmac_f32_e32 v145, v239, v239
	v_add_f32_e32 v144, v144, v145
	v_mul_f32_e32 v145, v240, v240
	v_fmac_f32_e32 v145, v241, v241
	v_fmac_f32_e32 v145, v242, v242
	v_fmac_f32_e32 v145, v243, v243
	v_add_f32_e32 v144, v144, v145
	v_mul_f32_e32 v145, v244, v244
	v_fmac_f32_e32 v145, v245, v245
	v_fmac_f32_e32 v145, v246, v246
	v_fmac_f32_e32 v145, v247, v247
	v_add_f32_e32 v144, v144, v145
	v_mul_f32_e32 v145, v248, v248
	v_fmac_f32_e32 v145, v249, v249
	v_fmac_f32_e32 v145, v250, v250
	v_fmac_f32_e32 v145, v251, v251
	v_add_f32_e32 v144, v144, v145
	s_nop 1
	v_add_f32_dpp v144, v144, v144 quad_perm:[1,0,3,2] row_mask:0xf bank_mask:0xf bound_ctrl:1
	s_nop 1
	v_add_f32_dpp v144, v144, v144 quad_perm:[2,3,0,1] row_mask:0xf bank_mask:0xf bound_ctrl:1
	s_nop 1
	v_add_f32_dpp v144, v144, v144 row_half_mirror row_mask:0xf bank_mask:0xf bound_ctrl:1
	s_nop 1
	v_add_f32_dpp v144, v144, v144 row_mirror row_mask:0xf bank_mask:0xf bound_ctrl:1
	s_nop 1
	v_readlane_b32 s10, v144, 0
	v_readlane_b32 s11, v144, 16
	v_readlane_b32 s14, v144, 32
	v_readlane_b32 s15, v144, 48
	s_nop 3
	v_mov_b32_e32 v144, s11
	v_mov_b32_e32 v145, s15
	v_add_f32_e32 v144, s10, v144
	v_add_f32_e32 v145, s14, v145
	v_add_f32_e32 v144, v144, v145
	v_fmamk_f32 v144, v144, 0x3a800000, v111
	v_rsq_f32_e32 v144, v144
	s_nop 0
	v_mul_f32_e32 v236, v236, v144
	v_mul_f32_e32 v237, v237, v144
	v_mul_f32_e32 v238, v238, v144
	v_mul_f32_e32 v239, v239, v144
	v_mul_f32_e32 v240, v240, v144
	v_mul_f32_e32 v241, v241, v144
	v_mul_f32_e32 v242, v242, v144
	v_mul_f32_e32 v243, v243, v144
	v_mul_f32_e32 v244, v244, v144
	v_mul_f32_e32 v245, v245, v144
	v_mul_f32_e32 v246, v246, v144
	v_mul_f32_e32 v247, v247, v144
	v_mul_f32_e32 v248, v248, v144
	v_mul_f32_e32 v249, v249, v144
	v_mul_f32_e32 v250, v250, v144
	v_mul_f32_e32 v251, v251, v144
	v_dot8c_i32_i4_e32 v38, v122, v48
	v_dot8c_i32_i4_e32 v39, v122, v46
	v_dot8c_i32_i4_e32 v40, v124, v48
	v_dot8c_i32_i4_e32 v41, v124, v46
	v_dot8c_i32_i4_e32 v42, v126, v48
	v_dot8c_i32_i4_e32 v43, v126, v46
	v_dot8c_i32_i4_e32 v44, v128, v48
	v_dot8c_i32_i4_e32 v45, v128, v46
	v_dot8c_i32_i4_e32 v38, v123, v49
	v_dot8c_i32_i4_e32 v39, v123, v47
	v_dot8c_i32_i4_e32 v40, v125, v49
	v_dot8c_i32_i4_e32 v41, v125, v47
	v_dot8c_i32_i4_e32 v42, v127, v49
	v_dot8c_i32_i4_e32 v43, v127, v47
	v_dot8c_i32_i4_e32 v44, v129, v49
	v_dot8c_i32_i4_e32 v45, v129, v47
	v_and_b32_e32 v78, 0xffff, v24
	v_lshrrev_b32_e32 v79, 16, v24
	v_lshl_add_u32 v78, v78, 7, v150
	v_lshl_add_u32 v79, v79, 7, v151
	s_mov_b32 m0, s98
	s_add_i32 s43, s98, 0x400
	global_load_lds_dwordx4 v78, s[50:51]
	s_mov_b32 m0, s43
	s_nop 0
	global_load_lds_dwordx4 v79, s[50:51]
	s_waitcnt vmcnt(9)
	v_add_u32_e32 v54, s76, v59
	v_add_u32_e32 v55, s76, v60
	v_add_u32_e32 v56, s76, v61
	v_add_u32_e32 v57, s76, v62
	ds_read_b64_tr_b4 v[46:47], v160 offset:256
	ds_read_b64_tr_b4 v[48:49], v160 offset:1280
	ds_read_b64_tr_b4 v[122:123], v54
	ds_read_b64_tr_b4 v[124:125], v55
	ds_read_b64_tr_b4 v[126:127], v56
	ds_read_b64_tr_b4 v[128:129], v57
	s_waitcnt lgkmcnt(6)
	v_dot8c_i32_i4_e32 v38, v130, v52
	v_dot8c_i32_i4_e32 v39, v130, v50
	v_dot8c_i32_i4_e32 v40, v132, v52
	v_dot8c_i32_i4_e32 v41, v132, v50
	v_dot8c_i32_i4_e32 v42, v134, v52
	v_dot8c_i32_i4_e32 v43, v134, v50
	v_dot8c_i32_i4_e32 v44, v136, v52
	v_dot8c_i32_i4_e32 v45, v136, v50
	v_dot8c_i32_i4_e32 v38, v131, v53
	v_dot8c_i32_i4_e32 v39, v131, v51
	v_dot8c_i32_i4_e32 v40, v133, v53
	v_dot8c_i32_i4_e32 v41, v133, v51
	v_dot8c_i32_i4_e32 v42, v135, v53
	v_dot8c_i32_i4_e32 v43, v135, v51
	v_dot8c_i32_i4_e32 v44, v137, v53
	v_dot8c_i32_i4_e32 v45, v137, v51
	v_and_b32_e32 v78, 0xffff, v25
	v_lshrrev_b32_e32 v79, 16, v25
	v_lshl_add_u32 v78, v78, 7, v150
	v_lshl_add_u32 v79, v79, 7, v151
	s_mov_b32 m0, s99
	s_add_i32 s43, s99, 0x400
	global_load_lds_dwordx4 v78, s[50:51]
	s_mov_b32 m0, s43
	s_nop 0
	global_load_lds_dwordx4 v79, s[50:51]
	s_waitcnt vmcnt(9)
; #define LAS __attribute__((address_space(3)))
; #define TR4(p_) __builtin_amdgcn_ds_read_tr4_b64_v2i32((LAS v2i*)(p_))
; __device__ __forceinline__ void peer_v_tokens(int j, const LAS unsigned short* EL, const LAS unsigned char* AL  , const LAS float* ASC  , const LAS int* SAL  , ...
;     ...
;         for (int m = 0; m < 2; ++m) {
;             const int idx = lane + 64 * m, tau = idx >> 4, sr = idx & 15, k = 16 * (sr & 7) + 2 * tau + (sr >> 3);
;             const int aq = (int)*(const LAS signed char*)(AL + tl * 128 + k); const int tq = aq + 8;
;             const unsigned lo = (((unsigned)tq & 15u) ^ 8u) * 0x11111111u, hi = ((unsigned)(tq >> 4) & 15u) * 0x11111111u;
;             typedef unsigned u2v __attribute__((ext_vector_type(2)));
;             u2v l2; l2.x = lo; l2.y = lo; u2v h2; h2.x = hi; h2.y = hi;
;             *(LAS u2v*)(ATL + 8 * idx) = l2; *(LAS u2v*)(ATL + 1024 + 8 * idx) = h2;
;         }
;     ...
;         for (int st = 0; st < 16; ++st) {
;             const int p = st >> 2, q = st & 3;
;             if (st < 14) VDMA(st + 2, (st + 2) % 3);
;             if (st < 14) asm volatile("s_waitcnt vmcnt(8)" ::: "memory");
;             else if (st == 14) asm volatile("s_waitcnt vmcnt(4)" ::: "memory");
;             else asm volatile("s_waitcnt vmcnt(0)" ::: "memory");
;             if (q == 0) {
; #pragma unroll
;                 for (int r = 0; r < 4; ++r) { accH[r] = 0; accL[r] = 0; } }
; #pragma unroll
;             for (int tp = 0; tp < 2; ++tp) {
;                 const v2i ao = TR4(ATL + (2 * q + tp) * 128 + 8 * s16), ah = TR4(ATL + 1024 + (2 * q + tp) * 128 + 8 * s16);
; #pragma unroll
;                 for (int r = 0; r < 4; ++r) {
;                     const v2i d = TR4(ldsb + BUF[st % 3] + 2048 * tp + roff[r]);
;                     accH[r] = __builtin_amdgcn_sdot8(d.x, ah.x, accH[r], false); accH[r] = __builtin_amdgcn_sdot8(d.y, ah.y, accH[r], false);
;                     accL[r] = __builtin_amdgcn_sdot8(d.x, ao.x, accL[r], false); accL[r] = __builtin_amdgcn_sdot8(d.y, ao.y, accL[r], false);
;                 }
;             }
	v_add_u32_e32 v54, s77, v59
	v_add_u32_e32 v55, s77, v60
	v_add_u32_e32 v56, s77, v61
	v_add_u32_e32 v57, s77, v62
	ds_read_b64_tr_b4 v[50:51], v160 offset:384
	ds_read_b64_tr_b4 v[52:53], v160 offset:1408
	ds_read_b64_tr_b4 v[130:131], v54
	ds_read_b64_tr_b4 v[132:133], v55
	ds_read_b64_tr_b4 v[134:135], v56
	ds_read_b64_tr_b4 v[136:137], v57
	s_waitcnt lgkmcnt(6)
	v_dot8c_i32_i4_e32 v38, v122, v48
	v_dot8c_i32_i4_e32 v39, v122, v46
	v_dot8c_i32_i4_e32 v40, v124, v48
	v_dot8c_i32_i4_e32 v41, v124, v46
	v_dot8c_i32_i4_e32 v42, v126, v48
	v_dot8c_i32_i4_e32 v43, v126, v46
	v_dot8c_i32_i4_e32 v44, v128, v48
	v_dot8c_i32_i4_e32 v45, v128, v46
	v_dot8c_i32_i4_e32 v38, v123, v49
	v_dot8c_i32_i4_e32 v39, v123, v47
	v_dot8c_i32_i4_e32 v40, v125, v49
	v_dot8c_i32_i4_e32 v41, v125, v47
	v_dot8c_i32_i4_e32 v42, v127, v49
	v_dot8c_i32_i4_e32 v43, v127, v47
	v_dot8c_i32_i4_e32 v44, v129, v49
	v_dot8c_i32_i4_e32 v45, v129, v47
	s_waitcnt lgkmcnt(15)
	v_and_b32_e32 v78, 0xffff, v26
	v_lshrrev_b32_e32 v79, 16, v26
	v_lshl_add_u32 v78, v78, 7, v150
	v_lshl_add_u32 v79, v79, 7, v151
	s_mov_b32 m0, s76
	s_add_i32 s43, s76, 0x400
	global_load_lds_dwordx4 v78, s[50:51]
	s_mov_b32 m0, s43
	s_nop 0
	global_load_lds_dwordx4 v79, s[50:51]
	s_waitcnt vmcnt(9)
	v_add_u32_e32 v54, s78, v59
	v_add_u32_e32 v55, s78, v60
	v_add_u32_e32 v56, s78, v61
	v_add_u32_e32 v57, s78, v62
	ds_read_b64_tr_b4 v[46:47], v160 offset:512
	ds_read_b64_tr_b4 v[48:49], v160 offset:1536
	ds_read_b64_tr_b4 v[122:123], v54
	ds_read_b64_tr_b4 v[124:125], v55
	ds_read_b64_tr_b4 v[126:127], v56
	ds_read_b64_tr_b4 v[128:129], v57
	s_waitcnt lgkmcnt(6)
	v_dot8c_i32_i4_e32 v38, v130, v52
	v_dot8c_i32_i4_e32 v39, v130, v50
	v_dot8c_i32_i4_e32 v40, v132, v52
	v_dot8c_i32_i4_e32 v41, v132, v50
	v_dot8c_i32_i4_e32 v42, v134, v52
	v_dot8c_i32_i4_e32 v43, v134, v50
	v_dot8c_i32_i4_e32 v44, v136, v52
	v_dot8c_i32_i4_e32 v45, v136, v50
	v_dot8c_i32_i4_e32 v38, v131, v53
	v_dot8c_i32_i4_e32 v39, v131, v51
	v_dot8c_i32_i4_e32 v40, v133, v53
	v_dot8c_i32_i4_e32 v41, v133, v51
	v_dot8c_i32_i4_e32 v42, v135, v53
	v_dot8c_i32_i4_e32 v43, v135, v51
	v_dot8c_i32_i4_e32 v44, v137, v53
	v_dot8c_i32_i4_e32 v45, v137, v51
	v_and_b32_e32 v78, 0xffff, v27
	v_lshrrev_b32_e32 v79, 16, v27
	v_lshl_add_u32 v78, v78, 7, v150
	v_lshl_add_u32 v79, v79, 7, v151
	s_mov_b32 m0, s77
	s_add_i32 s43, s77, 0x400
	global_load_lds_dwordx4 v78, s[50:51]
	s_mov_b32 m0, s43
	s_nop 0
	global_load_lds_dwordx4 v79, s[50:51]
	s_waitcnt vmcnt(8)
	v_add_u32_e32 v54, s79, v59
	v_add_u32_e32 v55, s79, v60
	v_add_u32_e32 v56, s79, v61
	v_add_u32_e32 v57, s79, v62
	ds_read_b64_tr_b4 v[50:51], v160 offset:640
	ds_read_b64_tr_b4 v[52:53], v160 offset:1664
	ds_read_b64_tr_b4 v[130:131], v54
	ds_read_b64_tr_b4 v[132:133], v55
	ds_read_b64_tr_b4 v[134:135], v56
	ds_read_b64_tr_b4 v[136:137], v57
	s_waitcnt lgkmcnt(6)
	v_dot8c_i32_i4_e32 v38, v122, v48
	v_dot8c_i32_i4_e32 v39, v122, v46
	v_dot8c_i32_i4_e32 v40, v124, v48
	v_dot8c_i32_i4_e32 v41, v124, v46
	v_dot8c_i32_i4_e32 v42, v126, v48
	v_dot8c_i32_i4_e32 v43, v126, v46
	v_dot8c_i32_i4_e32 v44, v128, v48
	v_dot8c_i32_i4_e32 v45, v128, v46
	v_dot8c_i32_i4_e32 v38, v123, v49
	v_dot8c_i32_i4_e32 v39, v123, v47
	v_dot8c_i32_i4_e32 v40, v125, v49
	v_dot8c_i32_i4_e32 v41, v125, v47
	v_dot8c_i32_i4_e32 v42, v127, v49
	v_dot8c_i32_i4_e32 v43, v127, v47
	v_dot8c_i32_i4_e32 v44, v129, v49
	v_dot8c_i32_i4_e32 v45, v129, v47
	s_waitcnt lgkmcnt(15)
	v_add_u32_e32 v143, 8, v139
	v_and_b32_e32 v142, 15, v143
	v_xor_b32_e32 v142, 8, v142
	v_bfe_u32 v144, v143, 4, 4
	v_mul_lo_u32 v142, v142, s92
	v_mul_lo_u32 v144, v144, s92
	v_mov_b32_e32 v143, v142
	v_mov_b32_e32 v145, v144
	ds_write2st64_b64 v159, v[142:143], v[144:145] offset1:2
	v_and_b32_e32 v78, 0xffff, v28
	v_lshrrev_b32_e32 v79, 16, v28
	v_lshl_add_u32 v78, v78, 7, v150
	v_lshl_add_u32 v79, v79, 7, v151
	s_mov_b32 m0, s78
	s_add_i32 s43, s78, 0x400
	global_load_lds_dwordx4 v78, s[50:51]
	s_mov_b32 m0, s43
	s_nop 0
	global_load_lds_dwordx4 v79, s[50:51]
	s_waitcnt vmcnt(8)
	v_add_u32_e32 v54, s98, v59
	v_add_u32_e32 v55, s98, v60
	v_add_u32_e32 v56, s98, v61
	v_add_u32_e32 v57, s98, v62
	ds_read_b64_tr_b4 v[46:47], v160 offset:768
	ds_read_b64_tr_b4 v[48:49], v160 offset:1792
	ds_read_b64_tr_b4 v[122:123], v54
	ds_read_b64_tr_b4 v[124:125], v55
	ds_read_b64_tr_b4 v[126:127], v56
	ds_read_b64_tr_b4 v[128:129], v57
	s_waitcnt lgkmcnt(7)
	v_dot8c_i32_i4_e32 v38, v130, v52
	v_dot8c_i32_i4_e32 v39, v130, v50
	v_dot8c_i32_i4_e32 v40, v132, v52
	v_dot8c_i32_i4_e32 v41, v132, v50
	v_dot8c_i32_i4_e32 v42, v134, v52
	v_dot8c_i32_i4_e32 v43, v134, v50
	v_dot8c_i32_i4_e32 v44, v136, v52
	v_dot8c_i32_i4_e32 v45, v136, v50
	v_dot8c_i32_i4_e32 v38, v131, v53
	v_dot8c_i32_i4_e32 v39, v131, v51
	v_dot8c_i32_i4_e32 v40, v133, v53
	v_dot8c_i32_i4_e32 v41, v133, v51
	v_dot8c_i32_i4_e32 v42, v135, v53
	v_dot8c_i32_i4_e32 v43, v135, v51
	v_dot8c_i32_i4_e32 v44, v137, v53
	v_dot8c_i32_i4_e32 v45, v137, v51
	v_and_b32_e32 v78, 0xffff, v29
	v_lshrrev_b32_e32 v79, 16, v29
	v_lshl_add_u32 v78, v78, 7, v150
	v_lshl_add_u32 v79, v79, 7, v151
	s_mov_b32 m0, s79
	s_add_i32 s43, s79, 0x400
	global_load_lds_dwordx4 v78, s[50:51]
	s_mov_b32 m0, s43
	s_nop 0
	global_load_lds_dwordx4 v79, s[50:51]
	s_waitcnt vmcnt(8)
	v_add_u32_e32 v54, s99, v59
	v_add_u32_e32 v55, s99, v60
	v_add_u32_e32 v56, s99, v61
	v_add_u32_e32 v57, s99, v62
	ds_read_b64_tr_b4 v[50:51], v160 offset:896
	ds_read_b64_tr_b4 v[52:53], v160 offset:1920
	ds_read_b64_tr_b4 v[130:131], v54
	ds_read_b64_tr_b4 v[132:133], v55
	ds_read_b64_tr_b4 v[134:135], v56
	ds_read_b64_tr_b4 v[136:137], v57
	s_waitcnt lgkmcnt(6)
; __device__ __forceinline__ bf16 f2bf(float f) { return (bf16)f2bfu(f); }
; #define TR4(p_) __builtin_amdgcn_ds_read_tr4_b64_v2i32((LAS v2i*)(p_))
; __device__ __forceinline__ void peer_v_tokens(int j, const LAS unsigned short* EL, const LAS unsigned char* AL  , const LAS float* ASC  , const LAS int* SAL  , ...
;     ...
;                     const v2i d = TR4(ldsb + BUF[st % 3] + 2048 * tp + roff[r]);
;                     accH[r] = __builtin_amdgcn_sdot8(d.x, ah.x, accH[r], false); accH[r] = __builtin_amdgcn_sdot8(d.y, ah.y, accH[r], false);
;                     accL[r] = __builtin_amdgcn_sdot8(d.x, ao.x, accL[r], false); accL[r] = __builtin_amdgcn_sdot8(d.y, ao.y, accL[r], false);
;                 }
;             }
;             asm volatile("s_waitcnt lgkmcnt(0)" ::: "memory");
;             if (q == 3) {
; #pragma unroll
;                 for (int r = 0; r < 4; ++r) STASH[256 * p + 16 * (grp + 4 * r) + pc] = f2bf(asc * (float)(2 * ((accH[r] << 4) + accL[r]) + sa));
;             }
;     ...
;             float4* op = (float4*)(outp + (size_t)t * D) + lane;
; #pragma unroll
;             for (int jq = 0; jq < 4; ++jq) { typedef float f4v __attribute__((ext_vector_type(4))); f4v o4; o4.x = v[jq].x * r3 * gv[jq].x; o4.y = v[jq].y * r3 * gv[jq].y; o4.z = v[jq].z * r3 * gv[jq].z; o4.w = v[jq].w * r3 * gv[jq].w;
;                 __builtin_nontemporal_store(o4, (f4v*)op + 64 * jq); }
	v_dot8c_i32_i4_e32 v38, v122, v48
	v_dot8c_i32_i4_e32 v39, v122, v46
	v_dot8c_i32_i4_e32 v40, v124, v48
	v_dot8c_i32_i4_e32 v41, v124, v46
	v_dot8c_i32_i4_e32 v42, v126, v48
	v_dot8c_i32_i4_e32 v43, v126, v46
	v_dot8c_i32_i4_e32 v44, v128, v48
	v_dot8c_i32_i4_e32 v45, v128, v46
	v_dot8c_i32_i4_e32 v38, v123, v49
	v_dot8c_i32_i4_e32 v39, v123, v47
	v_dot8c_i32_i4_e32 v40, v125, v49
	v_dot8c_i32_i4_e32 v41, v125, v47
	v_dot8c_i32_i4_e32 v42, v127, v49
	v_dot8c_i32_i4_e32 v43, v127, v47
	v_dot8c_i32_i4_e32 v44, v129, v49
	v_dot8c_i32_i4_e32 v45, v129, v47
	v_and_b32_e32 v78, 0xffff, v30
	v_lshrrev_b32_e32 v79, 16, v30
	v_lshl_add_u32 v78, v78, 7, v150
	v_lshl_add_u32 v79, v79, 7, v151
	s_mov_b32 m0, s98
	s_add_i32 s43, s98, 0x400
	global_load_lds_dwordx4 v78, s[50:51]
	s_mov_b32 m0, s43
	s_nop 0
	global_load_lds_dwordx4 v79, s[50:51]
	s_waitcnt vmcnt(8)
	v_add_u32_e32 v54, s76, v59
	v_add_u32_e32 v55, s76, v60
	v_add_u32_e32 v56, s76, v61
	v_add_u32_e32 v57, s76, v62
	ds_read_b64_tr_b4 v[46:47], v160
	ds_read_b64_tr_b4 v[48:49], v160 offset:1024
	ds_read_b64_tr_b4 v[122:123], v54
	ds_read_b64_tr_b4 v[124:125], v55
	ds_read_b64_tr_b4 v[126:127], v56
	ds_read_b64_tr_b4 v[128:129], v57
	s_waitcnt lgkmcnt(6)
	v_dot8c_i32_i4_e32 v38, v130, v52
	v_dot8c_i32_i4_e32 v39, v130, v50
	v_dot8c_i32_i4_e32 v40, v132, v52
	v_dot8c_i32_i4_e32 v41, v132, v50
	v_dot8c_i32_i4_e32 v42, v134, v52
	v_dot8c_i32_i4_e32 v43, v134, v50
	v_dot8c_i32_i4_e32 v44, v136, v52
	v_dot8c_i32_i4_e32 v45, v136, v50
	v_dot8c_i32_i4_e32 v38, v131, v53
	v_dot8c_i32_i4_e32 v39, v131, v51
	v_dot8c_i32_i4_e32 v40, v133, v53
	v_dot8c_i32_i4_e32 v41, v133, v51
	v_dot8c_i32_i4_e32 v42, v135, v53
	v_dot8c_i32_i4_e32 v43, v135, v51
	v_dot8c_i32_i4_e32 v44, v137, v53
	v_dot8c_i32_i4_e32 v45, v137, v51
	s_nop 3
	s_waitcnt lgkmcnt(15)
	v_lshlrev_b32_e32 v38, 5, v38
	v_lshlrev_b32_e32 v39, 1, v39
	v_add3_u32 v38, v39, v229, v38
	v_cvt_f32_i32_e32 v38, v38
	v_mul_f32_e32 v38, v228, v38
	v_lshlrev_b32_e32 v40, 5, v40
	v_lshlrev_b32_e32 v41, 1, v41
	v_add3_u32 v40, v41, v229, v40
	v_cvt_f32_i32_e32 v40, v40
	v_mul_f32_e32 v40, v228, v40
	v_lshlrev_b32_e32 v42, 5, v42
	v_lshlrev_b32_e32 v43, 1, v43
	v_add3_u32 v42, v43, v229, v42
	v_cvt_f32_i32_e32 v42, v42
	v_mul_f32_e32 v42, v228, v42
	v_lshlrev_b32_e32 v44, 5, v44
	v_lshlrev_b32_e32 v45, 1, v45
	v_add3_u32 v44, v45, v229, v44
	v_cvt_f32_i32_e32 v44, v44
	v_mul_f32_e32 v44, v228, v44
	v_cvt_pk_bf16_f32 v166, v38, v40
	v_cvt_pk_bf16_f32 v167, v42, v44
	ds_read_b128 v[252:255], v156 offset:1024
	s_add_i32 s44, s40, 16
	s_ashr_i32 s45, s44, 31
	s_lshl_b64 s[44:45], s[44:45], 12
	v_lshl_add_u64 v[80:81], v[36:37], 0, s[44:45]
	s_waitcnt lgkmcnt(0)
	v_mul_f32_e32 v222, v222, v252
	v_mul_f32_e32 v223, v223, v253
	v_mul_f32_e32 v224, v224, v254
	v_mul_f32_e32 v225, v225, v255
	global_store_dwordx4 v[80:81], v[222:225], off offset:3072 nt
	ds_read_b128 v[252:255], v155
	s_add_i32 s44, s40, 24
	s_ashr_i32 s45, s44, 31
	s_lshl_b64 s[44:45], s[44:45], 12
	v_lshl_add_u64 v[80:81], v[36:37], 0, s[44:45]
	s_waitcnt lgkmcnt(0)
	v_mul_f32_e32 v236, v236, v252
	v_mul_f32_e32 v237, v237, v253
	v_mul_f32_e32 v238, v238, v254
	v_mul_f32_e32 v239, v239, v255
	global_store_dwordx4 v[80:81], v[236:239], off nt
	v_add_u32_e32 v147, 8, v140
	v_and_b32_e32 v146, 15, v147
	v_xor_b32_e32 v146, 8, v146
	v_bfe_u32 v148, v147, 4, 4
	v_mul_lo_u32 v146, v146, s92
	v_mul_lo_u32 v148, v148, s92
	v_mov_b32_e32 v147, v146
	v_mov_b32_e32 v149, v148
	ds_write2st64_b64 v77, v[146:147], v[148:149] offset1:2
	v_add_u32_e32 v138, 0x1000, v74
	ds_read_u8 v139, v138
	v_add_u32_e32 v141, 0x1000, v73
	ds_read_u8 v140, v141
	s_add_i32 s43, s67, 160
	v_mov_b32_e32 v138, s43
	ds_read2st64_b32 v[228:229], v138 offset1:1
	ds_read_b128 v[18:21], v227 offset:8192
	ds_read_b128 v[22:25], v227 offset:8208
	v_add_u32_e32 v152, 0x600000, v63
	v_add_u32_e32 v153, 0x600000, v64
	v_mov_b32_e32 v38, 0
	v_mov_b32_e32 v39, 0
	v_mov_b32_e32 v40, 0
	v_mov_b32_e32 v41, 0
	v_mov_b32_e32 v42, 0
	v_mov_b32_e32 v43, 0
	v_mov_b32_e32 v44, 0
	v_mov_b32_e32 v45, 0
	v_and_b32_e32 v78, 0xffff, v31
	v_lshrrev_b32_e32 v79, 16, v31
	v_lshl_add_u32 v78, v78, 7, v150
	v_lshl_add_u32 v79, v79, 7, v151
	s_mov_b32 m0, s99
	s_add_i32 s43, s99, 0x400
	global_load_lds_dwordx4 v78, s[50:51]
	s_mov_b32 m0, s43
	s_nop 0
	global_load_lds_dwordx4 v79, s[50:51]
	s_waitcnt vmcnt(10)
	v_add_u32_e32 v54, s77, v59
	v_add_u32_e32 v55, s77, v60
	v_add_u32_e32 v56, s77, v61
	v_add_u32_e32 v57, s77, v62
	ds_read_b64_tr_b4 v[50:51], v160 offset:128
	ds_read_b64_tr_b4 v[52:53], v160 offset:1152
	ds_read_b64_tr_b4 v[130:131], v54
	ds_read_b64_tr_b4 v[132:133], v55
	ds_read_b64_tr_b4 v[134:135], v56
	ds_read_b64_tr_b4 v[136:137], v57
	s_waitcnt lgkmcnt(14)
	v_dot8c_i32_i4_e32 v38, v122, v48
	v_dot8c_i32_i4_e32 v39, v122, v46
	v_dot8c_i32_i4_e32 v40, v124, v48
	v_dot8c_i32_i4_e32 v41, v124, v46
	v_dot8c_i32_i4_e32 v42, v126, v48
	v_dot8c_i32_i4_e32 v43, v126, v46
	v_dot8c_i32_i4_e32 v44, v128, v48
	v_dot8c_i32_i4_e32 v45, v128, v46
	v_dot8c_i32_i4_e32 v38, v123, v49
	v_dot8c_i32_i4_e32 v39, v123, v47
	v_dot8c_i32_i4_e32 v40, v125, v49
	v_dot8c_i32_i4_e32 v41, v125, v47
	v_dot8c_i32_i4_e32 v42, v127, v49
	v_dot8c_i32_i4_e32 v43, v127, v47
	v_dot8c_i32_i4_e32 v44, v129, v49
	v_dot8c_i32_i4_e32 v45, v129, v47
	v_and_b32_e32 v78, 0xffff, v32
	v_lshrrev_b32_e32 v79, 16, v32
	v_lshl_add_u32 v78, v78, 7, v150
	v_lshl_add_u32 v79, v79, 7, v151
	s_mov_b32 m0, s76
	s_add_i32 s43, s76, 0x400
	global_load_lds_dwordx4 v78, s[50:51]
	s_mov_b32 m0, s43
	s_nop 0
	global_load_lds_dwordx4 v79, s[50:51]
	s_waitcnt vmcnt(10)
; #define TR4(p_) __builtin_amdgcn_ds_read_tr4_b64_v2i32((LAS v2i*)(p_))
; #define VDMA(st_, k_) do { _Pragma("unroll") for (int i_ = 0; i_ < 4; ++i_) { \
;         const unsigned off_ = (unsigned)((st_) >> 2) * (16384u * 128u) + (PE_ID(E, 4 * ((st_) & 3) + i_) << 7) + ((i_ & 1) ? cx1 : cx0); \
;         __builtin_amdgcn_global_load_lds((const unsigned*)(V4 + off_), (LAS unsigned*)(ldsb + BUF[k_] + 1024 * i_), 16, 0, 0); } } while (0)
; __device__ __forceinline__ void peer_v_tokens(int j, const LAS unsigned short* EL, const LAS unsigned char* AL  , const LAS float* ASC  , const LAS int* SAL  , ...
;     ...
;         for (int st = 0; st < 16; ++st) {
;             const int p = st >> 2, q = st & 3;
;             if (st < 14) VDMA(st + 2, (st + 2) % 3);
;             if (st < 14) asm volatile("s_waitcnt vmcnt(8)" ::: "memory");
;             else if (st == 14) asm volatile("s_waitcnt vmcnt(4)" ::: "memory");
;             else asm volatile("s_waitcnt vmcnt(0)" ::: "memory");
;             if (q == 0) {
; #pragma unroll
;                 for (int r = 0; r < 4; ++r) { accH[r] = 0; accL[r] = 0; } }
; #pragma unroll
;             for (int tp = 0; tp < 2; ++tp) {
;                 const v2i ao = TR4(ATL + (2 * q + tp) * 128 + 8 * s16), ah = TR4(ATL + 1024 + (2 * q + tp) * 128 + 8 * s16);
; #pragma unroll
;                 for (int r = 0; r < 4; ++r) {
;                     const v2i d = TR4(ldsb + BUF[st % 3] + 2048 * tp + roff[r]);
;                     accH[r] = __builtin_amdgcn_sdot8(d.x, ah.x, accH[r], false); accH[r] = __builtin_amdgcn_sdot8(d.y, ah.y, accH[r], false);
;                     accL[r] = __builtin_amdgcn_sdot8(d.x, ao.x, accL[r], false); accL[r] = __builtin_amdgcn_sdot8(d.y, ao.y, accL[r], false);
;                 }
;             }
	v_add_u32_e32 v54, s78, v59
	v_add_u32_e32 v55, s78, v60
	v_add_u32_e32 v56, s78, v61
	v_add_u32_e32 v57, s78, v62
	ds_read_b64_tr_b4 v[46:47], v160 offset:256
	ds_read_b64_tr_b4 v[48:49], v160 offset:1280
	ds_read_b64_tr_b4 v[122:123], v54
	ds_read_b64_tr_b4 v[124:125], v55
	ds_read_b64_tr_b4 v[126:127], v56
	ds_read_b64_tr_b4 v[128:129], v57
	s_waitcnt lgkmcnt(6)
	v_dot8c_i32_i4_e32 v38, v130, v52
	v_dot8c_i32_i4_e32 v39, v130, v50
	v_dot8c_i32_i4_e32 v40, v132, v52
	v_dot8c_i32_i4_e32 v41, v132, v50
	v_dot8c_i32_i4_e32 v42, v134, v52
	v_dot8c_i32_i4_e32 v43, v134, v50
	v_dot8c_i32_i4_e32 v44, v136, v52
	v_dot8c_i32_i4_e32 v45, v136, v50
	v_dot8c_i32_i4_e32 v38, v131, v53
	v_dot8c_i32_i4_e32 v39, v131, v51
	v_dot8c_i32_i4_e32 v40, v133, v53
	v_dot8c_i32_i4_e32 v41, v133, v51
	v_dot8c_i32_i4_e32 v42, v135, v53
	v_dot8c_i32_i4_e32 v43, v135, v51
	v_dot8c_i32_i4_e32 v44, v137, v53
	v_dot8c_i32_i4_e32 v45, v137, v51
	v_and_b32_e32 v78, 0xffff, v33
	v_lshrrev_b32_e32 v79, 16, v33
	v_lshl_add_u32 v78, v78, 7, v150
	v_lshl_add_u32 v79, v79, 7, v151
	s_mov_b32 m0, s77
	s_add_i32 s43, s77, 0x400
	global_load_lds_dwordx4 v78, s[50:51]
	s_mov_b32 m0, s43
	s_nop 0
	global_load_lds_dwordx4 v79, s[50:51]
	s_waitcnt vmcnt(10)
	v_add_u32_e32 v54, s79, v59
	v_add_u32_e32 v55, s79, v60
	v_add_u32_e32 v56, s79, v61
	v_add_u32_e32 v57, s79, v62
	ds_read_b64_tr_b4 v[50:51], v160 offset:384
	ds_read_b64_tr_b4 v[52:53], v160 offset:1408
	ds_read_b64_tr_b4 v[130:131], v54
	ds_read_b64_tr_b4 v[132:133], v55
	ds_read_b64_tr_b4 v[134:135], v56
	ds_read_b64_tr_b4 v[136:137], v57
	s_waitcnt lgkmcnt(6)
	v_dot8c_i32_i4_e32 v38, v122, v48
	v_dot8c_i32_i4_e32 v39, v122, v46
	v_dot8c_i32_i4_e32 v40, v124, v48
	v_dot8c_i32_i4_e32 v41, v124, v46
	v_dot8c_i32_i4_e32 v42, v126, v48
	v_dot8c_i32_i4_e32 v43, v126, v46
	v_dot8c_i32_i4_e32 v44, v128, v48
	v_dot8c_i32_i4_e32 v45, v128, v46
	v_dot8c_i32_i4_e32 v38, v123, v49
	v_dot8c_i32_i4_e32 v39, v123, v47
	v_dot8c_i32_i4_e32 v40, v125, v49
	v_dot8c_i32_i4_e32 v41, v125, v47
	v_dot8c_i32_i4_e32 v42, v127, v49
	v_dot8c_i32_i4_e32 v43, v127, v47
	v_dot8c_i32_i4_e32 v44, v129, v49
	v_dot8c_i32_i4_e32 v45, v129, v47
	s_waitcnt lgkmcnt(15)
	v_and_b32_e32 v78, 0xffff, v18
	v_lshrrev_b32_e32 v79, 16, v18
	v_lshl_add_u32 v78, v78, 7, v152
	v_lshl_add_u32 v79, v79, 7, v153
	s_mov_b32 m0, s78
	s_add_i32 s43, s78, 0x400
	global_load_lds_dwordx4 v78, s[50:51]
	s_mov_b32 m0, s43
	s_nop 0
	global_load_lds_dwordx4 v79, s[50:51]
	s_waitcnt vmcnt(10)
	v_add_u32_e32 v54, s98, v59
	v_add_u32_e32 v55, s98, v60
	v_add_u32_e32 v56, s98, v61
	v_add_u32_e32 v57, s98, v62
	ds_read_b64_tr_b4 v[46:47], v160 offset:512
	ds_read_b64_tr_b4 v[48:49], v160 offset:1536
	ds_read_b64_tr_b4 v[122:123], v54
	ds_read_b64_tr_b4 v[124:125], v55
	ds_read_b64_tr_b4 v[126:127], v56
	ds_read_b64_tr_b4 v[128:129], v57
	s_waitcnt lgkmcnt(6)
	v_dot8c_i32_i4_e32 v38, v130, v52
	v_dot8c_i32_i4_e32 v39, v130, v50
	v_dot8c_i32_i4_e32 v40, v132, v52
	v_dot8c_i32_i4_e32 v41, v132, v50
	v_dot8c_i32_i4_e32 v42, v134, v52
	v_dot8c_i32_i4_e32 v43, v134, v50
	v_dot8c_i32_i4_e32 v44, v136, v52
	v_dot8c_i32_i4_e32 v45, v136, v50
	v_dot8c_i32_i4_e32 v38, v131, v53
	v_dot8c_i32_i4_e32 v39, v131, v51
	v_dot8c_i32_i4_e32 v40, v133, v53
	v_dot8c_i32_i4_e32 v41, v133, v51
	v_dot8c_i32_i4_e32 v42, v135, v53
	v_dot8c_i32_i4_e32 v43, v135, v51
	v_dot8c_i32_i4_e32 v44, v137, v53
	v_dot8c_i32_i4_e32 v45, v137, v51
	v_and_b32_e32 v78, 0xffff, v19
	v_lshrrev_b32_e32 v79, 16, v19
	v_lshl_add_u32 v78, v78, 7, v152
	v_lshl_add_u32 v79, v79, 7, v153
	s_mov_b32 m0, s79
	s_add_i32 s43, s79, 0x400
	global_load_lds_dwordx4 v78, s[50:51]
	s_mov_b32 m0, s43
	s_nop 0
	global_load_lds_dwordx4 v79, s[50:51]
	s_waitcnt vmcnt(8)
	v_add_u32_e32 v54, s99, v59
	v_add_u32_e32 v55, s99, v60
	v_add_u32_e32 v56, s99, v61
	v_add_u32_e32 v57, s99, v62
	ds_read_b64_tr_b4 v[50:51], v160 offset:640
	ds_read_b64_tr_b4 v[52:53], v160 offset:1664
	ds_read_b64_tr_b4 v[130:131], v54
	ds_read_b64_tr_b4 v[132:133], v55
	ds_read_b64_tr_b4 v[134:135], v56
	ds_read_b64_tr_b4 v[136:137], v57
	s_waitcnt lgkmcnt(6)
	v_dot8c_i32_i4_e32 v38, v122, v48
	v_dot8c_i32_i4_e32 v39, v122, v46
	v_dot8c_i32_i4_e32 v40, v124, v48
	v_dot8c_i32_i4_e32 v41, v124, v46
	v_dot8c_i32_i4_e32 v42, v126, v48
	v_dot8c_i32_i4_e32 v43, v126, v46
	v_dot8c_i32_i4_e32 v44, v128, v48
	v_dot8c_i32_i4_e32 v45, v128, v46
	v_dot8c_i32_i4_e32 v38, v123, v49
	v_dot8c_i32_i4_e32 v39, v123, v47
	v_dot8c_i32_i4_e32 v40, v125, v49
	v_dot8c_i32_i4_e32 v41, v125, v47
	v_dot8c_i32_i4_e32 v42, v127, v49
	v_dot8c_i32_i4_e32 v43, v127, v47
	v_dot8c_i32_i4_e32 v44, v129, v49
	v_dot8c_i32_i4_e32 v45, v129, v47
	s_waitcnt lgkmcnt(15)
	v_add_u32_e32 v143, 8, v139
	v_and_b32_e32 v142, 15, v143
	v_xor_b32_e32 v142, 8, v142
	v_bfe_u32 v144, v143, 4, 4
	v_mul_lo_u32 v142, v142, s92
	v_mul_lo_u32 v144, v144, s92
	v_mov_b32_e32 v143, v142
	v_mov_b32_e32 v145, v144
	ds_write2st64_b64 v159, v[142:143], v[144:145] offset1:2
	v_and_b32_e32 v78, 0xffff, v20
	v_lshrrev_b32_e32 v79, 16, v20
	v_lshl_add_u32 v78, v78, 7, v152
	v_lshl_add_u32 v79, v79, 7, v153
	s_mov_b32 m0, s98
	s_add_i32 s43, s98, 0x400
	global_load_lds_dwordx4 v78, s[50:51]
	s_mov_b32 m0, s43
	s_nop 0
	global_load_lds_dwordx4 v79, s[50:51]
	s_waitcnt vmcnt(8)
	v_add_u32_e32 v54, s76, v59
	v_add_u32_e32 v55, s76, v60
	v_add_u32_e32 v56, s76, v61
	v_add_u32_e32 v57, s76, v62
	ds_read_b64_tr_b4 v[46:47], v160 offset:768
	ds_read_b64_tr_b4 v[48:49], v160 offset:1792
	ds_read_b64_tr_b4 v[122:123], v54
	ds_read_b64_tr_b4 v[124:125], v55
	ds_read_b64_tr_b4 v[126:127], v56
	ds_read_b64_tr_b4 v[128:129], v57
	s_waitcnt lgkmcnt(7)
; __device__ __forceinline__ bf16 f2bf(float f) { return (bf16)f2bfu(f); }
; #define TR4(p_) __builtin_amdgcn_ds_read_tr4_b64_v2i32((LAS v2i*)(p_))
; __device__ __forceinline__ void peer_v_tokens(int j, const LAS unsigned short* EL, const LAS unsigned char* AL  , const LAS float* ASC  , const LAS int* SAL  , ...
;     ...
;         for (int st = 0; st < 16; ++st) {
;             const int p = st >> 2, q = st & 3;
;             if (st < 14) VDMA(st + 2, (st + 2) % 3);
;             if (st < 14) asm volatile("s_waitcnt vmcnt(8)" ::: "memory");
;             else if (st == 14) asm volatile("s_waitcnt vmcnt(4)" ::: "memory");
;             else asm volatile("s_waitcnt vmcnt(0)" ::: "memory");
;             if (q == 0) {
; #pragma unroll
;                 for (int r = 0; r < 4; ++r) { accH[r] = 0; accL[r] = 0; } }
; #pragma unroll
;             for (int tp = 0; tp < 2; ++tp) {
;                 const v2i ao = TR4(ATL + (2 * q + tp) * 128 + 8 * s16), ah = TR4(ATL + 1024 + (2 * q + tp) * 128 + 8 * s16);
; #pragma unroll
;                 for (int r = 0; r < 4; ++r) {
;                     const v2i d = TR4(ldsb + BUF[st % 3] + 2048 * tp + roff[r]);
;                     accH[r] = __builtin_amdgcn_sdot8(d.x, ah.x, accH[r], false); accH[r] = __builtin_amdgcn_sdot8(d.y, ah.y, accH[r], false);
;                     accL[r] = __builtin_amdgcn_sdot8(d.x, ao.x, accL[r], false); accL[r] = __builtin_amdgcn_sdot8(d.y, ao.y, accL[r], false);
;                 }
;             }
;             asm volatile("s_waitcnt lgkmcnt(0)" ::: "memory");
;             if (q == 3) {
; #pragma unroll
;                 for (int r = 0; r < 4; ++r) STASH[256 * p + 16 * (grp + 4 * r) + pc] = f2bf(asc * (float)(2 * ((accH[r] << 4) + accL[r]) + sa));
;             }
;     ...
;             float4* op = (float4*)(outp + (size_t)t * D) + lane;
; #pragma unroll
;             for (int jq = 0; jq < 4; ++jq) { typedef float f4v __attribute__((ext_vector_type(4))); f4v o4; o4.x = v[jq].x * r3 * gv[jq].x; o4.y = v[jq].y * r3 * gv[jq].y; o4.z = v[jq].z * r3 * gv[jq].z; o4.w = v[jq].w * r3 * gv[jq].w;
;                 __builtin_nontemporal_store(o4, (f4v*)op + 64 * jq); }
	v_dot8c_i32_i4_e32 v38, v130, v52
	v_dot8c_i32_i4_e32 v39, v130, v50
	v_dot8c_i32_i4_e32 v40, v132, v52
	v_dot8c_i32_i4_e32 v41, v132, v50
	v_dot8c_i32_i4_e32 v42, v134, v52
	v_dot8c_i32_i4_e32 v43, v134, v50
	v_dot8c_i32_i4_e32 v44, v136, v52
	v_dot8c_i32_i4_e32 v45, v136, v50
	v_dot8c_i32_i4_e32 v38, v131, v53
	v_dot8c_i32_i4_e32 v39, v131, v51
	v_dot8c_i32_i4_e32 v40, v133, v53
	v_dot8c_i32_i4_e32 v41, v133, v51
	v_dot8c_i32_i4_e32 v42, v135, v53
	v_dot8c_i32_i4_e32 v43, v135, v51
	v_dot8c_i32_i4_e32 v44, v137, v53
	v_dot8c_i32_i4_e32 v45, v137, v51
	v_and_b32_e32 v78, 0xffff, v21
	v_lshrrev_b32_e32 v79, 16, v21
	v_lshl_add_u32 v78, v78, 7, v152
	v_lshl_add_u32 v79, v79, 7, v153
	s_mov_b32 m0, s99
	s_add_i32 s43, s99, 0x400
	global_load_lds_dwordx4 v78, s[50:51]
	s_mov_b32 m0, s43
	s_nop 0
	global_load_lds_dwordx4 v79, s[50:51]
	s_waitcnt vmcnt(8)
	v_add_u32_e32 v54, s77, v59
	v_add_u32_e32 v55, s77, v60
	v_add_u32_e32 v56, s77, v61
	v_add_u32_e32 v57, s77, v62
	ds_read_b64_tr_b4 v[50:51], v160 offset:896
	ds_read_b64_tr_b4 v[52:53], v160 offset:1920
	ds_read_b64_tr_b4 v[130:131], v54
	ds_read_b64_tr_b4 v[132:133], v55
	ds_read_b64_tr_b4 v[134:135], v56
	ds_read_b64_tr_b4 v[136:137], v57
	s_waitcnt lgkmcnt(6)
	v_dot8c_i32_i4_e32 v38, v122, v48
	v_dot8c_i32_i4_e32 v39, v122, v46
	v_dot8c_i32_i4_e32 v40, v124, v48
	v_dot8c_i32_i4_e32 v41, v124, v46
	v_dot8c_i32_i4_e32 v42, v126, v48
	v_dot8c_i32_i4_e32 v43, v126, v46
	v_dot8c_i32_i4_e32 v44, v128, v48
	v_dot8c_i32_i4_e32 v45, v128, v46
	v_dot8c_i32_i4_e32 v38, v123, v49
	v_dot8c_i32_i4_e32 v39, v123, v47
	v_dot8c_i32_i4_e32 v40, v125, v49
	v_dot8c_i32_i4_e32 v41, v125, v47
	v_dot8c_i32_i4_e32 v42, v127, v49
	v_dot8c_i32_i4_e32 v43, v127, v47
	v_dot8c_i32_i4_e32 v44, v129, v49
	v_dot8c_i32_i4_e32 v45, v129, v47
	v_and_b32_e32 v78, 0xffff, v22
	v_lshrrev_b32_e32 v79, 16, v22
	v_lshl_add_u32 v78, v78, 7, v152
	v_lshl_add_u32 v79, v79, 7, v153
	s_mov_b32 m0, s76
	s_add_i32 s43, s76, 0x400
	global_load_lds_dwordx4 v78, s[50:51]
	s_mov_b32 m0, s43
	s_nop 0
	global_load_lds_dwordx4 v79, s[50:51]
	s_waitcnt vmcnt(8)
	v_add_u32_e32 v54, s78, v59
	v_add_u32_e32 v55, s78, v60
	v_add_u32_e32 v56, s78, v61
	v_add_u32_e32 v57, s78, v62
	ds_read_b64_tr_b4 v[46:47], v160
	ds_read_b64_tr_b4 v[48:49], v160 offset:1024
	ds_read_b64_tr_b4 v[122:123], v54
	ds_read_b64_tr_b4 v[124:125], v55
	ds_read_b64_tr_b4 v[126:127], v56
	ds_read_b64_tr_b4 v[128:129], v57
	s_waitcnt lgkmcnt(6)
	v_dot8c_i32_i4_e32 v38, v130, v52
	v_dot8c_i32_i4_e32 v39, v130, v50
	v_dot8c_i32_i4_e32 v40, v132, v52
	v_dot8c_i32_i4_e32 v41, v132, v50
	v_dot8c_i32_i4_e32 v42, v134, v52
	v_dot8c_i32_i4_e32 v43, v134, v50
	v_dot8c_i32_i4_e32 v44, v136, v52
	v_dot8c_i32_i4_e32 v45, v136, v50
	v_dot8c_i32_i4_e32 v38, v131, v53
	v_dot8c_i32_i4_e32 v39, v131, v51
	v_dot8c_i32_i4_e32 v40, v133, v53
	v_dot8c_i32_i4_e32 v41, v133, v51
	v_dot8c_i32_i4_e32 v42, v135, v53
	v_dot8c_i32_i4_e32 v43, v135, v51
	v_dot8c_i32_i4_e32 v44, v137, v53
	v_dot8c_i32_i4_e32 v45, v137, v51
	s_nop 3
	s_waitcnt lgkmcnt(15)
	v_lshlrev_b32_e32 v38, 5, v38
	v_lshlrev_b32_e32 v39, 1, v39
	v_add3_u32 v38, v39, v229, v38
	v_cvt_f32_i32_e32 v38, v38
	v_mul_f32_e32 v38, v228, v38
	v_lshlrev_b32_e32 v40, 5, v40
	v_lshlrev_b32_e32 v41, 1, v41
	v_add3_u32 v40, v41, v229, v40
	v_cvt_f32_i32_e32 v40, v40
	v_mul_f32_e32 v40, v228, v40
	v_lshlrev_b32_e32 v42, 5, v42
	v_lshlrev_b32_e32 v43, 1, v43
	v_add3_u32 v42, v43, v229, v42
	v_cvt_f32_i32_e32 v42, v42
	v_mul_f32_e32 v42, v228, v42
	v_lshlrev_b32_e32 v44, 5, v44
	v_lshlrev_b32_e32 v45, 1, v45
	v_add3_u32 v44, v45, v229, v44
	v_cvt_f32_i32_e32 v44, v44
	v_mul_f32_e32 v44, v228, v44
	v_cvt_pk_bf16_f32 v174, v38, v40
	v_cvt_pk_bf16_f32 v175, v42, v44
	ds_read_b128 v[252:255], v155 offset:1024
	s_add_i32 s44, s40, 24
	s_ashr_i32 s45, s44, 31
	s_lshl_b64 s[44:45], s[44:45], 12
	v_lshl_add_u64 v[80:81], v[36:37], 0, s[44:45]
	s_waitcnt lgkmcnt(0)
	v_mul_f32_e32 v240, v240, v252
	v_mul_f32_e32 v241, v241, v253
	v_mul_f32_e32 v242, v242, v254
	v_mul_f32_e32 v243, v243, v255
	global_store_dwordx4 v[80:81], v[240:243], off offset:1024 nt
	v_add_u32_e32 v147, 8, v140
	v_and_b32_e32 v146, 15, v147
	v_xor_b32_e32 v146, 8, v146
	v_bfe_u32 v148, v147, 4, 4
	v_mul_lo_u32 v146, v146, s92
	v_mul_lo_u32 v148, v148, s92
	v_mov_b32_e32 v147, v146
	v_mov_b32_e32 v149, v148
	ds_write2st64_b64 v77, v[146:147], v[148:149] offset1:2
	v_add_u32_e32 v138, 0x1400, v74
	ds_read_u8 v139, v138
	v_add_u32_e32 v141, 0x1400, v73
	ds_read_u8 v140, v141
	s_add_i32 s43, s67, 128
	v_mov_b32_e32 v138, s43
	ds_read2st64_b32 v[228:229], v138 offset1:1
	ds_read_b128 v[26:29], v227 offset:10240
	ds_read_b128 v[30:33], v227 offset:10256
	v_mov_b32_e32 v38, 0
	v_mov_b32_e32 v39, 0
	v_mov_b32_e32 v40, 0
	v_mov_b32_e32 v41, 0
	v_mov_b32_e32 v42, 0
	v_mov_b32_e32 v43, 0
	v_mov_b32_e32 v44, 0
	v_mov_b32_e32 v45, 0
	v_and_b32_e32 v78, 0xffff, v23
	v_lshrrev_b32_e32 v79, 16, v23
	v_lshl_add_u32 v78, v78, 7, v152
	v_lshl_add_u32 v79, v79, 7, v153
	s_mov_b32 m0, s77
	s_add_i32 s43, s77, 0x400
	global_load_lds_dwordx4 v78, s[50:51]
	s_mov_b32 m0, s43
	s_nop 0
	global_load_lds_dwordx4 v79, s[50:51]
	s_waitcnt vmcnt(9)
	v_add_u32_e32 v54, s79, v59
	v_add_u32_e32 v55, s79, v60
	v_add_u32_e32 v56, s79, v61
	v_add_u32_e32 v57, s79, v62
	ds_read_b64_tr_b4 v[50:51], v160 offset:128
	ds_read_b64_tr_b4 v[52:53], v160 offset:1152
	ds_read_b64_tr_b4 v[130:131], v54
	ds_read_b64_tr_b4 v[132:133], v55
	ds_read_b64_tr_b4 v[134:135], v56
	ds_read_b64_tr_b4 v[136:137], v57
	s_waitcnt lgkmcnt(13)
; #define TR4(p_) __builtin_amdgcn_ds_read_tr4_b64_v2i32((LAS v2i*)(p_))
; #define VDMA(st_, k_) do { _Pragma("unroll") for (int i_ = 0; i_ < 4; ++i_) { \
;         const unsigned off_ = (unsigned)((st_) >> 2) * (16384u * 128u) + (PE_ID(E, 4 * ((st_) & 3) + i_) << 7) + ((i_ & 1) ? cx1 : cx0); \
;         __builtin_amdgcn_global_load_lds((const unsigned*)(V4 + off_), (LAS unsigned*)(ldsb + BUF[k_] + 1024 * i_), 16, 0, 0); } } while (0)
; __device__ __forceinline__ void peer_v_tokens(int j, const LAS unsigned short* EL, const LAS unsigned char* AL  , const LAS float* ASC  , const LAS int* SAL  , ...
;     ...
;         for (int st = 0; st < 16; ++st) {
;             const int p = st >> 2, q = st & 3;
;             if (st < 14) VDMA(st + 2, (st + 2) % 3);
;             if (st < 14) asm volatile("s_waitcnt vmcnt(8)" ::: "memory");
;             else if (st == 14) asm volatile("s_waitcnt vmcnt(4)" ::: "memory");
;             else asm volatile("s_waitcnt vmcnt(0)" ::: "memory");
;             if (q == 0) {
; #pragma unroll
;                 for (int r = 0; r < 4; ++r) { accH[r] = 0; accL[r] = 0; } }
; #pragma unroll
;             for (int tp = 0; tp < 2; ++tp) {
;                 const v2i ao = TR4(ATL + (2 * q + tp) * 128 + 8 * s16), ah = TR4(ATL + 1024 + (2 * q + tp) * 128 + 8 * s16);
; #pragma unroll
;                 for (int r = 0; r < 4; ++r) {
;                     const v2i d = TR4(ldsb + BUF[st % 3] + 2048 * tp + roff[r]);
;                     accH[r] = __builtin_amdgcn_sdot8(d.x, ah.x, accH[r], false); accH[r] = __builtin_amdgcn_sdot8(d.y, ah.y, accH[r], false);
;                     accL[r] = __builtin_amdgcn_sdot8(d.x, ao.x, accL[r], false); accL[r] = __builtin_amdgcn_sdot8(d.y, ao.y, accL[r], false);
;                 }
;             }
	v_dot8c_i32_i4_e32 v38, v122, v48
	v_dot8c_i32_i4_e32 v39, v122, v46
	v_dot8c_i32_i4_e32 v40, v124, v48
	v_dot8c_i32_i4_e32 v41, v124, v46
	v_dot8c_i32_i4_e32 v42, v126, v48
	v_dot8c_i32_i4_e32 v43, v126, v46
	v_dot8c_i32_i4_e32 v44, v128, v48
	v_dot8c_i32_i4_e32 v45, v128, v46
	v_dot8c_i32_i4_e32 v38, v123, v49
	v_dot8c_i32_i4_e32 v39, v123, v47
	v_dot8c_i32_i4_e32 v40, v125, v49
	v_dot8c_i32_i4_e32 v41, v125, v47
	v_dot8c_i32_i4_e32 v42, v127, v49
	v_dot8c_i32_i4_e32 v43, v127, v47
	v_dot8c_i32_i4_e32 v44, v129, v49
	v_dot8c_i32_i4_e32 v45, v129, v47
	v_and_b32_e32 v78, 0xffff, v24
	v_lshrrev_b32_e32 v79, 16, v24
	v_lshl_add_u32 v78, v78, 7, v152
	v_lshl_add_u32 v79, v79, 7, v153
	s_mov_b32 m0, s78
	s_add_i32 s43, s78, 0x400
	global_load_lds_dwordx4 v78, s[50:51]
	s_mov_b32 m0, s43
	s_nop 0
	global_load_lds_dwordx4 v79, s[50:51]
	s_waitcnt vmcnt(9)
	v_add_u32_e32 v54, s98, v59
	v_add_u32_e32 v55, s98, v60
	v_add_u32_e32 v56, s98, v61
	v_add_u32_e32 v57, s98, v62
	ds_read_b64_tr_b4 v[46:47], v160 offset:256
	ds_read_b64_tr_b4 v[48:49], v160 offset:1280
	ds_read_b64_tr_b4 v[122:123], v54
	ds_read_b64_tr_b4 v[124:125], v55
	ds_read_b64_tr_b4 v[126:127], v56
	ds_read_b64_tr_b4 v[128:129], v57
	s_waitcnt lgkmcnt(6)
	v_dot8c_i32_i4_e32 v38, v130, v52
	v_dot8c_i32_i4_e32 v39, v130, v50
	v_dot8c_i32_i4_e32 v40, v132, v52
	v_dot8c_i32_i4_e32 v41, v132, v50
	v_dot8c_i32_i4_e32 v42, v134, v52
	v_dot8c_i32_i4_e32 v43, v134, v50
	v_dot8c_i32_i4_e32 v44, v136, v52
	v_dot8c_i32_i4_e32 v45, v136, v50
	v_dot8c_i32_i4_e32 v38, v131, v53
	v_dot8c_i32_i4_e32 v39, v131, v51
	v_dot8c_i32_i4_e32 v40, v133, v53
	v_dot8c_i32_i4_e32 v41, v133, v51
	v_dot8c_i32_i4_e32 v42, v135, v53
	v_dot8c_i32_i4_e32 v43, v135, v51
	v_dot8c_i32_i4_e32 v44, v137, v53
	v_dot8c_i32_i4_e32 v45, v137, v51
	v_and_b32_e32 v78, 0xffff, v25
	v_lshrrev_b32_e32 v79, 16, v25
	v_lshl_add_u32 v78, v78, 7, v152
	v_lshl_add_u32 v79, v79, 7, v153
	s_mov_b32 m0, s79
	s_add_i32 s43, s79, 0x400
	global_load_lds_dwordx4 v78, s[50:51]
	s_mov_b32 m0, s43
	s_nop 0
	global_load_lds_dwordx4 v79, s[50:51]
	s_waitcnt vmcnt(9)
	v_add_u32_e32 v54, s99, v59
	v_add_u32_e32 v55, s99, v60
	v_add_u32_e32 v56, s99, v61
	v_add_u32_e32 v57, s99, v62
	ds_read_b64_tr_b4 v[50:51], v160 offset:384
	ds_read_b64_tr_b4 v[52:53], v160 offset:1408
	ds_read_b64_tr_b4 v[130:131], v54
	ds_read_b64_tr_b4 v[132:133], v55
	ds_read_b64_tr_b4 v[134:135], v56
	ds_read_b64_tr_b4 v[136:137], v57
	s_waitcnt lgkmcnt(6)
	v_dot8c_i32_i4_e32 v38, v122, v48
	v_dot8c_i32_i4_e32 v39, v122, v46
	v_dot8c_i32_i4_e32 v40, v124, v48
	v_dot8c_i32_i4_e32 v41, v124, v46
	v_dot8c_i32_i4_e32 v42, v126, v48
	v_dot8c_i32_i4_e32 v43, v126, v46
	v_dot8c_i32_i4_e32 v44, v128, v48
	v_dot8c_i32_i4_e32 v45, v128, v46
	v_dot8c_i32_i4_e32 v38, v123, v49
	v_dot8c_i32_i4_e32 v39, v123, v47
	v_dot8c_i32_i4_e32 v40, v125, v49
	v_dot8c_i32_i4_e32 v41, v125, v47
	v_dot8c_i32_i4_e32 v42, v127, v49
	v_dot8c_i32_i4_e32 v43, v127, v47
	v_dot8c_i32_i4_e32 v44, v129, v49
	v_dot8c_i32_i4_e32 v45, v129, v47
	s_waitcnt lgkmcnt(15)
	v_and_b32_e32 v78, 0xffff, v26
	v_lshrrev_b32_e32 v79, 16, v26
	v_lshl_add_u32 v78, v78, 7, v152
	v_lshl_add_u32 v79, v79, 7, v153
	s_mov_b32 m0, s98
	s_add_i32 s43, s98, 0x400
	global_load_lds_dwordx4 v78, s[50:51]
	s_mov_b32 m0, s43
	s_nop 0
	global_load_lds_dwordx4 v79, s[50:51]
	s_waitcnt vmcnt(9)
	v_add_u32_e32 v54, s76, v59
	v_add_u32_e32 v55, s76, v60
	v_add_u32_e32 v56, s76, v61
	v_add_u32_e32 v57, s76, v62
	ds_read_b64_tr_b4 v[46:47], v160 offset:512
	ds_read_b64_tr_b4 v[48:49], v160 offset:1536
	ds_read_b64_tr_b4 v[122:123], v54
	ds_read_b64_tr_b4 v[124:125], v55
	ds_read_b64_tr_b4 v[126:127], v56
	ds_read_b64_tr_b4 v[128:129], v57
	s_waitcnt lgkmcnt(6)
	v_dot8c_i32_i4_e32 v38, v130, v52
	v_dot8c_i32_i4_e32 v39, v130, v50
	v_dot8c_i32_i4_e32 v40, v132, v52
	v_dot8c_i32_i4_e32 v41, v132, v50
	v_dot8c_i32_i4_e32 v42, v134, v52
	v_dot8c_i32_i4_e32 v43, v134, v50
	v_dot8c_i32_i4_e32 v44, v136, v52
	v_dot8c_i32_i4_e32 v45, v136, v50
	v_dot8c_i32_i4_e32 v38, v131, v53
	v_dot8c_i32_i4_e32 v39, v131, v51
	v_dot8c_i32_i4_e32 v40, v133, v53
	v_dot8c_i32_i4_e32 v41, v133, v51
	v_dot8c_i32_i4_e32 v42, v135, v53
	v_dot8c_i32_i4_e32 v43, v135, v51
	v_dot8c_i32_i4_e32 v44, v137, v53
	v_dot8c_i32_i4_e32 v45, v137, v51
	v_and_b32_e32 v78, 0xffff, v27
	v_lshrrev_b32_e32 v79, 16, v27
	v_lshl_add_u32 v78, v78, 7, v152
	v_lshl_add_u32 v79, v79, 7, v153
	s_mov_b32 m0, s99
	s_add_i32 s43, s99, 0x400
	global_load_lds_dwordx4 v78, s[50:51]
	s_mov_b32 m0, s43
	s_nop 0
	global_load_lds_dwordx4 v79, s[50:51]
	s_waitcnt vmcnt(8)
	v_add_u32_e32 v54, s77, v59
	v_add_u32_e32 v55, s77, v60
	v_add_u32_e32 v56, s77, v61
	v_add_u32_e32 v57, s77, v62
	ds_read_b64_tr_b4 v[50:51], v160 offset:640
	ds_read_b64_tr_b4 v[52:53], v160 offset:1664
	ds_read_b64_tr_b4 v[130:131], v54
	ds_read_b64_tr_b4 v[132:133], v55
	ds_read_b64_tr_b4 v[134:135], v56
	ds_read_b64_tr_b4 v[136:137], v57
	s_waitcnt lgkmcnt(6)
	v_dot8c_i32_i4_e32 v38, v122, v48
	v_dot8c_i32_i4_e32 v39, v122, v46
	v_dot8c_i32_i4_e32 v40, v124, v48
	v_dot8c_i32_i4_e32 v41, v124, v46
	v_dot8c_i32_i4_e32 v42, v126, v48
	v_dot8c_i32_i4_e32 v43, v126, v46
	v_dot8c_i32_i4_e32 v44, v128, v48
	v_dot8c_i32_i4_e32 v45, v128, v46
	v_dot8c_i32_i4_e32 v38, v123, v49
	v_dot8c_i32_i4_e32 v39, v123, v47
	v_dot8c_i32_i4_e32 v40, v125, v49
	v_dot8c_i32_i4_e32 v41, v125, v47
	v_dot8c_i32_i4_e32 v42, v127, v49
	v_dot8c_i32_i4_e32 v43, v127, v47
	v_dot8c_i32_i4_e32 v44, v129, v49
	v_dot8c_i32_i4_e32 v45, v129, v47
	s_waitcnt lgkmcnt(15)
; __device__ __forceinline__ bf16 f2bf(float f) { return (bf16)f2bfu(f); }
; #define TR4(p_) __builtin_amdgcn_ds_read_tr4_b64_v2i32((LAS v2i*)(p_))
; #define VDMA(st_, k_) do { _Pragma("unroll") for (int i_ = 0; i_ < 4; ++i_) { \
;         const unsigned off_ = (unsigned)((st_) >> 2) * (16384u * 128u) + (PE_ID(E, 4 * ((st_) & 3) + i_) << 7) + ((i_ & 1) ? cx1 : cx0); \
;         __builtin_amdgcn_global_load_lds((const unsigned*)(V4 + off_), (LAS unsigned*)(ldsb + BUF[k_] + 1024 * i_), 16, 0, 0); } } while (0)
; __device__ __forceinline__ void peer_v_tokens(int j, const LAS unsigned short* EL, const LAS unsigned char* AL  , const LAS float* ASC  , const LAS int* SAL  , ...
;     ...
;         for (int st = 0; st < 16; ++st) {
;             const int p = st >> 2, q = st & 3;
;             if (st < 14) VDMA(st + 2, (st + 2) % 3);
;             if (st < 14) asm volatile("s_waitcnt vmcnt(8)" ::: "memory");
;             else if (st == 14) asm volatile("s_waitcnt vmcnt(4)" ::: "memory");
;             else asm volatile("s_waitcnt vmcnt(0)" ::: "memory");
;             if (q == 0) {
; #pragma unroll
;                 for (int r = 0; r < 4; ++r) { accH[r] = 0; accL[r] = 0; } }
; #pragma unroll
;             for (int tp = 0; tp < 2; ++tp) {
;                 const v2i ao = TR4(ATL + (2 * q + tp) * 128 + 8 * s16), ah = TR4(ATL + 1024 + (2 * q + tp) * 128 + 8 * s16);
; #pragma unroll
;                 for (int r = 0; r < 4; ++r) {
;                     const v2i d = TR4(ldsb + BUF[st % 3] + 2048 * tp + roff[r]);
;                     accH[r] = __builtin_amdgcn_sdot8(d.x, ah.x, accH[r], false); accH[r] = __builtin_amdgcn_sdot8(d.y, ah.y, accH[r], false);
;                     accL[r] = __builtin_amdgcn_sdot8(d.x, ao.x, accL[r], false); accL[r] = __builtin_amdgcn_sdot8(d.y, ao.y, accL[r], false);
;                 }
;             }
;             asm volatile("s_waitcnt lgkmcnt(0)" ::: "memory");
;             if (q == 3) {
; #pragma unroll
;                 for (int r = 0; r < 4; ++r) STASH[256 * p + 16 * (grp + 4 * r) + pc] = f2bf(asc * (float)(2 * ((accH[r] << 4) + accL[r]) + sa));
;             }
	v_add_u32_e32 v143, 8, v139
	v_and_b32_e32 v142, 15, v143
	v_xor_b32_e32 v142, 8, v142
	v_bfe_u32 v144, v143, 4, 4
	v_mul_lo_u32 v142, v142, s92
	v_mul_lo_u32 v144, v144, s92
	v_mov_b32_e32 v143, v142
	v_mov_b32_e32 v145, v144
	ds_write2st64_b64 v159, v[142:143], v[144:145] offset1:2
	v_and_b32_e32 v78, 0xffff, v28
	v_lshrrev_b32_e32 v79, 16, v28
	v_lshl_add_u32 v78, v78, 7, v152
	v_lshl_add_u32 v79, v79, 7, v153
	s_mov_b32 m0, s76
	s_add_i32 s43, s76, 0x400
	global_load_lds_dwordx4 v78, s[50:51]
	s_mov_b32 m0, s43
	s_nop 0
	global_load_lds_dwordx4 v79, s[50:51]
	s_waitcnt vmcnt(8)
	v_add_u32_e32 v54, s78, v59
	v_add_u32_e32 v55, s78, v60
	v_add_u32_e32 v56, s78, v61
	v_add_u32_e32 v57, s78, v62
	ds_read_b64_tr_b4 v[46:47], v160 offset:768
	ds_read_b64_tr_b4 v[48:49], v160 offset:1792
	ds_read_b64_tr_b4 v[122:123], v54
	ds_read_b64_tr_b4 v[124:125], v55
	ds_read_b64_tr_b4 v[126:127], v56
	ds_read_b64_tr_b4 v[128:129], v57
	s_waitcnt lgkmcnt(7)
	v_dot8c_i32_i4_e32 v38, v130, v52
	v_dot8c_i32_i4_e32 v39, v130, v50
	v_dot8c_i32_i4_e32 v40, v132, v52
	v_dot8c_i32_i4_e32 v41, v132, v50
	v_dot8c_i32_i4_e32 v42, v134, v52
	v_dot8c_i32_i4_e32 v43, v134, v50
	v_dot8c_i32_i4_e32 v44, v136, v52
	v_dot8c_i32_i4_e32 v45, v136, v50
	v_dot8c_i32_i4_e32 v38, v131, v53
	v_dot8c_i32_i4_e32 v39, v131, v51
	v_dot8c_i32_i4_e32 v40, v133, v53
	v_dot8c_i32_i4_e32 v41, v133, v51
	v_dot8c_i32_i4_e32 v42, v135, v53
	v_dot8c_i32_i4_e32 v43, v135, v51
	v_dot8c_i32_i4_e32 v44, v137, v53
	v_dot8c_i32_i4_e32 v45, v137, v51
	v_and_b32_e32 v78, 0xffff, v29
	v_lshrrev_b32_e32 v79, 16, v29
	v_lshl_add_u32 v78, v78, 7, v152
	v_lshl_add_u32 v79, v79, 7, v153
	s_mov_b32 m0, s77
	s_add_i32 s43, s77, 0x400
	global_load_lds_dwordx4 v78, s[50:51]
	s_mov_b32 m0, s43
	s_nop 0
	global_load_lds_dwordx4 v79, s[50:51]
	s_waitcnt vmcnt(8)
	v_add_u32_e32 v54, s79, v59
	v_add_u32_e32 v55, s79, v60
	v_add_u32_e32 v56, s79, v61
	v_add_u32_e32 v57, s79, v62
	ds_read_b64_tr_b4 v[50:51], v160 offset:896
	ds_read_b64_tr_b4 v[52:53], v160 offset:1920
	ds_read_b64_tr_b4 v[130:131], v54
	ds_read_b64_tr_b4 v[132:133], v55
	ds_read_b64_tr_b4 v[134:135], v56
	ds_read_b64_tr_b4 v[136:137], v57
	s_waitcnt lgkmcnt(6)
	v_dot8c_i32_i4_e32 v38, v122, v48
	v_dot8c_i32_i4_e32 v39, v122, v46
	v_dot8c_i32_i4_e32 v40, v124, v48
	v_dot8c_i32_i4_e32 v41, v124, v46
	v_dot8c_i32_i4_e32 v42, v126, v48
	v_dot8c_i32_i4_e32 v43, v126, v46
	v_dot8c_i32_i4_e32 v44, v128, v48
	v_dot8c_i32_i4_e32 v45, v128, v46
	v_dot8c_i32_i4_e32 v38, v123, v49
	v_dot8c_i32_i4_e32 v39, v123, v47
	v_dot8c_i32_i4_e32 v40, v125, v49
	v_dot8c_i32_i4_e32 v41, v125, v47
	v_dot8c_i32_i4_e32 v42, v127, v49
	v_dot8c_i32_i4_e32 v43, v127, v47
	v_dot8c_i32_i4_e32 v44, v129, v49
	v_dot8c_i32_i4_e32 v45, v129, v47
	v_and_b32_e32 v78, 0xffff, v30
	v_lshrrev_b32_e32 v79, 16, v30
	v_lshl_add_u32 v78, v78, 7, v152
	v_lshl_add_u32 v79, v79, 7, v153
	s_mov_b32 m0, s78
	s_add_i32 s43, s78, 0x400
	global_load_lds_dwordx4 v78, s[50:51]
	s_mov_b32 m0, s43
	s_nop 0
	global_load_lds_dwordx4 v79, s[50:51]
	s_waitcnt vmcnt(8)
	v_add_u32_e32 v54, s98, v59
	v_add_u32_e32 v55, s98, v60
	v_add_u32_e32 v56, s98, v61
	v_add_u32_e32 v57, s98, v62
	ds_read_b64_tr_b4 v[46:47], v160
	ds_read_b64_tr_b4 v[48:49], v160 offset:1024
	ds_read_b64_tr_b4 v[122:123], v54
	ds_read_b64_tr_b4 v[124:125], v55
	ds_read_b64_tr_b4 v[126:127], v56
	ds_read_b64_tr_b4 v[128:129], v57
	s_waitcnt lgkmcnt(6)
	v_dot8c_i32_i4_e32 v38, v130, v52
	v_dot8c_i32_i4_e32 v39, v130, v50
	v_dot8c_i32_i4_e32 v40, v132, v52
	v_dot8c_i32_i4_e32 v41, v132, v50
	v_dot8c_i32_i4_e32 v42, v134, v52
	v_dot8c_i32_i4_e32 v43, v134, v50
	v_dot8c_i32_i4_e32 v44, v136, v52
	v_dot8c_i32_i4_e32 v45, v136, v50
	v_dot8c_i32_i4_e32 v38, v131, v53
	v_dot8c_i32_i4_e32 v39, v131, v51
	v_dot8c_i32_i4_e32 v40, v133, v53
	v_dot8c_i32_i4_e32 v41, v133, v51
	v_dot8c_i32_i4_e32 v42, v135, v53
	v_dot8c_i32_i4_e32 v43, v135, v51
	v_dot8c_i32_i4_e32 v44, v137, v53
	v_dot8c_i32_i4_e32 v45, v137, v51
	s_nop 3
	s_waitcnt lgkmcnt(15)
	v_lshlrev_b32_e32 v38, 5, v38
	v_lshlrev_b32_e32 v39, 1, v39
	v_add3_u32 v38, v39, v229, v38
	v_cvt_f32_i32_e32 v38, v38
	v_mul_f32_e32 v38, v228, v38
	v_lshlrev_b32_e32 v40, 5, v40
	v_lshlrev_b32_e32 v41, 1, v41
	v_add3_u32 v40, v41, v229, v40
	v_cvt_f32_i32_e32 v40, v40
	v_mul_f32_e32 v40, v228, v40
	v_lshlrev_b32_e32 v42, 5, v42
	v_lshlrev_b32_e32 v43, 1, v43
	v_add3_u32 v42, v43, v229, v42
	v_cvt_f32_i32_e32 v42, v42
	v_mul_f32_e32 v42, v228, v42
	v_lshlrev_b32_e32 v44, 5, v44
	v_lshlrev_b32_e32 v45, 1, v45
	v_add3_u32 v44, v45, v229, v44
	v_cvt_f32_i32_e32 v44, v44
	v_mul_f32_e32 v44, v228, v44
	v_cvt_pk_bf16_f32 v168, v38, v40
	v_cvt_pk_bf16_f32 v169, v42, v44
	ds_read_b128 v[252:255], v156
	s_add_i32 s44, s40, 24
	s_ashr_i32 s45, s44, 31
	s_lshl_b64 s[44:45], s[44:45], 12
	v_lshl_add_u64 v[80:81], v[36:37], 0, s[44:45]
	s_waitcnt lgkmcnt(0)
; #define TR4(p_) __builtin_amdgcn_ds_read_tr4_b64_v2i32((LAS v2i*)(p_))
; __device__ __forceinline__ void peer_v_tokens(int j, const LAS unsigned short* EL, const LAS unsigned char* AL  , const LAS float* ASC  , const LAS int* SAL  , ...
;     ...
;         { unsigned ho = (unsigned)t * (D / 4) + (unsigned)lane; asm volatile("" : "+v"(ho)); const uint2* hp = (const uint2*)HB + ho; const float4* gp = (const float4*)fng + lane;
; #pragma unroll
;           for (int jq = 0; jq < 4; ++jq) { hv[jq] = hp[64 * jq]; gv[jq] = gp[64 * jq]; } }
;     ...
;         for (int st = 0; st < 16; ++st) {
;             const int p = st >> 2, q = st & 3;
;             if (st < 14) VDMA(st + 2, (st + 2) % 3);
;             if (st < 14) asm volatile("s_waitcnt vmcnt(8)" ::: "memory");
;             else if (st == 14) asm volatile("s_waitcnt vmcnt(4)" ::: "memory");
;             else asm volatile("s_waitcnt vmcnt(0)" ::: "memory");
;             if (q == 0) {
; #pragma unroll
;                 for (int r = 0; r < 4; ++r) { accH[r] = 0; accL[r] = 0; } }
; #pragma unroll
;             for (int tp = 0; tp < 2; ++tp) {
;                 const v2i ao = TR4(ATL + (2 * q + tp) * 128 + 8 * s16), ah = TR4(ATL + 1024 + (2 * q + tp) * 128 + 8 * s16);
; #pragma unroll
;                 for (int r = 0; r < 4; ++r) {
;                     const v2i d = TR4(ldsb + BUF[st % 3] + 2048 * tp + roff[r]);
;                     accH[r] = __builtin_amdgcn_sdot8(d.x, ah.x, accH[r], false); accH[r] = __builtin_amdgcn_sdot8(d.y, ah.y, accH[r], false);
;                     accL[r] = __builtin_amdgcn_sdot8(d.x, ao.x, accL[r], false); accL[r] = __builtin_amdgcn_sdot8(d.y, ao.y, accL[r], false);
;                 }
;             }
;     ...
;             float4* op = (float4*)(outp + (size_t)t * D) + lane;
; #pragma unroll
;             for (int jq = 0; jq < 4; ++jq) { typedef float f4v __attribute__((ext_vector_type(4))); f4v o4; o4.x = v[jq].x * r3 * gv[jq].x; o4.y = v[jq].y * r3 * gv[jq].y; o4.z = v[jq].z * r3 * gv[jq].z; o4.w = v[jq].w * r3 * gv[jq].w;
;                 __builtin_nontemporal_store(o4, (f4v*)op + 64 * jq); }
	v_mul_f32_e32 v244, v244, v252
	v_mul_f32_e32 v245, v245, v253
	v_mul_f32_e32 v246, v246, v254
	v_mul_f32_e32 v247, v247, v255
	global_store_dwordx4 v[80:81], v[244:247], off offset:2048 nt
	s_add_i32 s43, s40, 32
	s_lshl_b32 s43, s43, 11
	v_add_u32_e32 v138, s43, v66
	global_load_dwordx2 v[194:195], v138, s[70:71]
	global_load_dwordx2 v[196:197], v138, s[70:71] offset:512
	global_load_dwordx2 v[198:199], v138, s[70:71] offset:1024
	global_load_dwordx2 v[200:201], v138, s[70:71] offset:1536
	v_add_u32_e32 v147, 8, v140
	v_and_b32_e32 v146, 15, v147
	v_xor_b32_e32 v146, 8, v146
	v_bfe_u32 v148, v147, 4, 4
	v_mul_lo_u32 v146, v146, s92
	v_mul_lo_u32 v148, v148, s92
	v_mov_b32_e32 v147, v146
	v_mov_b32_e32 v149, v148
	ds_write2st64_b64 v77, v[146:147], v[148:149] offset1:2
	v_add_u32_e32 v138, 0x1800, v74
	ds_read_u8 v139, v138
	v_add_u32_e32 v141, 0x1800, v73
	ds_read_u8 v140, v141
	s_add_i32 s43, s67, 160
	v_mov_b32_e32 v138, s43
	ds_read2st64_b32 v[228:229], v138 offset1:1
	ds_read_b128 v[18:21], v227 offset:12288
	ds_read_b128 v[22:25], v227 offset:12304
	v_mov_b32_e32 v150, v63
	v_mov_b32_e32 v151, v64
	v_mov_b32_e32 v38, 0
	v_mov_b32_e32 v39, 0
	v_mov_b32_e32 v40, 0
	v_mov_b32_e32 v41, 0
	v_mov_b32_e32 v42, 0
	v_mov_b32_e32 v43, 0
	v_mov_b32_e32 v44, 0
	v_mov_b32_e32 v45, 0
	v_and_b32_e32 v78, 0xffff, v31
	v_lshrrev_b32_e32 v79, 16, v31
	v_lshl_add_u32 v78, v78, 7, v152
	v_lshl_add_u32 v79, v79, 7, v153
	s_mov_b32 m0, s79
	s_add_i32 s43, s79, 0x400
	global_load_lds_dwordx4 v78, s[50:51]
	s_mov_b32 m0, s43
	s_nop 0
	global_load_lds_dwordx4 v79, s[50:51]
	s_waitcnt vmcnt(13)
	v_add_u32_e32 v54, s99, v59
	v_add_u32_e32 v55, s99, v60
	v_add_u32_e32 v56, s99, v61
	v_add_u32_e32 v57, s99, v62
	ds_read_b64_tr_b4 v[50:51], v160 offset:128
	ds_read_b64_tr_b4 v[52:53], v160 offset:1152
	ds_read_b64_tr_b4 v[130:131], v54
	ds_read_b64_tr_b4 v[132:133], v55
	ds_read_b64_tr_b4 v[134:135], v56
	ds_read_b64_tr_b4 v[136:137], v57
	s_waitcnt lgkmcnt(13)
	v_dot8c_i32_i4_e32 v38, v122, v48
	v_dot8c_i32_i4_e32 v39, v122, v46
	v_dot8c_i32_i4_e32 v40, v124, v48
	v_dot8c_i32_i4_e32 v41, v124, v46
	v_dot8c_i32_i4_e32 v42, v126, v48
	v_dot8c_i32_i4_e32 v43, v126, v46
	v_dot8c_i32_i4_e32 v44, v128, v48
	v_dot8c_i32_i4_e32 v45, v128, v46
	v_dot8c_i32_i4_e32 v38, v123, v49
	v_dot8c_i32_i4_e32 v39, v123, v47
	v_dot8c_i32_i4_e32 v40, v125, v49
	v_dot8c_i32_i4_e32 v41, v125, v47
	v_dot8c_i32_i4_e32 v42, v127, v49
	v_dot8c_i32_i4_e32 v43, v127, v47
	v_dot8c_i32_i4_e32 v44, v129, v49
	v_dot8c_i32_i4_e32 v45, v129, v47
	v_and_b32_e32 v78, 0xffff, v32
	v_lshrrev_b32_e32 v79, 16, v32
	v_lshl_add_u32 v78, v78, 7, v152
	v_lshl_add_u32 v79, v79, 7, v153
	s_mov_b32 m0, s98
	s_add_i32 s43, s98, 0x400
	global_load_lds_dwordx4 v78, s[50:51]
	s_mov_b32 m0, s43
	s_nop 0
	global_load_lds_dwordx4 v79, s[50:51]
	s_waitcnt vmcnt(13)
	v_add_u32_e32 v54, s76, v59
	v_add_u32_e32 v55, s76, v60
	v_add_u32_e32 v56, s76, v61
	v_add_u32_e32 v57, s76, v62
	ds_read_b64_tr_b4 v[46:47], v160 offset:256
	ds_read_b64_tr_b4 v[48:49], v160 offset:1280
	ds_read_b64_tr_b4 v[122:123], v54
	ds_read_b64_tr_b4 v[124:125], v55
	ds_read_b64_tr_b4 v[126:127], v56
	ds_read_b64_tr_b4 v[128:129], v57
	s_waitcnt lgkmcnt(6)
	v_dot8c_i32_i4_e32 v38, v130, v52
	v_dot8c_i32_i4_e32 v39, v130, v50
	v_dot8c_i32_i4_e32 v40, v132, v52
	v_dot8c_i32_i4_e32 v41, v132, v50
	v_dot8c_i32_i4_e32 v42, v134, v52
	v_dot8c_i32_i4_e32 v43, v134, v50
	v_dot8c_i32_i4_e32 v44, v136, v52
	v_dot8c_i32_i4_e32 v45, v136, v50
	v_dot8c_i32_i4_e32 v38, v131, v53
	v_dot8c_i32_i4_e32 v39, v131, v51
	v_dot8c_i32_i4_e32 v40, v133, v53
	v_dot8c_i32_i4_e32 v41, v133, v51
	v_dot8c_i32_i4_e32 v42, v135, v53
	v_dot8c_i32_i4_e32 v43, v135, v51
	v_dot8c_i32_i4_e32 v44, v137, v53
	v_dot8c_i32_i4_e32 v45, v137, v51
	v_and_b32_e32 v78, 0xffff, v33
	v_lshrrev_b32_e32 v79, 16, v33
	v_lshl_add_u32 v78, v78, 7, v152
	v_lshl_add_u32 v79, v79, 7, v153
	s_mov_b32 m0, s99
	s_add_i32 s43, s99, 0x400
	global_load_lds_dwordx4 v78, s[50:51]
	s_mov_b32 m0, s43
	s_nop 0
	global_load_lds_dwordx4 v79, s[50:51]
	s_waitcnt vmcnt(13)
	v_add_u32_e32 v54, s77, v59
	v_add_u32_e32 v55, s77, v60
	v_add_u32_e32 v56, s77, v61
	v_add_u32_e32 v57, s77, v62
	ds_read_b64_tr_b4 v[50:51], v160 offset:384
	ds_read_b64_tr_b4 v[52:53], v160 offset:1408
	ds_read_b64_tr_b4 v[130:131], v54
	ds_read_b64_tr_b4 v[132:133], v55
	ds_read_b64_tr_b4 v[134:135], v56
	ds_read_b64_tr_b4 v[136:137], v57
	s_waitcnt lgkmcnt(6)
	v_dot8c_i32_i4_e32 v38, v122, v48
	v_dot8c_i32_i4_e32 v39, v122, v46
	v_dot8c_i32_i4_e32 v40, v124, v48
	v_dot8c_i32_i4_e32 v41, v124, v46
	v_dot8c_i32_i4_e32 v42, v126, v48
	v_dot8c_i32_i4_e32 v43, v126, v46
	v_dot8c_i32_i4_e32 v44, v128, v48
	v_dot8c_i32_i4_e32 v45, v128, v46
	v_dot8c_i32_i4_e32 v38, v123, v49
	v_dot8c_i32_i4_e32 v39, v123, v47
	v_dot8c_i32_i4_e32 v40, v125, v49
	v_dot8c_i32_i4_e32 v41, v125, v47
	v_dot8c_i32_i4_e32 v42, v127, v49
	v_dot8c_i32_i4_e32 v43, v127, v47
	v_dot8c_i32_i4_e32 v44, v129, v49
	v_dot8c_i32_i4_e32 v45, v129, v47
	s_waitcnt lgkmcnt(15)
	v_and_b32_e32 v78, 0xffff, v18
	v_lshrrev_b32_e32 v79, 16, v18
	v_lshl_add_u32 v78, v78, 7, v150
	v_lshl_add_u32 v79, v79, 7, v151
	s_mov_b32 m0, s76
	s_add_i32 s43, s76, 0x400
	global_load_lds_dwordx4 v78, s[50:51]
	s_mov_b32 m0, s43
	s_nop 0
	global_load_lds_dwordx4 v79, s[50:51]
	s_waitcnt vmcnt(13)
	v_add_u32_e32 v54, s78, v59
	v_add_u32_e32 v55, s78, v60
	v_add_u32_e32 v56, s78, v61
	v_add_u32_e32 v57, s78, v62
	ds_read_b64_tr_b4 v[46:47], v160 offset:512
	ds_read_b64_tr_b4 v[48:49], v160 offset:1536
	ds_read_b64_tr_b4 v[122:123], v54
	ds_read_b64_tr_b4 v[124:125], v55
	ds_read_b64_tr_b4 v[126:127], v56
	ds_read_b64_tr_b4 v[128:129], v57
	s_waitcnt lgkmcnt(6)
; #define TR4(p_) __builtin_amdgcn_ds_read_tr4_b64_v2i32((LAS v2i*)(p_))
; #define VDMA(st_, k_) do { _Pragma("unroll") for (int i_ = 0; i_ < 4; ++i_) { \
;         const unsigned off_ = (unsigned)((st_) >> 2) * (16384u * 128u) + (PE_ID(E, 4 * ((st_) & 3) + i_) << 7) + ((i_ & 1) ? cx1 : cx0); \
;         __builtin_amdgcn_global_load_lds((const unsigned*)(V4 + off_), (LAS unsigned*)(ldsb + BUF[k_] + 1024 * i_), 16, 0, 0); } } while (0)
; __device__ __forceinline__ void peer_v_tokens(int j, const LAS unsigned short* EL, const LAS unsigned char* AL  , const LAS float* ASC  , const LAS int* SAL  , ...
;     ...
;         for (int st = 0; st < 16; ++st) {
;             const int p = st >> 2, q = st & 3;
;             if (st < 14) VDMA(st + 2, (st + 2) % 3);
;             if (st < 14) asm volatile("s_waitcnt vmcnt(8)" ::: "memory");
;             else if (st == 14) asm volatile("s_waitcnt vmcnt(4)" ::: "memory");
;             else asm volatile("s_waitcnt vmcnt(0)" ::: "memory");
;             if (q == 0) {
; #pragma unroll
;                 for (int r = 0; r < 4; ++r) { accH[r] = 0; accL[r] = 0; } }
; #pragma unroll
;             for (int tp = 0; tp < 2; ++tp) {
;                 const v2i ao = TR4(ATL + (2 * q + tp) * 128 + 8 * s16), ah = TR4(ATL + 1024 + (2 * q + tp) * 128 + 8 * s16);
; #pragma unroll
;                 for (int r = 0; r < 4; ++r) {
;                     const v2i d = TR4(ldsb + BUF[st % 3] + 2048 * tp + roff[r]);
;                     accH[r] = __builtin_amdgcn_sdot8(d.x, ah.x, accH[r], false); accH[r] = __builtin_amdgcn_sdot8(d.y, ah.y, accH[r], false);
;                     accL[r] = __builtin_amdgcn_sdot8(d.x, ao.x, accL[r], false); accL[r] = __builtin_amdgcn_sdot8(d.y, ao.y, accL[r], false);
;                 }
;             }
	v_dot8c_i32_i4_e32 v38, v130, v52
	v_dot8c_i32_i4_e32 v39, v130, v50
	v_dot8c_i32_i4_e32 v40, v132, v52
	v_dot8c_i32_i4_e32 v41, v132, v50
	v_dot8c_i32_i4_e32 v42, v134, v52
	v_dot8c_i32_i4_e32 v43, v134, v50
	v_dot8c_i32_i4_e32 v44, v136, v52
	v_dot8c_i32_i4_e32 v45, v136, v50
	v_dot8c_i32_i4_e32 v38, v131, v53
	v_dot8c_i32_i4_e32 v39, v131, v51
	v_dot8c_i32_i4_e32 v40, v133, v53
	v_dot8c_i32_i4_e32 v41, v133, v51
	v_dot8c_i32_i4_e32 v42, v135, v53
	v_dot8c_i32_i4_e32 v43, v135, v51
	v_dot8c_i32_i4_e32 v44, v137, v53
	v_dot8c_i32_i4_e32 v45, v137, v51
	v_and_b32_e32 v78, 0xffff, v19
	v_lshrrev_b32_e32 v79, 16, v19
	v_lshl_add_u32 v78, v78, 7, v150
	v_lshl_add_u32 v79, v79, 7, v151
	s_mov_b32 m0, s77
	s_add_i32 s43, s77, 0x400
	global_load_lds_dwordx4 v78, s[50:51]
	s_mov_b32 m0, s43
	s_nop 0
	global_load_lds_dwordx4 v79, s[50:51]
	s_waitcnt vmcnt(8)
	v_add_u32_e32 v54, s79, v59
	v_add_u32_e32 v55, s79, v60
	v_add_u32_e32 v56, s79, v61
	v_add_u32_e32 v57, s79, v62
	ds_read_b64_tr_b4 v[50:51], v160 offset:640
	ds_read_b64_tr_b4 v[52:53], v160 offset:1664
	ds_read_b64_tr_b4 v[130:131], v54
	ds_read_b64_tr_b4 v[132:133], v55
	ds_read_b64_tr_b4 v[134:135], v56
	ds_read_b64_tr_b4 v[136:137], v57
	s_waitcnt lgkmcnt(6)
	v_dot8c_i32_i4_e32 v38, v122, v48
	v_dot8c_i32_i4_e32 v39, v122, v46
	v_dot8c_i32_i4_e32 v40, v124, v48
	v_dot8c_i32_i4_e32 v41, v124, v46
	v_dot8c_i32_i4_e32 v42, v126, v48
	v_dot8c_i32_i4_e32 v43, v126, v46
	v_dot8c_i32_i4_e32 v44, v128, v48
	v_dot8c_i32_i4_e32 v45, v128, v46
	v_dot8c_i32_i4_e32 v38, v123, v49
	v_dot8c_i32_i4_e32 v39, v123, v47
	v_dot8c_i32_i4_e32 v40, v125, v49
	v_dot8c_i32_i4_e32 v41, v125, v47
	v_dot8c_i32_i4_e32 v42, v127, v49
	v_dot8c_i32_i4_e32 v43, v127, v47
	v_dot8c_i32_i4_e32 v44, v129, v49
	v_dot8c_i32_i4_e32 v45, v129, v47
	s_waitcnt lgkmcnt(15)
	v_add_u32_e32 v143, 8, v139
	v_and_b32_e32 v142, 15, v143
	v_xor_b32_e32 v142, 8, v142
	v_bfe_u32 v144, v143, 4, 4
	v_mul_lo_u32 v142, v142, s92
	v_mul_lo_u32 v144, v144, s92
	v_mov_b32_e32 v143, v142
	v_mov_b32_e32 v145, v144
	ds_write2st64_b64 v159, v[142:143], v[144:145] offset1:2
	v_and_b32_e32 v78, 0xffff, v20
	v_lshrrev_b32_e32 v79, 16, v20
	v_lshl_add_u32 v78, v78, 7, v150
	v_lshl_add_u32 v79, v79, 7, v151
	s_mov_b32 m0, s78
	s_add_i32 s43, s78, 0x400
	global_load_lds_dwordx4 v78, s[50:51]
	s_mov_b32 m0, s43
	s_nop 0
	global_load_lds_dwordx4 v79, s[50:51]
	s_waitcnt vmcnt(8)
	v_add_u32_e32 v54, s98, v59
	v_add_u32_e32 v55, s98, v60
	v_add_u32_e32 v56, s98, v61
	v_add_u32_e32 v57, s98, v62
	ds_read_b64_tr_b4 v[46:47], v160 offset:768
	ds_read_b64_tr_b4 v[48:49], v160 offset:1792
	ds_read_b64_tr_b4 v[122:123], v54
	ds_read_b64_tr_b4 v[124:125], v55
	ds_read_b64_tr_b4 v[126:127], v56
	ds_read_b64_tr_b4 v[128:129], v57
	s_waitcnt lgkmcnt(7)
	v_dot8c_i32_i4_e32 v38, v130, v52
	v_dot8c_i32_i4_e32 v39, v130, v50
	v_dot8c_i32_i4_e32 v40, v132, v52
	v_dot8c_i32_i4_e32 v41, v132, v50
	v_dot8c_i32_i4_e32 v42, v134, v52
	v_dot8c_i32_i4_e32 v43, v134, v50
	v_dot8c_i32_i4_e32 v44, v136, v52
	v_dot8c_i32_i4_e32 v45, v136, v50
	v_dot8c_i32_i4_e32 v38, v131, v53
	v_dot8c_i32_i4_e32 v39, v131, v51
	v_dot8c_i32_i4_e32 v40, v133, v53
	v_dot8c_i32_i4_e32 v41, v133, v51
	v_dot8c_i32_i4_e32 v42, v135, v53
	v_dot8c_i32_i4_e32 v43, v135, v51
	v_dot8c_i32_i4_e32 v44, v137, v53
	v_dot8c_i32_i4_e32 v45, v137, v51
	v_and_b32_e32 v78, 0xffff, v21
	v_lshrrev_b32_e32 v79, 16, v21
	v_lshl_add_u32 v78, v78, 7, v150
	v_lshl_add_u32 v79, v79, 7, v151
	s_mov_b32 m0, s79
	s_add_i32 s43, s79, 0x400
	global_load_lds_dwordx4 v78, s[50:51]
	s_mov_b32 m0, s43
	s_nop 0
	global_load_lds_dwordx4 v79, s[50:51]
	s_waitcnt vmcnt(8)
	v_add_u32_e32 v54, s99, v59
	v_add_u32_e32 v55, s99, v60
	v_add_u32_e32 v56, s99, v61
	v_add_u32_e32 v57, s99, v62
	ds_read_b64_tr_b4 v[50:51], v160 offset:896
	ds_read_b64_tr_b4 v[52:53], v160 offset:1920
	ds_read_b64_tr_b4 v[130:131], v54
	ds_read_b64_tr_b4 v[132:133], v55
	ds_read_b64_tr_b4 v[134:135], v56
	ds_read_b64_tr_b4 v[136:137], v57
	s_waitcnt lgkmcnt(6)
	v_dot8c_i32_i4_e32 v38, v122, v48
	v_dot8c_i32_i4_e32 v39, v122, v46
	v_dot8c_i32_i4_e32 v40, v124, v48
	v_dot8c_i32_i4_e32 v41, v124, v46
	v_dot8c_i32_i4_e32 v42, v126, v48
	v_dot8c_i32_i4_e32 v43, v126, v46
	v_dot8c_i32_i4_e32 v44, v128, v48
	v_dot8c_i32_i4_e32 v45, v128, v46
	v_dot8c_i32_i4_e32 v38, v123, v49
	v_dot8c_i32_i4_e32 v39, v123, v47
	v_dot8c_i32_i4_e32 v40, v125, v49
	v_dot8c_i32_i4_e32 v41, v125, v47
	v_dot8c_i32_i4_e32 v42, v127, v49
	v_dot8c_i32_i4_e32 v43, v127, v47
	v_dot8c_i32_i4_e32 v44, v129, v49
	v_dot8c_i32_i4_e32 v45, v129, v47
	v_and_b32_e32 v78, 0xffff, v22
	v_lshrrev_b32_e32 v79, 16, v22
	v_lshl_add_u32 v78, v78, 7, v150
	v_lshl_add_u32 v79, v79, 7, v151
	s_mov_b32 m0, s98
	s_add_i32 s43, s98, 0x400
	global_load_lds_dwordx4 v78, s[50:51]
	s_mov_b32 m0, s43
	s_nop 0
	global_load_lds_dwordx4 v79, s[50:51]
	s_waitcnt vmcnt(8)
	v_add_u32_e32 v54, s76, v59
	v_add_u32_e32 v55, s76, v60
	v_add_u32_e32 v56, s76, v61
	v_add_u32_e32 v57, s76, v62
	ds_read_b64_tr_b4 v[46:47], v160
	ds_read_b64_tr_b4 v[48:49], v160 offset:1024
	ds_read_b64_tr_b4 v[122:123], v54
	ds_read_b64_tr_b4 v[124:125], v55
	ds_read_b64_tr_b4 v[126:127], v56
	ds_read_b64_tr_b4 v[128:129], v57
	s_waitcnt lgkmcnt(6)
	v_dot8c_i32_i4_e32 v38, v130, v52
	v_dot8c_i32_i4_e32 v39, v130, v50
	v_dot8c_i32_i4_e32 v40, v132, v52
	v_dot8c_i32_i4_e32 v41, v132, v50
	v_dot8c_i32_i4_e32 v42, v134, v52
	v_dot8c_i32_i4_e32 v43, v134, v50
	v_dot8c_i32_i4_e32 v44, v136, v52
	v_dot8c_i32_i4_e32 v45, v136, v50
	v_dot8c_i32_i4_e32 v38, v131, v53
	v_dot8c_i32_i4_e32 v39, v131, v51
	v_dot8c_i32_i4_e32 v40, v133, v53
	v_dot8c_i32_i4_e32 v41, v133, v51
	v_dot8c_i32_i4_e32 v42, v135, v53
	v_dot8c_i32_i4_e32 v43, v135, v51
	v_dot8c_i32_i4_e32 v44, v137, v53
	v_dot8c_i32_i4_e32 v45, v137, v51
	s_nop 3
	s_waitcnt lgkmcnt(15)
; #define LAS __attribute__((address_space(3)))
; __device__ __forceinline__ bf16 f2bf(float f) { return (bf16)f2bfu(f); }
; #define TR4(p_) __builtin_amdgcn_ds_read_tr4_b64_v2i32((LAS v2i*)(p_))
; #define CFENCE() asm volatile("" ::: "memory")
; __device__ __forceinline__ void peer_v_tokens(int j, const LAS unsigned short* EL, const LAS unsigned char* AL  , const LAS float* ASC  , const LAS int* SAL  , ...
;     ...
;         for (int st = 0; st < 16; ++st) {
;             const int p = st >> 2, q = st & 3;
;             if (st < 14) VDMA(st + 2, (st + 2) % 3);
;             if (st < 14) asm volatile("s_waitcnt vmcnt(8)" ::: "memory");
;             else if (st == 14) asm volatile("s_waitcnt vmcnt(4)" ::: "memory");
;             else asm volatile("s_waitcnt vmcnt(0)" ::: "memory");
;             if (q == 0) {
; #pragma unroll
;                 for (int r = 0; r < 4; ++r) { accH[r] = 0; accL[r] = 0; } }
; #pragma unroll
;             for (int tp = 0; tp < 2; ++tp) {
;                 const v2i ao = TR4(ATL + (2 * q + tp) * 128 + 8 * s16), ah = TR4(ATL + 1024 + (2 * q + tp) * 128 + 8 * s16);
; #pragma unroll
;                 for (int r = 0; r < 4; ++r) {
;                     const v2i d = TR4(ldsb + BUF[st % 3] + 2048 * tp + roff[r]);
;                     accH[r] = __builtin_amdgcn_sdot8(d.x, ah.x, accH[r], false); accH[r] = __builtin_amdgcn_sdot8(d.y, ah.y, accH[r], false);
;                     accL[r] = __builtin_amdgcn_sdot8(d.x, ao.x, accL[r], false); accL[r] = __builtin_amdgcn_sdot8(d.y, ao.y, accL[r], false);
;                 }
;             }
;             asm volatile("s_waitcnt lgkmcnt(0)" ::: "memory");
;             if (q == 3) {
; #pragma unroll
;                 for (int r = 0; r < 4; ++r) STASH[256 * p + 16 * (grp + 4 * r) + pc] = f2bf(asc * (float)(2 * ((accH[r] << 4) + accL[r]) + sa));
;             }
;         }
;         CFENCE();
;         {
;             float4 v[4]; float ss = 0.f;
; #pragma unroll
;             for (int jq = 0; jq < 4; ++jq) { typedef unsigned u2v __attribute__((ext_vector_type(2))); const u2v pw = *(const LAS u2v*)(STASH + 4 * lane + 256 * jq); const uint2 hw = hv[jq];
	v_lshlrev_b32_e32 v38, 5, v38
	v_lshlrev_b32_e32 v39, 1, v39
	v_add3_u32 v38, v39, v229, v38
	v_cvt_f32_i32_e32 v38, v38
	v_mul_f32_e32 v38, v228, v38
	v_lshlrev_b32_e32 v40, 5, v40
	v_lshlrev_b32_e32 v41, 1, v41
	v_add3_u32 v40, v41, v229, v40
	v_cvt_f32_i32_e32 v40, v40
	v_mul_f32_e32 v40, v228, v40
	v_lshlrev_b32_e32 v42, 5, v42
	v_lshlrev_b32_e32 v43, 1, v43
	v_add3_u32 v42, v43, v229, v42
	v_cvt_f32_i32_e32 v42, v42
	v_mul_f32_e32 v42, v228, v42
	v_lshlrev_b32_e32 v44, 5, v44
	v_lshlrev_b32_e32 v45, 1, v45
	v_add3_u32 v44, v45, v229, v44
	v_cvt_f32_i32_e32 v44, v44
	v_mul_f32_e32 v44, v228, v44
	v_cvt_pk_bf16_f32 v176, v38, v40
	v_cvt_pk_bf16_f32 v177, v42, v44
	ds_read_b128 v[252:255], v156 offset:1024
	s_add_i32 s44, s40, 24
	s_ashr_i32 s45, s44, 31
	s_lshl_b64 s[44:45], s[44:45], 12
	v_lshl_add_u64 v[80:81], v[36:37], 0, s[44:45]
	s_waitcnt lgkmcnt(0)
	v_mul_f32_e32 v248, v248, v252
	v_mul_f32_e32 v249, v249, v253
	v_mul_f32_e32 v250, v250, v254
	v_mul_f32_e32 v251, v251, v255
	global_store_dwordx4 v[80:81], v[248:251], off offset:3072 nt
	v_add_u32_e32 v147, 8, v140
	v_and_b32_e32 v146, 15, v147
	v_xor_b32_e32 v146, 8, v146
	v_bfe_u32 v148, v147, 4, 4
	v_mul_lo_u32 v146, v146, s92
	v_mul_lo_u32 v148, v148, s92
	v_mov_b32_e32 v147, v146
	v_mov_b32_e32 v149, v148
	ds_write2st64_b64 v77, v[146:147], v[148:149] offset1:2
	v_add_u32_e32 v138, 0x1c00, v74
	ds_read_u8 v139, v138
	v_add_u32_e32 v141, 0x1c00, v73
	ds_read_u8 v140, v141
	s_add_i32 s43, s67, 192
	v_mov_b32_e32 v138, s43
	ds_read2st64_b32 v[228:229], v138 offset1:1
	ds_read_b128 v[26:29], v227 offset:14336
	ds_read_b128 v[30:33], v227 offset:14352
	v_mov_b32_e32 v38, 0
	v_mov_b32_e32 v39, 0
	v_mov_b32_e32 v40, 0
	v_mov_b32_e32 v41, 0
	v_mov_b32_e32 v42, 0
	v_mov_b32_e32 v43, 0
	v_mov_b32_e32 v44, 0
	v_mov_b32_e32 v45, 0
	v_and_b32_e32 v78, 0xffff, v23
	v_lshrrev_b32_e32 v79, 16, v23
	v_lshl_add_u32 v78, v78, 7, v150
	v_lshl_add_u32 v79, v79, 7, v151
	s_mov_b32 m0, s99
	s_add_i32 s43, s99, 0x400
	global_load_lds_dwordx4 v78, s[50:51]
	s_mov_b32 m0, s43
	s_nop 0
	global_load_lds_dwordx4 v79, s[50:51]
	s_waitcnt vmcnt(9)
	v_add_u32_e32 v54, s77, v59
	v_add_u32_e32 v55, s77, v60
	v_add_u32_e32 v56, s77, v61
	v_add_u32_e32 v57, s77, v62
	ds_read_b64_tr_b4 v[50:51], v160 offset:128
	ds_read_b64_tr_b4 v[52:53], v160 offset:1152
	ds_read_b64_tr_b4 v[130:131], v54
	ds_read_b64_tr_b4 v[132:133], v55
	ds_read_b64_tr_b4 v[134:135], v56
	ds_read_b64_tr_b4 v[136:137], v57
	s_waitcnt lgkmcnt(13)
	v_dot8c_i32_i4_e32 v38, v122, v48
	v_dot8c_i32_i4_e32 v39, v122, v46
	v_dot8c_i32_i4_e32 v40, v124, v48
	v_dot8c_i32_i4_e32 v41, v124, v46
	v_dot8c_i32_i4_e32 v42, v126, v48
	v_dot8c_i32_i4_e32 v43, v126, v46
	v_dot8c_i32_i4_e32 v44, v128, v48
	v_dot8c_i32_i4_e32 v45, v128, v46
	v_dot8c_i32_i4_e32 v38, v123, v49
	v_dot8c_i32_i4_e32 v39, v123, v47
	v_dot8c_i32_i4_e32 v40, v125, v49
	v_dot8c_i32_i4_e32 v41, v125, v47
	v_dot8c_i32_i4_e32 v42, v127, v49
	v_dot8c_i32_i4_e32 v43, v127, v47
	v_dot8c_i32_i4_e32 v44, v129, v49
	v_dot8c_i32_i4_e32 v45, v129, v47
	v_and_b32_e32 v78, 0xffff, v24
	v_lshrrev_b32_e32 v79, 16, v24
	v_lshl_add_u32 v78, v78, 7, v150
	v_lshl_add_u32 v79, v79, 7, v151
	s_mov_b32 m0, s76
	s_add_i32 s43, s76, 0x400
	global_load_lds_dwordx4 v78, s[50:51]
	s_mov_b32 m0, s43
	s_nop 0
	global_load_lds_dwordx4 v79, s[50:51]
	s_waitcnt vmcnt(9)
	v_add_u32_e32 v54, s78, v59
	v_add_u32_e32 v55, s78, v60
	v_add_u32_e32 v56, s78, v61
	v_add_u32_e32 v57, s78, v62
	ds_read_b64_tr_b4 v[46:47], v160 offset:256
	ds_read_b64_tr_b4 v[48:49], v160 offset:1280
	ds_read_b64_tr_b4 v[122:123], v54
	ds_read_b64_tr_b4 v[124:125], v55
	ds_read_b64_tr_b4 v[126:127], v56
	ds_read_b64_tr_b4 v[128:129], v57
	s_waitcnt lgkmcnt(6)
	v_dot8c_i32_i4_e32 v38, v130, v52
	v_dot8c_i32_i4_e32 v39, v130, v50
	v_dot8c_i32_i4_e32 v40, v132, v52
	v_dot8c_i32_i4_e32 v41, v132, v50
	v_dot8c_i32_i4_e32 v42, v134, v52
	v_dot8c_i32_i4_e32 v43, v134, v50
	v_dot8c_i32_i4_e32 v44, v136, v52
	v_dot8c_i32_i4_e32 v45, v136, v50
	v_dot8c_i32_i4_e32 v38, v131, v53
	v_dot8c_i32_i4_e32 v39, v131, v51
	v_dot8c_i32_i4_e32 v40, v133, v53
	v_dot8c_i32_i4_e32 v41, v133, v51
	v_dot8c_i32_i4_e32 v42, v135, v53
	v_dot8c_i32_i4_e32 v43, v135, v51
	v_dot8c_i32_i4_e32 v44, v137, v53
	v_dot8c_i32_i4_e32 v45, v137, v51
	ds_write_b16 v65, v162
	ds_write_b16_d16_hi v65, v162 offset:128
	ds_write_b16 v65, v163 offset:256
	ds_write_b16_d16_hi v65, v163 offset:384
	ds_write_b16 v65, v164 offset:512
	ds_write_b16_d16_hi v65, v164 offset:640
	ds_write_b16 v65, v165 offset:768
	ds_write_b16_d16_hi v65, v165 offset:896
	ds_write_b16 v65, v166 offset:1024
	ds_write_b16_d16_hi v65, v166 offset:1152
	ds_write_b16 v65, v167 offset:1280
	ds_write_b16_d16_hi v65, v167 offset:1408
	ds_write_b16 v65, v168 offset:1536
	ds_write_b16_d16_hi v65, v168 offset:1664
	ds_write_b16 v65, v169 offset:1792
	ds_write_b16_d16_hi v65, v169 offset:1920
	ds_read_b64 v[202:203], v154
	ds_read_b64 v[204:205], v154 offset:512
	ds_read_b64 v[206:207], v154 offset:1024
	ds_read_b64 v[208:209], v154 offset:1536
	v_and_b32_e32 v78, 0xffff, v25
	v_lshrrev_b32_e32 v79, 16, v25
	v_lshl_add_u32 v78, v78, 7, v150
	v_lshl_add_u32 v79, v79, 7, v151
	s_mov_b32 m0, s77
	s_add_i32 s43, s77, 0x400
	global_load_lds_dwordx4 v78, s[50:51]
	s_mov_b32 m0, s43
	s_nop 0
	global_load_lds_dwordx4 v79, s[50:51]
	s_waitcnt vmcnt(9)
	v_add_u32_e32 v54, s79, v59
	v_add_u32_e32 v55, s79, v60
	v_add_u32_e32 v56, s79, v61
	v_add_u32_e32 v57, s79, v62
	ds_read_b64_tr_b4 v[50:51], v160 offset:384
	ds_read_b64_tr_b4 v[52:53], v160 offset:1408
	ds_read_b64_tr_b4 v[130:131], v54
	ds_read_b64_tr_b4 v[132:133], v55
	ds_read_b64_tr_b4 v[134:135], v56
	ds_read_b64_tr_b4 v[136:137], v57
	s_waitcnt lgkmcnt(15)
; #define TR4(p_) __builtin_amdgcn_ds_read_tr4_b64_v2i32((LAS v2i*)(p_))
; #define VDMA(st_, k_) do { _Pragma("unroll") for (int i_ = 0; i_ < 4; ++i_) { \
;         const unsigned off_ = (unsigned)((st_) >> 2) * (16384u * 128u) + (PE_ID(E, 4 * ((st_) & 3) + i_) << 7) + ((i_ & 1) ? cx1 : cx0); \
;         __builtin_amdgcn_global_load_lds((const unsigned*)(V4 + off_), (LAS unsigned*)(ldsb + BUF[k_] + 1024 * i_), 16, 0, 0); } } while (0)
; __device__ __forceinline__ void peer_v_tokens(int j, const LAS unsigned short* EL, const LAS unsigned char* AL  , const LAS float* ASC  , const LAS int* SAL  , ...
;     ...
;         for (int st = 0; st < 16; ++st) {
;             const int p = st >> 2, q = st & 3;
;             if (st < 14) VDMA(st + 2, (st + 2) % 3);
;             if (st < 14) asm volatile("s_waitcnt vmcnt(8)" ::: "memory");
;             else if (st == 14) asm volatile("s_waitcnt vmcnt(4)" ::: "memory");
;             else asm volatile("s_waitcnt vmcnt(0)" ::: "memory");
;             if (q == 0) {
; #pragma unroll
;                 for (int r = 0; r < 4; ++r) { accH[r] = 0; accL[r] = 0; } }
; #pragma unroll
;             for (int tp = 0; tp < 2; ++tp) {
;                 const v2i ao = TR4(ATL + (2 * q + tp) * 128 + 8 * s16), ah = TR4(ATL + 1024 + (2 * q + tp) * 128 + 8 * s16);
; #pragma unroll
;                 for (int r = 0; r < 4; ++r) {
;                     const v2i d = TR4(ldsb + BUF[st % 3] + 2048 * tp + roff[r]);
;                     accH[r] = __builtin_amdgcn_sdot8(d.x, ah.x, accH[r], false); accH[r] = __builtin_amdgcn_sdot8(d.y, ah.y, accH[r], false);
;                     accL[r] = __builtin_amdgcn_sdot8(d.x, ao.x, accL[r], false); accL[r] = __builtin_amdgcn_sdot8(d.y, ao.y, accL[r], false);
;                 }
;             }
	v_dot8c_i32_i4_e32 v38, v122, v48
	v_dot8c_i32_i4_e32 v39, v122, v46
	v_dot8c_i32_i4_e32 v40, v124, v48
	v_dot8c_i32_i4_e32 v41, v124, v46
	v_dot8c_i32_i4_e32 v42, v126, v48
	v_dot8c_i32_i4_e32 v43, v126, v46
	v_dot8c_i32_i4_e32 v44, v128, v48
	v_dot8c_i32_i4_e32 v45, v128, v46
	v_dot8c_i32_i4_e32 v38, v123, v49
	v_dot8c_i32_i4_e32 v39, v123, v47
	v_dot8c_i32_i4_e32 v40, v125, v49
	v_dot8c_i32_i4_e32 v41, v125, v47
	v_dot8c_i32_i4_e32 v42, v127, v49
	v_dot8c_i32_i4_e32 v43, v127, v47
	v_dot8c_i32_i4_e32 v44, v129, v49
	v_dot8c_i32_i4_e32 v45, v129, v47
	s_waitcnt lgkmcnt(15)
	v_and_b32_e32 v78, 0xffff, v26
	v_lshrrev_b32_e32 v79, 16, v26
	v_lshl_add_u32 v78, v78, 7, v150
	v_lshl_add_u32 v79, v79, 7, v151
	s_mov_b32 m0, s78
	s_add_i32 s43, s78, 0x400
	global_load_lds_dwordx4 v78, s[50:51]
	s_mov_b32 m0, s43
	s_nop 0
	global_load_lds_dwordx4 v79, s[50:51]
	s_waitcnt vmcnt(9)
	v_add_u32_e32 v54, s98, v59
	v_add_u32_e32 v55, s98, v60
	v_add_u32_e32 v56, s98, v61
	v_add_u32_e32 v57, s98, v62
	ds_read_b64_tr_b4 v[46:47], v160 offset:512
	ds_read_b64_tr_b4 v[48:49], v160 offset:1536
	ds_read_b64_tr_b4 v[122:123], v54
	ds_read_b64_tr_b4 v[124:125], v55
	ds_read_b64_tr_b4 v[126:127], v56
	ds_read_b64_tr_b4 v[128:129], v57
	s_waitcnt lgkmcnt(6)
	v_dot8c_i32_i4_e32 v38, v130, v52
	v_dot8c_i32_i4_e32 v39, v130, v50
	v_dot8c_i32_i4_e32 v40, v132, v52
	v_dot8c_i32_i4_e32 v41, v132, v50
	v_dot8c_i32_i4_e32 v42, v134, v52
	v_dot8c_i32_i4_e32 v43, v134, v50
	v_dot8c_i32_i4_e32 v44, v136, v52
	v_dot8c_i32_i4_e32 v45, v136, v50
	v_dot8c_i32_i4_e32 v38, v131, v53
	v_dot8c_i32_i4_e32 v39, v131, v51
	v_dot8c_i32_i4_e32 v40, v133, v53
	v_dot8c_i32_i4_e32 v41, v133, v51
	v_dot8c_i32_i4_e32 v42, v135, v53
	v_dot8c_i32_i4_e32 v43, v135, v51
	v_dot8c_i32_i4_e32 v44, v137, v53
	v_dot8c_i32_i4_e32 v45, v137, v51
	v_and_b32_e32 v78, 0xffff, v27
	v_lshrrev_b32_e32 v79, 16, v27
	v_lshl_add_u32 v78, v78, 7, v150
	v_lshl_add_u32 v79, v79, 7, v151
	s_mov_b32 m0, s79
	s_add_i32 s43, s79, 0x400
	global_load_lds_dwordx4 v78, s[50:51]
	s_mov_b32 m0, s43
	s_nop 0
	global_load_lds_dwordx4 v79, s[50:51]
	s_waitcnt vmcnt(8)
	v_add_u32_e32 v54, s99, v59
	v_add_u32_e32 v55, s99, v60
	v_add_u32_e32 v56, s99, v61
	v_add_u32_e32 v57, s99, v62
	ds_read_b64_tr_b4 v[50:51], v160 offset:640
	ds_read_b64_tr_b4 v[52:53], v160 offset:1664
	ds_read_b64_tr_b4 v[130:131], v54
	ds_read_b64_tr_b4 v[132:133], v55
	ds_read_b64_tr_b4 v[134:135], v56
	ds_read_b64_tr_b4 v[136:137], v57
	s_waitcnt lgkmcnt(6)
	v_dot8c_i32_i4_e32 v38, v122, v48
	v_dot8c_i32_i4_e32 v39, v122, v46
	v_dot8c_i32_i4_e32 v40, v124, v48
	v_dot8c_i32_i4_e32 v41, v124, v46
	v_dot8c_i32_i4_e32 v42, v126, v48
	v_dot8c_i32_i4_e32 v43, v126, v46
	v_dot8c_i32_i4_e32 v44, v128, v48
	v_dot8c_i32_i4_e32 v45, v128, v46
	v_dot8c_i32_i4_e32 v38, v123, v49
	v_dot8c_i32_i4_e32 v39, v123, v47
	v_dot8c_i32_i4_e32 v40, v125, v49
	v_dot8c_i32_i4_e32 v41, v125, v47
	v_dot8c_i32_i4_e32 v42, v127, v49
	v_dot8c_i32_i4_e32 v43, v127, v47
	v_dot8c_i32_i4_e32 v44, v129, v49
	v_dot8c_i32_i4_e32 v45, v129, v47
	s_waitcnt lgkmcnt(15)
	v_add_u32_e32 v143, 8, v139
	v_and_b32_e32 v142, 15, v143
	v_xor_b32_e32 v142, 8, v142
	v_bfe_u32 v144, v143, 4, 4
	v_mul_lo_u32 v142, v142, s92
	v_mul_lo_u32 v144, v144, s92
	v_mov_b32_e32 v143, v142
	v_mov_b32_e32 v145, v144
	ds_write2st64_b64 v159, v[142:143], v[144:145] offset1:2
	v_and_b32_e32 v78, 0xffff, v28
	v_lshrrev_b32_e32 v79, 16, v28
	v_lshl_add_u32 v78, v78, 7, v150
	v_lshl_add_u32 v79, v79, 7, v151
	s_mov_b32 m0, s98
	s_add_i32 s43, s98, 0x400
	global_load_lds_dwordx4 v78, s[50:51]
	s_mov_b32 m0, s43
	s_nop 0
	global_load_lds_dwordx4 v79, s[50:51]
	s_waitcnt vmcnt(8)
	v_add_u32_e32 v54, s76, v59
	v_add_u32_e32 v55, s76, v60
	v_add_u32_e32 v56, s76, v61
	v_add_u32_e32 v57, s76, v62
	ds_read_b64_tr_b4 v[46:47], v160 offset:768
	ds_read_b64_tr_b4 v[48:49], v160 offset:1792
	ds_read_b64_tr_b4 v[122:123], v54
	ds_read_b64_tr_b4 v[124:125], v55
	ds_read_b64_tr_b4 v[126:127], v56
	ds_read_b64_tr_b4 v[128:129], v57
	s_waitcnt lgkmcnt(7)
	v_dot8c_i32_i4_e32 v38, v130, v52
	v_dot8c_i32_i4_e32 v39, v130, v50
	v_dot8c_i32_i4_e32 v40, v132, v52
	v_dot8c_i32_i4_e32 v41, v132, v50
	v_dot8c_i32_i4_e32 v42, v134, v52
	v_dot8c_i32_i4_e32 v43, v134, v50
	v_dot8c_i32_i4_e32 v44, v136, v52
	v_dot8c_i32_i4_e32 v45, v136, v50
	v_dot8c_i32_i4_e32 v38, v131, v53
	v_dot8c_i32_i4_e32 v39, v131, v51
	v_dot8c_i32_i4_e32 v40, v133, v53
	v_dot8c_i32_i4_e32 v41, v133, v51
	v_dot8c_i32_i4_e32 v42, v135, v53
	v_dot8c_i32_i4_e32 v43, v135, v51
	v_dot8c_i32_i4_e32 v44, v137, v53
	v_dot8c_i32_i4_e32 v45, v137, v51
	v_and_b32_e32 v78, 0xffff, v29
	v_lshrrev_b32_e32 v79, 16, v29
	v_lshl_add_u32 v78, v78, 7, v150
	v_lshl_add_u32 v79, v79, 7, v151
	s_mov_b32 m0, s99
	s_add_i32 s43, s99, 0x400
	global_load_lds_dwordx4 v78, s[50:51]
	s_mov_b32 m0, s43
	s_nop 0
	global_load_lds_dwordx4 v79, s[50:51]
	s_waitcnt vmcnt(8)
	v_add_u32_e32 v54, s77, v59
	v_add_u32_e32 v55, s77, v60
	v_add_u32_e32 v56, s77, v61
	v_add_u32_e32 v57, s77, v62
	ds_read_b64_tr_b4 v[50:51], v160 offset:896
	ds_read_b64_tr_b4 v[52:53], v160 offset:1920
	ds_read_b64_tr_b4 v[130:131], v54
	ds_read_b64_tr_b4 v[132:133], v55
	ds_read_b64_tr_b4 v[134:135], v56
	ds_read_b64_tr_b4 v[136:137], v57
	s_waitcnt lgkmcnt(6)
; #define LAS __attribute__((address_space(3)))
; __device__ __forceinline__ bf16 f2bf(float f) { return (bf16)f2bfu(f); }
; __device__ __forceinline__ void peer_v_tokens(int j, const LAS unsigned short* EL, const LAS unsigned char* AL  , const LAS float* ASC  , const LAS int* SAL  , ...
;     ...
;         for (int st = 0; st < 16; ++st) {
;             const int p = st >> 2, q = st & 3;
;             if (st < 14) VDMA(st + 2, (st + 2) % 3);
;             if (st < 14) asm volatile("s_waitcnt vmcnt(8)" ::: "memory");
;             else if (st == 14) asm volatile("s_waitcnt vmcnt(4)" ::: "memory");
;             else asm volatile("s_waitcnt vmcnt(0)" ::: "memory");
;             if (q == 0) {
; #pragma unroll
;                 for (int r = 0; r < 4; ++r) { accH[r] = 0; accL[r] = 0; } }
; #pragma unroll
;             for (int tp = 0; tp < 2; ++tp) {
;                 const v2i ao = TR4(ATL + (2 * q + tp) * 128 + 8 * s16), ah = TR4(ATL + 1024 + (2 * q + tp) * 128 + 8 * s16);
; #pragma unroll
;                 for (int r = 0; r < 4; ++r) {
;                     const v2i d = TR4(ldsb + BUF[st % 3] + 2048 * tp + roff[r]);
;                     accH[r] = __builtin_amdgcn_sdot8(d.x, ah.x, accH[r], false); accH[r] = __builtin_amdgcn_sdot8(d.y, ah.y, accH[r], false);
;                     accL[r] = __builtin_amdgcn_sdot8(d.x, ao.x, accL[r], false); accL[r] = __builtin_amdgcn_sdot8(d.y, ao.y, accL[r], false);
;                 }
;             }
;             asm volatile("s_waitcnt lgkmcnt(0)" ::: "memory");
;             if (q == 3) {
; #pragma unroll
;                 for (int r = 0; r < 4; ++r) STASH[256 * p + 16 * (grp + 4 * r) + pc] = f2bf(asc * (float)(2 * ((accH[r] << 4) + accL[r]) + sa));
;             }
;     ...
;         {
;             float4 v[4]; float ss = 0.f;
; #pragma unroll
;             for (int jq = 0; jq < 4; ++jq) { typedef unsigned u2v __attribute__((ext_vector_type(2))); const u2v pw = *(const LAS u2v*)(STASH + 4 * lane + 256 * jq); const uint2 hw = hv[jq];
;                 v[jq] = make_float4(__uint_as_float(hw.x << 16) + __uint_as_float(pw.x << 16), __uint_as_float(hw.x & 0xffff0000u) + __uint_as_float(pw.x & 0xffff0000u),
;                                     __uint_as_float(hw.y << 16) + __uint_as_float(pw.y << 16), __uint_as_float(hw.y & 0xffff0000u) + __uint_as_float(pw.y & 0xffff0000u));
	v_dot8c_i32_i4_e32 v38, v122, v48
	v_dot8c_i32_i4_e32 v39, v122, v46
	v_dot8c_i32_i4_e32 v40, v124, v48
	v_dot8c_i32_i4_e32 v41, v124, v46
	v_dot8c_i32_i4_e32 v42, v126, v48
	v_dot8c_i32_i4_e32 v43, v126, v46
	v_dot8c_i32_i4_e32 v44, v128, v48
	v_dot8c_i32_i4_e32 v45, v128, v46
	v_dot8c_i32_i4_e32 v38, v123, v49
	v_dot8c_i32_i4_e32 v39, v123, v47
	v_dot8c_i32_i4_e32 v40, v125, v49
	v_dot8c_i32_i4_e32 v41, v125, v47
	v_dot8c_i32_i4_e32 v42, v127, v49
	v_dot8c_i32_i4_e32 v43, v127, v47
	v_dot8c_i32_i4_e32 v44, v129, v49
	v_dot8c_i32_i4_e32 v45, v129, v47
	v_and_b32_e32 v78, 0xffff, v30
	v_lshrrev_b32_e32 v79, 16, v30
	v_lshl_add_u32 v78, v78, 7, v150
	v_lshl_add_u32 v79, v79, 7, v151
	s_mov_b32 m0, s76
	s_add_i32 s43, s76, 0x400
	global_load_lds_dwordx4 v78, s[50:51]
	s_mov_b32 m0, s43
	s_nop 0
	global_load_lds_dwordx4 v79, s[50:51]
	s_waitcnt vmcnt(8)
	v_add_u32_e32 v54, s78, v59
	v_add_u32_e32 v55, s78, v60
	v_add_u32_e32 v56, s78, v61
	v_add_u32_e32 v57, s78, v62
	ds_read_b64_tr_b4 v[46:47], v160
	ds_read_b64_tr_b4 v[48:49], v160 offset:1024
	ds_read_b64_tr_b4 v[122:123], v54
	ds_read_b64_tr_b4 v[124:125], v55
	ds_read_b64_tr_b4 v[126:127], v56
	ds_read_b64_tr_b4 v[128:129], v57
	s_waitcnt lgkmcnt(6)
	v_dot8c_i32_i4_e32 v38, v130, v52
	v_dot8c_i32_i4_e32 v39, v130, v50
	v_dot8c_i32_i4_e32 v40, v132, v52
	v_dot8c_i32_i4_e32 v41, v132, v50
	v_dot8c_i32_i4_e32 v42, v134, v52
	v_dot8c_i32_i4_e32 v43, v134, v50
	v_dot8c_i32_i4_e32 v44, v136, v52
	v_dot8c_i32_i4_e32 v45, v136, v50
	v_dot8c_i32_i4_e32 v38, v131, v53
	v_dot8c_i32_i4_e32 v39, v131, v51
	v_dot8c_i32_i4_e32 v40, v133, v53
	v_dot8c_i32_i4_e32 v41, v133, v51
	v_dot8c_i32_i4_e32 v42, v135, v53
	v_dot8c_i32_i4_e32 v43, v135, v51
	v_dot8c_i32_i4_e32 v44, v137, v53
	v_dot8c_i32_i4_e32 v45, v137, v51
	s_nop 3
	s_waitcnt lgkmcnt(15)
	v_lshlrev_b32_e32 v38, 5, v38
	v_lshlrev_b32_e32 v39, 1, v39
	v_add3_u32 v38, v39, v229, v38
	v_cvt_f32_i32_e32 v38, v38
	v_mul_f32_e32 v38, v228, v38
	v_lshlrev_b32_e32 v40, 5, v40
	v_lshlrev_b32_e32 v41, 1, v41
	v_add3_u32 v40, v41, v229, v40
	v_cvt_f32_i32_e32 v40, v40
	v_mul_f32_e32 v40, v228, v40
	v_lshlrev_b32_e32 v42, 5, v42
	v_lshlrev_b32_e32 v43, 1, v43
	v_add3_u32 v42, v43, v229, v42
	v_cvt_f32_i32_e32 v42, v42
	v_mul_f32_e32 v42, v228, v42
	v_lshlrev_b32_e32 v44, 5, v44
	v_lshlrev_b32_e32 v45, 1, v45
	v_add3_u32 v44, v45, v229, v44
	v_cvt_f32_i32_e32 v44, v44
	v_mul_f32_e32 v44, v228, v44
	v_cvt_pk_bf16_f32 v178, v38, v40
	v_cvt_pk_bf16_f32 v179, v42, v44
	v_add_u32_e32 v147, 8, v140
	v_and_b32_e32 v146, 15, v147
	v_xor_b32_e32 v146, 8, v146
	v_bfe_u32 v148, v147, 4, 4
	v_mul_lo_u32 v146, v146, s92
	v_mul_lo_u32 v148, v148, s92
	v_mov_b32_e32 v147, v146
	v_mov_b32_e32 v149, v148
	ds_write2st64_b64 v77, v[146:147], v[148:149] offset1:2
	v_add_u32_e32 v138, 0x1800, v74
	ds_read_u8 v139, v138
	v_add_u32_e32 v141, 0x1800, v73
	ds_read_u8 v140, v141
	s_add_i32 s43, s67, 224
	v_mov_b32_e32 v138, s43
	ds_read2st64_b32 v[228:229], v138 offset1:1
	ds_read_b128 v[18:21], v227 offset:12288
	ds_read_b128 v[22:25], v227 offset:12304
	v_add_u32_e32 v152, 0x200000, v63
	v_add_u32_e32 v153, 0x200000, v64
	v_mov_b32_e32 v38, 0
	v_mov_b32_e32 v39, 0
	v_mov_b32_e32 v40, 0
	v_mov_b32_e32 v41, 0
	v_mov_b32_e32 v42, 0
	v_mov_b32_e32 v43, 0
	v_mov_b32_e32 v44, 0
	v_mov_b32_e32 v45, 0
	v_and_b32_e32 v78, 0xffff, v31
	v_lshrrev_b32_e32 v79, 16, v31
	v_lshl_add_u32 v78, v78, 7, v150
	v_lshl_add_u32 v79, v79, 7, v151
	s_mov_b32 m0, s77
	s_add_i32 s43, s77, 0x400
	global_load_lds_dwordx4 v78, s[50:51]
	s_mov_b32 m0, s43
	s_nop 0
	global_load_lds_dwordx4 v79, s[50:51]
	s_waitcnt vmcnt(8)
	v_add_u32_e32 v54, s79, v59
	v_add_u32_e32 v55, s79, v60
	v_add_u32_e32 v56, s79, v61
	v_add_u32_e32 v57, s79, v62
	ds_read_b64_tr_b4 v[50:51], v160 offset:128
	ds_read_b64_tr_b4 v[52:53], v160 offset:1152
	ds_read_b64_tr_b4 v[130:131], v54
	ds_read_b64_tr_b4 v[132:133], v55
	ds_read_b64_tr_b4 v[134:135], v56
	ds_read_b64_tr_b4 v[136:137], v57
	s_waitcnt lgkmcnt(12)
	s_waitcnt vmcnt(35) lgkmcnt(15)
	v_lshlrev_b32_e32 v210, 16, v194
	v_and_b32_e32 v211, 0xffff0000, v194
	v_lshlrev_b32_e32 v142, 16, v202
	v_and_b32_e32 v143, 0xffff0000, v202
	v_add_f32_e32 v210, v210, v142
	v_add_f32_e32 v211, v211, v143
	v_lshlrev_b32_e32 v212, 16, v195
	v_and_b32_e32 v213, 0xffff0000, v195
	v_lshlrev_b32_e32 v142, 16, v203
	v_and_b32_e32 v143, 0xffff0000, v203
	v_add_f32_e32 v212, v212, v142
	v_add_f32_e32 v213, v213, v143
	v_lshlrev_b32_e32 v214, 16, v196
	v_and_b32_e32 v215, 0xffff0000, v196
	v_lshlrev_b32_e32 v142, 16, v204
	v_and_b32_e32 v143, 0xffff0000, v204
	v_add_f32_e32 v214, v214, v142
	v_add_f32_e32 v215, v215, v143
	v_lshlrev_b32_e32 v216, 16, v197
	v_and_b32_e32 v217, 0xffff0000, v197
	v_lshlrev_b32_e32 v142, 16, v205
	v_and_b32_e32 v143, 0xffff0000, v205
	v_add_f32_e32 v216, v216, v142
	v_add_f32_e32 v217, v217, v143
	v_lshlrev_b32_e32 v218, 16, v198
	v_and_b32_e32 v219, 0xffff0000, v198
	v_lshlrev_b32_e32 v142, 16, v206
	v_and_b32_e32 v143, 0xffff0000, v206
	v_add_f32_e32 v218, v218, v142
	v_add_f32_e32 v219, v219, v143
	v_lshlrev_b32_e32 v220, 16, v199
	v_and_b32_e32 v221, 0xffff0000, v199
	v_lshlrev_b32_e32 v142, 16, v207
	v_and_b32_e32 v143, 0xffff0000, v207
	v_add_f32_e32 v220, v220, v142
	v_add_f32_e32 v221, v221, v143
	v_lshlrev_b32_e32 v222, 16, v200
	v_and_b32_e32 v223, 0xffff0000, v200
	v_lshlrev_b32_e32 v142, 16, v208
	v_and_b32_e32 v143, 0xffff0000, v208
	v_add_f32_e32 v222, v222, v142
	v_add_f32_e32 v223, v223, v143
	v_lshlrev_b32_e32 v224, 16, v201
	v_and_b32_e32 v225, 0xffff0000, v201
	v_lshlrev_b32_e32 v142, 16, v209
	v_and_b32_e32 v143, 0xffff0000, v209
	v_add_f32_e32 v224, v224, v142
; #define LAS __attribute__((address_space(3)))
; #define TR4(p_) __builtin_amdgcn_ds_read_tr4_b64_v2i32((LAS v2i*)(p_))
; __device__ __forceinline__ void peer_v_tokens(int j, const LAS unsigned short* EL, const LAS unsigned char* AL  , const LAS float* ASC  , const LAS int* SAL  , ...
;     ...
;         for (int st = 0; st < 16; ++st) {
;             const int p = st >> 2, q = st & 3;
;             if (st < 14) VDMA(st + 2, (st + 2) % 3);
;             if (st < 14) asm volatile("s_waitcnt vmcnt(8)" ::: "memory");
;             else if (st == 14) asm volatile("s_waitcnt vmcnt(4)" ::: "memory");
;             else asm volatile("s_waitcnt vmcnt(0)" ::: "memory");
;             if (q == 0) {
; #pragma unroll
;                 for (int r = 0; r < 4; ++r) { accH[r] = 0; accL[r] = 0; } }
; #pragma unroll
;             for (int tp = 0; tp < 2; ++tp) {
;                 const v2i ao = TR4(ATL + (2 * q + tp) * 128 + 8 * s16), ah = TR4(ATL + 1024 + (2 * q + tp) * 128 + 8 * s16);
; #pragma unroll
;                 for (int r = 0; r < 4; ++r) {
;                     const v2i d = TR4(ldsb + BUF[st % 3] + 2048 * tp + roff[r]);
;                     accH[r] = __builtin_amdgcn_sdot8(d.x, ah.x, accH[r], false); accH[r] = __builtin_amdgcn_sdot8(d.y, ah.y, accH[r], false);
;                     accL[r] = __builtin_amdgcn_sdot8(d.x, ao.x, accL[r], false); accL[r] = __builtin_amdgcn_sdot8(d.y, ao.y, accL[r], false);
;                 }
;             }
;     ...
;             for (int jq = 0; jq < 4; ++jq) { typedef unsigned u2v __attribute__((ext_vector_type(2))); const u2v pw = *(const LAS u2v*)(STASH + 4 * lane + 256 * jq); const uint2 hw = hv[jq];
;                 v[jq] = make_float4(__uint_as_float(hw.x << 16) + __uint_as_float(pw.x << 16), __uint_as_float(hw.x & 0xffff0000u) + __uint_as_float(pw.x & 0xffff0000u),
;                                     __uint_as_float(hw.y << 16) + __uint_as_float(pw.y << 16), __uint_as_float(hw.y & 0xffff0000u) + __uint_as_float(pw.y & 0xffff0000u));
;                 ss += v[jq].x * v[jq].x + v[jq].y * v[jq].y + v[jq].z * v[jq].z + v[jq].w * v[jq].w; }
;             ss = wave_sum(ss);
;             const float r3 = rsqrtf(ss * (1.f / D) + EPS);
	v_add_f32_e32 v225, v225, v143
	v_mov_b32_e32 v144, 0
	v_mul_f32_e32 v145, v210, v210
	v_fmac_f32_e32 v145, v211, v211
	v_fmac_f32_e32 v145, v212, v212
	v_fmac_f32_e32 v145, v213, v213
	v_add_f32_e32 v144, v144, v145
	v_mul_f32_e32 v145, v214, v214
	v_fmac_f32_e32 v145, v215, v215
	v_fmac_f32_e32 v145, v216, v216
	v_fmac_f32_e32 v145, v217, v217
	v_add_f32_e32 v144, v144, v145
	v_mul_f32_e32 v145, v218, v218
	v_fmac_f32_e32 v145, v219, v219
	v_fmac_f32_e32 v145, v220, v220
	v_fmac_f32_e32 v145, v221, v221
	v_add_f32_e32 v144, v144, v145
	v_mul_f32_e32 v145, v222, v222
	v_fmac_f32_e32 v145, v223, v223
	v_fmac_f32_e32 v145, v224, v224
	v_fmac_f32_e32 v145, v225, v225
	v_add_f32_e32 v144, v144, v145
	s_nop 1
	v_add_f32_dpp v144, v144, v144 quad_perm:[1,0,3,2] row_mask:0xf bank_mask:0xf bound_ctrl:1
	s_nop 1
	v_add_f32_dpp v144, v144, v144 quad_perm:[2,3,0,1] row_mask:0xf bank_mask:0xf bound_ctrl:1
	s_nop 1
	v_add_f32_dpp v144, v144, v144 row_half_mirror row_mask:0xf bank_mask:0xf bound_ctrl:1
	s_nop 1
	v_add_f32_dpp v144, v144, v144 row_mirror row_mask:0xf bank_mask:0xf bound_ctrl:1
	s_nop 1
	v_readlane_b32 s10, v144, 0
	v_readlane_b32 s11, v144, 16
	v_readlane_b32 s14, v144, 32
	v_readlane_b32 s15, v144, 48
	s_nop 3
	v_mov_b32_e32 v144, s11
	v_mov_b32_e32 v145, s15
	v_add_f32_e32 v144, s10, v144
	v_add_f32_e32 v145, s14, v145
	v_add_f32_e32 v144, v144, v145
	v_fmamk_f32 v144, v144, 0x3a800000, v111
	v_rsq_f32_e32 v144, v144
	s_nop 0
	v_mul_f32_e32 v210, v210, v144
	v_mul_f32_e32 v211, v211, v144
	v_mul_f32_e32 v212, v212, v144
	v_mul_f32_e32 v213, v213, v144
	v_mul_f32_e32 v214, v214, v144
	v_mul_f32_e32 v215, v215, v144
	v_mul_f32_e32 v216, v216, v144
	v_mul_f32_e32 v217, v217, v144
	v_mul_f32_e32 v218, v218, v144
	v_mul_f32_e32 v219, v219, v144
	v_mul_f32_e32 v220, v220, v144
	v_mul_f32_e32 v221, v221, v144
	v_mul_f32_e32 v222, v222, v144
	v_mul_f32_e32 v223, v223, v144
	v_mul_f32_e32 v224, v224, v144
	v_mul_f32_e32 v225, v225, v144
	v_dot8c_i32_i4_e32 v38, v122, v48
	v_dot8c_i32_i4_e32 v39, v122, v46
	v_dot8c_i32_i4_e32 v40, v124, v48
	v_dot8c_i32_i4_e32 v41, v124, v46
	v_dot8c_i32_i4_e32 v42, v126, v48
	v_dot8c_i32_i4_e32 v43, v126, v46
	v_dot8c_i32_i4_e32 v44, v128, v48
	v_dot8c_i32_i4_e32 v45, v128, v46
	v_dot8c_i32_i4_e32 v38, v123, v49
	v_dot8c_i32_i4_e32 v39, v123, v47
	v_dot8c_i32_i4_e32 v40, v125, v49
	v_dot8c_i32_i4_e32 v41, v125, v47
	v_dot8c_i32_i4_e32 v42, v127, v49
	v_dot8c_i32_i4_e32 v43, v127, v47
	v_dot8c_i32_i4_e32 v44, v129, v49
	v_dot8c_i32_i4_e32 v45, v129, v47
	v_and_b32_e32 v78, 0xffff, v32
	v_lshrrev_b32_e32 v79, 16, v32
	v_lshl_add_u32 v78, v78, 7, v150
	v_lshl_add_u32 v79, v79, 7, v151
	s_mov_b32 m0, s78
	s_add_i32 s43, s78, 0x400
	global_load_lds_dwordx4 v78, s[50:51]
	s_mov_b32 m0, s43
	s_nop 0
	global_load_lds_dwordx4 v79, s[50:51]
	s_waitcnt vmcnt(8)
	v_add_u32_e32 v54, s98, v59
	v_add_u32_e32 v55, s98, v60
	v_add_u32_e32 v56, s98, v61
	v_add_u32_e32 v57, s98, v62
	ds_read_b64_tr_b4 v[46:47], v160 offset:256
	ds_read_b64_tr_b4 v[48:49], v160 offset:1280
	ds_read_b64_tr_b4 v[122:123], v54
	ds_read_b64_tr_b4 v[124:125], v55
	ds_read_b64_tr_b4 v[126:127], v56
	ds_read_b64_tr_b4 v[128:129], v57
	s_waitcnt lgkmcnt(6)
	v_dot8c_i32_i4_e32 v38, v130, v52
	v_dot8c_i32_i4_e32 v39, v130, v50
	v_dot8c_i32_i4_e32 v40, v132, v52
	v_dot8c_i32_i4_e32 v41, v132, v50
	v_dot8c_i32_i4_e32 v42, v134, v52
	v_dot8c_i32_i4_e32 v43, v134, v50
	v_dot8c_i32_i4_e32 v44, v136, v52
	v_dot8c_i32_i4_e32 v45, v136, v50
	v_dot8c_i32_i4_e32 v38, v131, v53
	v_dot8c_i32_i4_e32 v39, v131, v51
	v_dot8c_i32_i4_e32 v40, v133, v53
	v_dot8c_i32_i4_e32 v41, v133, v51
	v_dot8c_i32_i4_e32 v42, v135, v53
	v_dot8c_i32_i4_e32 v43, v135, v51
	v_dot8c_i32_i4_e32 v44, v137, v53
	v_dot8c_i32_i4_e32 v45, v137, v51
	v_and_b32_e32 v78, 0xffff, v33
	v_lshrrev_b32_e32 v79, 16, v33
	v_lshl_add_u32 v78, v78, 7, v150
	v_lshl_add_u32 v79, v79, 7, v151
	s_mov_b32 m0, s79
	s_add_i32 s43, s79, 0x400
	global_load_lds_dwordx4 v78, s[50:51]
	s_mov_b32 m0, s43
	s_nop 0
	global_load_lds_dwordx4 v79, s[50:51]
	s_waitcnt vmcnt(8)
	v_add_u32_e32 v54, s99, v59
	v_add_u32_e32 v55, s99, v60
	v_add_u32_e32 v56, s99, v61
	v_add_u32_e32 v57, s99, v62
	ds_read_b64_tr_b4 v[50:51], v160 offset:384
	ds_read_b64_tr_b4 v[52:53], v160 offset:1408
	ds_read_b64_tr_b4 v[130:131], v54
	ds_read_b64_tr_b4 v[132:133], v55
	ds_read_b64_tr_b4 v[134:135], v56
	ds_read_b64_tr_b4 v[136:137], v57
	s_waitcnt lgkmcnt(6)
	v_dot8c_i32_i4_e32 v38, v122, v48
	v_dot8c_i32_i4_e32 v39, v122, v46
	v_dot8c_i32_i4_e32 v40, v124, v48
	v_dot8c_i32_i4_e32 v41, v124, v46
	v_dot8c_i32_i4_e32 v42, v126, v48
	v_dot8c_i32_i4_e32 v43, v126, v46
	v_dot8c_i32_i4_e32 v44, v128, v48
	v_dot8c_i32_i4_e32 v45, v128, v46
	v_dot8c_i32_i4_e32 v38, v123, v49
	v_dot8c_i32_i4_e32 v39, v123, v47
	v_dot8c_i32_i4_e32 v40, v125, v49
	v_dot8c_i32_i4_e32 v41, v125, v47
	v_dot8c_i32_i4_e32 v42, v127, v49
	v_dot8c_i32_i4_e32 v43, v127, v47
	v_dot8c_i32_i4_e32 v44, v129, v49
	v_dot8c_i32_i4_e32 v45, v129, v47
	s_waitcnt lgkmcnt(15)
	v_and_b32_e32 v78, 0xffff, v18
	v_lshrrev_b32_e32 v79, 16, v18
	v_lshl_add_u32 v78, v78, 7, v152
	v_lshl_add_u32 v79, v79, 7, v153
	s_mov_b32 m0, s98
	s_add_i32 s43, s98, 0x400
	global_load_lds_dwordx4 v78, s[50:51]
	s_mov_b32 m0, s43
	s_nop 0
	global_load_lds_dwordx4 v79, s[50:51]
	s_waitcnt vmcnt(8)
	v_add_u32_e32 v54, s76, v59
	v_add_u32_e32 v55, s76, v60
	v_add_u32_e32 v56, s76, v61
	v_add_u32_e32 v57, s76, v62
	ds_read_b64_tr_b4 v[46:47], v160 offset:512
	ds_read_b64_tr_b4 v[48:49], v160 offset:1536
	ds_read_b64_tr_b4 v[122:123], v54
	ds_read_b64_tr_b4 v[124:125], v55
	ds_read_b64_tr_b4 v[126:127], v56
	ds_read_b64_tr_b4 v[128:129], v57
	s_waitcnt lgkmcnt(6)
; #define TR4(p_) __builtin_amdgcn_ds_read_tr4_b64_v2i32((LAS v2i*)(p_))
; #define VDMA(st_, k_) do { _Pragma("unroll") for (int i_ = 0; i_ < 4; ++i_) { \
;         const unsigned off_ = (unsigned)((st_) >> 2) * (16384u * 128u) + (PE_ID(E, 4 * ((st_) & 3) + i_) << 7) + ((i_ & 1) ? cx1 : cx0); \
;         __builtin_amdgcn_global_load_lds((const unsigned*)(V4 + off_), (LAS unsigned*)(ldsb + BUF[k_] + 1024 * i_), 16, 0, 0); } } while (0)
; __device__ __forceinline__ void peer_v_tokens(int j, const LAS unsigned short* EL, const LAS unsigned char* AL  , const LAS float* ASC  , const LAS int* SAL  , ...
;     ...
;         for (int st = 0; st < 16; ++st) {
;             const int p = st >> 2, q = st & 3;
;             if (st < 14) VDMA(st + 2, (st + 2) % 3);
;             if (st < 14) asm volatile("s_waitcnt vmcnt(8)" ::: "memory");
;             else if (st == 14) asm volatile("s_waitcnt vmcnt(4)" ::: "memory");
;             else asm volatile("s_waitcnt vmcnt(0)" ::: "memory");
;             if (q == 0) {
; #pragma unroll
;                 for (int r = 0; r < 4; ++r) { accH[r] = 0; accL[r] = 0; } }
; #pragma unroll
;             for (int tp = 0; tp < 2; ++tp) {
;                 const v2i ao = TR4(ATL + (2 * q + tp) * 128 + 8 * s16), ah = TR4(ATL + 1024 + (2 * q + tp) * 128 + 8 * s16);
; #pragma unroll
;                 for (int r = 0; r < 4; ++r) {
;                     const v2i d = TR4(ldsb + BUF[st % 3] + 2048 * tp + roff[r]);
;                     accH[r] = __builtin_amdgcn_sdot8(d.x, ah.x, accH[r], false); accH[r] = __builtin_amdgcn_sdot8(d.y, ah.y, accH[r], false);
;                     accL[r] = __builtin_amdgcn_sdot8(d.x, ao.x, accL[r], false); accL[r] = __builtin_amdgcn_sdot8(d.y, ao.y, accL[r], false);
;                 }
;             }
	v_dot8c_i32_i4_e32 v38, v130, v52
	v_dot8c_i32_i4_e32 v39, v130, v50
	v_dot8c_i32_i4_e32 v40, v132, v52
	v_dot8c_i32_i4_e32 v41, v132, v50
	v_dot8c_i32_i4_e32 v42, v134, v52
	v_dot8c_i32_i4_e32 v43, v134, v50
	v_dot8c_i32_i4_e32 v44, v136, v52
	v_dot8c_i32_i4_e32 v45, v136, v50
	v_dot8c_i32_i4_e32 v38, v131, v53
	v_dot8c_i32_i4_e32 v39, v131, v51
	v_dot8c_i32_i4_e32 v40, v133, v53
	v_dot8c_i32_i4_e32 v41, v133, v51
	v_dot8c_i32_i4_e32 v42, v135, v53
	v_dot8c_i32_i4_e32 v43, v135, v51
	v_dot8c_i32_i4_e32 v44, v137, v53
	v_dot8c_i32_i4_e32 v45, v137, v51
	v_and_b32_e32 v78, 0xffff, v19
	v_lshrrev_b32_e32 v79, 16, v19
	v_lshl_add_u32 v78, v78, 7, v152
	v_lshl_add_u32 v79, v79, 7, v153
	s_mov_b32 m0, s99
	s_add_i32 s43, s99, 0x400
	global_load_lds_dwordx4 v78, s[50:51]
	s_mov_b32 m0, s43
	s_nop 0
	global_load_lds_dwordx4 v79, s[50:51]
	s_waitcnt vmcnt(8)
	v_add_u32_e32 v54, s77, v59
	v_add_u32_e32 v55, s77, v60
	v_add_u32_e32 v56, s77, v61
	v_add_u32_e32 v57, s77, v62
	ds_read_b64_tr_b4 v[50:51], v160 offset:640
	ds_read_b64_tr_b4 v[52:53], v160 offset:1664
	ds_read_b64_tr_b4 v[130:131], v54
	ds_read_b64_tr_b4 v[132:133], v55
	ds_read_b64_tr_b4 v[134:135], v56
	ds_read_b64_tr_b4 v[136:137], v57
	s_waitcnt lgkmcnt(6)
	v_dot8c_i32_i4_e32 v38, v122, v48
	v_dot8c_i32_i4_e32 v39, v122, v46
	v_dot8c_i32_i4_e32 v40, v124, v48
	v_dot8c_i32_i4_e32 v41, v124, v46
	v_dot8c_i32_i4_e32 v42, v126, v48
	v_dot8c_i32_i4_e32 v43, v126, v46
	v_dot8c_i32_i4_e32 v44, v128, v48
	v_dot8c_i32_i4_e32 v45, v128, v46
	v_dot8c_i32_i4_e32 v38, v123, v49
	v_dot8c_i32_i4_e32 v39, v123, v47
	v_dot8c_i32_i4_e32 v40, v125, v49
	v_dot8c_i32_i4_e32 v41, v125, v47
	v_dot8c_i32_i4_e32 v42, v127, v49
	v_dot8c_i32_i4_e32 v43, v127, v47
	v_dot8c_i32_i4_e32 v44, v129, v49
	v_dot8c_i32_i4_e32 v45, v129, v47
	s_waitcnt lgkmcnt(15)
	v_add_u32_e32 v143, 8, v139
	v_and_b32_e32 v142, 15, v143
	v_xor_b32_e32 v142, 8, v142
	v_bfe_u32 v144, v143, 4, 4
	v_mul_lo_u32 v142, v142, s92
	v_mul_lo_u32 v144, v144, s92
	v_mov_b32_e32 v143, v142
	v_mov_b32_e32 v145, v144
	ds_write2st64_b64 v159, v[142:143], v[144:145] offset1:2
	v_and_b32_e32 v78, 0xffff, v20
	v_lshrrev_b32_e32 v79, 16, v20
	v_lshl_add_u32 v78, v78, 7, v152
	v_lshl_add_u32 v79, v79, 7, v153
	s_mov_b32 m0, s76
	s_add_i32 s43, s76, 0x400
	global_load_lds_dwordx4 v78, s[50:51]
	s_mov_b32 m0, s43
	s_nop 0
	global_load_lds_dwordx4 v79, s[50:51]
	s_waitcnt vmcnt(8)
	v_add_u32_e32 v54, s78, v59
	v_add_u32_e32 v55, s78, v60
	v_add_u32_e32 v56, s78, v61
	v_add_u32_e32 v57, s78, v62
	ds_read_b64_tr_b4 v[46:47], v160 offset:768
	ds_read_b64_tr_b4 v[48:49], v160 offset:1792
	ds_read_b64_tr_b4 v[122:123], v54
	ds_read_b64_tr_b4 v[124:125], v55
	ds_read_b64_tr_b4 v[126:127], v56
	ds_read_b64_tr_b4 v[128:129], v57
	s_waitcnt lgkmcnt(7)
	v_dot8c_i32_i4_e32 v38, v130, v52
	v_dot8c_i32_i4_e32 v39, v130, v50
	v_dot8c_i32_i4_e32 v40, v132, v52
	v_dot8c_i32_i4_e32 v41, v132, v50
	v_dot8c_i32_i4_e32 v42, v134, v52
	v_dot8c_i32_i4_e32 v43, v134, v50
	v_dot8c_i32_i4_e32 v44, v136, v52
	v_dot8c_i32_i4_e32 v45, v136, v50
	v_dot8c_i32_i4_e32 v38, v131, v53
	v_dot8c_i32_i4_e32 v39, v131, v51
	v_dot8c_i32_i4_e32 v40, v133, v53
	v_dot8c_i32_i4_e32 v41, v133, v51
	v_dot8c_i32_i4_e32 v42, v135, v53
	v_dot8c_i32_i4_e32 v43, v135, v51
	v_dot8c_i32_i4_e32 v44, v137, v53
	v_dot8c_i32_i4_e32 v45, v137, v51
	v_and_b32_e32 v78, 0xffff, v21
	v_lshrrev_b32_e32 v79, 16, v21
	v_lshl_add_u32 v78, v78, 7, v152
	v_lshl_add_u32 v79, v79, 7, v153
	s_mov_b32 m0, s77
	s_add_i32 s43, s77, 0x400
	global_load_lds_dwordx4 v78, s[50:51]
	s_mov_b32 m0, s43
	s_nop 0
	global_load_lds_dwordx4 v79, s[50:51]
	s_waitcnt vmcnt(8)
	v_add_u32_e32 v54, s79, v59
	v_add_u32_e32 v55, s79, v60
	v_add_u32_e32 v56, s79, v61
	v_add_u32_e32 v57, s79, v62
	ds_read_b64_tr_b4 v[50:51], v160 offset:896
	ds_read_b64_tr_b4 v[52:53], v160 offset:1920
	ds_read_b64_tr_b4 v[130:131], v54
	ds_read_b64_tr_b4 v[132:133], v55
	ds_read_b64_tr_b4 v[134:135], v56
	ds_read_b64_tr_b4 v[136:137], v57
	s_waitcnt lgkmcnt(6)
	v_dot8c_i32_i4_e32 v38, v122, v48
	v_dot8c_i32_i4_e32 v39, v122, v46
	v_dot8c_i32_i4_e32 v40, v124, v48
	v_dot8c_i32_i4_e32 v41, v124, v46
	v_dot8c_i32_i4_e32 v42, v126, v48
	v_dot8c_i32_i4_e32 v43, v126, v46
	v_dot8c_i32_i4_e32 v44, v128, v48
	v_dot8c_i32_i4_e32 v45, v128, v46
	v_dot8c_i32_i4_e32 v38, v123, v49
	v_dot8c_i32_i4_e32 v39, v123, v47
	v_dot8c_i32_i4_e32 v40, v125, v49
	v_dot8c_i32_i4_e32 v41, v125, v47
	v_dot8c_i32_i4_e32 v42, v127, v49
	v_dot8c_i32_i4_e32 v43, v127, v47
	v_dot8c_i32_i4_e32 v44, v129, v49
	v_dot8c_i32_i4_e32 v45, v129, v47
	v_and_b32_e32 v78, 0xffff, v22
	v_lshrrev_b32_e32 v79, 16, v22
	v_lshl_add_u32 v78, v78, 7, v152
	v_lshl_add_u32 v79, v79, 7, v153
	s_mov_b32 m0, s78
	s_add_i32 s43, s78, 0x400
	global_load_lds_dwordx4 v78, s[50:51]
	s_mov_b32 m0, s43
	s_nop 0
	global_load_lds_dwordx4 v79, s[50:51]
	s_waitcnt vmcnt(8)
	v_add_u32_e32 v54, s98, v59
	v_add_u32_e32 v55, s98, v60
	v_add_u32_e32 v56, s98, v61
	v_add_u32_e32 v57, s98, v62
	ds_read_b64_tr_b4 v[46:47], v160
	ds_read_b64_tr_b4 v[48:49], v160 offset:1024
	ds_read_b64_tr_b4 v[122:123], v54
	ds_read_b64_tr_b4 v[124:125], v55
	ds_read_b64_tr_b4 v[126:127], v56
	ds_read_b64_tr_b4 v[128:129], v57
	s_waitcnt lgkmcnt(6)
	v_dot8c_i32_i4_e32 v38, v130, v52
	v_dot8c_i32_i4_e32 v39, v130, v50
	v_dot8c_i32_i4_e32 v40, v132, v52
	v_dot8c_i32_i4_e32 v41, v132, v50
	v_dot8c_i32_i4_e32 v42, v134, v52
	v_dot8c_i32_i4_e32 v43, v134, v50
	v_dot8c_i32_i4_e32 v44, v136, v52
	v_dot8c_i32_i4_e32 v45, v136, v50
	v_dot8c_i32_i4_e32 v38, v131, v53
	v_dot8c_i32_i4_e32 v39, v131, v51
	v_dot8c_i32_i4_e32 v40, v133, v53
	v_dot8c_i32_i4_e32 v41, v133, v51
	v_dot8c_i32_i4_e32 v42, v135, v53
	v_dot8c_i32_i4_e32 v43, v135, v51
	v_dot8c_i32_i4_e32 v44, v137, v53
	v_dot8c_i32_i4_e32 v45, v137, v51
	s_nop 3
	s_waitcnt lgkmcnt(15)
; __device__ __forceinline__ bf16 f2bf(float f) { return (bf16)f2bfu(f); }
; __device__ __forceinline__ void peer_v_tokens(int j, const LAS unsigned short* EL, const LAS unsigned char* AL  , const LAS float* ASC  , const LAS int* SAL  , ...
;     ...
;         { unsigned ho = (unsigned)t * (D / 4) + (unsigned)lane; asm volatile("" : "+v"(ho)); const uint2* hp = (const uint2*)HB + ho; const float4* gp = (const float4*)fng + lane;
; #pragma unroll
;           for (int jq = 0; jq < 4; ++jq) { hv[jq] = hp[64 * jq]; gv[jq] = gp[64 * jq]; } }
;     ...
;             asm volatile("s_waitcnt lgkmcnt(0)" ::: "memory");
;             if (q == 3) {
; #pragma unroll
;                 for (int r = 0; r < 4; ++r) STASH[256 * p + 16 * (grp + 4 * r) + pc] = f2bf(asc * (float)(2 * ((accH[r] << 4) + accL[r]) + sa));
;             }
;     ...
;             float4* op = (float4*)(outp + (size_t)t * D) + lane;
; #pragma unroll
;             for (int jq = 0; jq < 4; ++jq) { typedef float f4v __attribute__((ext_vector_type(4))); f4v o4; o4.x = v[jq].x * r3 * gv[jq].x; o4.y = v[jq].y * r3 * gv[jq].y; o4.z = v[jq].z * r3 * gv[jq].z; o4.w = v[jq].w * r3 * gv[jq].w;
;                 __builtin_nontemporal_store(o4, (f4v*)op + 64 * jq); }
	v_lshlrev_b32_e32 v38, 5, v38
	v_lshlrev_b32_e32 v39, 1, v39
	v_add3_u32 v38, v39, v229, v38
	v_cvt_f32_i32_e32 v38, v38
	v_mul_f32_e32 v38, v228, v38
	v_lshlrev_b32_e32 v40, 5, v40
	v_lshlrev_b32_e32 v41, 1, v41
	v_add3_u32 v40, v41, v229, v40
	v_cvt_f32_i32_e32 v40, v40
	v_mul_f32_e32 v40, v228, v40
	v_lshlrev_b32_e32 v42, 5, v42
	v_lshlrev_b32_e32 v43, 1, v43
	v_add3_u32 v42, v43, v229, v42
	v_cvt_f32_i32_e32 v42, v42
	v_mul_f32_e32 v42, v228, v42
	v_lshlrev_b32_e32 v44, 5, v44
	v_lshlrev_b32_e32 v45, 1, v45
	v_add3_u32 v44, v45, v229, v44
	v_cvt_f32_i32_e32 v44, v44
	v_mul_f32_e32 v44, v228, v44
	v_cvt_pk_bf16_f32 v186, v38, v40
	v_cvt_pk_bf16_f32 v187, v42, v44
	ds_read_b128 v[252:255], v155
	s_add_i32 s44, s40, 32
	s_ashr_i32 s45, s44, 31
	s_lshl_b64 s[44:45], s[44:45], 12
	v_lshl_add_u64 v[80:81], v[36:37], 0, s[44:45]
	s_waitcnt lgkmcnt(0)
	v_mul_f32_e32 v210, v210, v252
	v_mul_f32_e32 v211, v211, v253
	v_mul_f32_e32 v212, v212, v254
	v_mul_f32_e32 v213, v213, v255
	global_store_dwordx4 v[80:81], v[210:213], off nt
	s_add_i32 s43, s40, 40
	s_lshl_b32 s43, s43, 11
	v_add_u32_e32 v138, s43, v66
	global_load_dwordx2 v[194:195], v138, s[70:71]
	global_load_dwordx2 v[196:197], v138, s[70:71] offset:512
	global_load_dwordx2 v[198:199], v138, s[70:71] offset:1024
	global_load_dwordx2 v[200:201], v138, s[70:71] offset:1536
	v_add_u32_e32 v147, 8, v140
	v_and_b32_e32 v146, 15, v147
	v_xor_b32_e32 v146, 8, v146
	v_bfe_u32 v148, v147, 4, 4
	v_mul_lo_u32 v146, v146, s92
	v_mul_lo_u32 v148, v148, s92
	v_mov_b32_e32 v147, v146
	v_mov_b32_e32 v149, v148
	ds_write2st64_b64 v77, v[146:147], v[148:149] offset1:2
	v_add_u32_e32 v138, 0x1c00, v74
	ds_read_u8 v139, v138
	v_add_u32_e32 v141, 0x1c00, v73
	ds_read_u8 v140, v141
	s_add_i32 s43, s67, 192
	v_mov_b32_e32 v138, s43
	ds_read2st64_b32 v[228:229], v138 offset1:1
	ds_read_b128 v[26:29], v227 offset:14336
	ds_read_b128 v[30:33], v227 offset:14352
	v_mov_b32_e32 v38, 0
	v_mov_b32_e32 v39, 0
	v_mov_b32_e32 v40, 0
	v_mov_b32_e32 v41, 0
	v_mov_b32_e32 v42, 0
	v_mov_b32_e32 v43, 0
	v_mov_b32_e32 v44, 0
	v_mov_b32_e32 v45, 0
	v_and_b32_e32 v78, 0xffff, v23
	v_lshrrev_b32_e32 v79, 16, v23
	v_lshl_add_u32 v78, v78, 7, v152
	v_lshl_add_u32 v79, v79, 7, v153
	s_mov_b32 m0, s79
	s_add_i32 s43, s79, 0x400
	global_load_lds_dwordx4 v78, s[50:51]
	s_mov_b32 m0, s43
	s_nop 0
	global_load_lds_dwordx4 v79, s[50:51]
	s_waitcnt vmcnt(13)
	v_add_u32_e32 v54, s99, v59
	v_add_u32_e32 v55, s99, v60
	v_add_u32_e32 v56, s99, v61
	v_add_u32_e32 v57, s99, v62
	ds_read_b64_tr_b4 v[50:51], v160 offset:128
	ds_read_b64_tr_b4 v[52:53], v160 offset:1152
	ds_read_b64_tr_b4 v[130:131], v54
	ds_read_b64_tr_b4 v[132:133], v55
	ds_read_b64_tr_b4 v[134:135], v56
	ds_read_b64_tr_b4 v[136:137], v57
	s_waitcnt lgkmcnt(13)
	v_dot8c_i32_i4_e32 v38, v122, v48
	v_dot8c_i32_i4_e32 v39, v122, v46
	v_dot8c_i32_i4_e32 v40, v124, v48
	v_dot8c_i32_i4_e32 v41, v124, v46
	v_dot8c_i32_i4_e32 v42, v126, v48
	v_dot8c_i32_i4_e32 v43, v126, v46
	v_dot8c_i32_i4_e32 v44, v128, v48
	v_dot8c_i32_i4_e32 v45, v128, v46
	v_dot8c_i32_i4_e32 v38, v123, v49
	v_dot8c_i32_i4_e32 v39, v123, v47
	v_dot8c_i32_i4_e32 v40, v125, v49
	v_dot8c_i32_i4_e32 v41, v125, v47
	v_dot8c_i32_i4_e32 v42, v127, v49
	v_dot8c_i32_i4_e32 v43, v127, v47
	v_dot8c_i32_i4_e32 v44, v129, v49
	v_dot8c_i32_i4_e32 v45, v129, v47
	v_and_b32_e32 v78, 0xffff, v24
	v_lshrrev_b32_e32 v79, 16, v24
	v_lshl_add_u32 v78, v78, 7, v152
	v_lshl_add_u32 v79, v79, 7, v153
	s_mov_b32 m0, s98
	s_add_i32 s43, s98, 0x400
	global_load_lds_dwordx4 v78, s[50:51]
	s_mov_b32 m0, s43
	s_nop 0
	global_load_lds_dwordx4 v79, s[50:51]
	s_waitcnt vmcnt(13)
	v_add_u32_e32 v54, s76, v59
	v_add_u32_e32 v55, s76, v60
	v_add_u32_e32 v56, s76, v61
	v_add_u32_e32 v57, s76, v62
	ds_read_b64_tr_b4 v[46:47], v160 offset:256
	ds_read_b64_tr_b4 v[48:49], v160 offset:1280
	ds_read_b64_tr_b4 v[122:123], v54
	ds_read_b64_tr_b4 v[124:125], v55
	ds_read_b64_tr_b4 v[126:127], v56
	ds_read_b64_tr_b4 v[128:129], v57
	s_waitcnt lgkmcnt(6)
	v_dot8c_i32_i4_e32 v38, v130, v52
	v_dot8c_i32_i4_e32 v39, v130, v50
	v_dot8c_i32_i4_e32 v40, v132, v52
	v_dot8c_i32_i4_e32 v41, v132, v50
	v_dot8c_i32_i4_e32 v42, v134, v52
	v_dot8c_i32_i4_e32 v43, v134, v50
	v_dot8c_i32_i4_e32 v44, v136, v52
	v_dot8c_i32_i4_e32 v45, v136, v50
	v_dot8c_i32_i4_e32 v38, v131, v53
	v_dot8c_i32_i4_e32 v39, v131, v51
	v_dot8c_i32_i4_e32 v40, v133, v53
	v_dot8c_i32_i4_e32 v41, v133, v51
	v_dot8c_i32_i4_e32 v42, v135, v53
	v_dot8c_i32_i4_e32 v43, v135, v51
	v_dot8c_i32_i4_e32 v44, v137, v53
	v_dot8c_i32_i4_e32 v45, v137, v51
	v_and_b32_e32 v78, 0xffff, v25
	v_lshrrev_b32_e32 v79, 16, v25
	v_lshl_add_u32 v78, v78, 7, v152
	v_lshl_add_u32 v79, v79, 7, v153
	s_mov_b32 m0, s99
	s_add_i32 s43, s99, 0x400
	global_load_lds_dwordx4 v78, s[50:51]
	s_mov_b32 m0, s43
	s_nop 0
	global_load_lds_dwordx4 v79, s[50:51]
	s_waitcnt vmcnt(13)
	v_add_u32_e32 v54, s77, v59
	v_add_u32_e32 v55, s77, v60
	v_add_u32_e32 v56, s77, v61
	v_add_u32_e32 v57, s77, v62
	ds_read_b64_tr_b4 v[50:51], v160 offset:384
	ds_read_b64_tr_b4 v[52:53], v160 offset:1408
	ds_read_b64_tr_b4 v[130:131], v54
	ds_read_b64_tr_b4 v[132:133], v55
	ds_read_b64_tr_b4 v[134:135], v56
	ds_read_b64_tr_b4 v[136:137], v57
	s_waitcnt lgkmcnt(6)
	v_dot8c_i32_i4_e32 v38, v122, v48
	v_dot8c_i32_i4_e32 v39, v122, v46
	v_dot8c_i32_i4_e32 v40, v124, v48
	v_dot8c_i32_i4_e32 v41, v124, v46
	v_dot8c_i32_i4_e32 v42, v126, v48
	v_dot8c_i32_i4_e32 v43, v126, v46
	v_dot8c_i32_i4_e32 v44, v128, v48
	v_dot8c_i32_i4_e32 v45, v128, v46
	v_dot8c_i32_i4_e32 v38, v123, v49
	v_dot8c_i32_i4_e32 v39, v123, v47
	v_dot8c_i32_i4_e32 v40, v125, v49
	v_dot8c_i32_i4_e32 v41, v125, v47
	v_dot8c_i32_i4_e32 v42, v127, v49
	v_dot8c_i32_i4_e32 v43, v127, v47
	v_dot8c_i32_i4_e32 v44, v129, v49
	v_dot8c_i32_i4_e32 v45, v129, v47
	s_waitcnt lgkmcnt(15)
; #define TR4(p_) __builtin_amdgcn_ds_read_tr4_b64_v2i32((LAS v2i*)(p_))
; #define VDMA(st_, k_) do { _Pragma("unroll") for (int i_ = 0; i_ < 4; ++i_) { \
;         const unsigned off_ = (unsigned)((st_) >> 2) * (16384u * 128u) + (PE_ID(E, 4 * ((st_) & 3) + i_) << 7) + ((i_ & 1) ? cx1 : cx0); \
;         __builtin_amdgcn_global_load_lds((const unsigned*)(V4 + off_), (LAS unsigned*)(ldsb + BUF[k_] + 1024 * i_), 16, 0, 0); } } while (0)
; __device__ __forceinline__ void peer_v_tokens(int j, const LAS unsigned short* EL, const LAS unsigned char* AL  , const LAS float* ASC  , const LAS int* SAL  , ...
;     ...
;         for (int st = 0; st < 16; ++st) {
;             const int p = st >> 2, q = st & 3;
;             if (st < 14) VDMA(st + 2, (st + 2) % 3);
;             if (st < 14) asm volatile("s_waitcnt vmcnt(8)" ::: "memory");
;             else if (st == 14) asm volatile("s_waitcnt vmcnt(4)" ::: "memory");
;             else asm volatile("s_waitcnt vmcnt(0)" ::: "memory");
;             if (q == 0) {
; #pragma unroll
;                 for (int r = 0; r < 4; ++r) { accH[r] = 0; accL[r] = 0; } }
; #pragma unroll
;             for (int tp = 0; tp < 2; ++tp) {
;                 const v2i ao = TR4(ATL + (2 * q + tp) * 128 + 8 * s16), ah = TR4(ATL + 1024 + (2 * q + tp) * 128 + 8 * s16);
; #pragma unroll
;                 for (int r = 0; r < 4; ++r) {
;                     const v2i d = TR4(ldsb + BUF[st % 3] + 2048 * tp + roff[r]);
;                     accH[r] = __builtin_amdgcn_sdot8(d.x, ah.x, accH[r], false); accH[r] = __builtin_amdgcn_sdot8(d.y, ah.y, accH[r], false);
;                     accL[r] = __builtin_amdgcn_sdot8(d.x, ao.x, accL[r], false); accL[r] = __builtin_amdgcn_sdot8(d.y, ao.y, accL[r], false);
;                 }
;             }
	v_and_b32_e32 v78, 0xffff, v26
	v_lshrrev_b32_e32 v79, 16, v26
	v_lshl_add_u32 v78, v78, 7, v152
	v_lshl_add_u32 v79, v79, 7, v153
	s_mov_b32 m0, s76
	s_add_i32 s43, s76, 0x400
	global_load_lds_dwordx4 v78, s[50:51]
	s_mov_b32 m0, s43
	s_nop 0
	global_load_lds_dwordx4 v79, s[50:51]
	s_waitcnt vmcnt(13)
	v_add_u32_e32 v54, s78, v59
	v_add_u32_e32 v55, s78, v60
	v_add_u32_e32 v56, s78, v61
	v_add_u32_e32 v57, s78, v62
	ds_read_b64_tr_b4 v[46:47], v160 offset:512
	ds_read_b64_tr_b4 v[48:49], v160 offset:1536
	ds_read_b64_tr_b4 v[122:123], v54
	ds_read_b64_tr_b4 v[124:125], v55
	ds_read_b64_tr_b4 v[126:127], v56
	ds_read_b64_tr_b4 v[128:129], v57
	s_waitcnt lgkmcnt(6)
	v_dot8c_i32_i4_e32 v38, v130, v52
	v_dot8c_i32_i4_e32 v39, v130, v50
	v_dot8c_i32_i4_e32 v40, v132, v52
	v_dot8c_i32_i4_e32 v41, v132, v50
	v_dot8c_i32_i4_e32 v42, v134, v52
	v_dot8c_i32_i4_e32 v43, v134, v50
	v_dot8c_i32_i4_e32 v44, v136, v52
	v_dot8c_i32_i4_e32 v45, v136, v50
	v_dot8c_i32_i4_e32 v38, v131, v53
	v_dot8c_i32_i4_e32 v39, v131, v51
	v_dot8c_i32_i4_e32 v40, v133, v53
	v_dot8c_i32_i4_e32 v41, v133, v51
	v_dot8c_i32_i4_e32 v42, v135, v53
	v_dot8c_i32_i4_e32 v43, v135, v51
	v_dot8c_i32_i4_e32 v44, v137, v53
	v_dot8c_i32_i4_e32 v45, v137, v51
	v_and_b32_e32 v78, 0xffff, v27
	v_lshrrev_b32_e32 v79, 16, v27
	v_lshl_add_u32 v78, v78, 7, v152
	v_lshl_add_u32 v79, v79, 7, v153
	s_mov_b32 m0, s77
	s_add_i32 s43, s77, 0x400
	global_load_lds_dwordx4 v78, s[50:51]
	s_mov_b32 m0, s43
	s_nop 0
	global_load_lds_dwordx4 v79, s[50:51]
	s_waitcnt vmcnt(8)
	v_add_u32_e32 v54, s79, v59
	v_add_u32_e32 v55, s79, v60
	v_add_u32_e32 v56, s79, v61
	v_add_u32_e32 v57, s79, v62
	ds_read_b64_tr_b4 v[50:51], v160 offset:640
	ds_read_b64_tr_b4 v[52:53], v160 offset:1664
	ds_read_b64_tr_b4 v[130:131], v54
	ds_read_b64_tr_b4 v[132:133], v55
	ds_read_b64_tr_b4 v[134:135], v56
	ds_read_b64_tr_b4 v[136:137], v57
	s_waitcnt lgkmcnt(6)
	v_dot8c_i32_i4_e32 v38, v122, v48
	v_dot8c_i32_i4_e32 v39, v122, v46
	v_dot8c_i32_i4_e32 v40, v124, v48
	v_dot8c_i32_i4_e32 v41, v124, v46
	v_dot8c_i32_i4_e32 v42, v126, v48
	v_dot8c_i32_i4_e32 v43, v126, v46
	v_dot8c_i32_i4_e32 v44, v128, v48
	v_dot8c_i32_i4_e32 v45, v128, v46
	v_dot8c_i32_i4_e32 v38, v123, v49
	v_dot8c_i32_i4_e32 v39, v123, v47
	v_dot8c_i32_i4_e32 v40, v125, v49
	v_dot8c_i32_i4_e32 v41, v125, v47
	v_dot8c_i32_i4_e32 v42, v127, v49
	v_dot8c_i32_i4_e32 v43, v127, v47
	v_dot8c_i32_i4_e32 v44, v129, v49
	v_dot8c_i32_i4_e32 v45, v129, v47
	s_waitcnt lgkmcnt(15)
	v_add_u32_e32 v143, 8, v139
	v_and_b32_e32 v142, 15, v143
	v_xor_b32_e32 v142, 8, v142
	v_bfe_u32 v144, v143, 4, 4
	v_mul_lo_u32 v142, v142, s92
	v_mul_lo_u32 v144, v144, s92
	v_mov_b32_e32 v143, v142
	v_mov_b32_e32 v145, v144
	ds_write2st64_b64 v159, v[142:143], v[144:145] offset1:2
	v_and_b32_e32 v78, 0xffff, v28
	v_lshrrev_b32_e32 v79, 16, v28
	v_lshl_add_u32 v78, v78, 7, v152
	v_lshl_add_u32 v79, v79, 7, v153
	s_mov_b32 m0, s78
	s_add_i32 s43, s78, 0x400
	global_load_lds_dwordx4 v78, s[50:51]
	s_mov_b32 m0, s43
	s_nop 0
	global_load_lds_dwordx4 v79, s[50:51]
	s_waitcnt vmcnt(8)
	v_add_u32_e32 v54, s98, v59
	v_add_u32_e32 v55, s98, v60
	v_add_u32_e32 v56, s98, v61
	v_add_u32_e32 v57, s98, v62
	ds_read_b64_tr_b4 v[46:47], v160 offset:768
	ds_read_b64_tr_b4 v[48:49], v160 offset:1792
	ds_read_b64_tr_b4 v[122:123], v54
	ds_read_b64_tr_b4 v[124:125], v55
	ds_read_b64_tr_b4 v[126:127], v56
	ds_read_b64_tr_b4 v[128:129], v57
	s_waitcnt lgkmcnt(7)
	v_dot8c_i32_i4_e32 v38, v130, v52
	v_dot8c_i32_i4_e32 v39, v130, v50
	v_dot8c_i32_i4_e32 v40, v132, v52
	v_dot8c_i32_i4_e32 v41, v132, v50
	v_dot8c_i32_i4_e32 v42, v134, v52
	v_dot8c_i32_i4_e32 v43, v134, v50
	v_dot8c_i32_i4_e32 v44, v136, v52
	v_dot8c_i32_i4_e32 v45, v136, v50
	v_dot8c_i32_i4_e32 v38, v131, v53
	v_dot8c_i32_i4_e32 v39, v131, v51
	v_dot8c_i32_i4_e32 v40, v133, v53
	v_dot8c_i32_i4_e32 v41, v133, v51
	v_dot8c_i32_i4_e32 v42, v135, v53
	v_dot8c_i32_i4_e32 v43, v135, v51
	v_dot8c_i32_i4_e32 v44, v137, v53
	v_dot8c_i32_i4_e32 v45, v137, v51
	v_and_b32_e32 v78, 0xffff, v29
	v_lshrrev_b32_e32 v79, 16, v29
	v_lshl_add_u32 v78, v78, 7, v152
	v_lshl_add_u32 v79, v79, 7, v153
	s_mov_b32 m0, s79
	s_add_i32 s43, s79, 0x400
	global_load_lds_dwordx4 v78, s[50:51]
	s_mov_b32 m0, s43
	s_nop 0
	global_load_lds_dwordx4 v79, s[50:51]
	s_waitcnt vmcnt(8)
	v_add_u32_e32 v54, s99, v59
	v_add_u32_e32 v55, s99, v60
	v_add_u32_e32 v56, s99, v61
	v_add_u32_e32 v57, s99, v62
	ds_read_b64_tr_b4 v[50:51], v160 offset:896
	ds_read_b64_tr_b4 v[52:53], v160 offset:1920
	ds_read_b64_tr_b4 v[130:131], v54
	ds_read_b64_tr_b4 v[132:133], v55
	ds_read_b64_tr_b4 v[134:135], v56
	ds_read_b64_tr_b4 v[136:137], v57
	s_waitcnt lgkmcnt(6)
	v_dot8c_i32_i4_e32 v38, v122, v48
	v_dot8c_i32_i4_e32 v39, v122, v46
	v_dot8c_i32_i4_e32 v40, v124, v48
	v_dot8c_i32_i4_e32 v41, v124, v46
	v_dot8c_i32_i4_e32 v42, v126, v48
	v_dot8c_i32_i4_e32 v43, v126, v46
	v_dot8c_i32_i4_e32 v44, v128, v48
	v_dot8c_i32_i4_e32 v45, v128, v46
	v_dot8c_i32_i4_e32 v38, v123, v49
	v_dot8c_i32_i4_e32 v39, v123, v47
	v_dot8c_i32_i4_e32 v40, v125, v49
	v_dot8c_i32_i4_e32 v41, v125, v47
	v_dot8c_i32_i4_e32 v42, v127, v49
	v_dot8c_i32_i4_e32 v43, v127, v47
	v_dot8c_i32_i4_e32 v44, v129, v49
	v_dot8c_i32_i4_e32 v45, v129, v47
	v_and_b32_e32 v78, 0xffff, v30
	v_lshrrev_b32_e32 v79, 16, v30
	v_lshl_add_u32 v78, v78, 7, v152
	v_lshl_add_u32 v79, v79, 7, v153
	s_mov_b32 m0, s98
	s_add_i32 s43, s98, 0x400
	global_load_lds_dwordx4 v78, s[50:51]
	s_mov_b32 m0, s43
	s_nop 0
	global_load_lds_dwordx4 v79, s[50:51]
	s_waitcnt vmcnt(8)
; #define LAS __attribute__((address_space(3)))
; __device__ __forceinline__ bf16 f2bf(float f) { return (bf16)f2bfu(f); }
; #define TR4(p_) __builtin_amdgcn_ds_read_tr4_b64_v2i32((LAS v2i*)(p_))
; #define CFENCE() asm volatile("" ::: "memory")
; __device__ __forceinline__ void peer_v_tokens(int j, const LAS unsigned short* EL, const LAS unsigned char* AL  , const LAS float* ASC  , const LAS int* SAL  , ...
;     ...
;         for (int st = 0; st < 16; ++st) {
;             const int p = st >> 2, q = st & 3;
;             if (st < 14) VDMA(st + 2, (st + 2) % 3);
;             if (st < 14) asm volatile("s_waitcnt vmcnt(8)" ::: "memory");
;             else if (st == 14) asm volatile("s_waitcnt vmcnt(4)" ::: "memory");
;             else asm volatile("s_waitcnt vmcnt(0)" ::: "memory");
;             if (q == 0) {
; #pragma unroll
;                 for (int r = 0; r < 4; ++r) { accH[r] = 0; accL[r] = 0; } }
; #pragma unroll
;             for (int tp = 0; tp < 2; ++tp) {
;                 const v2i ao = TR4(ATL + (2 * q + tp) * 128 + 8 * s16), ah = TR4(ATL + 1024 + (2 * q + tp) * 128 + 8 * s16);
; #pragma unroll
;                 for (int r = 0; r < 4; ++r) {
;                     const v2i d = TR4(ldsb + BUF[st % 3] + 2048 * tp + roff[r]);
;                     accH[r] = __builtin_amdgcn_sdot8(d.x, ah.x, accH[r], false); accH[r] = __builtin_amdgcn_sdot8(d.y, ah.y, accH[r], false);
;                     accL[r] = __builtin_amdgcn_sdot8(d.x, ao.x, accL[r], false); accL[r] = __builtin_amdgcn_sdot8(d.y, ao.y, accL[r], false);
;                 }
;             }
;             asm volatile("s_waitcnt lgkmcnt(0)" ::: "memory");
;             if (q == 3) {
; #pragma unroll
;                 for (int r = 0; r < 4; ++r) STASH[256 * p + 16 * (grp + 4 * r) + pc] = f2bf(asc * (float)(2 * ((accH[r] << 4) + accL[r]) + sa));
;             }
;         }
;         CFENCE();
;         {
;             float4 v[4]; float ss = 0.f;
; #pragma unroll
;             for (int jq = 0; jq < 4; ++jq) { typedef unsigned u2v __attribute__((ext_vector_type(2))); const u2v pw = *(const LAS u2v*)(STASH + 4 * lane + 256 * jq); const uint2 hw = hv[jq];
	v_add_u32_e32 v54, s76, v59
	v_add_u32_e32 v55, s76, v60
	v_add_u32_e32 v56, s76, v61
	v_add_u32_e32 v57, s76, v62
	ds_read_b64_tr_b4 v[46:47], v160
	ds_read_b64_tr_b4 v[48:49], v160 offset:1024
	ds_read_b64_tr_b4 v[122:123], v54
	ds_read_b64_tr_b4 v[124:125], v55
	ds_read_b64_tr_b4 v[126:127], v56
	ds_read_b64_tr_b4 v[128:129], v57
	s_waitcnt lgkmcnt(6)
	v_dot8c_i32_i4_e32 v38, v130, v52
	v_dot8c_i32_i4_e32 v39, v130, v50
	v_dot8c_i32_i4_e32 v40, v132, v52
	v_dot8c_i32_i4_e32 v41, v132, v50
	v_dot8c_i32_i4_e32 v42, v134, v52
	v_dot8c_i32_i4_e32 v43, v134, v50
	v_dot8c_i32_i4_e32 v44, v136, v52
	v_dot8c_i32_i4_e32 v45, v136, v50
	v_dot8c_i32_i4_e32 v38, v131, v53
	v_dot8c_i32_i4_e32 v39, v131, v51
	v_dot8c_i32_i4_e32 v40, v133, v53
	v_dot8c_i32_i4_e32 v41, v133, v51
	v_dot8c_i32_i4_e32 v42, v135, v53
	v_dot8c_i32_i4_e32 v43, v135, v51
	v_dot8c_i32_i4_e32 v44, v137, v53
	v_dot8c_i32_i4_e32 v45, v137, v51
	s_nop 3
	s_waitcnt lgkmcnt(15)
	v_lshlrev_b32_e32 v38, 5, v38
	v_lshlrev_b32_e32 v39, 1, v39
	v_add3_u32 v38, v39, v229, v38
	v_cvt_f32_i32_e32 v38, v38
	v_mul_f32_e32 v38, v228, v38
	v_lshlrev_b32_e32 v40, 5, v40
	v_lshlrev_b32_e32 v41, 1, v41
	v_add3_u32 v40, v41, v229, v40
	v_cvt_f32_i32_e32 v40, v40
	v_mul_f32_e32 v40, v228, v40
	v_lshlrev_b32_e32 v42, 5, v42
	v_lshlrev_b32_e32 v43, 1, v43
	v_add3_u32 v42, v43, v229, v42
	v_cvt_f32_i32_e32 v42, v42
	v_mul_f32_e32 v42, v228, v42
	v_lshlrev_b32_e32 v44, 5, v44
	v_lshlrev_b32_e32 v45, 1, v45
	v_add3_u32 v44, v45, v229, v44
	v_cvt_f32_i32_e32 v44, v44
	v_mul_f32_e32 v44, v228, v44
	v_cvt_pk_bf16_f32 v180, v38, v40
	v_cvt_pk_bf16_f32 v181, v42, v44
	ds_read_b128 v[252:255], v155 offset:1024
	s_add_i32 s44, s40, 32
	s_ashr_i32 s45, s44, 31
	s_lshl_b64 s[44:45], s[44:45], 12
	v_lshl_add_u64 v[80:81], v[36:37], 0, s[44:45]
	s_waitcnt lgkmcnt(0)
	v_mul_f32_e32 v214, v214, v252
	v_mul_f32_e32 v215, v215, v253
	v_mul_f32_e32 v216, v216, v254
	v_mul_f32_e32 v217, v217, v255
	global_store_dwordx4 v[80:81], v[214:217], off offset:1024 nt
	v_add_u32_e32 v147, 8, v140
	v_and_b32_e32 v146, 15, v147
	v_xor_b32_e32 v146, 8, v146
	v_bfe_u32 v148, v147, 4, 4
	v_mul_lo_u32 v146, v146, s92
	v_mul_lo_u32 v148, v148, s92
	v_mov_b32_e32 v147, v146
	v_mov_b32_e32 v149, v148
	ds_write2st64_b64 v77, v[146:147], v[148:149] offset1:2
	v_add_u32_e32 v138, 0x1800, v74
	ds_read_u8 v139, v138
	v_add_u32_e32 v141, 0x1800, v73
	ds_read_u8 v140, v141
	s_add_i32 s43, s67, 224
	v_mov_b32_e32 v138, s43
	ds_read2st64_b32 v[228:229], v138 offset1:1
	ds_read_b128 v[18:21], v227 offset:12288
	ds_read_b128 v[22:25], v227 offset:12304
	v_add_u32_e32 v150, 0x400000, v63
	v_add_u32_e32 v151, 0x400000, v64
	v_mov_b32_e32 v38, 0
	v_mov_b32_e32 v39, 0
	v_mov_b32_e32 v40, 0
	v_mov_b32_e32 v41, 0
	v_mov_b32_e32 v42, 0
	v_mov_b32_e32 v43, 0
	v_mov_b32_e32 v44, 0
	v_mov_b32_e32 v45, 0
	v_and_b32_e32 v78, 0xffff, v31
	v_lshrrev_b32_e32 v79, 16, v31
	v_lshl_add_u32 v78, v78, 7, v152
	v_lshl_add_u32 v79, v79, 7, v153
	s_mov_b32 m0, s99
	s_add_i32 s43, s99, 0x400
	global_load_lds_dwordx4 v78, s[50:51]
	s_mov_b32 m0, s43
	s_nop 0
	global_load_lds_dwordx4 v79, s[50:51]
	s_waitcnt vmcnt(9)
	v_add_u32_e32 v54, s77, v59
	v_add_u32_e32 v55, s77, v60
	v_add_u32_e32 v56, s77, v61
	v_add_u32_e32 v57, s77, v62
	ds_read_b64_tr_b4 v[50:51], v160 offset:128
	ds_read_b64_tr_b4 v[52:53], v160 offset:1152
	ds_read_b64_tr_b4 v[130:131], v54
	ds_read_b64_tr_b4 v[132:133], v55
	ds_read_b64_tr_b4 v[134:135], v56
	ds_read_b64_tr_b4 v[136:137], v57
	s_waitcnt lgkmcnt(13)
	v_dot8c_i32_i4_e32 v38, v122, v48
	v_dot8c_i32_i4_e32 v39, v122, v46
	v_dot8c_i32_i4_e32 v40, v124, v48
	v_dot8c_i32_i4_e32 v41, v124, v46
	v_dot8c_i32_i4_e32 v42, v126, v48
	v_dot8c_i32_i4_e32 v43, v126, v46
	v_dot8c_i32_i4_e32 v44, v128, v48
	v_dot8c_i32_i4_e32 v45, v128, v46
	v_dot8c_i32_i4_e32 v38, v123, v49
	v_dot8c_i32_i4_e32 v39, v123, v47
	v_dot8c_i32_i4_e32 v40, v125, v49
	v_dot8c_i32_i4_e32 v41, v125, v47
	v_dot8c_i32_i4_e32 v42, v127, v49
	v_dot8c_i32_i4_e32 v43, v127, v47
	v_dot8c_i32_i4_e32 v44, v129, v49
	v_dot8c_i32_i4_e32 v45, v129, v47
	v_and_b32_e32 v78, 0xffff, v32
	v_lshrrev_b32_e32 v79, 16, v32
	v_lshl_add_u32 v78, v78, 7, v152
	v_lshl_add_u32 v79, v79, 7, v153
	s_mov_b32 m0, s76
	s_add_i32 s43, s76, 0x400
	global_load_lds_dwordx4 v78, s[50:51]
	s_mov_b32 m0, s43
	s_nop 0
	global_load_lds_dwordx4 v79, s[50:51]
	s_waitcnt vmcnt(9)
	v_add_u32_e32 v54, s78, v59
	v_add_u32_e32 v55, s78, v60
	v_add_u32_e32 v56, s78, v61
	v_add_u32_e32 v57, s78, v62
	ds_read_b64_tr_b4 v[46:47], v160 offset:256
	ds_read_b64_tr_b4 v[48:49], v160 offset:1280
	ds_read_b64_tr_b4 v[122:123], v54
	ds_read_b64_tr_b4 v[124:125], v55
	ds_read_b64_tr_b4 v[126:127], v56
	ds_read_b64_tr_b4 v[128:129], v57
	s_waitcnt lgkmcnt(6)
	v_dot8c_i32_i4_e32 v38, v130, v52
	v_dot8c_i32_i4_e32 v39, v130, v50
	v_dot8c_i32_i4_e32 v40, v132, v52
	v_dot8c_i32_i4_e32 v41, v132, v50
	v_dot8c_i32_i4_e32 v42, v134, v52
	v_dot8c_i32_i4_e32 v43, v134, v50
	v_dot8c_i32_i4_e32 v44, v136, v52
	v_dot8c_i32_i4_e32 v45, v136, v50
	v_dot8c_i32_i4_e32 v38, v131, v53
	v_dot8c_i32_i4_e32 v39, v131, v51
	v_dot8c_i32_i4_e32 v40, v133, v53
	v_dot8c_i32_i4_e32 v41, v133, v51
	v_dot8c_i32_i4_e32 v42, v135, v53
	v_dot8c_i32_i4_e32 v43, v135, v51
	v_dot8c_i32_i4_e32 v44, v137, v53
	v_dot8c_i32_i4_e32 v45, v137, v51
	ds_write_b16 v65, v170
	ds_write_b16_d16_hi v65, v170 offset:128
	ds_write_b16 v65, v171 offset:256
	ds_write_b16_d16_hi v65, v171 offset:384
	ds_write_b16 v65, v172 offset:512
	ds_write_b16_d16_hi v65, v172 offset:640
	ds_write_b16 v65, v173 offset:768
	ds_write_b16_d16_hi v65, v173 offset:896
	ds_write_b16 v65, v174 offset:1024
	ds_write_b16_d16_hi v65, v174 offset:1152
	ds_write_b16 v65, v175 offset:1280
	ds_write_b16_d16_hi v65, v175 offset:1408
	ds_write_b16 v65, v176 offset:1536
	ds_write_b16_d16_hi v65, v176 offset:1664
	ds_write_b16 v65, v177 offset:1792
	ds_write_b16_d16_hi v65, v177 offset:1920
	ds_read_b64 v[202:203], v154
	ds_read_b64 v[204:205], v154 offset:512
	ds_read_b64 v[206:207], v154 offset:1024
	ds_read_b64 v[208:209], v154 offset:1536
	v_and_b32_e32 v78, 0xffff, v33
	v_lshrrev_b32_e32 v79, 16, v33
	v_lshl_add_u32 v78, v78, 7, v152
	v_lshl_add_u32 v79, v79, 7, v153
	s_mov_b32 m0, s77
	s_add_i32 s43, s77, 0x400
	global_load_lds_dwordx4 v78, s[50:51]
	s_mov_b32 m0, s43
	s_nop 0
	global_load_lds_dwordx4 v79, s[50:51]
	s_waitcnt vmcnt(9)
; #define TR4(p_) __builtin_amdgcn_ds_read_tr4_b64_v2i32((LAS v2i*)(p_))
; #define VDMA(st_, k_) do { _Pragma("unroll") for (int i_ = 0; i_ < 4; ++i_) { \
;         const unsigned off_ = (unsigned)((st_) >> 2) * (16384u * 128u) + (PE_ID(E, 4 * ((st_) & 3) + i_) << 7) + ((i_ & 1) ? cx1 : cx0); \
;         __builtin_amdgcn_global_load_lds((const unsigned*)(V4 + off_), (LAS unsigned*)(ldsb + BUF[k_] + 1024 * i_), 16, 0, 0); } } while (0)
; __device__ __forceinline__ void peer_v_tokens(int j, const LAS unsigned short* EL, const LAS unsigned char* AL  , const LAS float* ASC  , const LAS int* SAL  , ...
;     ...
;         for (int st = 0; st < 16; ++st) {
;             const int p = st >> 2, q = st & 3;
;             if (st < 14) VDMA(st + 2, (st + 2) % 3);
;             if (st < 14) asm volatile("s_waitcnt vmcnt(8)" ::: "memory");
;             else if (st == 14) asm volatile("s_waitcnt vmcnt(4)" ::: "memory");
;             else asm volatile("s_waitcnt vmcnt(0)" ::: "memory");
;             if (q == 0) {
; #pragma unroll
;                 for (int r = 0; r < 4; ++r) { accH[r] = 0; accL[r] = 0; } }
; #pragma unroll
;             for (int tp = 0; tp < 2; ++tp) {
;                 const v2i ao = TR4(ATL + (2 * q + tp) * 128 + 8 * s16), ah = TR4(ATL + 1024 + (2 * q + tp) * 128 + 8 * s16);
; #pragma unroll
;                 for (int r = 0; r < 4; ++r) {
;                     const v2i d = TR4(ldsb + BUF[st % 3] + 2048 * tp + roff[r]);
;                     accH[r] = __builtin_amdgcn_sdot8(d.x, ah.x, accH[r], false); accH[r] = __builtin_amdgcn_sdot8(d.y, ah.y, accH[r], false);
;                     accL[r] = __builtin_amdgcn_sdot8(d.x, ao.x, accL[r], false); accL[r] = __builtin_amdgcn_sdot8(d.y, ao.y, accL[r], false);
;                 }
;             }
	v_add_u32_e32 v54, s79, v59
	v_add_u32_e32 v55, s79, v60
	v_add_u32_e32 v56, s79, v61
	v_add_u32_e32 v57, s79, v62
	ds_read_b64_tr_b4 v[50:51], v160 offset:384
	ds_read_b64_tr_b4 v[52:53], v160 offset:1408
	ds_read_b64_tr_b4 v[130:131], v54
	ds_read_b64_tr_b4 v[132:133], v55
	ds_read_b64_tr_b4 v[134:135], v56
	ds_read_b64_tr_b4 v[136:137], v57
	s_waitcnt lgkmcnt(15)
	v_dot8c_i32_i4_e32 v38, v122, v48
	v_dot8c_i32_i4_e32 v39, v122, v46
	v_dot8c_i32_i4_e32 v40, v124, v48
	v_dot8c_i32_i4_e32 v41, v124, v46
	v_dot8c_i32_i4_e32 v42, v126, v48
	v_dot8c_i32_i4_e32 v43, v126, v46
	v_dot8c_i32_i4_e32 v44, v128, v48
	v_dot8c_i32_i4_e32 v45, v128, v46
	v_dot8c_i32_i4_e32 v38, v123, v49
	v_dot8c_i32_i4_e32 v39, v123, v47
	v_dot8c_i32_i4_e32 v40, v125, v49
	v_dot8c_i32_i4_e32 v41, v125, v47
	v_dot8c_i32_i4_e32 v42, v127, v49
	v_dot8c_i32_i4_e32 v43, v127, v47
	v_dot8c_i32_i4_e32 v44, v129, v49
	v_dot8c_i32_i4_e32 v45, v129, v47
	s_waitcnt lgkmcnt(15)
	v_and_b32_e32 v78, 0xffff, v18
	v_lshrrev_b32_e32 v79, 16, v18
	v_lshl_add_u32 v78, v78, 7, v150
	v_lshl_add_u32 v79, v79, 7, v151
	s_mov_b32 m0, s78
	s_add_i32 s43, s78, 0x400
	global_load_lds_dwordx4 v78, s[50:51]
	s_mov_b32 m0, s43
	s_nop 0
	global_load_lds_dwordx4 v79, s[50:51]
	s_waitcnt vmcnt(9)
	v_add_u32_e32 v54, s98, v59
	v_add_u32_e32 v55, s98, v60
	v_add_u32_e32 v56, s98, v61
	v_add_u32_e32 v57, s98, v62
	ds_read_b64_tr_b4 v[46:47], v160 offset:512
	ds_read_b64_tr_b4 v[48:49], v160 offset:1536
	ds_read_b64_tr_b4 v[122:123], v54
	ds_read_b64_tr_b4 v[124:125], v55
	ds_read_b64_tr_b4 v[126:127], v56
	ds_read_b64_tr_b4 v[128:129], v57
	s_waitcnt lgkmcnt(6)
	v_dot8c_i32_i4_e32 v38, v130, v52
	v_dot8c_i32_i4_e32 v39, v130, v50
	v_dot8c_i32_i4_e32 v40, v132, v52
	v_dot8c_i32_i4_e32 v41, v132, v50
	v_dot8c_i32_i4_e32 v42, v134, v52
	v_dot8c_i32_i4_e32 v43, v134, v50
	v_dot8c_i32_i4_e32 v44, v136, v52
	v_dot8c_i32_i4_e32 v45, v136, v50
	v_dot8c_i32_i4_e32 v38, v131, v53
	v_dot8c_i32_i4_e32 v39, v131, v51
	v_dot8c_i32_i4_e32 v40, v133, v53
	v_dot8c_i32_i4_e32 v41, v133, v51
	v_dot8c_i32_i4_e32 v42, v135, v53
	v_dot8c_i32_i4_e32 v43, v135, v51
	v_dot8c_i32_i4_e32 v44, v137, v53
	v_dot8c_i32_i4_e32 v45, v137, v51
	v_and_b32_e32 v78, 0xffff, v19
	v_lshrrev_b32_e32 v79, 16, v19
	v_lshl_add_u32 v78, v78, 7, v150
	v_lshl_add_u32 v79, v79, 7, v151
	s_mov_b32 m0, s79
	s_add_i32 s43, s79, 0x400
	global_load_lds_dwordx4 v78, s[50:51]
	s_mov_b32 m0, s43
	s_nop 0
	global_load_lds_dwordx4 v79, s[50:51]
	s_waitcnt vmcnt(8)
	v_add_u32_e32 v54, s99, v59
	v_add_u32_e32 v55, s99, v60
	v_add_u32_e32 v56, s99, v61
	v_add_u32_e32 v57, s99, v62
	ds_read_b64_tr_b4 v[50:51], v160 offset:640
	ds_read_b64_tr_b4 v[52:53], v160 offset:1664
	ds_read_b64_tr_b4 v[130:131], v54
	ds_read_b64_tr_b4 v[132:133], v55
	ds_read_b64_tr_b4 v[134:135], v56
	ds_read_b64_tr_b4 v[136:137], v57
	s_waitcnt lgkmcnt(6)
	v_dot8c_i32_i4_e32 v38, v122, v48
	v_dot8c_i32_i4_e32 v39, v122, v46
	v_dot8c_i32_i4_e32 v40, v124, v48
	v_dot8c_i32_i4_e32 v41, v124, v46
	v_dot8c_i32_i4_e32 v42, v126, v48
	v_dot8c_i32_i4_e32 v43, v126, v46
	v_dot8c_i32_i4_e32 v44, v128, v48
	v_dot8c_i32_i4_e32 v45, v128, v46
	v_dot8c_i32_i4_e32 v38, v123, v49
	v_dot8c_i32_i4_e32 v39, v123, v47
	v_dot8c_i32_i4_e32 v40, v125, v49
	v_dot8c_i32_i4_e32 v41, v125, v47
	v_dot8c_i32_i4_e32 v42, v127, v49
	v_dot8c_i32_i4_e32 v43, v127, v47
	v_dot8c_i32_i4_e32 v44, v129, v49
	v_dot8c_i32_i4_e32 v45, v129, v47
	s_waitcnt lgkmcnt(15)
	v_add_u32_e32 v143, 8, v139
	v_and_b32_e32 v142, 15, v143
	v_xor_b32_e32 v142, 8, v142
	v_bfe_u32 v144, v143, 4, 4
	v_mul_lo_u32 v142, v142, s92
	v_mul_lo_u32 v144, v144, s92
	v_mov_b32_e32 v143, v142
	v_mov_b32_e32 v145, v144
	ds_write2st64_b64 v159, v[142:143], v[144:145] offset1:2
	v_and_b32_e32 v78, 0xffff, v20
	v_lshrrev_b32_e32 v79, 16, v20
	v_lshl_add_u32 v78, v78, 7, v150
	v_lshl_add_u32 v79, v79, 7, v151
	s_mov_b32 m0, s98
	s_add_i32 s43, s98, 0x400
	global_load_lds_dwordx4 v78, s[50:51]
	s_mov_b32 m0, s43
	s_nop 0
	global_load_lds_dwordx4 v79, s[50:51]
	s_waitcnt vmcnt(8)
	v_add_u32_e32 v54, s76, v59
	v_add_u32_e32 v55, s76, v60
	v_add_u32_e32 v56, s76, v61
	v_add_u32_e32 v57, s76, v62
	ds_read_b64_tr_b4 v[46:47], v160 offset:768
	ds_read_b64_tr_b4 v[48:49], v160 offset:1792
	ds_read_b64_tr_b4 v[122:123], v54
	ds_read_b64_tr_b4 v[124:125], v55
	ds_read_b64_tr_b4 v[126:127], v56
	ds_read_b64_tr_b4 v[128:129], v57
	s_waitcnt lgkmcnt(7)
	v_dot8c_i32_i4_e32 v38, v130, v52
	v_dot8c_i32_i4_e32 v39, v130, v50
	v_dot8c_i32_i4_e32 v40, v132, v52
	v_dot8c_i32_i4_e32 v41, v132, v50
	v_dot8c_i32_i4_e32 v42, v134, v52
	v_dot8c_i32_i4_e32 v43, v134, v50
	v_dot8c_i32_i4_e32 v44, v136, v52
	v_dot8c_i32_i4_e32 v45, v136, v50
	v_dot8c_i32_i4_e32 v38, v131, v53
	v_dot8c_i32_i4_e32 v39, v131, v51
	v_dot8c_i32_i4_e32 v40, v133, v53
	v_dot8c_i32_i4_e32 v41, v133, v51
	v_dot8c_i32_i4_e32 v42, v135, v53
	v_dot8c_i32_i4_e32 v43, v135, v51
	v_dot8c_i32_i4_e32 v44, v137, v53
	v_dot8c_i32_i4_e32 v45, v137, v51
	v_and_b32_e32 v78, 0xffff, v21
	v_lshrrev_b32_e32 v79, 16, v21
	v_lshl_add_u32 v78, v78, 7, v150
	v_lshl_add_u32 v79, v79, 7, v151
	s_mov_b32 m0, s99
	s_add_i32 s43, s99, 0x400
	global_load_lds_dwordx4 v78, s[50:51]
	s_mov_b32 m0, s43
	s_nop 0
	global_load_lds_dwordx4 v79, s[50:51]
	s_waitcnt vmcnt(8)
	v_add_u32_e32 v54, s77, v59
	v_add_u32_e32 v55, s77, v60
	v_add_u32_e32 v56, s77, v61
	v_add_u32_e32 v57, s77, v62
	ds_read_b64_tr_b4 v[50:51], v160 offset:896
	ds_read_b64_tr_b4 v[52:53], v160 offset:1920
	ds_read_b64_tr_b4 v[130:131], v54
	ds_read_b64_tr_b4 v[132:133], v55
	ds_read_b64_tr_b4 v[134:135], v56
	ds_read_b64_tr_b4 v[136:137], v57
	s_waitcnt lgkmcnt(6)
; __device__ __forceinline__ bf16 f2bf(float f) { return (bf16)f2bfu(f); }
; #define TR4(p_) __builtin_amdgcn_ds_read_tr4_b64_v2i32((LAS v2i*)(p_))
; __device__ __forceinline__ void peer_v_tokens(int j, const LAS unsigned short* EL, const LAS unsigned char* AL  , const LAS float* ASC  , const LAS int* SAL  , ...
;     ...
;         for (int st = 0; st < 16; ++st) {
;             const int p = st >> 2, q = st & 3;
;             if (st < 14) VDMA(st + 2, (st + 2) % 3);
;             if (st < 14) asm volatile("s_waitcnt vmcnt(8)" ::: "memory");
;             else if (st == 14) asm volatile("s_waitcnt vmcnt(4)" ::: "memory");
;             else asm volatile("s_waitcnt vmcnt(0)" ::: "memory");
;             if (q == 0) {
; #pragma unroll
;                 for (int r = 0; r < 4; ++r) { accH[r] = 0; accL[r] = 0; } }
; #pragma unroll
;             for (int tp = 0; tp < 2; ++tp) {
;                 const v2i ao = TR4(ATL + (2 * q + tp) * 128 + 8 * s16), ah = TR4(ATL + 1024 + (2 * q + tp) * 128 + 8 * s16);
; #pragma unroll
;                 for (int r = 0; r < 4; ++r) {
;                     const v2i d = TR4(ldsb + BUF[st % 3] + 2048 * tp + roff[r]);
;                     accH[r] = __builtin_amdgcn_sdot8(d.x, ah.x, accH[r], false); accH[r] = __builtin_amdgcn_sdot8(d.y, ah.y, accH[r], false);
;                     accL[r] = __builtin_amdgcn_sdot8(d.x, ao.x, accL[r], false); accL[r] = __builtin_amdgcn_sdot8(d.y, ao.y, accL[r], false);
;                 }
;             }
;             asm volatile("s_waitcnt lgkmcnt(0)" ::: "memory");
;             if (q == 3) {
; #pragma unroll
;                 for (int r = 0; r < 4; ++r) STASH[256 * p + 16 * (grp + 4 * r) + pc] = f2bf(asc * (float)(2 * ((accH[r] << 4) + accL[r]) + sa));
;             }
;     ...
;             float4* op = (float4*)(outp + (size_t)t * D) + lane;
; #pragma unroll
;             for (int jq = 0; jq < 4; ++jq) { typedef float f4v __attribute__((ext_vector_type(4))); f4v o4; o4.x = v[jq].x * r3 * gv[jq].x; o4.y = v[jq].y * r3 * gv[jq].y; o4.z = v[jq].z * r3 * gv[jq].z; o4.w = v[jq].w * r3 * gv[jq].w;
;                 __builtin_nontemporal_store(o4, (f4v*)op + 64 * jq); }
	v_dot8c_i32_i4_e32 v38, v122, v48
	v_dot8c_i32_i4_e32 v39, v122, v46
	v_dot8c_i32_i4_e32 v40, v124, v48
	v_dot8c_i32_i4_e32 v41, v124, v46
	v_dot8c_i32_i4_e32 v42, v126, v48
	v_dot8c_i32_i4_e32 v43, v126, v46
	v_dot8c_i32_i4_e32 v44, v128, v48
	v_dot8c_i32_i4_e32 v45, v128, v46
	v_dot8c_i32_i4_e32 v38, v123, v49
	v_dot8c_i32_i4_e32 v39, v123, v47
	v_dot8c_i32_i4_e32 v40, v125, v49
	v_dot8c_i32_i4_e32 v41, v125, v47
	v_dot8c_i32_i4_e32 v42, v127, v49
	v_dot8c_i32_i4_e32 v43, v127, v47
	v_dot8c_i32_i4_e32 v44, v129, v49
	v_dot8c_i32_i4_e32 v45, v129, v47
	v_and_b32_e32 v78, 0xffff, v22
	v_lshrrev_b32_e32 v79, 16, v22
	v_lshl_add_u32 v78, v78, 7, v150
	v_lshl_add_u32 v79, v79, 7, v151
	s_mov_b32 m0, s76
	s_add_i32 s43, s76, 0x400
	global_load_lds_dwordx4 v78, s[50:51]
	s_mov_b32 m0, s43
	s_nop 0
	global_load_lds_dwordx4 v79, s[50:51]
	s_waitcnt vmcnt(8)
	v_add_u32_e32 v54, s78, v59
	v_add_u32_e32 v55, s78, v60
	v_add_u32_e32 v56, s78, v61
	v_add_u32_e32 v57, s78, v62
	ds_read_b64_tr_b4 v[46:47], v160
	ds_read_b64_tr_b4 v[48:49], v160 offset:1024
	ds_read_b64_tr_b4 v[122:123], v54
	ds_read_b64_tr_b4 v[124:125], v55
	ds_read_b64_tr_b4 v[126:127], v56
	ds_read_b64_tr_b4 v[128:129], v57
	s_waitcnt lgkmcnt(6)
	v_dot8c_i32_i4_e32 v38, v130, v52
	v_dot8c_i32_i4_e32 v39, v130, v50
	v_dot8c_i32_i4_e32 v40, v132, v52
	v_dot8c_i32_i4_e32 v41, v132, v50
	v_dot8c_i32_i4_e32 v42, v134, v52
	v_dot8c_i32_i4_e32 v43, v134, v50
	v_dot8c_i32_i4_e32 v44, v136, v52
	v_dot8c_i32_i4_e32 v45, v136, v50
	v_dot8c_i32_i4_e32 v38, v131, v53
	v_dot8c_i32_i4_e32 v39, v131, v51
	v_dot8c_i32_i4_e32 v40, v133, v53
	v_dot8c_i32_i4_e32 v41, v133, v51
	v_dot8c_i32_i4_e32 v42, v135, v53
	v_dot8c_i32_i4_e32 v43, v135, v51
	v_dot8c_i32_i4_e32 v44, v137, v53
	v_dot8c_i32_i4_e32 v45, v137, v51
	s_nop 3
	s_waitcnt lgkmcnt(15)
	v_lshlrev_b32_e32 v38, 5, v38
	v_lshlrev_b32_e32 v39, 1, v39
	v_add3_u32 v38, v39, v229, v38
	v_cvt_f32_i32_e32 v38, v38
	v_mul_f32_e32 v38, v228, v38
	v_lshlrev_b32_e32 v40, 5, v40
	v_lshlrev_b32_e32 v41, 1, v41
	v_add3_u32 v40, v41, v229, v40
	v_cvt_f32_i32_e32 v40, v40
	v_mul_f32_e32 v40, v228, v40
	v_lshlrev_b32_e32 v42, 5, v42
	v_lshlrev_b32_e32 v43, 1, v43
	v_add3_u32 v42, v43, v229, v42
	v_cvt_f32_i32_e32 v42, v42
	v_mul_f32_e32 v42, v228, v42
	v_lshlrev_b32_e32 v44, 5, v44
	v_lshlrev_b32_e32 v45, 1, v45
	v_add3_u32 v44, v45, v229, v44
	v_cvt_f32_i32_e32 v44, v44
	v_mul_f32_e32 v44, v228, v44
	v_cvt_pk_bf16_f32 v188, v38, v40
	v_cvt_pk_bf16_f32 v189, v42, v44
	ds_read_b128 v[252:255], v156
	s_add_i32 s44, s40, 32
	s_ashr_i32 s45, s44, 31
	s_lshl_b64 s[44:45], s[44:45], 12
	v_lshl_add_u64 v[80:81], v[36:37], 0, s[44:45]
	s_waitcnt lgkmcnt(0)
	v_mul_f32_e32 v218, v218, v252
	v_mul_f32_e32 v219, v219, v253
	v_mul_f32_e32 v220, v220, v254
	v_mul_f32_e32 v221, v221, v255
	global_store_dwordx4 v[80:81], v[218:221], off offset:2048 nt
	v_add_u32_e32 v147, 8, v140
	v_and_b32_e32 v146, 15, v147
	v_xor_b32_e32 v146, 8, v146
	v_bfe_u32 v148, v147, 4, 4
	v_mul_lo_u32 v146, v146, s92
	v_mul_lo_u32 v148, v148, s92
	v_mov_b32_e32 v147, v146
	v_mov_b32_e32 v149, v148
	ds_write2st64_b64 v77, v[146:147], v[148:149] offset1:2
	v_add_u32_e32 v138, 0x1c00, v74
	ds_read_u8 v139, v138
	v_add_u32_e32 v141, 0x1c00, v73
	ds_read_u8 v140, v141
	s_add_i32 s43, s67, 192
	v_mov_b32_e32 v138, s43
	ds_read2st64_b32 v[228:229], v138 offset1:1
	ds_read_b128 v[26:29], v227 offset:14336
	ds_read_b128 v[30:33], v227 offset:14352
	v_mov_b32_e32 v38, 0
	v_mov_b32_e32 v39, 0
	v_mov_b32_e32 v40, 0
	v_mov_b32_e32 v41, 0
	v_mov_b32_e32 v42, 0
	v_mov_b32_e32 v43, 0
	v_mov_b32_e32 v44, 0
	v_mov_b32_e32 v45, 0
	v_and_b32_e32 v78, 0xffff, v23
	v_lshrrev_b32_e32 v79, 16, v23
	v_lshl_add_u32 v78, v78, 7, v150
	v_lshl_add_u32 v79, v79, 7, v151
	s_mov_b32 m0, s77
	s_add_i32 s43, s77, 0x400
	global_load_lds_dwordx4 v78, s[50:51]
	s_mov_b32 m0, s43
	s_nop 0
	global_load_lds_dwordx4 v79, s[50:51]
	s_waitcnt vmcnt(9)
	v_add_u32_e32 v54, s79, v59
	v_add_u32_e32 v55, s79, v60
	v_add_u32_e32 v56, s79, v61
	v_add_u32_e32 v57, s79, v62
	ds_read_b64_tr_b4 v[50:51], v160 offset:128
	ds_read_b64_tr_b4 v[52:53], v160 offset:1152
	ds_read_b64_tr_b4 v[130:131], v54
	ds_read_b64_tr_b4 v[132:133], v55
	ds_read_b64_tr_b4 v[134:135], v56
	ds_read_b64_tr_b4 v[136:137], v57
	s_waitcnt lgkmcnt(13)
	s_waitcnt vmcnt(36) lgkmcnt(15)
; #define LAS __attribute__((address_space(3)))
; #define TR4(p_) __builtin_amdgcn_ds_read_tr4_b64_v2i32((LAS v2i*)(p_))
; __device__ __forceinline__ void peer_v_tokens(int j, const LAS unsigned short* EL, const LAS unsigned char* AL  , const LAS float* ASC  , const LAS int* SAL  , ...
;     ...
;             for (int tp = 0; tp < 2; ++tp) {
;                 const v2i ao = TR4(ATL + (2 * q + tp) * 128 + 8 * s16), ah = TR4(ATL + 1024 + (2 * q + tp) * 128 + 8 * s16);
; #pragma unroll
;                 for (int r = 0; r < 4; ++r) {
;                     const v2i d = TR4(ldsb + BUF[st % 3] + 2048 * tp + roff[r]);
;                     accH[r] = __builtin_amdgcn_sdot8(d.x, ah.x, accH[r], false); accH[r] = __builtin_amdgcn_sdot8(d.y, ah.y, accH[r], false);
;                     accL[r] = __builtin_amdgcn_sdot8(d.x, ao.x, accL[r], false); accL[r] = __builtin_amdgcn_sdot8(d.y, ao.y, accL[r], false);
;                 }
;             }
;     ...
;         {
;             float4 v[4]; float ss = 0.f;
; #pragma unroll
;             for (int jq = 0; jq < 4; ++jq) { typedef unsigned u2v __attribute__((ext_vector_type(2))); const u2v pw = *(const LAS u2v*)(STASH + 4 * lane + 256 * jq); const uint2 hw = hv[jq];
;                 v[jq] = make_float4(__uint_as_float(hw.x << 16) + __uint_as_float(pw.x << 16), __uint_as_float(hw.x & 0xffff0000u) + __uint_as_float(pw.x & 0xffff0000u),
;                                     __uint_as_float(hw.y << 16) + __uint_as_float(pw.y << 16), __uint_as_float(hw.y & 0xffff0000u) + __uint_as_float(pw.y & 0xffff0000u));
;                 ss += v[jq].x * v[jq].x + v[jq].y * v[jq].y + v[jq].z * v[jq].z + v[jq].w * v[jq].w; }
;             ss = wave_sum(ss);
;             const float r3 = rsqrtf(ss * (1.f / D) + EPS);
	v_lshlrev_b32_e32 v236, 16, v194
	v_and_b32_e32 v237, 0xffff0000, v194
	v_lshlrev_b32_e32 v142, 16, v202
	v_and_b32_e32 v143, 0xffff0000, v202
	v_add_f32_e32 v236, v236, v142
	v_add_f32_e32 v237, v237, v143
	v_lshlrev_b32_e32 v238, 16, v195
	v_and_b32_e32 v239, 0xffff0000, v195
	v_lshlrev_b32_e32 v142, 16, v203
	v_and_b32_e32 v143, 0xffff0000, v203
	v_add_f32_e32 v238, v238, v142
	v_add_f32_e32 v239, v239, v143
	v_lshlrev_b32_e32 v240, 16, v196
	v_and_b32_e32 v241, 0xffff0000, v196
	v_lshlrev_b32_e32 v142, 16, v204
	v_and_b32_e32 v143, 0xffff0000, v204
	v_add_f32_e32 v240, v240, v142
	v_add_f32_e32 v241, v241, v143
	v_lshlrev_b32_e32 v242, 16, v197
	v_and_b32_e32 v243, 0xffff0000, v197
	v_lshlrev_b32_e32 v142, 16, v205
	v_and_b32_e32 v143, 0xffff0000, v205
	v_add_f32_e32 v242, v242, v142
	v_add_f32_e32 v243, v243, v143
	v_lshlrev_b32_e32 v244, 16, v198
	v_and_b32_e32 v245, 0xffff0000, v198
	v_lshlrev_b32_e32 v142, 16, v206
	v_and_b32_e32 v143, 0xffff0000, v206
	v_add_f32_e32 v244, v244, v142
	v_add_f32_e32 v245, v245, v143
	v_lshlrev_b32_e32 v246, 16, v199
	v_and_b32_e32 v247, 0xffff0000, v199
	v_lshlrev_b32_e32 v142, 16, v207
	v_and_b32_e32 v143, 0xffff0000, v207
	v_add_f32_e32 v246, v246, v142
	v_add_f32_e32 v247, v247, v143
	v_lshlrev_b32_e32 v248, 16, v200
	v_and_b32_e32 v249, 0xffff0000, v200
	v_lshlrev_b32_e32 v142, 16, v208
	v_and_b32_e32 v143, 0xffff0000, v208
	v_add_f32_e32 v248, v248, v142
	v_add_f32_e32 v249, v249, v143
	v_lshlrev_b32_e32 v250, 16, v201
	v_and_b32_e32 v251, 0xffff0000, v201
	v_lshlrev_b32_e32 v142, 16, v209
	v_and_b32_e32 v143, 0xffff0000, v209
	v_add_f32_e32 v250, v250, v142
	v_add_f32_e32 v251, v251, v143
	v_mov_b32_e32 v144, 0
	v_mul_f32_e32 v145, v236, v236
	v_fmac_f32_e32 v145, v237, v237
	v_fmac_f32_e32 v145, v238, v238
	v_fmac_f32_e32 v145, v239, v239
	v_add_f32_e32 v144, v144, v145
	v_mul_f32_e32 v145, v240, v240
	v_fmac_f32_e32 v145, v241, v241
	v_fmac_f32_e32 v145, v242, v242
	v_fmac_f32_e32 v145, v243, v243
	v_add_f32_e32 v144, v144, v145
	v_mul_f32_e32 v145, v244, v244
	v_fmac_f32_e32 v145, v245, v245
	v_fmac_f32_e32 v145, v246, v246
	v_fmac_f32_e32 v145, v247, v247
	v_add_f32_e32 v144, v144, v145
	v_mul_f32_e32 v145, v248, v248
	v_fmac_f32_e32 v145, v249, v249
	v_fmac_f32_e32 v145, v250, v250
	v_fmac_f32_e32 v145, v251, v251
	v_add_f32_e32 v144, v144, v145
	s_nop 1
	v_add_f32_dpp v144, v144, v144 quad_perm:[1,0,3,2] row_mask:0xf bank_mask:0xf bound_ctrl:1
	s_nop 1
	v_add_f32_dpp v144, v144, v144 quad_perm:[2,3,0,1] row_mask:0xf bank_mask:0xf bound_ctrl:1
	s_nop 1
	v_add_f32_dpp v144, v144, v144 row_half_mirror row_mask:0xf bank_mask:0xf bound_ctrl:1
	s_nop 1
	v_add_f32_dpp v144, v144, v144 row_mirror row_mask:0xf bank_mask:0xf bound_ctrl:1
	s_nop 1
	v_readlane_b32 s10, v144, 0
	v_readlane_b32 s11, v144, 16
	v_readlane_b32 s14, v144, 32
	v_readlane_b32 s15, v144, 48
	s_nop 3
	v_mov_b32_e32 v144, s11
	v_mov_b32_e32 v145, s15
	v_add_f32_e32 v144, s10, v144
	v_add_f32_e32 v145, s14, v145
	v_add_f32_e32 v144, v144, v145
	v_fmamk_f32 v144, v144, 0x3a800000, v111
	v_rsq_f32_e32 v144, v144
	s_nop 0
	v_mul_f32_e32 v236, v236, v144
	v_mul_f32_e32 v237, v237, v144
	v_mul_f32_e32 v238, v238, v144
	v_mul_f32_e32 v239, v239, v144
	v_mul_f32_e32 v240, v240, v144
	v_mul_f32_e32 v241, v241, v144
	v_mul_f32_e32 v242, v242, v144
	v_mul_f32_e32 v243, v243, v144
	v_mul_f32_e32 v244, v244, v144
	v_mul_f32_e32 v245, v245, v144
	v_mul_f32_e32 v246, v246, v144
	v_mul_f32_e32 v247, v247, v144
	v_mul_f32_e32 v248, v248, v144
	v_mul_f32_e32 v249, v249, v144
	v_mul_f32_e32 v250, v250, v144
	v_mul_f32_e32 v251, v251, v144
	v_dot8c_i32_i4_e32 v38, v122, v48
	v_dot8c_i32_i4_e32 v39, v122, v46
	v_dot8c_i32_i4_e32 v40, v124, v48
	v_dot8c_i32_i4_e32 v41, v124, v46
	v_dot8c_i32_i4_e32 v42, v126, v48
	v_dot8c_i32_i4_e32 v43, v126, v46
	v_dot8c_i32_i4_e32 v44, v128, v48
	v_dot8c_i32_i4_e32 v45, v128, v46
	v_dot8c_i32_i4_e32 v38, v123, v49
	v_dot8c_i32_i4_e32 v39, v123, v47
	v_dot8c_i32_i4_e32 v40, v125, v49
	v_dot8c_i32_i4_e32 v41, v125, v47
	v_dot8c_i32_i4_e32 v42, v127, v49
	v_dot8c_i32_i4_e32 v43, v127, v47
	v_dot8c_i32_i4_e32 v44, v129, v49
	v_dot8c_i32_i4_e32 v45, v129, v47
	v_and_b32_e32 v78, 0xffff, v24
	v_lshrrev_b32_e32 v79, 16, v24
	v_lshl_add_u32 v78, v78, 7, v150
	v_lshl_add_u32 v79, v79, 7, v151
	s_mov_b32 m0, s78
	s_add_i32 s43, s78, 0x400
	global_load_lds_dwordx4 v78, s[50:51]
	s_mov_b32 m0, s43
	s_nop 0
	global_load_lds_dwordx4 v79, s[50:51]
	s_waitcnt vmcnt(9)
	v_add_u32_e32 v54, s98, v59
	v_add_u32_e32 v55, s98, v60
	v_add_u32_e32 v56, s98, v61
	v_add_u32_e32 v57, s98, v62
	ds_read_b64_tr_b4 v[46:47], v160 offset:256
	ds_read_b64_tr_b4 v[48:49], v160 offset:1280
	ds_read_b64_tr_b4 v[122:123], v54
	ds_read_b64_tr_b4 v[124:125], v55
	ds_read_b64_tr_b4 v[126:127], v56
	ds_read_b64_tr_b4 v[128:129], v57
	s_waitcnt lgkmcnt(6)
	v_dot8c_i32_i4_e32 v38, v130, v52
	v_dot8c_i32_i4_e32 v39, v130, v50
	v_dot8c_i32_i4_e32 v40, v132, v52
	v_dot8c_i32_i4_e32 v41, v132, v50
	v_dot8c_i32_i4_e32 v42, v134, v52
	v_dot8c_i32_i4_e32 v43, v134, v50
	v_dot8c_i32_i4_e32 v44, v136, v52
	v_dot8c_i32_i4_e32 v45, v136, v50
	v_dot8c_i32_i4_e32 v38, v131, v53
	v_dot8c_i32_i4_e32 v39, v131, v51
	v_dot8c_i32_i4_e32 v40, v133, v53
	v_dot8c_i32_i4_e32 v41, v133, v51
	v_dot8c_i32_i4_e32 v42, v135, v53
	v_dot8c_i32_i4_e32 v43, v135, v51
	v_dot8c_i32_i4_e32 v44, v137, v53
	v_dot8c_i32_i4_e32 v45, v137, v51
	v_and_b32_e32 v78, 0xffff, v25
	v_lshrrev_b32_e32 v79, 16, v25
	v_lshl_add_u32 v78, v78, 7, v150
	v_lshl_add_u32 v79, v79, 7, v151
	s_mov_b32 m0, s79
	s_add_i32 s43, s79, 0x400
	global_load_lds_dwordx4 v78, s[50:51]
	s_mov_b32 m0, s43
	s_nop 0
	global_load_lds_dwordx4 v79, s[50:51]
	s_waitcnt vmcnt(9)
; #define TR4(p_) __builtin_amdgcn_ds_read_tr4_b64_v2i32((LAS v2i*)(p_))
; #define VDMA(st_, k_) do { _Pragma("unroll") for (int i_ = 0; i_ < 4; ++i_) { \
;         const unsigned off_ = (unsigned)((st_) >> 2) * (16384u * 128u) + (PE_ID(E, 4 * ((st_) & 3) + i_) << 7) + ((i_ & 1) ? cx1 : cx0); \
;         __builtin_amdgcn_global_load_lds((const unsigned*)(V4 + off_), (LAS unsigned*)(ldsb + BUF[k_] + 1024 * i_), 16, 0, 0); } } while (0)
; __device__ __forceinline__ void peer_v_tokens(int j, const LAS unsigned short* EL, const LAS unsigned char* AL  , const LAS float* ASC  , const LAS int* SAL  , ...
;     ...
;         for (int st = 0; st < 16; ++st) {
;             const int p = st >> 2, q = st & 3;
;             if (st < 14) VDMA(st + 2, (st + 2) % 3);
;             if (st < 14) asm volatile("s_waitcnt vmcnt(8)" ::: "memory");
;             else if (st == 14) asm volatile("s_waitcnt vmcnt(4)" ::: "memory");
;             else asm volatile("s_waitcnt vmcnt(0)" ::: "memory");
;             if (q == 0) {
; #pragma unroll
;                 for (int r = 0; r < 4; ++r) { accH[r] = 0; accL[r] = 0; } }
; #pragma unroll
;             for (int tp = 0; tp < 2; ++tp) {
;                 const v2i ao = TR4(ATL + (2 * q + tp) * 128 + 8 * s16), ah = TR4(ATL + 1024 + (2 * q + tp) * 128 + 8 * s16);
; #pragma unroll
;                 for (int r = 0; r < 4; ++r) {
;                     const v2i d = TR4(ldsb + BUF[st % 3] + 2048 * tp + roff[r]);
;                     accH[r] = __builtin_amdgcn_sdot8(d.x, ah.x, accH[r], false); accH[r] = __builtin_amdgcn_sdot8(d.y, ah.y, accH[r], false);
;                     accL[r] = __builtin_amdgcn_sdot8(d.x, ao.x, accL[r], false); accL[r] = __builtin_amdgcn_sdot8(d.y, ao.y, accL[r], false);
;                 }
;             }
	v_add_u32_e32 v54, s99, v59
	v_add_u32_e32 v55, s99, v60
	v_add_u32_e32 v56, s99, v61
	v_add_u32_e32 v57, s99, v62
	ds_read_b64_tr_b4 v[50:51], v160 offset:384
	ds_read_b64_tr_b4 v[52:53], v160 offset:1408
	ds_read_b64_tr_b4 v[130:131], v54
	ds_read_b64_tr_b4 v[132:133], v55
	ds_read_b64_tr_b4 v[134:135], v56
	ds_read_b64_tr_b4 v[136:137], v57
	s_waitcnt lgkmcnt(6)
	v_dot8c_i32_i4_e32 v38, v122, v48
	v_dot8c_i32_i4_e32 v39, v122, v46
	v_dot8c_i32_i4_e32 v40, v124, v48
	v_dot8c_i32_i4_e32 v41, v124, v46
	v_dot8c_i32_i4_e32 v42, v126, v48
	v_dot8c_i32_i4_e32 v43, v126, v46
	v_dot8c_i32_i4_e32 v44, v128, v48
	v_dot8c_i32_i4_e32 v45, v128, v46
	v_dot8c_i32_i4_e32 v38, v123, v49
	v_dot8c_i32_i4_e32 v39, v123, v47
	v_dot8c_i32_i4_e32 v40, v125, v49
	v_dot8c_i32_i4_e32 v41, v125, v47
	v_dot8c_i32_i4_e32 v42, v127, v49
	v_dot8c_i32_i4_e32 v43, v127, v47
	v_dot8c_i32_i4_e32 v44, v129, v49
	v_dot8c_i32_i4_e32 v45, v129, v47
	s_waitcnt lgkmcnt(15)
	v_and_b32_e32 v78, 0xffff, v26
	v_lshrrev_b32_e32 v79, 16, v26
	v_lshl_add_u32 v78, v78, 7, v150
	v_lshl_add_u32 v79, v79, 7, v151
	s_mov_b32 m0, s98
	s_add_i32 s43, s98, 0x400
	global_load_lds_dwordx4 v78, s[50:51]
	s_mov_b32 m0, s43
	s_nop 0
	global_load_lds_dwordx4 v79, s[50:51]
	s_waitcnt vmcnt(9)
	v_add_u32_e32 v54, s76, v59
	v_add_u32_e32 v55, s76, v60
	v_add_u32_e32 v56, s76, v61
	v_add_u32_e32 v57, s76, v62
	ds_read_b64_tr_b4 v[46:47], v160 offset:512
	ds_read_b64_tr_b4 v[48:49], v160 offset:1536
	ds_read_b64_tr_b4 v[122:123], v54
	ds_read_b64_tr_b4 v[124:125], v55
	ds_read_b64_tr_b4 v[126:127], v56
	ds_read_b64_tr_b4 v[128:129], v57
	s_waitcnt lgkmcnt(6)
	v_dot8c_i32_i4_e32 v38, v130, v52
	v_dot8c_i32_i4_e32 v39, v130, v50
	v_dot8c_i32_i4_e32 v40, v132, v52
	v_dot8c_i32_i4_e32 v41, v132, v50
	v_dot8c_i32_i4_e32 v42, v134, v52
	v_dot8c_i32_i4_e32 v43, v134, v50
	v_dot8c_i32_i4_e32 v44, v136, v52
	v_dot8c_i32_i4_e32 v45, v136, v50
	v_dot8c_i32_i4_e32 v38, v131, v53
	v_dot8c_i32_i4_e32 v39, v131, v51
	v_dot8c_i32_i4_e32 v40, v133, v53
	v_dot8c_i32_i4_e32 v41, v133, v51
	v_dot8c_i32_i4_e32 v42, v135, v53
	v_dot8c_i32_i4_e32 v43, v135, v51
	v_dot8c_i32_i4_e32 v44, v137, v53
	v_dot8c_i32_i4_e32 v45, v137, v51
	v_and_b32_e32 v78, 0xffff, v27
	v_lshrrev_b32_e32 v79, 16, v27
	v_lshl_add_u32 v78, v78, 7, v150
	v_lshl_add_u32 v79, v79, 7, v151
	s_mov_b32 m0, s99
	s_add_i32 s43, s99, 0x400
	global_load_lds_dwordx4 v78, s[50:51]
	s_mov_b32 m0, s43
	s_nop 0
	global_load_lds_dwordx4 v79, s[50:51]
	s_waitcnt vmcnt(8)
	v_add_u32_e32 v54, s77, v59
	v_add_u32_e32 v55, s77, v60
	v_add_u32_e32 v56, s77, v61
	v_add_u32_e32 v57, s77, v62
	ds_read_b64_tr_b4 v[50:51], v160 offset:640
	ds_read_b64_tr_b4 v[52:53], v160 offset:1664
	ds_read_b64_tr_b4 v[130:131], v54
	ds_read_b64_tr_b4 v[132:133], v55
	ds_read_b64_tr_b4 v[134:135], v56
	ds_read_b64_tr_b4 v[136:137], v57
	s_waitcnt lgkmcnt(6)
	v_dot8c_i32_i4_e32 v38, v122, v48
	v_dot8c_i32_i4_e32 v39, v122, v46
	v_dot8c_i32_i4_e32 v40, v124, v48
	v_dot8c_i32_i4_e32 v41, v124, v46
	v_dot8c_i32_i4_e32 v42, v126, v48
	v_dot8c_i32_i4_e32 v43, v126, v46
	v_dot8c_i32_i4_e32 v44, v128, v48
	v_dot8c_i32_i4_e32 v45, v128, v46
	v_dot8c_i32_i4_e32 v38, v123, v49
	v_dot8c_i32_i4_e32 v39, v123, v47
	v_dot8c_i32_i4_e32 v40, v125, v49
	v_dot8c_i32_i4_e32 v41, v125, v47
	v_dot8c_i32_i4_e32 v42, v127, v49
	v_dot8c_i32_i4_e32 v43, v127, v47
	v_dot8c_i32_i4_e32 v44, v129, v49
	v_dot8c_i32_i4_e32 v45, v129, v47
	s_waitcnt lgkmcnt(15)
	v_add_u32_e32 v143, 8, v139
	v_and_b32_e32 v142, 15, v143
	v_xor_b32_e32 v142, 8, v142
	v_bfe_u32 v144, v143, 4, 4
	v_mul_lo_u32 v142, v142, s92
	v_mul_lo_u32 v144, v144, s92
	v_mov_b32_e32 v143, v142
	v_mov_b32_e32 v145, v144
	ds_write2st64_b64 v159, v[142:143], v[144:145] offset1:2
	v_and_b32_e32 v78, 0xffff, v28
	v_lshrrev_b32_e32 v79, 16, v28
	v_lshl_add_u32 v78, v78, 7, v150
	v_lshl_add_u32 v79, v79, 7, v151
	s_mov_b32 m0, s76
	s_add_i32 s43, s76, 0x400
	global_load_lds_dwordx4 v78, s[50:51]
	s_mov_b32 m0, s43
	s_nop 0
	global_load_lds_dwordx4 v79, s[50:51]
	s_waitcnt vmcnt(8)
	v_add_u32_e32 v54, s78, v59
	v_add_u32_e32 v55, s78, v60
	v_add_u32_e32 v56, s78, v61
	v_add_u32_e32 v57, s78, v62
	ds_read_b64_tr_b4 v[46:47], v160 offset:768
	ds_read_b64_tr_b4 v[48:49], v160 offset:1792
	ds_read_b64_tr_b4 v[122:123], v54
	ds_read_b64_tr_b4 v[124:125], v55
	ds_read_b64_tr_b4 v[126:127], v56
	ds_read_b64_tr_b4 v[128:129], v57
	s_waitcnt lgkmcnt(7)
	v_dot8c_i32_i4_e32 v38, v130, v52
	v_dot8c_i32_i4_e32 v39, v130, v50
	v_dot8c_i32_i4_e32 v40, v132, v52
	v_dot8c_i32_i4_e32 v41, v132, v50
	v_dot8c_i32_i4_e32 v42, v134, v52
	v_dot8c_i32_i4_e32 v43, v134, v50
	v_dot8c_i32_i4_e32 v44, v136, v52
	v_dot8c_i32_i4_e32 v45, v136, v50
	v_dot8c_i32_i4_e32 v38, v131, v53
	v_dot8c_i32_i4_e32 v39, v131, v51
	v_dot8c_i32_i4_e32 v40, v133, v53
	v_dot8c_i32_i4_e32 v41, v133, v51
	v_dot8c_i32_i4_e32 v42, v135, v53
	v_dot8c_i32_i4_e32 v43, v135, v51
	v_dot8c_i32_i4_e32 v44, v137, v53
	v_dot8c_i32_i4_e32 v45, v137, v51
	v_and_b32_e32 v78, 0xffff, v29
	v_lshrrev_b32_e32 v79, 16, v29
	v_lshl_add_u32 v78, v78, 7, v150
	v_lshl_add_u32 v79, v79, 7, v151
	s_mov_b32 m0, s77
	s_add_i32 s43, s77, 0x400
	global_load_lds_dwordx4 v78, s[50:51]
	s_mov_b32 m0, s43
	s_nop 0
	global_load_lds_dwordx4 v79, s[50:51]
	s_waitcnt vmcnt(8)
	v_add_u32_e32 v54, s79, v59
	v_add_u32_e32 v55, s79, v60
	v_add_u32_e32 v56, s79, v61
	v_add_u32_e32 v57, s79, v62
	ds_read_b64_tr_b4 v[50:51], v160 offset:896
	ds_read_b64_tr_b4 v[52:53], v160 offset:1920
	ds_read_b64_tr_b4 v[130:131], v54
	ds_read_b64_tr_b4 v[132:133], v55
	ds_read_b64_tr_b4 v[134:135], v56
	ds_read_b64_tr_b4 v[136:137], v57
	s_waitcnt lgkmcnt(6)
; __device__ __forceinline__ bf16 f2bf(float f) { return (bf16)f2bfu(f); }
; #define TR4(p_) __builtin_amdgcn_ds_read_tr4_b64_v2i32((LAS v2i*)(p_))
; __device__ __forceinline__ void peer_v_tokens(int j, const LAS unsigned short* EL, const LAS unsigned char* AL  , const LAS float* ASC  , const LAS int* SAL  , ...
;     ...
;         for (int st = 0; st < 16; ++st) {
;             const int p = st >> 2, q = st & 3;
;             if (st < 14) VDMA(st + 2, (st + 2) % 3);
;             if (st < 14) asm volatile("s_waitcnt vmcnt(8)" ::: "memory");
;             else if (st == 14) asm volatile("s_waitcnt vmcnt(4)" ::: "memory");
;             else asm volatile("s_waitcnt vmcnt(0)" ::: "memory");
;             if (q == 0) {
; #pragma unroll
;                 for (int r = 0; r < 4; ++r) { accH[r] = 0; accL[r] = 0; } }
; #pragma unroll
;             for (int tp = 0; tp < 2; ++tp) {
;                 const v2i ao = TR4(ATL + (2 * q + tp) * 128 + 8 * s16), ah = TR4(ATL + 1024 + (2 * q + tp) * 128 + 8 * s16);
; #pragma unroll
;                 for (int r = 0; r < 4; ++r) {
;                     const v2i d = TR4(ldsb + BUF[st % 3] + 2048 * tp + roff[r]);
;                     accH[r] = __builtin_amdgcn_sdot8(d.x, ah.x, accH[r], false); accH[r] = __builtin_amdgcn_sdot8(d.y, ah.y, accH[r], false);
;                     accL[r] = __builtin_amdgcn_sdot8(d.x, ao.x, accL[r], false); accL[r] = __builtin_amdgcn_sdot8(d.y, ao.y, accL[r], false);
;                 }
;             }
;             asm volatile("s_waitcnt lgkmcnt(0)" ::: "memory");
;             if (q == 3) {
; #pragma unroll
;                 for (int r = 0; r < 4; ++r) STASH[256 * p + 16 * (grp + 4 * r) + pc] = f2bf(asc * (float)(2 * ((accH[r] << 4) + accL[r]) + sa));
;             }
;     ...
;             float4* op = (float4*)(outp + (size_t)t * D) + lane;
; #pragma unroll
;             for (int jq = 0; jq < 4; ++jq) { typedef float f4v __attribute__((ext_vector_type(4))); f4v o4; o4.x = v[jq].x * r3 * gv[jq].x; o4.y = v[jq].y * r3 * gv[jq].y; o4.z = v[jq].z * r3 * gv[jq].z; o4.w = v[jq].w * r3 * gv[jq].w;
;                 __builtin_nontemporal_store(o4, (f4v*)op + 64 * jq); }
	v_dot8c_i32_i4_e32 v38, v122, v48
	v_dot8c_i32_i4_e32 v39, v122, v46
	v_dot8c_i32_i4_e32 v40, v124, v48
	v_dot8c_i32_i4_e32 v41, v124, v46
	v_dot8c_i32_i4_e32 v42, v126, v48
	v_dot8c_i32_i4_e32 v43, v126, v46
	v_dot8c_i32_i4_e32 v44, v128, v48
	v_dot8c_i32_i4_e32 v45, v128, v46
	v_dot8c_i32_i4_e32 v38, v123, v49
	v_dot8c_i32_i4_e32 v39, v123, v47
	v_dot8c_i32_i4_e32 v40, v125, v49
	v_dot8c_i32_i4_e32 v41, v125, v47
	v_dot8c_i32_i4_e32 v42, v127, v49
	v_dot8c_i32_i4_e32 v43, v127, v47
	v_dot8c_i32_i4_e32 v44, v129, v49
	v_dot8c_i32_i4_e32 v45, v129, v47
	v_and_b32_e32 v78, 0xffff, v30
	v_lshrrev_b32_e32 v79, 16, v30
	v_lshl_add_u32 v78, v78, 7, v150
	v_lshl_add_u32 v79, v79, 7, v151
	s_mov_b32 m0, s78
	s_add_i32 s43, s78, 0x400
	global_load_lds_dwordx4 v78, s[50:51]
	s_mov_b32 m0, s43
	s_nop 0
	global_load_lds_dwordx4 v79, s[50:51]
	s_waitcnt vmcnt(8)
	v_add_u32_e32 v54, s98, v59
	v_add_u32_e32 v55, s98, v60
	v_add_u32_e32 v56, s98, v61
	v_add_u32_e32 v57, s98, v62
	ds_read_b64_tr_b4 v[46:47], v160
	ds_read_b64_tr_b4 v[48:49], v160 offset:1024
	ds_read_b64_tr_b4 v[122:123], v54
	ds_read_b64_tr_b4 v[124:125], v55
	ds_read_b64_tr_b4 v[126:127], v56
	ds_read_b64_tr_b4 v[128:129], v57
	s_waitcnt lgkmcnt(6)
	v_dot8c_i32_i4_e32 v38, v130, v52
	v_dot8c_i32_i4_e32 v39, v130, v50
	v_dot8c_i32_i4_e32 v40, v132, v52
	v_dot8c_i32_i4_e32 v41, v132, v50
	v_dot8c_i32_i4_e32 v42, v134, v52
	v_dot8c_i32_i4_e32 v43, v134, v50
	v_dot8c_i32_i4_e32 v44, v136, v52
	v_dot8c_i32_i4_e32 v45, v136, v50
	v_dot8c_i32_i4_e32 v38, v131, v53
	v_dot8c_i32_i4_e32 v39, v131, v51
	v_dot8c_i32_i4_e32 v40, v133, v53
	v_dot8c_i32_i4_e32 v41, v133, v51
	v_dot8c_i32_i4_e32 v42, v135, v53
	v_dot8c_i32_i4_e32 v43, v135, v51
	v_dot8c_i32_i4_e32 v44, v137, v53
	v_dot8c_i32_i4_e32 v45, v137, v51
	s_nop 3
	s_waitcnt lgkmcnt(15)
	v_lshlrev_b32_e32 v38, 5, v38
	v_lshlrev_b32_e32 v39, 1, v39
	v_add3_u32 v38, v39, v229, v38
	v_cvt_f32_i32_e32 v38, v38
	v_mul_f32_e32 v38, v228, v38
	v_lshlrev_b32_e32 v40, 5, v40
	v_lshlrev_b32_e32 v41, 1, v41
	v_add3_u32 v40, v41, v229, v40
	v_cvt_f32_i32_e32 v40, v40
	v_mul_f32_e32 v40, v228, v40
	v_lshlrev_b32_e32 v42, 5, v42
	v_lshlrev_b32_e32 v43, 1, v43
	v_add3_u32 v42, v43, v229, v42
	v_cvt_f32_i32_e32 v42, v42
	v_mul_f32_e32 v42, v228, v42
	v_lshlrev_b32_e32 v44, 5, v44
	v_lshlrev_b32_e32 v45, 1, v45
	v_add3_u32 v44, v45, v229, v44
	v_cvt_f32_i32_e32 v44, v44
	v_mul_f32_e32 v44, v228, v44
	v_cvt_pk_bf16_f32 v182, v38, v40
	v_cvt_pk_bf16_f32 v183, v42, v44
	ds_read_b128 v[252:255], v156 offset:1024
	s_add_i32 s44, s40, 32
	s_ashr_i32 s45, s44, 31
	s_lshl_b64 s[44:45], s[44:45], 12
	v_lshl_add_u64 v[80:81], v[36:37], 0, s[44:45]
	s_waitcnt lgkmcnt(0)
	v_mul_f32_e32 v222, v222, v252
	v_mul_f32_e32 v223, v223, v253
	v_mul_f32_e32 v224, v224, v254
	v_mul_f32_e32 v225, v225, v255
	global_store_dwordx4 v[80:81], v[222:225], off offset:3072 nt
	ds_read_b128 v[252:255], v155
	s_add_i32 s44, s40, 40
	s_ashr_i32 s45, s44, 31
	s_lshl_b64 s[44:45], s[44:45], 12
	v_lshl_add_u64 v[80:81], v[36:37], 0, s[44:45]
	s_waitcnt lgkmcnt(0)
	v_mul_f32_e32 v236, v236, v252
	v_mul_f32_e32 v237, v237, v253
	v_mul_f32_e32 v238, v238, v254
	v_mul_f32_e32 v239, v239, v255
	global_store_dwordx4 v[80:81], v[236:239], off nt
	v_add_u32_e32 v147, 8, v140
	v_and_b32_e32 v146, 15, v147
	v_xor_b32_e32 v146, 8, v146
	v_bfe_u32 v148, v147, 4, 4
	v_mul_lo_u32 v146, v146, s92
	v_mul_lo_u32 v148, v148, s92
	v_mov_b32_e32 v147, v146
	v_mov_b32_e32 v149, v148
	ds_write2st64_b64 v77, v[146:147], v[148:149] offset1:2
	v_add_u32_e32 v138, 0x1800, v74
	ds_read_u8 v139, v138
	v_add_u32_e32 v141, 0x1800, v73
	ds_read_u8 v140, v141
	s_add_i32 s43, s67, 224
	v_mov_b32_e32 v138, s43
	ds_read2st64_b32 v[228:229], v138 offset1:1
	ds_read_b128 v[18:21], v227 offset:12288
	ds_read_b128 v[22:25], v227 offset:12304
	v_add_u32_e32 v152, 0x600000, v63
	v_add_u32_e32 v153, 0x600000, v64
	v_mov_b32_e32 v38, 0
	v_mov_b32_e32 v39, 0
	v_mov_b32_e32 v40, 0
	v_mov_b32_e32 v41, 0
	v_mov_b32_e32 v42, 0
	v_mov_b32_e32 v43, 0
	v_mov_b32_e32 v44, 0
	v_mov_b32_e32 v45, 0
	v_and_b32_e32 v78, 0xffff, v31
	v_lshrrev_b32_e32 v79, 16, v31
	v_lshl_add_u32 v78, v78, 7, v150
	v_lshl_add_u32 v79, v79, 7, v151
	s_mov_b32 m0, s79
	s_add_i32 s43, s79, 0x400
	global_load_lds_dwordx4 v78, s[50:51]
	s_mov_b32 m0, s43
	s_nop 0
	global_load_lds_dwordx4 v79, s[50:51]
	s_waitcnt vmcnt(10)
	v_add_u32_e32 v54, s99, v59
	v_add_u32_e32 v55, s99, v60
	v_add_u32_e32 v56, s99, v61
	v_add_u32_e32 v57, s99, v62
	ds_read_b64_tr_b4 v[50:51], v160 offset:128
	ds_read_b64_tr_b4 v[52:53], v160 offset:1152
	ds_read_b64_tr_b4 v[130:131], v54
	ds_read_b64_tr_b4 v[132:133], v55
	ds_read_b64_tr_b4 v[134:135], v56
	ds_read_b64_tr_b4 v[136:137], v57
	s_waitcnt lgkmcnt(14)
	v_dot8c_i32_i4_e32 v38, v122, v48
	v_dot8c_i32_i4_e32 v39, v122, v46
	v_dot8c_i32_i4_e32 v40, v124, v48
	v_dot8c_i32_i4_e32 v41, v124, v46
	v_dot8c_i32_i4_e32 v42, v126, v48
	v_dot8c_i32_i4_e32 v43, v126, v46
	v_dot8c_i32_i4_e32 v44, v128, v48
	v_dot8c_i32_i4_e32 v45, v128, v46
	v_dot8c_i32_i4_e32 v38, v123, v49
	v_dot8c_i32_i4_e32 v39, v123, v47
	v_dot8c_i32_i4_e32 v40, v125, v49
	v_dot8c_i32_i4_e32 v41, v125, v47
	v_dot8c_i32_i4_e32 v42, v127, v49
	v_dot8c_i32_i4_e32 v43, v127, v47
	v_dot8c_i32_i4_e32 v44, v129, v49
	v_dot8c_i32_i4_e32 v45, v129, v47
	v_and_b32_e32 v78, 0xffff, v32
	v_lshrrev_b32_e32 v79, 16, v32
	v_lshl_add_u32 v78, v78, 7, v150
	v_lshl_add_u32 v79, v79, 7, v151
	s_mov_b32 m0, s98
	s_add_i32 s43, s98, 0x400
	global_load_lds_dwordx4 v78, s[50:51]
	s_mov_b32 m0, s43
	s_nop 0
	global_load_lds_dwordx4 v79, s[50:51]
	s_waitcnt vmcnt(10)
; __device__ __forceinline__ void peer_v_tokens(int j, const LAS unsigned short* EL, const LAS unsigned char* AL  , const LAS float* ASC  , const LAS int* SAL  , ...
;     ...
; #pragma unroll 1
;     for (int it = 0; it < 8; ++it) {
;         const int tl = it * 8 + wave, t = j * 64 + tl;
;         unsigned E[8];
;         { const LAS v4u* ep = (const LAS v4u*)(EL + tl * 128 + 16 * g); const v4u e0 = ep[0], e1 = ep[1];
;           E[0] = e0.x; E[1] = e0.y; E[2] = e0.z; E[3] = e0.w; E[4] = e1.x; E[5] = e1.y; E[6] = e1.z; E[7] = e1.w; }
;         uint2 hv[4]; float4 gv[4];
;         { unsigned ho = (unsigned)t * (D / 4) + (unsigned)lane; asm volatile("" : "+v"(ho)); const uint2* hp = (const uint2*)HB + ho; const float4* gp = (const float4*)fng + lane;
; #pragma unroll
;           for (int jq = 0; jq < 4; ++jq) { hv[jq] = hp[64 * jq]; gv[jq] = gp[64 * jq]; } }
;         VDMA(0, 0); VDMA(1, 1);
; #pragma unroll
;         for (int m = 0; m < 2; ++m) {
;             const int idx = lane + 64 * m, tau = idx >> 4, sr = idx & 15, k = 16 * (sr & 7) + 2 * tau + (sr >> 3);
;             const int aq = (int)*(const LAS signed char*)(AL + tl * 128 + k); const int tq = aq + 8;
;             const unsigned lo = (((unsigned)tq & 15u) ^ 8u) * 0x11111111u, hi = ((unsigned)(tq >> 4) & 15u) * 0x11111111u;
;             typedef unsigned u2v __attribute__((ext_vector_type(2)));
;             u2v l2; l2.x = lo; l2.y = lo; u2v h2; h2.x = hi; h2.y = hi;
;             *(LAS u2v*)(ATL + 8 * idx) = l2; *(LAS u2v*)(ATL + 1024 + 8 * idx) = h2;
;         }
;         const float asc = ASC[tl]; const int sa = SAL[tl];
;         CFENCE();
;         int accH[4], accL[4];
; #pragma unroll
;         for (int st = 0; st < 16; ++st) {
;             const int p = st >> 2, q = st & 3;
;             if (st < 14) VDMA(st + 2, (st + 2) % 3);
;             if (st < 14) asm volatile("s_waitcnt vmcnt(8)" ::: "memory");
;             else if (st == 14) asm volatile("s_waitcnt vmcnt(4)" ::: "memory");
;             else asm volatile("s_waitcnt vmcnt(0)" ::: "memory");
;             if (q == 0) {
; #pragma unroll
;                 for (int r = 0; r < 4; ++r) { accH[r] = 0; accL[r] = 0; } }
; #pragma unroll
;             for (int tp = 0; tp < 2; ++tp) {
;                 const v2i ao = TR4(ATL + (2 * q + tp) * 128 + 8 * s16), ah = TR4(ATL + 1024 + (2 * q + tp) * 128 + 8 * s16);
; #pragma unroll
	v_add_u32_e32 v54, s76, v59
	v_add_u32_e32 v55, s76, v60
	v_add_u32_e32 v56, s76, v61
	v_add_u32_e32 v57, s76, v62
	ds_read_b64_tr_b4 v[46:47], v160 offset:256
	ds_read_b64_tr_b4 v[48:49], v160 offset:1280
	ds_read_b64_tr_b4 v[122:123], v54
	ds_read_b64_tr_b4 v[124:125], v55
	ds_read_b64_tr_b4 v[126:127], v56
	ds_read_b64_tr_b4 v[128:129], v57
	s_waitcnt lgkmcnt(6)
	v_dot8c_i32_i4_e32 v38, v130, v52
	v_dot8c_i32_i4_e32 v39, v130, v50
	v_dot8c_i32_i4_e32 v40, v132, v52
	v_dot8c_i32_i4_e32 v41, v132, v50
	v_dot8c_i32_i4_e32 v42, v134, v52
	v_dot8c_i32_i4_e32 v43, v134, v50
	v_dot8c_i32_i4_e32 v44, v136, v52
	v_dot8c_i32_i4_e32 v45, v136, v50
	v_dot8c_i32_i4_e32 v38, v131, v53
	v_dot8c_i32_i4_e32 v39, v131, v51
	v_dot8c_i32_i4_e32 v40, v133, v53
	v_dot8c_i32_i4_e32 v41, v133, v51
	v_dot8c_i32_i4_e32 v42, v135, v53
	v_dot8c_i32_i4_e32 v43, v135, v51
	v_dot8c_i32_i4_e32 v44, v137, v53
	v_dot8c_i32_i4_e32 v45, v137, v51
	v_and_b32_e32 v78, 0xffff, v33
	v_lshrrev_b32_e32 v79, 16, v33
	v_lshl_add_u32 v78, v78, 7, v150
	v_lshl_add_u32 v79, v79, 7, v151
	s_mov_b32 m0, s99
	s_add_i32 s43, s99, 0x400
	global_load_lds_dwordx4 v78, s[50:51]
	s_mov_b32 m0, s43
	s_nop 0
	global_load_lds_dwordx4 v79, s[50:51]
	s_waitcnt vmcnt(10)
	v_add_u32_e32 v54, s77, v59
	v_add_u32_e32 v55, s77, v60
	v_add_u32_e32 v56, s77, v61
	v_add_u32_e32 v57, s77, v62
	ds_read_b64_tr_b4 v[50:51], v160 offset:384
	ds_read_b64_tr_b4 v[52:53], v160 offset:1408
	ds_read_b64_tr_b4 v[130:131], v54
	ds_read_b64_tr_b4 v[132:133], v55
	ds_read_b64_tr_b4 v[134:135], v56
	ds_read_b64_tr_b4 v[136:137], v57
	s_waitcnt lgkmcnt(6)
	v_dot8c_i32_i4_e32 v38, v122, v48
	v_dot8c_i32_i4_e32 v39, v122, v46
	v_dot8c_i32_i4_e32 v40, v124, v48
	v_dot8c_i32_i4_e32 v41, v124, v46
	v_dot8c_i32_i4_e32 v42, v126, v48
	v_dot8c_i32_i4_e32 v43, v126, v46
	v_dot8c_i32_i4_e32 v44, v128, v48
	v_dot8c_i32_i4_e32 v45, v128, v46
	v_dot8c_i32_i4_e32 v38, v123, v49
	v_dot8c_i32_i4_e32 v39, v123, v47
	v_dot8c_i32_i4_e32 v40, v125, v49
	v_dot8c_i32_i4_e32 v41, v125, v47
	v_dot8c_i32_i4_e32 v42, v127, v49
	v_dot8c_i32_i4_e32 v43, v127, v47
	v_dot8c_i32_i4_e32 v44, v129, v49
	v_dot8c_i32_i4_e32 v45, v129, v47
	s_waitcnt lgkmcnt(15)
	v_and_b32_e32 v78, 0xffff, v18
	v_lshrrev_b32_e32 v79, 16, v18
	v_lshl_add_u32 v78, v78, 7, v152
	v_lshl_add_u32 v79, v79, 7, v153
	s_mov_b32 m0, s76
	s_add_i32 s43, s76, 0x400
	global_load_lds_dwordx4 v78, s[50:51]
	s_mov_b32 m0, s43
	s_nop 0
	global_load_lds_dwordx4 v79, s[50:51]
	s_waitcnt vmcnt(10)
	v_add_u32_e32 v54, s78, v59
	v_add_u32_e32 v55, s78, v60
	v_add_u32_e32 v56, s78, v61
	v_add_u32_e32 v57, s78, v62
	ds_read_b64_tr_b4 v[46:47], v160 offset:512
	ds_read_b64_tr_b4 v[48:49], v160 offset:1536
	ds_read_b64_tr_b4 v[122:123], v54
	ds_read_b64_tr_b4 v[124:125], v55
	ds_read_b64_tr_b4 v[126:127], v56
	ds_read_b64_tr_b4 v[128:129], v57
	s_waitcnt lgkmcnt(6)
	v_dot8c_i32_i4_e32 v38, v130, v52
	v_dot8c_i32_i4_e32 v39, v130, v50
	v_dot8c_i32_i4_e32 v40, v132, v52
	v_dot8c_i32_i4_e32 v41, v132, v50
	v_dot8c_i32_i4_e32 v42, v134, v52
	v_dot8c_i32_i4_e32 v43, v134, v50
	v_dot8c_i32_i4_e32 v44, v136, v52
	v_dot8c_i32_i4_e32 v45, v136, v50
	v_dot8c_i32_i4_e32 v38, v131, v53
	v_dot8c_i32_i4_e32 v39, v131, v51
	v_dot8c_i32_i4_e32 v40, v133, v53
	v_dot8c_i32_i4_e32 v41, v133, v51
	v_dot8c_i32_i4_e32 v42, v135, v53
	v_dot8c_i32_i4_e32 v43, v135, v51
	v_dot8c_i32_i4_e32 v44, v137, v53
	v_dot8c_i32_i4_e32 v45, v137, v51
	v_and_b32_e32 v78, 0xffff, v19
	v_lshrrev_b32_e32 v79, 16, v19
	v_lshl_add_u32 v78, v78, 7, v152
	v_lshl_add_u32 v79, v79, 7, v153
	s_mov_b32 m0, s77
	s_add_i32 s43, s77, 0x400
	global_load_lds_dwordx4 v78, s[50:51]
	s_mov_b32 m0, s43
	s_nop 0
	global_load_lds_dwordx4 v79, s[50:51]
	s_waitcnt vmcnt(8)
	v_add_u32_e32 v54, s79, v59
	v_add_u32_e32 v55, s79, v60
	v_add_u32_e32 v56, s79, v61
	v_add_u32_e32 v57, s79, v62
	ds_read_b64_tr_b4 v[50:51], v160 offset:640
	ds_read_b64_tr_b4 v[52:53], v160 offset:1664
	ds_read_b64_tr_b4 v[130:131], v54
	ds_read_b64_tr_b4 v[132:133], v55
	ds_read_b64_tr_b4 v[134:135], v56
	ds_read_b64_tr_b4 v[136:137], v57
	s_waitcnt lgkmcnt(6)
	v_dot8c_i32_i4_e32 v38, v122, v48
	v_dot8c_i32_i4_e32 v39, v122, v46
	v_dot8c_i32_i4_e32 v40, v124, v48
	v_dot8c_i32_i4_e32 v41, v124, v46
	v_dot8c_i32_i4_e32 v42, v126, v48
	v_dot8c_i32_i4_e32 v43, v126, v46
	v_dot8c_i32_i4_e32 v44, v128, v48
	v_dot8c_i32_i4_e32 v45, v128, v46
	v_dot8c_i32_i4_e32 v38, v123, v49
	v_dot8c_i32_i4_e32 v39, v123, v47
	v_dot8c_i32_i4_e32 v40, v125, v49
	v_dot8c_i32_i4_e32 v41, v125, v47
	v_dot8c_i32_i4_e32 v42, v127, v49
	v_dot8c_i32_i4_e32 v43, v127, v47
	v_dot8c_i32_i4_e32 v44, v129, v49
	v_dot8c_i32_i4_e32 v45, v129, v47
	s_waitcnt lgkmcnt(15)
	v_add_u32_e32 v143, 8, v139
	v_and_b32_e32 v142, 15, v143
	v_xor_b32_e32 v142, 8, v142
	v_bfe_u32 v144, v143, 4, 4
	v_mul_lo_u32 v142, v142, s92
	v_mul_lo_u32 v144, v144, s92
	v_mov_b32_e32 v143, v142
	v_mov_b32_e32 v145, v144
	ds_write2st64_b64 v159, v[142:143], v[144:145] offset1:2
	v_and_b32_e32 v78, 0xffff, v20
	v_lshrrev_b32_e32 v79, 16, v20
	v_lshl_add_u32 v78, v78, 7, v152
	v_lshl_add_u32 v79, v79, 7, v153
	s_mov_b32 m0, s78
	s_add_i32 s43, s78, 0x400
	global_load_lds_dwordx4 v78, s[50:51]
	s_mov_b32 m0, s43
	s_nop 0
	global_load_lds_dwordx4 v79, s[50:51]
	s_waitcnt vmcnt(8)
	v_add_u32_e32 v54, s98, v59
	v_add_u32_e32 v55, s98, v60
	v_add_u32_e32 v56, s98, v61
	v_add_u32_e32 v57, s98, v62
	ds_read_b64_tr_b4 v[46:47], v160 offset:768
	ds_read_b64_tr_b4 v[48:49], v160 offset:1792
	ds_read_b64_tr_b4 v[122:123], v54
	ds_read_b64_tr_b4 v[124:125], v55
	ds_read_b64_tr_b4 v[126:127], v56
	ds_read_b64_tr_b4 v[128:129], v57
	s_waitcnt lgkmcnt(7)
; #define LAS __attribute__((address_space(3)))
; __device__ __forceinline__ void peer_v_tokens(int j, const LAS unsigned short* EL, const LAS unsigned char* AL  , const LAS float* ASC  , const LAS int* SAL  , ...
;     ...
;         for (int st = 0; st < 16; ++st) {
;             const int p = st >> 2, q = st & 3;
;             if (st < 14) VDMA(st + 2, (st + 2) % 3);
;             if (st < 14) asm volatile("s_waitcnt vmcnt(8)" ::: "memory");
;             else if (st == 14) asm volatile("s_waitcnt vmcnt(4)" ::: "memory");
;             else asm volatile("s_waitcnt vmcnt(0)" ::: "memory");
;             if (q == 0) {
; #pragma unroll
;                 for (int r = 0; r < 4; ++r) { accH[r] = 0; accL[r] = 0; } }
; #pragma unroll
;             for (int tp = 0; tp < 2; ++tp) {
;                 const v2i ao = TR4(ATL + (2 * q + tp) * 128 + 8 * s16), ah = TR4(ATL + 1024 + (2 * q + tp) * 128 + 8 * s16);
; #pragma unroll
;                 for (int r = 0; r < 4; ++r) {
;                     const v2i d = TR4(ldsb + BUF[st % 3] + 2048 * tp + roff[r]);
;                     accH[r] = __builtin_amdgcn_sdot8(d.x, ah.x, accH[r], false); accH[r] = __builtin_amdgcn_sdot8(d.y, ah.y, accH[r], false);
;                     accL[r] = __builtin_amdgcn_sdot8(d.x, ao.x, accL[r], false); accL[r] = __builtin_amdgcn_sdot8(d.y, ao.y, accL[r], false);
;                 }
;             }
;             asm volatile("s_waitcnt lgkmcnt(0)" ::: "memory");
;             if (q == 3) {
; #pragma unroll
;                 for (int r = 0; r < 4; ++r) STASH[256 * p + 16 * (grp + 4 * r) + pc] = f2bf(asc * (float)(2 * ((accH[r] << 4) + accL[r]) + sa));
;             }
;     ...
;         {
;             float4 v[4]; float ss = 0.f;
; #pragma unroll
;             for (int jq = 0; jq < 4; ++jq) { typedef unsigned u2v __attribute__((ext_vector_type(2))); const u2v pw = *(const LAS u2v*)(STASH + 4 * lane + 256 * jq); const uint2 hw = hv[jq];
;                 v[jq] = make_float4(__uint_as_float(hw.x << 16) + __uint_as_float(pw.x << 16), __uint_as_float(hw.x & 0xffff0000u) + __uint_as_float(pw.x & 0xffff0000u),
;                                     __uint_as_float(hw.y << 16) + __uint_as_float(pw.y << 16), __uint_as_float(hw.y & 0xffff0000u) + __uint_as_float(pw.y & 0xffff0000u));
;                 ss += v[jq].x * v[jq].x + v[jq].y * v[jq].y + v[jq].z * v[jq].z + v[jq].w * v[jq].w; }
;             ss = wave_sum(ss);
	v_dot8c_i32_i4_e32 v38, v130, v52
	v_dot8c_i32_i4_e32 v39, v130, v50
	v_dot8c_i32_i4_e32 v40, v132, v52
	v_dot8c_i32_i4_e32 v41, v132, v50
	v_dot8c_i32_i4_e32 v42, v134, v52
	v_dot8c_i32_i4_e32 v43, v134, v50
	v_dot8c_i32_i4_e32 v44, v136, v52
	v_dot8c_i32_i4_e32 v45, v136, v50
	v_dot8c_i32_i4_e32 v38, v131, v53
	v_dot8c_i32_i4_e32 v39, v131, v51
	v_dot8c_i32_i4_e32 v40, v133, v53
	v_dot8c_i32_i4_e32 v41, v133, v51
	v_dot8c_i32_i4_e32 v42, v135, v53
	v_dot8c_i32_i4_e32 v43, v135, v51
	v_dot8c_i32_i4_e32 v44, v137, v53
	v_dot8c_i32_i4_e32 v45, v137, v51
	v_and_b32_e32 v78, 0xffff, v21
	v_lshrrev_b32_e32 v79, 16, v21
	v_lshl_add_u32 v78, v78, 7, v152
	v_lshl_add_u32 v79, v79, 7, v153
	s_mov_b32 m0, s79
	s_add_i32 s43, s79, 0x400
	global_load_lds_dwordx4 v78, s[50:51]
	s_mov_b32 m0, s43
	s_nop 0
	global_load_lds_dwordx4 v79, s[50:51]
	s_waitcnt vmcnt(8)
	v_add_u32_e32 v54, s99, v59
	v_add_u32_e32 v55, s99, v60
	v_add_u32_e32 v56, s99, v61
	v_add_u32_e32 v57, s99, v62
	ds_read_b64_tr_b4 v[50:51], v160 offset:896
	ds_read_b64_tr_b4 v[52:53], v160 offset:1920
	ds_read_b64_tr_b4 v[130:131], v54
	ds_read_b64_tr_b4 v[132:133], v55
	ds_read_b64_tr_b4 v[134:135], v56
	ds_read_b64_tr_b4 v[136:137], v57
	s_waitcnt lgkmcnt(6)
	v_dot8c_i32_i4_e32 v38, v122, v48
	v_dot8c_i32_i4_e32 v39, v122, v46
	v_dot8c_i32_i4_e32 v40, v124, v48
	v_dot8c_i32_i4_e32 v41, v124, v46
	v_dot8c_i32_i4_e32 v42, v126, v48
	v_dot8c_i32_i4_e32 v43, v126, v46
	v_dot8c_i32_i4_e32 v44, v128, v48
	v_dot8c_i32_i4_e32 v45, v128, v46
	v_dot8c_i32_i4_e32 v38, v123, v49
	v_dot8c_i32_i4_e32 v39, v123, v47
	v_dot8c_i32_i4_e32 v40, v125, v49
	v_dot8c_i32_i4_e32 v41, v125, v47
	v_dot8c_i32_i4_e32 v42, v127, v49
	v_dot8c_i32_i4_e32 v43, v127, v47
	v_dot8c_i32_i4_e32 v44, v129, v49
	v_dot8c_i32_i4_e32 v45, v129, v47
	v_and_b32_e32 v78, 0xffff, v22
	v_lshrrev_b32_e32 v79, 16, v22
	v_lshl_add_u32 v78, v78, 7, v152
	v_lshl_add_u32 v79, v79, 7, v153
	s_mov_b32 m0, s98
	s_add_i32 s43, s98, 0x400
	global_load_lds_dwordx4 v78, s[50:51]
	s_mov_b32 m0, s43
	s_nop 0
	global_load_lds_dwordx4 v79, s[50:51]
	s_waitcnt vmcnt(8)
	v_add_u32_e32 v54, s76, v59
	v_add_u32_e32 v55, s76, v60
	v_add_u32_e32 v56, s76, v61
	v_add_u32_e32 v57, s76, v62
	ds_read_b64_tr_b4 v[46:47], v160
	ds_read_b64_tr_b4 v[48:49], v160 offset:1024
	ds_read_b64_tr_b4 v[122:123], v54
	ds_read_b64_tr_b4 v[124:125], v55
	ds_read_b64_tr_b4 v[126:127], v56
	ds_read_b64_tr_b4 v[128:129], v57
	s_waitcnt lgkmcnt(6)
	v_dot8c_i32_i4_e32 v38, v130, v52
	v_dot8c_i32_i4_e32 v39, v130, v50
	v_dot8c_i32_i4_e32 v40, v132, v52
	v_dot8c_i32_i4_e32 v41, v132, v50
	v_dot8c_i32_i4_e32 v42, v134, v52
	v_dot8c_i32_i4_e32 v43, v134, v50
	v_dot8c_i32_i4_e32 v44, v136, v52
	v_dot8c_i32_i4_e32 v45, v136, v50
	v_dot8c_i32_i4_e32 v38, v131, v53
	v_dot8c_i32_i4_e32 v39, v131, v51
	v_dot8c_i32_i4_e32 v40, v133, v53
	v_dot8c_i32_i4_e32 v41, v133, v51
	v_dot8c_i32_i4_e32 v42, v135, v53
	v_dot8c_i32_i4_e32 v43, v135, v51
	v_dot8c_i32_i4_e32 v44, v137, v53
	v_dot8c_i32_i4_e32 v45, v137, v51
	s_nop 3
	s_waitcnt lgkmcnt(15)
	v_lshlrev_b32_e32 v38, 5, v38
	v_lshlrev_b32_e32 v39, 1, v39
	v_add3_u32 v38, v39, v229, v38
	v_cvt_f32_i32_e32 v38, v38
	v_mul_f32_e32 v38, v228, v38
	v_lshlrev_b32_e32 v40, 5, v40
	v_lshlrev_b32_e32 v41, 1, v41
	v_add3_u32 v40, v41, v229, v40
	v_cvt_f32_i32_e32 v40, v40
	v_mul_f32_e32 v40, v228, v40
	v_lshlrev_b32_e32 v42, 5, v42
	v_lshlrev_b32_e32 v43, 1, v43
	v_add3_u32 v42, v43, v229, v42
	v_cvt_f32_i32_e32 v42, v42
	v_mul_f32_e32 v42, v228, v42
	v_lshlrev_b32_e32 v44, 5, v44
	v_lshlrev_b32_e32 v45, 1, v45
	v_add3_u32 v44, v45, v229, v44
	v_cvt_f32_i32_e32 v44, v44
	v_mul_f32_e32 v44, v228, v44
	v_cvt_pk_bf16_f32 v190, v38, v40
	v_cvt_pk_bf16_f32 v191, v42, v44
	ds_read_b128 v[252:255], v155 offset:1024
	s_add_i32 s44, s40, 40
	s_ashr_i32 s45, s44, 31
	s_lshl_b64 s[44:45], s[44:45], 12
	v_lshl_add_u64 v[80:81], v[36:37], 0, s[44:45]
	s_waitcnt lgkmcnt(0)
	v_mul_f32_e32 v240, v240, v252
	v_mul_f32_e32 v241, v241, v253
	v_mul_f32_e32 v242, v242, v254
	v_mul_f32_e32 v243, v243, v255
	global_store_dwordx4 v[80:81], v[240:243], off offset:1024 nt
	v_add_u32_e32 v147, 8, v140
	v_and_b32_e32 v146, 15, v147
	v_xor_b32_e32 v146, 8, v146
	v_bfe_u32 v148, v147, 4, 4
	v_mul_lo_u32 v146, v146, s92
	v_mul_lo_u32 v148, v148, s92
	v_mov_b32_e32 v147, v146
	v_mov_b32_e32 v149, v148
	ds_write2st64_b64 v77, v[146:147], v[148:149] offset1:2
	v_add_u32_e32 v138, 0x1c00, v74
	ds_read_u8 v139, v138
	v_add_u32_e32 v141, 0x1c00, v73
	ds_read_u8 v140, v141
	s_add_i32 s43, s67, 192
	v_mov_b32_e32 v138, s43
	ds_read2st64_b32 v[228:229], v138 offset1:1
	ds_read_b128 v[26:29], v227 offset:14336
	ds_read_b128 v[30:33], v227 offset:14352
	v_mov_b32_e32 v38, 0
	v_mov_b32_e32 v39, 0
	v_mov_b32_e32 v40, 0
	v_mov_b32_e32 v41, 0
	v_mov_b32_e32 v42, 0
	v_mov_b32_e32 v43, 0
	v_mov_b32_e32 v44, 0
	v_mov_b32_e32 v45, 0
	v_and_b32_e32 v78, 0xffff, v23
	v_lshrrev_b32_e32 v79, 16, v23
	v_lshl_add_u32 v78, v78, 7, v152
	v_lshl_add_u32 v79, v79, 7, v153
	s_mov_b32 m0, s99
	s_add_i32 s43, s99, 0x400
	global_load_lds_dwordx4 v78, s[50:51]
	s_mov_b32 m0, s43
	s_nop 0
	global_load_lds_dwordx4 v79, s[50:51]
	s_waitcnt vmcnt(9)
	v_add_u32_e32 v54, s77, v59
	v_add_u32_e32 v55, s77, v60
	v_add_u32_e32 v56, s77, v61
	v_add_u32_e32 v57, s77, v62
	ds_read_b64_tr_b4 v[50:51], v160 offset:128
	ds_read_b64_tr_b4 v[52:53], v160 offset:1152
	ds_read_b64_tr_b4 v[130:131], v54
	ds_read_b64_tr_b4 v[132:133], v55
	ds_read_b64_tr_b4 v[134:135], v56
	ds_read_b64_tr_b4 v[136:137], v57
	s_waitcnt lgkmcnt(13)
; __device__ __forceinline__ void peer_v_tokens(int j, const LAS unsigned short* EL, const LAS unsigned char* AL  , const LAS float* ASC  , const LAS int* SAL  , ...
;     ...
; #pragma unroll 1
;     for (int it = 0; it < 8; ++it) {
;         const int tl = it * 8 + wave, t = j * 64 + tl;
;         unsigned E[8];
;         { const LAS v4u* ep = (const LAS v4u*)(EL + tl * 128 + 16 * g); const v4u e0 = ep[0], e1 = ep[1];
;           E[0] = e0.x; E[1] = e0.y; E[2] = e0.z; E[3] = e0.w; E[4] = e1.x; E[5] = e1.y; E[6] = e1.z; E[7] = e1.w; }
;         uint2 hv[4]; float4 gv[4];
;         { unsigned ho = (unsigned)t * (D / 4) + (unsigned)lane; asm volatile("" : "+v"(ho)); const uint2* hp = (const uint2*)HB + ho; const float4* gp = (const float4*)fng + lane;
; #pragma unroll
;           for (int jq = 0; jq < 4; ++jq) { hv[jq] = hp[64 * jq]; gv[jq] = gp[64 * jq]; } }
;         VDMA(0, 0); VDMA(1, 1);
; #pragma unroll
;         for (int m = 0; m < 2; ++m) {
;             const int idx = lane + 64 * m, tau = idx >> 4, sr = idx & 15, k = 16 * (sr & 7) + 2 * tau + (sr >> 3);
;             const int aq = (int)*(const LAS signed char*)(AL + tl * 128 + k); const int tq = aq + 8;
;             const unsigned lo = (((unsigned)tq & 15u) ^ 8u) * 0x11111111u, hi = ((unsigned)(tq >> 4) & 15u) * 0x11111111u;
;             typedef unsigned u2v __attribute__((ext_vector_type(2)));
;             u2v l2; l2.x = lo; l2.y = lo; u2v h2; h2.x = hi; h2.y = hi;
;             *(LAS u2v*)(ATL + 8 * idx) = l2; *(LAS u2v*)(ATL + 1024 + 8 * idx) = h2;
;         }
;         const float asc = ASC[tl]; const int sa = SAL[tl];
;         CFENCE();
;         int accH[4], accL[4];
; #pragma unroll
;         for (int st = 0; st < 16; ++st) {
;             const int p = st >> 2, q = st & 3;
;             if (st < 14) VDMA(st + 2, (st + 2) % 3);
;             if (st < 14) asm volatile("s_waitcnt vmcnt(8)" ::: "memory");
;             else if (st == 14) asm volatile("s_waitcnt vmcnt(4)" ::: "memory");
;             else asm volatile("s_waitcnt vmcnt(0)" ::: "memory");
;             if (q == 0) {
; #pragma unroll
;                 for (int r = 0; r < 4; ++r) { accH[r] = 0; accL[r] = 0; } }
; #pragma unroll
;             for (int tp = 0; tp < 2; ++tp) {
;                 const v2i ao = TR4(ATL + (2 * q + tp) * 128 + 8 * s16), ah = TR4(ATL + 1024 + (2 * q + tp) * 128 + 8 * s16);
; #pragma unroll
	v_dot8c_i32_i4_e32 v38, v122, v48
	v_dot8c_i32_i4_e32 v39, v122, v46
	v_dot8c_i32_i4_e32 v40, v124, v48
	v_dot8c_i32_i4_e32 v41, v124, v46
	v_dot8c_i32_i4_e32 v42, v126, v48
	v_dot8c_i32_i4_e32 v43, v126, v46
	v_dot8c_i32_i4_e32 v44, v128, v48
	v_dot8c_i32_i4_e32 v45, v128, v46
	v_dot8c_i32_i4_e32 v38, v123, v49
	v_dot8c_i32_i4_e32 v39, v123, v47
	v_dot8c_i32_i4_e32 v40, v125, v49
	v_dot8c_i32_i4_e32 v41, v125, v47
	v_dot8c_i32_i4_e32 v42, v127, v49
	v_dot8c_i32_i4_e32 v43, v127, v47
	v_dot8c_i32_i4_e32 v44, v129, v49
	v_dot8c_i32_i4_e32 v45, v129, v47
	v_and_b32_e32 v78, 0xffff, v24
	v_lshrrev_b32_e32 v79, 16, v24
	v_lshl_add_u32 v78, v78, 7, v152
	v_lshl_add_u32 v79, v79, 7, v153
	s_mov_b32 m0, s76
	s_add_i32 s43, s76, 0x400
	global_load_lds_dwordx4 v78, s[50:51]
	s_mov_b32 m0, s43
	s_nop 0
	global_load_lds_dwordx4 v79, s[50:51]
	s_waitcnt vmcnt(9)
	v_add_u32_e32 v54, s78, v59
	v_add_u32_e32 v55, s78, v60
	v_add_u32_e32 v56, s78, v61
	v_add_u32_e32 v57, s78, v62
	ds_read_b64_tr_b4 v[46:47], v160 offset:256
	ds_read_b64_tr_b4 v[48:49], v160 offset:1280
	ds_read_b64_tr_b4 v[122:123], v54
	ds_read_b64_tr_b4 v[124:125], v55
	ds_read_b64_tr_b4 v[126:127], v56
	ds_read_b64_tr_b4 v[128:129], v57
	s_waitcnt lgkmcnt(6)
	v_dot8c_i32_i4_e32 v38, v130, v52
	v_dot8c_i32_i4_e32 v39, v130, v50
	v_dot8c_i32_i4_e32 v40, v132, v52
	v_dot8c_i32_i4_e32 v41, v132, v50
	v_dot8c_i32_i4_e32 v42, v134, v52
	v_dot8c_i32_i4_e32 v43, v134, v50
	v_dot8c_i32_i4_e32 v44, v136, v52
	v_dot8c_i32_i4_e32 v45, v136, v50
	v_dot8c_i32_i4_e32 v38, v131, v53
	v_dot8c_i32_i4_e32 v39, v131, v51
	v_dot8c_i32_i4_e32 v40, v133, v53
	v_dot8c_i32_i4_e32 v41, v133, v51
	v_dot8c_i32_i4_e32 v42, v135, v53
	v_dot8c_i32_i4_e32 v43, v135, v51
	v_dot8c_i32_i4_e32 v44, v137, v53
	v_dot8c_i32_i4_e32 v45, v137, v51
	v_and_b32_e32 v78, 0xffff, v25
	v_lshrrev_b32_e32 v79, 16, v25
	v_lshl_add_u32 v78, v78, 7, v152
	v_lshl_add_u32 v79, v79, 7, v153
	s_mov_b32 m0, s77
	s_add_i32 s43, s77, 0x400
	global_load_lds_dwordx4 v78, s[50:51]
	s_mov_b32 m0, s43
	s_nop 0
	global_load_lds_dwordx4 v79, s[50:51]
	s_waitcnt vmcnt(9)
	v_add_u32_e32 v54, s79, v59
	v_add_u32_e32 v55, s79, v60
	v_add_u32_e32 v56, s79, v61
	v_add_u32_e32 v57, s79, v62
	ds_read_b64_tr_b4 v[50:51], v160 offset:384
	ds_read_b64_tr_b4 v[52:53], v160 offset:1408
	ds_read_b64_tr_b4 v[130:131], v54
	ds_read_b64_tr_b4 v[132:133], v55
	ds_read_b64_tr_b4 v[134:135], v56
	ds_read_b64_tr_b4 v[136:137], v57
	s_waitcnt lgkmcnt(6)
	v_dot8c_i32_i4_e32 v38, v122, v48
	v_dot8c_i32_i4_e32 v39, v122, v46
	v_dot8c_i32_i4_e32 v40, v124, v48
	v_dot8c_i32_i4_e32 v41, v124, v46
	v_dot8c_i32_i4_e32 v42, v126, v48
	v_dot8c_i32_i4_e32 v43, v126, v46
	v_dot8c_i32_i4_e32 v44, v128, v48
	v_dot8c_i32_i4_e32 v45, v128, v46
	v_dot8c_i32_i4_e32 v38, v123, v49
	v_dot8c_i32_i4_e32 v39, v123, v47
	v_dot8c_i32_i4_e32 v40, v125, v49
	v_dot8c_i32_i4_e32 v41, v125, v47
	v_dot8c_i32_i4_e32 v42, v127, v49
	v_dot8c_i32_i4_e32 v43, v127, v47
	v_dot8c_i32_i4_e32 v44, v129, v49
	v_dot8c_i32_i4_e32 v45, v129, v47
	s_waitcnt lgkmcnt(15)
	v_and_b32_e32 v78, 0xffff, v26
	v_lshrrev_b32_e32 v79, 16, v26
	v_lshl_add_u32 v78, v78, 7, v152
	v_lshl_add_u32 v79, v79, 7, v153
	s_mov_b32 m0, s78
	s_add_i32 s43, s78, 0x400
	global_load_lds_dwordx4 v78, s[50:51]
	s_mov_b32 m0, s43
	s_nop 0
	global_load_lds_dwordx4 v79, s[50:51]
	s_waitcnt vmcnt(9)
	v_add_u32_e32 v54, s98, v59
	v_add_u32_e32 v55, s98, v60
	v_add_u32_e32 v56, s98, v61
	v_add_u32_e32 v57, s98, v62
	ds_read_b64_tr_b4 v[46:47], v160 offset:512
	ds_read_b64_tr_b4 v[48:49], v160 offset:1536
	ds_read_b64_tr_b4 v[122:123], v54
	ds_read_b64_tr_b4 v[124:125], v55
	ds_read_b64_tr_b4 v[126:127], v56
	ds_read_b64_tr_b4 v[128:129], v57
	s_waitcnt lgkmcnt(6)
	v_dot8c_i32_i4_e32 v38, v130, v52
	v_dot8c_i32_i4_e32 v39, v130, v50
	v_dot8c_i32_i4_e32 v40, v132, v52
	v_dot8c_i32_i4_e32 v41, v132, v50
	v_dot8c_i32_i4_e32 v42, v134, v52
	v_dot8c_i32_i4_e32 v43, v134, v50
	v_dot8c_i32_i4_e32 v44, v136, v52
	v_dot8c_i32_i4_e32 v45, v136, v50
	v_dot8c_i32_i4_e32 v38, v131, v53
	v_dot8c_i32_i4_e32 v39, v131, v51
	v_dot8c_i32_i4_e32 v40, v133, v53
	v_dot8c_i32_i4_e32 v41, v133, v51
	v_dot8c_i32_i4_e32 v42, v135, v53
	v_dot8c_i32_i4_e32 v43, v135, v51
	v_dot8c_i32_i4_e32 v44, v137, v53
	v_dot8c_i32_i4_e32 v45, v137, v51
	v_and_b32_e32 v78, 0xffff, v27
	v_lshrrev_b32_e32 v79, 16, v27
	v_lshl_add_u32 v78, v78, 7, v152
	v_lshl_add_u32 v79, v79, 7, v153
	s_mov_b32 m0, s79
	s_add_i32 s43, s79, 0x400
	global_load_lds_dwordx4 v78, s[50:51]
	s_mov_b32 m0, s43
	s_nop 0
	global_load_lds_dwordx4 v79, s[50:51]
	s_waitcnt vmcnt(8)
	v_add_u32_e32 v54, s99, v59
	v_add_u32_e32 v55, s99, v60
	v_add_u32_e32 v56, s99, v61
	v_add_u32_e32 v57, s99, v62
	ds_read_b64_tr_b4 v[50:51], v160 offset:640
	ds_read_b64_tr_b4 v[52:53], v160 offset:1664
	ds_read_b64_tr_b4 v[130:131], v54
	ds_read_b64_tr_b4 v[132:133], v55
	ds_read_b64_tr_b4 v[134:135], v56
	ds_read_b64_tr_b4 v[136:137], v57
	s_waitcnt lgkmcnt(6)
	v_dot8c_i32_i4_e32 v38, v122, v48
	v_dot8c_i32_i4_e32 v39, v122, v46
	v_dot8c_i32_i4_e32 v40, v124, v48
	v_dot8c_i32_i4_e32 v41, v124, v46
	v_dot8c_i32_i4_e32 v42, v126, v48
	v_dot8c_i32_i4_e32 v43, v126, v46
	v_dot8c_i32_i4_e32 v44, v128, v48
	v_dot8c_i32_i4_e32 v45, v128, v46
	v_dot8c_i32_i4_e32 v38, v123, v49
	v_dot8c_i32_i4_e32 v39, v123, v47
	v_dot8c_i32_i4_e32 v40, v125, v49
	v_dot8c_i32_i4_e32 v41, v125, v47
	v_dot8c_i32_i4_e32 v42, v127, v49
	v_dot8c_i32_i4_e32 v43, v127, v47
	v_dot8c_i32_i4_e32 v44, v129, v49
	v_dot8c_i32_i4_e32 v45, v129, v47
	s_waitcnt lgkmcnt(15)
; #define LAS __attribute__((address_space(3)))
; __device__ __forceinline__ void peer_v_tokens(int j, const LAS unsigned short* EL, const LAS unsigned char* AL  , const LAS float* ASC  , const LAS int* SAL  , ...
;     ...
;         for (int st = 0; st < 16; ++st) {
;             const int p = st >> 2, q = st & 3;
;             if (st < 14) VDMA(st + 2, (st + 2) % 3);
;             if (st < 14) asm volatile("s_waitcnt vmcnt(8)" ::: "memory");
;             else if (st == 14) asm volatile("s_waitcnt vmcnt(4)" ::: "memory");
;             else asm volatile("s_waitcnt vmcnt(0)" ::: "memory");
;             if (q == 0) {
; #pragma unroll
;                 for (int r = 0; r < 4; ++r) { accH[r] = 0; accL[r] = 0; } }
; #pragma unroll
;             for (int tp = 0; tp < 2; ++tp) {
;                 const v2i ao = TR4(ATL + (2 * q + tp) * 128 + 8 * s16), ah = TR4(ATL + 1024 + (2 * q + tp) * 128 + 8 * s16);
; #pragma unroll
;                 for (int r = 0; r < 4; ++r) {
;                     const v2i d = TR4(ldsb + BUF[st % 3] + 2048 * tp + roff[r]);
;                     accH[r] = __builtin_amdgcn_sdot8(d.x, ah.x, accH[r], false); accH[r] = __builtin_amdgcn_sdot8(d.y, ah.y, accH[r], false);
;                     accL[r] = __builtin_amdgcn_sdot8(d.x, ao.x, accL[r], false); accL[r] = __builtin_amdgcn_sdot8(d.y, ao.y, accL[r], false);
;                 }
;             }
;             asm volatile("s_waitcnt lgkmcnt(0)" ::: "memory");
;             if (q == 3) {
; #pragma unroll
;                 for (int r = 0; r < 4; ++r) STASH[256 * p + 16 * (grp + 4 * r) + pc] = f2bf(asc * (float)(2 * ((accH[r] << 4) + accL[r]) + sa));
;             }
;     ...
;         {
;             float4 v[4]; float ss = 0.f;
; #pragma unroll
;             for (int jq = 0; jq < 4; ++jq) { typedef unsigned u2v __attribute__((ext_vector_type(2))); const u2v pw = *(const LAS u2v*)(STASH + 4 * lane + 256 * jq); const uint2 hw = hv[jq];
;                 v[jq] = make_float4(__uint_as_float(hw.x << 16) + __uint_as_float(pw.x << 16), __uint_as_float(hw.x & 0xffff0000u) + __uint_as_float(pw.x & 0xffff0000u),
;                                     __uint_as_float(hw.y << 16) + __uint_as_float(pw.y << 16), __uint_as_float(hw.y & 0xffff0000u) + __uint_as_float(pw.y & 0xffff0000u));
;                 ss += v[jq].x * v[jq].x + v[jq].y * v[jq].y + v[jq].z * v[jq].z + v[jq].w * v[jq].w; }
;             ss = wave_sum(ss);
	v_add_u32_e32 v143, 8, v139
	v_and_b32_e32 v142, 15, v143
	v_xor_b32_e32 v142, 8, v142
	v_bfe_u32 v144, v143, 4, 4
	v_mul_lo_u32 v142, v142, s92
	v_mul_lo_u32 v144, v144, s92
	v_mov_b32_e32 v143, v142
	v_mov_b32_e32 v145, v144
	ds_write2st64_b64 v159, v[142:143], v[144:145] offset1:2
	v_and_b32_e32 v78, 0xffff, v28
	v_lshrrev_b32_e32 v79, 16, v28
	v_lshl_add_u32 v78, v78, 7, v152
	v_lshl_add_u32 v79, v79, 7, v153
	s_mov_b32 m0, s98
	s_add_i32 s43, s98, 0x400
	global_load_lds_dwordx4 v78, s[50:51]
	s_mov_b32 m0, s43
	s_nop 0
	global_load_lds_dwordx4 v79, s[50:51]
	s_waitcnt vmcnt(8)
	v_add_u32_e32 v54, s76, v59
	v_add_u32_e32 v55, s76, v60
	v_add_u32_e32 v56, s76, v61
	v_add_u32_e32 v57, s76, v62
	ds_read_b64_tr_b4 v[46:47], v160 offset:768
	ds_read_b64_tr_b4 v[48:49], v160 offset:1792
	ds_read_b64_tr_b4 v[122:123], v54
	ds_read_b64_tr_b4 v[124:125], v55
	ds_read_b64_tr_b4 v[126:127], v56
	ds_read_b64_tr_b4 v[128:129], v57
	s_waitcnt lgkmcnt(7)
	v_dot8c_i32_i4_e32 v38, v130, v52
	v_dot8c_i32_i4_e32 v39, v130, v50
	v_dot8c_i32_i4_e32 v40, v132, v52
	v_dot8c_i32_i4_e32 v41, v132, v50
	v_dot8c_i32_i4_e32 v42, v134, v52
	v_dot8c_i32_i4_e32 v43, v134, v50
	v_dot8c_i32_i4_e32 v44, v136, v52
	v_dot8c_i32_i4_e32 v45, v136, v50
	v_dot8c_i32_i4_e32 v38, v131, v53
	v_dot8c_i32_i4_e32 v39, v131, v51
	v_dot8c_i32_i4_e32 v40, v133, v53
	v_dot8c_i32_i4_e32 v41, v133, v51
	v_dot8c_i32_i4_e32 v42, v135, v53
	v_dot8c_i32_i4_e32 v43, v135, v51
	v_dot8c_i32_i4_e32 v44, v137, v53
	v_dot8c_i32_i4_e32 v45, v137, v51
	v_and_b32_e32 v78, 0xffff, v29
	v_lshrrev_b32_e32 v79, 16, v29
	v_lshl_add_u32 v78, v78, 7, v152
	v_lshl_add_u32 v79, v79, 7, v153
	s_mov_b32 m0, s99
	s_add_i32 s43, s99, 0x400
	global_load_lds_dwordx4 v78, s[50:51]
	s_mov_b32 m0, s43
	s_nop 0
	global_load_lds_dwordx4 v79, s[50:51]
	s_waitcnt vmcnt(8)
	v_add_u32_e32 v54, s77, v59
	v_add_u32_e32 v55, s77, v60
	v_add_u32_e32 v56, s77, v61
	v_add_u32_e32 v57, s77, v62
	ds_read_b64_tr_b4 v[50:51], v160 offset:896
	ds_read_b64_tr_b4 v[52:53], v160 offset:1920
	ds_read_b64_tr_b4 v[130:131], v54
	ds_read_b64_tr_b4 v[132:133], v55
	ds_read_b64_tr_b4 v[134:135], v56
	ds_read_b64_tr_b4 v[136:137], v57
	s_waitcnt lgkmcnt(6)
	v_dot8c_i32_i4_e32 v38, v122, v48
	v_dot8c_i32_i4_e32 v39, v122, v46
	v_dot8c_i32_i4_e32 v40, v124, v48
	v_dot8c_i32_i4_e32 v41, v124, v46
	v_dot8c_i32_i4_e32 v42, v126, v48
	v_dot8c_i32_i4_e32 v43, v126, v46
	v_dot8c_i32_i4_e32 v44, v128, v48
	v_dot8c_i32_i4_e32 v45, v128, v46
	v_dot8c_i32_i4_e32 v38, v123, v49
	v_dot8c_i32_i4_e32 v39, v123, v47
	v_dot8c_i32_i4_e32 v40, v125, v49
	v_dot8c_i32_i4_e32 v41, v125, v47
	v_dot8c_i32_i4_e32 v42, v127, v49
	v_dot8c_i32_i4_e32 v43, v127, v47
	v_dot8c_i32_i4_e32 v44, v129, v49
	v_dot8c_i32_i4_e32 v45, v129, v47
	v_and_b32_e32 v78, 0xffff, v30
	v_lshrrev_b32_e32 v79, 16, v30
	v_lshl_add_u32 v78, v78, 7, v152
	v_lshl_add_u32 v79, v79, 7, v153
	s_mov_b32 m0, s76
	s_add_i32 s43, s76, 0x400
	global_load_lds_dwordx4 v78, s[50:51]
	s_mov_b32 m0, s43
	s_nop 0
	global_load_lds_dwordx4 v79, s[50:51]
	s_waitcnt vmcnt(8)
	v_add_u32_e32 v54, s78, v59
	v_add_u32_e32 v55, s78, v60
	v_add_u32_e32 v56, s78, v61
	v_add_u32_e32 v57, s78, v62
	ds_read_b64_tr_b4 v[46:47], v160
	ds_read_b64_tr_b4 v[48:49], v160 offset:1024
	ds_read_b64_tr_b4 v[122:123], v54
	ds_read_b64_tr_b4 v[124:125], v55
	ds_read_b64_tr_b4 v[126:127], v56
	ds_read_b64_tr_b4 v[128:129], v57
	s_waitcnt lgkmcnt(6)
	v_dot8c_i32_i4_e32 v38, v130, v52
	v_dot8c_i32_i4_e32 v39, v130, v50
	v_dot8c_i32_i4_e32 v40, v132, v52
	v_dot8c_i32_i4_e32 v41, v132, v50
	v_dot8c_i32_i4_e32 v42, v134, v52
	v_dot8c_i32_i4_e32 v43, v134, v50
	v_dot8c_i32_i4_e32 v44, v136, v52
	v_dot8c_i32_i4_e32 v45, v136, v50
	v_dot8c_i32_i4_e32 v38, v131, v53
	v_dot8c_i32_i4_e32 v39, v131, v51
	v_dot8c_i32_i4_e32 v40, v133, v53
	v_dot8c_i32_i4_e32 v41, v133, v51
	v_dot8c_i32_i4_e32 v42, v135, v53
	v_dot8c_i32_i4_e32 v43, v135, v51
	v_dot8c_i32_i4_e32 v44, v137, v53
	v_dot8c_i32_i4_e32 v45, v137, v51
	s_nop 3
	s_waitcnt lgkmcnt(15)
	v_lshlrev_b32_e32 v38, 5, v38
	v_lshlrev_b32_e32 v39, 1, v39
	v_add3_u32 v38, v39, v229, v38
	v_cvt_f32_i32_e32 v38, v38
	v_mul_f32_e32 v38, v228, v38
	v_lshlrev_b32_e32 v40, 5, v40
	v_lshlrev_b32_e32 v41, 1, v41
	v_add3_u32 v40, v41, v229, v40
	v_cvt_f32_i32_e32 v40, v40
	v_mul_f32_e32 v40, v228, v40
	v_lshlrev_b32_e32 v42, 5, v42
	v_lshlrev_b32_e32 v43, 1, v43
	v_add3_u32 v42, v43, v229, v42
	v_cvt_f32_i32_e32 v42, v42
	v_mul_f32_e32 v42, v228, v42
	v_lshlrev_b32_e32 v44, 5, v44
	v_lshlrev_b32_e32 v45, 1, v45
	v_add3_u32 v44, v45, v229, v44
	v_cvt_f32_i32_e32 v44, v44
	v_mul_f32_e32 v44, v228, v44
	v_cvt_pk_bf16_f32 v184, v38, v40
	v_cvt_pk_bf16_f32 v185, v42, v44
	ds_read_b128 v[252:255], v156
	s_add_i32 s44, s40, 40
	s_ashr_i32 s45, s44, 31
	s_lshl_b64 s[44:45], s[44:45], 12
	v_lshl_add_u64 v[80:81], v[36:37], 0, s[44:45]
	s_waitcnt lgkmcnt(0)
; __device__ __forceinline__ bf16 f2bf(float f) { return (bf16)f2bfu(f); }
; #define TR4(p_) __builtin_amdgcn_ds_read_tr4_b64_v2i32((LAS v2i*)(p_))
; __device__ __forceinline__ void peer_v_tokens(int j, const LAS unsigned short* EL, const LAS unsigned char* AL  , const LAS float* ASC  , const LAS int* SAL  , ...
;     ...
;         { unsigned ho = (unsigned)t * (D / 4) + (unsigned)lane; asm volatile("" : "+v"(ho)); const uint2* hp = (const uint2*)HB + ho; const float4* gp = (const float4*)fng + lane;
; #pragma unroll
;           for (int jq = 0; jq < 4; ++jq) { hv[jq] = hp[64 * jq]; gv[jq] = gp[64 * jq]; } }
;     ...
;         for (int st = 0; st < 16; ++st) {
;             const int p = st >> 2, q = st & 3;
;             if (st < 14) VDMA(st + 2, (st + 2) % 3);
;             if (st < 14) asm volatile("s_waitcnt vmcnt(8)" ::: "memory");
;             else if (st == 14) asm volatile("s_waitcnt vmcnt(4)" ::: "memory");
;             else asm volatile("s_waitcnt vmcnt(0)" ::: "memory");
;             if (q == 0) {
; #pragma unroll
;                 for (int r = 0; r < 4; ++r) { accH[r] = 0; accL[r] = 0; } }
; #pragma unroll
;             for (int tp = 0; tp < 2; ++tp) {
;                 const v2i ao = TR4(ATL + (2 * q + tp) * 128 + 8 * s16), ah = TR4(ATL + 1024 + (2 * q + tp) * 128 + 8 * s16);
; #pragma unroll
;                 for (int r = 0; r < 4; ++r) {
;                     const v2i d = TR4(ldsb + BUF[st % 3] + 2048 * tp + roff[r]);
;                     accH[r] = __builtin_amdgcn_sdot8(d.x, ah.x, accH[r], false); accH[r] = __builtin_amdgcn_sdot8(d.y, ah.y, accH[r], false);
;                     accL[r] = __builtin_amdgcn_sdot8(d.x, ao.x, accL[r], false); accL[r] = __builtin_amdgcn_sdot8(d.y, ao.y, accL[r], false);
;                 }
;             }
;             asm volatile("s_waitcnt lgkmcnt(0)" ::: "memory");
;             if (q == 3) {
; #pragma unroll
;                 for (int r = 0; r < 4; ++r) STASH[256 * p + 16 * (grp + 4 * r) + pc] = f2bf(asc * (float)(2 * ((accH[r] << 4) + accL[r]) + sa));
;             }
	v_mul_f32_e32 v244, v244, v252
	v_mul_f32_e32 v245, v245, v253
	v_mul_f32_e32 v246, v246, v254
	v_mul_f32_e32 v247, v247, v255
	global_store_dwordx4 v[80:81], v[244:247], off offset:2048 nt
	s_add_i32 s43, s40, 48
	s_lshl_b32 s43, s43, 11
	v_add_u32_e32 v138, s43, v66
	global_load_dwordx2 v[194:195], v138, s[70:71]
	global_load_dwordx2 v[196:197], v138, s[70:71] offset:512
	global_load_dwordx2 v[198:199], v138, s[70:71] offset:1024
	global_load_dwordx2 v[200:201], v138, s[70:71] offset:1536
	s_add_i32 s43, s40, 56
	s_lshl_b32 s43, s43, 11
	v_add_u32_e32 v138, s43, v66
	global_load_dwordx2 v[18:19], v138, s[70:71]
	global_load_dwordx2 v[20:21], v138, s[70:71] offset:512
	global_load_dwordx2 v[22:23], v138, s[70:71] offset:1024
	global_load_dwordx2 v[24:25], v138, s[70:71] offset:1536
	v_add_u32_e32 v147, 8, v140
	v_and_b32_e32 v146, 15, v147
	v_xor_b32_e32 v146, 8, v146
	v_bfe_u32 v148, v147, 4, 4
	v_mul_lo_u32 v146, v146, s92
	v_mul_lo_u32 v148, v148, s92
	v_mov_b32_e32 v147, v146
	v_mov_b32_e32 v149, v148
	ds_write2st64_b64 v77, v[146:147], v[148:149] offset1:2
	s_add_i32 s43, s67, 224
	v_mov_b32_e32 v138, s43
	ds_read2st64_b32 v[228:229], v138 offset1:1
	v_mov_b32_e32 v38, 0
	v_mov_b32_e32 v39, 0
	v_mov_b32_e32 v40, 0
	v_mov_b32_e32 v41, 0
	v_mov_b32_e32 v42, 0
	v_mov_b32_e32 v43, 0
	v_mov_b32_e32 v44, 0
	v_mov_b32_e32 v45, 0
	v_and_b32_e32 v78, 0xffff, v31
	v_lshrrev_b32_e32 v79, 16, v31
	v_lshl_add_u32 v78, v78, 7, v152
	v_lshl_add_u32 v79, v79, 7, v153
	s_mov_b32 m0, s77
	s_add_i32 s43, s77, 0x400
	global_load_lds_dwordx4 v78, s[50:51]
	s_mov_b32 m0, s43
	s_nop 0
	global_load_lds_dwordx4 v79, s[50:51]
	s_waitcnt vmcnt(17)
	v_add_u32_e32 v54, s79, v59
	v_add_u32_e32 v55, s79, v60
	v_add_u32_e32 v56, s79, v61
	v_add_u32_e32 v57, s79, v62
	ds_read_b64_tr_b4 v[50:51], v160 offset:128
	ds_read_b64_tr_b4 v[52:53], v160 offset:1152
	ds_read_b64_tr_b4 v[130:131], v54
	ds_read_b64_tr_b4 v[132:133], v55
	ds_read_b64_tr_b4 v[134:135], v56
	ds_read_b64_tr_b4 v[136:137], v57
	s_waitcnt lgkmcnt(9)
	v_dot8c_i32_i4_e32 v38, v122, v48
	v_dot8c_i32_i4_e32 v39, v122, v46
	v_dot8c_i32_i4_e32 v40, v124, v48
	v_dot8c_i32_i4_e32 v41, v124, v46
	v_dot8c_i32_i4_e32 v42, v126, v48
	v_dot8c_i32_i4_e32 v43, v126, v46
	v_dot8c_i32_i4_e32 v44, v128, v48
	v_dot8c_i32_i4_e32 v45, v128, v46
	v_dot8c_i32_i4_e32 v38, v123, v49
	v_dot8c_i32_i4_e32 v39, v123, v47
	v_dot8c_i32_i4_e32 v40, v125, v49
	v_dot8c_i32_i4_e32 v41, v125, v47
	v_dot8c_i32_i4_e32 v42, v127, v49
	v_dot8c_i32_i4_e32 v43, v127, v47
	v_dot8c_i32_i4_e32 v44, v129, v49
	v_dot8c_i32_i4_e32 v45, v129, v47
	v_and_b32_e32 v78, 0xffff, v32
	v_lshrrev_b32_e32 v79, 16, v32
	v_lshl_add_u32 v78, v78, 7, v152
	v_lshl_add_u32 v79, v79, 7, v153
	s_mov_b32 m0, s78
	s_add_i32 s43, s78, 0x400
	global_load_lds_dwordx4 v78, s[50:51]
	s_mov_b32 m0, s43
	s_nop 0
	global_load_lds_dwordx4 v79, s[50:51]
	s_waitcnt vmcnt(17)
	v_add_u32_e32 v54, s98, v59
	v_add_u32_e32 v55, s98, v60
	v_add_u32_e32 v56, s98, v61
	v_add_u32_e32 v57, s98, v62
	ds_read_b64_tr_b4 v[46:47], v160 offset:256
	ds_read_b64_tr_b4 v[48:49], v160 offset:1280
	ds_read_b64_tr_b4 v[122:123], v54
	ds_read_b64_tr_b4 v[124:125], v55
	ds_read_b64_tr_b4 v[126:127], v56
	ds_read_b64_tr_b4 v[128:129], v57
	s_waitcnt lgkmcnt(6)
	v_dot8c_i32_i4_e32 v38, v130, v52
	v_dot8c_i32_i4_e32 v39, v130, v50
	v_dot8c_i32_i4_e32 v40, v132, v52
	v_dot8c_i32_i4_e32 v41, v132, v50
	v_dot8c_i32_i4_e32 v42, v134, v52
	v_dot8c_i32_i4_e32 v43, v134, v50
	v_dot8c_i32_i4_e32 v44, v136, v52
	v_dot8c_i32_i4_e32 v45, v136, v50
	v_dot8c_i32_i4_e32 v38, v131, v53
	v_dot8c_i32_i4_e32 v39, v131, v51
	v_dot8c_i32_i4_e32 v40, v133, v53
	v_dot8c_i32_i4_e32 v41, v133, v51
	v_dot8c_i32_i4_e32 v42, v135, v53
	v_dot8c_i32_i4_e32 v43, v135, v51
	v_dot8c_i32_i4_e32 v44, v137, v53
	v_dot8c_i32_i4_e32 v45, v137, v51
	v_and_b32_e32 v78, 0xffff, v33
	v_lshrrev_b32_e32 v79, 16, v33
	v_lshl_add_u32 v78, v78, 7, v152
	v_lshl_add_u32 v79, v79, 7, v153
	s_mov_b32 m0, s79
	s_add_i32 s43, s79, 0x400
	global_load_lds_dwordx4 v78, s[50:51]
	s_mov_b32 m0, s43
	s_nop 0
	global_load_lds_dwordx4 v79, s[50:51]
	s_waitcnt vmcnt(17)
	v_add_u32_e32 v54, s99, v59
	v_add_u32_e32 v55, s99, v60
	v_add_u32_e32 v56, s99, v61
	v_add_u32_e32 v57, s99, v62
	ds_read_b64_tr_b4 v[50:51], v160 offset:384
	ds_read_b64_tr_b4 v[52:53], v160 offset:1408
	ds_read_b64_tr_b4 v[130:131], v54
	ds_read_b64_tr_b4 v[132:133], v55
	ds_read_b64_tr_b4 v[134:135], v56
	ds_read_b64_tr_b4 v[136:137], v57
	s_waitcnt lgkmcnt(6)
	v_dot8c_i32_i4_e32 v38, v122, v48
	v_dot8c_i32_i4_e32 v39, v122, v46
	v_dot8c_i32_i4_e32 v40, v124, v48
	v_dot8c_i32_i4_e32 v41, v124, v46
	v_dot8c_i32_i4_e32 v42, v126, v48
	v_dot8c_i32_i4_e32 v43, v126, v46
	v_dot8c_i32_i4_e32 v44, v128, v48
	v_dot8c_i32_i4_e32 v45, v128, v46
	v_dot8c_i32_i4_e32 v38, v123, v49
	v_dot8c_i32_i4_e32 v39, v123, v47
	v_dot8c_i32_i4_e32 v40, v125, v49
	v_dot8c_i32_i4_e32 v41, v125, v47
	v_dot8c_i32_i4_e32 v42, v127, v49
	v_dot8c_i32_i4_e32 v43, v127, v47
	v_dot8c_i32_i4_e32 v44, v129, v49
	v_dot8c_i32_i4_e32 v45, v129, v47
	s_waitcnt vmcnt(15)
	v_add_u32_e32 v54, s76, v59
	v_add_u32_e32 v55, s76, v60
	v_add_u32_e32 v56, s76, v61
	v_add_u32_e32 v57, s76, v62
	ds_read_b64_tr_b4 v[46:47], v160 offset:512
	ds_read_b64_tr_b4 v[48:49], v160 offset:1536
	ds_read_b64_tr_b4 v[122:123], v54
	ds_read_b64_tr_b4 v[124:125], v55
	ds_read_b64_tr_b4 v[126:127], v56
	ds_read_b64_tr_b4 v[128:129], v57
	s_waitcnt lgkmcnt(6)
; #define LAS __attribute__((address_space(3)))
; __device__ __forceinline__ void peer_v_tokens(int j, const LAS unsigned short* EL, const LAS unsigned char* AL  , const LAS float* ASC  , const LAS int* SAL  , ...
;     ...
;         for (int st = 0; st < 16; ++st) {
;             const int p = st >> 2, q = st & 3;
;             if (st < 14) VDMA(st + 2, (st + 2) % 3);
;             if (st < 14) asm volatile("s_waitcnt vmcnt(8)" ::: "memory");
;             else if (st == 14) asm volatile("s_waitcnt vmcnt(4)" ::: "memory");
;             else asm volatile("s_waitcnt vmcnt(0)" ::: "memory");
;             if (q == 0) {
; #pragma unroll
;                 for (int r = 0; r < 4; ++r) { accH[r] = 0; accL[r] = 0; } }
; #pragma unroll
;             for (int tp = 0; tp < 2; ++tp) {
;                 const v2i ao = TR4(ATL + (2 * q + tp) * 128 + 8 * s16), ah = TR4(ATL + 1024 + (2 * q + tp) * 128 + 8 * s16);
; #pragma unroll
;                 for (int r = 0; r < 4; ++r) {
;                     const v2i d = TR4(ldsb + BUF[st % 3] + 2048 * tp + roff[r]);
;                     accH[r] = __builtin_amdgcn_sdot8(d.x, ah.x, accH[r], false); accH[r] = __builtin_amdgcn_sdot8(d.y, ah.y, accH[r], false);
;                     accL[r] = __builtin_amdgcn_sdot8(d.x, ao.x, accL[r], false); accL[r] = __builtin_amdgcn_sdot8(d.y, ao.y, accL[r], false);
;                 }
;             }
;             asm volatile("s_waitcnt lgkmcnt(0)" ::: "memory");
;             if (q == 3) {
; #pragma unroll
;                 for (int r = 0; r < 4; ++r) STASH[256 * p + 16 * (grp + 4 * r) + pc] = f2bf(asc * (float)(2 * ((accH[r] << 4) + accL[r]) + sa));
;             }
;         }
;     ...
;         {
;             float4 v[4]; float ss = 0.f;
; #pragma unroll
;             for (int jq = 0; jq < 4; ++jq) { typedef unsigned u2v __attribute__((ext_vector_type(2))); const u2v pw = *(const LAS u2v*)(STASH + 4 * lane + 256 * jq); const uint2 hw = hv[jq];
;                 v[jq] = make_float4(__uint_as_float(hw.x << 16) + __uint_as_float(pw.x << 16), __uint_as_float(hw.x & 0xffff0000u) + __uint_as_float(pw.x & 0xffff0000u),
;                                     __uint_as_float(hw.y << 16) + __uint_as_float(pw.y << 16), __uint_as_float(hw.y & 0xffff0000u) + __uint_as_float(pw.y & 0xffff0000u));
;                 ss += v[jq].x * v[jq].x + v[jq].y * v[jq].y + v[jq].z * v[jq].z + v[jq].w * v[jq].w; }
	v_dot8c_i32_i4_e32 v38, v130, v52
	v_dot8c_i32_i4_e32 v39, v130, v50
	v_dot8c_i32_i4_e32 v40, v132, v52
	v_dot8c_i32_i4_e32 v41, v132, v50
	v_dot8c_i32_i4_e32 v42, v134, v52
	v_dot8c_i32_i4_e32 v43, v134, v50
	v_dot8c_i32_i4_e32 v44, v136, v52
	v_dot8c_i32_i4_e32 v45, v136, v50
	v_dot8c_i32_i4_e32 v38, v131, v53
	v_dot8c_i32_i4_e32 v39, v131, v51
	v_dot8c_i32_i4_e32 v40, v133, v53
	v_dot8c_i32_i4_e32 v41, v133, v51
	v_dot8c_i32_i4_e32 v42, v135, v53
	v_dot8c_i32_i4_e32 v43, v135, v51
	v_dot8c_i32_i4_e32 v44, v137, v53
	v_dot8c_i32_i4_e32 v45, v137, v51
	s_waitcnt vmcnt(4)
	v_add_u32_e32 v54, s77, v59
	v_add_u32_e32 v55, s77, v60
	v_add_u32_e32 v56, s77, v61
	v_add_u32_e32 v57, s77, v62
	ds_read_b64_tr_b4 v[50:51], v160 offset:640
	ds_read_b64_tr_b4 v[52:53], v160 offset:1664
	ds_read_b64_tr_b4 v[130:131], v54
	ds_read_b64_tr_b4 v[132:133], v55
	ds_read_b64_tr_b4 v[134:135], v56
	ds_read_b64_tr_b4 v[136:137], v57
	s_waitcnt lgkmcnt(6)
	v_dot8c_i32_i4_e32 v38, v122, v48
	v_dot8c_i32_i4_e32 v39, v122, v46
	v_dot8c_i32_i4_e32 v40, v124, v48
	v_dot8c_i32_i4_e32 v41, v124, v46
	v_dot8c_i32_i4_e32 v42, v126, v48
	v_dot8c_i32_i4_e32 v43, v126, v46
	v_dot8c_i32_i4_e32 v44, v128, v48
	v_dot8c_i32_i4_e32 v45, v128, v46
	v_dot8c_i32_i4_e32 v38, v123, v49
	v_dot8c_i32_i4_e32 v39, v123, v47
	v_dot8c_i32_i4_e32 v40, v125, v49
	v_dot8c_i32_i4_e32 v41, v125, v47
	v_dot8c_i32_i4_e32 v42, v127, v49
	v_dot8c_i32_i4_e32 v43, v127, v47
	v_dot8c_i32_i4_e32 v44, v129, v49
	v_dot8c_i32_i4_e32 v45, v129, v47
	s_waitcnt vmcnt(2)
	v_add_u32_e32 v54, s78, v59
	v_add_u32_e32 v55, s78, v60
	v_add_u32_e32 v56, s78, v61
	v_add_u32_e32 v57, s78, v62
	ds_read_b64_tr_b4 v[46:47], v160 offset:768
	ds_read_b64_tr_b4 v[48:49], v160 offset:1792
	ds_read_b64_tr_b4 v[122:123], v54
	ds_read_b64_tr_b4 v[124:125], v55
	ds_read_b64_tr_b4 v[126:127], v56
	ds_read_b64_tr_b4 v[128:129], v57
	s_waitcnt lgkmcnt(6)
	v_dot8c_i32_i4_e32 v38, v130, v52
	v_dot8c_i32_i4_e32 v39, v130, v50
	v_dot8c_i32_i4_e32 v40, v132, v52
	v_dot8c_i32_i4_e32 v41, v132, v50
	v_dot8c_i32_i4_e32 v42, v134, v52
	v_dot8c_i32_i4_e32 v43, v134, v50
	v_dot8c_i32_i4_e32 v44, v136, v52
	v_dot8c_i32_i4_e32 v45, v136, v50
	v_dot8c_i32_i4_e32 v38, v131, v53
	v_dot8c_i32_i4_e32 v39, v131, v51
	v_dot8c_i32_i4_e32 v40, v133, v53
	v_dot8c_i32_i4_e32 v41, v133, v51
	v_dot8c_i32_i4_e32 v42, v135, v53
	v_dot8c_i32_i4_e32 v43, v135, v51
	v_dot8c_i32_i4_e32 v44, v137, v53
	v_dot8c_i32_i4_e32 v45, v137, v51
	s_waitcnt vmcnt(0)
	v_add_u32_e32 v54, s79, v59
	v_add_u32_e32 v55, s79, v60
	v_add_u32_e32 v56, s79, v61
	v_add_u32_e32 v57, s79, v62
	ds_read_b64_tr_b4 v[50:51], v160 offset:896
	ds_read_b64_tr_b4 v[52:53], v160 offset:1920
	ds_read_b64_tr_b4 v[130:131], v54
	ds_read_b64_tr_b4 v[132:133], v55
	ds_read_b64_tr_b4 v[134:135], v56
	ds_read_b64_tr_b4 v[136:137], v57
	s_waitcnt lgkmcnt(6)
	v_dot8c_i32_i4_e32 v38, v122, v48
	v_dot8c_i32_i4_e32 v39, v122, v46
	v_dot8c_i32_i4_e32 v40, v124, v48
	v_dot8c_i32_i4_e32 v41, v124, v46
	v_dot8c_i32_i4_e32 v42, v126, v48
	v_dot8c_i32_i4_e32 v43, v126, v46
	v_dot8c_i32_i4_e32 v44, v128, v48
	v_dot8c_i32_i4_e32 v45, v128, v46
	v_dot8c_i32_i4_e32 v38, v123, v49
	v_dot8c_i32_i4_e32 v39, v123, v47
	v_dot8c_i32_i4_e32 v40, v125, v49
	v_dot8c_i32_i4_e32 v41, v125, v47
	v_dot8c_i32_i4_e32 v42, v127, v49
	v_dot8c_i32_i4_e32 v43, v127, v47
	v_dot8c_i32_i4_e32 v44, v129, v49
	v_dot8c_i32_i4_e32 v45, v129, v47
	s_waitcnt lgkmcnt(0)
	v_dot8c_i32_i4_e32 v38, v130, v52
	v_dot8c_i32_i4_e32 v39, v130, v50
	v_dot8c_i32_i4_e32 v40, v132, v52
	v_dot8c_i32_i4_e32 v41, v132, v50
	v_dot8c_i32_i4_e32 v42, v134, v52
	v_dot8c_i32_i4_e32 v43, v134, v50
	v_dot8c_i32_i4_e32 v44, v136, v52
	v_dot8c_i32_i4_e32 v45, v136, v50
	v_dot8c_i32_i4_e32 v38, v131, v53
	v_dot8c_i32_i4_e32 v39, v131, v51
	v_dot8c_i32_i4_e32 v40, v133, v53
	v_dot8c_i32_i4_e32 v41, v133, v51
	v_dot8c_i32_i4_e32 v42, v135, v53
	v_dot8c_i32_i4_e32 v43, v135, v51
	v_dot8c_i32_i4_e32 v44, v137, v53
	v_dot8c_i32_i4_e32 v45, v137, v51
	s_nop 3
	s_waitcnt lgkmcnt(15)
	v_lshlrev_b32_e32 v38, 5, v38
	v_lshlrev_b32_e32 v39, 1, v39
	v_add3_u32 v38, v39, v229, v38
	v_cvt_f32_i32_e32 v38, v38
	v_mul_f32_e32 v38, v228, v38
	v_lshlrev_b32_e32 v40, 5, v40
	v_lshlrev_b32_e32 v41, 1, v41
	v_add3_u32 v40, v41, v229, v40
	v_cvt_f32_i32_e32 v40, v40
	v_mul_f32_e32 v40, v228, v40
	v_lshlrev_b32_e32 v42, 5, v42
	v_lshlrev_b32_e32 v43, 1, v43
	v_add3_u32 v42, v43, v229, v42
	v_cvt_f32_i32_e32 v42, v42
	v_mul_f32_e32 v42, v228, v42
	v_lshlrev_b32_e32 v44, 5, v44
	v_lshlrev_b32_e32 v45, 1, v45
	v_add3_u32 v44, v45, v229, v44
	v_cvt_f32_i32_e32 v44, v44
	v_mul_f32_e32 v44, v228, v44
	v_cvt_pk_bf16_f32 v192, v38, v40
	v_cvt_pk_bf16_f32 v193, v42, v44
	ds_read_b128 v[252:255], v156 offset:1024
	s_add_i32 s44, s40, 40
	s_ashr_i32 s45, s44, 31
	s_lshl_b64 s[44:45], s[44:45], 12
	v_lshl_add_u64 v[80:81], v[36:37], 0, s[44:45]
	s_waitcnt lgkmcnt(0)
	v_mul_f32_e32 v248, v248, v252
	v_mul_f32_e32 v249, v249, v253
	v_mul_f32_e32 v250, v250, v254
	v_mul_f32_e32 v251, v251, v255
	global_store_dwordx4 v[80:81], v[248:251], off offset:3072 nt
	ds_write_b16 v65, v178
	ds_write_b16_d16_hi v65, v178 offset:128
	ds_write_b16 v65, v179 offset:256
	ds_write_b16_d16_hi v65, v179 offset:384
	ds_write_b16 v65, v180 offset:512
	ds_write_b16_d16_hi v65, v180 offset:640
	ds_write_b16 v65, v181 offset:768
	ds_write_b16_d16_hi v65, v181 offset:896
	ds_write_b16 v65, v182 offset:1024
	ds_write_b16_d16_hi v65, v182 offset:1152
	ds_write_b16 v65, v183 offset:1280
	ds_write_b16_d16_hi v65, v183 offset:1408
	ds_write_b16 v65, v184 offset:1536
	ds_write_b16_d16_hi v65, v184 offset:1664
	ds_write_b16 v65, v185 offset:1792
	ds_write_b16_d16_hi v65, v185 offset:1920
	ds_read_b64 v[202:203], v154
	ds_read_b64 v[204:205], v154 offset:512
	ds_read_b64 v[206:207], v154 offset:1024
	ds_read_b64 v[208:209], v154 offset:1536
	s_waitcnt vmcnt(11) lgkmcnt(0)
; #define LAS __attribute__((address_space(3)))
; __device__ __forceinline__ void peer_v_tokens(int j, const LAS unsigned short* EL, const LAS unsigned char* AL  , const LAS float* ASC  , const LAS int* SAL  , ...
;     ...
;         {
;             float4 v[4]; float ss = 0.f;
; #pragma unroll
;             for (int jq = 0; jq < 4; ++jq) { typedef unsigned u2v __attribute__((ext_vector_type(2))); const u2v pw = *(const LAS u2v*)(STASH + 4 * lane + 256 * jq); const uint2 hw = hv[jq];
;                 v[jq] = make_float4(__uint_as_float(hw.x << 16) + __uint_as_float(pw.x << 16), __uint_as_float(hw.x & 0xffff0000u) + __uint_as_float(pw.x & 0xffff0000u),
;                                     __uint_as_float(hw.y << 16) + __uint_as_float(pw.y << 16), __uint_as_float(hw.y & 0xffff0000u) + __uint_as_float(pw.y & 0xffff0000u));
;                 ss += v[jq].x * v[jq].x + v[jq].y * v[jq].y + v[jq].z * v[jq].z + v[jq].w * v[jq].w; }
;             ss = wave_sum(ss);
;             const float r3 = rsqrtf(ss * (1.f / D) + EPS);
;             float4* op = (float4*)(outp + (size_t)t * D) + lane;
; #pragma unroll
;             for (int jq = 0; jq < 4; ++jq) { typedef float f4v __attribute__((ext_vector_type(4))); f4v o4; o4.x = v[jq].x * r3 * gv[jq].x; o4.y = v[jq].y * r3 * gv[jq].y; o4.z = v[jq].z * r3 * gv[jq].z; o4.w = v[jq].w * r3 * gv[jq].w;
;                 __builtin_nontemporal_store(o4, (f4v*)op + 64 * jq); }
;         }
	v_lshlrev_b32_e32 v210, 16, v194
	v_and_b32_e32 v211, 0xffff0000, v194
	v_lshlrev_b32_e32 v142, 16, v202
	v_and_b32_e32 v143, 0xffff0000, v202
	v_add_f32_e32 v210, v210, v142
	v_add_f32_e32 v211, v211, v143
	v_lshlrev_b32_e32 v212, 16, v195
	v_and_b32_e32 v213, 0xffff0000, v195
	v_lshlrev_b32_e32 v142, 16, v203
	v_and_b32_e32 v143, 0xffff0000, v203
	v_add_f32_e32 v212, v212, v142
	v_add_f32_e32 v213, v213, v143
	v_lshlrev_b32_e32 v214, 16, v196
	v_and_b32_e32 v215, 0xffff0000, v196
	v_lshlrev_b32_e32 v142, 16, v204
	v_and_b32_e32 v143, 0xffff0000, v204
	v_add_f32_e32 v214, v214, v142
	v_add_f32_e32 v215, v215, v143
	v_lshlrev_b32_e32 v216, 16, v197
	v_and_b32_e32 v217, 0xffff0000, v197
	v_lshlrev_b32_e32 v142, 16, v205
	v_and_b32_e32 v143, 0xffff0000, v205
	v_add_f32_e32 v216, v216, v142
	v_add_f32_e32 v217, v217, v143
	v_lshlrev_b32_e32 v218, 16, v198
	v_and_b32_e32 v219, 0xffff0000, v198
	v_lshlrev_b32_e32 v142, 16, v206
	v_and_b32_e32 v143, 0xffff0000, v206
	v_add_f32_e32 v218, v218, v142
	v_add_f32_e32 v219, v219, v143
	v_lshlrev_b32_e32 v220, 16, v199
	v_and_b32_e32 v221, 0xffff0000, v199
	v_lshlrev_b32_e32 v142, 16, v207
	v_and_b32_e32 v143, 0xffff0000, v207
	v_add_f32_e32 v220, v220, v142
	v_add_f32_e32 v221, v221, v143
	v_lshlrev_b32_e32 v222, 16, v200
	v_and_b32_e32 v223, 0xffff0000, v200
	v_lshlrev_b32_e32 v142, 16, v208
	v_and_b32_e32 v143, 0xffff0000, v208
	v_add_f32_e32 v222, v222, v142
	v_add_f32_e32 v223, v223, v143
	v_lshlrev_b32_e32 v224, 16, v201
	v_and_b32_e32 v225, 0xffff0000, v201
	v_lshlrev_b32_e32 v142, 16, v209
	v_and_b32_e32 v143, 0xffff0000, v209
	v_add_f32_e32 v224, v224, v142
	v_add_f32_e32 v225, v225, v143
	v_mov_b32_e32 v144, 0
	v_mul_f32_e32 v145, v210, v210
	v_fmac_f32_e32 v145, v211, v211
	v_fmac_f32_e32 v145, v212, v212
	v_fmac_f32_e32 v145, v213, v213
	v_add_f32_e32 v144, v144, v145
	v_mul_f32_e32 v145, v214, v214
	v_fmac_f32_e32 v145, v215, v215
	v_fmac_f32_e32 v145, v216, v216
	v_fmac_f32_e32 v145, v217, v217
	v_add_f32_e32 v144, v144, v145
	v_mul_f32_e32 v145, v218, v218
	v_fmac_f32_e32 v145, v219, v219
	v_fmac_f32_e32 v145, v220, v220
	v_fmac_f32_e32 v145, v221, v221
	v_add_f32_e32 v144, v144, v145
	v_mul_f32_e32 v145, v222, v222
	v_fmac_f32_e32 v145, v223, v223
	v_fmac_f32_e32 v145, v224, v224
	v_fmac_f32_e32 v145, v225, v225
	v_add_f32_e32 v144, v144, v145
	s_nop 1
	v_add_f32_dpp v144, v144, v144 quad_perm:[1,0,3,2] row_mask:0xf bank_mask:0xf bound_ctrl:1
	s_nop 1
	v_add_f32_dpp v144, v144, v144 quad_perm:[2,3,0,1] row_mask:0xf bank_mask:0xf bound_ctrl:1
	s_nop 1
	v_add_f32_dpp v144, v144, v144 row_half_mirror row_mask:0xf bank_mask:0xf bound_ctrl:1
	s_nop 1
	v_add_f32_dpp v144, v144, v144 row_mirror row_mask:0xf bank_mask:0xf bound_ctrl:1
	s_nop 1
	v_readlane_b32 s10, v144, 0
	v_readlane_b32 s11, v144, 16
	v_readlane_b32 s14, v144, 32
	v_readlane_b32 s15, v144, 48
	s_nop 3
	v_mov_b32_e32 v144, s11
	v_mov_b32_e32 v145, s15
	v_add_f32_e32 v144, s10, v144
	v_add_f32_e32 v145, s14, v145
	v_add_f32_e32 v144, v144, v145
	v_fmamk_f32 v144, v144, 0x3a800000, v111
	v_rsq_f32_e32 v144, v144
	s_nop 0
	v_mul_f32_e32 v210, v210, v144
	v_mul_f32_e32 v211, v211, v144
	v_mul_f32_e32 v212, v212, v144
	v_mul_f32_e32 v213, v213, v144
	v_mul_f32_e32 v214, v214, v144
	v_mul_f32_e32 v215, v215, v144
	v_mul_f32_e32 v216, v216, v144
	v_mul_f32_e32 v217, v217, v144
	v_mul_f32_e32 v218, v218, v144
	v_mul_f32_e32 v219, v219, v144
	v_mul_f32_e32 v220, v220, v144
	v_mul_f32_e32 v221, v221, v144
	v_mul_f32_e32 v222, v222, v144
	v_mul_f32_e32 v223, v223, v144
	v_mul_f32_e32 v224, v224, v144
	v_mul_f32_e32 v225, v225, v144
	ds_read_b128 v[252:255], v155
	s_add_i32 s44, s40, 48
	s_ashr_i32 s45, s44, 31
	s_lshl_b64 s[44:45], s[44:45], 12
	v_lshl_add_u64 v[80:81], v[36:37], 0, s[44:45]
	s_waitcnt lgkmcnt(0)
	v_mul_f32_e32 v210, v210, v252
	v_mul_f32_e32 v211, v211, v253
	v_mul_f32_e32 v212, v212, v254
	v_mul_f32_e32 v213, v213, v255
	global_store_dwordx4 v[80:81], v[210:213], off nt
	ds_read_b128 v[252:255], v155 offset:1024
	s_add_i32 s44, s40, 48
	s_ashr_i32 s45, s44, 31
	s_lshl_b64 s[44:45], s[44:45], 12
	v_lshl_add_u64 v[80:81], v[36:37], 0, s[44:45]
	s_waitcnt lgkmcnt(0)
	v_mul_f32_e32 v214, v214, v252
	v_mul_f32_e32 v215, v215, v253
	v_mul_f32_e32 v216, v216, v254
	v_mul_f32_e32 v217, v217, v255
	global_store_dwordx4 v[80:81], v[214:217], off offset:1024 nt
	ds_read_b128 v[252:255], v156
	s_add_i32 s44, s40, 48
	s_ashr_i32 s45, s44, 31
	s_lshl_b64 s[44:45], s[44:45], 12
	v_lshl_add_u64 v[80:81], v[36:37], 0, s[44:45]
	s_waitcnt lgkmcnt(0)
	v_mul_f32_e32 v218, v218, v252
	v_mul_f32_e32 v219, v219, v253
	v_mul_f32_e32 v220, v220, v254
	v_mul_f32_e32 v221, v221, v255
	global_store_dwordx4 v[80:81], v[218:221], off offset:2048 nt
	ds_read_b128 v[252:255], v156 offset:1024
	s_add_i32 s44, s40, 48
	s_ashr_i32 s45, s44, 31
	s_lshl_b64 s[44:45], s[44:45], 12
	v_lshl_add_u64 v[80:81], v[36:37], 0, s[44:45]
	s_waitcnt lgkmcnt(0)
	v_mul_f32_e32 v222, v222, v252
	v_mul_f32_e32 v223, v223, v253
	v_mul_f32_e32 v224, v224, v254
	v_mul_f32_e32 v225, v225, v255
	global_store_dwordx4 v[80:81], v[222:225], off offset:3072 nt
	ds_write_b16 v65, v186
	ds_write_b16_d16_hi v65, v186 offset:128
	ds_write_b16 v65, v187 offset:256
	ds_write_b16_d16_hi v65, v187 offset:384
	ds_write_b16 v65, v188 offset:512
	ds_write_b16_d16_hi v65, v188 offset:640
	ds_write_b16 v65, v189 offset:768
	ds_write_b16_d16_hi v65, v189 offset:896
	ds_write_b16 v65, v190 offset:1024
	ds_write_b16_d16_hi v65, v190 offset:1152
	ds_write_b16 v65, v191 offset:1280
	ds_write_b16_d16_hi v65, v191 offset:1408
	ds_write_b16 v65, v192 offset:1536
	ds_write_b16_d16_hi v65, v192 offset:1664
	ds_write_b16 v65, v193 offset:1792
	ds_write_b16_d16_hi v65, v193 offset:1920
	ds_read_b64 v[202:203], v154
	ds_read_b64 v[204:205], v154 offset:512
	ds_read_b64 v[206:207], v154 offset:1024
	ds_read_b64 v[208:209], v154 offset:1536
	s_waitcnt vmcnt(11) lgkmcnt(0)
; #define LAS __attribute__((address_space(3)))
; __device__ __forceinline__ void peer_v_tokens(int j, const LAS unsigned short* EL, const LAS unsigned char* AL  , const LAS float* ASC  , const LAS int* SAL  , ...
;     ...
;         {
;             float4 v[4]; float ss = 0.f;
; #pragma unroll
;             for (int jq = 0; jq < 4; ++jq) { typedef unsigned u2v __attribute__((ext_vector_type(2))); const u2v pw = *(const LAS u2v*)(STASH + 4 * lane + 256 * jq); const uint2 hw = hv[jq];
;                 v[jq] = make_float4(__uint_as_float(hw.x << 16) + __uint_as_float(pw.x << 16), __uint_as_float(hw.x & 0xffff0000u) + __uint_as_float(pw.x & 0xffff0000u),
;                                     __uint_as_float(hw.y << 16) + __uint_as_float(pw.y << 16), __uint_as_float(hw.y & 0xffff0000u) + __uint_as_float(pw.y & 0xffff0000u));
;                 ss += v[jq].x * v[jq].x + v[jq].y * v[jq].y + v[jq].z * v[jq].z + v[jq].w * v[jq].w; }
;             ss = wave_sum(ss);
;             const float r3 = rsqrtf(ss * (1.f / D) + EPS);
;             float4* op = (float4*)(outp + (size_t)t * D) + lane;
; #pragma unroll
;             for (int jq = 0; jq < 4; ++jq) { typedef float f4v __attribute__((ext_vector_type(4))); f4v o4; o4.x = v[jq].x * r3 * gv[jq].x; o4.y = v[jq].y * r3 * gv[jq].y; o4.z = v[jq].z * r3 * gv[jq].z; o4.w = v[jq].w * r3 * gv[jq].w;
;                 __builtin_nontemporal_store(o4, (f4v*)op + 64 * jq); }
;         }
	v_lshlrev_b32_e32 v236, 16, v18
	v_and_b32_e32 v237, 0xffff0000, v18
	v_lshlrev_b32_e32 v142, 16, v202
	v_and_b32_e32 v143, 0xffff0000, v202
	v_add_f32_e32 v236, v236, v142
	v_add_f32_e32 v237, v237, v143
	v_lshlrev_b32_e32 v238, 16, v19
	v_and_b32_e32 v239, 0xffff0000, v19
	v_lshlrev_b32_e32 v142, 16, v203
	v_and_b32_e32 v143, 0xffff0000, v203
	v_add_f32_e32 v238, v238, v142
	v_add_f32_e32 v239, v239, v143
	v_lshlrev_b32_e32 v240, 16, v20
	v_and_b32_e32 v241, 0xffff0000, v20
	v_lshlrev_b32_e32 v142, 16, v204
	v_and_b32_e32 v143, 0xffff0000, v204
	v_add_f32_e32 v240, v240, v142
	v_add_f32_e32 v241, v241, v143
	v_lshlrev_b32_e32 v242, 16, v21
	v_and_b32_e32 v243, 0xffff0000, v21
	v_lshlrev_b32_e32 v142, 16, v205
	v_and_b32_e32 v143, 0xffff0000, v205
	v_add_f32_e32 v242, v242, v142
	v_add_f32_e32 v243, v243, v143
	v_lshlrev_b32_e32 v244, 16, v22
	v_and_b32_e32 v245, 0xffff0000, v22
	v_lshlrev_b32_e32 v142, 16, v206
	v_and_b32_e32 v143, 0xffff0000, v206
	v_add_f32_e32 v244, v244, v142
	v_add_f32_e32 v245, v245, v143
	v_lshlrev_b32_e32 v246, 16, v23
	v_and_b32_e32 v247, 0xffff0000, v23
	v_lshlrev_b32_e32 v142, 16, v207
	v_and_b32_e32 v143, 0xffff0000, v207
	v_add_f32_e32 v246, v246, v142
	v_add_f32_e32 v247, v247, v143
	v_lshlrev_b32_e32 v248, 16, v24
	v_and_b32_e32 v249, 0xffff0000, v24
	v_lshlrev_b32_e32 v142, 16, v208
	v_and_b32_e32 v143, 0xffff0000, v208
	v_add_f32_e32 v248, v248, v142
	v_add_f32_e32 v249, v249, v143
	v_lshlrev_b32_e32 v250, 16, v25
	v_and_b32_e32 v251, 0xffff0000, v25
	v_lshlrev_b32_e32 v142, 16, v209
	v_and_b32_e32 v143, 0xffff0000, v209
	v_add_f32_e32 v250, v250, v142
	v_add_f32_e32 v251, v251, v143
	v_mov_b32_e32 v144, 0
	v_mul_f32_e32 v145, v236, v236
	v_fmac_f32_e32 v145, v237, v237
	v_fmac_f32_e32 v145, v238, v238
	v_fmac_f32_e32 v145, v239, v239
	v_add_f32_e32 v144, v144, v145
	v_mul_f32_e32 v145, v240, v240
	v_fmac_f32_e32 v145, v241, v241
	v_fmac_f32_e32 v145, v242, v242
	v_fmac_f32_e32 v145, v243, v243
	v_add_f32_e32 v144, v144, v145
	v_mul_f32_e32 v145, v244, v244
	v_fmac_f32_e32 v145, v245, v245
	v_fmac_f32_e32 v145, v246, v246
	v_fmac_f32_e32 v145, v247, v247
	v_add_f32_e32 v144, v144, v145
	v_mul_f32_e32 v145, v248, v248
	v_fmac_f32_e32 v145, v249, v249
	v_fmac_f32_e32 v145, v250, v250
	v_fmac_f32_e32 v145, v251, v251
	v_add_f32_e32 v144, v144, v145
	s_nop 1
	v_add_f32_dpp v144, v144, v144 quad_perm:[1,0,3,2] row_mask:0xf bank_mask:0xf bound_ctrl:1
	s_nop 1
	v_add_f32_dpp v144, v144, v144 quad_perm:[2,3,0,1] row_mask:0xf bank_mask:0xf bound_ctrl:1
	s_nop 1
	v_add_f32_dpp v144, v144, v144 row_half_mirror row_mask:0xf bank_mask:0xf bound_ctrl:1
	s_nop 1
	v_add_f32_dpp v144, v144, v144 row_mirror row_mask:0xf bank_mask:0xf bound_ctrl:1
	s_nop 1
	v_readlane_b32 s10, v144, 0
	v_readlane_b32 s11, v144, 16
	v_readlane_b32 s14, v144, 32
	v_readlane_b32 s15, v144, 48
	s_nop 3
	v_mov_b32_e32 v144, s11
	v_mov_b32_e32 v145, s15
	v_add_f32_e32 v144, s10, v144
	v_add_f32_e32 v145, s14, v145
	v_add_f32_e32 v144, v144, v145
	v_fmamk_f32 v144, v144, 0x3a800000, v111
	v_rsq_f32_e32 v144, v144
	s_nop 0
	v_mul_f32_e32 v236, v236, v144
	v_mul_f32_e32 v237, v237, v144
	v_mul_f32_e32 v238, v238, v144
	v_mul_f32_e32 v239, v239, v144
	v_mul_f32_e32 v240, v240, v144
	v_mul_f32_e32 v241, v241, v144
	v_mul_f32_e32 v242, v242, v144
	v_mul_f32_e32 v243, v243, v144
	v_mul_f32_e32 v244, v244, v144
	v_mul_f32_e32 v245, v245, v144
	v_mul_f32_e32 v246, v246, v144
	v_mul_f32_e32 v247, v247, v144
	v_mul_f32_e32 v248, v248, v144
	v_mul_f32_e32 v249, v249, v144
	v_mul_f32_e32 v250, v250, v144
	v_mul_f32_e32 v251, v251, v144
	ds_read_b128 v[252:255], v155
	s_add_i32 s44, s40, 56
	s_ashr_i32 s45, s44, 31
	s_lshl_b64 s[44:45], s[44:45], 12
	v_lshl_add_u64 v[80:81], v[36:37], 0, s[44:45]
	s_waitcnt lgkmcnt(0)
	v_mul_f32_e32 v236, v236, v252
	v_mul_f32_e32 v237, v237, v253
	v_mul_f32_e32 v238, v238, v254
	v_mul_f32_e32 v239, v239, v255
	global_store_dwordx4 v[80:81], v[236:239], off nt
	ds_read_b128 v[252:255], v155 offset:1024
	s_add_i32 s44, s40, 56
	s_ashr_i32 s45, s44, 31
	s_lshl_b64 s[44:45], s[44:45], 12
	v_lshl_add_u64 v[80:81], v[36:37], 0, s[44:45]
	s_waitcnt lgkmcnt(0)
	v_mul_f32_e32 v240, v240, v252
	v_mul_f32_e32 v241, v241, v253
	v_mul_f32_e32 v242, v242, v254
	v_mul_f32_e32 v243, v243, v255
	global_store_dwordx4 v[80:81], v[240:243], off offset:1024 nt
	ds_read_b128 v[252:255], v156
	s_add_i32 s44, s40, 56
	s_ashr_i32 s45, s44, 31
	s_lshl_b64 s[44:45], s[44:45], 12
	v_lshl_add_u64 v[80:81], v[36:37], 0, s[44:45]
	s_waitcnt lgkmcnt(0)
	v_mul_f32_e32 v244, v244, v252
	v_mul_f32_e32 v245, v245, v253
	v_mul_f32_e32 v246, v246, v254
	v_mul_f32_e32 v247, v247, v255
	global_store_dwordx4 v[80:81], v[244:247], off offset:2048 nt
	ds_read_b128 v[252:255], v156 offset:1024
	s_add_i32 s44, s40, 56
	s_ashr_i32 s45, s44, 31
	s_lshl_b64 s[44:45], s[44:45], 12
	v_lshl_add_u64 v[80:81], v[36:37], 0, s[44:45]
	s_waitcnt lgkmcnt(0)
	v_mul_f32_e32 v248, v248, v252
	v_mul_f32_e32 v249, v249, v253
	v_mul_f32_e32 v250, v250, v254
	v_mul_f32_e32 v251, v251, v255
	global_store_dwordx4 v[80:81], v[248:251], off offset:3072 nt
	s_add_i32 s2, s2, s33
	s_add_i32 s40, s40, s63
	s_add_i32 s73, s73, s74
	s_cmpk_lt_i32 s2, 0x100
	s_cbranch_scc1 .LBB0_648
